# hand-written pipelined rmsnorm/modulate row prep with 16-byte loads and stores (P1 and P11) + P3 prefetch-wait fix + seam0 XCD barrier
# speedup vs baseline: 1.0145x; 1.0111x over previous
.LBB0_106:
	s_cmp_lt_i32 s78, 2
	s_cselect_b64 s[2:3], -1, 0
	s_and_b64 s[12:13], s[2:3], s[0:1]
	s_andn2_b64 vcc, exec, s[12:13]
	s_cbranch_vccnz .LBB0_122
	s_mov_b64 s[2:3], s[72:73]
	s_load_dwordx2 s[0:1], s[2:3], 0x90
	s_load_dwordx2 s[4:5], s[2:3], 0xe8
	v_mov_b32_e32 v0, v254
	s_lshl_b32 s33, s96, 3
	v_readfirstlane_b32 s44, v0
	s_ashr_i32 s43, s44, 6
	s_add_i32 s42, s43, s33
	s_cmp_gt_i32 s42, 0x17fff
	v_and_b32_e32 v94, 63, v0
	s_cbranch_scc1 .LBB0_116
	s_load_dwordx2 s[6:7], s[72:73], 0x38
	s_load_dwordx2 s[10:11], s[72:73], 0x0
	s_load_dwordx2 s[14:15], s[72:73], 0x8
	s_load_dwordx2 s[8:9], s[72:73], 0xe8
	v_and_b32_e32 v82, 63, v254
	v_lshlrev_b32_e32 v80, 5, v82
	v_add_u32_e32 v81, 0x1000, v80
	v_xor_b32_e32 v83, 1, v82
	v_xor_b32_e32 v84, 2, v82
	v_xor_b32_e32 v85, 4, v82
	v_xor_b32_e32 v86, 8, v82
	v_xor_b32_e32 v87, 16, v82
	v_xor_b32_e32 v88, 32, v82
	v_lshlrev_b32_e32 v83, 2, v83
	v_lshlrev_b32_e32 v84, 2, v84
	v_lshlrev_b32_e32 v85, 2, v85
	v_lshlrev_b32_e32 v86, 2, v86
	v_lshlrev_b32_e32 v87, 2, v87
	v_lshlrev_b32_e32 v88, 2, v88
	v_lshlrev_b32_e32 v82, 4, v82
	v_mov_b32_e32 v89, 0x358637bd
	v_mov_b32_e32 v90, 0x260
	s_mov_b32 s54, 0xf800000
	v_readfirstlane_b32 s45, v254
	s_nop 3
	s_lshl_b32 s50, s96, 3
	s_lshr_b32 s45, s45, 6
	s_add_i32 s45, s45, s50
	s_waitcnt lgkmcnt(0)
	s_lshl_b32 s50, s45, 12
	s_add_u32 s16, s10, s50
	s_addc_u32 s17, s11, 0
	s_add_u32 s18, s14, s50
	s_addc_u32 s19, s15, 0
	s_lshl_b32 s50, s45, 11
	s_add_u32 s20, s8, s50
	s_addc_u32 s21, s9, 0
	s_add_u32 s20, s20, 0x3000000
	s_addc_u32 s21, s21, 0
	global_load_dwordx4 v[64:67], v80, s[6:7] offset:0
	global_load_dwordx4 v[68:71], v80, s[6:7] offset:16
	global_load_dwordx4 v[72:75], v80, s[6:7] offset:2048
	global_load_dwordx4 v[76:79], v80, s[6:7] offset:2064
	s_mov_b64 s[24:25], s[16:17]
	s_add_u32 s26, s16, 0x800000
	s_addc_u32 s27, s17, 0
	s_add_u32 s28, s16, 0x1000000
	s_addc_u32 s29, s17, 0
	s_add_u32 s30, s16, 0x1800000
	s_addc_u32 s31, s17, 0
	global_load_dwordx4 v[0:3], v80, s[24:25] offset:0
	global_load_dwordx4 v[4:7], v80, s[24:25] offset:16
	global_load_dwordx4 v[8:11], v80, s[24:25] offset:2048
	global_load_dwordx4 v[12:15], v80, s[24:25] offset:2064
	global_load_dwordx4 v[16:19], v80, s[26:27] offset:0
	global_load_dwordx4 v[20:23], v80, s[26:27] offset:16
	global_load_dwordx4 v[24:27], v80, s[26:27] offset:2048
	global_load_dwordx4 v[28:31], v80, s[26:27] offset:2064
	global_load_dwordx4 v[32:35], v80, s[28:29] offset:0
	global_load_dwordx4 v[36:39], v80, s[28:29] offset:16
	global_load_dwordx4 v[40:43], v80, s[28:29] offset:2048
	global_load_dwordx4 v[44:47], v80, s[28:29] offset:2064
	global_load_dwordx4 v[48:51], v80, s[30:31] offset:0
	global_load_dwordx4 v[52:55], v80, s[30:31] offset:16
	global_load_dwordx4 v[56:59], v80, s[30:31] offset:2048
	global_load_dwordx4 v[60:63], v80, s[30:31] offset:2064
	s_mov_b64 s[34:35], s[8:9]
	s_mov_b64 s[36:37], s[8:9]
	global_load_dwordx4 v[176:179], v80, s[34:35] offset:0
	global_load_dwordx4 v[180:183], v80, s[34:35] offset:16
	global_load_dwordx4 v[184:187], v80, s[34:35] offset:2048
	global_load_dwordx4 v[188:191], v80, s[34:35] offset:2064
	global_load_dwordx4 v[160:163], v81, s[34:35] offset:0
	global_load_dwordx4 v[164:167], v81, s[34:35] offset:16
	global_load_dwordx4 v[168:171], v81, s[34:35] offset:2048
	global_load_dwordx4 v[172:175], v81, s[34:35] offset:2064
	global_load_dwordx4 v[208:211], v80, s[36:37] offset:0
	global_load_dwordx4 v[212:215], v80, s[36:37] offset:16
	global_load_dwordx4 v[216:219], v80, s[36:37] offset:2048
	global_load_dwordx4 v[220:223], v80, s[36:37] offset:2064
	global_load_dwordx4 v[192:195], v81, s[36:37] offset:0
	global_load_dwordx4 v[196:199], v81, s[36:37] offset:16
	global_load_dwordx4 v[200:203], v81, s[36:37] offset:2048
	global_load_dwordx4 v[204:207], v81, s[36:37] offset:2064
	s_add_u32 s24, s16, 0x2000000
	s_addc_u32 s25, s17, 0
	s_add_u32 s26, s16, 0x2800000
	s_addc_u32 s27, s17, 0
	s_add_u32 s28, s16, 0x3000000
	s_addc_u32 s29, s17, 0
	s_add_u32 s30, s16, 0x3800000
	s_addc_u32 s31, s17, 0
	global_load_dwordx4 v[96:99], v80, s[24:25] offset:0
	global_load_dwordx4 v[100:103], v80, s[24:25] offset:16
	global_load_dwordx4 v[104:107], v80, s[24:25] offset:2048
	global_load_dwordx4 v[108:111], v80, s[24:25] offset:2064
	global_load_dwordx4 v[112:115], v80, s[26:27] offset:0
	global_load_dwordx4 v[116:119], v80, s[26:27] offset:16
	global_load_dwordx4 v[120:123], v80, s[26:27] offset:2048
	global_load_dwordx4 v[124:127], v80, s[26:27] offset:2064
	global_load_dwordx4 v[128:131], v80, s[28:29] offset:0
	global_load_dwordx4 v[132:135], v80, s[28:29] offset:16
	global_load_dwordx4 v[136:139], v80, s[28:29] offset:2048
	global_load_dwordx4 v[140:143], v80, s[28:29] offset:2064
	global_load_dwordx4 v[144:147], v80, s[30:31] offset:0
	global_load_dwordx4 v[148:151], v80, s[30:31] offset:16
	global_load_dwordx4 v[152:155], v80, s[30:31] offset:2048
	global_load_dwordx4 v[156:159], v80, s[30:31] offset:2064
	s_waitcnt vmcnt(32)
	v_pk_mul_f32 v[240:241], v[0:1], v[0:1]
	v_pk_mul_f32 v[242:243], v[16:17], v[16:17]
	v_pk_mul_f32 v[244:245], v[32:33], v[32:33]
	v_pk_mul_f32 v[246:247], v[48:49], v[48:49]
	v_pk_fma_f32 v[240:241], v[2:3], v[2:3], v[240:241]
	v_pk_fma_f32 v[242:243], v[18:19], v[18:19], v[242:243]
	v_pk_fma_f32 v[244:245], v[34:35], v[34:35], v[244:245]
	v_pk_fma_f32 v[246:247], v[50:51], v[50:51], v[246:247]
	v_pk_fma_f32 v[240:241], v[4:5], v[4:5], v[240:241]
	v_pk_fma_f32 v[242:243], v[20:21], v[20:21], v[242:243]
	v_pk_fma_f32 v[244:245], v[36:37], v[36:37], v[244:245]
	v_pk_fma_f32 v[246:247], v[52:53], v[52:53], v[246:247]
	v_pk_fma_f32 v[240:241], v[6:7], v[6:7], v[240:241]
	v_pk_fma_f32 v[242:243], v[22:23], v[22:23], v[242:243]
	v_pk_fma_f32 v[244:245], v[38:39], v[38:39], v[244:245]
	v_pk_fma_f32 v[246:247], v[54:55], v[54:55], v[246:247]
	v_pk_fma_f32 v[240:241], v[8:9], v[8:9], v[240:241]
	v_pk_fma_f32 v[242:243], v[24:25], v[24:25], v[242:243]
	v_pk_fma_f32 v[244:245], v[40:41], v[40:41], v[244:245]
	v_pk_fma_f32 v[246:247], v[56:57], v[56:57], v[246:247]
	v_pk_fma_f32 v[240:241], v[10:11], v[10:11], v[240:241]
	v_pk_fma_f32 v[242:243], v[26:27], v[26:27], v[242:243]
	v_pk_fma_f32 v[244:245], v[42:43], v[42:43], v[244:245]
	v_pk_fma_f32 v[246:247], v[58:59], v[58:59], v[246:247]
	v_pk_fma_f32 v[240:241], v[12:13], v[12:13], v[240:241]
	v_pk_fma_f32 v[242:243], v[28:29], v[28:29], v[242:243]
	v_pk_fma_f32 v[244:245], v[44:45], v[44:45], v[244:245]
	v_pk_fma_f32 v[246:247], v[60:61], v[60:61], v[246:247]
	v_pk_fma_f32 v[240:241], v[14:15], v[14:15], v[240:241]
	v_pk_fma_f32 v[242:243], v[30:31], v[30:31], v[242:243]
	v_pk_fma_f32 v[244:245], v[46:47], v[46:47], v[244:245]
	v_pk_fma_f32 v[246:247], v[62:63], v[62:63], v[246:247]
	v_add_f32_e32 v224, v240, v241
	v_add_f32_e32 v225, v242, v243
	v_add_f32_e32 v226, v244, v245
	v_add_f32_e32 v227, v246, v247
	ds_bpermute_b32 v228, v83, v224
	ds_bpermute_b32 v229, v83, v225
	ds_bpermute_b32 v230, v83, v226
	ds_bpermute_b32 v231, v83, v227
	s_waitcnt lgkmcnt(0)
	v_add_f32_e32 v224, v224, v228
	v_add_f32_e32 v225, v225, v229
	v_add_f32_e32 v226, v226, v230
	v_add_f32_e32 v227, v227, v231
	ds_bpermute_b32 v228, v84, v224
	ds_bpermute_b32 v229, v84, v225
	ds_bpermute_b32 v230, v84, v226
	ds_bpermute_b32 v231, v84, v227
	s_waitcnt lgkmcnt(0)
	v_add_f32_e32 v224, v224, v228
	v_add_f32_e32 v225, v225, v229
	v_add_f32_e32 v226, v226, v230
	v_add_f32_e32 v227, v227, v231
	ds_bpermute_b32 v228, v85, v224
	ds_bpermute_b32 v229, v85, v225
	ds_bpermute_b32 v230, v85, v226
	ds_bpermute_b32 v231, v85, v227
	s_waitcnt lgkmcnt(0)
	v_add_f32_e32 v224, v224, v228
	v_add_f32_e32 v225, v225, v229
	v_add_f32_e32 v226, v226, v230
	v_add_f32_e32 v227, v227, v231
	ds_bpermute_b32 v228, v86, v224
	ds_bpermute_b32 v229, v86, v225
	ds_bpermute_b32 v230, v86, v226
	ds_bpermute_b32 v231, v86, v227
	s_waitcnt lgkmcnt(0)
	v_add_f32_e32 v224, v224, v228
	v_add_f32_e32 v225, v225, v229
	v_add_f32_e32 v226, v226, v230
	v_add_f32_e32 v227, v227, v231
	ds_bpermute_b32 v228, v87, v224
	ds_bpermute_b32 v229, v87, v225
	ds_bpermute_b32 v230, v87, v226
	ds_bpermute_b32 v231, v87, v227
	s_waitcnt lgkmcnt(0)
	v_add_f32_e32 v224, v224, v228
	v_add_f32_e32 v225, v225, v229
	v_add_f32_e32 v226, v226, v230
	v_add_f32_e32 v227, v227, v231
	ds_bpermute_b32 v228, v88, v224
	ds_bpermute_b32 v229, v88, v225
	ds_bpermute_b32 v230, v88, v226
	ds_bpermute_b32 v231, v88, v227
	s_waitcnt lgkmcnt(0)
	v_add_f32_e32 v224, v224, v228
	v_add_f32_e32 v225, v225, v229
	v_add_f32_e32 v226, v226, v230
	v_add_f32_e32 v227, v227, v231
	v_fmamk_f32 v240, v224, 0x3a800000, v89
	v_mul_f32_e32 v241, 0x4f800000, v240
	v_cmp_gt_f32_e32 vcc, s54, v240
	s_nop 1
	v_cndmask_b32_e32 v247, v240, v241, vcc
	v_sqrt_f32_e32 v242, v247
	s_nop 1
	v_add_u32_e32 v243, -1, v242
	v_add_u32_e32 v244, 1, v242
	v_fma_f32 v245, -v243, v242, v247
	v_fma_f32 v246, -v244, v242, v247
	v_cmp_ge_f32_e64 s[52:53], 0, v245
	s_nop 1
	v_cndmask_b32_e64 v242, v242, v243, s[52:53]
	v_cmp_lt_f32_e64 s[52:53], 0, v246
	s_nop 1
	v_cndmask_b32_e64 v242, v242, v244, s[52:53]
	v_mul_f32_e32 v243, 0x37800000, v242
	v_cndmask_b32_e32 v242, v242, v243, vcc
	v_cmp_class_f32_e32 vcc, v247, v90
	s_nop 1
	v_cndmask_b32_e32 v247, v242, v247, vcc
	v_div_scale_f32 v248, s[52:53], v247, v247, 1.0
	v_rcp_f32_e32 v249, v248
	v_div_scale_f32 v228, vcc, 1.0, v247, 1.0
	s_nop 0
	v_fma_f32 v229, -v248, v249, 1.0
	v_fmac_f32_e32 v249, v229, v249
	v_mul_f32_e32 v230, v228, v249
	v_fma_f32 v229, -v248, v230, v228
	v_fmac_f32_e32 v230, v229, v249
	v_fma_f32 v248, -v248, v230, v228
	v_div_fmas_f32 v248, v248, v249, v230
	v_div_fixup_f32 v232, v248, v247, 1.0
	v_fmamk_f32 v240, v225, 0x3a800000, v89
	v_mul_f32_e32 v241, 0x4f800000, v240
	v_cmp_gt_f32_e32 vcc, s54, v240
	s_nop 1
	v_cndmask_b32_e32 v247, v240, v241, vcc
	v_sqrt_f32_e32 v242, v247
	s_nop 1
	v_add_u32_e32 v243, -1, v242
	v_add_u32_e32 v244, 1, v242
	v_fma_f32 v245, -v243, v242, v247
	v_fma_f32 v246, -v244, v242, v247
	v_cmp_ge_f32_e64 s[52:53], 0, v245
	s_nop 1
	v_cndmask_b32_e64 v242, v242, v243, s[52:53]
	v_cmp_lt_f32_e64 s[52:53], 0, v246
	s_nop 1
	v_cndmask_b32_e64 v242, v242, v244, s[52:53]
	v_mul_f32_e32 v243, 0x37800000, v242
	v_cndmask_b32_e32 v242, v242, v243, vcc
	v_cmp_class_f32_e32 vcc, v247, v90
	s_nop 1
	v_cndmask_b32_e32 v247, v242, v247, vcc
	v_div_scale_f32 v248, s[52:53], v247, v247, 1.0
	v_rcp_f32_e32 v249, v248
	v_div_scale_f32 v228, vcc, 1.0, v247, 1.0
	s_nop 0
	v_fma_f32 v229, -v248, v249, 1.0
	v_fmac_f32_e32 v249, v229, v249
	v_mul_f32_e32 v230, v228, v249
	v_fma_f32 v229, -v248, v230, v228
	v_fmac_f32_e32 v230, v229, v249
	v_fma_f32 v248, -v248, v230, v228
	v_div_fmas_f32 v248, v248, v249, v230
	v_div_fixup_f32 v234, v248, v247, 1.0
	v_fmamk_f32 v240, v226, 0x3a800000, v89
	v_mul_f32_e32 v241, 0x4f800000, v240
	v_cmp_gt_f32_e32 vcc, s54, v240
	s_nop 1
	v_cndmask_b32_e32 v247, v240, v241, vcc
	v_sqrt_f32_e32 v242, v247
	s_nop 1
	v_add_u32_e32 v243, -1, v242
	v_add_u32_e32 v244, 1, v242
	v_fma_f32 v245, -v243, v242, v247
	v_fma_f32 v246, -v244, v242, v247
	v_cmp_ge_f32_e64 s[52:53], 0, v245
	s_nop 1
	v_cndmask_b32_e64 v242, v242, v243, s[52:53]
	v_cmp_lt_f32_e64 s[52:53], 0, v246
	s_nop 1
	v_cndmask_b32_e64 v242, v242, v244, s[52:53]
	v_mul_f32_e32 v243, 0x37800000, v242
	v_cndmask_b32_e32 v242, v242, v243, vcc
	v_cmp_class_f32_e32 vcc, v247, v90
	s_nop 1
	v_cndmask_b32_e32 v247, v242, v247, vcc
	v_div_scale_f32 v248, s[52:53], v247, v247, 1.0
	v_rcp_f32_e32 v249, v248
	v_div_scale_f32 v228, vcc, 1.0, v247, 1.0
	s_nop 0
	v_fma_f32 v229, -v248, v249, 1.0
	v_fmac_f32_e32 v249, v229, v249
	v_mul_f32_e32 v230, v228, v249
	v_fma_f32 v229, -v248, v230, v228
	v_fmac_f32_e32 v230, v229, v249
	v_fma_f32 v248, -v248, v230, v228
	v_div_fmas_f32 v248, v248, v249, v230
	v_div_fixup_f32 v236, v248, v247, 1.0
	v_fmamk_f32 v240, v227, 0x3a800000, v89
	v_mul_f32_e32 v241, 0x4f800000, v240
	v_cmp_gt_f32_e32 vcc, s54, v240
	s_nop 1
	v_cndmask_b32_e32 v247, v240, v241, vcc
	v_sqrt_f32_e32 v242, v247
	s_nop 1
	v_add_u32_e32 v243, -1, v242
	v_add_u32_e32 v244, 1, v242
	v_fma_f32 v245, -v243, v242, v247
	v_fma_f32 v246, -v244, v242, v247
	v_cmp_ge_f32_e64 s[52:53], 0, v245
	s_nop 1
	v_cndmask_b32_e64 v242, v242, v243, s[52:53]
	v_cmp_lt_f32_e64 s[52:53], 0, v246
	s_nop 1
	v_cndmask_b32_e64 v242, v242, v244, s[52:53]
	v_mul_f32_e32 v243, 0x37800000, v242
	v_cndmask_b32_e32 v242, v242, v243, vcc
	v_cmp_class_f32_e32 vcc, v247, v90
	s_nop 1
	v_cndmask_b32_e32 v247, v242, v247, vcc
	v_div_scale_f32 v248, s[52:53], v247, v247, 1.0
	v_rcp_f32_e32 v249, v248
	v_div_scale_f32 v228, vcc, 1.0, v247, 1.0
	s_nop 0
	v_fma_f32 v229, -v248, v249, 1.0
	v_fmac_f32_e32 v249, v229, v249
	v_mul_f32_e32 v230, v228, v249
	v_fma_f32 v229, -v248, v230, v228
	v_fmac_f32_e32 v230, v229, v249
	v_fma_f32 v248, -v248, v230, v228
	v_div_fmas_f32 v248, v248, v249, v230
	v_div_fixup_f32 v238, v248, v247, 1.0
	s_waitcnt vmcnt(16)
	v_pk_add_f32 v[160:161], v[160:161], 1.0 op_sel_hi:[1,0]
	v_pk_add_f32 v[162:163], v[162:163], 1.0 op_sel_hi:[1,0]
	v_pk_add_f32 v[164:165], v[164:165], 1.0 op_sel_hi:[1,0]
	v_pk_add_f32 v[166:167], v[166:167], 1.0 op_sel_hi:[1,0]
	v_pk_add_f32 v[168:169], v[168:169], 1.0 op_sel_hi:[1,0]
	v_pk_add_f32 v[170:171], v[170:171], 1.0 op_sel_hi:[1,0]
	v_pk_add_f32 v[172:173], v[172:173], 1.0 op_sel_hi:[1,0]
	v_pk_add_f32 v[174:175], v[174:175], 1.0 op_sel_hi:[1,0]
	v_pk_add_f32 v[192:193], v[192:193], 1.0 op_sel_hi:[1,0]
	v_pk_add_f32 v[194:195], v[194:195], 1.0 op_sel_hi:[1,0]
	v_pk_add_f32 v[196:197], v[196:197], 1.0 op_sel_hi:[1,0]
	v_pk_add_f32 v[198:199], v[198:199], 1.0 op_sel_hi:[1,0]
	v_pk_add_f32 v[200:201], v[200:201], 1.0 op_sel_hi:[1,0]
	v_pk_add_f32 v[202:203], v[202:203], 1.0 op_sel_hi:[1,0]
	v_pk_add_f32 v[204:205], v[204:205], 1.0 op_sel_hi:[1,0]
	v_pk_add_f32 v[206:207], v[206:207], 1.0 op_sel_hi:[1,0]
	s_mov_b64 s[38:39], s[20:21]
	s_add_u32 s40, s20, 0x400000
	s_addc_u32 s41, s21, 0
	s_add_u32 s46, s20, 0x800000
	s_addc_u32 s47, s21, 0
	s_add_u32 s48, s20, 0xc00000
	s_addc_u32 s49, s21, 0
	v_pk_mul_f32 v[0:1], v[0:1], v[232:233] op_sel_hi:[1,0]
	v_pk_mul_f32 v[2:3], v[2:3], v[232:233] op_sel_hi:[1,0]
	v_pk_mul_f32 v[0:1], v[64:65], v[0:1]
	v_pk_mul_f32 v[2:3], v[66:67], v[2:3]
	v_pk_fma_f32 v[0:1], v[160:161], v[0:1], v[176:177]
	v_pk_fma_f32 v[2:3], v[162:163], v[2:3], v[178:179]
	v_cvt_pk_bf16_f32 v244, v0, v1
	v_cvt_pk_bf16_f32 v245, v2, v3
	v_pk_mul_f32 v[4:5], v[4:5], v[232:233] op_sel_hi:[1,0]
	v_pk_mul_f32 v[6:7], v[6:7], v[232:233] op_sel_hi:[1,0]
	v_pk_mul_f32 v[4:5], v[68:69], v[4:5]
	v_pk_mul_f32 v[6:7], v[70:71], v[6:7]
	v_pk_fma_f32 v[4:5], v[164:165], v[4:5], v[180:181]
	v_pk_fma_f32 v[6:7], v[166:167], v[6:7], v[182:183]
	v_cvt_pk_bf16_f32 v246, v4, v5
	v_cvt_pk_bf16_f32 v247, v6, v7
	global_store_dwordx4 v82, v[244:247], s[38:39] offset:0
	v_pk_mul_f32 v[8:9], v[8:9], v[232:233] op_sel_hi:[1,0]
	v_pk_mul_f32 v[10:11], v[10:11], v[232:233] op_sel_hi:[1,0]
	v_pk_mul_f32 v[8:9], v[72:73], v[8:9]
	v_pk_mul_f32 v[10:11], v[74:75], v[10:11]
	v_pk_fma_f32 v[8:9], v[168:169], v[8:9], v[184:185]
	v_pk_fma_f32 v[10:11], v[170:171], v[10:11], v[186:187]
	v_cvt_pk_bf16_f32 v240, v8, v9
	v_cvt_pk_bf16_f32 v241, v10, v11
	v_pk_mul_f32 v[12:13], v[12:13], v[232:233] op_sel_hi:[1,0]
	v_pk_mul_f32 v[14:15], v[14:15], v[232:233] op_sel_hi:[1,0]
	v_pk_mul_f32 v[12:13], v[76:77], v[12:13]
	v_pk_mul_f32 v[14:15], v[78:79], v[14:15]
	v_pk_fma_f32 v[12:13], v[172:173], v[12:13], v[188:189]
	v_pk_fma_f32 v[14:15], v[174:175], v[14:15], v[190:191]
	v_cvt_pk_bf16_f32 v242, v12, v13
	v_cvt_pk_bf16_f32 v243, v14, v15
	global_store_dwordx4 v82, v[240:243], s[38:39] offset:1024
	v_pk_mul_f32 v[16:17], v[16:17], v[234:235] op_sel_hi:[1,0]
	v_pk_mul_f32 v[18:19], v[18:19], v[234:235] op_sel_hi:[1,0]
	v_pk_mul_f32 v[16:17], v[64:65], v[16:17]
	v_pk_mul_f32 v[18:19], v[66:67], v[18:19]
	v_pk_fma_f32 v[16:17], v[160:161], v[16:17], v[176:177]
	v_pk_fma_f32 v[18:19], v[162:163], v[18:19], v[178:179]
	v_cvt_pk_bf16_f32 v244, v16, v17
	v_cvt_pk_bf16_f32 v245, v18, v19
	v_pk_mul_f32 v[20:21], v[20:21], v[234:235] op_sel_hi:[1,0]
	v_pk_mul_f32 v[22:23], v[22:23], v[234:235] op_sel_hi:[1,0]
	v_pk_mul_f32 v[20:21], v[68:69], v[20:21]
	v_pk_mul_f32 v[22:23], v[70:71], v[22:23]
	v_pk_fma_f32 v[20:21], v[164:165], v[20:21], v[180:181]
	v_pk_fma_f32 v[22:23], v[166:167], v[22:23], v[182:183]
	v_cvt_pk_bf16_f32 v246, v20, v21
	v_cvt_pk_bf16_f32 v247, v22, v23
	global_store_dwordx4 v82, v[244:247], s[40:41] offset:0
	v_pk_mul_f32 v[24:25], v[24:25], v[234:235] op_sel_hi:[1,0]
	v_pk_mul_f32 v[26:27], v[26:27], v[234:235] op_sel_hi:[1,0]
	v_pk_mul_f32 v[24:25], v[72:73], v[24:25]
	v_pk_mul_f32 v[26:27], v[74:75], v[26:27]
	v_pk_fma_f32 v[24:25], v[168:169], v[24:25], v[184:185]
	v_pk_fma_f32 v[26:27], v[170:171], v[26:27], v[186:187]
	v_cvt_pk_bf16_f32 v240, v24, v25
	v_cvt_pk_bf16_f32 v241, v26, v27
	v_pk_mul_f32 v[28:29], v[28:29], v[234:235] op_sel_hi:[1,0]
	v_pk_mul_f32 v[30:31], v[30:31], v[234:235] op_sel_hi:[1,0]
	v_pk_mul_f32 v[28:29], v[76:77], v[28:29]
	v_pk_mul_f32 v[30:31], v[78:79], v[30:31]
	v_pk_fma_f32 v[28:29], v[172:173], v[28:29], v[188:189]
	v_pk_fma_f32 v[30:31], v[174:175], v[30:31], v[190:191]
	v_cvt_pk_bf16_f32 v242, v28, v29
	v_cvt_pk_bf16_f32 v243, v30, v31
	global_store_dwordx4 v82, v[240:243], s[40:41] offset:1024
	v_pk_mul_f32 v[32:33], v[32:33], v[236:237] op_sel_hi:[1,0]
	v_pk_mul_f32 v[34:35], v[34:35], v[236:237] op_sel_hi:[1,0]
	v_pk_mul_f32 v[32:33], v[64:65], v[32:33]
	v_pk_mul_f32 v[34:35], v[66:67], v[34:35]
	v_pk_fma_f32 v[32:33], v[192:193], v[32:33], v[208:209]
	v_pk_fma_f32 v[34:35], v[194:195], v[34:35], v[210:211]
	v_cvt_pk_bf16_f32 v244, v32, v33
	v_cvt_pk_bf16_f32 v245, v34, v35
	v_pk_mul_f32 v[36:37], v[36:37], v[236:237] op_sel_hi:[1,0]
	v_pk_mul_f32 v[38:39], v[38:39], v[236:237] op_sel_hi:[1,0]
	v_pk_mul_f32 v[36:37], v[68:69], v[36:37]
	v_pk_mul_f32 v[38:39], v[70:71], v[38:39]
	v_pk_fma_f32 v[36:37], v[196:197], v[36:37], v[212:213]
	v_pk_fma_f32 v[38:39], v[198:199], v[38:39], v[214:215]
	v_cvt_pk_bf16_f32 v246, v36, v37
	v_cvt_pk_bf16_f32 v247, v38, v39
	global_store_dwordx4 v82, v[244:247], s[46:47] offset:0
	v_pk_mul_f32 v[40:41], v[40:41], v[236:237] op_sel_hi:[1,0]
	v_pk_mul_f32 v[42:43], v[42:43], v[236:237] op_sel_hi:[1,0]
	v_pk_mul_f32 v[40:41], v[72:73], v[40:41]
	v_pk_mul_f32 v[42:43], v[74:75], v[42:43]
	v_pk_fma_f32 v[40:41], v[200:201], v[40:41], v[216:217]
	v_pk_fma_f32 v[42:43], v[202:203], v[42:43], v[218:219]
	v_cvt_pk_bf16_f32 v240, v40, v41
	v_cvt_pk_bf16_f32 v241, v42, v43
	v_pk_mul_f32 v[44:45], v[44:45], v[236:237] op_sel_hi:[1,0]
	v_pk_mul_f32 v[46:47], v[46:47], v[236:237] op_sel_hi:[1,0]
	v_pk_mul_f32 v[44:45], v[76:77], v[44:45]
	v_pk_mul_f32 v[46:47], v[78:79], v[46:47]
	v_pk_fma_f32 v[44:45], v[204:205], v[44:45], v[220:221]
	v_pk_fma_f32 v[46:47], v[206:207], v[46:47], v[222:223]
	v_cvt_pk_bf16_f32 v242, v44, v45
	v_cvt_pk_bf16_f32 v243, v46, v47
	global_store_dwordx4 v82, v[240:243], s[46:47] offset:1024
	v_pk_mul_f32 v[48:49], v[48:49], v[238:239] op_sel_hi:[1,0]
	v_pk_mul_f32 v[50:51], v[50:51], v[238:239] op_sel_hi:[1,0]
	v_pk_mul_f32 v[48:49], v[64:65], v[48:49]
	v_pk_mul_f32 v[50:51], v[66:67], v[50:51]
	v_pk_fma_f32 v[48:49], v[192:193], v[48:49], v[208:209]
	v_pk_fma_f32 v[50:51], v[194:195], v[50:51], v[210:211]
	v_cvt_pk_bf16_f32 v244, v48, v49
	v_cvt_pk_bf16_f32 v245, v50, v51
	v_pk_mul_f32 v[52:53], v[52:53], v[238:239] op_sel_hi:[1,0]
	v_pk_mul_f32 v[54:55], v[54:55], v[238:239] op_sel_hi:[1,0]
	v_pk_mul_f32 v[52:53], v[68:69], v[52:53]
	v_pk_mul_f32 v[54:55], v[70:71], v[54:55]
	v_pk_fma_f32 v[52:53], v[196:197], v[52:53], v[212:213]
	v_pk_fma_f32 v[54:55], v[198:199], v[54:55], v[214:215]
	v_cvt_pk_bf16_f32 v246, v52, v53
	v_cvt_pk_bf16_f32 v247, v54, v55
	global_store_dwordx4 v82, v[244:247], s[48:49] offset:0
	v_pk_mul_f32 v[56:57], v[56:57], v[238:239] op_sel_hi:[1,0]
	v_pk_mul_f32 v[58:59], v[58:59], v[238:239] op_sel_hi:[1,0]
	v_pk_mul_f32 v[56:57], v[72:73], v[56:57]
	v_pk_mul_f32 v[58:59], v[74:75], v[58:59]
	v_pk_fma_f32 v[56:57], v[200:201], v[56:57], v[216:217]
	v_pk_fma_f32 v[58:59], v[202:203], v[58:59], v[218:219]
	v_cvt_pk_bf16_f32 v240, v56, v57
	v_cvt_pk_bf16_f32 v241, v58, v59
	v_pk_mul_f32 v[60:61], v[60:61], v[238:239] op_sel_hi:[1,0]
	v_pk_mul_f32 v[62:63], v[62:63], v[238:239] op_sel_hi:[1,0]
	v_pk_mul_f32 v[60:61], v[76:77], v[60:61]
	v_pk_mul_f32 v[62:63], v[78:79], v[62:63]
	v_pk_fma_f32 v[60:61], v[204:205], v[60:61], v[220:221]
	v_pk_fma_f32 v[62:63], v[206:207], v[62:63], v[222:223]
	v_cvt_pk_bf16_f32 v242, v60, v61
	v_cvt_pk_bf16_f32 v243, v62, v63
	global_store_dwordx4 v82, v[240:243], s[48:49] offset:1024
	s_add_u32 s34, s8, 0x6000
	s_addc_u32 s35, s9, 0
	s_add_u32 s36, s8, 0x6000
	s_addc_u32 s37, s9, 0
	global_load_dwordx4 v[176:179], v80, s[34:35] offset:0
	global_load_dwordx4 v[180:183], v80, s[34:35] offset:16
	global_load_dwordx4 v[184:187], v80, s[34:35] offset:2048
	global_load_dwordx4 v[188:191], v80, s[34:35] offset:2064
	global_load_dwordx4 v[160:163], v81, s[34:35] offset:0
	global_load_dwordx4 v[164:167], v81, s[34:35] offset:16
	global_load_dwordx4 v[168:171], v81, s[34:35] offset:2048
	global_load_dwordx4 v[172:175], v81, s[34:35] offset:2064
	global_load_dwordx4 v[208:211], v80, s[36:37] offset:0
	global_load_dwordx4 v[212:215], v80, s[36:37] offset:16
	global_load_dwordx4 v[216:219], v80, s[36:37] offset:2048
	global_load_dwordx4 v[220:223], v80, s[36:37] offset:2064
	global_load_dwordx4 v[192:195], v81, s[36:37] offset:0
	global_load_dwordx4 v[196:199], v81, s[36:37] offset:16
	global_load_dwordx4 v[200:203], v81, s[36:37] offset:2048
	global_load_dwordx4 v[204:207], v81, s[36:37] offset:2064
	s_add_u32 s24, s16, 0x4000000
	s_addc_u32 s25, s17, 0
	s_add_u32 s26, s16, 0x4800000
	s_addc_u32 s27, s17, 0
	s_add_u32 s28, s16, 0x5000000
	s_addc_u32 s29, s17, 0
	s_add_u32 s30, s16, 0x5800000
	s_addc_u32 s31, s17, 0
	global_load_dwordx4 v[0:3], v80, s[24:25] offset:0
	global_load_dwordx4 v[4:7], v80, s[24:25] offset:16
	global_load_dwordx4 v[8:11], v80, s[24:25] offset:2048
	global_load_dwordx4 v[12:15], v80, s[24:25] offset:2064
	global_load_dwordx4 v[16:19], v80, s[26:27] offset:0
	global_load_dwordx4 v[20:23], v80, s[26:27] offset:16
	global_load_dwordx4 v[24:27], v80, s[26:27] offset:2048
	global_load_dwordx4 v[28:31], v80, s[26:27] offset:2064
	global_load_dwordx4 v[32:35], v80, s[28:29] offset:0
	global_load_dwordx4 v[36:39], v80, s[28:29] offset:16
	global_load_dwordx4 v[40:43], v80, s[28:29] offset:2048
	global_load_dwordx4 v[44:47], v80, s[28:29] offset:2064
	global_load_dwordx4 v[48:51], v80, s[30:31] offset:0
	global_load_dwordx4 v[52:55], v80, s[30:31] offset:16
	global_load_dwordx4 v[56:59], v80, s[30:31] offset:2048
	global_load_dwordx4 v[60:63], v80, s[30:31] offset:2064
	s_waitcnt vmcnt(40)
	v_pk_mul_f32 v[240:241], v[96:97], v[96:97]
	v_pk_mul_f32 v[242:243], v[112:113], v[112:113]
	v_pk_mul_f32 v[244:245], v[128:129], v[128:129]
	v_pk_mul_f32 v[246:247], v[144:145], v[144:145]
	v_pk_fma_f32 v[240:241], v[98:99], v[98:99], v[240:241]
	v_pk_fma_f32 v[242:243], v[114:115], v[114:115], v[242:243]
	v_pk_fma_f32 v[244:245], v[130:131], v[130:131], v[244:245]
	v_pk_fma_f32 v[246:247], v[146:147], v[146:147], v[246:247]
	v_pk_fma_f32 v[240:241], v[100:101], v[100:101], v[240:241]
	v_pk_fma_f32 v[242:243], v[116:117], v[116:117], v[242:243]
	v_pk_fma_f32 v[244:245], v[132:133], v[132:133], v[244:245]
	v_pk_fma_f32 v[246:247], v[148:149], v[148:149], v[246:247]
	v_pk_fma_f32 v[240:241], v[102:103], v[102:103], v[240:241]
	v_pk_fma_f32 v[242:243], v[118:119], v[118:119], v[242:243]
	v_pk_fma_f32 v[244:245], v[134:135], v[134:135], v[244:245]
	v_pk_fma_f32 v[246:247], v[150:151], v[150:151], v[246:247]
	v_pk_fma_f32 v[240:241], v[104:105], v[104:105], v[240:241]
	v_pk_fma_f32 v[242:243], v[120:121], v[120:121], v[242:243]
	v_pk_fma_f32 v[244:245], v[136:137], v[136:137], v[244:245]
	v_pk_fma_f32 v[246:247], v[152:153], v[152:153], v[246:247]
	v_pk_fma_f32 v[240:241], v[106:107], v[106:107], v[240:241]
	v_pk_fma_f32 v[242:243], v[122:123], v[122:123], v[242:243]
	v_pk_fma_f32 v[244:245], v[138:139], v[138:139], v[244:245]
	v_pk_fma_f32 v[246:247], v[154:155], v[154:155], v[246:247]
	v_pk_fma_f32 v[240:241], v[108:109], v[108:109], v[240:241]
	v_pk_fma_f32 v[242:243], v[124:125], v[124:125], v[242:243]
	v_pk_fma_f32 v[244:245], v[140:141], v[140:141], v[244:245]
	v_pk_fma_f32 v[246:247], v[156:157], v[156:157], v[246:247]
	v_pk_fma_f32 v[240:241], v[110:111], v[110:111], v[240:241]
	v_pk_fma_f32 v[242:243], v[126:127], v[126:127], v[242:243]
	v_pk_fma_f32 v[244:245], v[142:143], v[142:143], v[244:245]
	v_pk_fma_f32 v[246:247], v[158:159], v[158:159], v[246:247]
	v_add_f32_e32 v224, v240, v241
	v_add_f32_e32 v225, v242, v243
	v_add_f32_e32 v226, v244, v245
	v_add_f32_e32 v227, v246, v247
	ds_bpermute_b32 v228, v83, v224
	ds_bpermute_b32 v229, v83, v225
	ds_bpermute_b32 v230, v83, v226
	ds_bpermute_b32 v231, v83, v227
	s_waitcnt lgkmcnt(0)
	v_add_f32_e32 v224, v224, v228
	v_add_f32_e32 v225, v225, v229
	v_add_f32_e32 v226, v226, v230
	v_add_f32_e32 v227, v227, v231
	ds_bpermute_b32 v228, v84, v224
	ds_bpermute_b32 v229, v84, v225
	ds_bpermute_b32 v230, v84, v226
	ds_bpermute_b32 v231, v84, v227
	s_waitcnt lgkmcnt(0)
	v_add_f32_e32 v224, v224, v228
	v_add_f32_e32 v225, v225, v229
	v_add_f32_e32 v226, v226, v230
	v_add_f32_e32 v227, v227, v231
	ds_bpermute_b32 v228, v85, v224
	ds_bpermute_b32 v229, v85, v225
	ds_bpermute_b32 v230, v85, v226
	ds_bpermute_b32 v231, v85, v227
	s_waitcnt lgkmcnt(0)
	v_add_f32_e32 v224, v224, v228
	v_add_f32_e32 v225, v225, v229
	v_add_f32_e32 v226, v226, v230
	v_add_f32_e32 v227, v227, v231
	ds_bpermute_b32 v228, v86, v224
	ds_bpermute_b32 v229, v86, v225
	ds_bpermute_b32 v230, v86, v226
	ds_bpermute_b32 v231, v86, v227
	s_waitcnt lgkmcnt(0)
	v_add_f32_e32 v224, v224, v228
	v_add_f32_e32 v225, v225, v229
	v_add_f32_e32 v226, v226, v230
	v_add_f32_e32 v227, v227, v231
	ds_bpermute_b32 v228, v87, v224
	ds_bpermute_b32 v229, v87, v225
	ds_bpermute_b32 v230, v87, v226
	ds_bpermute_b32 v231, v87, v227
	s_waitcnt lgkmcnt(0)
	v_add_f32_e32 v224, v224, v228
	v_add_f32_e32 v225, v225, v229
	v_add_f32_e32 v226, v226, v230
	v_add_f32_e32 v227, v227, v231
	ds_bpermute_b32 v228, v88, v224
	ds_bpermute_b32 v229, v88, v225
	ds_bpermute_b32 v230, v88, v226
	ds_bpermute_b32 v231, v88, v227
	s_waitcnt lgkmcnt(0)
	v_add_f32_e32 v224, v224, v228
	v_add_f32_e32 v225, v225, v229
	v_add_f32_e32 v226, v226, v230
	v_add_f32_e32 v227, v227, v231
	v_fmamk_f32 v240, v224, 0x3a800000, v89
	v_mul_f32_e32 v241, 0x4f800000, v240
	v_cmp_gt_f32_e32 vcc, s54, v240
	s_nop 1
	v_cndmask_b32_e32 v247, v240, v241, vcc
	v_sqrt_f32_e32 v242, v247
	s_nop 1
	v_add_u32_e32 v243, -1, v242
	v_add_u32_e32 v244, 1, v242
	v_fma_f32 v245, -v243, v242, v247
	v_fma_f32 v246, -v244, v242, v247
	v_cmp_ge_f32_e64 s[52:53], 0, v245
	s_nop 1
	v_cndmask_b32_e64 v242, v242, v243, s[52:53]
	v_cmp_lt_f32_e64 s[52:53], 0, v246
	s_nop 1
	v_cndmask_b32_e64 v242, v242, v244, s[52:53]
	v_mul_f32_e32 v243, 0x37800000, v242
	v_cndmask_b32_e32 v242, v242, v243, vcc
	v_cmp_class_f32_e32 vcc, v247, v90
	s_nop 1
	v_cndmask_b32_e32 v247, v242, v247, vcc
	v_div_scale_f32 v248, s[52:53], v247, v247, 1.0
	v_rcp_f32_e32 v249, v248
	v_div_scale_f32 v228, vcc, 1.0, v247, 1.0
	s_nop 0
	v_fma_f32 v229, -v248, v249, 1.0
	v_fmac_f32_e32 v249, v229, v249
	v_mul_f32_e32 v230, v228, v249
	v_fma_f32 v229, -v248, v230, v228
	v_fmac_f32_e32 v230, v229, v249
	v_fma_f32 v248, -v248, v230, v228
	v_div_fmas_f32 v248, v248, v249, v230
	v_div_fixup_f32 v232, v248, v247, 1.0
	v_fmamk_f32 v240, v225, 0x3a800000, v89
	v_mul_f32_e32 v241, 0x4f800000, v240
	v_cmp_gt_f32_e32 vcc, s54, v240
	s_nop 1
	v_cndmask_b32_e32 v247, v240, v241, vcc
	v_sqrt_f32_e32 v242, v247
	s_nop 1
	v_add_u32_e32 v243, -1, v242
	v_add_u32_e32 v244, 1, v242
	v_fma_f32 v245, -v243, v242, v247
	v_fma_f32 v246, -v244, v242, v247
	v_cmp_ge_f32_e64 s[52:53], 0, v245
	s_nop 1
	v_cndmask_b32_e64 v242, v242, v243, s[52:53]
	v_cmp_lt_f32_e64 s[52:53], 0, v246
	s_nop 1
	v_cndmask_b32_e64 v242, v242, v244, s[52:53]
	v_mul_f32_e32 v243, 0x37800000, v242
	v_cndmask_b32_e32 v242, v242, v243, vcc
	v_cmp_class_f32_e32 vcc, v247, v90
	s_nop 1
	v_cndmask_b32_e32 v247, v242, v247, vcc
	v_div_scale_f32 v248, s[52:53], v247, v247, 1.0
	v_rcp_f32_e32 v249, v248
	v_div_scale_f32 v228, vcc, 1.0, v247, 1.0
	s_nop 0
	v_fma_f32 v229, -v248, v249, 1.0
	v_fmac_f32_e32 v249, v229, v249
	v_mul_f32_e32 v230, v228, v249
	v_fma_f32 v229, -v248, v230, v228
	v_fmac_f32_e32 v230, v229, v249
	v_fma_f32 v248, -v248, v230, v228
	v_div_fmas_f32 v248, v248, v249, v230
	v_div_fixup_f32 v234, v248, v247, 1.0
	v_fmamk_f32 v240, v226, 0x3a800000, v89
	v_mul_f32_e32 v241, 0x4f800000, v240
	v_cmp_gt_f32_e32 vcc, s54, v240
	s_nop 1
	v_cndmask_b32_e32 v247, v240, v241, vcc
	v_sqrt_f32_e32 v242, v247
	s_nop 1
	v_add_u32_e32 v243, -1, v242
	v_add_u32_e32 v244, 1, v242
	v_fma_f32 v245, -v243, v242, v247
	v_fma_f32 v246, -v244, v242, v247
	v_cmp_ge_f32_e64 s[52:53], 0, v245
	s_nop 1
	v_cndmask_b32_e64 v242, v242, v243, s[52:53]
	v_cmp_lt_f32_e64 s[52:53], 0, v246
	s_nop 1
	v_cndmask_b32_e64 v242, v242, v244, s[52:53]
	v_mul_f32_e32 v243, 0x37800000, v242
	v_cndmask_b32_e32 v242, v242, v243, vcc
	v_cmp_class_f32_e32 vcc, v247, v90
	s_nop 1
	v_cndmask_b32_e32 v247, v242, v247, vcc
	v_div_scale_f32 v248, s[52:53], v247, v247, 1.0
	v_rcp_f32_e32 v249, v248
	v_div_scale_f32 v228, vcc, 1.0, v247, 1.0
	s_nop 0
	v_fma_f32 v229, -v248, v249, 1.0
	v_fmac_f32_e32 v249, v229, v249
	v_mul_f32_e32 v230, v228, v249
	v_fma_f32 v229, -v248, v230, v228
	v_fmac_f32_e32 v230, v229, v249
	v_fma_f32 v248, -v248, v230, v228
	v_div_fmas_f32 v248, v248, v249, v230
	v_div_fixup_f32 v236, v248, v247, 1.0
	v_fmamk_f32 v240, v227, 0x3a800000, v89
	v_mul_f32_e32 v241, 0x4f800000, v240
	v_cmp_gt_f32_e32 vcc, s54, v240
	s_nop 1
	v_cndmask_b32_e32 v247, v240, v241, vcc
	v_sqrt_f32_e32 v242, v247
	s_nop 1
	v_add_u32_e32 v243, -1, v242
	v_add_u32_e32 v244, 1, v242
	v_fma_f32 v245, -v243, v242, v247
	v_fma_f32 v246, -v244, v242, v247
	v_cmp_ge_f32_e64 s[52:53], 0, v245
	s_nop 1
	v_cndmask_b32_e64 v242, v242, v243, s[52:53]
	v_cmp_lt_f32_e64 s[52:53], 0, v246
	s_nop 1
	v_cndmask_b32_e64 v242, v242, v244, s[52:53]
	v_mul_f32_e32 v243, 0x37800000, v242
	v_cndmask_b32_e32 v242, v242, v243, vcc
	v_cmp_class_f32_e32 vcc, v247, v90
	s_nop 1
	v_cndmask_b32_e32 v247, v242, v247, vcc
	v_div_scale_f32 v248, s[52:53], v247, v247, 1.0
	v_rcp_f32_e32 v249, v248
	v_div_scale_f32 v228, vcc, 1.0, v247, 1.0
	s_nop 0
	v_fma_f32 v229, -v248, v249, 1.0
	v_fmac_f32_e32 v249, v229, v249
	v_mul_f32_e32 v230, v228, v249
	v_fma_f32 v229, -v248, v230, v228
	v_fmac_f32_e32 v230, v229, v249
	v_fma_f32 v248, -v248, v230, v228
	v_div_fmas_f32 v248, v248, v249, v230
	v_div_fixup_f32 v238, v248, v247, 1.0
	s_waitcnt vmcnt(16)
	v_pk_add_f32 v[160:161], v[160:161], 1.0 op_sel_hi:[1,0]
	v_pk_add_f32 v[162:163], v[162:163], 1.0 op_sel_hi:[1,0]
	v_pk_add_f32 v[164:165], v[164:165], 1.0 op_sel_hi:[1,0]
	v_pk_add_f32 v[166:167], v[166:167], 1.0 op_sel_hi:[1,0]
	v_pk_add_f32 v[168:169], v[168:169], 1.0 op_sel_hi:[1,0]
	v_pk_add_f32 v[170:171], v[170:171], 1.0 op_sel_hi:[1,0]
	v_pk_add_f32 v[172:173], v[172:173], 1.0 op_sel_hi:[1,0]
	v_pk_add_f32 v[174:175], v[174:175], 1.0 op_sel_hi:[1,0]
	v_pk_add_f32 v[192:193], v[192:193], 1.0 op_sel_hi:[1,0]
	v_pk_add_f32 v[194:195], v[194:195], 1.0 op_sel_hi:[1,0]
	v_pk_add_f32 v[196:197], v[196:197], 1.0 op_sel_hi:[1,0]
	v_pk_add_f32 v[198:199], v[198:199], 1.0 op_sel_hi:[1,0]
	v_pk_add_f32 v[200:201], v[200:201], 1.0 op_sel_hi:[1,0]
	v_pk_add_f32 v[202:203], v[202:203], 1.0 op_sel_hi:[1,0]
	v_pk_add_f32 v[204:205], v[204:205], 1.0 op_sel_hi:[1,0]
	v_pk_add_f32 v[206:207], v[206:207], 1.0 op_sel_hi:[1,0]
	s_add_u32 s38, s20, 0x1000000
	s_addc_u32 s39, s21, 0
	s_add_u32 s40, s20, 0x1400000
	s_addc_u32 s41, s21, 0
	s_add_u32 s46, s20, 0x1800000
	s_addc_u32 s47, s21, 0
	s_add_u32 s48, s20, 0x1c00000
	s_addc_u32 s49, s21, 0
	v_pk_mul_f32 v[96:97], v[96:97], v[232:233] op_sel_hi:[1,0]
	v_pk_mul_f32 v[98:99], v[98:99], v[232:233] op_sel_hi:[1,0]
	v_pk_mul_f32 v[96:97], v[64:65], v[96:97]
	v_pk_mul_f32 v[98:99], v[66:67], v[98:99]
	v_pk_fma_f32 v[96:97], v[160:161], v[96:97], v[176:177]
	v_pk_fma_f32 v[98:99], v[162:163], v[98:99], v[178:179]
	v_cvt_pk_bf16_f32 v244, v96, v97
	v_cvt_pk_bf16_f32 v245, v98, v99
	v_pk_mul_f32 v[100:101], v[100:101], v[232:233] op_sel_hi:[1,0]
	v_pk_mul_f32 v[102:103], v[102:103], v[232:233] op_sel_hi:[1,0]
	v_pk_mul_f32 v[100:101], v[68:69], v[100:101]
	v_pk_mul_f32 v[102:103], v[70:71], v[102:103]
	v_pk_fma_f32 v[100:101], v[164:165], v[100:101], v[180:181]
	v_pk_fma_f32 v[102:103], v[166:167], v[102:103], v[182:183]
	v_cvt_pk_bf16_f32 v246, v100, v101
	v_cvt_pk_bf16_f32 v247, v102, v103
	global_store_dwordx4 v82, v[244:247], s[38:39] offset:0
	v_pk_mul_f32 v[104:105], v[104:105], v[232:233] op_sel_hi:[1,0]
	v_pk_mul_f32 v[106:107], v[106:107], v[232:233] op_sel_hi:[1,0]
	v_pk_mul_f32 v[104:105], v[72:73], v[104:105]
	v_pk_mul_f32 v[106:107], v[74:75], v[106:107]
	v_pk_fma_f32 v[104:105], v[168:169], v[104:105], v[184:185]
	v_pk_fma_f32 v[106:107], v[170:171], v[106:107], v[186:187]
	v_cvt_pk_bf16_f32 v240, v104, v105
	v_cvt_pk_bf16_f32 v241, v106, v107
	v_pk_mul_f32 v[108:109], v[108:109], v[232:233] op_sel_hi:[1,0]
	v_pk_mul_f32 v[110:111], v[110:111], v[232:233] op_sel_hi:[1,0]
	v_pk_mul_f32 v[108:109], v[76:77], v[108:109]
	v_pk_mul_f32 v[110:111], v[78:79], v[110:111]
	v_pk_fma_f32 v[108:109], v[172:173], v[108:109], v[188:189]
	v_pk_fma_f32 v[110:111], v[174:175], v[110:111], v[190:191]
	v_cvt_pk_bf16_f32 v242, v108, v109
	v_cvt_pk_bf16_f32 v243, v110, v111
	global_store_dwordx4 v82, v[240:243], s[38:39] offset:1024
	v_pk_mul_f32 v[112:113], v[112:113], v[234:235] op_sel_hi:[1,0]
	v_pk_mul_f32 v[114:115], v[114:115], v[234:235] op_sel_hi:[1,0]
	v_pk_mul_f32 v[112:113], v[64:65], v[112:113]
	v_pk_mul_f32 v[114:115], v[66:67], v[114:115]
	v_pk_fma_f32 v[112:113], v[160:161], v[112:113], v[176:177]
	v_pk_fma_f32 v[114:115], v[162:163], v[114:115], v[178:179]
	v_cvt_pk_bf16_f32 v244, v112, v113
	v_cvt_pk_bf16_f32 v245, v114, v115
	v_pk_mul_f32 v[116:117], v[116:117], v[234:235] op_sel_hi:[1,0]
	v_pk_mul_f32 v[118:119], v[118:119], v[234:235] op_sel_hi:[1,0]
	v_pk_mul_f32 v[116:117], v[68:69], v[116:117]
	v_pk_mul_f32 v[118:119], v[70:71], v[118:119]
	v_pk_fma_f32 v[116:117], v[164:165], v[116:117], v[180:181]
	v_pk_fma_f32 v[118:119], v[166:167], v[118:119], v[182:183]
	v_cvt_pk_bf16_f32 v246, v116, v117
	v_cvt_pk_bf16_f32 v247, v118, v119
	global_store_dwordx4 v82, v[244:247], s[40:41] offset:0
	v_pk_mul_f32 v[120:121], v[120:121], v[234:235] op_sel_hi:[1,0]
	v_pk_mul_f32 v[122:123], v[122:123], v[234:235] op_sel_hi:[1,0]
	v_pk_mul_f32 v[120:121], v[72:73], v[120:121]
	v_pk_mul_f32 v[122:123], v[74:75], v[122:123]
	v_pk_fma_f32 v[120:121], v[168:169], v[120:121], v[184:185]
	v_pk_fma_f32 v[122:123], v[170:171], v[122:123], v[186:187]
	v_cvt_pk_bf16_f32 v240, v120, v121
	v_cvt_pk_bf16_f32 v241, v122, v123
	v_pk_mul_f32 v[124:125], v[124:125], v[234:235] op_sel_hi:[1,0]
	v_pk_mul_f32 v[126:127], v[126:127], v[234:235] op_sel_hi:[1,0]
	v_pk_mul_f32 v[124:125], v[76:77], v[124:125]
	v_pk_mul_f32 v[126:127], v[78:79], v[126:127]
	v_pk_fma_f32 v[124:125], v[172:173], v[124:125], v[188:189]
	v_pk_fma_f32 v[126:127], v[174:175], v[126:127], v[190:191]
	v_cvt_pk_bf16_f32 v242, v124, v125
	v_cvt_pk_bf16_f32 v243, v126, v127
	global_store_dwordx4 v82, v[240:243], s[40:41] offset:1024
	v_pk_mul_f32 v[128:129], v[128:129], v[236:237] op_sel_hi:[1,0]
	v_pk_mul_f32 v[130:131], v[130:131], v[236:237] op_sel_hi:[1,0]
	v_pk_mul_f32 v[128:129], v[64:65], v[128:129]
	v_pk_mul_f32 v[130:131], v[66:67], v[130:131]
	v_pk_fma_f32 v[128:129], v[192:193], v[128:129], v[208:209]
	v_pk_fma_f32 v[130:131], v[194:195], v[130:131], v[210:211]
	v_cvt_pk_bf16_f32 v244, v128, v129
	v_cvt_pk_bf16_f32 v245, v130, v131
	v_pk_mul_f32 v[132:133], v[132:133], v[236:237] op_sel_hi:[1,0]
	v_pk_mul_f32 v[134:135], v[134:135], v[236:237] op_sel_hi:[1,0]
	v_pk_mul_f32 v[132:133], v[68:69], v[132:133]
	v_pk_mul_f32 v[134:135], v[70:71], v[134:135]
	v_pk_fma_f32 v[132:133], v[196:197], v[132:133], v[212:213]
	v_pk_fma_f32 v[134:135], v[198:199], v[134:135], v[214:215]
	v_cvt_pk_bf16_f32 v246, v132, v133
	v_cvt_pk_bf16_f32 v247, v134, v135
	global_store_dwordx4 v82, v[244:247], s[46:47] offset:0
	v_pk_mul_f32 v[136:137], v[136:137], v[236:237] op_sel_hi:[1,0]
	v_pk_mul_f32 v[138:139], v[138:139], v[236:237] op_sel_hi:[1,0]
	v_pk_mul_f32 v[136:137], v[72:73], v[136:137]
	v_pk_mul_f32 v[138:139], v[74:75], v[138:139]
	v_pk_fma_f32 v[136:137], v[200:201], v[136:137], v[216:217]
	v_pk_fma_f32 v[138:139], v[202:203], v[138:139], v[218:219]
	v_cvt_pk_bf16_f32 v240, v136, v137
	v_cvt_pk_bf16_f32 v241, v138, v139
	v_pk_mul_f32 v[140:141], v[140:141], v[236:237] op_sel_hi:[1,0]
	v_pk_mul_f32 v[142:143], v[142:143], v[236:237] op_sel_hi:[1,0]
	v_pk_mul_f32 v[140:141], v[76:77], v[140:141]
	v_pk_mul_f32 v[142:143], v[78:79], v[142:143]
	v_pk_fma_f32 v[140:141], v[204:205], v[140:141], v[220:221]
	v_pk_fma_f32 v[142:143], v[206:207], v[142:143], v[222:223]
	v_cvt_pk_bf16_f32 v242, v140, v141
	v_cvt_pk_bf16_f32 v243, v142, v143
	global_store_dwordx4 v82, v[240:243], s[46:47] offset:1024
	v_pk_mul_f32 v[144:145], v[144:145], v[238:239] op_sel_hi:[1,0]
	v_pk_mul_f32 v[146:147], v[146:147], v[238:239] op_sel_hi:[1,0]
	v_pk_mul_f32 v[144:145], v[64:65], v[144:145]
	v_pk_mul_f32 v[146:147], v[66:67], v[146:147]
	v_pk_fma_f32 v[144:145], v[192:193], v[144:145], v[208:209]
	v_pk_fma_f32 v[146:147], v[194:195], v[146:147], v[210:211]
	v_cvt_pk_bf16_f32 v244, v144, v145
	v_cvt_pk_bf16_f32 v245, v146, v147
	v_pk_mul_f32 v[148:149], v[148:149], v[238:239] op_sel_hi:[1,0]
	v_pk_mul_f32 v[150:151], v[150:151], v[238:239] op_sel_hi:[1,0]
	v_pk_mul_f32 v[148:149], v[68:69], v[148:149]
	v_pk_mul_f32 v[150:151], v[70:71], v[150:151]
	v_pk_fma_f32 v[148:149], v[196:197], v[148:149], v[212:213]
	v_pk_fma_f32 v[150:151], v[198:199], v[150:151], v[214:215]
	v_cvt_pk_bf16_f32 v246, v148, v149
	v_cvt_pk_bf16_f32 v247, v150, v151
	global_store_dwordx4 v82, v[244:247], s[48:49] offset:0
	v_pk_mul_f32 v[152:153], v[152:153], v[238:239] op_sel_hi:[1,0]
	v_pk_mul_f32 v[154:155], v[154:155], v[238:239] op_sel_hi:[1,0]
	v_pk_mul_f32 v[152:153], v[72:73], v[152:153]
	v_pk_mul_f32 v[154:155], v[74:75], v[154:155]
	v_pk_fma_f32 v[152:153], v[200:201], v[152:153], v[216:217]
	v_pk_fma_f32 v[154:155], v[202:203], v[154:155], v[218:219]
	v_cvt_pk_bf16_f32 v240, v152, v153
	v_cvt_pk_bf16_f32 v241, v154, v155
	v_pk_mul_f32 v[156:157], v[156:157], v[238:239] op_sel_hi:[1,0]
	v_pk_mul_f32 v[158:159], v[158:159], v[238:239] op_sel_hi:[1,0]
	v_pk_mul_f32 v[156:157], v[76:77], v[156:157]
	v_pk_mul_f32 v[158:159], v[78:79], v[158:159]
	v_pk_fma_f32 v[156:157], v[204:205], v[156:157], v[220:221]
	v_pk_fma_f32 v[158:159], v[206:207], v[158:159], v[222:223]
	v_cvt_pk_bf16_f32 v242, v156, v157
	v_cvt_pk_bf16_f32 v243, v158, v159
	global_store_dwordx4 v82, v[240:243], s[48:49] offset:1024
	s_add_u32 s34, s8, 0xc000
	s_addc_u32 s35, s9, 0
	s_add_u32 s36, s8, 0xc000
	s_addc_u32 s37, s9, 0
	global_load_dwordx4 v[176:179], v80, s[34:35] offset:0
	global_load_dwordx4 v[180:183], v80, s[34:35] offset:16
	global_load_dwordx4 v[184:187], v80, s[34:35] offset:2048
	global_load_dwordx4 v[188:191], v80, s[34:35] offset:2064
	global_load_dwordx4 v[160:163], v81, s[34:35] offset:0
	global_load_dwordx4 v[164:167], v81, s[34:35] offset:16
	global_load_dwordx4 v[168:171], v81, s[34:35] offset:2048
	global_load_dwordx4 v[172:175], v81, s[34:35] offset:2064
	global_load_dwordx4 v[208:211], v80, s[36:37] offset:0
	global_load_dwordx4 v[212:215], v80, s[36:37] offset:16
	global_load_dwordx4 v[216:219], v80, s[36:37] offset:2048
	global_load_dwordx4 v[220:223], v80, s[36:37] offset:2064
	global_load_dwordx4 v[192:195], v81, s[36:37] offset:0
	global_load_dwordx4 v[196:199], v81, s[36:37] offset:16
	global_load_dwordx4 v[200:203], v81, s[36:37] offset:2048
	global_load_dwordx4 v[204:207], v81, s[36:37] offset:2064
	s_add_u32 s24, s16, 0x6000000
	s_addc_u32 s25, s17, 0
	s_add_u32 s26, s16, 0x6800000
	s_addc_u32 s27, s17, 0
	s_add_u32 s28, s16, 0x7000000
	s_addc_u32 s29, s17, 0
	s_add_u32 s30, s16, 0x7800000
	s_addc_u32 s31, s17, 0
	global_load_dwordx4 v[96:99], v80, s[24:25] offset:0
	global_load_dwordx4 v[100:103], v80, s[24:25] offset:16
	global_load_dwordx4 v[104:107], v80, s[24:25] offset:2048
	global_load_dwordx4 v[108:111], v80, s[24:25] offset:2064
	global_load_dwordx4 v[112:115], v80, s[26:27] offset:0
	global_load_dwordx4 v[116:119], v80, s[26:27] offset:16
	global_load_dwordx4 v[120:123], v80, s[26:27] offset:2048
	global_load_dwordx4 v[124:127], v80, s[26:27] offset:2064
	global_load_dwordx4 v[128:131], v80, s[28:29] offset:0
	global_load_dwordx4 v[132:135], v80, s[28:29] offset:16
	global_load_dwordx4 v[136:139], v80, s[28:29] offset:2048
	global_load_dwordx4 v[140:143], v80, s[28:29] offset:2064
	global_load_dwordx4 v[144:147], v80, s[30:31] offset:0
	global_load_dwordx4 v[148:151], v80, s[30:31] offset:16
	global_load_dwordx4 v[152:155], v80, s[30:31] offset:2048
	global_load_dwordx4 v[156:159], v80, s[30:31] offset:2064
	s_waitcnt vmcnt(40)
	v_pk_mul_f32 v[240:241], v[0:1], v[0:1]
	v_pk_mul_f32 v[242:243], v[16:17], v[16:17]
	v_pk_mul_f32 v[244:245], v[32:33], v[32:33]
	v_pk_mul_f32 v[246:247], v[48:49], v[48:49]
	v_pk_fma_f32 v[240:241], v[2:3], v[2:3], v[240:241]
	v_pk_fma_f32 v[242:243], v[18:19], v[18:19], v[242:243]
	v_pk_fma_f32 v[244:245], v[34:35], v[34:35], v[244:245]
	v_pk_fma_f32 v[246:247], v[50:51], v[50:51], v[246:247]
	v_pk_fma_f32 v[240:241], v[4:5], v[4:5], v[240:241]
	v_pk_fma_f32 v[242:243], v[20:21], v[20:21], v[242:243]
	v_pk_fma_f32 v[244:245], v[36:37], v[36:37], v[244:245]
	v_pk_fma_f32 v[246:247], v[52:53], v[52:53], v[246:247]
	v_pk_fma_f32 v[240:241], v[6:7], v[6:7], v[240:241]
	v_pk_fma_f32 v[242:243], v[22:23], v[22:23], v[242:243]
	v_pk_fma_f32 v[244:245], v[38:39], v[38:39], v[244:245]
	v_pk_fma_f32 v[246:247], v[54:55], v[54:55], v[246:247]
	v_pk_fma_f32 v[240:241], v[8:9], v[8:9], v[240:241]
	v_pk_fma_f32 v[242:243], v[24:25], v[24:25], v[242:243]
	v_pk_fma_f32 v[244:245], v[40:41], v[40:41], v[244:245]
	v_pk_fma_f32 v[246:247], v[56:57], v[56:57], v[246:247]
	v_pk_fma_f32 v[240:241], v[10:11], v[10:11], v[240:241]
	v_pk_fma_f32 v[242:243], v[26:27], v[26:27], v[242:243]
	v_pk_fma_f32 v[244:245], v[42:43], v[42:43], v[244:245]
	v_pk_fma_f32 v[246:247], v[58:59], v[58:59], v[246:247]
	v_pk_fma_f32 v[240:241], v[12:13], v[12:13], v[240:241]
	v_pk_fma_f32 v[242:243], v[28:29], v[28:29], v[242:243]
	v_pk_fma_f32 v[244:245], v[44:45], v[44:45], v[244:245]
	v_pk_fma_f32 v[246:247], v[60:61], v[60:61], v[246:247]
	v_pk_fma_f32 v[240:241], v[14:15], v[14:15], v[240:241]
	v_pk_fma_f32 v[242:243], v[30:31], v[30:31], v[242:243]
	v_pk_fma_f32 v[244:245], v[46:47], v[46:47], v[244:245]
	v_pk_fma_f32 v[246:247], v[62:63], v[62:63], v[246:247]
	v_add_f32_e32 v224, v240, v241
	v_add_f32_e32 v225, v242, v243
	v_add_f32_e32 v226, v244, v245
	v_add_f32_e32 v227, v246, v247
	ds_bpermute_b32 v228, v83, v224
	ds_bpermute_b32 v229, v83, v225
	ds_bpermute_b32 v230, v83, v226
	ds_bpermute_b32 v231, v83, v227
	s_waitcnt lgkmcnt(0)
	v_add_f32_e32 v224, v224, v228
	v_add_f32_e32 v225, v225, v229
	v_add_f32_e32 v226, v226, v230
	v_add_f32_e32 v227, v227, v231
	ds_bpermute_b32 v228, v84, v224
	ds_bpermute_b32 v229, v84, v225
	ds_bpermute_b32 v230, v84, v226
	ds_bpermute_b32 v231, v84, v227
	s_waitcnt lgkmcnt(0)
	v_add_f32_e32 v224, v224, v228
	v_add_f32_e32 v225, v225, v229
	v_add_f32_e32 v226, v226, v230
	v_add_f32_e32 v227, v227, v231
	ds_bpermute_b32 v228, v85, v224
	ds_bpermute_b32 v229, v85, v225
	ds_bpermute_b32 v230, v85, v226
	ds_bpermute_b32 v231, v85, v227
	s_waitcnt lgkmcnt(0)
	v_add_f32_e32 v224, v224, v228
	v_add_f32_e32 v225, v225, v229
	v_add_f32_e32 v226, v226, v230
	v_add_f32_e32 v227, v227, v231
	ds_bpermute_b32 v228, v86, v224
	ds_bpermute_b32 v229, v86, v225
	ds_bpermute_b32 v230, v86, v226
	ds_bpermute_b32 v231, v86, v227
	s_waitcnt lgkmcnt(0)
	v_add_f32_e32 v224, v224, v228
	v_add_f32_e32 v225, v225, v229
	v_add_f32_e32 v226, v226, v230
	v_add_f32_e32 v227, v227, v231
	ds_bpermute_b32 v228, v87, v224
	ds_bpermute_b32 v229, v87, v225
	ds_bpermute_b32 v230, v87, v226
	ds_bpermute_b32 v231, v87, v227
	s_waitcnt lgkmcnt(0)
	v_add_f32_e32 v224, v224, v228
	v_add_f32_e32 v225, v225, v229
	v_add_f32_e32 v226, v226, v230
	v_add_f32_e32 v227, v227, v231
	ds_bpermute_b32 v228, v88, v224
	ds_bpermute_b32 v229, v88, v225
	ds_bpermute_b32 v230, v88, v226
	ds_bpermute_b32 v231, v88, v227
	s_waitcnt lgkmcnt(0)
	v_add_f32_e32 v224, v224, v228
	v_add_f32_e32 v225, v225, v229
	v_add_f32_e32 v226, v226, v230
	v_add_f32_e32 v227, v227, v231
	v_fmamk_f32 v240, v224, 0x3a800000, v89
	v_mul_f32_e32 v241, 0x4f800000, v240
	v_cmp_gt_f32_e32 vcc, s54, v240
	s_nop 1
	v_cndmask_b32_e32 v247, v240, v241, vcc
	v_sqrt_f32_e32 v242, v247
	s_nop 1
	v_add_u32_e32 v243, -1, v242
	v_add_u32_e32 v244, 1, v242
	v_fma_f32 v245, -v243, v242, v247
	v_fma_f32 v246, -v244, v242, v247
	v_cmp_ge_f32_e64 s[52:53], 0, v245
	s_nop 1
	v_cndmask_b32_e64 v242, v242, v243, s[52:53]
	v_cmp_lt_f32_e64 s[52:53], 0, v246
	s_nop 1
	v_cndmask_b32_e64 v242, v242, v244, s[52:53]
	v_mul_f32_e32 v243, 0x37800000, v242
	v_cndmask_b32_e32 v242, v242, v243, vcc
	v_cmp_class_f32_e32 vcc, v247, v90
	s_nop 1
	v_cndmask_b32_e32 v247, v242, v247, vcc
	v_div_scale_f32 v248, s[52:53], v247, v247, 1.0
	v_rcp_f32_e32 v249, v248
	v_div_scale_f32 v228, vcc, 1.0, v247, 1.0
	s_nop 0
	v_fma_f32 v229, -v248, v249, 1.0
	v_fmac_f32_e32 v249, v229, v249
	v_mul_f32_e32 v230, v228, v249
	v_fma_f32 v229, -v248, v230, v228
	v_fmac_f32_e32 v230, v229, v249
	v_fma_f32 v248, -v248, v230, v228
	v_div_fmas_f32 v248, v248, v249, v230
	v_div_fixup_f32 v232, v248, v247, 1.0
	v_fmamk_f32 v240, v225, 0x3a800000, v89
	v_mul_f32_e32 v241, 0x4f800000, v240
	v_cmp_gt_f32_e32 vcc, s54, v240
	s_nop 1
	v_cndmask_b32_e32 v247, v240, v241, vcc
	v_sqrt_f32_e32 v242, v247
	s_nop 1
	v_add_u32_e32 v243, -1, v242
	v_add_u32_e32 v244, 1, v242
	v_fma_f32 v245, -v243, v242, v247
	v_fma_f32 v246, -v244, v242, v247
	v_cmp_ge_f32_e64 s[52:53], 0, v245
	s_nop 1
	v_cndmask_b32_e64 v242, v242, v243, s[52:53]
	v_cmp_lt_f32_e64 s[52:53], 0, v246
	s_nop 1
	v_cndmask_b32_e64 v242, v242, v244, s[52:53]
	v_mul_f32_e32 v243, 0x37800000, v242
	v_cndmask_b32_e32 v242, v242, v243, vcc
	v_cmp_class_f32_e32 vcc, v247, v90
	s_nop 1
	v_cndmask_b32_e32 v247, v242, v247, vcc
	v_div_scale_f32 v248, s[52:53], v247, v247, 1.0
	v_rcp_f32_e32 v249, v248
	v_div_scale_f32 v228, vcc, 1.0, v247, 1.0
	s_nop 0
	v_fma_f32 v229, -v248, v249, 1.0
	v_fmac_f32_e32 v249, v229, v249
	v_mul_f32_e32 v230, v228, v249
	v_fma_f32 v229, -v248, v230, v228
	v_fmac_f32_e32 v230, v229, v249
	v_fma_f32 v248, -v248, v230, v228
	v_div_fmas_f32 v248, v248, v249, v230
	v_div_fixup_f32 v234, v248, v247, 1.0
	v_fmamk_f32 v240, v226, 0x3a800000, v89
	v_mul_f32_e32 v241, 0x4f800000, v240
	v_cmp_gt_f32_e32 vcc, s54, v240
	s_nop 1
	v_cndmask_b32_e32 v247, v240, v241, vcc
	v_sqrt_f32_e32 v242, v247
	s_nop 1
	v_add_u32_e32 v243, -1, v242
	v_add_u32_e32 v244, 1, v242
	v_fma_f32 v245, -v243, v242, v247
	v_fma_f32 v246, -v244, v242, v247
	v_cmp_ge_f32_e64 s[52:53], 0, v245
	s_nop 1
	v_cndmask_b32_e64 v242, v242, v243, s[52:53]
	v_cmp_lt_f32_e64 s[52:53], 0, v246
	s_nop 1
	v_cndmask_b32_e64 v242, v242, v244, s[52:53]
	v_mul_f32_e32 v243, 0x37800000, v242
	v_cndmask_b32_e32 v242, v242, v243, vcc
	v_cmp_class_f32_e32 vcc, v247, v90
	s_nop 1
	v_cndmask_b32_e32 v247, v242, v247, vcc
	v_div_scale_f32 v248, s[52:53], v247, v247, 1.0
	v_rcp_f32_e32 v249, v248
	v_div_scale_f32 v228, vcc, 1.0, v247, 1.0
	s_nop 0
	v_fma_f32 v229, -v248, v249, 1.0
	v_fmac_f32_e32 v249, v229, v249
	v_mul_f32_e32 v230, v228, v249
	v_fma_f32 v229, -v248, v230, v228
	v_fmac_f32_e32 v230, v229, v249
	v_fma_f32 v248, -v248, v230, v228
	v_div_fmas_f32 v248, v248, v249, v230
	v_div_fixup_f32 v236, v248, v247, 1.0
	v_fmamk_f32 v240, v227, 0x3a800000, v89
	v_mul_f32_e32 v241, 0x4f800000, v240
	v_cmp_gt_f32_e32 vcc, s54, v240
	s_nop 1
	v_cndmask_b32_e32 v247, v240, v241, vcc
	v_sqrt_f32_e32 v242, v247
	s_nop 1
	v_add_u32_e32 v243, -1, v242
	v_add_u32_e32 v244, 1, v242
	v_fma_f32 v245, -v243, v242, v247
	v_fma_f32 v246, -v244, v242, v247
	v_cmp_ge_f32_e64 s[52:53], 0, v245
	s_nop 1
	v_cndmask_b32_e64 v242, v242, v243, s[52:53]
	v_cmp_lt_f32_e64 s[52:53], 0, v246
	s_nop 1
	v_cndmask_b32_e64 v242, v242, v244, s[52:53]
	v_mul_f32_e32 v243, 0x37800000, v242
	v_cndmask_b32_e32 v242, v242, v243, vcc
	v_cmp_class_f32_e32 vcc, v247, v90
	s_nop 1
	v_cndmask_b32_e32 v247, v242, v247, vcc
	v_div_scale_f32 v248, s[52:53], v247, v247, 1.0
	v_rcp_f32_e32 v249, v248
	v_div_scale_f32 v228, vcc, 1.0, v247, 1.0
	s_nop 0
	v_fma_f32 v229, -v248, v249, 1.0
	v_fmac_f32_e32 v249, v229, v249
	v_mul_f32_e32 v230, v228, v249
	v_fma_f32 v229, -v248, v230, v228
	v_fmac_f32_e32 v230, v229, v249
	v_fma_f32 v248, -v248, v230, v228
	v_div_fmas_f32 v248, v248, v249, v230
	v_div_fixup_f32 v238, v248, v247, 1.0
	s_waitcnt vmcnt(16)
	v_pk_add_f32 v[160:161], v[160:161], 1.0 op_sel_hi:[1,0]
	v_pk_add_f32 v[162:163], v[162:163], 1.0 op_sel_hi:[1,0]
	v_pk_add_f32 v[164:165], v[164:165], 1.0 op_sel_hi:[1,0]
	v_pk_add_f32 v[166:167], v[166:167], 1.0 op_sel_hi:[1,0]
	v_pk_add_f32 v[168:169], v[168:169], 1.0 op_sel_hi:[1,0]
	v_pk_add_f32 v[170:171], v[170:171], 1.0 op_sel_hi:[1,0]
	v_pk_add_f32 v[172:173], v[172:173], 1.0 op_sel_hi:[1,0]
	v_pk_add_f32 v[174:175], v[174:175], 1.0 op_sel_hi:[1,0]
	v_pk_add_f32 v[192:193], v[192:193], 1.0 op_sel_hi:[1,0]
	v_pk_add_f32 v[194:195], v[194:195], 1.0 op_sel_hi:[1,0]
	v_pk_add_f32 v[196:197], v[196:197], 1.0 op_sel_hi:[1,0]
	v_pk_add_f32 v[198:199], v[198:199], 1.0 op_sel_hi:[1,0]
	v_pk_add_f32 v[200:201], v[200:201], 1.0 op_sel_hi:[1,0]
	v_pk_add_f32 v[202:203], v[202:203], 1.0 op_sel_hi:[1,0]
	v_pk_add_f32 v[204:205], v[204:205], 1.0 op_sel_hi:[1,0]
	v_pk_add_f32 v[206:207], v[206:207], 1.0 op_sel_hi:[1,0]
	s_add_u32 s38, s20, 0x2000000
	s_addc_u32 s39, s21, 0
	s_add_u32 s40, s20, 0x2400000
	s_addc_u32 s41, s21, 0
	s_add_u32 s46, s20, 0x2800000
	s_addc_u32 s47, s21, 0
	s_add_u32 s48, s20, 0x2c00000
	s_addc_u32 s49, s21, 0
	v_pk_mul_f32 v[0:1], v[0:1], v[232:233] op_sel_hi:[1,0]
	v_pk_mul_f32 v[2:3], v[2:3], v[232:233] op_sel_hi:[1,0]
	v_pk_mul_f32 v[0:1], v[64:65], v[0:1]
	v_pk_mul_f32 v[2:3], v[66:67], v[2:3]
	v_pk_fma_f32 v[0:1], v[160:161], v[0:1], v[176:177]
	v_pk_fma_f32 v[2:3], v[162:163], v[2:3], v[178:179]
	v_cvt_pk_bf16_f32 v244, v0, v1
	v_cvt_pk_bf16_f32 v245, v2, v3
	v_pk_mul_f32 v[4:5], v[4:5], v[232:233] op_sel_hi:[1,0]
	v_pk_mul_f32 v[6:7], v[6:7], v[232:233] op_sel_hi:[1,0]
	v_pk_mul_f32 v[4:5], v[68:69], v[4:5]
	v_pk_mul_f32 v[6:7], v[70:71], v[6:7]
	v_pk_fma_f32 v[4:5], v[164:165], v[4:5], v[180:181]
	v_pk_fma_f32 v[6:7], v[166:167], v[6:7], v[182:183]
	v_cvt_pk_bf16_f32 v246, v4, v5
	v_cvt_pk_bf16_f32 v247, v6, v7
	global_store_dwordx4 v82, v[244:247], s[38:39] offset:0
	v_pk_mul_f32 v[8:9], v[8:9], v[232:233] op_sel_hi:[1,0]
	v_pk_mul_f32 v[10:11], v[10:11], v[232:233] op_sel_hi:[1,0]
	v_pk_mul_f32 v[8:9], v[72:73], v[8:9]
	v_pk_mul_f32 v[10:11], v[74:75], v[10:11]
	v_pk_fma_f32 v[8:9], v[168:169], v[8:9], v[184:185]
	v_pk_fma_f32 v[10:11], v[170:171], v[10:11], v[186:187]
	v_cvt_pk_bf16_f32 v240, v8, v9
	v_cvt_pk_bf16_f32 v241, v10, v11
	v_pk_mul_f32 v[12:13], v[12:13], v[232:233] op_sel_hi:[1,0]
	v_pk_mul_f32 v[14:15], v[14:15], v[232:233] op_sel_hi:[1,0]
	v_pk_mul_f32 v[12:13], v[76:77], v[12:13]
	v_pk_mul_f32 v[14:15], v[78:79], v[14:15]
	v_pk_fma_f32 v[12:13], v[172:173], v[12:13], v[188:189]
	v_pk_fma_f32 v[14:15], v[174:175], v[14:15], v[190:191]
	v_cvt_pk_bf16_f32 v242, v12, v13
	v_cvt_pk_bf16_f32 v243, v14, v15
	global_store_dwordx4 v82, v[240:243], s[38:39] offset:1024
	v_pk_mul_f32 v[16:17], v[16:17], v[234:235] op_sel_hi:[1,0]
	v_pk_mul_f32 v[18:19], v[18:19], v[234:235] op_sel_hi:[1,0]
	v_pk_mul_f32 v[16:17], v[64:65], v[16:17]
	v_pk_mul_f32 v[18:19], v[66:67], v[18:19]
	v_pk_fma_f32 v[16:17], v[160:161], v[16:17], v[176:177]
	v_pk_fma_f32 v[18:19], v[162:163], v[18:19], v[178:179]
	v_cvt_pk_bf16_f32 v244, v16, v17
	v_cvt_pk_bf16_f32 v245, v18, v19
	v_pk_mul_f32 v[20:21], v[20:21], v[234:235] op_sel_hi:[1,0]
	v_pk_mul_f32 v[22:23], v[22:23], v[234:235] op_sel_hi:[1,0]
	v_pk_mul_f32 v[20:21], v[68:69], v[20:21]
	v_pk_mul_f32 v[22:23], v[70:71], v[22:23]
	v_pk_fma_f32 v[20:21], v[164:165], v[20:21], v[180:181]
	v_pk_fma_f32 v[22:23], v[166:167], v[22:23], v[182:183]
	v_cvt_pk_bf16_f32 v246, v20, v21
	v_cvt_pk_bf16_f32 v247, v22, v23
	global_store_dwordx4 v82, v[244:247], s[40:41] offset:0
	v_pk_mul_f32 v[24:25], v[24:25], v[234:235] op_sel_hi:[1,0]
	v_pk_mul_f32 v[26:27], v[26:27], v[234:235] op_sel_hi:[1,0]
	v_pk_mul_f32 v[24:25], v[72:73], v[24:25]
	v_pk_mul_f32 v[26:27], v[74:75], v[26:27]
	v_pk_fma_f32 v[24:25], v[168:169], v[24:25], v[184:185]
	v_pk_fma_f32 v[26:27], v[170:171], v[26:27], v[186:187]
	v_cvt_pk_bf16_f32 v240, v24, v25
	v_cvt_pk_bf16_f32 v241, v26, v27
	v_pk_mul_f32 v[28:29], v[28:29], v[234:235] op_sel_hi:[1,0]
	v_pk_mul_f32 v[30:31], v[30:31], v[234:235] op_sel_hi:[1,0]
	v_pk_mul_f32 v[28:29], v[76:77], v[28:29]
	v_pk_mul_f32 v[30:31], v[78:79], v[30:31]
	v_pk_fma_f32 v[28:29], v[172:173], v[28:29], v[188:189]
	v_pk_fma_f32 v[30:31], v[174:175], v[30:31], v[190:191]
	v_cvt_pk_bf16_f32 v242, v28, v29
	v_cvt_pk_bf16_f32 v243, v30, v31
	global_store_dwordx4 v82, v[240:243], s[40:41] offset:1024
	v_pk_mul_f32 v[32:33], v[32:33], v[236:237] op_sel_hi:[1,0]
	v_pk_mul_f32 v[34:35], v[34:35], v[236:237] op_sel_hi:[1,0]
	v_pk_mul_f32 v[32:33], v[64:65], v[32:33]
	v_pk_mul_f32 v[34:35], v[66:67], v[34:35]
	v_pk_fma_f32 v[32:33], v[192:193], v[32:33], v[208:209]
	v_pk_fma_f32 v[34:35], v[194:195], v[34:35], v[210:211]
	v_cvt_pk_bf16_f32 v244, v32, v33
	v_cvt_pk_bf16_f32 v245, v34, v35
	v_pk_mul_f32 v[36:37], v[36:37], v[236:237] op_sel_hi:[1,0]
	v_pk_mul_f32 v[38:39], v[38:39], v[236:237] op_sel_hi:[1,0]
	v_pk_mul_f32 v[36:37], v[68:69], v[36:37]
	v_pk_mul_f32 v[38:39], v[70:71], v[38:39]
	v_pk_fma_f32 v[36:37], v[196:197], v[36:37], v[212:213]
	v_pk_fma_f32 v[38:39], v[198:199], v[38:39], v[214:215]
	v_cvt_pk_bf16_f32 v246, v36, v37
	v_cvt_pk_bf16_f32 v247, v38, v39
	global_store_dwordx4 v82, v[244:247], s[46:47] offset:0
	v_pk_mul_f32 v[40:41], v[40:41], v[236:237] op_sel_hi:[1,0]
	v_pk_mul_f32 v[42:43], v[42:43], v[236:237] op_sel_hi:[1,0]
	v_pk_mul_f32 v[40:41], v[72:73], v[40:41]
	v_pk_mul_f32 v[42:43], v[74:75], v[42:43]
	v_pk_fma_f32 v[40:41], v[200:201], v[40:41], v[216:217]
	v_pk_fma_f32 v[42:43], v[202:203], v[42:43], v[218:219]
	v_cvt_pk_bf16_f32 v240, v40, v41
	v_cvt_pk_bf16_f32 v241, v42, v43
	v_pk_mul_f32 v[44:45], v[44:45], v[236:237] op_sel_hi:[1,0]
	v_pk_mul_f32 v[46:47], v[46:47], v[236:237] op_sel_hi:[1,0]
	v_pk_mul_f32 v[44:45], v[76:77], v[44:45]
	v_pk_mul_f32 v[46:47], v[78:79], v[46:47]
	v_pk_fma_f32 v[44:45], v[204:205], v[44:45], v[220:221]
	v_pk_fma_f32 v[46:47], v[206:207], v[46:47], v[222:223]
	v_cvt_pk_bf16_f32 v242, v44, v45
	v_cvt_pk_bf16_f32 v243, v46, v47
	global_store_dwordx4 v82, v[240:243], s[46:47] offset:1024
	v_pk_mul_f32 v[48:49], v[48:49], v[238:239] op_sel_hi:[1,0]
	v_pk_mul_f32 v[50:51], v[50:51], v[238:239] op_sel_hi:[1,0]
	v_pk_mul_f32 v[48:49], v[64:65], v[48:49]
	v_pk_mul_f32 v[50:51], v[66:67], v[50:51]
	v_pk_fma_f32 v[48:49], v[192:193], v[48:49], v[208:209]
	v_pk_fma_f32 v[50:51], v[194:195], v[50:51], v[210:211]
	v_cvt_pk_bf16_f32 v244, v48, v49
	v_cvt_pk_bf16_f32 v245, v50, v51
	v_pk_mul_f32 v[52:53], v[52:53], v[238:239] op_sel_hi:[1,0]
	v_pk_mul_f32 v[54:55], v[54:55], v[238:239] op_sel_hi:[1,0]
	v_pk_mul_f32 v[52:53], v[68:69], v[52:53]
	v_pk_mul_f32 v[54:55], v[70:71], v[54:55]
	v_pk_fma_f32 v[52:53], v[196:197], v[52:53], v[212:213]
	v_pk_fma_f32 v[54:55], v[198:199], v[54:55], v[214:215]
	v_cvt_pk_bf16_f32 v246, v52, v53
	v_cvt_pk_bf16_f32 v247, v54, v55
	global_store_dwordx4 v82, v[244:247], s[48:49] offset:0
	v_pk_mul_f32 v[56:57], v[56:57], v[238:239] op_sel_hi:[1,0]
	v_pk_mul_f32 v[58:59], v[58:59], v[238:239] op_sel_hi:[1,0]
	v_pk_mul_f32 v[56:57], v[72:73], v[56:57]
	v_pk_mul_f32 v[58:59], v[74:75], v[58:59]
	v_pk_fma_f32 v[56:57], v[200:201], v[56:57], v[216:217]
	v_pk_fma_f32 v[58:59], v[202:203], v[58:59], v[218:219]
	v_cvt_pk_bf16_f32 v240, v56, v57
	v_cvt_pk_bf16_f32 v241, v58, v59
	v_pk_mul_f32 v[60:61], v[60:61], v[238:239] op_sel_hi:[1,0]
	v_pk_mul_f32 v[62:63], v[62:63], v[238:239] op_sel_hi:[1,0]
	v_pk_mul_f32 v[60:61], v[76:77], v[60:61]
	v_pk_mul_f32 v[62:63], v[78:79], v[62:63]
	v_pk_fma_f32 v[60:61], v[204:205], v[60:61], v[220:221]
	v_pk_fma_f32 v[62:63], v[206:207], v[62:63], v[222:223]
	v_cvt_pk_bf16_f32 v242, v60, v61
	v_cvt_pk_bf16_f32 v243, v62, v63
	global_store_dwordx4 v82, v[240:243], s[48:49] offset:1024
	s_add_u32 s34, s8, 0x12000
	s_addc_u32 s35, s9, 0
	s_add_u32 s36, s8, 0x12000
	s_addc_u32 s37, s9, 0
	global_load_dwordx4 v[176:179], v80, s[34:35] offset:0
	global_load_dwordx4 v[180:183], v80, s[34:35] offset:16
	global_load_dwordx4 v[184:187], v80, s[34:35] offset:2048
	global_load_dwordx4 v[188:191], v80, s[34:35] offset:2064
	global_load_dwordx4 v[160:163], v81, s[34:35] offset:0
	global_load_dwordx4 v[164:167], v81, s[34:35] offset:16
	global_load_dwordx4 v[168:171], v81, s[34:35] offset:2048
	global_load_dwordx4 v[172:175], v81, s[34:35] offset:2064
	global_load_dwordx4 v[208:211], v80, s[36:37] offset:0
	global_load_dwordx4 v[212:215], v80, s[36:37] offset:16
	global_load_dwordx4 v[216:219], v80, s[36:37] offset:2048
	global_load_dwordx4 v[220:223], v80, s[36:37] offset:2064
	global_load_dwordx4 v[192:195], v81, s[36:37] offset:0
	global_load_dwordx4 v[196:199], v81, s[36:37] offset:16
	global_load_dwordx4 v[200:203], v81, s[36:37] offset:2048
	global_load_dwordx4 v[204:207], v81, s[36:37] offset:2064
	s_add_u32 s24, s16, 0x8000000
	s_addc_u32 s25, s17, 0
	s_add_u32 s26, s16, 0x8800000
	s_addc_u32 s27, s17, 0
	s_add_u32 s28, s16, 0x9000000
	s_addc_u32 s29, s17, 0
	s_add_u32 s30, s16, 0x9800000
	s_addc_u32 s31, s17, 0
	global_load_dwordx4 v[0:3], v80, s[24:25] offset:0
	global_load_dwordx4 v[4:7], v80, s[24:25] offset:16
	global_load_dwordx4 v[8:11], v80, s[24:25] offset:2048
	global_load_dwordx4 v[12:15], v80, s[24:25] offset:2064
	global_load_dwordx4 v[16:19], v80, s[26:27] offset:0
	global_load_dwordx4 v[20:23], v80, s[26:27] offset:16
	global_load_dwordx4 v[24:27], v80, s[26:27] offset:2048
	global_load_dwordx4 v[28:31], v80, s[26:27] offset:2064
	global_load_dwordx4 v[32:35], v80, s[28:29] offset:0
	global_load_dwordx4 v[36:39], v80, s[28:29] offset:16
	global_load_dwordx4 v[40:43], v80, s[28:29] offset:2048
	global_load_dwordx4 v[44:47], v80, s[28:29] offset:2064
	global_load_dwordx4 v[48:51], v80, s[30:31] offset:0
	global_load_dwordx4 v[52:55], v80, s[30:31] offset:16
	global_load_dwordx4 v[56:59], v80, s[30:31] offset:2048
	global_load_dwordx4 v[60:63], v80, s[30:31] offset:2064
	s_waitcnt vmcnt(40)
	v_pk_mul_f32 v[240:241], v[96:97], v[96:97]
	v_pk_mul_f32 v[242:243], v[112:113], v[112:113]
	v_pk_mul_f32 v[244:245], v[128:129], v[128:129]
	v_pk_mul_f32 v[246:247], v[144:145], v[144:145]
	v_pk_fma_f32 v[240:241], v[98:99], v[98:99], v[240:241]
	v_pk_fma_f32 v[242:243], v[114:115], v[114:115], v[242:243]
	v_pk_fma_f32 v[244:245], v[130:131], v[130:131], v[244:245]
	v_pk_fma_f32 v[246:247], v[146:147], v[146:147], v[246:247]
	v_pk_fma_f32 v[240:241], v[100:101], v[100:101], v[240:241]
	v_pk_fma_f32 v[242:243], v[116:117], v[116:117], v[242:243]
	v_pk_fma_f32 v[244:245], v[132:133], v[132:133], v[244:245]
	v_pk_fma_f32 v[246:247], v[148:149], v[148:149], v[246:247]
	v_pk_fma_f32 v[240:241], v[102:103], v[102:103], v[240:241]
	v_pk_fma_f32 v[242:243], v[118:119], v[118:119], v[242:243]
	v_pk_fma_f32 v[244:245], v[134:135], v[134:135], v[244:245]
	v_pk_fma_f32 v[246:247], v[150:151], v[150:151], v[246:247]
	v_pk_fma_f32 v[240:241], v[104:105], v[104:105], v[240:241]
	v_pk_fma_f32 v[242:243], v[120:121], v[120:121], v[242:243]
	v_pk_fma_f32 v[244:245], v[136:137], v[136:137], v[244:245]
	v_pk_fma_f32 v[246:247], v[152:153], v[152:153], v[246:247]
	v_pk_fma_f32 v[240:241], v[106:107], v[106:107], v[240:241]
	v_pk_fma_f32 v[242:243], v[122:123], v[122:123], v[242:243]
	v_pk_fma_f32 v[244:245], v[138:139], v[138:139], v[244:245]
	v_pk_fma_f32 v[246:247], v[154:155], v[154:155], v[246:247]
	v_pk_fma_f32 v[240:241], v[108:109], v[108:109], v[240:241]
	v_pk_fma_f32 v[242:243], v[124:125], v[124:125], v[242:243]
	v_pk_fma_f32 v[244:245], v[140:141], v[140:141], v[244:245]
	v_pk_fma_f32 v[246:247], v[156:157], v[156:157], v[246:247]
	v_pk_fma_f32 v[240:241], v[110:111], v[110:111], v[240:241]
	v_pk_fma_f32 v[242:243], v[126:127], v[126:127], v[242:243]
	v_pk_fma_f32 v[244:245], v[142:143], v[142:143], v[244:245]
	v_pk_fma_f32 v[246:247], v[158:159], v[158:159], v[246:247]
	v_add_f32_e32 v224, v240, v241
	v_add_f32_e32 v225, v242, v243
	v_add_f32_e32 v226, v244, v245
	v_add_f32_e32 v227, v246, v247
	ds_bpermute_b32 v228, v83, v224
	ds_bpermute_b32 v229, v83, v225
	ds_bpermute_b32 v230, v83, v226
	ds_bpermute_b32 v231, v83, v227
	s_waitcnt lgkmcnt(0)
	v_add_f32_e32 v224, v224, v228
	v_add_f32_e32 v225, v225, v229
	v_add_f32_e32 v226, v226, v230
	v_add_f32_e32 v227, v227, v231
	ds_bpermute_b32 v228, v84, v224
	ds_bpermute_b32 v229, v84, v225
	ds_bpermute_b32 v230, v84, v226
	ds_bpermute_b32 v231, v84, v227
	s_waitcnt lgkmcnt(0)
	v_add_f32_e32 v224, v224, v228
	v_add_f32_e32 v225, v225, v229
	v_add_f32_e32 v226, v226, v230
	v_add_f32_e32 v227, v227, v231
	ds_bpermute_b32 v228, v85, v224
	ds_bpermute_b32 v229, v85, v225
	ds_bpermute_b32 v230, v85, v226
	ds_bpermute_b32 v231, v85, v227
	s_waitcnt lgkmcnt(0)
	v_add_f32_e32 v224, v224, v228
	v_add_f32_e32 v225, v225, v229
	v_add_f32_e32 v226, v226, v230
	v_add_f32_e32 v227, v227, v231
	ds_bpermute_b32 v228, v86, v224
	ds_bpermute_b32 v229, v86, v225
	ds_bpermute_b32 v230, v86, v226
	ds_bpermute_b32 v231, v86, v227
	s_waitcnt lgkmcnt(0)
	v_add_f32_e32 v224, v224, v228
	v_add_f32_e32 v225, v225, v229
	v_add_f32_e32 v226, v226, v230
	v_add_f32_e32 v227, v227, v231
	ds_bpermute_b32 v228, v87, v224
	ds_bpermute_b32 v229, v87, v225
	ds_bpermute_b32 v230, v87, v226
	ds_bpermute_b32 v231, v87, v227
	s_waitcnt lgkmcnt(0)
	v_add_f32_e32 v224, v224, v228
	v_add_f32_e32 v225, v225, v229
	v_add_f32_e32 v226, v226, v230
	v_add_f32_e32 v227, v227, v231
	ds_bpermute_b32 v228, v88, v224
	ds_bpermute_b32 v229, v88, v225
	ds_bpermute_b32 v230, v88, v226
	ds_bpermute_b32 v231, v88, v227
	s_waitcnt lgkmcnt(0)
	v_add_f32_e32 v224, v224, v228
	v_add_f32_e32 v225, v225, v229
	v_add_f32_e32 v226, v226, v230
	v_add_f32_e32 v227, v227, v231
	v_fmamk_f32 v240, v224, 0x3a800000, v89
	v_mul_f32_e32 v241, 0x4f800000, v240
	v_cmp_gt_f32_e32 vcc, s54, v240
	s_nop 1
	v_cndmask_b32_e32 v247, v240, v241, vcc
	v_sqrt_f32_e32 v242, v247
	s_nop 1
	v_add_u32_e32 v243, -1, v242
	v_add_u32_e32 v244, 1, v242
	v_fma_f32 v245, -v243, v242, v247
	v_fma_f32 v246, -v244, v242, v247
	v_cmp_ge_f32_e64 s[52:53], 0, v245
	s_nop 1
	v_cndmask_b32_e64 v242, v242, v243, s[52:53]
	v_cmp_lt_f32_e64 s[52:53], 0, v246
	s_nop 1
	v_cndmask_b32_e64 v242, v242, v244, s[52:53]
	v_mul_f32_e32 v243, 0x37800000, v242
	v_cndmask_b32_e32 v242, v242, v243, vcc
	v_cmp_class_f32_e32 vcc, v247, v90
	s_nop 1
	v_cndmask_b32_e32 v247, v242, v247, vcc
	v_div_scale_f32 v248, s[52:53], v247, v247, 1.0
	v_rcp_f32_e32 v249, v248
	v_div_scale_f32 v228, vcc, 1.0, v247, 1.0
	s_nop 0
	v_fma_f32 v229, -v248, v249, 1.0
	v_fmac_f32_e32 v249, v229, v249
	v_mul_f32_e32 v230, v228, v249
	v_fma_f32 v229, -v248, v230, v228
	v_fmac_f32_e32 v230, v229, v249
	v_fma_f32 v248, -v248, v230, v228
	v_div_fmas_f32 v248, v248, v249, v230
	v_div_fixup_f32 v232, v248, v247, 1.0
	v_fmamk_f32 v240, v225, 0x3a800000, v89
	v_mul_f32_e32 v241, 0x4f800000, v240
	v_cmp_gt_f32_e32 vcc, s54, v240
	s_nop 1
	v_cndmask_b32_e32 v247, v240, v241, vcc
	v_sqrt_f32_e32 v242, v247
	s_nop 1
	v_add_u32_e32 v243, -1, v242
	v_add_u32_e32 v244, 1, v242
	v_fma_f32 v245, -v243, v242, v247
	v_fma_f32 v246, -v244, v242, v247
	v_cmp_ge_f32_e64 s[52:53], 0, v245
	s_nop 1
	v_cndmask_b32_e64 v242, v242, v243, s[52:53]
	v_cmp_lt_f32_e64 s[52:53], 0, v246
	s_nop 1
	v_cndmask_b32_e64 v242, v242, v244, s[52:53]
	v_mul_f32_e32 v243, 0x37800000, v242
	v_cndmask_b32_e32 v242, v242, v243, vcc
	v_cmp_class_f32_e32 vcc, v247, v90
	s_nop 1
	v_cndmask_b32_e32 v247, v242, v247, vcc
	v_div_scale_f32 v248, s[52:53], v247, v247, 1.0
	v_rcp_f32_e32 v249, v248
	v_div_scale_f32 v228, vcc, 1.0, v247, 1.0
	s_nop 0
	v_fma_f32 v229, -v248, v249, 1.0
	v_fmac_f32_e32 v249, v229, v249
	v_mul_f32_e32 v230, v228, v249
	v_fma_f32 v229, -v248, v230, v228
	v_fmac_f32_e32 v230, v229, v249
	v_fma_f32 v248, -v248, v230, v228
	v_div_fmas_f32 v248, v248, v249, v230
	v_div_fixup_f32 v234, v248, v247, 1.0
	v_fmamk_f32 v240, v226, 0x3a800000, v89
	v_mul_f32_e32 v241, 0x4f800000, v240
	v_cmp_gt_f32_e32 vcc, s54, v240
	s_nop 1
	v_cndmask_b32_e32 v247, v240, v241, vcc
	v_sqrt_f32_e32 v242, v247
	s_nop 1
	v_add_u32_e32 v243, -1, v242
	v_add_u32_e32 v244, 1, v242
	v_fma_f32 v245, -v243, v242, v247
	v_fma_f32 v246, -v244, v242, v247
	v_cmp_ge_f32_e64 s[52:53], 0, v245
	s_nop 1
	v_cndmask_b32_e64 v242, v242, v243, s[52:53]
	v_cmp_lt_f32_e64 s[52:53], 0, v246
	s_nop 1
	v_cndmask_b32_e64 v242, v242, v244, s[52:53]
	v_mul_f32_e32 v243, 0x37800000, v242
	v_cndmask_b32_e32 v242, v242, v243, vcc
	v_cmp_class_f32_e32 vcc, v247, v90
	s_nop 1
	v_cndmask_b32_e32 v247, v242, v247, vcc
	v_div_scale_f32 v248, s[52:53], v247, v247, 1.0
	v_rcp_f32_e32 v249, v248
	v_div_scale_f32 v228, vcc, 1.0, v247, 1.0
	s_nop 0
	v_fma_f32 v229, -v248, v249, 1.0
	v_fmac_f32_e32 v249, v229, v249
	v_mul_f32_e32 v230, v228, v249
	v_fma_f32 v229, -v248, v230, v228
	v_fmac_f32_e32 v230, v229, v249
	v_fma_f32 v248, -v248, v230, v228
	v_div_fmas_f32 v248, v248, v249, v230
	v_div_fixup_f32 v236, v248, v247, 1.0
	v_fmamk_f32 v240, v227, 0x3a800000, v89
	v_mul_f32_e32 v241, 0x4f800000, v240
	v_cmp_gt_f32_e32 vcc, s54, v240
	s_nop 1
	v_cndmask_b32_e32 v247, v240, v241, vcc
	v_sqrt_f32_e32 v242, v247
	s_nop 1
	v_add_u32_e32 v243, -1, v242
	v_add_u32_e32 v244, 1, v242
	v_fma_f32 v245, -v243, v242, v247
	v_fma_f32 v246, -v244, v242, v247
	v_cmp_ge_f32_e64 s[52:53], 0, v245
	s_nop 1
	v_cndmask_b32_e64 v242, v242, v243, s[52:53]
	v_cmp_lt_f32_e64 s[52:53], 0, v246
	s_nop 1
	v_cndmask_b32_e64 v242, v242, v244, s[52:53]
	v_mul_f32_e32 v243, 0x37800000, v242
	v_cndmask_b32_e32 v242, v242, v243, vcc
	v_cmp_class_f32_e32 vcc, v247, v90
	s_nop 1
	v_cndmask_b32_e32 v247, v242, v247, vcc
	v_div_scale_f32 v248, s[52:53], v247, v247, 1.0
	v_rcp_f32_e32 v249, v248
	v_div_scale_f32 v228, vcc, 1.0, v247, 1.0
	s_nop 0
	v_fma_f32 v229, -v248, v249, 1.0
	v_fmac_f32_e32 v249, v229, v249
	v_mul_f32_e32 v230, v228, v249
	v_fma_f32 v229, -v248, v230, v228
	v_fmac_f32_e32 v230, v229, v249
	v_fma_f32 v248, -v248, v230, v228
	v_div_fmas_f32 v248, v248, v249, v230
	v_div_fixup_f32 v238, v248, v247, 1.0
	s_waitcnt vmcnt(16)
; __device__ __forceinline__ unsigned pk2(float lo, float hi) { return pg8::cvt_pk_bf16(lo, hi); }
; template <bool BF> __device__ __forceinline__ void prep_rows(const float* xp, const float* xs, const bf16* hb, const float* g, const float* MOD, int shoff, int scoff, bf16* U, int gw, int NGW, int lane) {
;     ...
;         for (int r = 0; r < R; ++r) { const int m = mb + r * NGW; if (m < MT) {
;             const float rstd = 1.0f / sqrtf(s[r] * (1.0f / DM) + RMS_EPS);
;             const float* mr = MOD + (size_t)(m < MP ? (m >> 13) : 8 + ((m - MP) >> 12)) * 6144;
; #pragma unroll
;             for (int j = 0; j < 4; ++j) { const int c = 4 * lane + 256 * j;
;                 const f32x4 gg = *(const f32x4*)(g + c), sc = *(const f32x4*)(mr + scoff + c), sh = *(const f32x4*)(mr + shoff + c);
;                 const f32x4 o = v[r][j] * rstd * gg * (sc + 1.0f) + sh; v2u w; w.x = pk2(o.x, o.y); w.y = pk2(o.z, o.w); *(v2u*)(U + (size_t)m * DM + c) = w; } } }
	v_pk_add_f32 v[160:161], v[160:161], 1.0 op_sel_hi:[1,0]
	v_pk_add_f32 v[162:163], v[162:163], 1.0 op_sel_hi:[1,0]
	v_pk_add_f32 v[164:165], v[164:165], 1.0 op_sel_hi:[1,0]
	v_pk_add_f32 v[166:167], v[166:167], 1.0 op_sel_hi:[1,0]
	v_pk_add_f32 v[168:169], v[168:169], 1.0 op_sel_hi:[1,0]
	v_pk_add_f32 v[170:171], v[170:171], 1.0 op_sel_hi:[1,0]
	v_pk_add_f32 v[172:173], v[172:173], 1.0 op_sel_hi:[1,0]
	v_pk_add_f32 v[174:175], v[174:175], 1.0 op_sel_hi:[1,0]
	v_pk_add_f32 v[192:193], v[192:193], 1.0 op_sel_hi:[1,0]
	v_pk_add_f32 v[194:195], v[194:195], 1.0 op_sel_hi:[1,0]
	v_pk_add_f32 v[196:197], v[196:197], 1.0 op_sel_hi:[1,0]
	v_pk_add_f32 v[198:199], v[198:199], 1.0 op_sel_hi:[1,0]
	v_pk_add_f32 v[200:201], v[200:201], 1.0 op_sel_hi:[1,0]
	v_pk_add_f32 v[202:203], v[202:203], 1.0 op_sel_hi:[1,0]
	v_pk_add_f32 v[204:205], v[204:205], 1.0 op_sel_hi:[1,0]
	v_pk_add_f32 v[206:207], v[206:207], 1.0 op_sel_hi:[1,0]
	s_add_u32 s38, s20, 0x3000000
	s_addc_u32 s39, s21, 0
	s_add_u32 s40, s20, 0x3400000
	s_addc_u32 s41, s21, 0
	s_add_u32 s46, s20, 0x3800000
	s_addc_u32 s47, s21, 0
	s_add_u32 s48, s20, 0x3c00000
	s_addc_u32 s49, s21, 0
	v_pk_mul_f32 v[96:97], v[96:97], v[232:233] op_sel_hi:[1,0]
	v_pk_mul_f32 v[98:99], v[98:99], v[232:233] op_sel_hi:[1,0]
	v_pk_mul_f32 v[96:97], v[64:65], v[96:97]
	v_pk_mul_f32 v[98:99], v[66:67], v[98:99]
	v_pk_fma_f32 v[96:97], v[160:161], v[96:97], v[176:177]
	v_pk_fma_f32 v[98:99], v[162:163], v[98:99], v[178:179]
	v_cvt_pk_bf16_f32 v244, v96, v97
	v_cvt_pk_bf16_f32 v245, v98, v99
	v_pk_mul_f32 v[100:101], v[100:101], v[232:233] op_sel_hi:[1,0]
	v_pk_mul_f32 v[102:103], v[102:103], v[232:233] op_sel_hi:[1,0]
	v_pk_mul_f32 v[100:101], v[68:69], v[100:101]
	v_pk_mul_f32 v[102:103], v[70:71], v[102:103]
	v_pk_fma_f32 v[100:101], v[164:165], v[100:101], v[180:181]
	v_pk_fma_f32 v[102:103], v[166:167], v[102:103], v[182:183]
	v_cvt_pk_bf16_f32 v246, v100, v101
	v_cvt_pk_bf16_f32 v247, v102, v103
	global_store_dwordx4 v82, v[244:247], s[38:39] offset:0
	v_pk_mul_f32 v[104:105], v[104:105], v[232:233] op_sel_hi:[1,0]
	v_pk_mul_f32 v[106:107], v[106:107], v[232:233] op_sel_hi:[1,0]
	v_pk_mul_f32 v[104:105], v[72:73], v[104:105]
	v_pk_mul_f32 v[106:107], v[74:75], v[106:107]
	v_pk_fma_f32 v[104:105], v[168:169], v[104:105], v[184:185]
	v_pk_fma_f32 v[106:107], v[170:171], v[106:107], v[186:187]
	v_cvt_pk_bf16_f32 v240, v104, v105
	v_cvt_pk_bf16_f32 v241, v106, v107
	v_pk_mul_f32 v[108:109], v[108:109], v[232:233] op_sel_hi:[1,0]
	v_pk_mul_f32 v[110:111], v[110:111], v[232:233] op_sel_hi:[1,0]
	v_pk_mul_f32 v[108:109], v[76:77], v[108:109]
	v_pk_mul_f32 v[110:111], v[78:79], v[110:111]
	v_pk_fma_f32 v[108:109], v[172:173], v[108:109], v[188:189]
	v_pk_fma_f32 v[110:111], v[174:175], v[110:111], v[190:191]
	v_cvt_pk_bf16_f32 v242, v108, v109
	v_cvt_pk_bf16_f32 v243, v110, v111
	global_store_dwordx4 v82, v[240:243], s[38:39] offset:1024
	v_pk_mul_f32 v[112:113], v[112:113], v[234:235] op_sel_hi:[1,0]
	v_pk_mul_f32 v[114:115], v[114:115], v[234:235] op_sel_hi:[1,0]
	v_pk_mul_f32 v[112:113], v[64:65], v[112:113]
	v_pk_mul_f32 v[114:115], v[66:67], v[114:115]
	v_pk_fma_f32 v[112:113], v[160:161], v[112:113], v[176:177]
	v_pk_fma_f32 v[114:115], v[162:163], v[114:115], v[178:179]
	v_cvt_pk_bf16_f32 v244, v112, v113
	v_cvt_pk_bf16_f32 v245, v114, v115
	v_pk_mul_f32 v[116:117], v[116:117], v[234:235] op_sel_hi:[1,0]
	v_pk_mul_f32 v[118:119], v[118:119], v[234:235] op_sel_hi:[1,0]
	v_pk_mul_f32 v[116:117], v[68:69], v[116:117]
	v_pk_mul_f32 v[118:119], v[70:71], v[118:119]
	v_pk_fma_f32 v[116:117], v[164:165], v[116:117], v[180:181]
	v_pk_fma_f32 v[118:119], v[166:167], v[118:119], v[182:183]
	v_cvt_pk_bf16_f32 v246, v116, v117
	v_cvt_pk_bf16_f32 v247, v118, v119
	global_store_dwordx4 v82, v[244:247], s[40:41] offset:0
	v_pk_mul_f32 v[120:121], v[120:121], v[234:235] op_sel_hi:[1,0]
	v_pk_mul_f32 v[122:123], v[122:123], v[234:235] op_sel_hi:[1,0]
	v_pk_mul_f32 v[120:121], v[72:73], v[120:121]
	v_pk_mul_f32 v[122:123], v[74:75], v[122:123]
	v_pk_fma_f32 v[120:121], v[168:169], v[120:121], v[184:185]
	v_pk_fma_f32 v[122:123], v[170:171], v[122:123], v[186:187]
	v_cvt_pk_bf16_f32 v240, v120, v121
	v_cvt_pk_bf16_f32 v241, v122, v123
	v_pk_mul_f32 v[124:125], v[124:125], v[234:235] op_sel_hi:[1,0]
	v_pk_mul_f32 v[126:127], v[126:127], v[234:235] op_sel_hi:[1,0]
	v_pk_mul_f32 v[124:125], v[76:77], v[124:125]
	v_pk_mul_f32 v[126:127], v[78:79], v[126:127]
	v_pk_fma_f32 v[124:125], v[172:173], v[124:125], v[188:189]
	v_pk_fma_f32 v[126:127], v[174:175], v[126:127], v[190:191]
	v_cvt_pk_bf16_f32 v242, v124, v125
	v_cvt_pk_bf16_f32 v243, v126, v127
	global_store_dwordx4 v82, v[240:243], s[40:41] offset:1024
	v_pk_mul_f32 v[128:129], v[128:129], v[236:237] op_sel_hi:[1,0]
	v_pk_mul_f32 v[130:131], v[130:131], v[236:237] op_sel_hi:[1,0]
	v_pk_mul_f32 v[128:129], v[64:65], v[128:129]
	v_pk_mul_f32 v[130:131], v[66:67], v[130:131]
	v_pk_fma_f32 v[128:129], v[192:193], v[128:129], v[208:209]
	v_pk_fma_f32 v[130:131], v[194:195], v[130:131], v[210:211]
	v_cvt_pk_bf16_f32 v244, v128, v129
	v_cvt_pk_bf16_f32 v245, v130, v131
	v_pk_mul_f32 v[132:133], v[132:133], v[236:237] op_sel_hi:[1,0]
	v_pk_mul_f32 v[134:135], v[134:135], v[236:237] op_sel_hi:[1,0]
	v_pk_mul_f32 v[132:133], v[68:69], v[132:133]
	v_pk_mul_f32 v[134:135], v[70:71], v[134:135]
	v_pk_fma_f32 v[132:133], v[196:197], v[132:133], v[212:213]
	v_pk_fma_f32 v[134:135], v[198:199], v[134:135], v[214:215]
	v_cvt_pk_bf16_f32 v246, v132, v133
	v_cvt_pk_bf16_f32 v247, v134, v135
	global_store_dwordx4 v82, v[244:247], s[46:47] offset:0
	v_pk_mul_f32 v[136:137], v[136:137], v[236:237] op_sel_hi:[1,0]
; __device__ __forceinline__ float bf_lo(unsigned w) { return __uint_as_float(w << 16); }
; __device__ __forceinline__ float bf_hi(unsigned w) { return __uint_as_float(w & 0xffff0000u); }
; __device__ __forceinline__ unsigned pk2(float lo, float hi) { return pg8::cvt_pk_bf16(lo, hi); }
; template <bool BF> __device__ __forceinline__ void prep_rows(const float* xp, const float* xs, const bf16* hb, const float* g, const float* MOD, int shoff, int scoff, bf16* U, int gw, int NGW, int lane) {
;     ...
;         f32x4 v[R][4]; float s[R];
; #pragma unroll
;         for (int r = 0; r < R; ++r) { const int m = mb + r * NGW; const int mc = m < MT ? m : mb;
; #pragma unroll
;             for (int j = 0; j < 4; ++j) {
;                 if (BF) { const v2u a0 = *(const v2u*)(hb + (size_t)mc * DM + 4 * lane + 256 * j);
;                     v[r][j].x = pg8::bf_lo(a0.x); v[r][j].y = pg8::bf_hi(a0.x); v[r][j].z = pg8::bf_lo(a0.y); v[r][j].w = pg8::bf_hi(a0.y); }
;                 else { const float* xr = mc < MP ? xp + (size_t)mc * DM : xs + (size_t)(mc - MP) * DM; v[r][j] = *(const f32x4*)(xr + 4 * lane + 256 * j); } } }
; #pragma unroll
;         for (int r = 0; r < R; ++r) { float t = 0.f;
; #pragma unroll
;             for (int j = 0; j < 4; ++j) t += (v[r][j].x * v[r][j].x + v[r][j].y * v[r][j].y) + (v[r][j].z * v[r][j].z + v[r][j].w * v[r][j].w);
;             s[r] = t; }
; #pragma unroll
;         for (int o = 1; o < 64; o <<= 1) {
; #pragma unroll
;             for (int r = 0; r < R; ++r) s[r] += __shfl_xor(s[r], o); }
; #pragma unroll
;         for (int r = 0; r < R; ++r) { const int m = mb + r * NGW; if (m < MT) {
;             const float rstd = 1.0f / sqrtf(s[r] * (1.0f / DM) + RMS_EPS);
;             const float* mr = MOD + (size_t)(m < MP ? (m >> 13) : 8 + ((m - MP) >> 12)) * 6144;
; #pragma unroll
;             for (int j = 0; j < 4; ++j) { const int c = 4 * lane + 256 * j;
;                 const f32x4 gg = *(const f32x4*)(g + c), sc = *(const f32x4*)(mr + scoff + c), sh = *(const f32x4*)(mr + shoff + c);
;                 const f32x4 o = v[r][j] * rstd * gg * (sc + 1.0f) + sh; v2u w; w.x = pk2(o.x, o.y); w.y = pk2(o.z, o.w); *(v2u*)(U + (size_t)m * DM + c) = w; } } }
	v_pk_mul_f32 v[138:139], v[138:139], v[236:237] op_sel_hi:[1,0]
	v_pk_mul_f32 v[136:137], v[72:73], v[136:137]
	v_pk_mul_f32 v[138:139], v[74:75], v[138:139]
	v_pk_fma_f32 v[136:137], v[200:201], v[136:137], v[216:217]
	v_pk_fma_f32 v[138:139], v[202:203], v[138:139], v[218:219]
	v_cvt_pk_bf16_f32 v240, v136, v137
	v_cvt_pk_bf16_f32 v241, v138, v139
	v_pk_mul_f32 v[140:141], v[140:141], v[236:237] op_sel_hi:[1,0]
	v_pk_mul_f32 v[142:143], v[142:143], v[236:237] op_sel_hi:[1,0]
	v_pk_mul_f32 v[140:141], v[76:77], v[140:141]
	v_pk_mul_f32 v[142:143], v[78:79], v[142:143]
	v_pk_fma_f32 v[140:141], v[204:205], v[140:141], v[220:221]
	v_pk_fma_f32 v[142:143], v[206:207], v[142:143], v[222:223]
	v_cvt_pk_bf16_f32 v242, v140, v141
	v_cvt_pk_bf16_f32 v243, v142, v143
	global_store_dwordx4 v82, v[240:243], s[46:47] offset:1024
	v_pk_mul_f32 v[144:145], v[144:145], v[238:239] op_sel_hi:[1,0]
	v_pk_mul_f32 v[146:147], v[146:147], v[238:239] op_sel_hi:[1,0]
	v_pk_mul_f32 v[144:145], v[64:65], v[144:145]
	v_pk_mul_f32 v[146:147], v[66:67], v[146:147]
	v_pk_fma_f32 v[144:145], v[192:193], v[144:145], v[208:209]
	v_pk_fma_f32 v[146:147], v[194:195], v[146:147], v[210:211]
	v_cvt_pk_bf16_f32 v244, v144, v145
	v_cvt_pk_bf16_f32 v245, v146, v147
	v_pk_mul_f32 v[148:149], v[148:149], v[238:239] op_sel_hi:[1,0]
	v_pk_mul_f32 v[150:151], v[150:151], v[238:239] op_sel_hi:[1,0]
	v_pk_mul_f32 v[148:149], v[68:69], v[148:149]
	v_pk_mul_f32 v[150:151], v[70:71], v[150:151]
	v_pk_fma_f32 v[148:149], v[196:197], v[148:149], v[212:213]
	v_pk_fma_f32 v[150:151], v[198:199], v[150:151], v[214:215]
	v_cvt_pk_bf16_f32 v246, v148, v149
	v_cvt_pk_bf16_f32 v247, v150, v151
	global_store_dwordx4 v82, v[244:247], s[48:49] offset:0
	v_pk_mul_f32 v[152:153], v[152:153], v[238:239] op_sel_hi:[1,0]
	v_pk_mul_f32 v[154:155], v[154:155], v[238:239] op_sel_hi:[1,0]
	v_pk_mul_f32 v[152:153], v[72:73], v[152:153]
	v_pk_mul_f32 v[154:155], v[74:75], v[154:155]
	v_pk_fma_f32 v[152:153], v[200:201], v[152:153], v[216:217]
	v_pk_fma_f32 v[154:155], v[202:203], v[154:155], v[218:219]
	v_cvt_pk_bf16_f32 v240, v152, v153
	v_cvt_pk_bf16_f32 v241, v154, v155
	v_pk_mul_f32 v[156:157], v[156:157], v[238:239] op_sel_hi:[1,0]
	v_pk_mul_f32 v[158:159], v[158:159], v[238:239] op_sel_hi:[1,0]
	v_pk_mul_f32 v[156:157], v[76:77], v[156:157]
	v_pk_mul_f32 v[158:159], v[78:79], v[158:159]
	v_pk_fma_f32 v[156:157], v[204:205], v[156:157], v[220:221]
	v_pk_fma_f32 v[158:159], v[206:207], v[158:159], v[222:223]
	v_cvt_pk_bf16_f32 v242, v156, v157
	v_cvt_pk_bf16_f32 v243, v158, v159
	global_store_dwordx4 v82, v[240:243], s[48:49] offset:1024
	s_add_u32 s34, s8, 0x18000
	s_addc_u32 s35, s9, 0
	s_add_u32 s36, s8, 0x18000
	s_addc_u32 s37, s9, 0
	global_load_dwordx4 v[176:179], v80, s[34:35] offset:0
	global_load_dwordx4 v[180:183], v80, s[34:35] offset:16
	global_load_dwordx4 v[184:187], v80, s[34:35] offset:2048
	global_load_dwordx4 v[188:191], v80, s[34:35] offset:2064
	global_load_dwordx4 v[160:163], v81, s[34:35] offset:0
	global_load_dwordx4 v[164:167], v81, s[34:35] offset:16
	global_load_dwordx4 v[168:171], v81, s[34:35] offset:2048
	global_load_dwordx4 v[172:175], v81, s[34:35] offset:2064
	global_load_dwordx4 v[208:211], v80, s[36:37] offset:0
	global_load_dwordx4 v[212:215], v80, s[36:37] offset:16
	global_load_dwordx4 v[216:219], v80, s[36:37] offset:2048
	global_load_dwordx4 v[220:223], v80, s[36:37] offset:2064
	global_load_dwordx4 v[192:195], v81, s[36:37] offset:0
	global_load_dwordx4 v[196:199], v81, s[36:37] offset:16
	global_load_dwordx4 v[200:203], v81, s[36:37] offset:2048
	global_load_dwordx4 v[204:207], v81, s[36:37] offset:2064
	s_add_u32 s24, s16, 0xa000000
	s_addc_u32 s25, s17, 0
	s_add_u32 s26, s16, 0xa800000
	s_addc_u32 s27, s17, 0
	s_add_u32 s28, s16, 0xb000000
	s_addc_u32 s29, s17, 0
	s_add_u32 s30, s16, 0xb800000
	s_addc_u32 s31, s17, 0
	global_load_dwordx4 v[96:99], v80, s[24:25] offset:0
	global_load_dwordx4 v[100:103], v80, s[24:25] offset:16
	global_load_dwordx4 v[104:107], v80, s[24:25] offset:2048
	global_load_dwordx4 v[108:111], v80, s[24:25] offset:2064
	global_load_dwordx4 v[112:115], v80, s[26:27] offset:0
	global_load_dwordx4 v[116:119], v80, s[26:27] offset:16
	global_load_dwordx4 v[120:123], v80, s[26:27] offset:2048
	global_load_dwordx4 v[124:127], v80, s[26:27] offset:2064
	global_load_dwordx4 v[128:131], v80, s[28:29] offset:0
	global_load_dwordx4 v[132:135], v80, s[28:29] offset:16
	global_load_dwordx4 v[136:139], v80, s[28:29] offset:2048
	global_load_dwordx4 v[140:143], v80, s[28:29] offset:2064
	global_load_dwordx4 v[144:147], v80, s[30:31] offset:0
	global_load_dwordx4 v[148:151], v80, s[30:31] offset:16
	global_load_dwordx4 v[152:155], v80, s[30:31] offset:2048
	global_load_dwordx4 v[156:159], v80, s[30:31] offset:2064
	s_waitcnt vmcnt(40)
; template <bool BF> __device__ __forceinline__ void prep_rows(const float* xp, const float* xs, const bf16* hb, const float* g, const float* MOD, int shoff, int scoff, bf16* U, int gw, int NGW, int lane) {
;     ...
;         for (int r = 0; r < R; ++r) { float t = 0.f;
; #pragma unroll
;             for (int j = 0; j < 4; ++j) t += (v[r][j].x * v[r][j].x + v[r][j].y * v[r][j].y) + (v[r][j].z * v[r][j].z + v[r][j].w * v[r][j].w);
;             s[r] = t; }
; #pragma unroll
;         for (int o = 1; o < 64; o <<= 1) {
; #pragma unroll
;             for (int r = 0; r < R; ++r) s[r] += __shfl_xor(s[r], o); }
; #pragma unroll
;         for (int r = 0; r < R; ++r) { const int m = mb + r * NGW; if (m < MT) {
;             const float rstd = 1.0f / sqrtf(s[r] * (1.0f / DM) + RMS_EPS);
	v_pk_mul_f32 v[240:241], v[0:1], v[0:1]
	v_pk_mul_f32 v[242:243], v[16:17], v[16:17]
	v_pk_mul_f32 v[244:245], v[32:33], v[32:33]
	v_pk_mul_f32 v[246:247], v[48:49], v[48:49]
	v_pk_fma_f32 v[240:241], v[2:3], v[2:3], v[240:241]
	v_pk_fma_f32 v[242:243], v[18:19], v[18:19], v[242:243]
	v_pk_fma_f32 v[244:245], v[34:35], v[34:35], v[244:245]
	v_pk_fma_f32 v[246:247], v[50:51], v[50:51], v[246:247]
	v_pk_fma_f32 v[240:241], v[4:5], v[4:5], v[240:241]
	v_pk_fma_f32 v[242:243], v[20:21], v[20:21], v[242:243]
	v_pk_fma_f32 v[244:245], v[36:37], v[36:37], v[244:245]
	v_pk_fma_f32 v[246:247], v[52:53], v[52:53], v[246:247]
	v_pk_fma_f32 v[240:241], v[6:7], v[6:7], v[240:241]
	v_pk_fma_f32 v[242:243], v[22:23], v[22:23], v[242:243]
	v_pk_fma_f32 v[244:245], v[38:39], v[38:39], v[244:245]
	v_pk_fma_f32 v[246:247], v[54:55], v[54:55], v[246:247]
	v_pk_fma_f32 v[240:241], v[8:9], v[8:9], v[240:241]
	v_pk_fma_f32 v[242:243], v[24:25], v[24:25], v[242:243]
	v_pk_fma_f32 v[244:245], v[40:41], v[40:41], v[244:245]
	v_pk_fma_f32 v[246:247], v[56:57], v[56:57], v[246:247]
	v_pk_fma_f32 v[240:241], v[10:11], v[10:11], v[240:241]
	v_pk_fma_f32 v[242:243], v[26:27], v[26:27], v[242:243]
	v_pk_fma_f32 v[244:245], v[42:43], v[42:43], v[244:245]
	v_pk_fma_f32 v[246:247], v[58:59], v[58:59], v[246:247]
	v_pk_fma_f32 v[240:241], v[12:13], v[12:13], v[240:241]
	v_pk_fma_f32 v[242:243], v[28:29], v[28:29], v[242:243]
	v_pk_fma_f32 v[244:245], v[44:45], v[44:45], v[244:245]
	v_pk_fma_f32 v[246:247], v[60:61], v[60:61], v[246:247]
	v_pk_fma_f32 v[240:241], v[14:15], v[14:15], v[240:241]
	v_pk_fma_f32 v[242:243], v[30:31], v[30:31], v[242:243]
	v_pk_fma_f32 v[244:245], v[46:47], v[46:47], v[244:245]
	v_pk_fma_f32 v[246:247], v[62:63], v[62:63], v[246:247]
	v_add_f32_e32 v224, v240, v241
	v_add_f32_e32 v225, v242, v243
	v_add_f32_e32 v226, v244, v245
	v_add_f32_e32 v227, v246, v247
	ds_bpermute_b32 v228, v83, v224
	ds_bpermute_b32 v229, v83, v225
	ds_bpermute_b32 v230, v83, v226
	ds_bpermute_b32 v231, v83, v227
	s_waitcnt lgkmcnt(0)
	v_add_f32_e32 v224, v224, v228
	v_add_f32_e32 v225, v225, v229
	v_add_f32_e32 v226, v226, v230
	v_add_f32_e32 v227, v227, v231
	ds_bpermute_b32 v228, v84, v224
	ds_bpermute_b32 v229, v84, v225
	ds_bpermute_b32 v230, v84, v226
	ds_bpermute_b32 v231, v84, v227
	s_waitcnt lgkmcnt(0)
	v_add_f32_e32 v224, v224, v228
	v_add_f32_e32 v225, v225, v229
	v_add_f32_e32 v226, v226, v230
	v_add_f32_e32 v227, v227, v231
	ds_bpermute_b32 v228, v85, v224
	ds_bpermute_b32 v229, v85, v225
	ds_bpermute_b32 v230, v85, v226
	ds_bpermute_b32 v231, v85, v227
	s_waitcnt lgkmcnt(0)
	v_add_f32_e32 v224, v224, v228
	v_add_f32_e32 v225, v225, v229
	v_add_f32_e32 v226, v226, v230
	v_add_f32_e32 v227, v227, v231
	ds_bpermute_b32 v228, v86, v224
	ds_bpermute_b32 v229, v86, v225
	ds_bpermute_b32 v230, v86, v226
	ds_bpermute_b32 v231, v86, v227
	s_waitcnt lgkmcnt(0)
	v_add_f32_e32 v224, v224, v228
	v_add_f32_e32 v225, v225, v229
	v_add_f32_e32 v226, v226, v230
	v_add_f32_e32 v227, v227, v231
	ds_bpermute_b32 v228, v87, v224
	ds_bpermute_b32 v229, v87, v225
	ds_bpermute_b32 v230, v87, v226
	ds_bpermute_b32 v231, v87, v227
	s_waitcnt lgkmcnt(0)
	v_add_f32_e32 v224, v224, v228
	v_add_f32_e32 v225, v225, v229
	v_add_f32_e32 v226, v226, v230
	v_add_f32_e32 v227, v227, v231
	ds_bpermute_b32 v228, v88, v224
	ds_bpermute_b32 v229, v88, v225
	ds_bpermute_b32 v230, v88, v226
	ds_bpermute_b32 v231, v88, v227
	s_waitcnt lgkmcnt(0)
	v_add_f32_e32 v224, v224, v228
	v_add_f32_e32 v225, v225, v229
	v_add_f32_e32 v226, v226, v230
	v_add_f32_e32 v227, v227, v231
	v_fmamk_f32 v240, v224, 0x3a800000, v89
	v_mul_f32_e32 v241, 0x4f800000, v240
	v_cmp_gt_f32_e32 vcc, s54, v240
	s_nop 1
	v_cndmask_b32_e32 v247, v240, v241, vcc
	v_sqrt_f32_e32 v242, v247
	s_nop 1
	v_add_u32_e32 v243, -1, v242
	v_add_u32_e32 v244, 1, v242
	v_fma_f32 v245, -v243, v242, v247
	v_fma_f32 v246, -v244, v242, v247
	v_cmp_ge_f32_e64 s[52:53], 0, v245
	s_nop 1
	v_cndmask_b32_e64 v242, v242, v243, s[52:53]
	v_cmp_lt_f32_e64 s[52:53], 0, v246
	s_nop 1
	v_cndmask_b32_e64 v242, v242, v244, s[52:53]
	v_mul_f32_e32 v243, 0x37800000, v242
	v_cndmask_b32_e32 v242, v242, v243, vcc
	v_cmp_class_f32_e32 vcc, v247, v90
	s_nop 1
	v_cndmask_b32_e32 v247, v242, v247, vcc
	v_div_scale_f32 v248, s[52:53], v247, v247, 1.0
	v_rcp_f32_e32 v249, v248
	v_div_scale_f32 v228, vcc, 1.0, v247, 1.0
	s_nop 0
	v_fma_f32 v229, -v248, v249, 1.0
	v_fmac_f32_e32 v249, v229, v249
	v_mul_f32_e32 v230, v228, v249
	v_fma_f32 v229, -v248, v230, v228
	v_fmac_f32_e32 v230, v229, v249
	v_fma_f32 v248, -v248, v230, v228
	v_div_fmas_f32 v248, v248, v249, v230
	v_div_fixup_f32 v232, v248, v247, 1.0
	v_fmamk_f32 v240, v225, 0x3a800000, v89
	v_mul_f32_e32 v241, 0x4f800000, v240
	v_cmp_gt_f32_e32 vcc, s54, v240
	s_nop 1
	v_cndmask_b32_e32 v247, v240, v241, vcc
	v_sqrt_f32_e32 v242, v247
	s_nop 1
	v_add_u32_e32 v243, -1, v242
	v_add_u32_e32 v244, 1, v242
	v_fma_f32 v245, -v243, v242, v247
	v_fma_f32 v246, -v244, v242, v247
	v_cmp_ge_f32_e64 s[52:53], 0, v245
	s_nop 1
	v_cndmask_b32_e64 v242, v242, v243, s[52:53]
	v_cmp_lt_f32_e64 s[52:53], 0, v246
	s_nop 1
	v_cndmask_b32_e64 v242, v242, v244, s[52:53]
	v_mul_f32_e32 v243, 0x37800000, v242
	v_cndmask_b32_e32 v242, v242, v243, vcc
	v_cmp_class_f32_e32 vcc, v247, v90
	s_nop 1
	v_cndmask_b32_e32 v247, v242, v247, vcc
	v_div_scale_f32 v248, s[52:53], v247, v247, 1.0
	v_rcp_f32_e32 v249, v248
	v_div_scale_f32 v228, vcc, 1.0, v247, 1.0
	s_nop 0
	v_fma_f32 v229, -v248, v249, 1.0
	v_fmac_f32_e32 v249, v229, v249
	v_mul_f32_e32 v230, v228, v249
	v_fma_f32 v229, -v248, v230, v228
	v_fmac_f32_e32 v230, v229, v249
; __device__ __forceinline__ unsigned pk2(float lo, float hi) { return pg8::cvt_pk_bf16(lo, hi); }
; template <bool BF> __device__ __forceinline__ void prep_rows(const float* xp, const float* xs, const bf16* hb, const float* g, const float* MOD, int shoff, int scoff, bf16* U, int gw, int NGW, int lane) {
;     ...
;             const float rstd = 1.0f / sqrtf(s[r] * (1.0f / DM) + RMS_EPS);
;             const float* mr = MOD + (size_t)(m < MP ? (m >> 13) : 8 + ((m - MP) >> 12)) * 6144;
; #pragma unroll
;             for (int j = 0; j < 4; ++j) { const int c = 4 * lane + 256 * j;
;                 const f32x4 gg = *(const f32x4*)(g + c), sc = *(const f32x4*)(mr + scoff + c), sh = *(const f32x4*)(mr + shoff + c);
;                 const f32x4 o = v[r][j] * rstd * gg * (sc + 1.0f) + sh; v2u w; w.x = pk2(o.x, o.y); w.y = pk2(o.z, o.w); *(v2u*)(U + (size_t)m * DM + c) = w; } } }
	v_fma_f32 v248, -v248, v230, v228
	v_div_fmas_f32 v248, v248, v249, v230
	v_div_fixup_f32 v234, v248, v247, 1.0
	v_fmamk_f32 v240, v226, 0x3a800000, v89
	v_mul_f32_e32 v241, 0x4f800000, v240
	v_cmp_gt_f32_e32 vcc, s54, v240
	s_nop 1
	v_cndmask_b32_e32 v247, v240, v241, vcc
	v_sqrt_f32_e32 v242, v247
	s_nop 1
	v_add_u32_e32 v243, -1, v242
	v_add_u32_e32 v244, 1, v242
	v_fma_f32 v245, -v243, v242, v247
	v_fma_f32 v246, -v244, v242, v247
	v_cmp_ge_f32_e64 s[52:53], 0, v245
	s_nop 1
	v_cndmask_b32_e64 v242, v242, v243, s[52:53]
	v_cmp_lt_f32_e64 s[52:53], 0, v246
	s_nop 1
	v_cndmask_b32_e64 v242, v242, v244, s[52:53]
	v_mul_f32_e32 v243, 0x37800000, v242
	v_cndmask_b32_e32 v242, v242, v243, vcc
	v_cmp_class_f32_e32 vcc, v247, v90
	s_nop 1
	v_cndmask_b32_e32 v247, v242, v247, vcc
	v_div_scale_f32 v248, s[52:53], v247, v247, 1.0
	v_rcp_f32_e32 v249, v248
	v_div_scale_f32 v228, vcc, 1.0, v247, 1.0
	s_nop 0
	v_fma_f32 v229, -v248, v249, 1.0
	v_fmac_f32_e32 v249, v229, v249
	v_mul_f32_e32 v230, v228, v249
	v_fma_f32 v229, -v248, v230, v228
	v_fmac_f32_e32 v230, v229, v249
	v_fma_f32 v248, -v248, v230, v228
	v_div_fmas_f32 v248, v248, v249, v230
	v_div_fixup_f32 v236, v248, v247, 1.0
	v_fmamk_f32 v240, v227, 0x3a800000, v89
	v_mul_f32_e32 v241, 0x4f800000, v240
	v_cmp_gt_f32_e32 vcc, s54, v240
	s_nop 1
	v_cndmask_b32_e32 v247, v240, v241, vcc
	v_sqrt_f32_e32 v242, v247
	s_nop 1
	v_add_u32_e32 v243, -1, v242
	v_add_u32_e32 v244, 1, v242
	v_fma_f32 v245, -v243, v242, v247
	v_fma_f32 v246, -v244, v242, v247
	v_cmp_ge_f32_e64 s[52:53], 0, v245
	s_nop 1
	v_cndmask_b32_e64 v242, v242, v243, s[52:53]
	v_cmp_lt_f32_e64 s[52:53], 0, v246
	s_nop 1
	v_cndmask_b32_e64 v242, v242, v244, s[52:53]
	v_mul_f32_e32 v243, 0x37800000, v242
	v_cndmask_b32_e32 v242, v242, v243, vcc
	v_cmp_class_f32_e32 vcc, v247, v90
	s_nop 1
	v_cndmask_b32_e32 v247, v242, v247, vcc
	v_div_scale_f32 v248, s[52:53], v247, v247, 1.0
	v_rcp_f32_e32 v249, v248
	v_div_scale_f32 v228, vcc, 1.0, v247, 1.0
	s_nop 0
	v_fma_f32 v229, -v248, v249, 1.0
	v_fmac_f32_e32 v249, v229, v249
	v_mul_f32_e32 v230, v228, v249
	v_fma_f32 v229, -v248, v230, v228
	v_fmac_f32_e32 v230, v229, v249
	v_fma_f32 v248, -v248, v230, v228
	v_div_fmas_f32 v248, v248, v249, v230
	v_div_fixup_f32 v238, v248, v247, 1.0
	s_waitcnt vmcnt(16)
	v_pk_add_f32 v[160:161], v[160:161], 1.0 op_sel_hi:[1,0]
	v_pk_add_f32 v[162:163], v[162:163], 1.0 op_sel_hi:[1,0]
	v_pk_add_f32 v[164:165], v[164:165], 1.0 op_sel_hi:[1,0]
	v_pk_add_f32 v[166:167], v[166:167], 1.0 op_sel_hi:[1,0]
	v_pk_add_f32 v[168:169], v[168:169], 1.0 op_sel_hi:[1,0]
	v_pk_add_f32 v[170:171], v[170:171], 1.0 op_sel_hi:[1,0]
	v_pk_add_f32 v[172:173], v[172:173], 1.0 op_sel_hi:[1,0]
	v_pk_add_f32 v[174:175], v[174:175], 1.0 op_sel_hi:[1,0]
	v_pk_add_f32 v[192:193], v[192:193], 1.0 op_sel_hi:[1,0]
	v_pk_add_f32 v[194:195], v[194:195], 1.0 op_sel_hi:[1,0]
	v_pk_add_f32 v[196:197], v[196:197], 1.0 op_sel_hi:[1,0]
	v_pk_add_f32 v[198:199], v[198:199], 1.0 op_sel_hi:[1,0]
	v_pk_add_f32 v[200:201], v[200:201], 1.0 op_sel_hi:[1,0]
	v_pk_add_f32 v[202:203], v[202:203], 1.0 op_sel_hi:[1,0]
	v_pk_add_f32 v[204:205], v[204:205], 1.0 op_sel_hi:[1,0]
	v_pk_add_f32 v[206:207], v[206:207], 1.0 op_sel_hi:[1,0]
	s_add_u32 s38, s20, 0x4000000
	s_addc_u32 s39, s21, 0
	s_add_u32 s40, s20, 0x4400000
	s_addc_u32 s41, s21, 0
	s_add_u32 s46, s20, 0x4800000
	s_addc_u32 s47, s21, 0
	s_add_u32 s48, s20, 0x4c00000
	s_addc_u32 s49, s21, 0
	v_pk_mul_f32 v[0:1], v[0:1], v[232:233] op_sel_hi:[1,0]
	v_pk_mul_f32 v[2:3], v[2:3], v[232:233] op_sel_hi:[1,0]
	v_pk_mul_f32 v[0:1], v[64:65], v[0:1]
	v_pk_mul_f32 v[2:3], v[66:67], v[2:3]
	v_pk_fma_f32 v[0:1], v[160:161], v[0:1], v[176:177]
	v_pk_fma_f32 v[2:3], v[162:163], v[2:3], v[178:179]
	v_cvt_pk_bf16_f32 v244, v0, v1
	v_cvt_pk_bf16_f32 v245, v2, v3
	v_pk_mul_f32 v[4:5], v[4:5], v[232:233] op_sel_hi:[1,0]
	v_pk_mul_f32 v[6:7], v[6:7], v[232:233] op_sel_hi:[1,0]
	v_pk_mul_f32 v[4:5], v[68:69], v[4:5]
	v_pk_mul_f32 v[6:7], v[70:71], v[6:7]
	v_pk_fma_f32 v[4:5], v[164:165], v[4:5], v[180:181]
	v_pk_fma_f32 v[6:7], v[166:167], v[6:7], v[182:183]
	v_cvt_pk_bf16_f32 v246, v4, v5
	v_cvt_pk_bf16_f32 v247, v6, v7
	global_store_dwordx4 v82, v[244:247], s[38:39] offset:0
	v_pk_mul_f32 v[8:9], v[8:9], v[232:233] op_sel_hi:[1,0]
	v_pk_mul_f32 v[10:11], v[10:11], v[232:233] op_sel_hi:[1,0]
	v_pk_mul_f32 v[8:9], v[72:73], v[8:9]
	v_pk_mul_f32 v[10:11], v[74:75], v[10:11]
	v_pk_fma_f32 v[8:9], v[168:169], v[8:9], v[184:185]
	v_pk_fma_f32 v[10:11], v[170:171], v[10:11], v[186:187]
	v_cvt_pk_bf16_f32 v240, v8, v9
	v_cvt_pk_bf16_f32 v241, v10, v11
	v_pk_mul_f32 v[12:13], v[12:13], v[232:233] op_sel_hi:[1,0]
	v_pk_mul_f32 v[14:15], v[14:15], v[232:233] op_sel_hi:[1,0]
	v_pk_mul_f32 v[12:13], v[76:77], v[12:13]
	v_pk_mul_f32 v[14:15], v[78:79], v[14:15]
	v_pk_fma_f32 v[12:13], v[172:173], v[12:13], v[188:189]
	v_pk_fma_f32 v[14:15], v[174:175], v[14:15], v[190:191]
	v_cvt_pk_bf16_f32 v242, v12, v13
	v_cvt_pk_bf16_f32 v243, v14, v15
	global_store_dwordx4 v82, v[240:243], s[38:39] offset:1024
	v_pk_mul_f32 v[16:17], v[16:17], v[234:235] op_sel_hi:[1,0]
	v_pk_mul_f32 v[18:19], v[18:19], v[234:235] op_sel_hi:[1,0]
	v_pk_mul_f32 v[16:17], v[64:65], v[16:17]
	v_pk_mul_f32 v[18:19], v[66:67], v[18:19]
	v_pk_fma_f32 v[16:17], v[160:161], v[16:17], v[176:177]
	v_pk_fma_f32 v[18:19], v[162:163], v[18:19], v[178:179]
	v_cvt_pk_bf16_f32 v244, v16, v17
	v_cvt_pk_bf16_f32 v245, v18, v19
	v_pk_mul_f32 v[20:21], v[20:21], v[234:235] op_sel_hi:[1,0]
	v_pk_mul_f32 v[22:23], v[22:23], v[234:235] op_sel_hi:[1,0]
	v_pk_mul_f32 v[20:21], v[68:69], v[20:21]
	v_pk_mul_f32 v[22:23], v[70:71], v[22:23]
; __device__ __forceinline__ float bf_lo(unsigned w) { return __uint_as_float(w << 16); }
; __device__ __forceinline__ float bf_hi(unsigned w) { return __uint_as_float(w & 0xffff0000u); }
; __device__ __forceinline__ unsigned pk2(float lo, float hi) { return pg8::cvt_pk_bf16(lo, hi); }
; template <bool BF> __device__ __forceinline__ void prep_rows(const float* xp, const float* xs, const bf16* hb, const float* g, const float* MOD, int shoff, int scoff, bf16* U, int gw, int NGW, int lane) {
;     ...
;         f32x4 v[R][4]; float s[R];
; #pragma unroll
;         for (int r = 0; r < R; ++r) { const int m = mb + r * NGW; const int mc = m < MT ? m : mb;
; #pragma unroll
;             for (int j = 0; j < 4; ++j) {
;                 if (BF) { const v2u a0 = *(const v2u*)(hb + (size_t)mc * DM + 4 * lane + 256 * j);
;                     v[r][j].x = pg8::bf_lo(a0.x); v[r][j].y = pg8::bf_hi(a0.x); v[r][j].z = pg8::bf_lo(a0.y); v[r][j].w = pg8::bf_hi(a0.y); }
;                 else { const float* xr = mc < MP ? xp + (size_t)mc * DM : xs + (size_t)(mc - MP) * DM; v[r][j] = *(const f32x4*)(xr + 4 * lane + 256 * j); } } }
; #pragma unroll
;         for (int r = 0; r < R; ++r) { float t = 0.f;
; #pragma unroll
;             for (int j = 0; j < 4; ++j) t += (v[r][j].x * v[r][j].x + v[r][j].y * v[r][j].y) + (v[r][j].z * v[r][j].z + v[r][j].w * v[r][j].w);
;             s[r] = t; }
; #pragma unroll
;         for (int o = 1; o < 64; o <<= 1) {
; #pragma unroll
;             for (int r = 0; r < R; ++r) s[r] += __shfl_xor(s[r], o); }
; #pragma unroll
;         for (int r = 0; r < R; ++r) { const int m = mb + r * NGW; if (m < MT) {
;             const float rstd = 1.0f / sqrtf(s[r] * (1.0f / DM) + RMS_EPS);
;             const float* mr = MOD + (size_t)(m < MP ? (m >> 13) : 8 + ((m - MP) >> 12)) * 6144;
; #pragma unroll
;             for (int j = 0; j < 4; ++j) { const int c = 4 * lane + 256 * j;
;                 const f32x4 gg = *(const f32x4*)(g + c), sc = *(const f32x4*)(mr + scoff + c), sh = *(const f32x4*)(mr + shoff + c);
;                 const f32x4 o = v[r][j] * rstd * gg * (sc + 1.0f) + sh; v2u w; w.x = pk2(o.x, o.y); w.y = pk2(o.z, o.w); *(v2u*)(U + (size_t)m * DM + c) = w; } } }
	v_pk_fma_f32 v[20:21], v[164:165], v[20:21], v[180:181]
	v_pk_fma_f32 v[22:23], v[166:167], v[22:23], v[182:183]
	v_cvt_pk_bf16_f32 v246, v20, v21
	v_cvt_pk_bf16_f32 v247, v22, v23
	global_store_dwordx4 v82, v[244:247], s[40:41] offset:0
	v_pk_mul_f32 v[24:25], v[24:25], v[234:235] op_sel_hi:[1,0]
	v_pk_mul_f32 v[26:27], v[26:27], v[234:235] op_sel_hi:[1,0]
	v_pk_mul_f32 v[24:25], v[72:73], v[24:25]
	v_pk_mul_f32 v[26:27], v[74:75], v[26:27]
	v_pk_fma_f32 v[24:25], v[168:169], v[24:25], v[184:185]
	v_pk_fma_f32 v[26:27], v[170:171], v[26:27], v[186:187]
	v_cvt_pk_bf16_f32 v240, v24, v25
	v_cvt_pk_bf16_f32 v241, v26, v27
	v_pk_mul_f32 v[28:29], v[28:29], v[234:235] op_sel_hi:[1,0]
	v_pk_mul_f32 v[30:31], v[30:31], v[234:235] op_sel_hi:[1,0]
	v_pk_mul_f32 v[28:29], v[76:77], v[28:29]
	v_pk_mul_f32 v[30:31], v[78:79], v[30:31]
	v_pk_fma_f32 v[28:29], v[172:173], v[28:29], v[188:189]
	v_pk_fma_f32 v[30:31], v[174:175], v[30:31], v[190:191]
	v_cvt_pk_bf16_f32 v242, v28, v29
	v_cvt_pk_bf16_f32 v243, v30, v31
	global_store_dwordx4 v82, v[240:243], s[40:41] offset:1024
	v_pk_mul_f32 v[32:33], v[32:33], v[236:237] op_sel_hi:[1,0]
	v_pk_mul_f32 v[34:35], v[34:35], v[236:237] op_sel_hi:[1,0]
	v_pk_mul_f32 v[32:33], v[64:65], v[32:33]
	v_pk_mul_f32 v[34:35], v[66:67], v[34:35]
	v_pk_fma_f32 v[32:33], v[192:193], v[32:33], v[208:209]
	v_pk_fma_f32 v[34:35], v[194:195], v[34:35], v[210:211]
	v_cvt_pk_bf16_f32 v244, v32, v33
	v_cvt_pk_bf16_f32 v245, v34, v35
	v_pk_mul_f32 v[36:37], v[36:37], v[236:237] op_sel_hi:[1,0]
	v_pk_mul_f32 v[38:39], v[38:39], v[236:237] op_sel_hi:[1,0]
	v_pk_mul_f32 v[36:37], v[68:69], v[36:37]
	v_pk_mul_f32 v[38:39], v[70:71], v[38:39]
	v_pk_fma_f32 v[36:37], v[196:197], v[36:37], v[212:213]
	v_pk_fma_f32 v[38:39], v[198:199], v[38:39], v[214:215]
	v_cvt_pk_bf16_f32 v246, v36, v37
	v_cvt_pk_bf16_f32 v247, v38, v39
	global_store_dwordx4 v82, v[244:247], s[46:47] offset:0
	v_pk_mul_f32 v[40:41], v[40:41], v[236:237] op_sel_hi:[1,0]
	v_pk_mul_f32 v[42:43], v[42:43], v[236:237] op_sel_hi:[1,0]
	v_pk_mul_f32 v[40:41], v[72:73], v[40:41]
	v_pk_mul_f32 v[42:43], v[74:75], v[42:43]
	v_pk_fma_f32 v[40:41], v[200:201], v[40:41], v[216:217]
	v_pk_fma_f32 v[42:43], v[202:203], v[42:43], v[218:219]
	v_cvt_pk_bf16_f32 v240, v40, v41
	v_cvt_pk_bf16_f32 v241, v42, v43
	v_pk_mul_f32 v[44:45], v[44:45], v[236:237] op_sel_hi:[1,0]
	v_pk_mul_f32 v[46:47], v[46:47], v[236:237] op_sel_hi:[1,0]
	v_pk_mul_f32 v[44:45], v[76:77], v[44:45]
	v_pk_mul_f32 v[46:47], v[78:79], v[46:47]
	v_pk_fma_f32 v[44:45], v[204:205], v[44:45], v[220:221]
	v_pk_fma_f32 v[46:47], v[206:207], v[46:47], v[222:223]
	v_cvt_pk_bf16_f32 v242, v44, v45
	v_cvt_pk_bf16_f32 v243, v46, v47
	global_store_dwordx4 v82, v[240:243], s[46:47] offset:1024
	v_pk_mul_f32 v[48:49], v[48:49], v[238:239] op_sel_hi:[1,0]
	v_pk_mul_f32 v[50:51], v[50:51], v[238:239] op_sel_hi:[1,0]
	v_pk_mul_f32 v[48:49], v[64:65], v[48:49]
	v_pk_mul_f32 v[50:51], v[66:67], v[50:51]
	v_pk_fma_f32 v[48:49], v[192:193], v[48:49], v[208:209]
	v_pk_fma_f32 v[50:51], v[194:195], v[50:51], v[210:211]
	v_cvt_pk_bf16_f32 v244, v48, v49
	v_cvt_pk_bf16_f32 v245, v50, v51
	v_pk_mul_f32 v[52:53], v[52:53], v[238:239] op_sel_hi:[1,0]
	v_pk_mul_f32 v[54:55], v[54:55], v[238:239] op_sel_hi:[1,0]
	v_pk_mul_f32 v[52:53], v[68:69], v[52:53]
	v_pk_mul_f32 v[54:55], v[70:71], v[54:55]
	v_pk_fma_f32 v[52:53], v[196:197], v[52:53], v[212:213]
	v_pk_fma_f32 v[54:55], v[198:199], v[54:55], v[214:215]
	v_cvt_pk_bf16_f32 v246, v52, v53
	v_cvt_pk_bf16_f32 v247, v54, v55
	global_store_dwordx4 v82, v[244:247], s[48:49] offset:0
	v_pk_mul_f32 v[56:57], v[56:57], v[238:239] op_sel_hi:[1,0]
	v_pk_mul_f32 v[58:59], v[58:59], v[238:239] op_sel_hi:[1,0]
	v_pk_mul_f32 v[56:57], v[72:73], v[56:57]
	v_pk_mul_f32 v[58:59], v[74:75], v[58:59]
	v_pk_fma_f32 v[56:57], v[200:201], v[56:57], v[216:217]
	v_pk_fma_f32 v[58:59], v[202:203], v[58:59], v[218:219]
	v_cvt_pk_bf16_f32 v240, v56, v57
	v_cvt_pk_bf16_f32 v241, v58, v59
	v_pk_mul_f32 v[60:61], v[60:61], v[238:239] op_sel_hi:[1,0]
	v_pk_mul_f32 v[62:63], v[62:63], v[238:239] op_sel_hi:[1,0]
	v_pk_mul_f32 v[60:61], v[76:77], v[60:61]
	v_pk_mul_f32 v[62:63], v[78:79], v[62:63]
	v_pk_fma_f32 v[60:61], v[204:205], v[60:61], v[220:221]
	v_pk_fma_f32 v[62:63], v[206:207], v[62:63], v[222:223]
	v_cvt_pk_bf16_f32 v242, v60, v61
	v_cvt_pk_bf16_f32 v243, v62, v63
	global_store_dwordx4 v82, v[240:243], s[48:49] offset:1024
	s_add_u32 s34, s8, 0x1e000
	s_addc_u32 s35, s9, 0
	s_add_u32 s36, s8, 0x1e000
	s_addc_u32 s37, s9, 0
	global_load_dwordx4 v[176:179], v80, s[34:35] offset:0
	global_load_dwordx4 v[180:183], v80, s[34:35] offset:16
	global_load_dwordx4 v[184:187], v80, s[34:35] offset:2048
	global_load_dwordx4 v[188:191], v80, s[34:35] offset:2064
	global_load_dwordx4 v[160:163], v81, s[34:35] offset:0
	global_load_dwordx4 v[164:167], v81, s[34:35] offset:16
	global_load_dwordx4 v[168:171], v81, s[34:35] offset:2048
	global_load_dwordx4 v[172:175], v81, s[34:35] offset:2064
	global_load_dwordx4 v[208:211], v80, s[36:37] offset:0
	global_load_dwordx4 v[212:215], v80, s[36:37] offset:16
	global_load_dwordx4 v[216:219], v80, s[36:37] offset:2048
	global_load_dwordx4 v[220:223], v80, s[36:37] offset:2064
	global_load_dwordx4 v[192:195], v81, s[36:37] offset:0
	global_load_dwordx4 v[196:199], v81, s[36:37] offset:16
	global_load_dwordx4 v[200:203], v81, s[36:37] offset:2048
	global_load_dwordx4 v[204:207], v81, s[36:37] offset:2064
	s_add_u32 s24, s16, 0xc000000
	s_addc_u32 s25, s17, 0
	s_add_u32 s26, s16, 0xc800000
	s_addc_u32 s27, s17, 0
	s_add_u32 s28, s16, 0xd000000
	s_addc_u32 s29, s17, 0
	s_add_u32 s30, s16, 0xd800000
	s_addc_u32 s31, s17, 0
	global_load_dwordx4 v[0:3], v80, s[24:25] offset:0
	global_load_dwordx4 v[4:7], v80, s[24:25] offset:16
	global_load_dwordx4 v[8:11], v80, s[24:25] offset:2048
	global_load_dwordx4 v[12:15], v80, s[24:25] offset:2064
	global_load_dwordx4 v[16:19], v80, s[26:27] offset:0
	global_load_dwordx4 v[20:23], v80, s[26:27] offset:16
	global_load_dwordx4 v[24:27], v80, s[26:27] offset:2048
	global_load_dwordx4 v[28:31], v80, s[26:27] offset:2064
	global_load_dwordx4 v[32:35], v80, s[28:29] offset:0
	global_load_dwordx4 v[36:39], v80, s[28:29] offset:16
	global_load_dwordx4 v[40:43], v80, s[28:29] offset:2048
	global_load_dwordx4 v[44:47], v80, s[28:29] offset:2064
	global_load_dwordx4 v[48:51], v80, s[30:31] offset:0
	global_load_dwordx4 v[52:55], v80, s[30:31] offset:16
	global_load_dwordx4 v[56:59], v80, s[30:31] offset:2048
	global_load_dwordx4 v[60:63], v80, s[30:31] offset:2064
	s_waitcnt vmcnt(40)
; template <bool BF> __device__ __forceinline__ void prep_rows(const float* xp, const float* xs, const bf16* hb, const float* g, const float* MOD, int shoff, int scoff, bf16* U, int gw, int NGW, int lane) {
;     ...
;         for (int r = 0; r < R; ++r) { float t = 0.f;
; #pragma unroll
;             for (int j = 0; j < 4; ++j) t += (v[r][j].x * v[r][j].x + v[r][j].y * v[r][j].y) + (v[r][j].z * v[r][j].z + v[r][j].w * v[r][j].w);
;             s[r] = t; }
; #pragma unroll
;         for (int o = 1; o < 64; o <<= 1) {
; #pragma unroll
;             for (int r = 0; r < R; ++r) s[r] += __shfl_xor(s[r], o); }
; #pragma unroll
;         for (int r = 0; r < R; ++r) { const int m = mb + r * NGW; if (m < MT) {
;             const float rstd = 1.0f / sqrtf(s[r] * (1.0f / DM) + RMS_EPS);
	v_pk_mul_f32 v[240:241], v[96:97], v[96:97]
	v_pk_mul_f32 v[242:243], v[112:113], v[112:113]
	v_pk_mul_f32 v[244:245], v[128:129], v[128:129]
	v_pk_mul_f32 v[246:247], v[144:145], v[144:145]
	v_pk_fma_f32 v[240:241], v[98:99], v[98:99], v[240:241]
	v_pk_fma_f32 v[242:243], v[114:115], v[114:115], v[242:243]
	v_pk_fma_f32 v[244:245], v[130:131], v[130:131], v[244:245]
	v_pk_fma_f32 v[246:247], v[146:147], v[146:147], v[246:247]
	v_pk_fma_f32 v[240:241], v[100:101], v[100:101], v[240:241]
	v_pk_fma_f32 v[242:243], v[116:117], v[116:117], v[242:243]
	v_pk_fma_f32 v[244:245], v[132:133], v[132:133], v[244:245]
	v_pk_fma_f32 v[246:247], v[148:149], v[148:149], v[246:247]
	v_pk_fma_f32 v[240:241], v[102:103], v[102:103], v[240:241]
	v_pk_fma_f32 v[242:243], v[118:119], v[118:119], v[242:243]
	v_pk_fma_f32 v[244:245], v[134:135], v[134:135], v[244:245]
	v_pk_fma_f32 v[246:247], v[150:151], v[150:151], v[246:247]
	v_pk_fma_f32 v[240:241], v[104:105], v[104:105], v[240:241]
	v_pk_fma_f32 v[242:243], v[120:121], v[120:121], v[242:243]
	v_pk_fma_f32 v[244:245], v[136:137], v[136:137], v[244:245]
	v_pk_fma_f32 v[246:247], v[152:153], v[152:153], v[246:247]
	v_pk_fma_f32 v[240:241], v[106:107], v[106:107], v[240:241]
	v_pk_fma_f32 v[242:243], v[122:123], v[122:123], v[242:243]
	v_pk_fma_f32 v[244:245], v[138:139], v[138:139], v[244:245]
	v_pk_fma_f32 v[246:247], v[154:155], v[154:155], v[246:247]
	v_pk_fma_f32 v[240:241], v[108:109], v[108:109], v[240:241]
	v_pk_fma_f32 v[242:243], v[124:125], v[124:125], v[242:243]
	v_pk_fma_f32 v[244:245], v[140:141], v[140:141], v[244:245]
	v_pk_fma_f32 v[246:247], v[156:157], v[156:157], v[246:247]
	v_pk_fma_f32 v[240:241], v[110:111], v[110:111], v[240:241]
	v_pk_fma_f32 v[242:243], v[126:127], v[126:127], v[242:243]
	v_pk_fma_f32 v[244:245], v[142:143], v[142:143], v[244:245]
	v_pk_fma_f32 v[246:247], v[158:159], v[158:159], v[246:247]
	v_add_f32_e32 v224, v240, v241
	v_add_f32_e32 v225, v242, v243
	v_add_f32_e32 v226, v244, v245
	v_add_f32_e32 v227, v246, v247
	ds_bpermute_b32 v228, v83, v224
	ds_bpermute_b32 v229, v83, v225
	ds_bpermute_b32 v230, v83, v226
	ds_bpermute_b32 v231, v83, v227
	s_waitcnt lgkmcnt(0)
	v_add_f32_e32 v224, v224, v228
	v_add_f32_e32 v225, v225, v229
	v_add_f32_e32 v226, v226, v230
	v_add_f32_e32 v227, v227, v231
	ds_bpermute_b32 v228, v84, v224
	ds_bpermute_b32 v229, v84, v225
	ds_bpermute_b32 v230, v84, v226
	ds_bpermute_b32 v231, v84, v227
	s_waitcnt lgkmcnt(0)
	v_add_f32_e32 v224, v224, v228
	v_add_f32_e32 v225, v225, v229
	v_add_f32_e32 v226, v226, v230
	v_add_f32_e32 v227, v227, v231
	ds_bpermute_b32 v228, v85, v224
	ds_bpermute_b32 v229, v85, v225
	ds_bpermute_b32 v230, v85, v226
	ds_bpermute_b32 v231, v85, v227
	s_waitcnt lgkmcnt(0)
	v_add_f32_e32 v224, v224, v228
	v_add_f32_e32 v225, v225, v229
	v_add_f32_e32 v226, v226, v230
	v_add_f32_e32 v227, v227, v231
	ds_bpermute_b32 v228, v86, v224
	ds_bpermute_b32 v229, v86, v225
	ds_bpermute_b32 v230, v86, v226
	ds_bpermute_b32 v231, v86, v227
	s_waitcnt lgkmcnt(0)
	v_add_f32_e32 v224, v224, v228
	v_add_f32_e32 v225, v225, v229
	v_add_f32_e32 v226, v226, v230
	v_add_f32_e32 v227, v227, v231
	ds_bpermute_b32 v228, v87, v224
	ds_bpermute_b32 v229, v87, v225
	ds_bpermute_b32 v230, v87, v226
	ds_bpermute_b32 v231, v87, v227
	s_waitcnt lgkmcnt(0)
	v_add_f32_e32 v224, v224, v228
	v_add_f32_e32 v225, v225, v229
	v_add_f32_e32 v226, v226, v230
	v_add_f32_e32 v227, v227, v231
	ds_bpermute_b32 v228, v88, v224
	ds_bpermute_b32 v229, v88, v225
	ds_bpermute_b32 v230, v88, v226
	ds_bpermute_b32 v231, v88, v227
	s_waitcnt lgkmcnt(0)
	v_add_f32_e32 v224, v224, v228
	v_add_f32_e32 v225, v225, v229
	v_add_f32_e32 v226, v226, v230
	v_add_f32_e32 v227, v227, v231
	v_fmamk_f32 v240, v224, 0x3a800000, v89
	v_mul_f32_e32 v241, 0x4f800000, v240
	v_cmp_gt_f32_e32 vcc, s54, v240
	s_nop 1
	v_cndmask_b32_e32 v247, v240, v241, vcc
	v_sqrt_f32_e32 v242, v247
	s_nop 1
	v_add_u32_e32 v243, -1, v242
	v_add_u32_e32 v244, 1, v242
	v_fma_f32 v245, -v243, v242, v247
	v_fma_f32 v246, -v244, v242, v247
	v_cmp_ge_f32_e64 s[52:53], 0, v245
	s_nop 1
	v_cndmask_b32_e64 v242, v242, v243, s[52:53]
	v_cmp_lt_f32_e64 s[52:53], 0, v246
	s_nop 1
	v_cndmask_b32_e64 v242, v242, v244, s[52:53]
	v_mul_f32_e32 v243, 0x37800000, v242
	v_cndmask_b32_e32 v242, v242, v243, vcc
	v_cmp_class_f32_e32 vcc, v247, v90
	s_nop 1
	v_cndmask_b32_e32 v247, v242, v247, vcc
	v_div_scale_f32 v248, s[52:53], v247, v247, 1.0
	v_rcp_f32_e32 v249, v248
	v_div_scale_f32 v228, vcc, 1.0, v247, 1.0
	s_nop 0
	v_fma_f32 v229, -v248, v249, 1.0
	v_fmac_f32_e32 v249, v229, v249
	v_mul_f32_e32 v230, v228, v249
	v_fma_f32 v229, -v248, v230, v228
	v_fmac_f32_e32 v230, v229, v249
	v_fma_f32 v248, -v248, v230, v228
	v_div_fmas_f32 v248, v248, v249, v230
	v_div_fixup_f32 v232, v248, v247, 1.0
	v_fmamk_f32 v240, v225, 0x3a800000, v89
	v_mul_f32_e32 v241, 0x4f800000, v240
	v_cmp_gt_f32_e32 vcc, s54, v240
	s_nop 1
	v_cndmask_b32_e32 v247, v240, v241, vcc
	v_sqrt_f32_e32 v242, v247
	s_nop 1
	v_add_u32_e32 v243, -1, v242
	v_add_u32_e32 v244, 1, v242
	v_fma_f32 v245, -v243, v242, v247
	v_fma_f32 v246, -v244, v242, v247
	v_cmp_ge_f32_e64 s[52:53], 0, v245
	s_nop 1
	v_cndmask_b32_e64 v242, v242, v243, s[52:53]
	v_cmp_lt_f32_e64 s[52:53], 0, v246
	s_nop 1
	v_cndmask_b32_e64 v242, v242, v244, s[52:53]
	v_mul_f32_e32 v243, 0x37800000, v242
	v_cndmask_b32_e32 v242, v242, v243, vcc
	v_cmp_class_f32_e32 vcc, v247, v90
	s_nop 1
	v_cndmask_b32_e32 v247, v242, v247, vcc
	v_div_scale_f32 v248, s[52:53], v247, v247, 1.0
	v_rcp_f32_e32 v249, v248
	v_div_scale_f32 v228, vcc, 1.0, v247, 1.0
	s_nop 0
	v_fma_f32 v229, -v248, v249, 1.0
; __device__ __forceinline__ unsigned pk2(float lo, float hi) { return pg8::cvt_pk_bf16(lo, hi); }
; template <bool BF> __device__ __forceinline__ void prep_rows(const float* xp, const float* xs, const bf16* hb, const float* g, const float* MOD, int shoff, int scoff, bf16* U, int gw, int NGW, int lane) {
;     ...
;             const float rstd = 1.0f / sqrtf(s[r] * (1.0f / DM) + RMS_EPS);
;             const float* mr = MOD + (size_t)(m < MP ? (m >> 13) : 8 + ((m - MP) >> 12)) * 6144;
; #pragma unroll
;             for (int j = 0; j < 4; ++j) { const int c = 4 * lane + 256 * j;
;                 const f32x4 gg = *(const f32x4*)(g + c), sc = *(const f32x4*)(mr + scoff + c), sh = *(const f32x4*)(mr + shoff + c);
;                 const f32x4 o = v[r][j] * rstd * gg * (sc + 1.0f) + sh; v2u w; w.x = pk2(o.x, o.y); w.y = pk2(o.z, o.w); *(v2u*)(U + (size_t)m * DM + c) = w; } } }
	v_fmac_f32_e32 v249, v229, v249
	v_mul_f32_e32 v230, v228, v249
	v_fma_f32 v229, -v248, v230, v228
	v_fmac_f32_e32 v230, v229, v249
	v_fma_f32 v248, -v248, v230, v228
	v_div_fmas_f32 v248, v248, v249, v230
	v_div_fixup_f32 v234, v248, v247, 1.0
	v_fmamk_f32 v240, v226, 0x3a800000, v89
	v_mul_f32_e32 v241, 0x4f800000, v240
	v_cmp_gt_f32_e32 vcc, s54, v240
	s_nop 1
	v_cndmask_b32_e32 v247, v240, v241, vcc
	v_sqrt_f32_e32 v242, v247
	s_nop 1
	v_add_u32_e32 v243, -1, v242
	v_add_u32_e32 v244, 1, v242
	v_fma_f32 v245, -v243, v242, v247
	v_fma_f32 v246, -v244, v242, v247
	v_cmp_ge_f32_e64 s[52:53], 0, v245
	s_nop 1
	v_cndmask_b32_e64 v242, v242, v243, s[52:53]
	v_cmp_lt_f32_e64 s[52:53], 0, v246
	s_nop 1
	v_cndmask_b32_e64 v242, v242, v244, s[52:53]
	v_mul_f32_e32 v243, 0x37800000, v242
	v_cndmask_b32_e32 v242, v242, v243, vcc
	v_cmp_class_f32_e32 vcc, v247, v90
	s_nop 1
	v_cndmask_b32_e32 v247, v242, v247, vcc
	v_div_scale_f32 v248, s[52:53], v247, v247, 1.0
	v_rcp_f32_e32 v249, v248
	v_div_scale_f32 v228, vcc, 1.0, v247, 1.0
	s_nop 0
	v_fma_f32 v229, -v248, v249, 1.0
	v_fmac_f32_e32 v249, v229, v249
	v_mul_f32_e32 v230, v228, v249
	v_fma_f32 v229, -v248, v230, v228
	v_fmac_f32_e32 v230, v229, v249
	v_fma_f32 v248, -v248, v230, v228
	v_div_fmas_f32 v248, v248, v249, v230
	v_div_fixup_f32 v236, v248, v247, 1.0
	v_fmamk_f32 v240, v227, 0x3a800000, v89
	v_mul_f32_e32 v241, 0x4f800000, v240
	v_cmp_gt_f32_e32 vcc, s54, v240
	s_nop 1
	v_cndmask_b32_e32 v247, v240, v241, vcc
	v_sqrt_f32_e32 v242, v247
	s_nop 1
	v_add_u32_e32 v243, -1, v242
	v_add_u32_e32 v244, 1, v242
	v_fma_f32 v245, -v243, v242, v247
	v_fma_f32 v246, -v244, v242, v247
	v_cmp_ge_f32_e64 s[52:53], 0, v245
	s_nop 1
	v_cndmask_b32_e64 v242, v242, v243, s[52:53]
	v_cmp_lt_f32_e64 s[52:53], 0, v246
	s_nop 1
	v_cndmask_b32_e64 v242, v242, v244, s[52:53]
	v_mul_f32_e32 v243, 0x37800000, v242
	v_cndmask_b32_e32 v242, v242, v243, vcc
	v_cmp_class_f32_e32 vcc, v247, v90
	s_nop 1
	v_cndmask_b32_e32 v247, v242, v247, vcc
	v_div_scale_f32 v248, s[52:53], v247, v247, 1.0
	v_rcp_f32_e32 v249, v248
	v_div_scale_f32 v228, vcc, 1.0, v247, 1.0
	s_nop 0
	v_fma_f32 v229, -v248, v249, 1.0
	v_fmac_f32_e32 v249, v229, v249
	v_mul_f32_e32 v230, v228, v249
	v_fma_f32 v229, -v248, v230, v228
	v_fmac_f32_e32 v230, v229, v249
	v_fma_f32 v248, -v248, v230, v228
	v_div_fmas_f32 v248, v248, v249, v230
	v_div_fixup_f32 v238, v248, v247, 1.0
	s_waitcnt vmcnt(16)
	v_pk_add_f32 v[160:161], v[160:161], 1.0 op_sel_hi:[1,0]
	v_pk_add_f32 v[162:163], v[162:163], 1.0 op_sel_hi:[1,0]
	v_pk_add_f32 v[164:165], v[164:165], 1.0 op_sel_hi:[1,0]
	v_pk_add_f32 v[166:167], v[166:167], 1.0 op_sel_hi:[1,0]
	v_pk_add_f32 v[168:169], v[168:169], 1.0 op_sel_hi:[1,0]
	v_pk_add_f32 v[170:171], v[170:171], 1.0 op_sel_hi:[1,0]
	v_pk_add_f32 v[172:173], v[172:173], 1.0 op_sel_hi:[1,0]
	v_pk_add_f32 v[174:175], v[174:175], 1.0 op_sel_hi:[1,0]
	v_pk_add_f32 v[192:193], v[192:193], 1.0 op_sel_hi:[1,0]
	v_pk_add_f32 v[194:195], v[194:195], 1.0 op_sel_hi:[1,0]
	v_pk_add_f32 v[196:197], v[196:197], 1.0 op_sel_hi:[1,0]
	v_pk_add_f32 v[198:199], v[198:199], 1.0 op_sel_hi:[1,0]
	v_pk_add_f32 v[200:201], v[200:201], 1.0 op_sel_hi:[1,0]
	v_pk_add_f32 v[202:203], v[202:203], 1.0 op_sel_hi:[1,0]
	v_pk_add_f32 v[204:205], v[204:205], 1.0 op_sel_hi:[1,0]
	v_pk_add_f32 v[206:207], v[206:207], 1.0 op_sel_hi:[1,0]
	s_add_u32 s38, s20, 0x5000000
	s_addc_u32 s39, s21, 0
	s_add_u32 s40, s20, 0x5400000
	s_addc_u32 s41, s21, 0
	s_add_u32 s46, s20, 0x5800000
	s_addc_u32 s47, s21, 0
	s_add_u32 s48, s20, 0x5c00000
	s_addc_u32 s49, s21, 0
	v_pk_mul_f32 v[96:97], v[96:97], v[232:233] op_sel_hi:[1,0]
	v_pk_mul_f32 v[98:99], v[98:99], v[232:233] op_sel_hi:[1,0]
	v_pk_mul_f32 v[96:97], v[64:65], v[96:97]
	v_pk_mul_f32 v[98:99], v[66:67], v[98:99]
	v_pk_fma_f32 v[96:97], v[160:161], v[96:97], v[176:177]
	v_pk_fma_f32 v[98:99], v[162:163], v[98:99], v[178:179]
	v_cvt_pk_bf16_f32 v244, v96, v97
	v_cvt_pk_bf16_f32 v245, v98, v99
	v_pk_mul_f32 v[100:101], v[100:101], v[232:233] op_sel_hi:[1,0]
	v_pk_mul_f32 v[102:103], v[102:103], v[232:233] op_sel_hi:[1,0]
	v_pk_mul_f32 v[100:101], v[68:69], v[100:101]
	v_pk_mul_f32 v[102:103], v[70:71], v[102:103]
	v_pk_fma_f32 v[100:101], v[164:165], v[100:101], v[180:181]
	v_pk_fma_f32 v[102:103], v[166:167], v[102:103], v[182:183]
	v_cvt_pk_bf16_f32 v246, v100, v101
	v_cvt_pk_bf16_f32 v247, v102, v103
	global_store_dwordx4 v82, v[244:247], s[38:39] offset:0
	v_pk_mul_f32 v[104:105], v[104:105], v[232:233] op_sel_hi:[1,0]
	v_pk_mul_f32 v[106:107], v[106:107], v[232:233] op_sel_hi:[1,0]
	v_pk_mul_f32 v[104:105], v[72:73], v[104:105]
	v_pk_mul_f32 v[106:107], v[74:75], v[106:107]
	v_pk_fma_f32 v[104:105], v[168:169], v[104:105], v[184:185]
	v_pk_fma_f32 v[106:107], v[170:171], v[106:107], v[186:187]
	v_cvt_pk_bf16_f32 v240, v104, v105
	v_cvt_pk_bf16_f32 v241, v106, v107
	v_pk_mul_f32 v[108:109], v[108:109], v[232:233] op_sel_hi:[1,0]
	v_pk_mul_f32 v[110:111], v[110:111], v[232:233] op_sel_hi:[1,0]
	v_pk_mul_f32 v[108:109], v[76:77], v[108:109]
	v_pk_mul_f32 v[110:111], v[78:79], v[110:111]
	v_pk_fma_f32 v[108:109], v[172:173], v[108:109], v[188:189]
	v_pk_fma_f32 v[110:111], v[174:175], v[110:111], v[190:191]
	v_cvt_pk_bf16_f32 v242, v108, v109
	v_cvt_pk_bf16_f32 v243, v110, v111
	global_store_dwordx4 v82, v[240:243], s[38:39] offset:1024
	v_pk_mul_f32 v[112:113], v[112:113], v[234:235] op_sel_hi:[1,0]
	v_pk_mul_f32 v[114:115], v[114:115], v[234:235] op_sel_hi:[1,0]
	v_pk_mul_f32 v[112:113], v[64:65], v[112:113]
	v_pk_mul_f32 v[114:115], v[66:67], v[114:115]
	v_pk_fma_f32 v[112:113], v[160:161], v[112:113], v[176:177]
; __device__ __forceinline__ unsigned pk2(float lo, float hi) { return pg8::cvt_pk_bf16(lo, hi); }
; template <bool BF> __device__ __forceinline__ void prep_rows(const float* xp, const float* xs, const bf16* hb, const float* g, const float* MOD, int shoff, int scoff, bf16* U, int gw, int NGW, int lane) {
;     ...
;         for (int r = 0; r < R; ++r) { const int m = mb + r * NGW; if (m < MT) {
;             const float rstd = 1.0f / sqrtf(s[r] * (1.0f / DM) + RMS_EPS);
;             const float* mr = MOD + (size_t)(m < MP ? (m >> 13) : 8 + ((m - MP) >> 12)) * 6144;
; #pragma unroll
;             for (int j = 0; j < 4; ++j) { const int c = 4 * lane + 256 * j;
;                 const f32x4 gg = *(const f32x4*)(g + c), sc = *(const f32x4*)(mr + scoff + c), sh = *(const f32x4*)(mr + shoff + c);
;                 const f32x4 o = v[r][j] * rstd * gg * (sc + 1.0f) + sh; v2u w; w.x = pk2(o.x, o.y); w.y = pk2(o.z, o.w); *(v2u*)(U + (size_t)m * DM + c) = w; } } }
	v_pk_fma_f32 v[114:115], v[162:163], v[114:115], v[178:179]
	v_cvt_pk_bf16_f32 v244, v112, v113
	v_cvt_pk_bf16_f32 v245, v114, v115
	v_pk_mul_f32 v[116:117], v[116:117], v[234:235] op_sel_hi:[1,0]
	v_pk_mul_f32 v[118:119], v[118:119], v[234:235] op_sel_hi:[1,0]
	v_pk_mul_f32 v[116:117], v[68:69], v[116:117]
	v_pk_mul_f32 v[118:119], v[70:71], v[118:119]
	v_pk_fma_f32 v[116:117], v[164:165], v[116:117], v[180:181]
	v_pk_fma_f32 v[118:119], v[166:167], v[118:119], v[182:183]
	v_cvt_pk_bf16_f32 v246, v116, v117
	v_cvt_pk_bf16_f32 v247, v118, v119
	global_store_dwordx4 v82, v[244:247], s[40:41] offset:0
	v_pk_mul_f32 v[120:121], v[120:121], v[234:235] op_sel_hi:[1,0]
	v_pk_mul_f32 v[122:123], v[122:123], v[234:235] op_sel_hi:[1,0]
	v_pk_mul_f32 v[120:121], v[72:73], v[120:121]
	v_pk_mul_f32 v[122:123], v[74:75], v[122:123]
	v_pk_fma_f32 v[120:121], v[168:169], v[120:121], v[184:185]
	v_pk_fma_f32 v[122:123], v[170:171], v[122:123], v[186:187]
	v_cvt_pk_bf16_f32 v240, v120, v121
	v_cvt_pk_bf16_f32 v241, v122, v123
	v_pk_mul_f32 v[124:125], v[124:125], v[234:235] op_sel_hi:[1,0]
	v_pk_mul_f32 v[126:127], v[126:127], v[234:235] op_sel_hi:[1,0]
	v_pk_mul_f32 v[124:125], v[76:77], v[124:125]
	v_pk_mul_f32 v[126:127], v[78:79], v[126:127]
	v_pk_fma_f32 v[124:125], v[172:173], v[124:125], v[188:189]
	v_pk_fma_f32 v[126:127], v[174:175], v[126:127], v[190:191]
	v_cvt_pk_bf16_f32 v242, v124, v125
	v_cvt_pk_bf16_f32 v243, v126, v127
	global_store_dwordx4 v82, v[240:243], s[40:41] offset:1024
	v_pk_mul_f32 v[128:129], v[128:129], v[236:237] op_sel_hi:[1,0]
	v_pk_mul_f32 v[130:131], v[130:131], v[236:237] op_sel_hi:[1,0]
	v_pk_mul_f32 v[128:129], v[64:65], v[128:129]
	v_pk_mul_f32 v[130:131], v[66:67], v[130:131]
	v_pk_fma_f32 v[128:129], v[192:193], v[128:129], v[208:209]
	v_pk_fma_f32 v[130:131], v[194:195], v[130:131], v[210:211]
	v_cvt_pk_bf16_f32 v244, v128, v129
	v_cvt_pk_bf16_f32 v245, v130, v131
	v_pk_mul_f32 v[132:133], v[132:133], v[236:237] op_sel_hi:[1,0]
	v_pk_mul_f32 v[134:135], v[134:135], v[236:237] op_sel_hi:[1,0]
	v_pk_mul_f32 v[132:133], v[68:69], v[132:133]
	v_pk_mul_f32 v[134:135], v[70:71], v[134:135]
	v_pk_fma_f32 v[132:133], v[196:197], v[132:133], v[212:213]
	v_pk_fma_f32 v[134:135], v[198:199], v[134:135], v[214:215]
	v_cvt_pk_bf16_f32 v246, v132, v133
	v_cvt_pk_bf16_f32 v247, v134, v135
	global_store_dwordx4 v82, v[244:247], s[46:47] offset:0
	v_pk_mul_f32 v[136:137], v[136:137], v[236:237] op_sel_hi:[1,0]
	v_pk_mul_f32 v[138:139], v[138:139], v[236:237] op_sel_hi:[1,0]
	v_pk_mul_f32 v[136:137], v[72:73], v[136:137]
	v_pk_mul_f32 v[138:139], v[74:75], v[138:139]
	v_pk_fma_f32 v[136:137], v[200:201], v[136:137], v[216:217]
	v_pk_fma_f32 v[138:139], v[202:203], v[138:139], v[218:219]
	v_cvt_pk_bf16_f32 v240, v136, v137
	v_cvt_pk_bf16_f32 v241, v138, v139
	v_pk_mul_f32 v[140:141], v[140:141], v[236:237] op_sel_hi:[1,0]
	v_pk_mul_f32 v[142:143], v[142:143], v[236:237] op_sel_hi:[1,0]
	v_pk_mul_f32 v[140:141], v[76:77], v[140:141]
	v_pk_mul_f32 v[142:143], v[78:79], v[142:143]
	v_pk_fma_f32 v[140:141], v[204:205], v[140:141], v[220:221]
	v_pk_fma_f32 v[142:143], v[206:207], v[142:143], v[222:223]
	v_cvt_pk_bf16_f32 v242, v140, v141
	v_cvt_pk_bf16_f32 v243, v142, v143
	global_store_dwordx4 v82, v[240:243], s[46:47] offset:1024
	v_pk_mul_f32 v[144:145], v[144:145], v[238:239] op_sel_hi:[1,0]
	v_pk_mul_f32 v[146:147], v[146:147], v[238:239] op_sel_hi:[1,0]
	v_pk_mul_f32 v[144:145], v[64:65], v[144:145]
	v_pk_mul_f32 v[146:147], v[66:67], v[146:147]
	v_pk_fma_f32 v[144:145], v[192:193], v[144:145], v[208:209]
	v_pk_fma_f32 v[146:147], v[194:195], v[146:147], v[210:211]
	v_cvt_pk_bf16_f32 v244, v144, v145
	v_cvt_pk_bf16_f32 v245, v146, v147
	v_pk_mul_f32 v[148:149], v[148:149], v[238:239] op_sel_hi:[1,0]
	v_pk_mul_f32 v[150:151], v[150:151], v[238:239] op_sel_hi:[1,0]
	v_pk_mul_f32 v[148:149], v[68:69], v[148:149]
	v_pk_mul_f32 v[150:151], v[70:71], v[150:151]
	v_pk_fma_f32 v[148:149], v[196:197], v[148:149], v[212:213]
	v_pk_fma_f32 v[150:151], v[198:199], v[150:151], v[214:215]
	v_cvt_pk_bf16_f32 v246, v148, v149
	v_cvt_pk_bf16_f32 v247, v150, v151
	global_store_dwordx4 v82, v[244:247], s[48:49] offset:0
	v_pk_mul_f32 v[152:153], v[152:153], v[238:239] op_sel_hi:[1,0]
	v_pk_mul_f32 v[154:155], v[154:155], v[238:239] op_sel_hi:[1,0]
	v_pk_mul_f32 v[152:153], v[72:73], v[152:153]
	v_pk_mul_f32 v[154:155], v[74:75], v[154:155]
	v_pk_fma_f32 v[152:153], v[200:201], v[152:153], v[216:217]
	v_pk_fma_f32 v[154:155], v[202:203], v[154:155], v[218:219]
	v_cvt_pk_bf16_f32 v240, v152, v153
	v_cvt_pk_bf16_f32 v241, v154, v155
	v_pk_mul_f32 v[156:157], v[156:157], v[238:239] op_sel_hi:[1,0]
	v_pk_mul_f32 v[158:159], v[158:159], v[238:239] op_sel_hi:[1,0]
	v_pk_mul_f32 v[156:157], v[76:77], v[156:157]
	v_pk_mul_f32 v[158:159], v[78:79], v[158:159]
	v_pk_fma_f32 v[156:157], v[204:205], v[156:157], v[220:221]
	v_pk_fma_f32 v[158:159], v[206:207], v[158:159], v[222:223]
	v_cvt_pk_bf16_f32 v242, v156, v157
	v_cvt_pk_bf16_f32 v243, v158, v159
	global_store_dwordx4 v82, v[240:243], s[48:49] offset:1024
	s_add_u32 s34, s8, 0x24000
	s_addc_u32 s35, s9, 0
	s_add_u32 s36, s8, 0x24000
	s_addc_u32 s37, s9, 0
	global_load_dwordx4 v[176:179], v80, s[34:35] offset:0
	global_load_dwordx4 v[180:183], v80, s[34:35] offset:16
	global_load_dwordx4 v[184:187], v80, s[34:35] offset:2048
	global_load_dwordx4 v[188:191], v80, s[34:35] offset:2064
	global_load_dwordx4 v[160:163], v81, s[34:35] offset:0
	global_load_dwordx4 v[164:167], v81, s[34:35] offset:16
	global_load_dwordx4 v[168:171], v81, s[34:35] offset:2048
	global_load_dwordx4 v[172:175], v81, s[34:35] offset:2064
; __device__ __forceinline__ float bf_lo(unsigned w) { return __uint_as_float(w << 16); }
; __device__ __forceinline__ float bf_hi(unsigned w) { return __uint_as_float(w & 0xffff0000u); }
; template <bool BF> __device__ __forceinline__ void prep_rows(const float* xp, const float* xs, const bf16* hb, const float* g, const float* MOD, int shoff, int scoff, bf16* U, int gw, int NGW, int lane) {
;     ...
;         f32x4 v[R][4]; float s[R];
; #pragma unroll
;         for (int r = 0; r < R; ++r) { const int m = mb + r * NGW; const int mc = m < MT ? m : mb;
; #pragma unroll
;             for (int j = 0; j < 4; ++j) {
;                 if (BF) { const v2u a0 = *(const v2u*)(hb + (size_t)mc * DM + 4 * lane + 256 * j);
;                     v[r][j].x = pg8::bf_lo(a0.x); v[r][j].y = pg8::bf_hi(a0.x); v[r][j].z = pg8::bf_lo(a0.y); v[r][j].w = pg8::bf_hi(a0.y); }
;                 else { const float* xr = mc < MP ? xp + (size_t)mc * DM : xs + (size_t)(mc - MP) * DM; v[r][j] = *(const f32x4*)(xr + 4 * lane + 256 * j); } } }
; #pragma unroll
;         for (int r = 0; r < R; ++r) { float t = 0.f;
; #pragma unroll
;             for (int j = 0; j < 4; ++j) t += (v[r][j].x * v[r][j].x + v[r][j].y * v[r][j].y) + (v[r][j].z * v[r][j].z + v[r][j].w * v[r][j].w);
;             s[r] = t; }
; #pragma unroll
;         for (int o = 1; o < 64; o <<= 1) {
; #pragma unroll
;             for (int r = 0; r < R; ++r) s[r] += __shfl_xor(s[r], o); }
	global_load_dwordx4 v[208:211], v80, s[36:37] offset:0
	global_load_dwordx4 v[212:215], v80, s[36:37] offset:16
	global_load_dwordx4 v[216:219], v80, s[36:37] offset:2048
	global_load_dwordx4 v[220:223], v80, s[36:37] offset:2064
	global_load_dwordx4 v[192:195], v81, s[36:37] offset:0
	global_load_dwordx4 v[196:199], v81, s[36:37] offset:16
	global_load_dwordx4 v[200:203], v81, s[36:37] offset:2048
	global_load_dwordx4 v[204:207], v81, s[36:37] offset:2064
	s_add_u32 s24, s16, 0xe000000
	s_addc_u32 s25, s17, 0
	s_add_u32 s26, s16, 0xe800000
	s_addc_u32 s27, s17, 0
	s_add_u32 s28, s16, 0xf000000
	s_addc_u32 s29, s17, 0
	s_add_u32 s30, s16, 0xf800000
	s_addc_u32 s31, s17, 0
	global_load_dwordx4 v[96:99], v80, s[24:25] offset:0
	global_load_dwordx4 v[100:103], v80, s[24:25] offset:16
	global_load_dwordx4 v[104:107], v80, s[24:25] offset:2048
	global_load_dwordx4 v[108:111], v80, s[24:25] offset:2064
	global_load_dwordx4 v[112:115], v80, s[26:27] offset:0
	global_load_dwordx4 v[116:119], v80, s[26:27] offset:16
	global_load_dwordx4 v[120:123], v80, s[26:27] offset:2048
	global_load_dwordx4 v[124:127], v80, s[26:27] offset:2064
	global_load_dwordx4 v[128:131], v80, s[28:29] offset:0
	global_load_dwordx4 v[132:135], v80, s[28:29] offset:16
	global_load_dwordx4 v[136:139], v80, s[28:29] offset:2048
	global_load_dwordx4 v[140:143], v80, s[28:29] offset:2064
	global_load_dwordx4 v[144:147], v80, s[30:31] offset:0
	global_load_dwordx4 v[148:151], v80, s[30:31] offset:16
	global_load_dwordx4 v[152:155], v80, s[30:31] offset:2048
	global_load_dwordx4 v[156:159], v80, s[30:31] offset:2064
	s_waitcnt vmcnt(40)
	v_pk_mul_f32 v[240:241], v[0:1], v[0:1]
	v_pk_mul_f32 v[242:243], v[16:17], v[16:17]
	v_pk_mul_f32 v[244:245], v[32:33], v[32:33]
	v_pk_mul_f32 v[246:247], v[48:49], v[48:49]
	v_pk_fma_f32 v[240:241], v[2:3], v[2:3], v[240:241]
	v_pk_fma_f32 v[242:243], v[18:19], v[18:19], v[242:243]
	v_pk_fma_f32 v[244:245], v[34:35], v[34:35], v[244:245]
	v_pk_fma_f32 v[246:247], v[50:51], v[50:51], v[246:247]
	v_pk_fma_f32 v[240:241], v[4:5], v[4:5], v[240:241]
	v_pk_fma_f32 v[242:243], v[20:21], v[20:21], v[242:243]
	v_pk_fma_f32 v[244:245], v[36:37], v[36:37], v[244:245]
	v_pk_fma_f32 v[246:247], v[52:53], v[52:53], v[246:247]
	v_pk_fma_f32 v[240:241], v[6:7], v[6:7], v[240:241]
	v_pk_fma_f32 v[242:243], v[22:23], v[22:23], v[242:243]
	v_pk_fma_f32 v[244:245], v[38:39], v[38:39], v[244:245]
	v_pk_fma_f32 v[246:247], v[54:55], v[54:55], v[246:247]
	v_pk_fma_f32 v[240:241], v[8:9], v[8:9], v[240:241]
	v_pk_fma_f32 v[242:243], v[24:25], v[24:25], v[242:243]
	v_pk_fma_f32 v[244:245], v[40:41], v[40:41], v[244:245]
	v_pk_fma_f32 v[246:247], v[56:57], v[56:57], v[246:247]
	v_pk_fma_f32 v[240:241], v[10:11], v[10:11], v[240:241]
	v_pk_fma_f32 v[242:243], v[26:27], v[26:27], v[242:243]
	v_pk_fma_f32 v[244:245], v[42:43], v[42:43], v[244:245]
	v_pk_fma_f32 v[246:247], v[58:59], v[58:59], v[246:247]
	v_pk_fma_f32 v[240:241], v[12:13], v[12:13], v[240:241]
	v_pk_fma_f32 v[242:243], v[28:29], v[28:29], v[242:243]
	v_pk_fma_f32 v[244:245], v[44:45], v[44:45], v[244:245]
	v_pk_fma_f32 v[246:247], v[60:61], v[60:61], v[246:247]
	v_pk_fma_f32 v[240:241], v[14:15], v[14:15], v[240:241]
	v_pk_fma_f32 v[242:243], v[30:31], v[30:31], v[242:243]
	v_pk_fma_f32 v[244:245], v[46:47], v[46:47], v[244:245]
	v_pk_fma_f32 v[246:247], v[62:63], v[62:63], v[246:247]
	v_add_f32_e32 v224, v240, v241
	v_add_f32_e32 v225, v242, v243
	v_add_f32_e32 v226, v244, v245
	v_add_f32_e32 v227, v246, v247
	ds_bpermute_b32 v228, v83, v224
	ds_bpermute_b32 v229, v83, v225
	ds_bpermute_b32 v230, v83, v226
	ds_bpermute_b32 v231, v83, v227
	s_waitcnt lgkmcnt(0)
	v_add_f32_e32 v224, v224, v228
	v_add_f32_e32 v225, v225, v229
	v_add_f32_e32 v226, v226, v230
	v_add_f32_e32 v227, v227, v231
	ds_bpermute_b32 v228, v84, v224
	ds_bpermute_b32 v229, v84, v225
	ds_bpermute_b32 v230, v84, v226
	ds_bpermute_b32 v231, v84, v227
	s_waitcnt lgkmcnt(0)
	v_add_f32_e32 v224, v224, v228
	v_add_f32_e32 v225, v225, v229
	v_add_f32_e32 v226, v226, v230
	v_add_f32_e32 v227, v227, v231
	ds_bpermute_b32 v228, v85, v224
	ds_bpermute_b32 v229, v85, v225
	ds_bpermute_b32 v230, v85, v226
	ds_bpermute_b32 v231, v85, v227
	s_waitcnt lgkmcnt(0)
	v_add_f32_e32 v224, v224, v228
	v_add_f32_e32 v225, v225, v229
	v_add_f32_e32 v226, v226, v230
	v_add_f32_e32 v227, v227, v231
	ds_bpermute_b32 v228, v86, v224
	ds_bpermute_b32 v229, v86, v225
	ds_bpermute_b32 v230, v86, v226
	ds_bpermute_b32 v231, v86, v227
	s_waitcnt lgkmcnt(0)
	v_add_f32_e32 v224, v224, v228
	v_add_f32_e32 v225, v225, v229
	v_add_f32_e32 v226, v226, v230
	v_add_f32_e32 v227, v227, v231
	ds_bpermute_b32 v228, v87, v224
	ds_bpermute_b32 v229, v87, v225
	ds_bpermute_b32 v230, v87, v226
	ds_bpermute_b32 v231, v87, v227
	s_waitcnt lgkmcnt(0)
	v_add_f32_e32 v224, v224, v228
	v_add_f32_e32 v225, v225, v229
	v_add_f32_e32 v226, v226, v230
	v_add_f32_e32 v227, v227, v231
	ds_bpermute_b32 v228, v88, v224
	ds_bpermute_b32 v229, v88, v225
	ds_bpermute_b32 v230, v88, v226
	ds_bpermute_b32 v231, v88, v227
	s_waitcnt lgkmcnt(0)
; template <bool BF> __device__ __forceinline__ void prep_rows(const float* xp, const float* xs, const bf16* hb, const float* g, const float* MOD, int shoff, int scoff, bf16* U, int gw, int NGW, int lane) {
;     ...
;             for (int r = 0; r < R; ++r) s[r] += __shfl_xor(s[r], o); }
; #pragma unroll
;         for (int r = 0; r < R; ++r) { const int m = mb + r * NGW; if (m < MT) {
;             const float rstd = 1.0f / sqrtf(s[r] * (1.0f / DM) + RMS_EPS);
	v_add_f32_e32 v224, v224, v228
	v_add_f32_e32 v225, v225, v229
	v_add_f32_e32 v226, v226, v230
	v_add_f32_e32 v227, v227, v231
	v_fmamk_f32 v240, v224, 0x3a800000, v89
	v_mul_f32_e32 v241, 0x4f800000, v240
	v_cmp_gt_f32_e32 vcc, s54, v240
	s_nop 1
	v_cndmask_b32_e32 v247, v240, v241, vcc
	v_sqrt_f32_e32 v242, v247
	s_nop 1
	v_add_u32_e32 v243, -1, v242
	v_add_u32_e32 v244, 1, v242
	v_fma_f32 v245, -v243, v242, v247
	v_fma_f32 v246, -v244, v242, v247
	v_cmp_ge_f32_e64 s[52:53], 0, v245
	s_nop 1
	v_cndmask_b32_e64 v242, v242, v243, s[52:53]
	v_cmp_lt_f32_e64 s[52:53], 0, v246
	s_nop 1
	v_cndmask_b32_e64 v242, v242, v244, s[52:53]
	v_mul_f32_e32 v243, 0x37800000, v242
	v_cndmask_b32_e32 v242, v242, v243, vcc
	v_cmp_class_f32_e32 vcc, v247, v90
	s_nop 1
	v_cndmask_b32_e32 v247, v242, v247, vcc
	v_div_scale_f32 v248, s[52:53], v247, v247, 1.0
	v_rcp_f32_e32 v249, v248
	v_div_scale_f32 v228, vcc, 1.0, v247, 1.0
	s_nop 0
	v_fma_f32 v229, -v248, v249, 1.0
	v_fmac_f32_e32 v249, v229, v249
	v_mul_f32_e32 v230, v228, v249
	v_fma_f32 v229, -v248, v230, v228
	v_fmac_f32_e32 v230, v229, v249
	v_fma_f32 v248, -v248, v230, v228
	v_div_fmas_f32 v248, v248, v249, v230
	v_div_fixup_f32 v232, v248, v247, 1.0
	v_fmamk_f32 v240, v225, 0x3a800000, v89
	v_mul_f32_e32 v241, 0x4f800000, v240
	v_cmp_gt_f32_e32 vcc, s54, v240
	s_nop 1
	v_cndmask_b32_e32 v247, v240, v241, vcc
	v_sqrt_f32_e32 v242, v247
	s_nop 1
	v_add_u32_e32 v243, -1, v242
	v_add_u32_e32 v244, 1, v242
	v_fma_f32 v245, -v243, v242, v247
	v_fma_f32 v246, -v244, v242, v247
	v_cmp_ge_f32_e64 s[52:53], 0, v245
	s_nop 1
	v_cndmask_b32_e64 v242, v242, v243, s[52:53]
	v_cmp_lt_f32_e64 s[52:53], 0, v246
	s_nop 1
	v_cndmask_b32_e64 v242, v242, v244, s[52:53]
	v_mul_f32_e32 v243, 0x37800000, v242
	v_cndmask_b32_e32 v242, v242, v243, vcc
	v_cmp_class_f32_e32 vcc, v247, v90
	s_nop 1
	v_cndmask_b32_e32 v247, v242, v247, vcc
	v_div_scale_f32 v248, s[52:53], v247, v247, 1.0
	v_rcp_f32_e32 v249, v248
	v_div_scale_f32 v228, vcc, 1.0, v247, 1.0
	s_nop 0
	v_fma_f32 v229, -v248, v249, 1.0
	v_fmac_f32_e32 v249, v229, v249
	v_mul_f32_e32 v230, v228, v249
	v_fma_f32 v229, -v248, v230, v228
	v_fmac_f32_e32 v230, v229, v249
	v_fma_f32 v248, -v248, v230, v228
	v_div_fmas_f32 v248, v248, v249, v230
	v_div_fixup_f32 v234, v248, v247, 1.0
	v_fmamk_f32 v240, v226, 0x3a800000, v89
	v_mul_f32_e32 v241, 0x4f800000, v240
	v_cmp_gt_f32_e32 vcc, s54, v240
	s_nop 1
	v_cndmask_b32_e32 v247, v240, v241, vcc
	v_sqrt_f32_e32 v242, v247
	s_nop 1
	v_add_u32_e32 v243, -1, v242
	v_add_u32_e32 v244, 1, v242
	v_fma_f32 v245, -v243, v242, v247
	v_fma_f32 v246, -v244, v242, v247
	v_cmp_ge_f32_e64 s[52:53], 0, v245
	s_nop 1
	v_cndmask_b32_e64 v242, v242, v243, s[52:53]
	v_cmp_lt_f32_e64 s[52:53], 0, v246
	s_nop 1
	v_cndmask_b32_e64 v242, v242, v244, s[52:53]
	v_mul_f32_e32 v243, 0x37800000, v242
	v_cndmask_b32_e32 v242, v242, v243, vcc
	v_cmp_class_f32_e32 vcc, v247, v90
	s_nop 1
	v_cndmask_b32_e32 v247, v242, v247, vcc
	v_div_scale_f32 v248, s[52:53], v247, v247, 1.0
	v_rcp_f32_e32 v249, v248
	v_div_scale_f32 v228, vcc, 1.0, v247, 1.0
	s_nop 0
	v_fma_f32 v229, -v248, v249, 1.0
	v_fmac_f32_e32 v249, v229, v249
	v_mul_f32_e32 v230, v228, v249
	v_fma_f32 v229, -v248, v230, v228
	v_fmac_f32_e32 v230, v229, v249
	v_fma_f32 v248, -v248, v230, v228
	v_div_fmas_f32 v248, v248, v249, v230
	v_div_fixup_f32 v236, v248, v247, 1.0
	v_fmamk_f32 v240, v227, 0x3a800000, v89
	v_mul_f32_e32 v241, 0x4f800000, v240
	v_cmp_gt_f32_e32 vcc, s54, v240
	s_nop 1
	v_cndmask_b32_e32 v247, v240, v241, vcc
	v_sqrt_f32_e32 v242, v247
	s_nop 1
	v_add_u32_e32 v243, -1, v242
	v_add_u32_e32 v244, 1, v242
	v_fma_f32 v245, -v243, v242, v247
	v_fma_f32 v246, -v244, v242, v247
	v_cmp_ge_f32_e64 s[52:53], 0, v245
	s_nop 1
	v_cndmask_b32_e64 v242, v242, v243, s[52:53]
	v_cmp_lt_f32_e64 s[52:53], 0, v246
	s_nop 1
	v_cndmask_b32_e64 v242, v242, v244, s[52:53]
	v_mul_f32_e32 v243, 0x37800000, v242
	v_cndmask_b32_e32 v242, v242, v243, vcc
	v_cmp_class_f32_e32 vcc, v247, v90
	s_nop 1
	v_cndmask_b32_e32 v247, v242, v247, vcc
	v_div_scale_f32 v248, s[52:53], v247, v247, 1.0
	v_rcp_f32_e32 v249, v248
	v_div_scale_f32 v228, vcc, 1.0, v247, 1.0
	s_nop 0
	v_fma_f32 v229, -v248, v249, 1.0
	v_fmac_f32_e32 v249, v229, v249
	v_mul_f32_e32 v230, v228, v249
	v_fma_f32 v229, -v248, v230, v228
	v_fmac_f32_e32 v230, v229, v249
	v_fma_f32 v248, -v248, v230, v228
	v_div_fmas_f32 v248, v248, v249, v230
	v_div_fixup_f32 v238, v248, v247, 1.0
	s_waitcnt vmcnt(16)
; __device__ __forceinline__ unsigned pk2(float lo, float hi) { return pg8::cvt_pk_bf16(lo, hi); }
; template <bool BF> __device__ __forceinline__ void prep_rows(const float* xp, const float* xs, const bf16* hb, const float* g, const float* MOD, int shoff, int scoff, bf16* U, int gw, int NGW, int lane) {
;     ...
;         for (int r = 0; r < R; ++r) { const int m = mb + r * NGW; if (m < MT) {
;             const float rstd = 1.0f / sqrtf(s[r] * (1.0f / DM) + RMS_EPS);
;             const float* mr = MOD + (size_t)(m < MP ? (m >> 13) : 8 + ((m - MP) >> 12)) * 6144;
; #pragma unroll
;             for (int j = 0; j < 4; ++j) { const int c = 4 * lane + 256 * j;
;                 const f32x4 gg = *(const f32x4*)(g + c), sc = *(const f32x4*)(mr + scoff + c), sh = *(const f32x4*)(mr + shoff + c);
;                 const f32x4 o = v[r][j] * rstd * gg * (sc + 1.0f) + sh; v2u w; w.x = pk2(o.x, o.y); w.y = pk2(o.z, o.w); *(v2u*)(U + (size_t)m * DM + c) = w; } } }
	v_pk_add_f32 v[160:161], v[160:161], 1.0 op_sel_hi:[1,0]
	v_pk_add_f32 v[162:163], v[162:163], 1.0 op_sel_hi:[1,0]
	v_pk_add_f32 v[164:165], v[164:165], 1.0 op_sel_hi:[1,0]
	v_pk_add_f32 v[166:167], v[166:167], 1.0 op_sel_hi:[1,0]
	v_pk_add_f32 v[168:169], v[168:169], 1.0 op_sel_hi:[1,0]
	v_pk_add_f32 v[170:171], v[170:171], 1.0 op_sel_hi:[1,0]
	v_pk_add_f32 v[172:173], v[172:173], 1.0 op_sel_hi:[1,0]
	v_pk_add_f32 v[174:175], v[174:175], 1.0 op_sel_hi:[1,0]
	v_pk_add_f32 v[192:193], v[192:193], 1.0 op_sel_hi:[1,0]
	v_pk_add_f32 v[194:195], v[194:195], 1.0 op_sel_hi:[1,0]
	v_pk_add_f32 v[196:197], v[196:197], 1.0 op_sel_hi:[1,0]
	v_pk_add_f32 v[198:199], v[198:199], 1.0 op_sel_hi:[1,0]
	v_pk_add_f32 v[200:201], v[200:201], 1.0 op_sel_hi:[1,0]
	v_pk_add_f32 v[202:203], v[202:203], 1.0 op_sel_hi:[1,0]
	v_pk_add_f32 v[204:205], v[204:205], 1.0 op_sel_hi:[1,0]
	v_pk_add_f32 v[206:207], v[206:207], 1.0 op_sel_hi:[1,0]
	s_add_u32 s38, s20, 0x6000000
	s_addc_u32 s39, s21, 0
	s_add_u32 s40, s20, 0x6400000
	s_addc_u32 s41, s21, 0
	s_add_u32 s46, s20, 0x6800000
	s_addc_u32 s47, s21, 0
	s_add_u32 s48, s20, 0x6c00000
	s_addc_u32 s49, s21, 0
	v_pk_mul_f32 v[0:1], v[0:1], v[232:233] op_sel_hi:[1,0]
	v_pk_mul_f32 v[2:3], v[2:3], v[232:233] op_sel_hi:[1,0]
	v_pk_mul_f32 v[0:1], v[64:65], v[0:1]
	v_pk_mul_f32 v[2:3], v[66:67], v[2:3]
	v_pk_fma_f32 v[0:1], v[160:161], v[0:1], v[176:177]
	v_pk_fma_f32 v[2:3], v[162:163], v[2:3], v[178:179]
	v_cvt_pk_bf16_f32 v244, v0, v1
	v_cvt_pk_bf16_f32 v245, v2, v3
	v_pk_mul_f32 v[4:5], v[4:5], v[232:233] op_sel_hi:[1,0]
	v_pk_mul_f32 v[6:7], v[6:7], v[232:233] op_sel_hi:[1,0]
	v_pk_mul_f32 v[4:5], v[68:69], v[4:5]
	v_pk_mul_f32 v[6:7], v[70:71], v[6:7]
	v_pk_fma_f32 v[4:5], v[164:165], v[4:5], v[180:181]
	v_pk_fma_f32 v[6:7], v[166:167], v[6:7], v[182:183]
	v_cvt_pk_bf16_f32 v246, v4, v5
	v_cvt_pk_bf16_f32 v247, v6, v7
	global_store_dwordx4 v82, v[244:247], s[38:39] offset:0
	v_pk_mul_f32 v[8:9], v[8:9], v[232:233] op_sel_hi:[1,0]
	v_pk_mul_f32 v[10:11], v[10:11], v[232:233] op_sel_hi:[1,0]
	v_pk_mul_f32 v[8:9], v[72:73], v[8:9]
	v_pk_mul_f32 v[10:11], v[74:75], v[10:11]
	v_pk_fma_f32 v[8:9], v[168:169], v[8:9], v[184:185]
	v_pk_fma_f32 v[10:11], v[170:171], v[10:11], v[186:187]
	v_cvt_pk_bf16_f32 v240, v8, v9
	v_cvt_pk_bf16_f32 v241, v10, v11
	v_pk_mul_f32 v[12:13], v[12:13], v[232:233] op_sel_hi:[1,0]
	v_pk_mul_f32 v[14:15], v[14:15], v[232:233] op_sel_hi:[1,0]
	v_pk_mul_f32 v[12:13], v[76:77], v[12:13]
	v_pk_mul_f32 v[14:15], v[78:79], v[14:15]
	v_pk_fma_f32 v[12:13], v[172:173], v[12:13], v[188:189]
	v_pk_fma_f32 v[14:15], v[174:175], v[14:15], v[190:191]
	v_cvt_pk_bf16_f32 v242, v12, v13
	v_cvt_pk_bf16_f32 v243, v14, v15
	global_store_dwordx4 v82, v[240:243], s[38:39] offset:1024
	v_pk_mul_f32 v[16:17], v[16:17], v[234:235] op_sel_hi:[1,0]
	v_pk_mul_f32 v[18:19], v[18:19], v[234:235] op_sel_hi:[1,0]
	v_pk_mul_f32 v[16:17], v[64:65], v[16:17]
	v_pk_mul_f32 v[18:19], v[66:67], v[18:19]
	v_pk_fma_f32 v[16:17], v[160:161], v[16:17], v[176:177]
	v_pk_fma_f32 v[18:19], v[162:163], v[18:19], v[178:179]
	v_cvt_pk_bf16_f32 v244, v16, v17
	v_cvt_pk_bf16_f32 v245, v18, v19
	v_pk_mul_f32 v[20:21], v[20:21], v[234:235] op_sel_hi:[1,0]
	v_pk_mul_f32 v[22:23], v[22:23], v[234:235] op_sel_hi:[1,0]
	v_pk_mul_f32 v[20:21], v[68:69], v[20:21]
	v_pk_mul_f32 v[22:23], v[70:71], v[22:23]
	v_pk_fma_f32 v[20:21], v[164:165], v[20:21], v[180:181]
	v_pk_fma_f32 v[22:23], v[166:167], v[22:23], v[182:183]
	v_cvt_pk_bf16_f32 v246, v20, v21
	v_cvt_pk_bf16_f32 v247, v22, v23
	global_store_dwordx4 v82, v[244:247], s[40:41] offset:0
	v_pk_mul_f32 v[24:25], v[24:25], v[234:235] op_sel_hi:[1,0]
	v_pk_mul_f32 v[26:27], v[26:27], v[234:235] op_sel_hi:[1,0]
	v_pk_mul_f32 v[24:25], v[72:73], v[24:25]
	v_pk_mul_f32 v[26:27], v[74:75], v[26:27]
	v_pk_fma_f32 v[24:25], v[168:169], v[24:25], v[184:185]
	v_pk_fma_f32 v[26:27], v[170:171], v[26:27], v[186:187]
	v_cvt_pk_bf16_f32 v240, v24, v25
	v_cvt_pk_bf16_f32 v241, v26, v27
	v_pk_mul_f32 v[28:29], v[28:29], v[234:235] op_sel_hi:[1,0]
	v_pk_mul_f32 v[30:31], v[30:31], v[234:235] op_sel_hi:[1,0]
	v_pk_mul_f32 v[28:29], v[76:77], v[28:29]
	v_pk_mul_f32 v[30:31], v[78:79], v[30:31]
	v_pk_fma_f32 v[28:29], v[172:173], v[28:29], v[188:189]
	v_pk_fma_f32 v[30:31], v[174:175], v[30:31], v[190:191]
	v_cvt_pk_bf16_f32 v242, v28, v29
	v_cvt_pk_bf16_f32 v243, v30, v31
	global_store_dwordx4 v82, v[240:243], s[40:41] offset:1024
	v_pk_mul_f32 v[32:33], v[32:33], v[236:237] op_sel_hi:[1,0]
	v_pk_mul_f32 v[34:35], v[34:35], v[236:237] op_sel_hi:[1,0]
	v_pk_mul_f32 v[32:33], v[64:65], v[32:33]
	v_pk_mul_f32 v[34:35], v[66:67], v[34:35]
	v_pk_fma_f32 v[32:33], v[192:193], v[32:33], v[208:209]
	v_pk_fma_f32 v[34:35], v[194:195], v[34:35], v[210:211]
	v_cvt_pk_bf16_f32 v244, v32, v33
	v_cvt_pk_bf16_f32 v245, v34, v35
	v_pk_mul_f32 v[36:37], v[36:37], v[236:237] op_sel_hi:[1,0]
	v_pk_mul_f32 v[38:39], v[38:39], v[236:237] op_sel_hi:[1,0]
	v_pk_mul_f32 v[36:37], v[68:69], v[36:37]
	v_pk_mul_f32 v[38:39], v[70:71], v[38:39]
	v_pk_fma_f32 v[36:37], v[196:197], v[36:37], v[212:213]
	v_pk_fma_f32 v[38:39], v[198:199], v[38:39], v[214:215]
	v_cvt_pk_bf16_f32 v246, v36, v37
	v_cvt_pk_bf16_f32 v247, v38, v39
	global_store_dwordx4 v82, v[244:247], s[46:47] offset:0
	v_pk_mul_f32 v[40:41], v[40:41], v[236:237] op_sel_hi:[1,0]
	v_pk_mul_f32 v[42:43], v[42:43], v[236:237] op_sel_hi:[1,0]
	v_pk_mul_f32 v[40:41], v[72:73], v[40:41]
	v_pk_mul_f32 v[42:43], v[74:75], v[42:43]
	v_pk_fma_f32 v[40:41], v[200:201], v[40:41], v[216:217]
	v_pk_fma_f32 v[42:43], v[202:203], v[42:43], v[218:219]
	v_cvt_pk_bf16_f32 v240, v40, v41
; __device__ __forceinline__ float bf_lo(unsigned w) { return __uint_as_float(w << 16); }
; __device__ __forceinline__ float bf_hi(unsigned w) { return __uint_as_float(w & 0xffff0000u); }
; __device__ __forceinline__ unsigned pk2(float lo, float hi) { return pg8::cvt_pk_bf16(lo, hi); }
; template <bool BF> __device__ __forceinline__ void prep_rows(const float* xp, const float* xs, const bf16* hb, const float* g, const float* MOD, int shoff, int scoff, bf16* U, int gw, int NGW, int lane) {
;     ...
;         f32x4 v[R][4]; float s[R];
; #pragma unroll
;         for (int r = 0; r < R; ++r) { const int m = mb + r * NGW; const int mc = m < MT ? m : mb;
; #pragma unroll
;             for (int j = 0; j < 4; ++j) {
;                 if (BF) { const v2u a0 = *(const v2u*)(hb + (size_t)mc * DM + 4 * lane + 256 * j);
;                     v[r][j].x = pg8::bf_lo(a0.x); v[r][j].y = pg8::bf_hi(a0.x); v[r][j].z = pg8::bf_lo(a0.y); v[r][j].w = pg8::bf_hi(a0.y); }
;                 else { const float* xr = mc < MP ? xp + (size_t)mc * DM : xs + (size_t)(mc - MP) * DM; v[r][j] = *(const f32x4*)(xr + 4 * lane + 256 * j); } } }
; #pragma unroll
;         for (int r = 0; r < R; ++r) { float t = 0.f;
; #pragma unroll
;             for (int j = 0; j < 4; ++j) t += (v[r][j].x * v[r][j].x + v[r][j].y * v[r][j].y) + (v[r][j].z * v[r][j].z + v[r][j].w * v[r][j].w);
;             s[r] = t; }
; #pragma unroll
;         for (int o = 1; o < 64; o <<= 1) {
; #pragma unroll
;             for (int r = 0; r < R; ++r) s[r] += __shfl_xor(s[r], o); }
; #pragma unroll
;         for (int r = 0; r < R; ++r) { const int m = mb + r * NGW; if (m < MT) {
;             const float rstd = 1.0f / sqrtf(s[r] * (1.0f / DM) + RMS_EPS);
;             const float* mr = MOD + (size_t)(m < MP ? (m >> 13) : 8 + ((m - MP) >> 12)) * 6144;
; #pragma unroll
;             for (int j = 0; j < 4; ++j) { const int c = 4 * lane + 256 * j;
;                 const f32x4 gg = *(const f32x4*)(g + c), sc = *(const f32x4*)(mr + scoff + c), sh = *(const f32x4*)(mr + shoff + c);
;                 const f32x4 o = v[r][j] * rstd * gg * (sc + 1.0f) + sh; v2u w; w.x = pk2(o.x, o.y); w.y = pk2(o.z, o.w); *(v2u*)(U + (size_t)m * DM + c) = w; } } }
	v_cvt_pk_bf16_f32 v241, v42, v43
	v_pk_mul_f32 v[44:45], v[44:45], v[236:237] op_sel_hi:[1,0]
	v_pk_mul_f32 v[46:47], v[46:47], v[236:237] op_sel_hi:[1,0]
	v_pk_mul_f32 v[44:45], v[76:77], v[44:45]
	v_pk_mul_f32 v[46:47], v[78:79], v[46:47]
	v_pk_fma_f32 v[44:45], v[204:205], v[44:45], v[220:221]
	v_pk_fma_f32 v[46:47], v[206:207], v[46:47], v[222:223]
	v_cvt_pk_bf16_f32 v242, v44, v45
	v_cvt_pk_bf16_f32 v243, v46, v47
	global_store_dwordx4 v82, v[240:243], s[46:47] offset:1024
	v_pk_mul_f32 v[48:49], v[48:49], v[238:239] op_sel_hi:[1,0]
	v_pk_mul_f32 v[50:51], v[50:51], v[238:239] op_sel_hi:[1,0]
	v_pk_mul_f32 v[48:49], v[64:65], v[48:49]
	v_pk_mul_f32 v[50:51], v[66:67], v[50:51]
	v_pk_fma_f32 v[48:49], v[192:193], v[48:49], v[208:209]
	v_pk_fma_f32 v[50:51], v[194:195], v[50:51], v[210:211]
	v_cvt_pk_bf16_f32 v244, v48, v49
	v_cvt_pk_bf16_f32 v245, v50, v51
	v_pk_mul_f32 v[52:53], v[52:53], v[238:239] op_sel_hi:[1,0]
	v_pk_mul_f32 v[54:55], v[54:55], v[238:239] op_sel_hi:[1,0]
	v_pk_mul_f32 v[52:53], v[68:69], v[52:53]
	v_pk_mul_f32 v[54:55], v[70:71], v[54:55]
	v_pk_fma_f32 v[52:53], v[196:197], v[52:53], v[212:213]
	v_pk_fma_f32 v[54:55], v[198:199], v[54:55], v[214:215]
	v_cvt_pk_bf16_f32 v246, v52, v53
	v_cvt_pk_bf16_f32 v247, v54, v55
	global_store_dwordx4 v82, v[244:247], s[48:49] offset:0
	v_pk_mul_f32 v[56:57], v[56:57], v[238:239] op_sel_hi:[1,0]
	v_pk_mul_f32 v[58:59], v[58:59], v[238:239] op_sel_hi:[1,0]
	v_pk_mul_f32 v[56:57], v[72:73], v[56:57]
	v_pk_mul_f32 v[58:59], v[74:75], v[58:59]
	v_pk_fma_f32 v[56:57], v[200:201], v[56:57], v[216:217]
	v_pk_fma_f32 v[58:59], v[202:203], v[58:59], v[218:219]
	v_cvt_pk_bf16_f32 v240, v56, v57
	v_cvt_pk_bf16_f32 v241, v58, v59
	v_pk_mul_f32 v[60:61], v[60:61], v[238:239] op_sel_hi:[1,0]
	v_pk_mul_f32 v[62:63], v[62:63], v[238:239] op_sel_hi:[1,0]
	v_pk_mul_f32 v[60:61], v[76:77], v[60:61]
	v_pk_mul_f32 v[62:63], v[78:79], v[62:63]
	v_pk_fma_f32 v[60:61], v[204:205], v[60:61], v[220:221]
	v_pk_fma_f32 v[62:63], v[206:207], v[62:63], v[222:223]
	v_cvt_pk_bf16_f32 v242, v60, v61
	v_cvt_pk_bf16_f32 v243, v62, v63
	global_store_dwordx4 v82, v[240:243], s[48:49] offset:1024
	s_add_u32 s34, s8, 0x2a000
	s_addc_u32 s35, s9, 0
	s_add_u32 s36, s8, 0x2a000
	s_addc_u32 s37, s9, 0
	global_load_dwordx4 v[176:179], v80, s[34:35] offset:0
	global_load_dwordx4 v[180:183], v80, s[34:35] offset:16
	global_load_dwordx4 v[184:187], v80, s[34:35] offset:2048
	global_load_dwordx4 v[188:191], v80, s[34:35] offset:2064
	global_load_dwordx4 v[160:163], v81, s[34:35] offset:0
	global_load_dwordx4 v[164:167], v81, s[34:35] offset:16
	global_load_dwordx4 v[168:171], v81, s[34:35] offset:2048
	global_load_dwordx4 v[172:175], v81, s[34:35] offset:2064
	global_load_dwordx4 v[208:211], v80, s[36:37] offset:0
	global_load_dwordx4 v[212:215], v80, s[36:37] offset:16
	global_load_dwordx4 v[216:219], v80, s[36:37] offset:2048
	global_load_dwordx4 v[220:223], v80, s[36:37] offset:2064
	global_load_dwordx4 v[192:195], v81, s[36:37] offset:0
	global_load_dwordx4 v[196:199], v81, s[36:37] offset:16
	global_load_dwordx4 v[200:203], v81, s[36:37] offset:2048
	global_load_dwordx4 v[204:207], v81, s[36:37] offset:2064
	s_mov_b64 s[24:25], s[18:19]
	s_add_u32 s26, s18, 0x800000
	s_addc_u32 s27, s19, 0
	s_add_u32 s28, s18, 0x1000000
	s_addc_u32 s29, s19, 0
	s_add_u32 s30, s18, 0x1800000
	s_addc_u32 s31, s19, 0
	global_load_dwordx4 v[0:3], v80, s[24:25] offset:0
	global_load_dwordx4 v[4:7], v80, s[24:25] offset:16
	global_load_dwordx4 v[8:11], v80, s[24:25] offset:2048
	global_load_dwordx4 v[12:15], v80, s[24:25] offset:2064
	global_load_dwordx4 v[16:19], v80, s[26:27] offset:0
	global_load_dwordx4 v[20:23], v80, s[26:27] offset:16
	global_load_dwordx4 v[24:27], v80, s[26:27] offset:2048
	global_load_dwordx4 v[28:31], v80, s[26:27] offset:2064
	global_load_dwordx4 v[32:35], v80, s[28:29] offset:0
	global_load_dwordx4 v[36:39], v80, s[28:29] offset:16
	global_load_dwordx4 v[40:43], v80, s[28:29] offset:2048
	global_load_dwordx4 v[44:47], v80, s[28:29] offset:2064
	global_load_dwordx4 v[48:51], v80, s[30:31] offset:0
	global_load_dwordx4 v[52:55], v80, s[30:31] offset:16
	global_load_dwordx4 v[56:59], v80, s[30:31] offset:2048
	global_load_dwordx4 v[60:63], v80, s[30:31] offset:2064
	s_waitcnt vmcnt(40)
	v_pk_mul_f32 v[240:241], v[96:97], v[96:97]
	v_pk_mul_f32 v[242:243], v[112:113], v[112:113]
	v_pk_mul_f32 v[244:245], v[128:129], v[128:129]
	v_pk_mul_f32 v[246:247], v[144:145], v[144:145]
	v_pk_fma_f32 v[240:241], v[98:99], v[98:99], v[240:241]
	v_pk_fma_f32 v[242:243], v[114:115], v[114:115], v[242:243]
	v_pk_fma_f32 v[244:245], v[130:131], v[130:131], v[244:245]
	v_pk_fma_f32 v[246:247], v[146:147], v[146:147], v[246:247]
	v_pk_fma_f32 v[240:241], v[100:101], v[100:101], v[240:241]
	v_pk_fma_f32 v[242:243], v[116:117], v[116:117], v[242:243]
	v_pk_fma_f32 v[244:245], v[132:133], v[132:133], v[244:245]
	v_pk_fma_f32 v[246:247], v[148:149], v[148:149], v[246:247]
	v_pk_fma_f32 v[240:241], v[102:103], v[102:103], v[240:241]
	v_pk_fma_f32 v[242:243], v[118:119], v[118:119], v[242:243]
	v_pk_fma_f32 v[244:245], v[134:135], v[134:135], v[244:245]
	v_pk_fma_f32 v[246:247], v[150:151], v[150:151], v[246:247]
	v_pk_fma_f32 v[240:241], v[104:105], v[104:105], v[240:241]
	v_pk_fma_f32 v[242:243], v[120:121], v[120:121], v[242:243]
	v_pk_fma_f32 v[244:245], v[136:137], v[136:137], v[244:245]
	v_pk_fma_f32 v[246:247], v[152:153], v[152:153], v[246:247]
	v_pk_fma_f32 v[240:241], v[106:107], v[106:107], v[240:241]
	v_pk_fma_f32 v[242:243], v[122:123], v[122:123], v[242:243]
	v_pk_fma_f32 v[244:245], v[138:139], v[138:139], v[244:245]
	v_pk_fma_f32 v[246:247], v[154:155], v[154:155], v[246:247]
	v_pk_fma_f32 v[240:241], v[108:109], v[108:109], v[240:241]
	v_pk_fma_f32 v[242:243], v[124:125], v[124:125], v[242:243]
	v_pk_fma_f32 v[244:245], v[140:141], v[140:141], v[244:245]
	v_pk_fma_f32 v[246:247], v[156:157], v[156:157], v[246:247]
	v_pk_fma_f32 v[240:241], v[110:111], v[110:111], v[240:241]
	v_pk_fma_f32 v[242:243], v[126:127], v[126:127], v[242:243]
	v_pk_fma_f32 v[244:245], v[142:143], v[142:143], v[244:245]
	v_pk_fma_f32 v[246:247], v[158:159], v[158:159], v[246:247]
	v_add_f32_e32 v224, v240, v241
	v_add_f32_e32 v225, v242, v243
	v_add_f32_e32 v226, v244, v245
	v_add_f32_e32 v227, v246, v247
	ds_bpermute_b32 v228, v83, v224
	ds_bpermute_b32 v229, v83, v225
	ds_bpermute_b32 v230, v83, v226
	ds_bpermute_b32 v231, v83, v227
	s_waitcnt lgkmcnt(0)
; template <bool BF> __device__ __forceinline__ void prep_rows(const float* xp, const float* xs, const bf16* hb, const float* g, const float* MOD, int shoff, int scoff, bf16* U, int gw, int NGW, int lane) {
;     ...
;             for (int r = 0; r < R; ++r) s[r] += __shfl_xor(s[r], o); }
; #pragma unroll
;         for (int r = 0; r < R; ++r) { const int m = mb + r * NGW; if (m < MT) {
;             const float rstd = 1.0f / sqrtf(s[r] * (1.0f / DM) + RMS_EPS);
	v_add_f32_e32 v224, v224, v228
	v_add_f32_e32 v225, v225, v229
	v_add_f32_e32 v226, v226, v230
	v_add_f32_e32 v227, v227, v231
	ds_bpermute_b32 v228, v84, v224
	ds_bpermute_b32 v229, v84, v225
	ds_bpermute_b32 v230, v84, v226
	ds_bpermute_b32 v231, v84, v227
	s_waitcnt lgkmcnt(0)
	v_add_f32_e32 v224, v224, v228
	v_add_f32_e32 v225, v225, v229
	v_add_f32_e32 v226, v226, v230
	v_add_f32_e32 v227, v227, v231
	ds_bpermute_b32 v228, v85, v224
	ds_bpermute_b32 v229, v85, v225
	ds_bpermute_b32 v230, v85, v226
	ds_bpermute_b32 v231, v85, v227
	s_waitcnt lgkmcnt(0)
	v_add_f32_e32 v224, v224, v228
	v_add_f32_e32 v225, v225, v229
	v_add_f32_e32 v226, v226, v230
	v_add_f32_e32 v227, v227, v231
	ds_bpermute_b32 v228, v86, v224
	ds_bpermute_b32 v229, v86, v225
	ds_bpermute_b32 v230, v86, v226
	ds_bpermute_b32 v231, v86, v227
	s_waitcnt lgkmcnt(0)
	v_add_f32_e32 v224, v224, v228
	v_add_f32_e32 v225, v225, v229
	v_add_f32_e32 v226, v226, v230
	v_add_f32_e32 v227, v227, v231
	ds_bpermute_b32 v228, v87, v224
	ds_bpermute_b32 v229, v87, v225
	ds_bpermute_b32 v230, v87, v226
	ds_bpermute_b32 v231, v87, v227
	s_waitcnt lgkmcnt(0)
	v_add_f32_e32 v224, v224, v228
	v_add_f32_e32 v225, v225, v229
	v_add_f32_e32 v226, v226, v230
	v_add_f32_e32 v227, v227, v231
	ds_bpermute_b32 v228, v88, v224
	ds_bpermute_b32 v229, v88, v225
	ds_bpermute_b32 v230, v88, v226
	ds_bpermute_b32 v231, v88, v227
	s_waitcnt lgkmcnt(0)
	v_add_f32_e32 v224, v224, v228
	v_add_f32_e32 v225, v225, v229
	v_add_f32_e32 v226, v226, v230
	v_add_f32_e32 v227, v227, v231
	v_fmamk_f32 v240, v224, 0x3a800000, v89
	v_mul_f32_e32 v241, 0x4f800000, v240
	v_cmp_gt_f32_e32 vcc, s54, v240
	s_nop 1
	v_cndmask_b32_e32 v247, v240, v241, vcc
	v_sqrt_f32_e32 v242, v247
	s_nop 1
	v_add_u32_e32 v243, -1, v242
	v_add_u32_e32 v244, 1, v242
	v_fma_f32 v245, -v243, v242, v247
	v_fma_f32 v246, -v244, v242, v247
	v_cmp_ge_f32_e64 s[52:53], 0, v245
	s_nop 1
	v_cndmask_b32_e64 v242, v242, v243, s[52:53]
	v_cmp_lt_f32_e64 s[52:53], 0, v246
	s_nop 1
	v_cndmask_b32_e64 v242, v242, v244, s[52:53]
	v_mul_f32_e32 v243, 0x37800000, v242
	v_cndmask_b32_e32 v242, v242, v243, vcc
	v_cmp_class_f32_e32 vcc, v247, v90
	s_nop 1
	v_cndmask_b32_e32 v247, v242, v247, vcc
	v_div_scale_f32 v248, s[52:53], v247, v247, 1.0
	v_rcp_f32_e32 v249, v248
	v_div_scale_f32 v228, vcc, 1.0, v247, 1.0
	s_nop 0
	v_fma_f32 v229, -v248, v249, 1.0
	v_fmac_f32_e32 v249, v229, v249
	v_mul_f32_e32 v230, v228, v249
	v_fma_f32 v229, -v248, v230, v228
	v_fmac_f32_e32 v230, v229, v249
	v_fma_f32 v248, -v248, v230, v228
	v_div_fmas_f32 v248, v248, v249, v230
	v_div_fixup_f32 v232, v248, v247, 1.0
	v_fmamk_f32 v240, v225, 0x3a800000, v89
	v_mul_f32_e32 v241, 0x4f800000, v240
	v_cmp_gt_f32_e32 vcc, s54, v240
	s_nop 1
	v_cndmask_b32_e32 v247, v240, v241, vcc
	v_sqrt_f32_e32 v242, v247
	s_nop 1
	v_add_u32_e32 v243, -1, v242
	v_add_u32_e32 v244, 1, v242
	v_fma_f32 v245, -v243, v242, v247
	v_fma_f32 v246, -v244, v242, v247
	v_cmp_ge_f32_e64 s[52:53], 0, v245
	s_nop 1
	v_cndmask_b32_e64 v242, v242, v243, s[52:53]
	v_cmp_lt_f32_e64 s[52:53], 0, v246
	s_nop 1
	v_cndmask_b32_e64 v242, v242, v244, s[52:53]
	v_mul_f32_e32 v243, 0x37800000, v242
	v_cndmask_b32_e32 v242, v242, v243, vcc
	v_cmp_class_f32_e32 vcc, v247, v90
	s_nop 1
	v_cndmask_b32_e32 v247, v242, v247, vcc
	v_div_scale_f32 v248, s[52:53], v247, v247, 1.0
	v_rcp_f32_e32 v249, v248
	v_div_scale_f32 v228, vcc, 1.0, v247, 1.0
	s_nop 0
	v_fma_f32 v229, -v248, v249, 1.0
	v_fmac_f32_e32 v249, v229, v249
	v_mul_f32_e32 v230, v228, v249
	v_fma_f32 v229, -v248, v230, v228
	v_fmac_f32_e32 v230, v229, v249
	v_fma_f32 v248, -v248, v230, v228
	v_div_fmas_f32 v248, v248, v249, v230
	v_div_fixup_f32 v234, v248, v247, 1.0
	v_fmamk_f32 v240, v226, 0x3a800000, v89
	v_mul_f32_e32 v241, 0x4f800000, v240
	v_cmp_gt_f32_e32 vcc, s54, v240
	s_nop 1
	v_cndmask_b32_e32 v247, v240, v241, vcc
	v_sqrt_f32_e32 v242, v247
	s_nop 1
	v_add_u32_e32 v243, -1, v242
	v_add_u32_e32 v244, 1, v242
	v_fma_f32 v245, -v243, v242, v247
	v_fma_f32 v246, -v244, v242, v247
	v_cmp_ge_f32_e64 s[52:53], 0, v245
	s_nop 1
	v_cndmask_b32_e64 v242, v242, v243, s[52:53]
	v_cmp_lt_f32_e64 s[52:53], 0, v246
	s_nop 1
	v_cndmask_b32_e64 v242, v242, v244, s[52:53]
	v_mul_f32_e32 v243, 0x37800000, v242
	v_cndmask_b32_e32 v242, v242, v243, vcc
	v_cmp_class_f32_e32 vcc, v247, v90
	s_nop 1
	v_cndmask_b32_e32 v247, v242, v247, vcc
	v_div_scale_f32 v248, s[52:53], v247, v247, 1.0
	v_rcp_f32_e32 v249, v248
	v_div_scale_f32 v228, vcc, 1.0, v247, 1.0
	s_nop 0
	v_fma_f32 v229, -v248, v249, 1.0
	v_fmac_f32_e32 v249, v229, v249
	v_mul_f32_e32 v230, v228, v249
	v_fma_f32 v229, -v248, v230, v228
	v_fmac_f32_e32 v230, v229, v249
	v_fma_f32 v248, -v248, v230, v228
	v_div_fmas_f32 v248, v248, v249, v230
	v_div_fixup_f32 v236, v248, v247, 1.0
	v_fmamk_f32 v240, v227, 0x3a800000, v89
	v_mul_f32_e32 v241, 0x4f800000, v240
	v_cmp_gt_f32_e32 vcc, s54, v240
	s_nop 1
	v_cndmask_b32_e32 v247, v240, v241, vcc
	v_sqrt_f32_e32 v242, v247
	s_nop 1
	v_add_u32_e32 v243, -1, v242
	v_add_u32_e32 v244, 1, v242
	v_fma_f32 v245, -v243, v242, v247
	v_fma_f32 v246, -v244, v242, v247
	v_cmp_ge_f32_e64 s[52:53], 0, v245
	s_nop 1
	v_cndmask_b32_e64 v242, v242, v243, s[52:53]
	v_cmp_lt_f32_e64 s[52:53], 0, v246
	s_nop 1
	v_cndmask_b32_e64 v242, v242, v244, s[52:53]
	v_mul_f32_e32 v243, 0x37800000, v242
	v_cndmask_b32_e32 v242, v242, v243, vcc
	v_cmp_class_f32_e32 vcc, v247, v90
	s_nop 1
	v_cndmask_b32_e32 v247, v242, v247, vcc
	v_div_scale_f32 v248, s[52:53], v247, v247, 1.0
	v_rcp_f32_e32 v249, v248
	v_div_scale_f32 v228, vcc, 1.0, v247, 1.0
	s_nop 0
	v_fma_f32 v229, -v248, v249, 1.0
	v_fmac_f32_e32 v249, v229, v249
	v_mul_f32_e32 v230, v228, v249
	v_fma_f32 v229, -v248, v230, v228
	v_fmac_f32_e32 v230, v229, v249
	v_fma_f32 v248, -v248, v230, v228
	v_div_fmas_f32 v248, v248, v249, v230
	v_div_fixup_f32 v238, v248, v247, 1.0
	s_waitcnt vmcnt(16)
; __device__ __forceinline__ unsigned pk2(float lo, float hi) { return pg8::cvt_pk_bf16(lo, hi); }
; template <bool BF> __device__ __forceinline__ void prep_rows(const float* xp, const float* xs, const bf16* hb, const float* g, const float* MOD, int shoff, int scoff, bf16* U, int gw, int NGW, int lane) {
;     ...
;         for (int r = 0; r < R; ++r) { const int m = mb + r * NGW; if (m < MT) {
;             const float rstd = 1.0f / sqrtf(s[r] * (1.0f / DM) + RMS_EPS);
;             const float* mr = MOD + (size_t)(m < MP ? (m >> 13) : 8 + ((m - MP) >> 12)) * 6144;
; #pragma unroll
;             for (int j = 0; j < 4; ++j) { const int c = 4 * lane + 256 * j;
;                 const f32x4 gg = *(const f32x4*)(g + c), sc = *(const f32x4*)(mr + scoff + c), sh = *(const f32x4*)(mr + shoff + c);
;                 const f32x4 o = v[r][j] * rstd * gg * (sc + 1.0f) + sh; v2u w; w.x = pk2(o.x, o.y); w.y = pk2(o.z, o.w); *(v2u*)(U + (size_t)m * DM + c) = w; } } }
	v_pk_add_f32 v[160:161], v[160:161], 1.0 op_sel_hi:[1,0]
	v_pk_add_f32 v[162:163], v[162:163], 1.0 op_sel_hi:[1,0]
	v_pk_add_f32 v[164:165], v[164:165], 1.0 op_sel_hi:[1,0]
	v_pk_add_f32 v[166:167], v[166:167], 1.0 op_sel_hi:[1,0]
	v_pk_add_f32 v[168:169], v[168:169], 1.0 op_sel_hi:[1,0]
	v_pk_add_f32 v[170:171], v[170:171], 1.0 op_sel_hi:[1,0]
	v_pk_add_f32 v[172:173], v[172:173], 1.0 op_sel_hi:[1,0]
	v_pk_add_f32 v[174:175], v[174:175], 1.0 op_sel_hi:[1,0]
	v_pk_add_f32 v[192:193], v[192:193], 1.0 op_sel_hi:[1,0]
	v_pk_add_f32 v[194:195], v[194:195], 1.0 op_sel_hi:[1,0]
	v_pk_add_f32 v[196:197], v[196:197], 1.0 op_sel_hi:[1,0]
	v_pk_add_f32 v[198:199], v[198:199], 1.0 op_sel_hi:[1,0]
	v_pk_add_f32 v[200:201], v[200:201], 1.0 op_sel_hi:[1,0]
	v_pk_add_f32 v[202:203], v[202:203], 1.0 op_sel_hi:[1,0]
	v_pk_add_f32 v[204:205], v[204:205], 1.0 op_sel_hi:[1,0]
	v_pk_add_f32 v[206:207], v[206:207], 1.0 op_sel_hi:[1,0]
	s_add_u32 s38, s20, 0x7000000
	s_addc_u32 s39, s21, 0
	s_add_u32 s40, s20, 0x7400000
	s_addc_u32 s41, s21, 0
	s_add_u32 s46, s20, 0x7800000
	s_addc_u32 s47, s21, 0
	s_add_u32 s48, s20, 0x7c00000
	s_addc_u32 s49, s21, 0
	v_pk_mul_f32 v[96:97], v[96:97], v[232:233] op_sel_hi:[1,0]
	v_pk_mul_f32 v[98:99], v[98:99], v[232:233] op_sel_hi:[1,0]
	v_pk_mul_f32 v[96:97], v[64:65], v[96:97]
	v_pk_mul_f32 v[98:99], v[66:67], v[98:99]
	v_pk_fma_f32 v[96:97], v[160:161], v[96:97], v[176:177]
	v_pk_fma_f32 v[98:99], v[162:163], v[98:99], v[178:179]
	v_cvt_pk_bf16_f32 v244, v96, v97
	v_cvt_pk_bf16_f32 v245, v98, v99
	v_pk_mul_f32 v[100:101], v[100:101], v[232:233] op_sel_hi:[1,0]
	v_pk_mul_f32 v[102:103], v[102:103], v[232:233] op_sel_hi:[1,0]
	v_pk_mul_f32 v[100:101], v[68:69], v[100:101]
	v_pk_mul_f32 v[102:103], v[70:71], v[102:103]
	v_pk_fma_f32 v[100:101], v[164:165], v[100:101], v[180:181]
	v_pk_fma_f32 v[102:103], v[166:167], v[102:103], v[182:183]
	v_cvt_pk_bf16_f32 v246, v100, v101
	v_cvt_pk_bf16_f32 v247, v102, v103
	global_store_dwordx4 v82, v[244:247], s[38:39] offset:0
	v_pk_mul_f32 v[104:105], v[104:105], v[232:233] op_sel_hi:[1,0]
	v_pk_mul_f32 v[106:107], v[106:107], v[232:233] op_sel_hi:[1,0]
	v_pk_mul_f32 v[104:105], v[72:73], v[104:105]
	v_pk_mul_f32 v[106:107], v[74:75], v[106:107]
	v_pk_fma_f32 v[104:105], v[168:169], v[104:105], v[184:185]
	v_pk_fma_f32 v[106:107], v[170:171], v[106:107], v[186:187]
	v_cvt_pk_bf16_f32 v240, v104, v105
	v_cvt_pk_bf16_f32 v241, v106, v107
	v_pk_mul_f32 v[108:109], v[108:109], v[232:233] op_sel_hi:[1,0]
	v_pk_mul_f32 v[110:111], v[110:111], v[232:233] op_sel_hi:[1,0]
	v_pk_mul_f32 v[108:109], v[76:77], v[108:109]
	v_pk_mul_f32 v[110:111], v[78:79], v[110:111]
	v_pk_fma_f32 v[108:109], v[172:173], v[108:109], v[188:189]
	v_pk_fma_f32 v[110:111], v[174:175], v[110:111], v[190:191]
	v_cvt_pk_bf16_f32 v242, v108, v109
	v_cvt_pk_bf16_f32 v243, v110, v111
	global_store_dwordx4 v82, v[240:243], s[38:39] offset:1024
	v_pk_mul_f32 v[112:113], v[112:113], v[234:235] op_sel_hi:[1,0]
	v_pk_mul_f32 v[114:115], v[114:115], v[234:235] op_sel_hi:[1,0]
	v_pk_mul_f32 v[112:113], v[64:65], v[112:113]
	v_pk_mul_f32 v[114:115], v[66:67], v[114:115]
	v_pk_fma_f32 v[112:113], v[160:161], v[112:113], v[176:177]
	v_pk_fma_f32 v[114:115], v[162:163], v[114:115], v[178:179]
	v_cvt_pk_bf16_f32 v244, v112, v113
	v_cvt_pk_bf16_f32 v245, v114, v115
	v_pk_mul_f32 v[116:117], v[116:117], v[234:235] op_sel_hi:[1,0]
	v_pk_mul_f32 v[118:119], v[118:119], v[234:235] op_sel_hi:[1,0]
	v_pk_mul_f32 v[116:117], v[68:69], v[116:117]
	v_pk_mul_f32 v[118:119], v[70:71], v[118:119]
	v_pk_fma_f32 v[116:117], v[164:165], v[116:117], v[180:181]
	v_pk_fma_f32 v[118:119], v[166:167], v[118:119], v[182:183]
	v_cvt_pk_bf16_f32 v246, v116, v117
	v_cvt_pk_bf16_f32 v247, v118, v119
	global_store_dwordx4 v82, v[244:247], s[40:41] offset:0
	v_pk_mul_f32 v[120:121], v[120:121], v[234:235] op_sel_hi:[1,0]
	v_pk_mul_f32 v[122:123], v[122:123], v[234:235] op_sel_hi:[1,0]
	v_pk_mul_f32 v[120:121], v[72:73], v[120:121]
	v_pk_mul_f32 v[122:123], v[74:75], v[122:123]
	v_pk_fma_f32 v[120:121], v[168:169], v[120:121], v[184:185]
	v_pk_fma_f32 v[122:123], v[170:171], v[122:123], v[186:187]
	v_cvt_pk_bf16_f32 v240, v120, v121
	v_cvt_pk_bf16_f32 v241, v122, v123
	v_pk_mul_f32 v[124:125], v[124:125], v[234:235] op_sel_hi:[1,0]
	v_pk_mul_f32 v[126:127], v[126:127], v[234:235] op_sel_hi:[1,0]
	v_pk_mul_f32 v[124:125], v[76:77], v[124:125]
	v_pk_mul_f32 v[126:127], v[78:79], v[126:127]
	v_pk_fma_f32 v[124:125], v[172:173], v[124:125], v[188:189]
	v_pk_fma_f32 v[126:127], v[174:175], v[126:127], v[190:191]
	v_cvt_pk_bf16_f32 v242, v124, v125
	v_cvt_pk_bf16_f32 v243, v126, v127
	global_store_dwordx4 v82, v[240:243], s[40:41] offset:1024
	v_pk_mul_f32 v[128:129], v[128:129], v[236:237] op_sel_hi:[1,0]
	v_pk_mul_f32 v[130:131], v[130:131], v[236:237] op_sel_hi:[1,0]
	v_pk_mul_f32 v[128:129], v[64:65], v[128:129]
	v_pk_mul_f32 v[130:131], v[66:67], v[130:131]
	v_pk_fma_f32 v[128:129], v[192:193], v[128:129], v[208:209]
	v_pk_fma_f32 v[130:131], v[194:195], v[130:131], v[210:211]
	v_cvt_pk_bf16_f32 v244, v128, v129
	v_cvt_pk_bf16_f32 v245, v130, v131
	v_pk_mul_f32 v[132:133], v[132:133], v[236:237] op_sel_hi:[1,0]
	v_pk_mul_f32 v[134:135], v[134:135], v[236:237] op_sel_hi:[1,0]
	v_pk_mul_f32 v[132:133], v[68:69], v[132:133]
	v_pk_mul_f32 v[134:135], v[70:71], v[134:135]
	v_pk_fma_f32 v[132:133], v[196:197], v[132:133], v[212:213]
	v_pk_fma_f32 v[134:135], v[198:199], v[134:135], v[214:215]
	v_cvt_pk_bf16_f32 v246, v132, v133
	v_cvt_pk_bf16_f32 v247, v134, v135
	global_store_dwordx4 v82, v[244:247], s[46:47] offset:0
	v_pk_mul_f32 v[136:137], v[136:137], v[236:237] op_sel_hi:[1,0]
; __device__ __forceinline__ float bf_lo(unsigned w) { return __uint_as_float(w << 16); }
; __device__ __forceinline__ float bf_hi(unsigned w) { return __uint_as_float(w & 0xffff0000u); }
; __device__ __forceinline__ unsigned pk2(float lo, float hi) { return pg8::cvt_pk_bf16(lo, hi); }
; template <bool BF> __device__ __forceinline__ void prep_rows(const float* xp, const float* xs, const bf16* hb, const float* g, const float* MOD, int shoff, int scoff, bf16* U, int gw, int NGW, int lane) {
;     ...
;         f32x4 v[R][4]; float s[R];
; #pragma unroll
;         for (int r = 0; r < R; ++r) { const int m = mb + r * NGW; const int mc = m < MT ? m : mb;
; #pragma unroll
;             for (int j = 0; j < 4; ++j) {
;                 if (BF) { const v2u a0 = *(const v2u*)(hb + (size_t)mc * DM + 4 * lane + 256 * j);
;                     v[r][j].x = pg8::bf_lo(a0.x); v[r][j].y = pg8::bf_hi(a0.x); v[r][j].z = pg8::bf_lo(a0.y); v[r][j].w = pg8::bf_hi(a0.y); }
;                 else { const float* xr = mc < MP ? xp + (size_t)mc * DM : xs + (size_t)(mc - MP) * DM; v[r][j] = *(const f32x4*)(xr + 4 * lane + 256 * j); } } }
; #pragma unroll
;         for (int r = 0; r < R; ++r) { float t = 0.f;
; #pragma unroll
;             for (int j = 0; j < 4; ++j) t += (v[r][j].x * v[r][j].x + v[r][j].y * v[r][j].y) + (v[r][j].z * v[r][j].z + v[r][j].w * v[r][j].w);
;             s[r] = t; }
; #pragma unroll
;         for (int o = 1; o < 64; o <<= 1) {
; #pragma unroll
;             for (int r = 0; r < R; ++r) s[r] += __shfl_xor(s[r], o); }
; #pragma unroll
;         for (int r = 0; r < R; ++r) { const int m = mb + r * NGW; if (m < MT) {
;             const float rstd = 1.0f / sqrtf(s[r] * (1.0f / DM) + RMS_EPS);
;             const float* mr = MOD + (size_t)(m < MP ? (m >> 13) : 8 + ((m - MP) >> 12)) * 6144;
; #pragma unroll
;             for (int j = 0; j < 4; ++j) { const int c = 4 * lane + 256 * j;
;                 const f32x4 gg = *(const f32x4*)(g + c), sc = *(const f32x4*)(mr + scoff + c), sh = *(const f32x4*)(mr + shoff + c);
;                 const f32x4 o = v[r][j] * rstd * gg * (sc + 1.0f) + sh; v2u w; w.x = pk2(o.x, o.y); w.y = pk2(o.z, o.w); *(v2u*)(U + (size_t)m * DM + c) = w; } } }
	v_pk_mul_f32 v[138:139], v[138:139], v[236:237] op_sel_hi:[1,0]
	v_pk_mul_f32 v[136:137], v[72:73], v[136:137]
	v_pk_mul_f32 v[138:139], v[74:75], v[138:139]
	v_pk_fma_f32 v[136:137], v[200:201], v[136:137], v[216:217]
	v_pk_fma_f32 v[138:139], v[202:203], v[138:139], v[218:219]
	v_cvt_pk_bf16_f32 v240, v136, v137
	v_cvt_pk_bf16_f32 v241, v138, v139
	v_pk_mul_f32 v[140:141], v[140:141], v[236:237] op_sel_hi:[1,0]
	v_pk_mul_f32 v[142:143], v[142:143], v[236:237] op_sel_hi:[1,0]
	v_pk_mul_f32 v[140:141], v[76:77], v[140:141]
	v_pk_mul_f32 v[142:143], v[78:79], v[142:143]
	v_pk_fma_f32 v[140:141], v[204:205], v[140:141], v[220:221]
	v_pk_fma_f32 v[142:143], v[206:207], v[142:143], v[222:223]
	v_cvt_pk_bf16_f32 v242, v140, v141
	v_cvt_pk_bf16_f32 v243, v142, v143
	global_store_dwordx4 v82, v[240:243], s[46:47] offset:1024
	v_pk_mul_f32 v[144:145], v[144:145], v[238:239] op_sel_hi:[1,0]
	v_pk_mul_f32 v[146:147], v[146:147], v[238:239] op_sel_hi:[1,0]
	v_pk_mul_f32 v[144:145], v[64:65], v[144:145]
	v_pk_mul_f32 v[146:147], v[66:67], v[146:147]
	v_pk_fma_f32 v[144:145], v[192:193], v[144:145], v[208:209]
	v_pk_fma_f32 v[146:147], v[194:195], v[146:147], v[210:211]
	v_cvt_pk_bf16_f32 v244, v144, v145
	v_cvt_pk_bf16_f32 v245, v146, v147
	v_pk_mul_f32 v[148:149], v[148:149], v[238:239] op_sel_hi:[1,0]
	v_pk_mul_f32 v[150:151], v[150:151], v[238:239] op_sel_hi:[1,0]
	v_pk_mul_f32 v[148:149], v[68:69], v[148:149]
	v_pk_mul_f32 v[150:151], v[70:71], v[150:151]
	v_pk_fma_f32 v[148:149], v[196:197], v[148:149], v[212:213]
	v_pk_fma_f32 v[150:151], v[198:199], v[150:151], v[214:215]
	v_cvt_pk_bf16_f32 v246, v148, v149
	v_cvt_pk_bf16_f32 v247, v150, v151
	global_store_dwordx4 v82, v[244:247], s[48:49] offset:0
	v_pk_mul_f32 v[152:153], v[152:153], v[238:239] op_sel_hi:[1,0]
	v_pk_mul_f32 v[154:155], v[154:155], v[238:239] op_sel_hi:[1,0]
	v_pk_mul_f32 v[152:153], v[72:73], v[152:153]
	v_pk_mul_f32 v[154:155], v[74:75], v[154:155]
	v_pk_fma_f32 v[152:153], v[200:201], v[152:153], v[216:217]
	v_pk_fma_f32 v[154:155], v[202:203], v[154:155], v[218:219]
	v_cvt_pk_bf16_f32 v240, v152, v153
	v_cvt_pk_bf16_f32 v241, v154, v155
	v_pk_mul_f32 v[156:157], v[156:157], v[238:239] op_sel_hi:[1,0]
	v_pk_mul_f32 v[158:159], v[158:159], v[238:239] op_sel_hi:[1,0]
	v_pk_mul_f32 v[156:157], v[76:77], v[156:157]
	v_pk_mul_f32 v[158:159], v[78:79], v[158:159]
	v_pk_fma_f32 v[156:157], v[204:205], v[156:157], v[220:221]
	v_pk_fma_f32 v[158:159], v[206:207], v[158:159], v[222:223]
	v_cvt_pk_bf16_f32 v242, v156, v157
	v_cvt_pk_bf16_f32 v243, v158, v159
	global_store_dwordx4 v82, v[240:243], s[48:49] offset:1024
	s_add_u32 s34, s8, 0x30000
	s_addc_u32 s35, s9, 0
	s_add_u32 s36, s8, 0x36000
	s_addc_u32 s37, s9, 0
	global_load_dwordx4 v[176:179], v80, s[34:35] offset:0
	global_load_dwordx4 v[180:183], v80, s[34:35] offset:16
	global_load_dwordx4 v[184:187], v80, s[34:35] offset:2048
	global_load_dwordx4 v[188:191], v80, s[34:35] offset:2064
	global_load_dwordx4 v[160:163], v81, s[34:35] offset:0
	global_load_dwordx4 v[164:167], v81, s[34:35] offset:16
	global_load_dwordx4 v[168:171], v81, s[34:35] offset:2048
	global_load_dwordx4 v[172:175], v81, s[34:35] offset:2064
	global_load_dwordx4 v[208:211], v80, s[36:37] offset:0
	global_load_dwordx4 v[212:215], v80, s[36:37] offset:16
	global_load_dwordx4 v[216:219], v80, s[36:37] offset:2048
	global_load_dwordx4 v[220:223], v80, s[36:37] offset:2064
	global_load_dwordx4 v[192:195], v81, s[36:37] offset:0
	global_load_dwordx4 v[196:199], v81, s[36:37] offset:16
	global_load_dwordx4 v[200:203], v81, s[36:37] offset:2048
	global_load_dwordx4 v[204:207], v81, s[36:37] offset:2064
	s_add_u32 s24, s18, 0x2000000
	s_addc_u32 s25, s19, 0
	s_add_u32 s26, s18, 0x2800000
	s_addc_u32 s27, s19, 0
	s_add_u32 s28, s18, 0x3000000
	s_addc_u32 s29, s19, 0
	s_add_u32 s30, s18, 0x3800000
	s_addc_u32 s31, s19, 0
	global_load_dwordx4 v[96:99], v80, s[24:25] offset:0
	global_load_dwordx4 v[100:103], v80, s[24:25] offset:16
	global_load_dwordx4 v[104:107], v80, s[24:25] offset:2048
	global_load_dwordx4 v[108:111], v80, s[24:25] offset:2064
	global_load_dwordx4 v[112:115], v80, s[26:27] offset:0
	global_load_dwordx4 v[116:119], v80, s[26:27] offset:16
	global_load_dwordx4 v[120:123], v80, s[26:27] offset:2048
	global_load_dwordx4 v[124:127], v80, s[26:27] offset:2064
	global_load_dwordx4 v[128:131], v80, s[28:29] offset:0
	global_load_dwordx4 v[132:135], v80, s[28:29] offset:16
	global_load_dwordx4 v[136:139], v80, s[28:29] offset:2048
	global_load_dwordx4 v[140:143], v80, s[28:29] offset:2064
	global_load_dwordx4 v[144:147], v80, s[30:31] offset:0
	global_load_dwordx4 v[148:151], v80, s[30:31] offset:16
	global_load_dwordx4 v[152:155], v80, s[30:31] offset:2048
	global_load_dwordx4 v[156:159], v80, s[30:31] offset:2064
	s_waitcnt vmcnt(40)
; template <bool BF> __device__ __forceinline__ void prep_rows(const float* xp, const float* xs, const bf16* hb, const float* g, const float* MOD, int shoff, int scoff, bf16* U, int gw, int NGW, int lane) {
;     ...
;         for (int r = 0; r < R; ++r) { float t = 0.f;
; #pragma unroll
;             for (int j = 0; j < 4; ++j) t += (v[r][j].x * v[r][j].x + v[r][j].y * v[r][j].y) + (v[r][j].z * v[r][j].z + v[r][j].w * v[r][j].w);
;             s[r] = t; }
; #pragma unroll
;         for (int o = 1; o < 64; o <<= 1) {
; #pragma unroll
;             for (int r = 0; r < R; ++r) s[r] += __shfl_xor(s[r], o); }
; #pragma unroll
;         for (int r = 0; r < R; ++r) { const int m = mb + r * NGW; if (m < MT) {
;             const float rstd = 1.0f / sqrtf(s[r] * (1.0f / DM) + RMS_EPS);
	v_pk_mul_f32 v[240:241], v[0:1], v[0:1]
	v_pk_mul_f32 v[242:243], v[16:17], v[16:17]
	v_pk_mul_f32 v[244:245], v[32:33], v[32:33]
	v_pk_mul_f32 v[246:247], v[48:49], v[48:49]
	v_pk_fma_f32 v[240:241], v[2:3], v[2:3], v[240:241]
	v_pk_fma_f32 v[242:243], v[18:19], v[18:19], v[242:243]
	v_pk_fma_f32 v[244:245], v[34:35], v[34:35], v[244:245]
	v_pk_fma_f32 v[246:247], v[50:51], v[50:51], v[246:247]
	v_pk_fma_f32 v[240:241], v[4:5], v[4:5], v[240:241]
	v_pk_fma_f32 v[242:243], v[20:21], v[20:21], v[242:243]
	v_pk_fma_f32 v[244:245], v[36:37], v[36:37], v[244:245]
	v_pk_fma_f32 v[246:247], v[52:53], v[52:53], v[246:247]
	v_pk_fma_f32 v[240:241], v[6:7], v[6:7], v[240:241]
	v_pk_fma_f32 v[242:243], v[22:23], v[22:23], v[242:243]
	v_pk_fma_f32 v[244:245], v[38:39], v[38:39], v[244:245]
	v_pk_fma_f32 v[246:247], v[54:55], v[54:55], v[246:247]
	v_pk_fma_f32 v[240:241], v[8:9], v[8:9], v[240:241]
	v_pk_fma_f32 v[242:243], v[24:25], v[24:25], v[242:243]
	v_pk_fma_f32 v[244:245], v[40:41], v[40:41], v[244:245]
	v_pk_fma_f32 v[246:247], v[56:57], v[56:57], v[246:247]
	v_pk_fma_f32 v[240:241], v[10:11], v[10:11], v[240:241]
	v_pk_fma_f32 v[242:243], v[26:27], v[26:27], v[242:243]
	v_pk_fma_f32 v[244:245], v[42:43], v[42:43], v[244:245]
	v_pk_fma_f32 v[246:247], v[58:59], v[58:59], v[246:247]
	v_pk_fma_f32 v[240:241], v[12:13], v[12:13], v[240:241]
	v_pk_fma_f32 v[242:243], v[28:29], v[28:29], v[242:243]
	v_pk_fma_f32 v[244:245], v[44:45], v[44:45], v[244:245]
	v_pk_fma_f32 v[246:247], v[60:61], v[60:61], v[246:247]
	v_pk_fma_f32 v[240:241], v[14:15], v[14:15], v[240:241]
	v_pk_fma_f32 v[242:243], v[30:31], v[30:31], v[242:243]
	v_pk_fma_f32 v[244:245], v[46:47], v[46:47], v[244:245]
	v_pk_fma_f32 v[246:247], v[62:63], v[62:63], v[246:247]
	v_add_f32_e32 v224, v240, v241
	v_add_f32_e32 v225, v242, v243
	v_add_f32_e32 v226, v244, v245
	v_add_f32_e32 v227, v246, v247
	ds_bpermute_b32 v228, v83, v224
	ds_bpermute_b32 v229, v83, v225
	ds_bpermute_b32 v230, v83, v226
	ds_bpermute_b32 v231, v83, v227
	s_waitcnt lgkmcnt(0)
	v_add_f32_e32 v224, v224, v228
	v_add_f32_e32 v225, v225, v229
	v_add_f32_e32 v226, v226, v230
	v_add_f32_e32 v227, v227, v231
	ds_bpermute_b32 v228, v84, v224
	ds_bpermute_b32 v229, v84, v225
	ds_bpermute_b32 v230, v84, v226
	ds_bpermute_b32 v231, v84, v227
	s_waitcnt lgkmcnt(0)
	v_add_f32_e32 v224, v224, v228
	v_add_f32_e32 v225, v225, v229
	v_add_f32_e32 v226, v226, v230
	v_add_f32_e32 v227, v227, v231
	ds_bpermute_b32 v228, v85, v224
	ds_bpermute_b32 v229, v85, v225
	ds_bpermute_b32 v230, v85, v226
	ds_bpermute_b32 v231, v85, v227
	s_waitcnt lgkmcnt(0)
	v_add_f32_e32 v224, v224, v228
	v_add_f32_e32 v225, v225, v229
	v_add_f32_e32 v226, v226, v230
	v_add_f32_e32 v227, v227, v231
	ds_bpermute_b32 v228, v86, v224
	ds_bpermute_b32 v229, v86, v225
	ds_bpermute_b32 v230, v86, v226
	ds_bpermute_b32 v231, v86, v227
	s_waitcnt lgkmcnt(0)
	v_add_f32_e32 v224, v224, v228
	v_add_f32_e32 v225, v225, v229
	v_add_f32_e32 v226, v226, v230
	v_add_f32_e32 v227, v227, v231
	ds_bpermute_b32 v228, v87, v224
	ds_bpermute_b32 v229, v87, v225
	ds_bpermute_b32 v230, v87, v226
	ds_bpermute_b32 v231, v87, v227
	s_waitcnt lgkmcnt(0)
	v_add_f32_e32 v224, v224, v228
	v_add_f32_e32 v225, v225, v229
	v_add_f32_e32 v226, v226, v230
	v_add_f32_e32 v227, v227, v231
	ds_bpermute_b32 v228, v88, v224
	ds_bpermute_b32 v229, v88, v225
	ds_bpermute_b32 v230, v88, v226
	ds_bpermute_b32 v231, v88, v227
	s_waitcnt lgkmcnt(0)
	v_add_f32_e32 v224, v224, v228
	v_add_f32_e32 v225, v225, v229
	v_add_f32_e32 v226, v226, v230
	v_add_f32_e32 v227, v227, v231
	v_fmamk_f32 v240, v224, 0x3a800000, v89
	v_mul_f32_e32 v241, 0x4f800000, v240
	v_cmp_gt_f32_e32 vcc, s54, v240
	s_nop 1
	v_cndmask_b32_e32 v247, v240, v241, vcc
	v_sqrt_f32_e32 v242, v247
	s_nop 1
	v_add_u32_e32 v243, -1, v242
	v_add_u32_e32 v244, 1, v242
	v_fma_f32 v245, -v243, v242, v247
	v_fma_f32 v246, -v244, v242, v247
	v_cmp_ge_f32_e64 s[52:53], 0, v245
	s_nop 1
	v_cndmask_b32_e64 v242, v242, v243, s[52:53]
	v_cmp_lt_f32_e64 s[52:53], 0, v246
	s_nop 1
	v_cndmask_b32_e64 v242, v242, v244, s[52:53]
	v_mul_f32_e32 v243, 0x37800000, v242
	v_cndmask_b32_e32 v242, v242, v243, vcc
	v_cmp_class_f32_e32 vcc, v247, v90
	s_nop 1
	v_cndmask_b32_e32 v247, v242, v247, vcc
	v_div_scale_f32 v248, s[52:53], v247, v247, 1.0
	v_rcp_f32_e32 v249, v248
	v_div_scale_f32 v228, vcc, 1.0, v247, 1.0
	s_nop 0
	v_fma_f32 v229, -v248, v249, 1.0
	v_fmac_f32_e32 v249, v229, v249
	v_mul_f32_e32 v230, v228, v249
	v_fma_f32 v229, -v248, v230, v228
	v_fmac_f32_e32 v230, v229, v249
	v_fma_f32 v248, -v248, v230, v228
	v_div_fmas_f32 v248, v248, v249, v230
	v_div_fixup_f32 v232, v248, v247, 1.0
	v_fmamk_f32 v240, v225, 0x3a800000, v89
	v_mul_f32_e32 v241, 0x4f800000, v240
	v_cmp_gt_f32_e32 vcc, s54, v240
	s_nop 1
	v_cndmask_b32_e32 v247, v240, v241, vcc
	v_sqrt_f32_e32 v242, v247
	s_nop 1
	v_add_u32_e32 v243, -1, v242
	v_add_u32_e32 v244, 1, v242
	v_fma_f32 v245, -v243, v242, v247
	v_fma_f32 v246, -v244, v242, v247
	v_cmp_ge_f32_e64 s[52:53], 0, v245
	s_nop 1
	v_cndmask_b32_e64 v242, v242, v243, s[52:53]
	v_cmp_lt_f32_e64 s[52:53], 0, v246
	s_nop 1
	v_cndmask_b32_e64 v242, v242, v244, s[52:53]
	v_mul_f32_e32 v243, 0x37800000, v242
	v_cndmask_b32_e32 v242, v242, v243, vcc
	v_cmp_class_f32_e32 vcc, v247, v90
	s_nop 1
	v_cndmask_b32_e32 v247, v242, v247, vcc
	v_div_scale_f32 v248, s[52:53], v247, v247, 1.0
	v_rcp_f32_e32 v249, v248
	v_div_scale_f32 v228, vcc, 1.0, v247, 1.0
	s_nop 0
	v_fma_f32 v229, -v248, v249, 1.0
	v_fmac_f32_e32 v249, v229, v249
	v_mul_f32_e32 v230, v228, v249
	v_fma_f32 v229, -v248, v230, v228
	v_fmac_f32_e32 v230, v229, v249
; __device__ __forceinline__ unsigned pk2(float lo, float hi) { return pg8::cvt_pk_bf16(lo, hi); }
; template <bool BF> __device__ __forceinline__ void prep_rows(const float* xp, const float* xs, const bf16* hb, const float* g, const float* MOD, int shoff, int scoff, bf16* U, int gw, int NGW, int lane) {
;     ...
;             const float rstd = 1.0f / sqrtf(s[r] * (1.0f / DM) + RMS_EPS);
;             const float* mr = MOD + (size_t)(m < MP ? (m >> 13) : 8 + ((m - MP) >> 12)) * 6144;
; #pragma unroll
;             for (int j = 0; j < 4; ++j) { const int c = 4 * lane + 256 * j;
;                 const f32x4 gg = *(const f32x4*)(g + c), sc = *(const f32x4*)(mr + scoff + c), sh = *(const f32x4*)(mr + shoff + c);
;                 const f32x4 o = v[r][j] * rstd * gg * (sc + 1.0f) + sh; v2u w; w.x = pk2(o.x, o.y); w.y = pk2(o.z, o.w); *(v2u*)(U + (size_t)m * DM + c) = w; } } }
	v_fma_f32 v248, -v248, v230, v228
	v_div_fmas_f32 v248, v248, v249, v230
	v_div_fixup_f32 v234, v248, v247, 1.0
	v_fmamk_f32 v240, v226, 0x3a800000, v89
	v_mul_f32_e32 v241, 0x4f800000, v240
	v_cmp_gt_f32_e32 vcc, s54, v240
	s_nop 1
	v_cndmask_b32_e32 v247, v240, v241, vcc
	v_sqrt_f32_e32 v242, v247
	s_nop 1
	v_add_u32_e32 v243, -1, v242
	v_add_u32_e32 v244, 1, v242
	v_fma_f32 v245, -v243, v242, v247
	v_fma_f32 v246, -v244, v242, v247
	v_cmp_ge_f32_e64 s[52:53], 0, v245
	s_nop 1
	v_cndmask_b32_e64 v242, v242, v243, s[52:53]
	v_cmp_lt_f32_e64 s[52:53], 0, v246
	s_nop 1
	v_cndmask_b32_e64 v242, v242, v244, s[52:53]
	v_mul_f32_e32 v243, 0x37800000, v242
	v_cndmask_b32_e32 v242, v242, v243, vcc
	v_cmp_class_f32_e32 vcc, v247, v90
	s_nop 1
	v_cndmask_b32_e32 v247, v242, v247, vcc
	v_div_scale_f32 v248, s[52:53], v247, v247, 1.0
	v_rcp_f32_e32 v249, v248
	v_div_scale_f32 v228, vcc, 1.0, v247, 1.0
	s_nop 0
	v_fma_f32 v229, -v248, v249, 1.0
	v_fmac_f32_e32 v249, v229, v249
	v_mul_f32_e32 v230, v228, v249
	v_fma_f32 v229, -v248, v230, v228
	v_fmac_f32_e32 v230, v229, v249
	v_fma_f32 v248, -v248, v230, v228
	v_div_fmas_f32 v248, v248, v249, v230
	v_div_fixup_f32 v236, v248, v247, 1.0
	v_fmamk_f32 v240, v227, 0x3a800000, v89
	v_mul_f32_e32 v241, 0x4f800000, v240
	v_cmp_gt_f32_e32 vcc, s54, v240
	s_nop 1
	v_cndmask_b32_e32 v247, v240, v241, vcc
	v_sqrt_f32_e32 v242, v247
	s_nop 1
	v_add_u32_e32 v243, -1, v242
	v_add_u32_e32 v244, 1, v242
	v_fma_f32 v245, -v243, v242, v247
	v_fma_f32 v246, -v244, v242, v247
	v_cmp_ge_f32_e64 s[52:53], 0, v245
	s_nop 1
	v_cndmask_b32_e64 v242, v242, v243, s[52:53]
	v_cmp_lt_f32_e64 s[52:53], 0, v246
	s_nop 1
	v_cndmask_b32_e64 v242, v242, v244, s[52:53]
	v_mul_f32_e32 v243, 0x37800000, v242
	v_cndmask_b32_e32 v242, v242, v243, vcc
	v_cmp_class_f32_e32 vcc, v247, v90
	s_nop 1
	v_cndmask_b32_e32 v247, v242, v247, vcc
	v_div_scale_f32 v248, s[52:53], v247, v247, 1.0
	v_rcp_f32_e32 v249, v248
	v_div_scale_f32 v228, vcc, 1.0, v247, 1.0
	s_nop 0
	v_fma_f32 v229, -v248, v249, 1.0
	v_fmac_f32_e32 v249, v229, v249
	v_mul_f32_e32 v230, v228, v249
	v_fma_f32 v229, -v248, v230, v228
	v_fmac_f32_e32 v230, v229, v249
	v_fma_f32 v248, -v248, v230, v228
	v_div_fmas_f32 v248, v248, v249, v230
	v_div_fixup_f32 v238, v248, v247, 1.0
	s_waitcnt vmcnt(16)
	v_pk_add_f32 v[160:161], v[160:161], 1.0 op_sel_hi:[1,0]
	v_pk_add_f32 v[162:163], v[162:163], 1.0 op_sel_hi:[1,0]
	v_pk_add_f32 v[164:165], v[164:165], 1.0 op_sel_hi:[1,0]
	v_pk_add_f32 v[166:167], v[166:167], 1.0 op_sel_hi:[1,0]
	v_pk_add_f32 v[168:169], v[168:169], 1.0 op_sel_hi:[1,0]
	v_pk_add_f32 v[170:171], v[170:171], 1.0 op_sel_hi:[1,0]
	v_pk_add_f32 v[172:173], v[172:173], 1.0 op_sel_hi:[1,0]
	v_pk_add_f32 v[174:175], v[174:175], 1.0 op_sel_hi:[1,0]
	v_pk_add_f32 v[192:193], v[192:193], 1.0 op_sel_hi:[1,0]
	v_pk_add_f32 v[194:195], v[194:195], 1.0 op_sel_hi:[1,0]
	v_pk_add_f32 v[196:197], v[196:197], 1.0 op_sel_hi:[1,0]
	v_pk_add_f32 v[198:199], v[198:199], 1.0 op_sel_hi:[1,0]
	v_pk_add_f32 v[200:201], v[200:201], 1.0 op_sel_hi:[1,0]
	v_pk_add_f32 v[202:203], v[202:203], 1.0 op_sel_hi:[1,0]
	v_pk_add_f32 v[204:205], v[204:205], 1.0 op_sel_hi:[1,0]
	v_pk_add_f32 v[206:207], v[206:207], 1.0 op_sel_hi:[1,0]
	s_add_u32 s38, s20, 0x8000000
	s_addc_u32 s39, s21, 0
	s_add_u32 s40, s20, 0x8400000
	s_addc_u32 s41, s21, 0
	s_add_u32 s46, s20, 0x8800000
	s_addc_u32 s47, s21, 0
	s_add_u32 s48, s20, 0x8c00000
	s_addc_u32 s49, s21, 0
	v_pk_mul_f32 v[0:1], v[0:1], v[232:233] op_sel_hi:[1,0]
	v_pk_mul_f32 v[2:3], v[2:3], v[232:233] op_sel_hi:[1,0]
	v_pk_mul_f32 v[0:1], v[64:65], v[0:1]
	v_pk_mul_f32 v[2:3], v[66:67], v[2:3]
	v_pk_fma_f32 v[0:1], v[160:161], v[0:1], v[176:177]
	v_pk_fma_f32 v[2:3], v[162:163], v[2:3], v[178:179]
	v_cvt_pk_bf16_f32 v244, v0, v1
	v_cvt_pk_bf16_f32 v245, v2, v3
	v_pk_mul_f32 v[4:5], v[4:5], v[232:233] op_sel_hi:[1,0]
	v_pk_mul_f32 v[6:7], v[6:7], v[232:233] op_sel_hi:[1,0]
	v_pk_mul_f32 v[4:5], v[68:69], v[4:5]
	v_pk_mul_f32 v[6:7], v[70:71], v[6:7]
	v_pk_fma_f32 v[4:5], v[164:165], v[4:5], v[180:181]
	v_pk_fma_f32 v[6:7], v[166:167], v[6:7], v[182:183]
	v_cvt_pk_bf16_f32 v246, v4, v5
	v_cvt_pk_bf16_f32 v247, v6, v7
	global_store_dwordx4 v82, v[244:247], s[38:39] offset:0
	v_pk_mul_f32 v[8:9], v[8:9], v[232:233] op_sel_hi:[1,0]
	v_pk_mul_f32 v[10:11], v[10:11], v[232:233] op_sel_hi:[1,0]
	v_pk_mul_f32 v[8:9], v[72:73], v[8:9]
	v_pk_mul_f32 v[10:11], v[74:75], v[10:11]
	v_pk_fma_f32 v[8:9], v[168:169], v[8:9], v[184:185]
	v_pk_fma_f32 v[10:11], v[170:171], v[10:11], v[186:187]
	v_cvt_pk_bf16_f32 v240, v8, v9
	v_cvt_pk_bf16_f32 v241, v10, v11
	v_pk_mul_f32 v[12:13], v[12:13], v[232:233] op_sel_hi:[1,0]
	v_pk_mul_f32 v[14:15], v[14:15], v[232:233] op_sel_hi:[1,0]
	v_pk_mul_f32 v[12:13], v[76:77], v[12:13]
	v_pk_mul_f32 v[14:15], v[78:79], v[14:15]
	v_pk_fma_f32 v[12:13], v[172:173], v[12:13], v[188:189]
	v_pk_fma_f32 v[14:15], v[174:175], v[14:15], v[190:191]
	v_cvt_pk_bf16_f32 v242, v12, v13
	v_cvt_pk_bf16_f32 v243, v14, v15
	global_store_dwordx4 v82, v[240:243], s[38:39] offset:1024
	v_pk_mul_f32 v[16:17], v[16:17], v[234:235] op_sel_hi:[1,0]
	v_pk_mul_f32 v[18:19], v[18:19], v[234:235] op_sel_hi:[1,0]
	v_pk_mul_f32 v[16:17], v[64:65], v[16:17]
	v_pk_mul_f32 v[18:19], v[66:67], v[18:19]
	v_pk_fma_f32 v[16:17], v[160:161], v[16:17], v[176:177]
	v_pk_fma_f32 v[18:19], v[162:163], v[18:19], v[178:179]
	v_cvt_pk_bf16_f32 v244, v16, v17
	v_cvt_pk_bf16_f32 v245, v18, v19
	v_pk_mul_f32 v[20:21], v[20:21], v[234:235] op_sel_hi:[1,0]
	v_pk_mul_f32 v[22:23], v[22:23], v[234:235] op_sel_hi:[1,0]
	v_pk_mul_f32 v[20:21], v[68:69], v[20:21]
	v_pk_mul_f32 v[22:23], v[70:71], v[22:23]
; __device__ __forceinline__ float bf_lo(unsigned w) { return __uint_as_float(w << 16); }
; __device__ __forceinline__ float bf_hi(unsigned w) { return __uint_as_float(w & 0xffff0000u); }
; __device__ __forceinline__ unsigned pk2(float lo, float hi) { return pg8::cvt_pk_bf16(lo, hi); }
; template <bool BF> __device__ __forceinline__ void prep_rows(const float* xp, const float* xs, const bf16* hb, const float* g, const float* MOD, int shoff, int scoff, bf16* U, int gw, int NGW, int lane) {
;     ...
;         f32x4 v[R][4]; float s[R];
; #pragma unroll
;         for (int r = 0; r < R; ++r) { const int m = mb + r * NGW; const int mc = m < MT ? m : mb;
; #pragma unroll
;             for (int j = 0; j < 4; ++j) {
;                 if (BF) { const v2u a0 = *(const v2u*)(hb + (size_t)mc * DM + 4 * lane + 256 * j);
;                     v[r][j].x = pg8::bf_lo(a0.x); v[r][j].y = pg8::bf_hi(a0.x); v[r][j].z = pg8::bf_lo(a0.y); v[r][j].w = pg8::bf_hi(a0.y); }
;                 else { const float* xr = mc < MP ? xp + (size_t)mc * DM : xs + (size_t)(mc - MP) * DM; v[r][j] = *(const f32x4*)(xr + 4 * lane + 256 * j); } } }
; #pragma unroll
;         for (int r = 0; r < R; ++r) { float t = 0.f;
; #pragma unroll
;             for (int j = 0; j < 4; ++j) t += (v[r][j].x * v[r][j].x + v[r][j].y * v[r][j].y) + (v[r][j].z * v[r][j].z + v[r][j].w * v[r][j].w);
;             s[r] = t; }
; #pragma unroll
;         for (int o = 1; o < 64; o <<= 1) {
; #pragma unroll
;             for (int r = 0; r < R; ++r) s[r] += __shfl_xor(s[r], o); }
; #pragma unroll
;         for (int r = 0; r < R; ++r) { const int m = mb + r * NGW; if (m < MT) {
;             const float rstd = 1.0f / sqrtf(s[r] * (1.0f / DM) + RMS_EPS);
;             const float* mr = MOD + (size_t)(m < MP ? (m >> 13) : 8 + ((m - MP) >> 12)) * 6144;
; #pragma unroll
;             for (int j = 0; j < 4; ++j) { const int c = 4 * lane + 256 * j;
;                 const f32x4 gg = *(const f32x4*)(g + c), sc = *(const f32x4*)(mr + scoff + c), sh = *(const f32x4*)(mr + shoff + c);
;                 const f32x4 o = v[r][j] * rstd * gg * (sc + 1.0f) + sh; v2u w; w.x = pk2(o.x, o.y); w.y = pk2(o.z, o.w); *(v2u*)(U + (size_t)m * DM + c) = w; } } }
	v_pk_fma_f32 v[20:21], v[164:165], v[20:21], v[180:181]
	v_pk_fma_f32 v[22:23], v[166:167], v[22:23], v[182:183]
	v_cvt_pk_bf16_f32 v246, v20, v21
	v_cvt_pk_bf16_f32 v247, v22, v23
	global_store_dwordx4 v82, v[244:247], s[40:41] offset:0
	v_pk_mul_f32 v[24:25], v[24:25], v[234:235] op_sel_hi:[1,0]
	v_pk_mul_f32 v[26:27], v[26:27], v[234:235] op_sel_hi:[1,0]
	v_pk_mul_f32 v[24:25], v[72:73], v[24:25]
	v_pk_mul_f32 v[26:27], v[74:75], v[26:27]
	v_pk_fma_f32 v[24:25], v[168:169], v[24:25], v[184:185]
	v_pk_fma_f32 v[26:27], v[170:171], v[26:27], v[186:187]
	v_cvt_pk_bf16_f32 v240, v24, v25
	v_cvt_pk_bf16_f32 v241, v26, v27
	v_pk_mul_f32 v[28:29], v[28:29], v[234:235] op_sel_hi:[1,0]
	v_pk_mul_f32 v[30:31], v[30:31], v[234:235] op_sel_hi:[1,0]
	v_pk_mul_f32 v[28:29], v[76:77], v[28:29]
	v_pk_mul_f32 v[30:31], v[78:79], v[30:31]
	v_pk_fma_f32 v[28:29], v[172:173], v[28:29], v[188:189]
	v_pk_fma_f32 v[30:31], v[174:175], v[30:31], v[190:191]
	v_cvt_pk_bf16_f32 v242, v28, v29
	v_cvt_pk_bf16_f32 v243, v30, v31
	global_store_dwordx4 v82, v[240:243], s[40:41] offset:1024
	v_pk_mul_f32 v[32:33], v[32:33], v[236:237] op_sel_hi:[1,0]
	v_pk_mul_f32 v[34:35], v[34:35], v[236:237] op_sel_hi:[1,0]
	v_pk_mul_f32 v[32:33], v[64:65], v[32:33]
	v_pk_mul_f32 v[34:35], v[66:67], v[34:35]
	v_pk_fma_f32 v[32:33], v[192:193], v[32:33], v[208:209]
	v_pk_fma_f32 v[34:35], v[194:195], v[34:35], v[210:211]
	v_cvt_pk_bf16_f32 v244, v32, v33
	v_cvt_pk_bf16_f32 v245, v34, v35
	v_pk_mul_f32 v[36:37], v[36:37], v[236:237] op_sel_hi:[1,0]
	v_pk_mul_f32 v[38:39], v[38:39], v[236:237] op_sel_hi:[1,0]
	v_pk_mul_f32 v[36:37], v[68:69], v[36:37]
	v_pk_mul_f32 v[38:39], v[70:71], v[38:39]
	v_pk_fma_f32 v[36:37], v[196:197], v[36:37], v[212:213]
	v_pk_fma_f32 v[38:39], v[198:199], v[38:39], v[214:215]
	v_cvt_pk_bf16_f32 v246, v36, v37
	v_cvt_pk_bf16_f32 v247, v38, v39
	global_store_dwordx4 v82, v[244:247], s[46:47] offset:0
	v_pk_mul_f32 v[40:41], v[40:41], v[236:237] op_sel_hi:[1,0]
	v_pk_mul_f32 v[42:43], v[42:43], v[236:237] op_sel_hi:[1,0]
	v_pk_mul_f32 v[40:41], v[72:73], v[40:41]
	v_pk_mul_f32 v[42:43], v[74:75], v[42:43]
	v_pk_fma_f32 v[40:41], v[200:201], v[40:41], v[216:217]
	v_pk_fma_f32 v[42:43], v[202:203], v[42:43], v[218:219]
	v_cvt_pk_bf16_f32 v240, v40, v41
	v_cvt_pk_bf16_f32 v241, v42, v43
	v_pk_mul_f32 v[44:45], v[44:45], v[236:237] op_sel_hi:[1,0]
	v_pk_mul_f32 v[46:47], v[46:47], v[236:237] op_sel_hi:[1,0]
	v_pk_mul_f32 v[44:45], v[76:77], v[44:45]
	v_pk_mul_f32 v[46:47], v[78:79], v[46:47]
	v_pk_fma_f32 v[44:45], v[204:205], v[44:45], v[220:221]
	v_pk_fma_f32 v[46:47], v[206:207], v[46:47], v[222:223]
	v_cvt_pk_bf16_f32 v242, v44, v45
	v_cvt_pk_bf16_f32 v243, v46, v47
	global_store_dwordx4 v82, v[240:243], s[46:47] offset:1024
	v_pk_mul_f32 v[48:49], v[48:49], v[238:239] op_sel_hi:[1,0]
	v_pk_mul_f32 v[50:51], v[50:51], v[238:239] op_sel_hi:[1,0]
	v_pk_mul_f32 v[48:49], v[64:65], v[48:49]
	v_pk_mul_f32 v[50:51], v[66:67], v[50:51]
	v_pk_fma_f32 v[48:49], v[192:193], v[48:49], v[208:209]
	v_pk_fma_f32 v[50:51], v[194:195], v[50:51], v[210:211]
	v_cvt_pk_bf16_f32 v244, v48, v49
	v_cvt_pk_bf16_f32 v245, v50, v51
	v_pk_mul_f32 v[52:53], v[52:53], v[238:239] op_sel_hi:[1,0]
	v_pk_mul_f32 v[54:55], v[54:55], v[238:239] op_sel_hi:[1,0]
	v_pk_mul_f32 v[52:53], v[68:69], v[52:53]
	v_pk_mul_f32 v[54:55], v[70:71], v[54:55]
	v_pk_fma_f32 v[52:53], v[196:197], v[52:53], v[212:213]
	v_pk_fma_f32 v[54:55], v[198:199], v[54:55], v[214:215]
	v_cvt_pk_bf16_f32 v246, v52, v53
	v_cvt_pk_bf16_f32 v247, v54, v55
	global_store_dwordx4 v82, v[244:247], s[48:49] offset:0
	v_pk_mul_f32 v[56:57], v[56:57], v[238:239] op_sel_hi:[1,0]
	v_pk_mul_f32 v[58:59], v[58:59], v[238:239] op_sel_hi:[1,0]
	v_pk_mul_f32 v[56:57], v[72:73], v[56:57]
	v_pk_mul_f32 v[58:59], v[74:75], v[58:59]
	v_pk_fma_f32 v[56:57], v[200:201], v[56:57], v[216:217]
	v_pk_fma_f32 v[58:59], v[202:203], v[58:59], v[218:219]
	v_cvt_pk_bf16_f32 v240, v56, v57
	v_cvt_pk_bf16_f32 v241, v58, v59
	v_pk_mul_f32 v[60:61], v[60:61], v[238:239] op_sel_hi:[1,0]
	v_pk_mul_f32 v[62:63], v[62:63], v[238:239] op_sel_hi:[1,0]
	v_pk_mul_f32 v[60:61], v[76:77], v[60:61]
	v_pk_mul_f32 v[62:63], v[78:79], v[62:63]
	v_pk_fma_f32 v[60:61], v[204:205], v[60:61], v[220:221]
	v_pk_fma_f32 v[62:63], v[206:207], v[62:63], v[222:223]
	v_cvt_pk_bf16_f32 v242, v60, v61
	v_cvt_pk_bf16_f32 v243, v62, v63
	global_store_dwordx4 v82, v[240:243], s[48:49] offset:1024
	s_add_u32 s34, s8, 0x3c000
	s_addc_u32 s35, s9, 0
	s_add_u32 s36, s8, 0x42000
	s_addc_u32 s37, s9, 0
	global_load_dwordx4 v[176:179], v80, s[34:35] offset:0
	global_load_dwordx4 v[180:183], v80, s[34:35] offset:16
	global_load_dwordx4 v[184:187], v80, s[34:35] offset:2048
	global_load_dwordx4 v[188:191], v80, s[34:35] offset:2064
	global_load_dwordx4 v[160:163], v81, s[34:35] offset:0
	global_load_dwordx4 v[164:167], v81, s[34:35] offset:16
	global_load_dwordx4 v[168:171], v81, s[34:35] offset:2048
	global_load_dwordx4 v[172:175], v81, s[34:35] offset:2064
	global_load_dwordx4 v[208:211], v80, s[36:37] offset:0
	global_load_dwordx4 v[212:215], v80, s[36:37] offset:16
	global_load_dwordx4 v[216:219], v80, s[36:37] offset:2048
	global_load_dwordx4 v[220:223], v80, s[36:37] offset:2064
	global_load_dwordx4 v[192:195], v81, s[36:37] offset:0
	global_load_dwordx4 v[196:199], v81, s[36:37] offset:16
	global_load_dwordx4 v[200:203], v81, s[36:37] offset:2048
	global_load_dwordx4 v[204:207], v81, s[36:37] offset:2064
	s_add_u32 s24, s18, 0x4000000
	s_addc_u32 s25, s19, 0
	s_add_u32 s26, s18, 0x4800000
	s_addc_u32 s27, s19, 0
	s_add_u32 s28, s18, 0x5000000
	s_addc_u32 s29, s19, 0
	s_add_u32 s30, s18, 0x5800000
	s_addc_u32 s31, s19, 0
	global_load_dwordx4 v[0:3], v80, s[24:25] offset:0
	global_load_dwordx4 v[4:7], v80, s[24:25] offset:16
	global_load_dwordx4 v[8:11], v80, s[24:25] offset:2048
	global_load_dwordx4 v[12:15], v80, s[24:25] offset:2064
	global_load_dwordx4 v[16:19], v80, s[26:27] offset:0
	global_load_dwordx4 v[20:23], v80, s[26:27] offset:16
	global_load_dwordx4 v[24:27], v80, s[26:27] offset:2048
	global_load_dwordx4 v[28:31], v80, s[26:27] offset:2064
	global_load_dwordx4 v[32:35], v80, s[28:29] offset:0
	global_load_dwordx4 v[36:39], v80, s[28:29] offset:16
	global_load_dwordx4 v[40:43], v80, s[28:29] offset:2048
	global_load_dwordx4 v[44:47], v80, s[28:29] offset:2064
	global_load_dwordx4 v[48:51], v80, s[30:31] offset:0
	global_load_dwordx4 v[52:55], v80, s[30:31] offset:16
	global_load_dwordx4 v[56:59], v80, s[30:31] offset:2048
	global_load_dwordx4 v[60:63], v80, s[30:31] offset:2064
	s_waitcnt vmcnt(40)
; template <bool BF> __device__ __forceinline__ void prep_rows(const float* xp, const float* xs, const bf16* hb, const float* g, const float* MOD, int shoff, int scoff, bf16* U, int gw, int NGW, int lane) {
;     ...
;         for (int r = 0; r < R; ++r) { float t = 0.f;
; #pragma unroll
;             for (int j = 0; j < 4; ++j) t += (v[r][j].x * v[r][j].x + v[r][j].y * v[r][j].y) + (v[r][j].z * v[r][j].z + v[r][j].w * v[r][j].w);
;             s[r] = t; }
; #pragma unroll
;         for (int o = 1; o < 64; o <<= 1) {
; #pragma unroll
;             for (int r = 0; r < R; ++r) s[r] += __shfl_xor(s[r], o); }
; #pragma unroll
;         for (int r = 0; r < R; ++r) { const int m = mb + r * NGW; if (m < MT) {
;             const float rstd = 1.0f / sqrtf(s[r] * (1.0f / DM) + RMS_EPS);
	v_pk_mul_f32 v[240:241], v[96:97], v[96:97]
	v_pk_mul_f32 v[242:243], v[112:113], v[112:113]
	v_pk_mul_f32 v[244:245], v[128:129], v[128:129]
	v_pk_mul_f32 v[246:247], v[144:145], v[144:145]
	v_pk_fma_f32 v[240:241], v[98:99], v[98:99], v[240:241]
	v_pk_fma_f32 v[242:243], v[114:115], v[114:115], v[242:243]
	v_pk_fma_f32 v[244:245], v[130:131], v[130:131], v[244:245]
	v_pk_fma_f32 v[246:247], v[146:147], v[146:147], v[246:247]
	v_pk_fma_f32 v[240:241], v[100:101], v[100:101], v[240:241]
	v_pk_fma_f32 v[242:243], v[116:117], v[116:117], v[242:243]
	v_pk_fma_f32 v[244:245], v[132:133], v[132:133], v[244:245]
	v_pk_fma_f32 v[246:247], v[148:149], v[148:149], v[246:247]
	v_pk_fma_f32 v[240:241], v[102:103], v[102:103], v[240:241]
	v_pk_fma_f32 v[242:243], v[118:119], v[118:119], v[242:243]
	v_pk_fma_f32 v[244:245], v[134:135], v[134:135], v[244:245]
	v_pk_fma_f32 v[246:247], v[150:151], v[150:151], v[246:247]
	v_pk_fma_f32 v[240:241], v[104:105], v[104:105], v[240:241]
	v_pk_fma_f32 v[242:243], v[120:121], v[120:121], v[242:243]
	v_pk_fma_f32 v[244:245], v[136:137], v[136:137], v[244:245]
	v_pk_fma_f32 v[246:247], v[152:153], v[152:153], v[246:247]
	v_pk_fma_f32 v[240:241], v[106:107], v[106:107], v[240:241]
	v_pk_fma_f32 v[242:243], v[122:123], v[122:123], v[242:243]
	v_pk_fma_f32 v[244:245], v[138:139], v[138:139], v[244:245]
	v_pk_fma_f32 v[246:247], v[154:155], v[154:155], v[246:247]
	v_pk_fma_f32 v[240:241], v[108:109], v[108:109], v[240:241]
	v_pk_fma_f32 v[242:243], v[124:125], v[124:125], v[242:243]
	v_pk_fma_f32 v[244:245], v[140:141], v[140:141], v[244:245]
	v_pk_fma_f32 v[246:247], v[156:157], v[156:157], v[246:247]
	v_pk_fma_f32 v[240:241], v[110:111], v[110:111], v[240:241]
	v_pk_fma_f32 v[242:243], v[126:127], v[126:127], v[242:243]
	v_pk_fma_f32 v[244:245], v[142:143], v[142:143], v[244:245]
	v_pk_fma_f32 v[246:247], v[158:159], v[158:159], v[246:247]
	v_add_f32_e32 v224, v240, v241
	v_add_f32_e32 v225, v242, v243
	v_add_f32_e32 v226, v244, v245
	v_add_f32_e32 v227, v246, v247
	ds_bpermute_b32 v228, v83, v224
	ds_bpermute_b32 v229, v83, v225
	ds_bpermute_b32 v230, v83, v226
	ds_bpermute_b32 v231, v83, v227
	s_waitcnt lgkmcnt(0)
	v_add_f32_e32 v224, v224, v228
	v_add_f32_e32 v225, v225, v229
	v_add_f32_e32 v226, v226, v230
	v_add_f32_e32 v227, v227, v231
	ds_bpermute_b32 v228, v84, v224
	ds_bpermute_b32 v229, v84, v225
	ds_bpermute_b32 v230, v84, v226
	ds_bpermute_b32 v231, v84, v227
	s_waitcnt lgkmcnt(0)
	v_add_f32_e32 v224, v224, v228
	v_add_f32_e32 v225, v225, v229
	v_add_f32_e32 v226, v226, v230
	v_add_f32_e32 v227, v227, v231
	ds_bpermute_b32 v228, v85, v224
	ds_bpermute_b32 v229, v85, v225
	ds_bpermute_b32 v230, v85, v226
	ds_bpermute_b32 v231, v85, v227
	s_waitcnt lgkmcnt(0)
	v_add_f32_e32 v224, v224, v228
	v_add_f32_e32 v225, v225, v229
	v_add_f32_e32 v226, v226, v230
	v_add_f32_e32 v227, v227, v231
	ds_bpermute_b32 v228, v86, v224
	ds_bpermute_b32 v229, v86, v225
	ds_bpermute_b32 v230, v86, v226
	ds_bpermute_b32 v231, v86, v227
	s_waitcnt lgkmcnt(0)
	v_add_f32_e32 v224, v224, v228
	v_add_f32_e32 v225, v225, v229
	v_add_f32_e32 v226, v226, v230
	v_add_f32_e32 v227, v227, v231
	ds_bpermute_b32 v228, v87, v224
	ds_bpermute_b32 v229, v87, v225
	ds_bpermute_b32 v230, v87, v226
	ds_bpermute_b32 v231, v87, v227
	s_waitcnt lgkmcnt(0)
	v_add_f32_e32 v224, v224, v228
	v_add_f32_e32 v225, v225, v229
	v_add_f32_e32 v226, v226, v230
	v_add_f32_e32 v227, v227, v231
	ds_bpermute_b32 v228, v88, v224
	ds_bpermute_b32 v229, v88, v225
	ds_bpermute_b32 v230, v88, v226
	ds_bpermute_b32 v231, v88, v227
	s_waitcnt lgkmcnt(0)
	v_add_f32_e32 v224, v224, v228
	v_add_f32_e32 v225, v225, v229
	v_add_f32_e32 v226, v226, v230
	v_add_f32_e32 v227, v227, v231
	v_fmamk_f32 v240, v224, 0x3a800000, v89
	v_mul_f32_e32 v241, 0x4f800000, v240
	v_cmp_gt_f32_e32 vcc, s54, v240
	s_nop 1
	v_cndmask_b32_e32 v247, v240, v241, vcc
	v_sqrt_f32_e32 v242, v247
	s_nop 1
	v_add_u32_e32 v243, -1, v242
	v_add_u32_e32 v244, 1, v242
	v_fma_f32 v245, -v243, v242, v247
	v_fma_f32 v246, -v244, v242, v247
	v_cmp_ge_f32_e64 s[52:53], 0, v245
	s_nop 1
	v_cndmask_b32_e64 v242, v242, v243, s[52:53]
	v_cmp_lt_f32_e64 s[52:53], 0, v246
	s_nop 1
	v_cndmask_b32_e64 v242, v242, v244, s[52:53]
	v_mul_f32_e32 v243, 0x37800000, v242
	v_cndmask_b32_e32 v242, v242, v243, vcc
	v_cmp_class_f32_e32 vcc, v247, v90
	s_nop 1
	v_cndmask_b32_e32 v247, v242, v247, vcc
	v_div_scale_f32 v248, s[52:53], v247, v247, 1.0
	v_rcp_f32_e32 v249, v248
	v_div_scale_f32 v228, vcc, 1.0, v247, 1.0
	s_nop 0
	v_fma_f32 v229, -v248, v249, 1.0
	v_fmac_f32_e32 v249, v229, v249
	v_mul_f32_e32 v230, v228, v249
	v_fma_f32 v229, -v248, v230, v228
	v_fmac_f32_e32 v230, v229, v249
	v_fma_f32 v248, -v248, v230, v228
	v_div_fmas_f32 v248, v248, v249, v230
	v_div_fixup_f32 v232, v248, v247, 1.0
	v_fmamk_f32 v240, v225, 0x3a800000, v89
	v_mul_f32_e32 v241, 0x4f800000, v240
	v_cmp_gt_f32_e32 vcc, s54, v240
	s_nop 1
	v_cndmask_b32_e32 v247, v240, v241, vcc
	v_sqrt_f32_e32 v242, v247
	s_nop 1
	v_add_u32_e32 v243, -1, v242
	v_add_u32_e32 v244, 1, v242
	v_fma_f32 v245, -v243, v242, v247
	v_fma_f32 v246, -v244, v242, v247
	v_cmp_ge_f32_e64 s[52:53], 0, v245
	s_nop 1
	v_cndmask_b32_e64 v242, v242, v243, s[52:53]
	v_cmp_lt_f32_e64 s[52:53], 0, v246
	s_nop 1
	v_cndmask_b32_e64 v242, v242, v244, s[52:53]
	v_mul_f32_e32 v243, 0x37800000, v242
	v_cndmask_b32_e32 v242, v242, v243, vcc
	v_cmp_class_f32_e32 vcc, v247, v90
	s_nop 1
	v_cndmask_b32_e32 v247, v242, v247, vcc
	v_div_scale_f32 v248, s[52:53], v247, v247, 1.0
	v_rcp_f32_e32 v249, v248
	v_div_scale_f32 v228, vcc, 1.0, v247, 1.0
	s_nop 0
	v_fma_f32 v229, -v248, v249, 1.0
; __device__ __forceinline__ unsigned pk2(float lo, float hi) { return pg8::cvt_pk_bf16(lo, hi); }
; template <bool BF> __device__ __forceinline__ void prep_rows(const float* xp, const float* xs, const bf16* hb, const float* g, const float* MOD, int shoff, int scoff, bf16* U, int gw, int NGW, int lane) {
;     ...
;             const float rstd = 1.0f / sqrtf(s[r] * (1.0f / DM) + RMS_EPS);
;             const float* mr = MOD + (size_t)(m < MP ? (m >> 13) : 8 + ((m - MP) >> 12)) * 6144;
; #pragma unroll
;             for (int j = 0; j < 4; ++j) { const int c = 4 * lane + 256 * j;
;                 const f32x4 gg = *(const f32x4*)(g + c), sc = *(const f32x4*)(mr + scoff + c), sh = *(const f32x4*)(mr + shoff + c);
;                 const f32x4 o = v[r][j] * rstd * gg * (sc + 1.0f) + sh; v2u w; w.x = pk2(o.x, o.y); w.y = pk2(o.z, o.w); *(v2u*)(U + (size_t)m * DM + c) = w; } } }
	v_fmac_f32_e32 v249, v229, v249
	v_mul_f32_e32 v230, v228, v249
	v_fma_f32 v229, -v248, v230, v228
	v_fmac_f32_e32 v230, v229, v249
	v_fma_f32 v248, -v248, v230, v228
	v_div_fmas_f32 v248, v248, v249, v230
	v_div_fixup_f32 v234, v248, v247, 1.0
	v_fmamk_f32 v240, v226, 0x3a800000, v89
	v_mul_f32_e32 v241, 0x4f800000, v240
	v_cmp_gt_f32_e32 vcc, s54, v240
	s_nop 1
	v_cndmask_b32_e32 v247, v240, v241, vcc
	v_sqrt_f32_e32 v242, v247
	s_nop 1
	v_add_u32_e32 v243, -1, v242
	v_add_u32_e32 v244, 1, v242
	v_fma_f32 v245, -v243, v242, v247
	v_fma_f32 v246, -v244, v242, v247
	v_cmp_ge_f32_e64 s[52:53], 0, v245
	s_nop 1
	v_cndmask_b32_e64 v242, v242, v243, s[52:53]
	v_cmp_lt_f32_e64 s[52:53], 0, v246
	s_nop 1
	v_cndmask_b32_e64 v242, v242, v244, s[52:53]
	v_mul_f32_e32 v243, 0x37800000, v242
	v_cndmask_b32_e32 v242, v242, v243, vcc
	v_cmp_class_f32_e32 vcc, v247, v90
	s_nop 1
	v_cndmask_b32_e32 v247, v242, v247, vcc
	v_div_scale_f32 v248, s[52:53], v247, v247, 1.0
	v_rcp_f32_e32 v249, v248
	v_div_scale_f32 v228, vcc, 1.0, v247, 1.0
	s_nop 0
	v_fma_f32 v229, -v248, v249, 1.0
	v_fmac_f32_e32 v249, v229, v249
	v_mul_f32_e32 v230, v228, v249
	v_fma_f32 v229, -v248, v230, v228
	v_fmac_f32_e32 v230, v229, v249
	v_fma_f32 v248, -v248, v230, v228
	v_div_fmas_f32 v248, v248, v249, v230
	v_div_fixup_f32 v236, v248, v247, 1.0
	v_fmamk_f32 v240, v227, 0x3a800000, v89
	v_mul_f32_e32 v241, 0x4f800000, v240
	v_cmp_gt_f32_e32 vcc, s54, v240
	s_nop 1
	v_cndmask_b32_e32 v247, v240, v241, vcc
	v_sqrt_f32_e32 v242, v247
	s_nop 1
	v_add_u32_e32 v243, -1, v242
	v_add_u32_e32 v244, 1, v242
	v_fma_f32 v245, -v243, v242, v247
	v_fma_f32 v246, -v244, v242, v247
	v_cmp_ge_f32_e64 s[52:53], 0, v245
	s_nop 1
	v_cndmask_b32_e64 v242, v242, v243, s[52:53]
	v_cmp_lt_f32_e64 s[52:53], 0, v246
	s_nop 1
	v_cndmask_b32_e64 v242, v242, v244, s[52:53]
	v_mul_f32_e32 v243, 0x37800000, v242
	v_cndmask_b32_e32 v242, v242, v243, vcc
	v_cmp_class_f32_e32 vcc, v247, v90
	s_nop 1
	v_cndmask_b32_e32 v247, v242, v247, vcc
	v_div_scale_f32 v248, s[52:53], v247, v247, 1.0
	v_rcp_f32_e32 v249, v248
	v_div_scale_f32 v228, vcc, 1.0, v247, 1.0
	s_nop 0
	v_fma_f32 v229, -v248, v249, 1.0
	v_fmac_f32_e32 v249, v229, v249
	v_mul_f32_e32 v230, v228, v249
	v_fma_f32 v229, -v248, v230, v228
	v_fmac_f32_e32 v230, v229, v249
	v_fma_f32 v248, -v248, v230, v228
	v_div_fmas_f32 v248, v248, v249, v230
	v_div_fixup_f32 v238, v248, v247, 1.0
	s_waitcnt vmcnt(16)
	v_pk_add_f32 v[160:161], v[160:161], 1.0 op_sel_hi:[1,0]
	v_pk_add_f32 v[162:163], v[162:163], 1.0 op_sel_hi:[1,0]
	v_pk_add_f32 v[164:165], v[164:165], 1.0 op_sel_hi:[1,0]
	v_pk_add_f32 v[166:167], v[166:167], 1.0 op_sel_hi:[1,0]
	v_pk_add_f32 v[168:169], v[168:169], 1.0 op_sel_hi:[1,0]
	v_pk_add_f32 v[170:171], v[170:171], 1.0 op_sel_hi:[1,0]
	v_pk_add_f32 v[172:173], v[172:173], 1.0 op_sel_hi:[1,0]
	v_pk_add_f32 v[174:175], v[174:175], 1.0 op_sel_hi:[1,0]
	v_pk_add_f32 v[192:193], v[192:193], 1.0 op_sel_hi:[1,0]
	v_pk_add_f32 v[194:195], v[194:195], 1.0 op_sel_hi:[1,0]
	v_pk_add_f32 v[196:197], v[196:197], 1.0 op_sel_hi:[1,0]
	v_pk_add_f32 v[198:199], v[198:199], 1.0 op_sel_hi:[1,0]
	v_pk_add_f32 v[200:201], v[200:201], 1.0 op_sel_hi:[1,0]
	v_pk_add_f32 v[202:203], v[202:203], 1.0 op_sel_hi:[1,0]
	v_pk_add_f32 v[204:205], v[204:205], 1.0 op_sel_hi:[1,0]
	v_pk_add_f32 v[206:207], v[206:207], 1.0 op_sel_hi:[1,0]
	s_add_u32 s38, s20, 0x9000000
	s_addc_u32 s39, s21, 0
	s_add_u32 s40, s20, 0x9400000
	s_addc_u32 s41, s21, 0
	s_add_u32 s46, s20, 0x9800000
	s_addc_u32 s47, s21, 0
	s_add_u32 s48, s20, 0x9c00000
	s_addc_u32 s49, s21, 0
	v_pk_mul_f32 v[96:97], v[96:97], v[232:233] op_sel_hi:[1,0]
	v_pk_mul_f32 v[98:99], v[98:99], v[232:233] op_sel_hi:[1,0]
	v_pk_mul_f32 v[96:97], v[64:65], v[96:97]
	v_pk_mul_f32 v[98:99], v[66:67], v[98:99]
	v_pk_fma_f32 v[96:97], v[160:161], v[96:97], v[176:177]
	v_pk_fma_f32 v[98:99], v[162:163], v[98:99], v[178:179]
	v_cvt_pk_bf16_f32 v244, v96, v97
	v_cvt_pk_bf16_f32 v245, v98, v99
	v_pk_mul_f32 v[100:101], v[100:101], v[232:233] op_sel_hi:[1,0]
	v_pk_mul_f32 v[102:103], v[102:103], v[232:233] op_sel_hi:[1,0]
	v_pk_mul_f32 v[100:101], v[68:69], v[100:101]
	v_pk_mul_f32 v[102:103], v[70:71], v[102:103]
	v_pk_fma_f32 v[100:101], v[164:165], v[100:101], v[180:181]
	v_pk_fma_f32 v[102:103], v[166:167], v[102:103], v[182:183]
	v_cvt_pk_bf16_f32 v246, v100, v101
	v_cvt_pk_bf16_f32 v247, v102, v103
	global_store_dwordx4 v82, v[244:247], s[38:39] offset:0
	v_pk_mul_f32 v[104:105], v[104:105], v[232:233] op_sel_hi:[1,0]
	v_pk_mul_f32 v[106:107], v[106:107], v[232:233] op_sel_hi:[1,0]
	v_pk_mul_f32 v[104:105], v[72:73], v[104:105]
	v_pk_mul_f32 v[106:107], v[74:75], v[106:107]
	v_pk_fma_f32 v[104:105], v[168:169], v[104:105], v[184:185]
	v_pk_fma_f32 v[106:107], v[170:171], v[106:107], v[186:187]
	v_cvt_pk_bf16_f32 v240, v104, v105
	v_cvt_pk_bf16_f32 v241, v106, v107
	v_pk_mul_f32 v[108:109], v[108:109], v[232:233] op_sel_hi:[1,0]
	v_pk_mul_f32 v[110:111], v[110:111], v[232:233] op_sel_hi:[1,0]
	v_pk_mul_f32 v[108:109], v[76:77], v[108:109]
	v_pk_mul_f32 v[110:111], v[78:79], v[110:111]
	v_pk_fma_f32 v[108:109], v[172:173], v[108:109], v[188:189]
	v_pk_fma_f32 v[110:111], v[174:175], v[110:111], v[190:191]
	v_cvt_pk_bf16_f32 v242, v108, v109
	v_cvt_pk_bf16_f32 v243, v110, v111
	global_store_dwordx4 v82, v[240:243], s[38:39] offset:1024
	v_pk_mul_f32 v[112:113], v[112:113], v[234:235] op_sel_hi:[1,0]
	v_pk_mul_f32 v[114:115], v[114:115], v[234:235] op_sel_hi:[1,0]
	v_pk_mul_f32 v[112:113], v[64:65], v[112:113]
	v_pk_mul_f32 v[114:115], v[66:67], v[114:115]
	v_pk_fma_f32 v[112:113], v[160:161], v[112:113], v[176:177]
; __device__ __forceinline__ unsigned pk2(float lo, float hi) { return pg8::cvt_pk_bf16(lo, hi); }
; template <bool BF> __device__ __forceinline__ void prep_rows(const float* xp, const float* xs, const bf16* hb, const float* g, const float* MOD, int shoff, int scoff, bf16* U, int gw, int NGW, int lane) {
;     ...
;         for (int r = 0; r < R; ++r) { const int m = mb + r * NGW; if (m < MT) {
;             const float rstd = 1.0f / sqrtf(s[r] * (1.0f / DM) + RMS_EPS);
;             const float* mr = MOD + (size_t)(m < MP ? (m >> 13) : 8 + ((m - MP) >> 12)) * 6144;
; #pragma unroll
;             for (int j = 0; j < 4; ++j) { const int c = 4 * lane + 256 * j;
;                 const f32x4 gg = *(const f32x4*)(g + c), sc = *(const f32x4*)(mr + scoff + c), sh = *(const f32x4*)(mr + shoff + c);
;                 const f32x4 o = v[r][j] * rstd * gg * (sc + 1.0f) + sh; v2u w; w.x = pk2(o.x, o.y); w.y = pk2(o.z, o.w); *(v2u*)(U + (size_t)m * DM + c) = w; } } }
	v_pk_fma_f32 v[114:115], v[162:163], v[114:115], v[178:179]
	v_cvt_pk_bf16_f32 v244, v112, v113
	v_cvt_pk_bf16_f32 v245, v114, v115
	v_pk_mul_f32 v[116:117], v[116:117], v[234:235] op_sel_hi:[1,0]
	v_pk_mul_f32 v[118:119], v[118:119], v[234:235] op_sel_hi:[1,0]
	v_pk_mul_f32 v[116:117], v[68:69], v[116:117]
	v_pk_mul_f32 v[118:119], v[70:71], v[118:119]
	v_pk_fma_f32 v[116:117], v[164:165], v[116:117], v[180:181]
	v_pk_fma_f32 v[118:119], v[166:167], v[118:119], v[182:183]
	v_cvt_pk_bf16_f32 v246, v116, v117
	v_cvt_pk_bf16_f32 v247, v118, v119
	global_store_dwordx4 v82, v[244:247], s[40:41] offset:0
	v_pk_mul_f32 v[120:121], v[120:121], v[234:235] op_sel_hi:[1,0]
	v_pk_mul_f32 v[122:123], v[122:123], v[234:235] op_sel_hi:[1,0]
	v_pk_mul_f32 v[120:121], v[72:73], v[120:121]
	v_pk_mul_f32 v[122:123], v[74:75], v[122:123]
	v_pk_fma_f32 v[120:121], v[168:169], v[120:121], v[184:185]
	v_pk_fma_f32 v[122:123], v[170:171], v[122:123], v[186:187]
	v_cvt_pk_bf16_f32 v240, v120, v121
	v_cvt_pk_bf16_f32 v241, v122, v123
	v_pk_mul_f32 v[124:125], v[124:125], v[234:235] op_sel_hi:[1,0]
	v_pk_mul_f32 v[126:127], v[126:127], v[234:235] op_sel_hi:[1,0]
	v_pk_mul_f32 v[124:125], v[76:77], v[124:125]
	v_pk_mul_f32 v[126:127], v[78:79], v[126:127]
	v_pk_fma_f32 v[124:125], v[172:173], v[124:125], v[188:189]
	v_pk_fma_f32 v[126:127], v[174:175], v[126:127], v[190:191]
	v_cvt_pk_bf16_f32 v242, v124, v125
	v_cvt_pk_bf16_f32 v243, v126, v127
	global_store_dwordx4 v82, v[240:243], s[40:41] offset:1024
	v_pk_mul_f32 v[128:129], v[128:129], v[236:237] op_sel_hi:[1,0]
	v_pk_mul_f32 v[130:131], v[130:131], v[236:237] op_sel_hi:[1,0]
	v_pk_mul_f32 v[128:129], v[64:65], v[128:129]
	v_pk_mul_f32 v[130:131], v[66:67], v[130:131]
	v_pk_fma_f32 v[128:129], v[192:193], v[128:129], v[208:209]
	v_pk_fma_f32 v[130:131], v[194:195], v[130:131], v[210:211]
	v_cvt_pk_bf16_f32 v244, v128, v129
	v_cvt_pk_bf16_f32 v245, v130, v131
	v_pk_mul_f32 v[132:133], v[132:133], v[236:237] op_sel_hi:[1,0]
	v_pk_mul_f32 v[134:135], v[134:135], v[236:237] op_sel_hi:[1,0]
	v_pk_mul_f32 v[132:133], v[68:69], v[132:133]
	v_pk_mul_f32 v[134:135], v[70:71], v[134:135]
	v_pk_fma_f32 v[132:133], v[196:197], v[132:133], v[212:213]
	v_pk_fma_f32 v[134:135], v[198:199], v[134:135], v[214:215]
	v_cvt_pk_bf16_f32 v246, v132, v133
	v_cvt_pk_bf16_f32 v247, v134, v135
	global_store_dwordx4 v82, v[244:247], s[46:47] offset:0
	v_pk_mul_f32 v[136:137], v[136:137], v[236:237] op_sel_hi:[1,0]
	v_pk_mul_f32 v[138:139], v[138:139], v[236:237] op_sel_hi:[1,0]
	v_pk_mul_f32 v[136:137], v[72:73], v[136:137]
	v_pk_mul_f32 v[138:139], v[74:75], v[138:139]
	v_pk_fma_f32 v[136:137], v[200:201], v[136:137], v[216:217]
	v_pk_fma_f32 v[138:139], v[202:203], v[138:139], v[218:219]
	v_cvt_pk_bf16_f32 v240, v136, v137
	v_cvt_pk_bf16_f32 v241, v138, v139
	v_pk_mul_f32 v[140:141], v[140:141], v[236:237] op_sel_hi:[1,0]
	v_pk_mul_f32 v[142:143], v[142:143], v[236:237] op_sel_hi:[1,0]
	v_pk_mul_f32 v[140:141], v[76:77], v[140:141]
	v_pk_mul_f32 v[142:143], v[78:79], v[142:143]
	v_pk_fma_f32 v[140:141], v[204:205], v[140:141], v[220:221]
	v_pk_fma_f32 v[142:143], v[206:207], v[142:143], v[222:223]
	v_cvt_pk_bf16_f32 v242, v140, v141
	v_cvt_pk_bf16_f32 v243, v142, v143
	global_store_dwordx4 v82, v[240:243], s[46:47] offset:1024
	v_pk_mul_f32 v[144:145], v[144:145], v[238:239] op_sel_hi:[1,0]
	v_pk_mul_f32 v[146:147], v[146:147], v[238:239] op_sel_hi:[1,0]
	v_pk_mul_f32 v[144:145], v[64:65], v[144:145]
	v_pk_mul_f32 v[146:147], v[66:67], v[146:147]
	v_pk_fma_f32 v[144:145], v[192:193], v[144:145], v[208:209]
	v_pk_fma_f32 v[146:147], v[194:195], v[146:147], v[210:211]
	v_cvt_pk_bf16_f32 v244, v144, v145
	v_cvt_pk_bf16_f32 v245, v146, v147
	v_pk_mul_f32 v[148:149], v[148:149], v[238:239] op_sel_hi:[1,0]
	v_pk_mul_f32 v[150:151], v[150:151], v[238:239] op_sel_hi:[1,0]
	v_pk_mul_f32 v[148:149], v[68:69], v[148:149]
	v_pk_mul_f32 v[150:151], v[70:71], v[150:151]
	v_pk_fma_f32 v[148:149], v[196:197], v[148:149], v[212:213]
	v_pk_fma_f32 v[150:151], v[198:199], v[150:151], v[214:215]
	v_cvt_pk_bf16_f32 v246, v148, v149
	v_cvt_pk_bf16_f32 v247, v150, v151
	global_store_dwordx4 v82, v[244:247], s[48:49] offset:0
	v_pk_mul_f32 v[152:153], v[152:153], v[238:239] op_sel_hi:[1,0]
	v_pk_mul_f32 v[154:155], v[154:155], v[238:239] op_sel_hi:[1,0]
	v_pk_mul_f32 v[152:153], v[72:73], v[152:153]
	v_pk_mul_f32 v[154:155], v[74:75], v[154:155]
	v_pk_fma_f32 v[152:153], v[200:201], v[152:153], v[216:217]
	v_pk_fma_f32 v[154:155], v[202:203], v[154:155], v[218:219]
	v_cvt_pk_bf16_f32 v240, v152, v153
	v_cvt_pk_bf16_f32 v241, v154, v155
	v_pk_mul_f32 v[156:157], v[156:157], v[238:239] op_sel_hi:[1,0]
	v_pk_mul_f32 v[158:159], v[158:159], v[238:239] op_sel_hi:[1,0]
	v_pk_mul_f32 v[156:157], v[76:77], v[156:157]
	v_pk_mul_f32 v[158:159], v[78:79], v[158:159]
	v_pk_fma_f32 v[156:157], v[204:205], v[156:157], v[220:221]
	v_pk_fma_f32 v[158:159], v[206:207], v[158:159], v[222:223]
	v_cvt_pk_bf16_f32 v242, v156, v157
	v_cvt_pk_bf16_f32 v243, v158, v159
	global_store_dwordx4 v82, v[240:243], s[48:49] offset:1024
	s_add_u32 s34, s8, 0x48000
	s_addc_u32 s35, s9, 0
	s_add_u32 s36, s8, 0x4e000
	s_addc_u32 s37, s9, 0
	global_load_dwordx4 v[176:179], v80, s[34:35] offset:0
	global_load_dwordx4 v[180:183], v80, s[34:35] offset:16
	global_load_dwordx4 v[184:187], v80, s[34:35] offset:2048
	global_load_dwordx4 v[188:191], v80, s[34:35] offset:2064
	global_load_dwordx4 v[160:163], v81, s[34:35] offset:0
	global_load_dwordx4 v[164:167], v81, s[34:35] offset:16
	global_load_dwordx4 v[168:171], v81, s[34:35] offset:2048
	global_load_dwordx4 v[172:175], v81, s[34:35] offset:2064
; __device__ __forceinline__ float bf_lo(unsigned w) { return __uint_as_float(w << 16); }
; __device__ __forceinline__ float bf_hi(unsigned w) { return __uint_as_float(w & 0xffff0000u); }
; template <bool BF> __device__ __forceinline__ void prep_rows(const float* xp, const float* xs, const bf16* hb, const float* g, const float* MOD, int shoff, int scoff, bf16* U, int gw, int NGW, int lane) {
;     ...
;         f32x4 v[R][4]; float s[R];
; #pragma unroll
;         for (int r = 0; r < R; ++r) { const int m = mb + r * NGW; const int mc = m < MT ? m : mb;
; #pragma unroll
;             for (int j = 0; j < 4; ++j) {
;                 if (BF) { const v2u a0 = *(const v2u*)(hb + (size_t)mc * DM + 4 * lane + 256 * j);
;                     v[r][j].x = pg8::bf_lo(a0.x); v[r][j].y = pg8::bf_hi(a0.x); v[r][j].z = pg8::bf_lo(a0.y); v[r][j].w = pg8::bf_hi(a0.y); }
;                 else { const float* xr = mc < MP ? xp + (size_t)mc * DM : xs + (size_t)(mc - MP) * DM; v[r][j] = *(const f32x4*)(xr + 4 * lane + 256 * j); } } }
; #pragma unroll
;         for (int r = 0; r < R; ++r) { float t = 0.f;
; #pragma unroll
;             for (int j = 0; j < 4; ++j) t += (v[r][j].x * v[r][j].x + v[r][j].y * v[r][j].y) + (v[r][j].z * v[r][j].z + v[r][j].w * v[r][j].w);
;             s[r] = t; }
; #pragma unroll
;         for (int o = 1; o < 64; o <<= 1) {
; #pragma unroll
;             for (int r = 0; r < R; ++r) s[r] += __shfl_xor(s[r], o); }
	global_load_dwordx4 v[208:211], v80, s[36:37] offset:0
	global_load_dwordx4 v[212:215], v80, s[36:37] offset:16
	global_load_dwordx4 v[216:219], v80, s[36:37] offset:2048
	global_load_dwordx4 v[220:223], v80, s[36:37] offset:2064
	global_load_dwordx4 v[192:195], v81, s[36:37] offset:0
	global_load_dwordx4 v[196:199], v81, s[36:37] offset:16
	global_load_dwordx4 v[200:203], v81, s[36:37] offset:2048
	global_load_dwordx4 v[204:207], v81, s[36:37] offset:2064
	s_add_u32 s24, s18, 0x6000000
	s_addc_u32 s25, s19, 0
	s_add_u32 s26, s18, 0x6800000
	s_addc_u32 s27, s19, 0
	s_add_u32 s28, s18, 0x7000000
	s_addc_u32 s29, s19, 0
	s_add_u32 s30, s18, 0x7800000
	s_addc_u32 s31, s19, 0
	global_load_dwordx4 v[96:99], v80, s[24:25] offset:0
	global_load_dwordx4 v[100:103], v80, s[24:25] offset:16
	global_load_dwordx4 v[104:107], v80, s[24:25] offset:2048
	global_load_dwordx4 v[108:111], v80, s[24:25] offset:2064
	global_load_dwordx4 v[112:115], v80, s[26:27] offset:0
	global_load_dwordx4 v[116:119], v80, s[26:27] offset:16
	global_load_dwordx4 v[120:123], v80, s[26:27] offset:2048
	global_load_dwordx4 v[124:127], v80, s[26:27] offset:2064
	global_load_dwordx4 v[128:131], v80, s[28:29] offset:0
	global_load_dwordx4 v[132:135], v80, s[28:29] offset:16
	global_load_dwordx4 v[136:139], v80, s[28:29] offset:2048
	global_load_dwordx4 v[140:143], v80, s[28:29] offset:2064
	global_load_dwordx4 v[144:147], v80, s[30:31] offset:0
	global_load_dwordx4 v[148:151], v80, s[30:31] offset:16
	global_load_dwordx4 v[152:155], v80, s[30:31] offset:2048
	global_load_dwordx4 v[156:159], v80, s[30:31] offset:2064
	s_waitcnt vmcnt(40)
	v_pk_mul_f32 v[240:241], v[0:1], v[0:1]
	v_pk_mul_f32 v[242:243], v[16:17], v[16:17]
	v_pk_mul_f32 v[244:245], v[32:33], v[32:33]
	v_pk_mul_f32 v[246:247], v[48:49], v[48:49]
	v_pk_fma_f32 v[240:241], v[2:3], v[2:3], v[240:241]
	v_pk_fma_f32 v[242:243], v[18:19], v[18:19], v[242:243]
	v_pk_fma_f32 v[244:245], v[34:35], v[34:35], v[244:245]
	v_pk_fma_f32 v[246:247], v[50:51], v[50:51], v[246:247]
	v_pk_fma_f32 v[240:241], v[4:5], v[4:5], v[240:241]
	v_pk_fma_f32 v[242:243], v[20:21], v[20:21], v[242:243]
	v_pk_fma_f32 v[244:245], v[36:37], v[36:37], v[244:245]
	v_pk_fma_f32 v[246:247], v[52:53], v[52:53], v[246:247]
	v_pk_fma_f32 v[240:241], v[6:7], v[6:7], v[240:241]
	v_pk_fma_f32 v[242:243], v[22:23], v[22:23], v[242:243]
	v_pk_fma_f32 v[244:245], v[38:39], v[38:39], v[244:245]
	v_pk_fma_f32 v[246:247], v[54:55], v[54:55], v[246:247]
	v_pk_fma_f32 v[240:241], v[8:9], v[8:9], v[240:241]
	v_pk_fma_f32 v[242:243], v[24:25], v[24:25], v[242:243]
	v_pk_fma_f32 v[244:245], v[40:41], v[40:41], v[244:245]
	v_pk_fma_f32 v[246:247], v[56:57], v[56:57], v[246:247]
	v_pk_fma_f32 v[240:241], v[10:11], v[10:11], v[240:241]
	v_pk_fma_f32 v[242:243], v[26:27], v[26:27], v[242:243]
	v_pk_fma_f32 v[244:245], v[42:43], v[42:43], v[244:245]
	v_pk_fma_f32 v[246:247], v[58:59], v[58:59], v[246:247]
	v_pk_fma_f32 v[240:241], v[12:13], v[12:13], v[240:241]
	v_pk_fma_f32 v[242:243], v[28:29], v[28:29], v[242:243]
	v_pk_fma_f32 v[244:245], v[44:45], v[44:45], v[244:245]
	v_pk_fma_f32 v[246:247], v[60:61], v[60:61], v[246:247]
	v_pk_fma_f32 v[240:241], v[14:15], v[14:15], v[240:241]
	v_pk_fma_f32 v[242:243], v[30:31], v[30:31], v[242:243]
	v_pk_fma_f32 v[244:245], v[46:47], v[46:47], v[244:245]
	v_pk_fma_f32 v[246:247], v[62:63], v[62:63], v[246:247]
	v_add_f32_e32 v224, v240, v241
	v_add_f32_e32 v225, v242, v243
	v_add_f32_e32 v226, v244, v245
	v_add_f32_e32 v227, v246, v247
	ds_bpermute_b32 v228, v83, v224
	ds_bpermute_b32 v229, v83, v225
	ds_bpermute_b32 v230, v83, v226
	ds_bpermute_b32 v231, v83, v227
	s_waitcnt lgkmcnt(0)
	v_add_f32_e32 v224, v224, v228
	v_add_f32_e32 v225, v225, v229
	v_add_f32_e32 v226, v226, v230
	v_add_f32_e32 v227, v227, v231
	ds_bpermute_b32 v228, v84, v224
	ds_bpermute_b32 v229, v84, v225
	ds_bpermute_b32 v230, v84, v226
	ds_bpermute_b32 v231, v84, v227
	s_waitcnt lgkmcnt(0)
	v_add_f32_e32 v224, v224, v228
	v_add_f32_e32 v225, v225, v229
	v_add_f32_e32 v226, v226, v230
	v_add_f32_e32 v227, v227, v231
	ds_bpermute_b32 v228, v85, v224
	ds_bpermute_b32 v229, v85, v225
	ds_bpermute_b32 v230, v85, v226
	ds_bpermute_b32 v231, v85, v227
	s_waitcnt lgkmcnt(0)
	v_add_f32_e32 v224, v224, v228
	v_add_f32_e32 v225, v225, v229
	v_add_f32_e32 v226, v226, v230
	v_add_f32_e32 v227, v227, v231
	ds_bpermute_b32 v228, v86, v224
	ds_bpermute_b32 v229, v86, v225
	ds_bpermute_b32 v230, v86, v226
	ds_bpermute_b32 v231, v86, v227
	s_waitcnt lgkmcnt(0)
	v_add_f32_e32 v224, v224, v228
	v_add_f32_e32 v225, v225, v229
	v_add_f32_e32 v226, v226, v230
	v_add_f32_e32 v227, v227, v231
	ds_bpermute_b32 v228, v87, v224
	ds_bpermute_b32 v229, v87, v225
	ds_bpermute_b32 v230, v87, v226
	ds_bpermute_b32 v231, v87, v227
	s_waitcnt lgkmcnt(0)
	v_add_f32_e32 v224, v224, v228
	v_add_f32_e32 v225, v225, v229
	v_add_f32_e32 v226, v226, v230
	v_add_f32_e32 v227, v227, v231
	ds_bpermute_b32 v228, v88, v224
	ds_bpermute_b32 v229, v88, v225
	ds_bpermute_b32 v230, v88, v226
	ds_bpermute_b32 v231, v88, v227
	s_waitcnt lgkmcnt(0)
; template <bool BF> __device__ __forceinline__ void prep_rows(const float* xp, const float* xs, const bf16* hb, const float* g, const float* MOD, int shoff, int scoff, bf16* U, int gw, int NGW, int lane) {
;     ...
; #pragma unroll
;         for (int o = 1; o < 64; o <<= 1) {
; #pragma unroll
;             for (int r = 0; r < R; ++r) s[r] += __shfl_xor(s[r], o); }
; #pragma unroll
;         for (int r = 0; r < R; ++r) { const int m = mb + r * NGW; if (m < MT) {
;             const float rstd = 1.0f / sqrtf(s[r] * (1.0f / DM) + RMS_EPS);
	v_add_f32_e32 v224, v224, v228
	v_add_f32_e32 v225, v225, v229
	v_add_f32_e32 v226, v226, v230
	v_add_f32_e32 v227, v227, v231
	v_fmamk_f32 v240, v224, 0x3a800000, v89
	v_mul_f32_e32 v241, 0x4f800000, v240
	v_cmp_gt_f32_e32 vcc, s54, v240
	s_nop 1
	v_cndmask_b32_e32 v247, v240, v241, vcc
	v_sqrt_f32_e32 v242, v247
	s_nop 1
	v_add_u32_e32 v243, -1, v242
	v_add_u32_e32 v244, 1, v242
	v_fma_f32 v245, -v243, v242, v247
	v_fma_f32 v246, -v244, v242, v247
	v_cmp_ge_f32_e64 s[52:53], 0, v245
	s_nop 1
	v_cndmask_b32_e64 v242, v242, v243, s[52:53]
	v_cmp_lt_f32_e64 s[52:53], 0, v246
	s_nop 1
	v_cndmask_b32_e64 v242, v242, v244, s[52:53]
	v_mul_f32_e32 v243, 0x37800000, v242
	v_cndmask_b32_e32 v242, v242, v243, vcc
	v_cmp_class_f32_e32 vcc, v247, v90
	s_nop 1
	v_cndmask_b32_e32 v247, v242, v247, vcc
	v_div_scale_f32 v248, s[52:53], v247, v247, 1.0
	v_rcp_f32_e32 v249, v248
	v_div_scale_f32 v228, vcc, 1.0, v247, 1.0
	s_nop 0
	v_fma_f32 v229, -v248, v249, 1.0
	v_fmac_f32_e32 v249, v229, v249
	v_mul_f32_e32 v230, v228, v249
	v_fma_f32 v229, -v248, v230, v228
	v_fmac_f32_e32 v230, v229, v249
	v_fma_f32 v248, -v248, v230, v228
	v_div_fmas_f32 v248, v248, v249, v230
	v_div_fixup_f32 v232, v248, v247, 1.0
	v_fmamk_f32 v240, v225, 0x3a800000, v89
	v_mul_f32_e32 v241, 0x4f800000, v240
	v_cmp_gt_f32_e32 vcc, s54, v240
	s_nop 1
	v_cndmask_b32_e32 v247, v240, v241, vcc
	v_sqrt_f32_e32 v242, v247
	s_nop 1
	v_add_u32_e32 v243, -1, v242
	v_add_u32_e32 v244, 1, v242
	v_fma_f32 v245, -v243, v242, v247
	v_fma_f32 v246, -v244, v242, v247
	v_cmp_ge_f32_e64 s[52:53], 0, v245
	s_nop 1
	v_cndmask_b32_e64 v242, v242, v243, s[52:53]
	v_cmp_lt_f32_e64 s[52:53], 0, v246
	s_nop 1
	v_cndmask_b32_e64 v242, v242, v244, s[52:53]
	v_mul_f32_e32 v243, 0x37800000, v242
	v_cndmask_b32_e32 v242, v242, v243, vcc
	v_cmp_class_f32_e32 vcc, v247, v90
	s_nop 1
	v_cndmask_b32_e32 v247, v242, v247, vcc
	v_div_scale_f32 v248, s[52:53], v247, v247, 1.0
	v_rcp_f32_e32 v249, v248
	v_div_scale_f32 v228, vcc, 1.0, v247, 1.0
	s_nop 0
	v_fma_f32 v229, -v248, v249, 1.0
	v_fmac_f32_e32 v249, v229, v249
	v_mul_f32_e32 v230, v228, v249
	v_fma_f32 v229, -v248, v230, v228
	v_fmac_f32_e32 v230, v229, v249
	v_fma_f32 v248, -v248, v230, v228
	v_div_fmas_f32 v248, v248, v249, v230
	v_div_fixup_f32 v234, v248, v247, 1.0
	v_fmamk_f32 v240, v226, 0x3a800000, v89
	v_mul_f32_e32 v241, 0x4f800000, v240
	v_cmp_gt_f32_e32 vcc, s54, v240
	s_nop 1
	v_cndmask_b32_e32 v247, v240, v241, vcc
	v_sqrt_f32_e32 v242, v247
	s_nop 1
	v_add_u32_e32 v243, -1, v242
	v_add_u32_e32 v244, 1, v242
	v_fma_f32 v245, -v243, v242, v247
	v_fma_f32 v246, -v244, v242, v247
	v_cmp_ge_f32_e64 s[52:53], 0, v245
	s_nop 1
	v_cndmask_b32_e64 v242, v242, v243, s[52:53]
	v_cmp_lt_f32_e64 s[52:53], 0, v246
	s_nop 1
	v_cndmask_b32_e64 v242, v242, v244, s[52:53]
	v_mul_f32_e32 v243, 0x37800000, v242
	v_cndmask_b32_e32 v242, v242, v243, vcc
	v_cmp_class_f32_e32 vcc, v247, v90
	s_nop 1
	v_cndmask_b32_e32 v247, v242, v247, vcc
	v_div_scale_f32 v248, s[52:53], v247, v247, 1.0
	v_rcp_f32_e32 v249, v248
	v_div_scale_f32 v228, vcc, 1.0, v247, 1.0
	s_nop 0
	v_fma_f32 v229, -v248, v249, 1.0
	v_fmac_f32_e32 v249, v229, v249
	v_mul_f32_e32 v230, v228, v249
	v_fma_f32 v229, -v248, v230, v228
	v_fmac_f32_e32 v230, v229, v249
	v_fma_f32 v248, -v248, v230, v228
	v_div_fmas_f32 v248, v248, v249, v230
	v_div_fixup_f32 v236, v248, v247, 1.0
	v_fmamk_f32 v240, v227, 0x3a800000, v89
	v_mul_f32_e32 v241, 0x4f800000, v240
	v_cmp_gt_f32_e32 vcc, s54, v240
	s_nop 1
	v_cndmask_b32_e32 v247, v240, v241, vcc
	v_sqrt_f32_e32 v242, v247
	s_nop 1
	v_add_u32_e32 v243, -1, v242
	v_add_u32_e32 v244, 1, v242
	v_fma_f32 v245, -v243, v242, v247
	v_fma_f32 v246, -v244, v242, v247
	v_cmp_ge_f32_e64 s[52:53], 0, v245
	s_nop 1
	v_cndmask_b32_e64 v242, v242, v243, s[52:53]
	v_cmp_lt_f32_e64 s[52:53], 0, v246
	s_nop 1
	v_cndmask_b32_e64 v242, v242, v244, s[52:53]
	v_mul_f32_e32 v243, 0x37800000, v242
	v_cndmask_b32_e32 v242, v242, v243, vcc
	v_cmp_class_f32_e32 vcc, v247, v90
	s_nop 1
	v_cndmask_b32_e32 v247, v242, v247, vcc
	v_div_scale_f32 v248, s[52:53], v247, v247, 1.0
	v_rcp_f32_e32 v249, v248
	v_div_scale_f32 v228, vcc, 1.0, v247, 1.0
	s_nop 0
	v_fma_f32 v229, -v248, v249, 1.0
	v_fmac_f32_e32 v249, v229, v249
	v_mul_f32_e32 v230, v228, v249
	v_fma_f32 v229, -v248, v230, v228
	v_fmac_f32_e32 v230, v229, v249
	v_fma_f32 v248, -v248, v230, v228
	v_div_fmas_f32 v248, v248, v249, v230
	v_div_fixup_f32 v238, v248, v247, 1.0
	s_waitcnt vmcnt(16)
; __device__ __forceinline__ unsigned pk2(float lo, float hi) { return pg8::cvt_pk_bf16(lo, hi); }
; template <bool BF> __device__ __forceinline__ void prep_rows(const float* xp, const float* xs, const bf16* hb, const float* g, const float* MOD, int shoff, int scoff, bf16* U, int gw, int NGW, int lane) {
;     ...
;         for (int r = 0; r < R; ++r) { const int m = mb + r * NGW; if (m < MT) {
;             const float rstd = 1.0f / sqrtf(s[r] * (1.0f / DM) + RMS_EPS);
;             const float* mr = MOD + (size_t)(m < MP ? (m >> 13) : 8 + ((m - MP) >> 12)) * 6144;
; #pragma unroll
;             for (int j = 0; j < 4; ++j) { const int c = 4 * lane + 256 * j;
;                 const f32x4 gg = *(const f32x4*)(g + c), sc = *(const f32x4*)(mr + scoff + c), sh = *(const f32x4*)(mr + shoff + c);
;                 const f32x4 o = v[r][j] * rstd * gg * (sc + 1.0f) + sh; v2u w; w.x = pk2(o.x, o.y); w.y = pk2(o.z, o.w); *(v2u*)(U + (size_t)m * DM + c) = w; } } }
	v_pk_add_f32 v[160:161], v[160:161], 1.0 op_sel_hi:[1,0]
	v_pk_add_f32 v[162:163], v[162:163], 1.0 op_sel_hi:[1,0]
	v_pk_add_f32 v[164:165], v[164:165], 1.0 op_sel_hi:[1,0]
	v_pk_add_f32 v[166:167], v[166:167], 1.0 op_sel_hi:[1,0]
	v_pk_add_f32 v[168:169], v[168:169], 1.0 op_sel_hi:[1,0]
	v_pk_add_f32 v[170:171], v[170:171], 1.0 op_sel_hi:[1,0]
	v_pk_add_f32 v[172:173], v[172:173], 1.0 op_sel_hi:[1,0]
	v_pk_add_f32 v[174:175], v[174:175], 1.0 op_sel_hi:[1,0]
	v_pk_add_f32 v[192:193], v[192:193], 1.0 op_sel_hi:[1,0]
	v_pk_add_f32 v[194:195], v[194:195], 1.0 op_sel_hi:[1,0]
	v_pk_add_f32 v[196:197], v[196:197], 1.0 op_sel_hi:[1,0]
	v_pk_add_f32 v[198:199], v[198:199], 1.0 op_sel_hi:[1,0]
	v_pk_add_f32 v[200:201], v[200:201], 1.0 op_sel_hi:[1,0]
	v_pk_add_f32 v[202:203], v[202:203], 1.0 op_sel_hi:[1,0]
	v_pk_add_f32 v[204:205], v[204:205], 1.0 op_sel_hi:[1,0]
	v_pk_add_f32 v[206:207], v[206:207], 1.0 op_sel_hi:[1,0]
	s_add_u32 s38, s20, 0xa000000
	s_addc_u32 s39, s21, 0
	s_add_u32 s40, s20, 0xa400000
	s_addc_u32 s41, s21, 0
	s_add_u32 s46, s20, 0xa800000
	s_addc_u32 s47, s21, 0
	s_add_u32 s48, s20, 0xac00000
	s_addc_u32 s49, s21, 0
	v_pk_mul_f32 v[0:1], v[0:1], v[232:233] op_sel_hi:[1,0]
	v_pk_mul_f32 v[2:3], v[2:3], v[232:233] op_sel_hi:[1,0]
	v_pk_mul_f32 v[0:1], v[64:65], v[0:1]
	v_pk_mul_f32 v[2:3], v[66:67], v[2:3]
	v_pk_fma_f32 v[0:1], v[160:161], v[0:1], v[176:177]
	v_pk_fma_f32 v[2:3], v[162:163], v[2:3], v[178:179]
	v_cvt_pk_bf16_f32 v244, v0, v1
	v_cvt_pk_bf16_f32 v245, v2, v3
	v_pk_mul_f32 v[4:5], v[4:5], v[232:233] op_sel_hi:[1,0]
	v_pk_mul_f32 v[6:7], v[6:7], v[232:233] op_sel_hi:[1,0]
	v_pk_mul_f32 v[4:5], v[68:69], v[4:5]
	v_pk_mul_f32 v[6:7], v[70:71], v[6:7]
	v_pk_fma_f32 v[4:5], v[164:165], v[4:5], v[180:181]
	v_pk_fma_f32 v[6:7], v[166:167], v[6:7], v[182:183]
	v_cvt_pk_bf16_f32 v246, v4, v5
	v_cvt_pk_bf16_f32 v247, v6, v7
	global_store_dwordx4 v82, v[244:247], s[38:39] offset:0
	v_pk_mul_f32 v[8:9], v[8:9], v[232:233] op_sel_hi:[1,0]
	v_pk_mul_f32 v[10:11], v[10:11], v[232:233] op_sel_hi:[1,0]
	v_pk_mul_f32 v[8:9], v[72:73], v[8:9]
	v_pk_mul_f32 v[10:11], v[74:75], v[10:11]
	v_pk_fma_f32 v[8:9], v[168:169], v[8:9], v[184:185]
	v_pk_fma_f32 v[10:11], v[170:171], v[10:11], v[186:187]
	v_cvt_pk_bf16_f32 v240, v8, v9
	v_cvt_pk_bf16_f32 v241, v10, v11
	v_pk_mul_f32 v[12:13], v[12:13], v[232:233] op_sel_hi:[1,0]
	v_pk_mul_f32 v[14:15], v[14:15], v[232:233] op_sel_hi:[1,0]
	v_pk_mul_f32 v[12:13], v[76:77], v[12:13]
	v_pk_mul_f32 v[14:15], v[78:79], v[14:15]
	v_pk_fma_f32 v[12:13], v[172:173], v[12:13], v[188:189]
	v_pk_fma_f32 v[14:15], v[174:175], v[14:15], v[190:191]
	v_cvt_pk_bf16_f32 v242, v12, v13
	v_cvt_pk_bf16_f32 v243, v14, v15
	global_store_dwordx4 v82, v[240:243], s[38:39] offset:1024
	v_pk_mul_f32 v[16:17], v[16:17], v[234:235] op_sel_hi:[1,0]
	v_pk_mul_f32 v[18:19], v[18:19], v[234:235] op_sel_hi:[1,0]
	v_pk_mul_f32 v[16:17], v[64:65], v[16:17]
	v_pk_mul_f32 v[18:19], v[66:67], v[18:19]
	v_pk_fma_f32 v[16:17], v[160:161], v[16:17], v[176:177]
	v_pk_fma_f32 v[18:19], v[162:163], v[18:19], v[178:179]
	v_cvt_pk_bf16_f32 v244, v16, v17
	v_cvt_pk_bf16_f32 v245, v18, v19
	v_pk_mul_f32 v[20:21], v[20:21], v[234:235] op_sel_hi:[1,0]
	v_pk_mul_f32 v[22:23], v[22:23], v[234:235] op_sel_hi:[1,0]
	v_pk_mul_f32 v[20:21], v[68:69], v[20:21]
	v_pk_mul_f32 v[22:23], v[70:71], v[22:23]
	v_pk_fma_f32 v[20:21], v[164:165], v[20:21], v[180:181]
	v_pk_fma_f32 v[22:23], v[166:167], v[22:23], v[182:183]
	v_cvt_pk_bf16_f32 v246, v20, v21
	v_cvt_pk_bf16_f32 v247, v22, v23
	global_store_dwordx4 v82, v[244:247], s[40:41] offset:0
	v_pk_mul_f32 v[24:25], v[24:25], v[234:235] op_sel_hi:[1,0]
	v_pk_mul_f32 v[26:27], v[26:27], v[234:235] op_sel_hi:[1,0]
	v_pk_mul_f32 v[24:25], v[72:73], v[24:25]
	v_pk_mul_f32 v[26:27], v[74:75], v[26:27]
	v_pk_fma_f32 v[24:25], v[168:169], v[24:25], v[184:185]
	v_pk_fma_f32 v[26:27], v[170:171], v[26:27], v[186:187]
	v_cvt_pk_bf16_f32 v240, v24, v25
	v_cvt_pk_bf16_f32 v241, v26, v27
	v_pk_mul_f32 v[28:29], v[28:29], v[234:235] op_sel_hi:[1,0]
	v_pk_mul_f32 v[30:31], v[30:31], v[234:235] op_sel_hi:[1,0]
	v_pk_mul_f32 v[28:29], v[76:77], v[28:29]
	v_pk_mul_f32 v[30:31], v[78:79], v[30:31]
	v_pk_fma_f32 v[28:29], v[172:173], v[28:29], v[188:189]
	v_pk_fma_f32 v[30:31], v[174:175], v[30:31], v[190:191]
	v_cvt_pk_bf16_f32 v242, v28, v29
	v_cvt_pk_bf16_f32 v243, v30, v31
	global_store_dwordx4 v82, v[240:243], s[40:41] offset:1024
	v_pk_mul_f32 v[32:33], v[32:33], v[236:237] op_sel_hi:[1,0]
	v_pk_mul_f32 v[34:35], v[34:35], v[236:237] op_sel_hi:[1,0]
	v_pk_mul_f32 v[32:33], v[64:65], v[32:33]
	v_pk_mul_f32 v[34:35], v[66:67], v[34:35]
	v_pk_fma_f32 v[32:33], v[192:193], v[32:33], v[208:209]
	v_pk_fma_f32 v[34:35], v[194:195], v[34:35], v[210:211]
	v_cvt_pk_bf16_f32 v244, v32, v33
	v_cvt_pk_bf16_f32 v245, v34, v35
	v_pk_mul_f32 v[36:37], v[36:37], v[236:237] op_sel_hi:[1,0]
	v_pk_mul_f32 v[38:39], v[38:39], v[236:237] op_sel_hi:[1,0]
	v_pk_mul_f32 v[36:37], v[68:69], v[36:37]
	v_pk_mul_f32 v[38:39], v[70:71], v[38:39]
	v_pk_fma_f32 v[36:37], v[196:197], v[36:37], v[212:213]
	v_pk_fma_f32 v[38:39], v[198:199], v[38:39], v[214:215]
	v_cvt_pk_bf16_f32 v246, v36, v37
	v_cvt_pk_bf16_f32 v247, v38, v39
	global_store_dwordx4 v82, v[244:247], s[46:47] offset:0
	v_pk_mul_f32 v[40:41], v[40:41], v[236:237] op_sel_hi:[1,0]
	v_pk_mul_f32 v[42:43], v[42:43], v[236:237] op_sel_hi:[1,0]
	v_pk_mul_f32 v[40:41], v[72:73], v[40:41]
	v_pk_mul_f32 v[42:43], v[74:75], v[42:43]
	v_pk_fma_f32 v[40:41], v[200:201], v[40:41], v[216:217]
	v_pk_fma_f32 v[42:43], v[202:203], v[42:43], v[218:219]
	v_cvt_pk_bf16_f32 v240, v40, v41
; __device__ __forceinline__ unsigned pk2(float lo, float hi) { return pg8::cvt_pk_bf16(lo, hi); }
; template <bool BF> __device__ __forceinline__ void prep_rows(const float* xp, const float* xs, const bf16* hb, const float* g, const float* MOD, int shoff, int scoff, bf16* U, int gw, int NGW, int lane) {
;     ...
;         for (int r = 0; r < R; ++r) { float t = 0.f;
; #pragma unroll
;             for (int j = 0; j < 4; ++j) t += (v[r][j].x * v[r][j].x + v[r][j].y * v[r][j].y) + (v[r][j].z * v[r][j].z + v[r][j].w * v[r][j].w);
;             s[r] = t; }
; #pragma unroll
;         for (int o = 1; o < 64; o <<= 1) {
; #pragma unroll
;             for (int r = 0; r < R; ++r) s[r] += __shfl_xor(s[r], o); }
;     ...
;         for (int r = 0; r < R; ++r) { const int m = mb + r * NGW; if (m < MT) {
;             const float rstd = 1.0f / sqrtf(s[r] * (1.0f / DM) + RMS_EPS);
;             const float* mr = MOD + (size_t)(m < MP ? (m >> 13) : 8 + ((m - MP) >> 12)) * 6144;
; #pragma unroll
;             for (int j = 0; j < 4; ++j) { const int c = 4 * lane + 256 * j;
;                 const f32x4 gg = *(const f32x4*)(g + c), sc = *(const f32x4*)(mr + scoff + c), sh = *(const f32x4*)(mr + shoff + c);
;                 const f32x4 o = v[r][j] * rstd * gg * (sc + 1.0f) + sh; v2u w; w.x = pk2(o.x, o.y); w.y = pk2(o.z, o.w); *(v2u*)(U + (size_t)m * DM + c) = w; } } }
	v_cvt_pk_bf16_f32 v241, v42, v43
	v_pk_mul_f32 v[44:45], v[44:45], v[236:237] op_sel_hi:[1,0]
	v_pk_mul_f32 v[46:47], v[46:47], v[236:237] op_sel_hi:[1,0]
	v_pk_mul_f32 v[44:45], v[76:77], v[44:45]
	v_pk_mul_f32 v[46:47], v[78:79], v[46:47]
	v_pk_fma_f32 v[44:45], v[204:205], v[44:45], v[220:221]
	v_pk_fma_f32 v[46:47], v[206:207], v[46:47], v[222:223]
	v_cvt_pk_bf16_f32 v242, v44, v45
	v_cvt_pk_bf16_f32 v243, v46, v47
	global_store_dwordx4 v82, v[240:243], s[46:47] offset:1024
	v_pk_mul_f32 v[48:49], v[48:49], v[238:239] op_sel_hi:[1,0]
	v_pk_mul_f32 v[50:51], v[50:51], v[238:239] op_sel_hi:[1,0]
	v_pk_mul_f32 v[48:49], v[64:65], v[48:49]
	v_pk_mul_f32 v[50:51], v[66:67], v[50:51]
	v_pk_fma_f32 v[48:49], v[192:193], v[48:49], v[208:209]
	v_pk_fma_f32 v[50:51], v[194:195], v[50:51], v[210:211]
	v_cvt_pk_bf16_f32 v244, v48, v49
	v_cvt_pk_bf16_f32 v245, v50, v51
	v_pk_mul_f32 v[52:53], v[52:53], v[238:239] op_sel_hi:[1,0]
	v_pk_mul_f32 v[54:55], v[54:55], v[238:239] op_sel_hi:[1,0]
	v_pk_mul_f32 v[52:53], v[68:69], v[52:53]
	v_pk_mul_f32 v[54:55], v[70:71], v[54:55]
	v_pk_fma_f32 v[52:53], v[196:197], v[52:53], v[212:213]
	v_pk_fma_f32 v[54:55], v[198:199], v[54:55], v[214:215]
	v_cvt_pk_bf16_f32 v246, v52, v53
	v_cvt_pk_bf16_f32 v247, v54, v55
	global_store_dwordx4 v82, v[244:247], s[48:49] offset:0
	v_pk_mul_f32 v[56:57], v[56:57], v[238:239] op_sel_hi:[1,0]
	v_pk_mul_f32 v[58:59], v[58:59], v[238:239] op_sel_hi:[1,0]
	v_pk_mul_f32 v[56:57], v[72:73], v[56:57]
	v_pk_mul_f32 v[58:59], v[74:75], v[58:59]
	v_pk_fma_f32 v[56:57], v[200:201], v[56:57], v[216:217]
	v_pk_fma_f32 v[58:59], v[202:203], v[58:59], v[218:219]
	v_cvt_pk_bf16_f32 v240, v56, v57
	v_cvt_pk_bf16_f32 v241, v58, v59
	v_pk_mul_f32 v[60:61], v[60:61], v[238:239] op_sel_hi:[1,0]
	v_pk_mul_f32 v[62:63], v[62:63], v[238:239] op_sel_hi:[1,0]
	v_pk_mul_f32 v[60:61], v[76:77], v[60:61]
	v_pk_mul_f32 v[62:63], v[78:79], v[62:63]
	v_pk_fma_f32 v[60:61], v[204:205], v[60:61], v[220:221]
	v_pk_fma_f32 v[62:63], v[206:207], v[62:63], v[222:223]
	v_cvt_pk_bf16_f32 v242, v60, v61
	v_cvt_pk_bf16_f32 v243, v62, v63
	global_store_dwordx4 v82, v[240:243], s[48:49] offset:1024
	s_add_u32 s34, s8, 0x54000
	s_addc_u32 s35, s9, 0
	s_add_u32 s36, s8, 0x5a000
	s_addc_u32 s37, s9, 0
	global_load_dwordx4 v[176:179], v80, s[34:35] offset:0
	global_load_dwordx4 v[180:183], v80, s[34:35] offset:16
	global_load_dwordx4 v[184:187], v80, s[34:35] offset:2048
	global_load_dwordx4 v[188:191], v80, s[34:35] offset:2064
	global_load_dwordx4 v[160:163], v81, s[34:35] offset:0
	global_load_dwordx4 v[164:167], v81, s[34:35] offset:16
	global_load_dwordx4 v[168:171], v81, s[34:35] offset:2048
	global_load_dwordx4 v[172:175], v81, s[34:35] offset:2064
	global_load_dwordx4 v[208:211], v80, s[36:37] offset:0
	global_load_dwordx4 v[212:215], v80, s[36:37] offset:16
	global_load_dwordx4 v[216:219], v80, s[36:37] offset:2048
	global_load_dwordx4 v[220:223], v80, s[36:37] offset:2064
	global_load_dwordx4 v[192:195], v81, s[36:37] offset:0
	global_load_dwordx4 v[196:199], v81, s[36:37] offset:16
	global_load_dwordx4 v[200:203], v81, s[36:37] offset:2048
	global_load_dwordx4 v[204:207], v81, s[36:37] offset:2064
	s_waitcnt vmcnt(24)
	v_pk_mul_f32 v[240:241], v[96:97], v[96:97]
	v_pk_mul_f32 v[242:243], v[112:113], v[112:113]
	v_pk_mul_f32 v[244:245], v[128:129], v[128:129]
	v_pk_mul_f32 v[246:247], v[144:145], v[144:145]
	v_pk_fma_f32 v[240:241], v[98:99], v[98:99], v[240:241]
	v_pk_fma_f32 v[242:243], v[114:115], v[114:115], v[242:243]
	v_pk_fma_f32 v[244:245], v[130:131], v[130:131], v[244:245]
	v_pk_fma_f32 v[246:247], v[146:147], v[146:147], v[246:247]
	v_pk_fma_f32 v[240:241], v[100:101], v[100:101], v[240:241]
	v_pk_fma_f32 v[242:243], v[116:117], v[116:117], v[242:243]
	v_pk_fma_f32 v[244:245], v[132:133], v[132:133], v[244:245]
	v_pk_fma_f32 v[246:247], v[148:149], v[148:149], v[246:247]
	v_pk_fma_f32 v[240:241], v[102:103], v[102:103], v[240:241]
	v_pk_fma_f32 v[242:243], v[118:119], v[118:119], v[242:243]
	v_pk_fma_f32 v[244:245], v[134:135], v[134:135], v[244:245]
	v_pk_fma_f32 v[246:247], v[150:151], v[150:151], v[246:247]
	v_pk_fma_f32 v[240:241], v[104:105], v[104:105], v[240:241]
	v_pk_fma_f32 v[242:243], v[120:121], v[120:121], v[242:243]
	v_pk_fma_f32 v[244:245], v[136:137], v[136:137], v[244:245]
	v_pk_fma_f32 v[246:247], v[152:153], v[152:153], v[246:247]
	v_pk_fma_f32 v[240:241], v[106:107], v[106:107], v[240:241]
	v_pk_fma_f32 v[242:243], v[122:123], v[122:123], v[242:243]
	v_pk_fma_f32 v[244:245], v[138:139], v[138:139], v[244:245]
	v_pk_fma_f32 v[246:247], v[154:155], v[154:155], v[246:247]
	v_pk_fma_f32 v[240:241], v[108:109], v[108:109], v[240:241]
	v_pk_fma_f32 v[242:243], v[124:125], v[124:125], v[242:243]
	v_pk_fma_f32 v[244:245], v[140:141], v[140:141], v[244:245]
	v_pk_fma_f32 v[246:247], v[156:157], v[156:157], v[246:247]
	v_pk_fma_f32 v[240:241], v[110:111], v[110:111], v[240:241]
	v_pk_fma_f32 v[242:243], v[126:127], v[126:127], v[242:243]
	v_pk_fma_f32 v[244:245], v[142:143], v[142:143], v[244:245]
	v_pk_fma_f32 v[246:247], v[158:159], v[158:159], v[246:247]
	v_add_f32_e32 v224, v240, v241
	v_add_f32_e32 v225, v242, v243
	v_add_f32_e32 v226, v244, v245
	v_add_f32_e32 v227, v246, v247
	ds_bpermute_b32 v228, v83, v224
	ds_bpermute_b32 v229, v83, v225
	ds_bpermute_b32 v230, v83, v226
	ds_bpermute_b32 v231, v83, v227
	s_waitcnt lgkmcnt(0)
	v_add_f32_e32 v224, v224, v228
	v_add_f32_e32 v225, v225, v229
	v_add_f32_e32 v226, v226, v230
	v_add_f32_e32 v227, v227, v231
	ds_bpermute_b32 v228, v84, v224
	ds_bpermute_b32 v229, v84, v225
	ds_bpermute_b32 v230, v84, v226
	ds_bpermute_b32 v231, v84, v227
	s_waitcnt lgkmcnt(0)
; template <bool BF> __device__ __forceinline__ void prep_rows(const float* xp, const float* xs, const bf16* hb, const float* g, const float* MOD, int shoff, int scoff, bf16* U, int gw, int NGW, int lane) {
;     ...
; #pragma unroll
;         for (int o = 1; o < 64; o <<= 1) {
; #pragma unroll
;             for (int r = 0; r < R; ++r) s[r] += __shfl_xor(s[r], o); }
; #pragma unroll
;         for (int r = 0; r < R; ++r) { const int m = mb + r * NGW; if (m < MT) {
;             const float rstd = 1.0f / sqrtf(s[r] * (1.0f / DM) + RMS_EPS);
	v_add_f32_e32 v224, v224, v228
	v_add_f32_e32 v225, v225, v229
	v_add_f32_e32 v226, v226, v230
	v_add_f32_e32 v227, v227, v231
	ds_bpermute_b32 v228, v85, v224
	ds_bpermute_b32 v229, v85, v225
	ds_bpermute_b32 v230, v85, v226
	ds_bpermute_b32 v231, v85, v227
	s_waitcnt lgkmcnt(0)
	v_add_f32_e32 v224, v224, v228
	v_add_f32_e32 v225, v225, v229
	v_add_f32_e32 v226, v226, v230
	v_add_f32_e32 v227, v227, v231
	ds_bpermute_b32 v228, v86, v224
	ds_bpermute_b32 v229, v86, v225
	ds_bpermute_b32 v230, v86, v226
	ds_bpermute_b32 v231, v86, v227
	s_waitcnt lgkmcnt(0)
	v_add_f32_e32 v224, v224, v228
	v_add_f32_e32 v225, v225, v229
	v_add_f32_e32 v226, v226, v230
	v_add_f32_e32 v227, v227, v231
	ds_bpermute_b32 v228, v87, v224
	ds_bpermute_b32 v229, v87, v225
	ds_bpermute_b32 v230, v87, v226
	ds_bpermute_b32 v231, v87, v227
	s_waitcnt lgkmcnt(0)
	v_add_f32_e32 v224, v224, v228
	v_add_f32_e32 v225, v225, v229
	v_add_f32_e32 v226, v226, v230
	v_add_f32_e32 v227, v227, v231
	ds_bpermute_b32 v228, v88, v224
	ds_bpermute_b32 v229, v88, v225
	ds_bpermute_b32 v230, v88, v226
	ds_bpermute_b32 v231, v88, v227
	s_waitcnt lgkmcnt(0)
	v_add_f32_e32 v224, v224, v228
	v_add_f32_e32 v225, v225, v229
	v_add_f32_e32 v226, v226, v230
	v_add_f32_e32 v227, v227, v231
	v_fmamk_f32 v240, v224, 0x3a800000, v89
	v_mul_f32_e32 v241, 0x4f800000, v240
	v_cmp_gt_f32_e32 vcc, s54, v240
	s_nop 1
	v_cndmask_b32_e32 v247, v240, v241, vcc
	v_sqrt_f32_e32 v242, v247
	s_nop 1
	v_add_u32_e32 v243, -1, v242
	v_add_u32_e32 v244, 1, v242
	v_fma_f32 v245, -v243, v242, v247
	v_fma_f32 v246, -v244, v242, v247
	v_cmp_ge_f32_e64 s[52:53], 0, v245
	s_nop 1
	v_cndmask_b32_e64 v242, v242, v243, s[52:53]
	v_cmp_lt_f32_e64 s[52:53], 0, v246
	s_nop 1
	v_cndmask_b32_e64 v242, v242, v244, s[52:53]
	v_mul_f32_e32 v243, 0x37800000, v242
	v_cndmask_b32_e32 v242, v242, v243, vcc
	v_cmp_class_f32_e32 vcc, v247, v90
	s_nop 1
	v_cndmask_b32_e32 v247, v242, v247, vcc
	v_div_scale_f32 v248, s[52:53], v247, v247, 1.0
	v_rcp_f32_e32 v249, v248
	v_div_scale_f32 v228, vcc, 1.0, v247, 1.0
	s_nop 0
	v_fma_f32 v229, -v248, v249, 1.0
	v_fmac_f32_e32 v249, v229, v249
	v_mul_f32_e32 v230, v228, v249
	v_fma_f32 v229, -v248, v230, v228
	v_fmac_f32_e32 v230, v229, v249
	v_fma_f32 v248, -v248, v230, v228
	v_div_fmas_f32 v248, v248, v249, v230
	v_div_fixup_f32 v232, v248, v247, 1.0
	v_fmamk_f32 v240, v225, 0x3a800000, v89
	v_mul_f32_e32 v241, 0x4f800000, v240
	v_cmp_gt_f32_e32 vcc, s54, v240
	s_nop 1
	v_cndmask_b32_e32 v247, v240, v241, vcc
	v_sqrt_f32_e32 v242, v247
	s_nop 1
	v_add_u32_e32 v243, -1, v242
	v_add_u32_e32 v244, 1, v242
	v_fma_f32 v245, -v243, v242, v247
	v_fma_f32 v246, -v244, v242, v247
	v_cmp_ge_f32_e64 s[52:53], 0, v245
	s_nop 1
	v_cndmask_b32_e64 v242, v242, v243, s[52:53]
	v_cmp_lt_f32_e64 s[52:53], 0, v246
	s_nop 1
	v_cndmask_b32_e64 v242, v242, v244, s[52:53]
	v_mul_f32_e32 v243, 0x37800000, v242
	v_cndmask_b32_e32 v242, v242, v243, vcc
	v_cmp_class_f32_e32 vcc, v247, v90
	s_nop 1
	v_cndmask_b32_e32 v247, v242, v247, vcc
	v_div_scale_f32 v248, s[52:53], v247, v247, 1.0
	v_rcp_f32_e32 v249, v248
	v_div_scale_f32 v228, vcc, 1.0, v247, 1.0
	s_nop 0
	v_fma_f32 v229, -v248, v249, 1.0
	v_fmac_f32_e32 v249, v229, v249
	v_mul_f32_e32 v230, v228, v249
	v_fma_f32 v229, -v248, v230, v228
	v_fmac_f32_e32 v230, v229, v249
	v_fma_f32 v248, -v248, v230, v228
	v_div_fmas_f32 v248, v248, v249, v230
	v_div_fixup_f32 v234, v248, v247, 1.0
	v_fmamk_f32 v240, v226, 0x3a800000, v89
	v_mul_f32_e32 v241, 0x4f800000, v240
	v_cmp_gt_f32_e32 vcc, s54, v240
	s_nop 1
	v_cndmask_b32_e32 v247, v240, v241, vcc
	v_sqrt_f32_e32 v242, v247
	s_nop 1
	v_add_u32_e32 v243, -1, v242
	v_add_u32_e32 v244, 1, v242
	v_fma_f32 v245, -v243, v242, v247
	v_fma_f32 v246, -v244, v242, v247
	v_cmp_ge_f32_e64 s[52:53], 0, v245
	s_nop 1
	v_cndmask_b32_e64 v242, v242, v243, s[52:53]
	v_cmp_lt_f32_e64 s[52:53], 0, v246
	s_nop 1
	v_cndmask_b32_e64 v242, v242, v244, s[52:53]
	v_mul_f32_e32 v243, 0x37800000, v242
	v_cndmask_b32_e32 v242, v242, v243, vcc
	v_cmp_class_f32_e32 vcc, v247, v90
	s_nop 1
	v_cndmask_b32_e32 v247, v242, v247, vcc
	v_div_scale_f32 v248, s[52:53], v247, v247, 1.0
	v_rcp_f32_e32 v249, v248
	v_div_scale_f32 v228, vcc, 1.0, v247, 1.0
	s_nop 0
	v_fma_f32 v229, -v248, v249, 1.0
	v_fmac_f32_e32 v249, v229, v249
	v_mul_f32_e32 v230, v228, v249
	v_fma_f32 v229, -v248, v230, v228
	v_fmac_f32_e32 v230, v229, v249
	v_fma_f32 v248, -v248, v230, v228
	v_div_fmas_f32 v248, v248, v249, v230
	v_div_fixup_f32 v236, v248, v247, 1.0
	v_fmamk_f32 v240, v227, 0x3a800000, v89
	v_mul_f32_e32 v241, 0x4f800000, v240
	v_cmp_gt_f32_e32 vcc, s54, v240
	s_nop 1
	v_cndmask_b32_e32 v247, v240, v241, vcc
	v_sqrt_f32_e32 v242, v247
	s_nop 1
	v_add_u32_e32 v243, -1, v242
	v_add_u32_e32 v244, 1, v242
	v_fma_f32 v245, -v243, v242, v247
	v_fma_f32 v246, -v244, v242, v247
	v_cmp_ge_f32_e64 s[52:53], 0, v245
	s_nop 1
	v_cndmask_b32_e64 v242, v242, v243, s[52:53]
	v_cmp_lt_f32_e64 s[52:53], 0, v246
	s_nop 1
	v_cndmask_b32_e64 v242, v242, v244, s[52:53]
	v_mul_f32_e32 v243, 0x37800000, v242
	v_cndmask_b32_e32 v242, v242, v243, vcc
	v_cmp_class_f32_e32 vcc, v247, v90
	s_nop 1
	v_cndmask_b32_e32 v247, v242, v247, vcc
	v_div_scale_f32 v248, s[52:53], v247, v247, 1.0
	v_rcp_f32_e32 v249, v248
	v_div_scale_f32 v228, vcc, 1.0, v247, 1.0
	s_nop 0
	v_fma_f32 v229, -v248, v249, 1.0
	v_fmac_f32_e32 v249, v229, v249
	v_mul_f32_e32 v230, v228, v249
	v_fma_f32 v229, -v248, v230, v228
	v_fmac_f32_e32 v230, v229, v249
	v_fma_f32 v248, -v248, v230, v228
	v_div_fmas_f32 v248, v248, v249, v230
	v_div_fixup_f32 v238, v248, v247, 1.0
	s_waitcnt vmcnt(0)
; __device__ __forceinline__ unsigned pk2(float lo, float hi) { return pg8::cvt_pk_bf16(lo, hi); }
; template <bool BF> __device__ __forceinline__ void prep_rows(const float* xp, const float* xs, const bf16* hb, const float* g, const float* MOD, int shoff, int scoff, bf16* U, int gw, int NGW, int lane) {
;     ...
;         for (int r = 0; r < R; ++r) { const int m = mb + r * NGW; if (m < MT) {
;             const float rstd = 1.0f / sqrtf(s[r] * (1.0f / DM) + RMS_EPS);
;             const float* mr = MOD + (size_t)(m < MP ? (m >> 13) : 8 + ((m - MP) >> 12)) * 6144;
; #pragma unroll
;             for (int j = 0; j < 4; ++j) { const int c = 4 * lane + 256 * j;
;                 const f32x4 gg = *(const f32x4*)(g + c), sc = *(const f32x4*)(mr + scoff + c), sh = *(const f32x4*)(mr + shoff + c);
;                 const f32x4 o = v[r][j] * rstd * gg * (sc + 1.0f) + sh; v2u w; w.x = pk2(o.x, o.y); w.y = pk2(o.z, o.w); *(v2u*)(U + (size_t)m * DM + c) = w; } } }
	v_pk_add_f32 v[160:161], v[160:161], 1.0 op_sel_hi:[1,0]
	v_pk_add_f32 v[162:163], v[162:163], 1.0 op_sel_hi:[1,0]
	v_pk_add_f32 v[164:165], v[164:165], 1.0 op_sel_hi:[1,0]
	v_pk_add_f32 v[166:167], v[166:167], 1.0 op_sel_hi:[1,0]
	v_pk_add_f32 v[168:169], v[168:169], 1.0 op_sel_hi:[1,0]
	v_pk_add_f32 v[170:171], v[170:171], 1.0 op_sel_hi:[1,0]
	v_pk_add_f32 v[172:173], v[172:173], 1.0 op_sel_hi:[1,0]
	v_pk_add_f32 v[174:175], v[174:175], 1.0 op_sel_hi:[1,0]
	v_pk_add_f32 v[192:193], v[192:193], 1.0 op_sel_hi:[1,0]
	v_pk_add_f32 v[194:195], v[194:195], 1.0 op_sel_hi:[1,0]
	v_pk_add_f32 v[196:197], v[196:197], 1.0 op_sel_hi:[1,0]
	v_pk_add_f32 v[198:199], v[198:199], 1.0 op_sel_hi:[1,0]
	v_pk_add_f32 v[200:201], v[200:201], 1.0 op_sel_hi:[1,0]
	v_pk_add_f32 v[202:203], v[202:203], 1.0 op_sel_hi:[1,0]
	v_pk_add_f32 v[204:205], v[204:205], 1.0 op_sel_hi:[1,0]
	v_pk_add_f32 v[206:207], v[206:207], 1.0 op_sel_hi:[1,0]
	s_add_u32 s38, s20, 0xb000000
	s_addc_u32 s39, s21, 0
	s_add_u32 s40, s20, 0xb400000
	s_addc_u32 s41, s21, 0
	s_add_u32 s46, s20, 0xb800000
	s_addc_u32 s47, s21, 0
	s_add_u32 s48, s20, 0xbc00000
	s_addc_u32 s49, s21, 0
	v_pk_mul_f32 v[96:97], v[96:97], v[232:233] op_sel_hi:[1,0]
	v_pk_mul_f32 v[98:99], v[98:99], v[232:233] op_sel_hi:[1,0]
	v_pk_mul_f32 v[96:97], v[64:65], v[96:97]
	v_pk_mul_f32 v[98:99], v[66:67], v[98:99]
	v_pk_fma_f32 v[96:97], v[160:161], v[96:97], v[176:177]
	v_pk_fma_f32 v[98:99], v[162:163], v[98:99], v[178:179]
	v_cvt_pk_bf16_f32 v244, v96, v97
	v_cvt_pk_bf16_f32 v245, v98, v99
	v_pk_mul_f32 v[100:101], v[100:101], v[232:233] op_sel_hi:[1,0]
	v_pk_mul_f32 v[102:103], v[102:103], v[232:233] op_sel_hi:[1,0]
	v_pk_mul_f32 v[100:101], v[68:69], v[100:101]
	v_pk_mul_f32 v[102:103], v[70:71], v[102:103]
	v_pk_fma_f32 v[100:101], v[164:165], v[100:101], v[180:181]
	v_pk_fma_f32 v[102:103], v[166:167], v[102:103], v[182:183]
	v_cvt_pk_bf16_f32 v246, v100, v101
	v_cvt_pk_bf16_f32 v247, v102, v103
	global_store_dwordx4 v82, v[244:247], s[38:39] offset:0
	v_pk_mul_f32 v[104:105], v[104:105], v[232:233] op_sel_hi:[1,0]
	v_pk_mul_f32 v[106:107], v[106:107], v[232:233] op_sel_hi:[1,0]
	v_pk_mul_f32 v[104:105], v[72:73], v[104:105]
	v_pk_mul_f32 v[106:107], v[74:75], v[106:107]
	v_pk_fma_f32 v[104:105], v[168:169], v[104:105], v[184:185]
	v_pk_fma_f32 v[106:107], v[170:171], v[106:107], v[186:187]
	v_cvt_pk_bf16_f32 v240, v104, v105
	v_cvt_pk_bf16_f32 v241, v106, v107
	v_pk_mul_f32 v[108:109], v[108:109], v[232:233] op_sel_hi:[1,0]
	v_pk_mul_f32 v[110:111], v[110:111], v[232:233] op_sel_hi:[1,0]
	v_pk_mul_f32 v[108:109], v[76:77], v[108:109]
	v_pk_mul_f32 v[110:111], v[78:79], v[110:111]
	v_pk_fma_f32 v[108:109], v[172:173], v[108:109], v[188:189]
	v_pk_fma_f32 v[110:111], v[174:175], v[110:111], v[190:191]
	v_cvt_pk_bf16_f32 v242, v108, v109
	v_cvt_pk_bf16_f32 v243, v110, v111
	global_store_dwordx4 v82, v[240:243], s[38:39] offset:1024
	v_pk_mul_f32 v[112:113], v[112:113], v[234:235] op_sel_hi:[1,0]
	v_pk_mul_f32 v[114:115], v[114:115], v[234:235] op_sel_hi:[1,0]
	v_pk_mul_f32 v[112:113], v[64:65], v[112:113]
	v_pk_mul_f32 v[114:115], v[66:67], v[114:115]
	v_pk_fma_f32 v[112:113], v[160:161], v[112:113], v[176:177]
	v_pk_fma_f32 v[114:115], v[162:163], v[114:115], v[178:179]
	v_cvt_pk_bf16_f32 v244, v112, v113
	v_cvt_pk_bf16_f32 v245, v114, v115
	v_pk_mul_f32 v[116:117], v[116:117], v[234:235] op_sel_hi:[1,0]
	v_pk_mul_f32 v[118:119], v[118:119], v[234:235] op_sel_hi:[1,0]
	v_pk_mul_f32 v[116:117], v[68:69], v[116:117]
	v_pk_mul_f32 v[118:119], v[70:71], v[118:119]
	v_pk_fma_f32 v[116:117], v[164:165], v[116:117], v[180:181]
	v_pk_fma_f32 v[118:119], v[166:167], v[118:119], v[182:183]
	v_cvt_pk_bf16_f32 v246, v116, v117
	v_cvt_pk_bf16_f32 v247, v118, v119
	global_store_dwordx4 v82, v[244:247], s[40:41] offset:0
	v_pk_mul_f32 v[120:121], v[120:121], v[234:235] op_sel_hi:[1,0]
	v_pk_mul_f32 v[122:123], v[122:123], v[234:235] op_sel_hi:[1,0]
	v_pk_mul_f32 v[120:121], v[72:73], v[120:121]
	v_pk_mul_f32 v[122:123], v[74:75], v[122:123]
	v_pk_fma_f32 v[120:121], v[168:169], v[120:121], v[184:185]
	v_pk_fma_f32 v[122:123], v[170:171], v[122:123], v[186:187]
; __device__ __forceinline__ unsigned pk2(float lo, float hi) { return pg8::cvt_pk_bf16(lo, hi); }
; template <bool BF> __device__ __forceinline__ void prep_rows(const float* xp, const float* xs, const bf16* hb, const float* g, const float* MOD, int shoff, int scoff, bf16* U, int gw, int NGW, int lane) {
;     ...
;         for (int r = 0; r < R; ++r) { const int m = mb + r * NGW; if (m < MT) {
;             const float rstd = 1.0f / sqrtf(s[r] * (1.0f / DM) + RMS_EPS);
;             const float* mr = MOD + (size_t)(m < MP ? (m >> 13) : 8 + ((m - MP) >> 12)) * 6144;
; #pragma unroll
;             for (int j = 0; j < 4; ++j) { const int c = 4 * lane + 256 * j;
;                 const f32x4 gg = *(const f32x4*)(g + c), sc = *(const f32x4*)(mr + scoff + c), sh = *(const f32x4*)(mr + shoff + c);
;                 const f32x4 o = v[r][j] * rstd * gg * (sc + 1.0f) + sh; v2u w; w.x = pk2(o.x, o.y); w.y = pk2(o.z, o.w); *(v2u*)(U + (size_t)m * DM + c) = w; } } }
	v_cvt_pk_bf16_f32 v240, v120, v121
	v_cvt_pk_bf16_f32 v241, v122, v123
	v_pk_mul_f32 v[124:125], v[124:125], v[234:235] op_sel_hi:[1,0]
	v_pk_mul_f32 v[126:127], v[126:127], v[234:235] op_sel_hi:[1,0]
	v_pk_mul_f32 v[124:125], v[76:77], v[124:125]
	v_pk_mul_f32 v[126:127], v[78:79], v[126:127]
	v_pk_fma_f32 v[124:125], v[172:173], v[124:125], v[188:189]
	v_pk_fma_f32 v[126:127], v[174:175], v[126:127], v[190:191]
	v_cvt_pk_bf16_f32 v242, v124, v125
	v_cvt_pk_bf16_f32 v243, v126, v127
	global_store_dwordx4 v82, v[240:243], s[40:41] offset:1024
	v_pk_mul_f32 v[128:129], v[128:129], v[236:237] op_sel_hi:[1,0]
	v_pk_mul_f32 v[130:131], v[130:131], v[236:237] op_sel_hi:[1,0]
	v_pk_mul_f32 v[128:129], v[64:65], v[128:129]
	v_pk_mul_f32 v[130:131], v[66:67], v[130:131]
	v_pk_fma_f32 v[128:129], v[192:193], v[128:129], v[208:209]
	v_pk_fma_f32 v[130:131], v[194:195], v[130:131], v[210:211]
	v_cvt_pk_bf16_f32 v244, v128, v129
	v_cvt_pk_bf16_f32 v245, v130, v131
	v_pk_mul_f32 v[132:133], v[132:133], v[236:237] op_sel_hi:[1,0]
	v_pk_mul_f32 v[134:135], v[134:135], v[236:237] op_sel_hi:[1,0]
	v_pk_mul_f32 v[132:133], v[68:69], v[132:133]
	v_pk_mul_f32 v[134:135], v[70:71], v[134:135]
	v_pk_fma_f32 v[132:133], v[196:197], v[132:133], v[212:213]
	v_pk_fma_f32 v[134:135], v[198:199], v[134:135], v[214:215]
	v_cvt_pk_bf16_f32 v246, v132, v133
	v_cvt_pk_bf16_f32 v247, v134, v135
	global_store_dwordx4 v82, v[244:247], s[46:47] offset:0
	v_pk_mul_f32 v[136:137], v[136:137], v[236:237] op_sel_hi:[1,0]
	v_pk_mul_f32 v[138:139], v[138:139], v[236:237] op_sel_hi:[1,0]
	v_pk_mul_f32 v[136:137], v[72:73], v[136:137]
	v_pk_mul_f32 v[138:139], v[74:75], v[138:139]
	v_pk_fma_f32 v[136:137], v[200:201], v[136:137], v[216:217]
	v_pk_fma_f32 v[138:139], v[202:203], v[138:139], v[218:219]
	v_cvt_pk_bf16_f32 v240, v136, v137
	v_cvt_pk_bf16_f32 v241, v138, v139
	v_pk_mul_f32 v[140:141], v[140:141], v[236:237] op_sel_hi:[1,0]
	v_pk_mul_f32 v[142:143], v[142:143], v[236:237] op_sel_hi:[1,0]
	v_pk_mul_f32 v[140:141], v[76:77], v[140:141]
	v_pk_mul_f32 v[142:143], v[78:79], v[142:143]
	v_pk_fma_f32 v[140:141], v[204:205], v[140:141], v[220:221]
	v_pk_fma_f32 v[142:143], v[206:207], v[142:143], v[222:223]
	v_cvt_pk_bf16_f32 v242, v140, v141
	v_cvt_pk_bf16_f32 v243, v142, v143
	global_store_dwordx4 v82, v[240:243], s[46:47] offset:1024
	v_pk_mul_f32 v[144:145], v[144:145], v[238:239] op_sel_hi:[1,0]
	v_pk_mul_f32 v[146:147], v[146:147], v[238:239] op_sel_hi:[1,0]
	v_pk_mul_f32 v[144:145], v[64:65], v[144:145]
	v_pk_mul_f32 v[146:147], v[66:67], v[146:147]
	v_pk_fma_f32 v[144:145], v[192:193], v[144:145], v[208:209]
	v_pk_fma_f32 v[146:147], v[194:195], v[146:147], v[210:211]
	v_cvt_pk_bf16_f32 v244, v144, v145
	v_cvt_pk_bf16_f32 v245, v146, v147
	v_pk_mul_f32 v[148:149], v[148:149], v[238:239] op_sel_hi:[1,0]
	v_pk_mul_f32 v[150:151], v[150:151], v[238:239] op_sel_hi:[1,0]
	v_pk_mul_f32 v[148:149], v[68:69], v[148:149]
	v_pk_mul_f32 v[150:151], v[70:71], v[150:151]
	v_pk_fma_f32 v[148:149], v[196:197], v[148:149], v[212:213]
	v_pk_fma_f32 v[150:151], v[198:199], v[150:151], v[214:215]
	v_cvt_pk_bf16_f32 v246, v148, v149
	v_cvt_pk_bf16_f32 v247, v150, v151
	global_store_dwordx4 v82, v[244:247], s[48:49] offset:0
	v_pk_mul_f32 v[152:153], v[152:153], v[238:239] op_sel_hi:[1,0]
	v_pk_mul_f32 v[154:155], v[154:155], v[238:239] op_sel_hi:[1,0]
	v_pk_mul_f32 v[152:153], v[72:73], v[152:153]
	v_pk_mul_f32 v[154:155], v[74:75], v[154:155]
	v_pk_fma_f32 v[152:153], v[200:201], v[152:153], v[216:217]
	v_pk_fma_f32 v[154:155], v[202:203], v[154:155], v[218:219]
	v_cvt_pk_bf16_f32 v240, v152, v153
	v_cvt_pk_bf16_f32 v241, v154, v155
	v_pk_mul_f32 v[156:157], v[156:157], v[238:239] op_sel_hi:[1,0]
	v_pk_mul_f32 v[158:159], v[158:159], v[238:239] op_sel_hi:[1,0]
	v_pk_mul_f32 v[156:157], v[76:77], v[156:157]
	v_pk_mul_f32 v[158:159], v[78:79], v[158:159]
	v_pk_fma_f32 v[156:157], v[204:205], v[156:157], v[220:221]
	v_pk_fma_f32 v[158:159], v[206:207], v[158:159], v[222:223]
	v_cvt_pk_bf16_f32 v242, v156, v157
	v_cvt_pk_bf16_f32 v243, v158, v159
	global_store_dwordx4 v82, v[240:243], s[48:49] offset:1024

; __device__ __forceinline__ float bf_lo(unsigned w) { return __uint_as_float(w << 16); }
; __device__ __forceinline__ float bf_hi(unsigned w) { return __uint_as_float(w & 0xffff0000u); }
; #define PH_IDS() const int tid = lnd((int)threadIdx.x), lane = tid & 63, wave = __builtin_amdgcn_readfirstlane(tid >> 6), gw = bid * 8 + wave; (void)lane; (void)gw
; #define REPS(k) for (int rep_ = 0; rep_ < (((REP_MASK >> (k)) & 1) ? 2 : 1); ++rep_)
; template <bool BF> __device__ __forceinline__ void prep_rows(const float* xp, const float* xs, const bf16* hb, const float* g, const float* MOD, int shoff, int scoff, bf16* U, int gw, int NGW, int lane) {
;     constexpr int R = 4;
;     for (int mb = gw; mb < MT; mb += R * NGW) {
;         f32x4 v[R][4]; float s[R];
; #pragma unroll
;         for (int r = 0; r < R; ++r) { const int m = mb + r * NGW; const int mc = m < MT ? m : mb;
; #pragma unroll
;             for (int j = 0; j < 4; ++j) {
;                 if (BF) { const v2u a0 = *(const v2u*)(hb + (size_t)mc * DM + 4 * lane + 256 * j);
;                     v[r][j].x = pg8::bf_lo(a0.x); v[r][j].y = pg8::bf_hi(a0.x); v[r][j].z = pg8::bf_lo(a0.y); v[r][j].w = pg8::bf_hi(a0.y); }
;                 else { const float* xr = mc < MP ? xp + (size_t)mc * DM : xs + (size_t)(mc - MP) * DM; v[r][j] = *(const f32x4*)(xr + 4 * lane + 256 * j); } } }
; template <int PHM> __global__ void __launch_bounds__(512, 2) mk_fwd(Args karg) {
;     ...
;     if (IN(11)) REPS(11) { PH_ARGS(); PH_IDS(); prep_rows<true>(nullptr, nullptr, (const bf16*)(ws + WS_H16), a.in[I_N2G], MOD, 3072, 4096, (bf16*)(ws + WS_U2), gw, NGW, lane); }
.LBB0_1168:
	s_cmp_lt_i32 s78, 12
	s_cselect_b64 s[0:1], -1, 0
	s_and_b64 s[0:1], s[0:1], s[4:5]
	s_andn2_b64 vcc, exec, s[0:1]
	s_cbranch_vccnz .LBB0_1178
	s_mov_b64 s[2:3], s[72:73]
	s_waitcnt vmcnt(0)
	v_mov_b32_e32 v8, v254
	s_lshl_b32 s6, s96, 3
	v_readfirstlane_b32 s4, v8
	s_ashr_i32 s7, s4, 6
	s_add_i32 s26, s7, s6
	s_cmp_gt_i32 s26, 0x17fff
	s_cbranch_scc1 .LBB0_1178
	s_load_dwordx2 s[6:7], s[72:73], 0xc8
	s_load_dwordx2 s[8:9], s[72:73], 0xe8
	v_and_b32_e32 v82, 63, v254
	v_lshlrev_b32_e32 v80, 5, v82
	v_add_u32_e32 v81, 0x1000, v80
	v_xor_b32_e32 v83, 1, v82
	v_xor_b32_e32 v84, 2, v82
	v_xor_b32_e32 v85, 4, v82
	v_xor_b32_e32 v86, 8, v82
	v_xor_b32_e32 v87, 16, v82
	v_xor_b32_e32 v88, 32, v82
	v_lshlrev_b32_e32 v83, 2, v83
	v_lshlrev_b32_e32 v84, 2, v84
	v_lshlrev_b32_e32 v85, 2, v85
	v_lshlrev_b32_e32 v86, 2, v86
	v_lshlrev_b32_e32 v87, 2, v87
	v_lshlrev_b32_e32 v88, 2, v88
	v_lshlrev_b32_e32 v82, 4, v82
	v_mov_b32_e32 v89, 0x358637bd
	v_mov_b32_e32 v90, 0x260
	s_mov_b32 s54, 0xf800000
	v_readfirstlane_b32 s45, v254
	s_nop 3
	s_lshl_b32 s50, s96, 3
	s_lshr_b32 s45, s45, 6
	s_add_i32 s45, s45, s50
	s_waitcnt lgkmcnt(0)
	s_lshl_b32 s50, s45, 11
	s_add_u32 s16, s8, s50
	s_addc_u32 s17, s9, 0
	s_add_u32 s16, s16, 0xf000000
	s_addc_u32 s17, s17, 0
	s_add_u32 s20, s8, s50
	s_addc_u32 s21, s9, 0
	s_add_u32 s20, s20, 0x33000000
	s_addc_u32 s21, s21, 0
	global_load_dwordx4 v[64:67], v80, s[6:7] offset:0
	global_load_dwordx4 v[68:71], v80, s[6:7] offset:16
	global_load_dwordx4 v[72:75], v80, s[6:7] offset:2048
	global_load_dwordx4 v[76:79], v80, s[6:7] offset:2064
	s_mov_b64 s[24:25], s[16:17]
	s_add_u32 s26, s16, 0x400000
	s_addc_u32 s27, s17, 0
	s_add_u32 s28, s16, 0x800000
	s_addc_u32 s29, s17, 0
	s_add_u32 s30, s16, 0xc00000
	s_addc_u32 s31, s17, 0
	global_load_dwordx4 v[96:99], v82, s[24:25] offset:0
	global_load_dwordx4 v[100:103], v82, s[24:25] offset:1024
	global_load_dwordx4 v[104:107], v82, s[26:27] offset:0
	global_load_dwordx4 v[108:111], v82, s[26:27] offset:1024
	global_load_dwordx4 v[112:115], v82, s[28:29] offset:0
	global_load_dwordx4 v[116:119], v82, s[28:29] offset:1024
	global_load_dwordx4 v[120:123], v82, s[30:31] offset:0
	global_load_dwordx4 v[124:127], v82, s[30:31] offset:1024
	s_add_u32 s34, s8, 0x3000
	s_addc_u32 s35, s9, 0
	s_add_u32 s36, s8, 0x3000
	s_addc_u32 s37, s9, 0
	global_load_dwordx4 v[176:179], v80, s[34:35] offset:0
	global_load_dwordx4 v[180:183], v80, s[34:35] offset:16
	global_load_dwordx4 v[184:187], v80, s[34:35] offset:2048
	global_load_dwordx4 v[188:191], v80, s[34:35] offset:2064
	global_load_dwordx4 v[160:163], v81, s[34:35] offset:0
	global_load_dwordx4 v[164:167], v81, s[34:35] offset:16
	global_load_dwordx4 v[168:171], v81, s[34:35] offset:2048
	global_load_dwordx4 v[172:175], v81, s[34:35] offset:2064
	global_load_dwordx4 v[208:211], v80, s[36:37] offset:0
	global_load_dwordx4 v[212:215], v80, s[36:37] offset:16
	global_load_dwordx4 v[216:219], v80, s[36:37] offset:2048
	global_load_dwordx4 v[220:223], v80, s[36:37] offset:2064
	global_load_dwordx4 v[192:195], v81, s[36:37] offset:0
	global_load_dwordx4 v[196:199], v81, s[36:37] offset:16
	global_load_dwordx4 v[200:203], v81, s[36:37] offset:2048
	global_load_dwordx4 v[204:207], v81, s[36:37] offset:2064
	s_add_u32 s24, s16, 0x1000000
	s_addc_u32 s25, s17, 0
	s_add_u32 s26, s16, 0x1400000
	s_addc_u32 s27, s17, 0
	s_add_u32 s28, s16, 0x1800000
	s_addc_u32 s29, s17, 0
	s_add_u32 s30, s16, 0x1c00000
	s_addc_u32 s31, s17, 0
	global_load_dwordx4 v[128:131], v82, s[24:25] offset:0
	global_load_dwordx4 v[132:135], v82, s[24:25] offset:1024
	global_load_dwordx4 v[136:139], v82, s[26:27] offset:0
	global_load_dwordx4 v[140:143], v82, s[26:27] offset:1024
	global_load_dwordx4 v[144:147], v82, s[28:29] offset:0
	global_load_dwordx4 v[148:151], v82, s[28:29] offset:1024
	global_load_dwordx4 v[152:155], v82, s[30:31] offset:0
	global_load_dwordx4 v[156:159], v82, s[30:31] offset:1024
	s_waitcnt vmcnt(24)
	v_lshlrev_b32_e32 v0, 16, v96
	v_and_b32_e32 v1, 0xffff0000, v96
	v_lshlrev_b32_e32 v2, 16, v97
	v_and_b32_e32 v3, 0xffff0000, v97
	v_lshlrev_b32_e32 v4, 16, v98
	v_and_b32_e32 v5, 0xffff0000, v98
	v_lshlrev_b32_e32 v6, 16, v99
	v_and_b32_e32 v7, 0xffff0000, v99
	v_lshlrev_b32_e32 v8, 16, v100
	v_and_b32_e32 v9, 0xffff0000, v100
	v_lshlrev_b32_e32 v10, 16, v101
	v_and_b32_e32 v11, 0xffff0000, v101
	v_lshlrev_b32_e32 v12, 16, v102
	v_and_b32_e32 v13, 0xffff0000, v102
	v_lshlrev_b32_e32 v14, 16, v103
	v_and_b32_e32 v15, 0xffff0000, v103
	v_lshlrev_b32_e32 v16, 16, v104
	v_and_b32_e32 v17, 0xffff0000, v104
	v_lshlrev_b32_e32 v18, 16, v105
	v_and_b32_e32 v19, 0xffff0000, v105
	v_lshlrev_b32_e32 v20, 16, v106
	v_and_b32_e32 v21, 0xffff0000, v106
	v_lshlrev_b32_e32 v22, 16, v107
	v_and_b32_e32 v23, 0xffff0000, v107
	v_lshlrev_b32_e32 v24, 16, v108
	v_and_b32_e32 v25, 0xffff0000, v108
	v_lshlrev_b32_e32 v26, 16, v109
	v_and_b32_e32 v27, 0xffff0000, v109
	v_lshlrev_b32_e32 v28, 16, v110
	v_and_b32_e32 v29, 0xffff0000, v110
	v_lshlrev_b32_e32 v30, 16, v111
	v_and_b32_e32 v31, 0xffff0000, v111
	v_lshlrev_b32_e32 v32, 16, v112
	v_and_b32_e32 v33, 0xffff0000, v112
	v_lshlrev_b32_e32 v34, 16, v113
	v_and_b32_e32 v35, 0xffff0000, v113
	v_lshlrev_b32_e32 v36, 16, v114
	v_and_b32_e32 v37, 0xffff0000, v114
	v_lshlrev_b32_e32 v38, 16, v115
	v_and_b32_e32 v39, 0xffff0000, v115
	v_lshlrev_b32_e32 v40, 16, v116
	v_and_b32_e32 v41, 0xffff0000, v116
	v_lshlrev_b32_e32 v42, 16, v117
	v_and_b32_e32 v43, 0xffff0000, v117
	v_lshlrev_b32_e32 v44, 16, v118
	v_and_b32_e32 v45, 0xffff0000, v118
	v_lshlrev_b32_e32 v46, 16, v119
	v_and_b32_e32 v47, 0xffff0000, v119
; __device__ __forceinline__ float bf_lo(unsigned w) { return __uint_as_float(w << 16); }
; __device__ __forceinline__ float bf_hi(unsigned w) { return __uint_as_float(w & 0xffff0000u); }
; template <bool BF> __device__ __forceinline__ void prep_rows(const float* xp, const float* xs, const bf16* hb, const float* g, const float* MOD, int shoff, int scoff, bf16* U, int gw, int NGW, int lane) {
;     ...
;                 if (BF) { const v2u a0 = *(const v2u*)(hb + (size_t)mc * DM + 4 * lane + 256 * j);
;                     v[r][j].x = pg8::bf_lo(a0.x); v[r][j].y = pg8::bf_hi(a0.x); v[r][j].z = pg8::bf_lo(a0.y); v[r][j].w = pg8::bf_hi(a0.y); }
;                 else { const float* xr = mc < MP ? xp + (size_t)mc * DM : xs + (size_t)(mc - MP) * DM; v[r][j] = *(const f32x4*)(xr + 4 * lane + 256 * j); } } }
; #pragma unroll
;         for (int r = 0; r < R; ++r) { float t = 0.f;
; #pragma unroll
;             for (int j = 0; j < 4; ++j) t += (v[r][j].x * v[r][j].x + v[r][j].y * v[r][j].y) + (v[r][j].z * v[r][j].z + v[r][j].w * v[r][j].w);
;             s[r] = t; }
; #pragma unroll
;         for (int o = 1; o < 64; o <<= 1) {
; #pragma unroll
;             for (int r = 0; r < R; ++r) s[r] += __shfl_xor(s[r], o); }
; #pragma unroll
;         for (int r = 0; r < R; ++r) { const int m = mb + r * NGW; if (m < MT) {
;             const float rstd = 1.0f / sqrtf(s[r] * (1.0f / DM) + RMS_EPS);
	v_lshlrev_b32_e32 v48, 16, v120
	v_and_b32_e32 v49, 0xffff0000, v120
	v_lshlrev_b32_e32 v50, 16, v121
	v_and_b32_e32 v51, 0xffff0000, v121
	v_lshlrev_b32_e32 v52, 16, v122
	v_and_b32_e32 v53, 0xffff0000, v122
	v_lshlrev_b32_e32 v54, 16, v123
	v_and_b32_e32 v55, 0xffff0000, v123
	v_lshlrev_b32_e32 v56, 16, v124
	v_and_b32_e32 v57, 0xffff0000, v124
	v_lshlrev_b32_e32 v58, 16, v125
	v_and_b32_e32 v59, 0xffff0000, v125
	v_lshlrev_b32_e32 v60, 16, v126
	v_and_b32_e32 v61, 0xffff0000, v126
	v_lshlrev_b32_e32 v62, 16, v127
	v_and_b32_e32 v63, 0xffff0000, v127
	v_pk_mul_f32 v[240:241], v[0:1], v[0:1]
	v_pk_mul_f32 v[242:243], v[16:17], v[16:17]
	v_pk_mul_f32 v[244:245], v[32:33], v[32:33]
	v_pk_mul_f32 v[246:247], v[48:49], v[48:49]
	v_pk_fma_f32 v[240:241], v[2:3], v[2:3], v[240:241]
	v_pk_fma_f32 v[242:243], v[18:19], v[18:19], v[242:243]
	v_pk_fma_f32 v[244:245], v[34:35], v[34:35], v[244:245]
	v_pk_fma_f32 v[246:247], v[50:51], v[50:51], v[246:247]
	v_pk_fma_f32 v[240:241], v[4:5], v[4:5], v[240:241]
	v_pk_fma_f32 v[242:243], v[20:21], v[20:21], v[242:243]
	v_pk_fma_f32 v[244:245], v[36:37], v[36:37], v[244:245]
	v_pk_fma_f32 v[246:247], v[52:53], v[52:53], v[246:247]
	v_pk_fma_f32 v[240:241], v[6:7], v[6:7], v[240:241]
	v_pk_fma_f32 v[242:243], v[22:23], v[22:23], v[242:243]
	v_pk_fma_f32 v[244:245], v[38:39], v[38:39], v[244:245]
	v_pk_fma_f32 v[246:247], v[54:55], v[54:55], v[246:247]
	v_pk_fma_f32 v[240:241], v[8:9], v[8:9], v[240:241]
	v_pk_fma_f32 v[242:243], v[24:25], v[24:25], v[242:243]
	v_pk_fma_f32 v[244:245], v[40:41], v[40:41], v[244:245]
	v_pk_fma_f32 v[246:247], v[56:57], v[56:57], v[246:247]
	v_pk_fma_f32 v[240:241], v[10:11], v[10:11], v[240:241]
	v_pk_fma_f32 v[242:243], v[26:27], v[26:27], v[242:243]
	v_pk_fma_f32 v[244:245], v[42:43], v[42:43], v[244:245]
	v_pk_fma_f32 v[246:247], v[58:59], v[58:59], v[246:247]
	v_pk_fma_f32 v[240:241], v[12:13], v[12:13], v[240:241]
	v_pk_fma_f32 v[242:243], v[28:29], v[28:29], v[242:243]
	v_pk_fma_f32 v[244:245], v[44:45], v[44:45], v[244:245]
	v_pk_fma_f32 v[246:247], v[60:61], v[60:61], v[246:247]
	v_pk_fma_f32 v[240:241], v[14:15], v[14:15], v[240:241]
	v_pk_fma_f32 v[242:243], v[30:31], v[30:31], v[242:243]
	v_pk_fma_f32 v[244:245], v[46:47], v[46:47], v[244:245]
	v_pk_fma_f32 v[246:247], v[62:63], v[62:63], v[246:247]
	v_add_f32_e32 v224, v240, v241
	v_add_f32_e32 v225, v242, v243
	v_add_f32_e32 v226, v244, v245
	v_add_f32_e32 v227, v246, v247
	ds_bpermute_b32 v228, v83, v224
	ds_bpermute_b32 v229, v83, v225
	ds_bpermute_b32 v230, v83, v226
	ds_bpermute_b32 v231, v83, v227
	s_waitcnt lgkmcnt(0)
	v_add_f32_e32 v224, v224, v228
	v_add_f32_e32 v225, v225, v229
	v_add_f32_e32 v226, v226, v230
	v_add_f32_e32 v227, v227, v231
	ds_bpermute_b32 v228, v84, v224
	ds_bpermute_b32 v229, v84, v225
	ds_bpermute_b32 v230, v84, v226
	ds_bpermute_b32 v231, v84, v227
	s_waitcnt lgkmcnt(0)
	v_add_f32_e32 v224, v224, v228
	v_add_f32_e32 v225, v225, v229
	v_add_f32_e32 v226, v226, v230
	v_add_f32_e32 v227, v227, v231
	ds_bpermute_b32 v228, v85, v224
	ds_bpermute_b32 v229, v85, v225
	ds_bpermute_b32 v230, v85, v226
	ds_bpermute_b32 v231, v85, v227
	s_waitcnt lgkmcnt(0)
	v_add_f32_e32 v224, v224, v228
	v_add_f32_e32 v225, v225, v229
	v_add_f32_e32 v226, v226, v230
	v_add_f32_e32 v227, v227, v231
	ds_bpermute_b32 v228, v86, v224
	ds_bpermute_b32 v229, v86, v225
	ds_bpermute_b32 v230, v86, v226
	ds_bpermute_b32 v231, v86, v227
	s_waitcnt lgkmcnt(0)
	v_add_f32_e32 v224, v224, v228
	v_add_f32_e32 v225, v225, v229
	v_add_f32_e32 v226, v226, v230
	v_add_f32_e32 v227, v227, v231
	ds_bpermute_b32 v228, v87, v224
	ds_bpermute_b32 v229, v87, v225
	ds_bpermute_b32 v230, v87, v226
	ds_bpermute_b32 v231, v87, v227
	s_waitcnt lgkmcnt(0)
	v_add_f32_e32 v224, v224, v228
	v_add_f32_e32 v225, v225, v229
	v_add_f32_e32 v226, v226, v230
	v_add_f32_e32 v227, v227, v231
	ds_bpermute_b32 v228, v88, v224
	ds_bpermute_b32 v229, v88, v225
	ds_bpermute_b32 v230, v88, v226
	ds_bpermute_b32 v231, v88, v227
	s_waitcnt lgkmcnt(0)
	v_add_f32_e32 v224, v224, v228
	v_add_f32_e32 v225, v225, v229
	v_add_f32_e32 v226, v226, v230
	v_add_f32_e32 v227, v227, v231
	v_fmamk_f32 v240, v224, 0x3a800000, v89
	v_mul_f32_e32 v241, 0x4f800000, v240
	v_cmp_gt_f32_e32 vcc, s54, v240
	s_nop 1
	v_cndmask_b32_e32 v247, v240, v241, vcc
	v_sqrt_f32_e32 v242, v247
	s_nop 1
	v_add_u32_e32 v243, -1, v242
	v_add_u32_e32 v244, 1, v242
	v_fma_f32 v245, -v243, v242, v247
	v_fma_f32 v246, -v244, v242, v247
	v_cmp_ge_f32_e64 s[52:53], 0, v245
	s_nop 1
	v_cndmask_b32_e64 v242, v242, v243, s[52:53]
	v_cmp_lt_f32_e64 s[52:53], 0, v246
	s_nop 1
	v_cndmask_b32_e64 v242, v242, v244, s[52:53]
	v_mul_f32_e32 v243, 0x37800000, v242
	v_cndmask_b32_e32 v242, v242, v243, vcc
	v_cmp_class_f32_e32 vcc, v247, v90
	s_nop 1
	v_cndmask_b32_e32 v247, v242, v247, vcc
	v_div_scale_f32 v248, s[52:53], v247, v247, 1.0
	v_rcp_f32_e32 v249, v248
	v_div_scale_f32 v228, vcc, 1.0, v247, 1.0
	s_nop 0
	v_fma_f32 v229, -v248, v249, 1.0
	v_fmac_f32_e32 v249, v229, v249
	v_mul_f32_e32 v230, v228, v249
	v_fma_f32 v229, -v248, v230, v228
	v_fmac_f32_e32 v230, v229, v249
	v_fma_f32 v248, -v248, v230, v228
	v_div_fmas_f32 v248, v248, v249, v230
	v_div_fixup_f32 v232, v248, v247, 1.0
	v_fmamk_f32 v240, v225, 0x3a800000, v89
	v_mul_f32_e32 v241, 0x4f800000, v240
	v_cmp_gt_f32_e32 vcc, s54, v240
	s_nop 1
	v_cndmask_b32_e32 v247, v240, v241, vcc
	v_sqrt_f32_e32 v242, v247
	s_nop 1
	v_add_u32_e32 v243, -1, v242
	v_add_u32_e32 v244, 1, v242
	v_fma_f32 v245, -v243, v242, v247
	v_fma_f32 v246, -v244, v242, v247
	v_cmp_ge_f32_e64 s[52:53], 0, v245
	s_nop 1
	v_cndmask_b32_e64 v242, v242, v243, s[52:53]
; __device__ __forceinline__ unsigned pk2(float lo, float hi) { return pg8::cvt_pk_bf16(lo, hi); }
; template <bool BF> __device__ __forceinline__ void prep_rows(const float* xp, const float* xs, const bf16* hb, const float* g, const float* MOD, int shoff, int scoff, bf16* U, int gw, int NGW, int lane) {
;     ...
;         for (int r = 0; r < R; ++r) { const int m = mb + r * NGW; if (m < MT) {
;             const float rstd = 1.0f / sqrtf(s[r] * (1.0f / DM) + RMS_EPS);
;             const float* mr = MOD + (size_t)(m < MP ? (m >> 13) : 8 + ((m - MP) >> 12)) * 6144;
; #pragma unroll
;             for (int j = 0; j < 4; ++j) { const int c = 4 * lane + 256 * j;
;                 const f32x4 gg = *(const f32x4*)(g + c), sc = *(const f32x4*)(mr + scoff + c), sh = *(const f32x4*)(mr + shoff + c);
;                 const f32x4 o = v[r][j] * rstd * gg * (sc + 1.0f) + sh; v2u w; w.x = pk2(o.x, o.y); w.y = pk2(o.z, o.w); *(v2u*)(U + (size_t)m * DM + c) = w; } } }
	v_cmp_lt_f32_e64 s[52:53], 0, v246
	s_nop 1
	v_cndmask_b32_e64 v242, v242, v244, s[52:53]
	v_mul_f32_e32 v243, 0x37800000, v242
	v_cndmask_b32_e32 v242, v242, v243, vcc
	v_cmp_class_f32_e32 vcc, v247, v90
	s_nop 1
	v_cndmask_b32_e32 v247, v242, v247, vcc
	v_div_scale_f32 v248, s[52:53], v247, v247, 1.0
	v_rcp_f32_e32 v249, v248
	v_div_scale_f32 v228, vcc, 1.0, v247, 1.0
	s_nop 0
	v_fma_f32 v229, -v248, v249, 1.0
	v_fmac_f32_e32 v249, v229, v249
	v_mul_f32_e32 v230, v228, v249
	v_fma_f32 v229, -v248, v230, v228
	v_fmac_f32_e32 v230, v229, v249
	v_fma_f32 v248, -v248, v230, v228
	v_div_fmas_f32 v248, v248, v249, v230
	v_div_fixup_f32 v234, v248, v247, 1.0
	v_fmamk_f32 v240, v226, 0x3a800000, v89
	v_mul_f32_e32 v241, 0x4f800000, v240
	v_cmp_gt_f32_e32 vcc, s54, v240
	s_nop 1
	v_cndmask_b32_e32 v247, v240, v241, vcc
	v_sqrt_f32_e32 v242, v247
	s_nop 1
	v_add_u32_e32 v243, -1, v242
	v_add_u32_e32 v244, 1, v242
	v_fma_f32 v245, -v243, v242, v247
	v_fma_f32 v246, -v244, v242, v247
	v_cmp_ge_f32_e64 s[52:53], 0, v245
	s_nop 1
	v_cndmask_b32_e64 v242, v242, v243, s[52:53]
	v_cmp_lt_f32_e64 s[52:53], 0, v246
	s_nop 1
	v_cndmask_b32_e64 v242, v242, v244, s[52:53]
	v_mul_f32_e32 v243, 0x37800000, v242
	v_cndmask_b32_e32 v242, v242, v243, vcc
	v_cmp_class_f32_e32 vcc, v247, v90
	s_nop 1
	v_cndmask_b32_e32 v247, v242, v247, vcc
	v_div_scale_f32 v248, s[52:53], v247, v247, 1.0
	v_rcp_f32_e32 v249, v248
	v_div_scale_f32 v228, vcc, 1.0, v247, 1.0
	s_nop 0
	v_fma_f32 v229, -v248, v249, 1.0
	v_fmac_f32_e32 v249, v229, v249
	v_mul_f32_e32 v230, v228, v249
	v_fma_f32 v229, -v248, v230, v228
	v_fmac_f32_e32 v230, v229, v249
	v_fma_f32 v248, -v248, v230, v228
	v_div_fmas_f32 v248, v248, v249, v230
	v_div_fixup_f32 v236, v248, v247, 1.0
	v_fmamk_f32 v240, v227, 0x3a800000, v89
	v_mul_f32_e32 v241, 0x4f800000, v240
	v_cmp_gt_f32_e32 vcc, s54, v240
	s_nop 1
	v_cndmask_b32_e32 v247, v240, v241, vcc
	v_sqrt_f32_e32 v242, v247
	s_nop 1
	v_add_u32_e32 v243, -1, v242
	v_add_u32_e32 v244, 1, v242
	v_fma_f32 v245, -v243, v242, v247
	v_fma_f32 v246, -v244, v242, v247
	v_cmp_ge_f32_e64 s[52:53], 0, v245
	s_nop 1
	v_cndmask_b32_e64 v242, v242, v243, s[52:53]
	v_cmp_lt_f32_e64 s[52:53], 0, v246
	s_nop 1
	v_cndmask_b32_e64 v242, v242, v244, s[52:53]
	v_mul_f32_e32 v243, 0x37800000, v242
	v_cndmask_b32_e32 v242, v242, v243, vcc
	v_cmp_class_f32_e32 vcc, v247, v90
	s_nop 1
	v_cndmask_b32_e32 v247, v242, v247, vcc
	v_div_scale_f32 v248, s[52:53], v247, v247, 1.0
	v_rcp_f32_e32 v249, v248
	v_div_scale_f32 v228, vcc, 1.0, v247, 1.0
	s_nop 0
	v_fma_f32 v229, -v248, v249, 1.0
	v_fmac_f32_e32 v249, v229, v249
	v_mul_f32_e32 v230, v228, v249
	v_fma_f32 v229, -v248, v230, v228
	v_fmac_f32_e32 v230, v229, v249
	v_fma_f32 v248, -v248, v230, v228
	v_div_fmas_f32 v248, v248, v249, v230
	v_div_fixup_f32 v238, v248, v247, 1.0
	s_waitcnt vmcnt(8)
	v_pk_add_f32 v[160:161], v[160:161], 1.0 op_sel_hi:[1,0]
	v_pk_add_f32 v[162:163], v[162:163], 1.0 op_sel_hi:[1,0]
	v_pk_add_f32 v[164:165], v[164:165], 1.0 op_sel_hi:[1,0]
	v_pk_add_f32 v[166:167], v[166:167], 1.0 op_sel_hi:[1,0]
	v_pk_add_f32 v[168:169], v[168:169], 1.0 op_sel_hi:[1,0]
	v_pk_add_f32 v[170:171], v[170:171], 1.0 op_sel_hi:[1,0]
	v_pk_add_f32 v[172:173], v[172:173], 1.0 op_sel_hi:[1,0]
	v_pk_add_f32 v[174:175], v[174:175], 1.0 op_sel_hi:[1,0]
	v_pk_add_f32 v[192:193], v[192:193], 1.0 op_sel_hi:[1,0]
	v_pk_add_f32 v[194:195], v[194:195], 1.0 op_sel_hi:[1,0]
	v_pk_add_f32 v[196:197], v[196:197], 1.0 op_sel_hi:[1,0]
	v_pk_add_f32 v[198:199], v[198:199], 1.0 op_sel_hi:[1,0]
	v_pk_add_f32 v[200:201], v[200:201], 1.0 op_sel_hi:[1,0]
	v_pk_add_f32 v[202:203], v[202:203], 1.0 op_sel_hi:[1,0]
	v_pk_add_f32 v[204:205], v[204:205], 1.0 op_sel_hi:[1,0]
	v_pk_add_f32 v[206:207], v[206:207], 1.0 op_sel_hi:[1,0]
	s_mov_b64 s[38:39], s[20:21]
	s_add_u32 s40, s20, 0x400000
	s_addc_u32 s41, s21, 0
	s_add_u32 s46, s20, 0x800000
	s_addc_u32 s47, s21, 0
	s_add_u32 s48, s20, 0xc00000
	s_addc_u32 s49, s21, 0
	v_pk_mul_f32 v[0:1], v[0:1], v[232:233] op_sel_hi:[1,0]
	v_pk_mul_f32 v[2:3], v[2:3], v[232:233] op_sel_hi:[1,0]
	v_pk_mul_f32 v[0:1], v[64:65], v[0:1]
	v_pk_mul_f32 v[2:3], v[66:67], v[2:3]
	v_pk_fma_f32 v[0:1], v[160:161], v[0:1], v[176:177]
	v_pk_fma_f32 v[2:3], v[162:163], v[2:3], v[178:179]
	v_cvt_pk_bf16_f32 v244, v0, v1
	v_cvt_pk_bf16_f32 v245, v2, v3
	v_pk_mul_f32 v[4:5], v[4:5], v[232:233] op_sel_hi:[1,0]
	v_pk_mul_f32 v[6:7], v[6:7], v[232:233] op_sel_hi:[1,0]
	v_pk_mul_f32 v[4:5], v[68:69], v[4:5]
	v_pk_mul_f32 v[6:7], v[70:71], v[6:7]
	v_pk_fma_f32 v[4:5], v[164:165], v[4:5], v[180:181]
	v_pk_fma_f32 v[6:7], v[166:167], v[6:7], v[182:183]
	v_cvt_pk_bf16_f32 v246, v4, v5
	v_cvt_pk_bf16_f32 v247, v6, v7
	global_store_dwordx4 v82, v[244:247], s[38:39] offset:0
	v_pk_mul_f32 v[8:9], v[8:9], v[232:233] op_sel_hi:[1,0]
	v_pk_mul_f32 v[10:11], v[10:11], v[232:233] op_sel_hi:[1,0]
	v_pk_mul_f32 v[8:9], v[72:73], v[8:9]
	v_pk_mul_f32 v[10:11], v[74:75], v[10:11]
	v_pk_fma_f32 v[8:9], v[168:169], v[8:9], v[184:185]
	v_pk_fma_f32 v[10:11], v[170:171], v[10:11], v[186:187]
	v_cvt_pk_bf16_f32 v240, v8, v9
	v_cvt_pk_bf16_f32 v241, v10, v11
	v_pk_mul_f32 v[12:13], v[12:13], v[232:233] op_sel_hi:[1,0]
	v_pk_mul_f32 v[14:15], v[14:15], v[232:233] op_sel_hi:[1,0]
	v_pk_mul_f32 v[12:13], v[76:77], v[12:13]
	v_pk_mul_f32 v[14:15], v[78:79], v[14:15]
	v_pk_fma_f32 v[12:13], v[172:173], v[12:13], v[188:189]
	v_pk_fma_f32 v[14:15], v[174:175], v[14:15], v[190:191]
	v_cvt_pk_bf16_f32 v242, v12, v13
	v_cvt_pk_bf16_f32 v243, v14, v15
	global_store_dwordx4 v82, v[240:243], s[38:39] offset:1024
	v_pk_mul_f32 v[16:17], v[16:17], v[234:235] op_sel_hi:[1,0]
; __device__ __forceinline__ unsigned pk2(float lo, float hi) { return pg8::cvt_pk_bf16(lo, hi); }
; template <bool BF> __device__ __forceinline__ void prep_rows(const float* xp, const float* xs, const bf16* hb, const float* g, const float* MOD, int shoff, int scoff, bf16* U, int gw, int NGW, int lane) {
;     ...
;         for (int r = 0; r < R; ++r) { const int m = mb + r * NGW; if (m < MT) {
;             const float rstd = 1.0f / sqrtf(s[r] * (1.0f / DM) + RMS_EPS);
;             const float* mr = MOD + (size_t)(m < MP ? (m >> 13) : 8 + ((m - MP) >> 12)) * 6144;
; #pragma unroll
;             for (int j = 0; j < 4; ++j) { const int c = 4 * lane + 256 * j;
;                 const f32x4 gg = *(const f32x4*)(g + c), sc = *(const f32x4*)(mr + scoff + c), sh = *(const f32x4*)(mr + shoff + c);
;                 const f32x4 o = v[r][j] * rstd * gg * (sc + 1.0f) + sh; v2u w; w.x = pk2(o.x, o.y); w.y = pk2(o.z, o.w); *(v2u*)(U + (size_t)m * DM + c) = w; } } }
	v_pk_mul_f32 v[18:19], v[18:19], v[234:235] op_sel_hi:[1,0]
	v_pk_mul_f32 v[16:17], v[64:65], v[16:17]
	v_pk_mul_f32 v[18:19], v[66:67], v[18:19]
	v_pk_fma_f32 v[16:17], v[160:161], v[16:17], v[176:177]
	v_pk_fma_f32 v[18:19], v[162:163], v[18:19], v[178:179]
	v_cvt_pk_bf16_f32 v244, v16, v17
	v_cvt_pk_bf16_f32 v245, v18, v19
	v_pk_mul_f32 v[20:21], v[20:21], v[234:235] op_sel_hi:[1,0]
	v_pk_mul_f32 v[22:23], v[22:23], v[234:235] op_sel_hi:[1,0]
	v_pk_mul_f32 v[20:21], v[68:69], v[20:21]
	v_pk_mul_f32 v[22:23], v[70:71], v[22:23]
	v_pk_fma_f32 v[20:21], v[164:165], v[20:21], v[180:181]
	v_pk_fma_f32 v[22:23], v[166:167], v[22:23], v[182:183]
	v_cvt_pk_bf16_f32 v246, v20, v21
	v_cvt_pk_bf16_f32 v247, v22, v23
	global_store_dwordx4 v82, v[244:247], s[40:41] offset:0
	v_pk_mul_f32 v[24:25], v[24:25], v[234:235] op_sel_hi:[1,0]
	v_pk_mul_f32 v[26:27], v[26:27], v[234:235] op_sel_hi:[1,0]
	v_pk_mul_f32 v[24:25], v[72:73], v[24:25]
	v_pk_mul_f32 v[26:27], v[74:75], v[26:27]
	v_pk_fma_f32 v[24:25], v[168:169], v[24:25], v[184:185]
	v_pk_fma_f32 v[26:27], v[170:171], v[26:27], v[186:187]
	v_cvt_pk_bf16_f32 v240, v24, v25
	v_cvt_pk_bf16_f32 v241, v26, v27
	v_pk_mul_f32 v[28:29], v[28:29], v[234:235] op_sel_hi:[1,0]
	v_pk_mul_f32 v[30:31], v[30:31], v[234:235] op_sel_hi:[1,0]
	v_pk_mul_f32 v[28:29], v[76:77], v[28:29]
	v_pk_mul_f32 v[30:31], v[78:79], v[30:31]
	v_pk_fma_f32 v[28:29], v[172:173], v[28:29], v[188:189]
	v_pk_fma_f32 v[30:31], v[174:175], v[30:31], v[190:191]
	v_cvt_pk_bf16_f32 v242, v28, v29
	v_cvt_pk_bf16_f32 v243, v30, v31
	global_store_dwordx4 v82, v[240:243], s[40:41] offset:1024
	v_pk_mul_f32 v[32:33], v[32:33], v[236:237] op_sel_hi:[1,0]
	v_pk_mul_f32 v[34:35], v[34:35], v[236:237] op_sel_hi:[1,0]
	v_pk_mul_f32 v[32:33], v[64:65], v[32:33]
	v_pk_mul_f32 v[34:35], v[66:67], v[34:35]
	v_pk_fma_f32 v[32:33], v[192:193], v[32:33], v[208:209]
	v_pk_fma_f32 v[34:35], v[194:195], v[34:35], v[210:211]
	v_cvt_pk_bf16_f32 v244, v32, v33
	v_cvt_pk_bf16_f32 v245, v34, v35
	v_pk_mul_f32 v[36:37], v[36:37], v[236:237] op_sel_hi:[1,0]
	v_pk_mul_f32 v[38:39], v[38:39], v[236:237] op_sel_hi:[1,0]
	v_pk_mul_f32 v[36:37], v[68:69], v[36:37]
	v_pk_mul_f32 v[38:39], v[70:71], v[38:39]
	v_pk_fma_f32 v[36:37], v[196:197], v[36:37], v[212:213]
	v_pk_fma_f32 v[38:39], v[198:199], v[38:39], v[214:215]
	v_cvt_pk_bf16_f32 v246, v36, v37
	v_cvt_pk_bf16_f32 v247, v38, v39
	global_store_dwordx4 v82, v[244:247], s[46:47] offset:0
	v_pk_mul_f32 v[40:41], v[40:41], v[236:237] op_sel_hi:[1,0]
	v_pk_mul_f32 v[42:43], v[42:43], v[236:237] op_sel_hi:[1,0]
	v_pk_mul_f32 v[40:41], v[72:73], v[40:41]
	v_pk_mul_f32 v[42:43], v[74:75], v[42:43]
	v_pk_fma_f32 v[40:41], v[200:201], v[40:41], v[216:217]
	v_pk_fma_f32 v[42:43], v[202:203], v[42:43], v[218:219]
	v_cvt_pk_bf16_f32 v240, v40, v41
	v_cvt_pk_bf16_f32 v241, v42, v43
	v_pk_mul_f32 v[44:45], v[44:45], v[236:237] op_sel_hi:[1,0]
	v_pk_mul_f32 v[46:47], v[46:47], v[236:237] op_sel_hi:[1,0]
	v_pk_mul_f32 v[44:45], v[76:77], v[44:45]
	v_pk_mul_f32 v[46:47], v[78:79], v[46:47]
	v_pk_fma_f32 v[44:45], v[204:205], v[44:45], v[220:221]
	v_pk_fma_f32 v[46:47], v[206:207], v[46:47], v[222:223]
	v_cvt_pk_bf16_f32 v242, v44, v45
	v_cvt_pk_bf16_f32 v243, v46, v47
	global_store_dwordx4 v82, v[240:243], s[46:47] offset:1024
	v_pk_mul_f32 v[48:49], v[48:49], v[238:239] op_sel_hi:[1,0]
	v_pk_mul_f32 v[50:51], v[50:51], v[238:239] op_sel_hi:[1,0]
	v_pk_mul_f32 v[48:49], v[64:65], v[48:49]
	v_pk_mul_f32 v[50:51], v[66:67], v[50:51]
	v_pk_fma_f32 v[48:49], v[192:193], v[48:49], v[208:209]
	v_pk_fma_f32 v[50:51], v[194:195], v[50:51], v[210:211]
	v_cvt_pk_bf16_f32 v244, v48, v49
	v_cvt_pk_bf16_f32 v245, v50, v51
	v_pk_mul_f32 v[52:53], v[52:53], v[238:239] op_sel_hi:[1,0]
	v_pk_mul_f32 v[54:55], v[54:55], v[238:239] op_sel_hi:[1,0]
	v_pk_mul_f32 v[52:53], v[68:69], v[52:53]
	v_pk_mul_f32 v[54:55], v[70:71], v[54:55]
	v_pk_fma_f32 v[52:53], v[196:197], v[52:53], v[212:213]
	v_pk_fma_f32 v[54:55], v[198:199], v[54:55], v[214:215]
	v_cvt_pk_bf16_f32 v246, v52, v53
	v_cvt_pk_bf16_f32 v247, v54, v55
	global_store_dwordx4 v82, v[244:247], s[48:49] offset:0
	v_pk_mul_f32 v[56:57], v[56:57], v[238:239] op_sel_hi:[1,0]
	v_pk_mul_f32 v[58:59], v[58:59], v[238:239] op_sel_hi:[1,0]
	v_pk_mul_f32 v[56:57], v[72:73], v[56:57]
	v_pk_mul_f32 v[58:59], v[74:75], v[58:59]
	v_pk_fma_f32 v[56:57], v[200:201], v[56:57], v[216:217]
	v_pk_fma_f32 v[58:59], v[202:203], v[58:59], v[218:219]
	v_cvt_pk_bf16_f32 v240, v56, v57
	v_cvt_pk_bf16_f32 v241, v58, v59
	v_pk_mul_f32 v[60:61], v[60:61], v[238:239] op_sel_hi:[1,0]
	v_pk_mul_f32 v[62:63], v[62:63], v[238:239] op_sel_hi:[1,0]
	v_pk_mul_f32 v[60:61], v[76:77], v[60:61]
	v_pk_mul_f32 v[62:63], v[78:79], v[62:63]
	v_pk_fma_f32 v[60:61], v[204:205], v[60:61], v[220:221]
	v_pk_fma_f32 v[62:63], v[206:207], v[62:63], v[222:223]
	v_cvt_pk_bf16_f32 v242, v60, v61
	v_cvt_pk_bf16_f32 v243, v62, v63
	global_store_dwordx4 v82, v[240:243], s[48:49] offset:1024
	s_add_u32 s34, s8, 0x9000
	s_addc_u32 s35, s9, 0
	s_add_u32 s36, s8, 0x9000
	s_addc_u32 s37, s9, 0
	global_load_dwordx4 v[176:179], v80, s[34:35] offset:0
	global_load_dwordx4 v[180:183], v80, s[34:35] offset:16
	global_load_dwordx4 v[184:187], v80, s[34:35] offset:2048
	global_load_dwordx4 v[188:191], v80, s[34:35] offset:2064
	global_load_dwordx4 v[160:163], v81, s[34:35] offset:0
	global_load_dwordx4 v[164:167], v81, s[34:35] offset:16
	global_load_dwordx4 v[168:171], v81, s[34:35] offset:2048
	global_load_dwordx4 v[172:175], v81, s[34:35] offset:2064
	global_load_dwordx4 v[208:211], v80, s[36:37] offset:0
	global_load_dwordx4 v[212:215], v80, s[36:37] offset:16
	global_load_dwordx4 v[216:219], v80, s[36:37] offset:2048
	global_load_dwordx4 v[220:223], v80, s[36:37] offset:2064
	global_load_dwordx4 v[192:195], v81, s[36:37] offset:0
	global_load_dwordx4 v[196:199], v81, s[36:37] offset:16
	global_load_dwordx4 v[200:203], v81, s[36:37] offset:2048
	global_load_dwordx4 v[204:207], v81, s[36:37] offset:2064
	s_add_u32 s24, s16, 0x2000000
	s_addc_u32 s25, s17, 0
	s_add_u32 s26, s16, 0x2400000
	s_addc_u32 s27, s17, 0
	s_add_u32 s28, s16, 0x2800000
	s_addc_u32 s29, s17, 0
	s_add_u32 s30, s16, 0x2c00000
	s_addc_u32 s31, s17, 0
	global_load_dwordx4 v[96:99], v82, s[24:25] offset:0
	global_load_dwordx4 v[100:103], v82, s[24:25] offset:1024
	global_load_dwordx4 v[104:107], v82, s[26:27] offset:0
	global_load_dwordx4 v[108:111], v82, s[26:27] offset:1024
	global_load_dwordx4 v[112:115], v82, s[28:29] offset:0
	global_load_dwordx4 v[116:119], v82, s[28:29] offset:1024
	global_load_dwordx4 v[120:123], v82, s[30:31] offset:0
	global_load_dwordx4 v[124:127], v82, s[30:31] offset:1024
	s_waitcnt vmcnt(32)
; __device__ __forceinline__ float bf_lo(unsigned w) { return __uint_as_float(w << 16); }
; __device__ __forceinline__ float bf_hi(unsigned w) { return __uint_as_float(w & 0xffff0000u); }
; template <bool BF> __device__ __forceinline__ void prep_rows(const float* xp, const float* xs, const bf16* hb, const float* g, const float* MOD, int shoff, int scoff, bf16* U, int gw, int NGW, int lane) {
;     ...
;                 if (BF) { const v2u a0 = *(const v2u*)(hb + (size_t)mc * DM + 4 * lane + 256 * j);
;                     v[r][j].x = pg8::bf_lo(a0.x); v[r][j].y = pg8::bf_hi(a0.x); v[r][j].z = pg8::bf_lo(a0.y); v[r][j].w = pg8::bf_hi(a0.y); }
;                 else { const float* xr = mc < MP ? xp + (size_t)mc * DM : xs + (size_t)(mc - MP) * DM; v[r][j] = *(const f32x4*)(xr + 4 * lane + 256 * j); } } }
; #pragma unroll
;         for (int r = 0; r < R; ++r) { float t = 0.f;
; #pragma unroll
;             for (int j = 0; j < 4; ++j) t += (v[r][j].x * v[r][j].x + v[r][j].y * v[r][j].y) + (v[r][j].z * v[r][j].z + v[r][j].w * v[r][j].w);
;             s[r] = t; }
; #pragma unroll
;         for (int o = 1; o < 64; o <<= 1) {
; #pragma unroll
;             for (int r = 0; r < R; ++r) s[r] += __shfl_xor(s[r], o); }
	v_lshlrev_b32_e32 v0, 16, v128
	v_and_b32_e32 v1, 0xffff0000, v128
	v_lshlrev_b32_e32 v2, 16, v129
	v_and_b32_e32 v3, 0xffff0000, v129
	v_lshlrev_b32_e32 v4, 16, v130
	v_and_b32_e32 v5, 0xffff0000, v130
	v_lshlrev_b32_e32 v6, 16, v131
	v_and_b32_e32 v7, 0xffff0000, v131
	v_lshlrev_b32_e32 v8, 16, v132
	v_and_b32_e32 v9, 0xffff0000, v132
	v_lshlrev_b32_e32 v10, 16, v133
	v_and_b32_e32 v11, 0xffff0000, v133
	v_lshlrev_b32_e32 v12, 16, v134
	v_and_b32_e32 v13, 0xffff0000, v134
	v_lshlrev_b32_e32 v14, 16, v135
	v_and_b32_e32 v15, 0xffff0000, v135
	v_lshlrev_b32_e32 v16, 16, v136
	v_and_b32_e32 v17, 0xffff0000, v136
	v_lshlrev_b32_e32 v18, 16, v137
	v_and_b32_e32 v19, 0xffff0000, v137
	v_lshlrev_b32_e32 v20, 16, v138
	v_and_b32_e32 v21, 0xffff0000, v138
	v_lshlrev_b32_e32 v22, 16, v139
	v_and_b32_e32 v23, 0xffff0000, v139
	v_lshlrev_b32_e32 v24, 16, v140
	v_and_b32_e32 v25, 0xffff0000, v140
	v_lshlrev_b32_e32 v26, 16, v141
	v_and_b32_e32 v27, 0xffff0000, v141
	v_lshlrev_b32_e32 v28, 16, v142
	v_and_b32_e32 v29, 0xffff0000, v142
	v_lshlrev_b32_e32 v30, 16, v143
	v_and_b32_e32 v31, 0xffff0000, v143
	v_lshlrev_b32_e32 v32, 16, v144
	v_and_b32_e32 v33, 0xffff0000, v144
	v_lshlrev_b32_e32 v34, 16, v145
	v_and_b32_e32 v35, 0xffff0000, v145
	v_lshlrev_b32_e32 v36, 16, v146
	v_and_b32_e32 v37, 0xffff0000, v146
	v_lshlrev_b32_e32 v38, 16, v147
	v_and_b32_e32 v39, 0xffff0000, v147
	v_lshlrev_b32_e32 v40, 16, v148
	v_and_b32_e32 v41, 0xffff0000, v148
	v_lshlrev_b32_e32 v42, 16, v149
	v_and_b32_e32 v43, 0xffff0000, v149
	v_lshlrev_b32_e32 v44, 16, v150
	v_and_b32_e32 v45, 0xffff0000, v150
	v_lshlrev_b32_e32 v46, 16, v151
	v_and_b32_e32 v47, 0xffff0000, v151
	v_lshlrev_b32_e32 v48, 16, v152
	v_and_b32_e32 v49, 0xffff0000, v152
	v_lshlrev_b32_e32 v50, 16, v153
	v_and_b32_e32 v51, 0xffff0000, v153
	v_lshlrev_b32_e32 v52, 16, v154
	v_and_b32_e32 v53, 0xffff0000, v154
	v_lshlrev_b32_e32 v54, 16, v155
	v_and_b32_e32 v55, 0xffff0000, v155
	v_lshlrev_b32_e32 v56, 16, v156
	v_and_b32_e32 v57, 0xffff0000, v156
	v_lshlrev_b32_e32 v58, 16, v157
	v_and_b32_e32 v59, 0xffff0000, v157
	v_lshlrev_b32_e32 v60, 16, v158
	v_and_b32_e32 v61, 0xffff0000, v158
	v_lshlrev_b32_e32 v62, 16, v159
	v_and_b32_e32 v63, 0xffff0000, v159
	v_pk_mul_f32 v[240:241], v[0:1], v[0:1]
	v_pk_mul_f32 v[242:243], v[16:17], v[16:17]
	v_pk_mul_f32 v[244:245], v[32:33], v[32:33]
	v_pk_mul_f32 v[246:247], v[48:49], v[48:49]
	v_pk_fma_f32 v[240:241], v[2:3], v[2:3], v[240:241]
	v_pk_fma_f32 v[242:243], v[18:19], v[18:19], v[242:243]
	v_pk_fma_f32 v[244:245], v[34:35], v[34:35], v[244:245]
	v_pk_fma_f32 v[246:247], v[50:51], v[50:51], v[246:247]
	v_pk_fma_f32 v[240:241], v[4:5], v[4:5], v[240:241]
	v_pk_fma_f32 v[242:243], v[20:21], v[20:21], v[242:243]
	v_pk_fma_f32 v[244:245], v[36:37], v[36:37], v[244:245]
	v_pk_fma_f32 v[246:247], v[52:53], v[52:53], v[246:247]
	v_pk_fma_f32 v[240:241], v[6:7], v[6:7], v[240:241]
	v_pk_fma_f32 v[242:243], v[22:23], v[22:23], v[242:243]
	v_pk_fma_f32 v[244:245], v[38:39], v[38:39], v[244:245]
	v_pk_fma_f32 v[246:247], v[54:55], v[54:55], v[246:247]
	v_pk_fma_f32 v[240:241], v[8:9], v[8:9], v[240:241]
	v_pk_fma_f32 v[242:243], v[24:25], v[24:25], v[242:243]
	v_pk_fma_f32 v[244:245], v[40:41], v[40:41], v[244:245]
	v_pk_fma_f32 v[246:247], v[56:57], v[56:57], v[246:247]
	v_pk_fma_f32 v[240:241], v[10:11], v[10:11], v[240:241]
	v_pk_fma_f32 v[242:243], v[26:27], v[26:27], v[242:243]
	v_pk_fma_f32 v[244:245], v[42:43], v[42:43], v[244:245]
	v_pk_fma_f32 v[246:247], v[58:59], v[58:59], v[246:247]
	v_pk_fma_f32 v[240:241], v[12:13], v[12:13], v[240:241]
	v_pk_fma_f32 v[242:243], v[28:29], v[28:29], v[242:243]
	v_pk_fma_f32 v[244:245], v[44:45], v[44:45], v[244:245]
	v_pk_fma_f32 v[246:247], v[60:61], v[60:61], v[246:247]
	v_pk_fma_f32 v[240:241], v[14:15], v[14:15], v[240:241]
	v_pk_fma_f32 v[242:243], v[30:31], v[30:31], v[242:243]
	v_pk_fma_f32 v[244:245], v[46:47], v[46:47], v[244:245]
	v_pk_fma_f32 v[246:247], v[62:63], v[62:63], v[246:247]
	v_add_f32_e32 v224, v240, v241
	v_add_f32_e32 v225, v242, v243
	v_add_f32_e32 v226, v244, v245
	v_add_f32_e32 v227, v246, v247
	ds_bpermute_b32 v228, v83, v224
	ds_bpermute_b32 v229, v83, v225
	ds_bpermute_b32 v230, v83, v226
	ds_bpermute_b32 v231, v83, v227
	s_waitcnt lgkmcnt(0)
	v_add_f32_e32 v224, v224, v228
	v_add_f32_e32 v225, v225, v229
	v_add_f32_e32 v226, v226, v230
	v_add_f32_e32 v227, v227, v231
	ds_bpermute_b32 v228, v84, v224
	ds_bpermute_b32 v229, v84, v225
	ds_bpermute_b32 v230, v84, v226
	ds_bpermute_b32 v231, v84, v227
	s_waitcnt lgkmcnt(0)
	v_add_f32_e32 v224, v224, v228
	v_add_f32_e32 v225, v225, v229
	v_add_f32_e32 v226, v226, v230
	v_add_f32_e32 v227, v227, v231
	ds_bpermute_b32 v228, v85, v224
	ds_bpermute_b32 v229, v85, v225
	ds_bpermute_b32 v230, v85, v226
	ds_bpermute_b32 v231, v85, v227
	s_waitcnt lgkmcnt(0)
	v_add_f32_e32 v224, v224, v228
	v_add_f32_e32 v225, v225, v229
	v_add_f32_e32 v226, v226, v230
	v_add_f32_e32 v227, v227, v231
	ds_bpermute_b32 v228, v86, v224
	ds_bpermute_b32 v229, v86, v225
	ds_bpermute_b32 v230, v86, v226
	ds_bpermute_b32 v231, v86, v227
	s_waitcnt lgkmcnt(0)
	v_add_f32_e32 v224, v224, v228
	v_add_f32_e32 v225, v225, v229
	v_add_f32_e32 v226, v226, v230
	v_add_f32_e32 v227, v227, v231
	ds_bpermute_b32 v228, v87, v224
	ds_bpermute_b32 v229, v87, v225
	ds_bpermute_b32 v230, v87, v226
	ds_bpermute_b32 v231, v87, v227
	s_waitcnt lgkmcnt(0)
	v_add_f32_e32 v224, v224, v228
	v_add_f32_e32 v225, v225, v229
	v_add_f32_e32 v226, v226, v230
	v_add_f32_e32 v227, v227, v231
	ds_bpermute_b32 v228, v88, v224
	ds_bpermute_b32 v229, v88, v225
	ds_bpermute_b32 v230, v88, v226
	ds_bpermute_b32 v231, v88, v227
	s_waitcnt lgkmcnt(0)
; template <bool BF> __device__ __forceinline__ void prep_rows(const float* xp, const float* xs, const bf16* hb, const float* g, const float* MOD, int shoff, int scoff, bf16* U, int gw, int NGW, int lane) {
;     ...
;             const float rstd = 1.0f / sqrtf(s[r] * (1.0f / DM) + RMS_EPS);
	v_add_f32_e32 v224, v224, v228
	v_add_f32_e32 v225, v225, v229
	v_add_f32_e32 v226, v226, v230
	v_add_f32_e32 v227, v227, v231
	v_fmamk_f32 v240, v224, 0x3a800000, v89
	v_mul_f32_e32 v241, 0x4f800000, v240
	v_cmp_gt_f32_e32 vcc, s54, v240
	s_nop 1
	v_cndmask_b32_e32 v247, v240, v241, vcc
	v_sqrt_f32_e32 v242, v247
	s_nop 1
	v_add_u32_e32 v243, -1, v242
	v_add_u32_e32 v244, 1, v242
	v_fma_f32 v245, -v243, v242, v247
	v_fma_f32 v246, -v244, v242, v247
	v_cmp_ge_f32_e64 s[52:53], 0, v245
	s_nop 1
	v_cndmask_b32_e64 v242, v242, v243, s[52:53]
	v_cmp_lt_f32_e64 s[52:53], 0, v246
	s_nop 1
	v_cndmask_b32_e64 v242, v242, v244, s[52:53]
	v_mul_f32_e32 v243, 0x37800000, v242
	v_cndmask_b32_e32 v242, v242, v243, vcc
	v_cmp_class_f32_e32 vcc, v247, v90
	s_nop 1
	v_cndmask_b32_e32 v247, v242, v247, vcc
	v_div_scale_f32 v248, s[52:53], v247, v247, 1.0
	v_rcp_f32_e32 v249, v248
	v_div_scale_f32 v228, vcc, 1.0, v247, 1.0
	s_nop 0
	v_fma_f32 v229, -v248, v249, 1.0
	v_fmac_f32_e32 v249, v229, v249
	v_mul_f32_e32 v230, v228, v249
	v_fma_f32 v229, -v248, v230, v228
	v_fmac_f32_e32 v230, v229, v249
	v_fma_f32 v248, -v248, v230, v228
	v_div_fmas_f32 v248, v248, v249, v230
	v_div_fixup_f32 v232, v248, v247, 1.0
	v_fmamk_f32 v240, v225, 0x3a800000, v89
	v_mul_f32_e32 v241, 0x4f800000, v240
	v_cmp_gt_f32_e32 vcc, s54, v240
	s_nop 1
	v_cndmask_b32_e32 v247, v240, v241, vcc
	v_sqrt_f32_e32 v242, v247
	s_nop 1
	v_add_u32_e32 v243, -1, v242
	v_add_u32_e32 v244, 1, v242
	v_fma_f32 v245, -v243, v242, v247
	v_fma_f32 v246, -v244, v242, v247
	v_cmp_ge_f32_e64 s[52:53], 0, v245
	s_nop 1
	v_cndmask_b32_e64 v242, v242, v243, s[52:53]
	v_cmp_lt_f32_e64 s[52:53], 0, v246
	s_nop 1
	v_cndmask_b32_e64 v242, v242, v244, s[52:53]
	v_mul_f32_e32 v243, 0x37800000, v242
	v_cndmask_b32_e32 v242, v242, v243, vcc
	v_cmp_class_f32_e32 vcc, v247, v90
	s_nop 1
	v_cndmask_b32_e32 v247, v242, v247, vcc
	v_div_scale_f32 v248, s[52:53], v247, v247, 1.0
	v_rcp_f32_e32 v249, v248
	v_div_scale_f32 v228, vcc, 1.0, v247, 1.0
	s_nop 0
	v_fma_f32 v229, -v248, v249, 1.0
	v_fmac_f32_e32 v249, v229, v249
	v_mul_f32_e32 v230, v228, v249
	v_fma_f32 v229, -v248, v230, v228
	v_fmac_f32_e32 v230, v229, v249
	v_fma_f32 v248, -v248, v230, v228
	v_div_fmas_f32 v248, v248, v249, v230
	v_div_fixup_f32 v234, v248, v247, 1.0
	v_fmamk_f32 v240, v226, 0x3a800000, v89
	v_mul_f32_e32 v241, 0x4f800000, v240
	v_cmp_gt_f32_e32 vcc, s54, v240
	s_nop 1
	v_cndmask_b32_e32 v247, v240, v241, vcc
	v_sqrt_f32_e32 v242, v247
	s_nop 1
	v_add_u32_e32 v243, -1, v242
	v_add_u32_e32 v244, 1, v242
	v_fma_f32 v245, -v243, v242, v247
	v_fma_f32 v246, -v244, v242, v247
	v_cmp_ge_f32_e64 s[52:53], 0, v245
	s_nop 1
	v_cndmask_b32_e64 v242, v242, v243, s[52:53]
	v_cmp_lt_f32_e64 s[52:53], 0, v246
	s_nop 1
	v_cndmask_b32_e64 v242, v242, v244, s[52:53]
	v_mul_f32_e32 v243, 0x37800000, v242
	v_cndmask_b32_e32 v242, v242, v243, vcc
	v_cmp_class_f32_e32 vcc, v247, v90
	s_nop 1
	v_cndmask_b32_e32 v247, v242, v247, vcc
	v_div_scale_f32 v248, s[52:53], v247, v247, 1.0
	v_rcp_f32_e32 v249, v248
	v_div_scale_f32 v228, vcc, 1.0, v247, 1.0
	s_nop 0
	v_fma_f32 v229, -v248, v249, 1.0
	v_fmac_f32_e32 v249, v229, v249
	v_mul_f32_e32 v230, v228, v249
	v_fma_f32 v229, -v248, v230, v228
	v_fmac_f32_e32 v230, v229, v249
	v_fma_f32 v248, -v248, v230, v228
	v_div_fmas_f32 v248, v248, v249, v230
	v_div_fixup_f32 v236, v248, v247, 1.0
	v_fmamk_f32 v240, v227, 0x3a800000, v89
	v_mul_f32_e32 v241, 0x4f800000, v240
	v_cmp_gt_f32_e32 vcc, s54, v240
	s_nop 1
	v_cndmask_b32_e32 v247, v240, v241, vcc
	v_sqrt_f32_e32 v242, v247
	s_nop 1
	v_add_u32_e32 v243, -1, v242
	v_add_u32_e32 v244, 1, v242
	v_fma_f32 v245, -v243, v242, v247
	v_fma_f32 v246, -v244, v242, v247
	v_cmp_ge_f32_e64 s[52:53], 0, v245
	s_nop 1
	v_cndmask_b32_e64 v242, v242, v243, s[52:53]
	v_cmp_lt_f32_e64 s[52:53], 0, v246
	s_nop 1
	v_cndmask_b32_e64 v242, v242, v244, s[52:53]
	v_mul_f32_e32 v243, 0x37800000, v242
	v_cndmask_b32_e32 v242, v242, v243, vcc
	v_cmp_class_f32_e32 vcc, v247, v90
	s_nop 1
	v_cndmask_b32_e32 v247, v242, v247, vcc
	v_div_scale_f32 v248, s[52:53], v247, v247, 1.0
	v_rcp_f32_e32 v249, v248
	v_div_scale_f32 v228, vcc, 1.0, v247, 1.0
	s_nop 0
	v_fma_f32 v229, -v248, v249, 1.0
	v_fmac_f32_e32 v249, v229, v249
	v_mul_f32_e32 v230, v228, v249
	v_fma_f32 v229, -v248, v230, v228
	v_fmac_f32_e32 v230, v229, v249
	v_fma_f32 v248, -v248, v230, v228
	v_div_fmas_f32 v248, v248, v249, v230
	v_div_fixup_f32 v238, v248, v247, 1.0
	s_waitcnt vmcnt(8)
; __device__ __forceinline__ unsigned pk2(float lo, float hi) { return pg8::cvt_pk_bf16(lo, hi); }
; template <bool BF> __device__ __forceinline__ void prep_rows(const float* xp, const float* xs, const bf16* hb, const float* g, const float* MOD, int shoff, int scoff, bf16* U, int gw, int NGW, int lane) {
;     ...
;         for (int r = 0; r < R; ++r) { const int m = mb + r * NGW; if (m < MT) {
;             const float rstd = 1.0f / sqrtf(s[r] * (1.0f / DM) + RMS_EPS);
;             const float* mr = MOD + (size_t)(m < MP ? (m >> 13) : 8 + ((m - MP) >> 12)) * 6144;
; #pragma unroll
;             for (int j = 0; j < 4; ++j) { const int c = 4 * lane + 256 * j;
;                 const f32x4 gg = *(const f32x4*)(g + c), sc = *(const f32x4*)(mr + scoff + c), sh = *(const f32x4*)(mr + shoff + c);
;                 const f32x4 o = v[r][j] * rstd * gg * (sc + 1.0f) + sh; v2u w; w.x = pk2(o.x, o.y); w.y = pk2(o.z, o.w); *(v2u*)(U + (size_t)m * DM + c) = w; } } }
	v_pk_add_f32 v[160:161], v[160:161], 1.0 op_sel_hi:[1,0]
	v_pk_add_f32 v[162:163], v[162:163], 1.0 op_sel_hi:[1,0]
	v_pk_add_f32 v[164:165], v[164:165], 1.0 op_sel_hi:[1,0]
	v_pk_add_f32 v[166:167], v[166:167], 1.0 op_sel_hi:[1,0]
	v_pk_add_f32 v[168:169], v[168:169], 1.0 op_sel_hi:[1,0]
	v_pk_add_f32 v[170:171], v[170:171], 1.0 op_sel_hi:[1,0]
	v_pk_add_f32 v[172:173], v[172:173], 1.0 op_sel_hi:[1,0]
	v_pk_add_f32 v[174:175], v[174:175], 1.0 op_sel_hi:[1,0]
	v_pk_add_f32 v[192:193], v[192:193], 1.0 op_sel_hi:[1,0]
	v_pk_add_f32 v[194:195], v[194:195], 1.0 op_sel_hi:[1,0]
	v_pk_add_f32 v[196:197], v[196:197], 1.0 op_sel_hi:[1,0]
	v_pk_add_f32 v[198:199], v[198:199], 1.0 op_sel_hi:[1,0]
	v_pk_add_f32 v[200:201], v[200:201], 1.0 op_sel_hi:[1,0]
	v_pk_add_f32 v[202:203], v[202:203], 1.0 op_sel_hi:[1,0]
	v_pk_add_f32 v[204:205], v[204:205], 1.0 op_sel_hi:[1,0]
	v_pk_add_f32 v[206:207], v[206:207], 1.0 op_sel_hi:[1,0]
	s_add_u32 s38, s20, 0x1000000
	s_addc_u32 s39, s21, 0
	s_add_u32 s40, s20, 0x1400000
	s_addc_u32 s41, s21, 0
	s_add_u32 s46, s20, 0x1800000
	s_addc_u32 s47, s21, 0
	s_add_u32 s48, s20, 0x1c00000
	s_addc_u32 s49, s21, 0
	v_pk_mul_f32 v[0:1], v[0:1], v[232:233] op_sel_hi:[1,0]
	v_pk_mul_f32 v[2:3], v[2:3], v[232:233] op_sel_hi:[1,0]
	v_pk_mul_f32 v[0:1], v[64:65], v[0:1]
	v_pk_mul_f32 v[2:3], v[66:67], v[2:3]
	v_pk_fma_f32 v[0:1], v[160:161], v[0:1], v[176:177]
	v_pk_fma_f32 v[2:3], v[162:163], v[2:3], v[178:179]
	v_cvt_pk_bf16_f32 v244, v0, v1
	v_cvt_pk_bf16_f32 v245, v2, v3
	v_pk_mul_f32 v[4:5], v[4:5], v[232:233] op_sel_hi:[1,0]
	v_pk_mul_f32 v[6:7], v[6:7], v[232:233] op_sel_hi:[1,0]
	v_pk_mul_f32 v[4:5], v[68:69], v[4:5]
	v_pk_mul_f32 v[6:7], v[70:71], v[6:7]
	v_pk_fma_f32 v[4:5], v[164:165], v[4:5], v[180:181]
	v_pk_fma_f32 v[6:7], v[166:167], v[6:7], v[182:183]
	v_cvt_pk_bf16_f32 v246, v4, v5
	v_cvt_pk_bf16_f32 v247, v6, v7
	global_store_dwordx4 v82, v[244:247], s[38:39] offset:0
	v_pk_mul_f32 v[8:9], v[8:9], v[232:233] op_sel_hi:[1,0]
	v_pk_mul_f32 v[10:11], v[10:11], v[232:233] op_sel_hi:[1,0]
	v_pk_mul_f32 v[8:9], v[72:73], v[8:9]
	v_pk_mul_f32 v[10:11], v[74:75], v[10:11]
	v_pk_fma_f32 v[8:9], v[168:169], v[8:9], v[184:185]
	v_pk_fma_f32 v[10:11], v[170:171], v[10:11], v[186:187]
	v_cvt_pk_bf16_f32 v240, v8, v9
	v_cvt_pk_bf16_f32 v241, v10, v11
	v_pk_mul_f32 v[12:13], v[12:13], v[232:233] op_sel_hi:[1,0]
	v_pk_mul_f32 v[14:15], v[14:15], v[232:233] op_sel_hi:[1,0]
	v_pk_mul_f32 v[12:13], v[76:77], v[12:13]
	v_pk_mul_f32 v[14:15], v[78:79], v[14:15]
	v_pk_fma_f32 v[12:13], v[172:173], v[12:13], v[188:189]
	v_pk_fma_f32 v[14:15], v[174:175], v[14:15], v[190:191]
	v_cvt_pk_bf16_f32 v242, v12, v13
	v_cvt_pk_bf16_f32 v243, v14, v15
	global_store_dwordx4 v82, v[240:243], s[38:39] offset:1024
	v_pk_mul_f32 v[16:17], v[16:17], v[234:235] op_sel_hi:[1,0]
	v_pk_mul_f32 v[18:19], v[18:19], v[234:235] op_sel_hi:[1,0]
	v_pk_mul_f32 v[16:17], v[64:65], v[16:17]
	v_pk_mul_f32 v[18:19], v[66:67], v[18:19]
	v_pk_fma_f32 v[16:17], v[160:161], v[16:17], v[176:177]
	v_pk_fma_f32 v[18:19], v[162:163], v[18:19], v[178:179]
	v_cvt_pk_bf16_f32 v244, v16, v17
	v_cvt_pk_bf16_f32 v245, v18, v19
	v_pk_mul_f32 v[20:21], v[20:21], v[234:235] op_sel_hi:[1,0]
	v_pk_mul_f32 v[22:23], v[22:23], v[234:235] op_sel_hi:[1,0]
	v_pk_mul_f32 v[20:21], v[68:69], v[20:21]
	v_pk_mul_f32 v[22:23], v[70:71], v[22:23]
	v_pk_fma_f32 v[20:21], v[164:165], v[20:21], v[180:181]
	v_pk_fma_f32 v[22:23], v[166:167], v[22:23], v[182:183]
	v_cvt_pk_bf16_f32 v246, v20, v21
	v_cvt_pk_bf16_f32 v247, v22, v23
	global_store_dwordx4 v82, v[244:247], s[40:41] offset:0
	v_pk_mul_f32 v[24:25], v[24:25], v[234:235] op_sel_hi:[1,0]
	v_pk_mul_f32 v[26:27], v[26:27], v[234:235] op_sel_hi:[1,0]
	v_pk_mul_f32 v[24:25], v[72:73], v[24:25]
	v_pk_mul_f32 v[26:27], v[74:75], v[26:27]
	v_pk_fma_f32 v[24:25], v[168:169], v[24:25], v[184:185]
	v_pk_fma_f32 v[26:27], v[170:171], v[26:27], v[186:187]
	v_cvt_pk_bf16_f32 v240, v24, v25
	v_cvt_pk_bf16_f32 v241, v26, v27
	v_pk_mul_f32 v[28:29], v[28:29], v[234:235] op_sel_hi:[1,0]
	v_pk_mul_f32 v[30:31], v[30:31], v[234:235] op_sel_hi:[1,0]
	v_pk_mul_f32 v[28:29], v[76:77], v[28:29]
	v_pk_mul_f32 v[30:31], v[78:79], v[30:31]
	v_pk_fma_f32 v[28:29], v[172:173], v[28:29], v[188:189]
	v_pk_fma_f32 v[30:31], v[174:175], v[30:31], v[190:191]
	v_cvt_pk_bf16_f32 v242, v28, v29
	v_cvt_pk_bf16_f32 v243, v30, v31
	global_store_dwordx4 v82, v[240:243], s[40:41] offset:1024
	v_pk_mul_f32 v[32:33], v[32:33], v[236:237] op_sel_hi:[1,0]
	v_pk_mul_f32 v[34:35], v[34:35], v[236:237] op_sel_hi:[1,0]
	v_pk_mul_f32 v[32:33], v[64:65], v[32:33]
	v_pk_mul_f32 v[34:35], v[66:67], v[34:35]
	v_pk_fma_f32 v[32:33], v[192:193], v[32:33], v[208:209]
	v_pk_fma_f32 v[34:35], v[194:195], v[34:35], v[210:211]
	v_cvt_pk_bf16_f32 v244, v32, v33
	v_cvt_pk_bf16_f32 v245, v34, v35
	v_pk_mul_f32 v[36:37], v[36:37], v[236:237] op_sel_hi:[1,0]
	v_pk_mul_f32 v[38:39], v[38:39], v[236:237] op_sel_hi:[1,0]
	v_pk_mul_f32 v[36:37], v[68:69], v[36:37]
	v_pk_mul_f32 v[38:39], v[70:71], v[38:39]
	v_pk_fma_f32 v[36:37], v[196:197], v[36:37], v[212:213]
	v_pk_fma_f32 v[38:39], v[198:199], v[38:39], v[214:215]
	v_cvt_pk_bf16_f32 v246, v36, v37
	v_cvt_pk_bf16_f32 v247, v38, v39
	global_store_dwordx4 v82, v[244:247], s[46:47] offset:0
	v_pk_mul_f32 v[40:41], v[40:41], v[236:237] op_sel_hi:[1,0]
	v_pk_mul_f32 v[42:43], v[42:43], v[236:237] op_sel_hi:[1,0]
	v_pk_mul_f32 v[40:41], v[72:73], v[40:41]
	v_pk_mul_f32 v[42:43], v[74:75], v[42:43]
	v_pk_fma_f32 v[40:41], v[200:201], v[40:41], v[216:217]
	v_pk_fma_f32 v[42:43], v[202:203], v[42:43], v[218:219]
	v_cvt_pk_bf16_f32 v240, v40, v41
; __device__ __forceinline__ float bf_lo(unsigned w) { return __uint_as_float(w << 16); }
; __device__ __forceinline__ float bf_hi(unsigned w) { return __uint_as_float(w & 0xffff0000u); }
; __device__ __forceinline__ unsigned pk2(float lo, float hi) { return pg8::cvt_pk_bf16(lo, hi); }
; template <bool BF> __device__ __forceinline__ void prep_rows(const float* xp, const float* xs, const bf16* hb, const float* g, const float* MOD, int shoff, int scoff, bf16* U, int gw, int NGW, int lane) {
;     ...
;                 if (BF) { const v2u a0 = *(const v2u*)(hb + (size_t)mc * DM + 4 * lane + 256 * j);
;                     v[r][j].x = pg8::bf_lo(a0.x); v[r][j].y = pg8::bf_hi(a0.x); v[r][j].z = pg8::bf_lo(a0.y); v[r][j].w = pg8::bf_hi(a0.y); }
;                 else { const float* xr = mc < MP ? xp + (size_t)mc * DM : xs + (size_t)(mc - MP) * DM; v[r][j] = *(const f32x4*)(xr + 4 * lane + 256 * j); } } }
;     ...
;         for (int r = 0; r < R; ++r) { const int m = mb + r * NGW; if (m < MT) {
;             const float rstd = 1.0f / sqrtf(s[r] * (1.0f / DM) + RMS_EPS);
;             const float* mr = MOD + (size_t)(m < MP ? (m >> 13) : 8 + ((m - MP) >> 12)) * 6144;
; #pragma unroll
;             for (int j = 0; j < 4; ++j) { const int c = 4 * lane + 256 * j;
;                 const f32x4 gg = *(const f32x4*)(g + c), sc = *(const f32x4*)(mr + scoff + c), sh = *(const f32x4*)(mr + shoff + c);
;                 const f32x4 o = v[r][j] * rstd * gg * (sc + 1.0f) + sh; v2u w; w.x = pk2(o.x, o.y); w.y = pk2(o.z, o.w); *(v2u*)(U + (size_t)m * DM + c) = w; } } }
	v_cvt_pk_bf16_f32 v241, v42, v43
	v_pk_mul_f32 v[44:45], v[44:45], v[236:237] op_sel_hi:[1,0]
	v_pk_mul_f32 v[46:47], v[46:47], v[236:237] op_sel_hi:[1,0]
	v_pk_mul_f32 v[44:45], v[76:77], v[44:45]
	v_pk_mul_f32 v[46:47], v[78:79], v[46:47]
	v_pk_fma_f32 v[44:45], v[204:205], v[44:45], v[220:221]
	v_pk_fma_f32 v[46:47], v[206:207], v[46:47], v[222:223]
	v_cvt_pk_bf16_f32 v242, v44, v45
	v_cvt_pk_bf16_f32 v243, v46, v47
	global_store_dwordx4 v82, v[240:243], s[46:47] offset:1024
	v_pk_mul_f32 v[48:49], v[48:49], v[238:239] op_sel_hi:[1,0]
	v_pk_mul_f32 v[50:51], v[50:51], v[238:239] op_sel_hi:[1,0]
	v_pk_mul_f32 v[48:49], v[64:65], v[48:49]
	v_pk_mul_f32 v[50:51], v[66:67], v[50:51]
	v_pk_fma_f32 v[48:49], v[192:193], v[48:49], v[208:209]
	v_pk_fma_f32 v[50:51], v[194:195], v[50:51], v[210:211]
	v_cvt_pk_bf16_f32 v244, v48, v49
	v_cvt_pk_bf16_f32 v245, v50, v51
	v_pk_mul_f32 v[52:53], v[52:53], v[238:239] op_sel_hi:[1,0]
	v_pk_mul_f32 v[54:55], v[54:55], v[238:239] op_sel_hi:[1,0]
	v_pk_mul_f32 v[52:53], v[68:69], v[52:53]
	v_pk_mul_f32 v[54:55], v[70:71], v[54:55]
	v_pk_fma_f32 v[52:53], v[196:197], v[52:53], v[212:213]
	v_pk_fma_f32 v[54:55], v[198:199], v[54:55], v[214:215]
	v_cvt_pk_bf16_f32 v246, v52, v53
	v_cvt_pk_bf16_f32 v247, v54, v55
	global_store_dwordx4 v82, v[244:247], s[48:49] offset:0
	v_pk_mul_f32 v[56:57], v[56:57], v[238:239] op_sel_hi:[1,0]
	v_pk_mul_f32 v[58:59], v[58:59], v[238:239] op_sel_hi:[1,0]
	v_pk_mul_f32 v[56:57], v[72:73], v[56:57]
	v_pk_mul_f32 v[58:59], v[74:75], v[58:59]
	v_pk_fma_f32 v[56:57], v[200:201], v[56:57], v[216:217]
	v_pk_fma_f32 v[58:59], v[202:203], v[58:59], v[218:219]
	v_cvt_pk_bf16_f32 v240, v56, v57
	v_cvt_pk_bf16_f32 v241, v58, v59
	v_pk_mul_f32 v[60:61], v[60:61], v[238:239] op_sel_hi:[1,0]
	v_pk_mul_f32 v[62:63], v[62:63], v[238:239] op_sel_hi:[1,0]
	v_pk_mul_f32 v[60:61], v[76:77], v[60:61]
	v_pk_mul_f32 v[62:63], v[78:79], v[62:63]
	v_pk_fma_f32 v[60:61], v[204:205], v[60:61], v[220:221]
	v_pk_fma_f32 v[62:63], v[206:207], v[62:63], v[222:223]
	v_cvt_pk_bf16_f32 v242, v60, v61
	v_cvt_pk_bf16_f32 v243, v62, v63
	global_store_dwordx4 v82, v[240:243], s[48:49] offset:1024
	s_add_u32 s34, s8, 0xf000
	s_addc_u32 s35, s9, 0
	s_add_u32 s36, s8, 0xf000
	s_addc_u32 s37, s9, 0
	global_load_dwordx4 v[176:179], v80, s[34:35] offset:0
	global_load_dwordx4 v[180:183], v80, s[34:35] offset:16
	global_load_dwordx4 v[184:187], v80, s[34:35] offset:2048
	global_load_dwordx4 v[188:191], v80, s[34:35] offset:2064
	global_load_dwordx4 v[160:163], v81, s[34:35] offset:0
	global_load_dwordx4 v[164:167], v81, s[34:35] offset:16
	global_load_dwordx4 v[168:171], v81, s[34:35] offset:2048
	global_load_dwordx4 v[172:175], v81, s[34:35] offset:2064
	global_load_dwordx4 v[208:211], v80, s[36:37] offset:0
	global_load_dwordx4 v[212:215], v80, s[36:37] offset:16
	global_load_dwordx4 v[216:219], v80, s[36:37] offset:2048
	global_load_dwordx4 v[220:223], v80, s[36:37] offset:2064
	global_load_dwordx4 v[192:195], v81, s[36:37] offset:0
	global_load_dwordx4 v[196:199], v81, s[36:37] offset:16
	global_load_dwordx4 v[200:203], v81, s[36:37] offset:2048
	global_load_dwordx4 v[204:207], v81, s[36:37] offset:2064
	s_add_u32 s24, s16, 0x3000000
	s_addc_u32 s25, s17, 0
	s_add_u32 s26, s16, 0x3400000
	s_addc_u32 s27, s17, 0
	s_add_u32 s28, s16, 0x3800000
	s_addc_u32 s29, s17, 0
	s_add_u32 s30, s16, 0x3c00000
	s_addc_u32 s31, s17, 0
	global_load_dwordx4 v[128:131], v82, s[24:25] offset:0
	global_load_dwordx4 v[132:135], v82, s[24:25] offset:1024
	global_load_dwordx4 v[136:139], v82, s[26:27] offset:0
	global_load_dwordx4 v[140:143], v82, s[26:27] offset:1024
	global_load_dwordx4 v[144:147], v82, s[28:29] offset:0
	global_load_dwordx4 v[148:151], v82, s[28:29] offset:1024
	global_load_dwordx4 v[152:155], v82, s[30:31] offset:0
	global_load_dwordx4 v[156:159], v82, s[30:31] offset:1024
	s_waitcnt vmcnt(32)
	v_lshlrev_b32_e32 v0, 16, v96
	v_and_b32_e32 v1, 0xffff0000, v96
	v_lshlrev_b32_e32 v2, 16, v97
	v_and_b32_e32 v3, 0xffff0000, v97
	v_lshlrev_b32_e32 v4, 16, v98
	v_and_b32_e32 v5, 0xffff0000, v98
	v_lshlrev_b32_e32 v6, 16, v99
	v_and_b32_e32 v7, 0xffff0000, v99
	v_lshlrev_b32_e32 v8, 16, v100
	v_and_b32_e32 v9, 0xffff0000, v100
	v_lshlrev_b32_e32 v10, 16, v101
	v_and_b32_e32 v11, 0xffff0000, v101
	v_lshlrev_b32_e32 v12, 16, v102
	v_and_b32_e32 v13, 0xffff0000, v102
	v_lshlrev_b32_e32 v14, 16, v103
	v_and_b32_e32 v15, 0xffff0000, v103
	v_lshlrev_b32_e32 v16, 16, v104
	v_and_b32_e32 v17, 0xffff0000, v104
	v_lshlrev_b32_e32 v18, 16, v105
	v_and_b32_e32 v19, 0xffff0000, v105
	v_lshlrev_b32_e32 v20, 16, v106
	v_and_b32_e32 v21, 0xffff0000, v106
	v_lshlrev_b32_e32 v22, 16, v107
	v_and_b32_e32 v23, 0xffff0000, v107
	v_lshlrev_b32_e32 v24, 16, v108
	v_and_b32_e32 v25, 0xffff0000, v108
	v_lshlrev_b32_e32 v26, 16, v109
	v_and_b32_e32 v27, 0xffff0000, v109
	v_lshlrev_b32_e32 v28, 16, v110
	v_and_b32_e32 v29, 0xffff0000, v110
	v_lshlrev_b32_e32 v30, 16, v111
	v_and_b32_e32 v31, 0xffff0000, v111
	v_lshlrev_b32_e32 v32, 16, v112
	v_and_b32_e32 v33, 0xffff0000, v112
	v_lshlrev_b32_e32 v34, 16, v113
	v_and_b32_e32 v35, 0xffff0000, v113
	v_lshlrev_b32_e32 v36, 16, v114
	v_and_b32_e32 v37, 0xffff0000, v114
	v_lshlrev_b32_e32 v38, 16, v115
	v_and_b32_e32 v39, 0xffff0000, v115
	v_lshlrev_b32_e32 v40, 16, v116
	v_and_b32_e32 v41, 0xffff0000, v116
	v_lshlrev_b32_e32 v42, 16, v117
	v_and_b32_e32 v43, 0xffff0000, v117
	v_lshlrev_b32_e32 v44, 16, v118
	v_and_b32_e32 v45, 0xffff0000, v118
	v_lshlrev_b32_e32 v46, 16, v119
	v_and_b32_e32 v47, 0xffff0000, v119
	v_lshlrev_b32_e32 v48, 16, v120
	v_and_b32_e32 v49, 0xffff0000, v120
	v_lshlrev_b32_e32 v50, 16, v121
; __device__ __forceinline__ float bf_lo(unsigned w) { return __uint_as_float(w << 16); }
; __device__ __forceinline__ float bf_hi(unsigned w) { return __uint_as_float(w & 0xffff0000u); }
; template <bool BF> __device__ __forceinline__ void prep_rows(const float* xp, const float* xs, const bf16* hb, const float* g, const float* MOD, int shoff, int scoff, bf16* U, int gw, int NGW, int lane) {
;     ...
;                 if (BF) { const v2u a0 = *(const v2u*)(hb + (size_t)mc * DM + 4 * lane + 256 * j);
;                     v[r][j].x = pg8::bf_lo(a0.x); v[r][j].y = pg8::bf_hi(a0.x); v[r][j].z = pg8::bf_lo(a0.y); v[r][j].w = pg8::bf_hi(a0.y); }
;                 else { const float* xr = mc < MP ? xp + (size_t)mc * DM : xs + (size_t)(mc - MP) * DM; v[r][j] = *(const f32x4*)(xr + 4 * lane + 256 * j); } } }
; #pragma unroll
;         for (int r = 0; r < R; ++r) { float t = 0.f;
; #pragma unroll
;             for (int j = 0; j < 4; ++j) t += (v[r][j].x * v[r][j].x + v[r][j].y * v[r][j].y) + (v[r][j].z * v[r][j].z + v[r][j].w * v[r][j].w);
;             s[r] = t; }
; #pragma unroll
;         for (int o = 1; o < 64; o <<= 1) {
; #pragma unroll
;             for (int r = 0; r < R; ++r) s[r] += __shfl_xor(s[r], o); }
; #pragma unroll
;         for (int r = 0; r < R; ++r) { const int m = mb + r * NGW; if (m < MT) {
;             const float rstd = 1.0f / sqrtf(s[r] * (1.0f / DM) + RMS_EPS);
	v_and_b32_e32 v51, 0xffff0000, v121
	v_lshlrev_b32_e32 v52, 16, v122
	v_and_b32_e32 v53, 0xffff0000, v122
	v_lshlrev_b32_e32 v54, 16, v123
	v_and_b32_e32 v55, 0xffff0000, v123
	v_lshlrev_b32_e32 v56, 16, v124
	v_and_b32_e32 v57, 0xffff0000, v124
	v_lshlrev_b32_e32 v58, 16, v125
	v_and_b32_e32 v59, 0xffff0000, v125
	v_lshlrev_b32_e32 v60, 16, v126
	v_and_b32_e32 v61, 0xffff0000, v126
	v_lshlrev_b32_e32 v62, 16, v127
	v_and_b32_e32 v63, 0xffff0000, v127
	v_pk_mul_f32 v[240:241], v[0:1], v[0:1]
	v_pk_mul_f32 v[242:243], v[16:17], v[16:17]
	v_pk_mul_f32 v[244:245], v[32:33], v[32:33]
	v_pk_mul_f32 v[246:247], v[48:49], v[48:49]
	v_pk_fma_f32 v[240:241], v[2:3], v[2:3], v[240:241]
	v_pk_fma_f32 v[242:243], v[18:19], v[18:19], v[242:243]
	v_pk_fma_f32 v[244:245], v[34:35], v[34:35], v[244:245]
	v_pk_fma_f32 v[246:247], v[50:51], v[50:51], v[246:247]
	v_pk_fma_f32 v[240:241], v[4:5], v[4:5], v[240:241]
	v_pk_fma_f32 v[242:243], v[20:21], v[20:21], v[242:243]
	v_pk_fma_f32 v[244:245], v[36:37], v[36:37], v[244:245]
	v_pk_fma_f32 v[246:247], v[52:53], v[52:53], v[246:247]
	v_pk_fma_f32 v[240:241], v[6:7], v[6:7], v[240:241]
	v_pk_fma_f32 v[242:243], v[22:23], v[22:23], v[242:243]
	v_pk_fma_f32 v[244:245], v[38:39], v[38:39], v[244:245]
	v_pk_fma_f32 v[246:247], v[54:55], v[54:55], v[246:247]
	v_pk_fma_f32 v[240:241], v[8:9], v[8:9], v[240:241]
	v_pk_fma_f32 v[242:243], v[24:25], v[24:25], v[242:243]
	v_pk_fma_f32 v[244:245], v[40:41], v[40:41], v[244:245]
	v_pk_fma_f32 v[246:247], v[56:57], v[56:57], v[246:247]
	v_pk_fma_f32 v[240:241], v[10:11], v[10:11], v[240:241]
	v_pk_fma_f32 v[242:243], v[26:27], v[26:27], v[242:243]
	v_pk_fma_f32 v[244:245], v[42:43], v[42:43], v[244:245]
	v_pk_fma_f32 v[246:247], v[58:59], v[58:59], v[246:247]
	v_pk_fma_f32 v[240:241], v[12:13], v[12:13], v[240:241]
	v_pk_fma_f32 v[242:243], v[28:29], v[28:29], v[242:243]
	v_pk_fma_f32 v[244:245], v[44:45], v[44:45], v[244:245]
	v_pk_fma_f32 v[246:247], v[60:61], v[60:61], v[246:247]
	v_pk_fma_f32 v[240:241], v[14:15], v[14:15], v[240:241]
	v_pk_fma_f32 v[242:243], v[30:31], v[30:31], v[242:243]
	v_pk_fma_f32 v[244:245], v[46:47], v[46:47], v[244:245]
	v_pk_fma_f32 v[246:247], v[62:63], v[62:63], v[246:247]
	v_add_f32_e32 v224, v240, v241
	v_add_f32_e32 v225, v242, v243
	v_add_f32_e32 v226, v244, v245
	v_add_f32_e32 v227, v246, v247
	ds_bpermute_b32 v228, v83, v224
	ds_bpermute_b32 v229, v83, v225
	ds_bpermute_b32 v230, v83, v226
	ds_bpermute_b32 v231, v83, v227
	s_waitcnt lgkmcnt(0)
	v_add_f32_e32 v224, v224, v228
	v_add_f32_e32 v225, v225, v229
	v_add_f32_e32 v226, v226, v230
	v_add_f32_e32 v227, v227, v231
	ds_bpermute_b32 v228, v84, v224
	ds_bpermute_b32 v229, v84, v225
	ds_bpermute_b32 v230, v84, v226
	ds_bpermute_b32 v231, v84, v227
	s_waitcnt lgkmcnt(0)
	v_add_f32_e32 v224, v224, v228
	v_add_f32_e32 v225, v225, v229
	v_add_f32_e32 v226, v226, v230
	v_add_f32_e32 v227, v227, v231
	ds_bpermute_b32 v228, v85, v224
	ds_bpermute_b32 v229, v85, v225
	ds_bpermute_b32 v230, v85, v226
	ds_bpermute_b32 v231, v85, v227
	s_waitcnt lgkmcnt(0)
	v_add_f32_e32 v224, v224, v228
	v_add_f32_e32 v225, v225, v229
	v_add_f32_e32 v226, v226, v230
	v_add_f32_e32 v227, v227, v231
	ds_bpermute_b32 v228, v86, v224
	ds_bpermute_b32 v229, v86, v225
	ds_bpermute_b32 v230, v86, v226
	ds_bpermute_b32 v231, v86, v227
	s_waitcnt lgkmcnt(0)
	v_add_f32_e32 v224, v224, v228
	v_add_f32_e32 v225, v225, v229
	v_add_f32_e32 v226, v226, v230
	v_add_f32_e32 v227, v227, v231
	ds_bpermute_b32 v228, v87, v224
	ds_bpermute_b32 v229, v87, v225
	ds_bpermute_b32 v230, v87, v226
	ds_bpermute_b32 v231, v87, v227
	s_waitcnt lgkmcnt(0)
	v_add_f32_e32 v224, v224, v228
	v_add_f32_e32 v225, v225, v229
	v_add_f32_e32 v226, v226, v230
	v_add_f32_e32 v227, v227, v231
	ds_bpermute_b32 v228, v88, v224
	ds_bpermute_b32 v229, v88, v225
	ds_bpermute_b32 v230, v88, v226
	ds_bpermute_b32 v231, v88, v227
	s_waitcnt lgkmcnt(0)
	v_add_f32_e32 v224, v224, v228
	v_add_f32_e32 v225, v225, v229
	v_add_f32_e32 v226, v226, v230
	v_add_f32_e32 v227, v227, v231
	v_fmamk_f32 v240, v224, 0x3a800000, v89
	v_mul_f32_e32 v241, 0x4f800000, v240
	v_cmp_gt_f32_e32 vcc, s54, v240
	s_nop 1
	v_cndmask_b32_e32 v247, v240, v241, vcc
	v_sqrt_f32_e32 v242, v247
	s_nop 1
	v_add_u32_e32 v243, -1, v242
	v_add_u32_e32 v244, 1, v242
	v_fma_f32 v245, -v243, v242, v247
	v_fma_f32 v246, -v244, v242, v247
	v_cmp_ge_f32_e64 s[52:53], 0, v245
	s_nop 1
	v_cndmask_b32_e64 v242, v242, v243, s[52:53]
	v_cmp_lt_f32_e64 s[52:53], 0, v246
	s_nop 1
	v_cndmask_b32_e64 v242, v242, v244, s[52:53]
	v_mul_f32_e32 v243, 0x37800000, v242
	v_cndmask_b32_e32 v242, v242, v243, vcc
	v_cmp_class_f32_e32 vcc, v247, v90
	s_nop 1
	v_cndmask_b32_e32 v247, v242, v247, vcc
	v_div_scale_f32 v248, s[52:53], v247, v247, 1.0
	v_rcp_f32_e32 v249, v248
	v_div_scale_f32 v228, vcc, 1.0, v247, 1.0
	s_nop 0
	v_fma_f32 v229, -v248, v249, 1.0
	v_fmac_f32_e32 v249, v229, v249
	v_mul_f32_e32 v230, v228, v249
	v_fma_f32 v229, -v248, v230, v228
	v_fmac_f32_e32 v230, v229, v249
	v_fma_f32 v248, -v248, v230, v228
	v_div_fmas_f32 v248, v248, v249, v230
	v_div_fixup_f32 v232, v248, v247, 1.0
	v_fmamk_f32 v240, v225, 0x3a800000, v89
	v_mul_f32_e32 v241, 0x4f800000, v240
	v_cmp_gt_f32_e32 vcc, s54, v240
	s_nop 1
	v_cndmask_b32_e32 v247, v240, v241, vcc
	v_sqrt_f32_e32 v242, v247
	s_nop 1
	v_add_u32_e32 v243, -1, v242
	v_add_u32_e32 v244, 1, v242
	v_fma_f32 v245, -v243, v242, v247
	v_fma_f32 v246, -v244, v242, v247
	v_cmp_ge_f32_e64 s[52:53], 0, v245
	s_nop 1
	v_cndmask_b32_e64 v242, v242, v243, s[52:53]
	v_cmp_lt_f32_e64 s[52:53], 0, v246
	s_nop 1
	v_cndmask_b32_e64 v242, v242, v244, s[52:53]
; __device__ __forceinline__ unsigned pk2(float lo, float hi) { return pg8::cvt_pk_bf16(lo, hi); }
; template <bool BF> __device__ __forceinline__ void prep_rows(const float* xp, const float* xs, const bf16* hb, const float* g, const float* MOD, int shoff, int scoff, bf16* U, int gw, int NGW, int lane) {
;     ...
;             const float rstd = 1.0f / sqrtf(s[r] * (1.0f / DM) + RMS_EPS);
;             const float* mr = MOD + (size_t)(m < MP ? (m >> 13) : 8 + ((m - MP) >> 12)) * 6144;
; #pragma unroll
;             for (int j = 0; j < 4; ++j) { const int c = 4 * lane + 256 * j;
;                 const f32x4 gg = *(const f32x4*)(g + c), sc = *(const f32x4*)(mr + scoff + c), sh = *(const f32x4*)(mr + shoff + c);
;                 const f32x4 o = v[r][j] * rstd * gg * (sc + 1.0f) + sh; v2u w; w.x = pk2(o.x, o.y); w.y = pk2(o.z, o.w); *(v2u*)(U + (size_t)m * DM + c) = w; } } }
	v_mul_f32_e32 v243, 0x37800000, v242
	v_cndmask_b32_e32 v242, v242, v243, vcc
	v_cmp_class_f32_e32 vcc, v247, v90
	s_nop 1
	v_cndmask_b32_e32 v247, v242, v247, vcc
	v_div_scale_f32 v248, s[52:53], v247, v247, 1.0
	v_rcp_f32_e32 v249, v248
	v_div_scale_f32 v228, vcc, 1.0, v247, 1.0
	s_nop 0
	v_fma_f32 v229, -v248, v249, 1.0
	v_fmac_f32_e32 v249, v229, v249
	v_mul_f32_e32 v230, v228, v249
	v_fma_f32 v229, -v248, v230, v228
	v_fmac_f32_e32 v230, v229, v249
	v_fma_f32 v248, -v248, v230, v228
	v_div_fmas_f32 v248, v248, v249, v230
	v_div_fixup_f32 v234, v248, v247, 1.0
	v_fmamk_f32 v240, v226, 0x3a800000, v89
	v_mul_f32_e32 v241, 0x4f800000, v240
	v_cmp_gt_f32_e32 vcc, s54, v240
	s_nop 1
	v_cndmask_b32_e32 v247, v240, v241, vcc
	v_sqrt_f32_e32 v242, v247
	s_nop 1
	v_add_u32_e32 v243, -1, v242
	v_add_u32_e32 v244, 1, v242
	v_fma_f32 v245, -v243, v242, v247
	v_fma_f32 v246, -v244, v242, v247
	v_cmp_ge_f32_e64 s[52:53], 0, v245
	s_nop 1
	v_cndmask_b32_e64 v242, v242, v243, s[52:53]
	v_cmp_lt_f32_e64 s[52:53], 0, v246
	s_nop 1
	v_cndmask_b32_e64 v242, v242, v244, s[52:53]
	v_mul_f32_e32 v243, 0x37800000, v242
	v_cndmask_b32_e32 v242, v242, v243, vcc
	v_cmp_class_f32_e32 vcc, v247, v90
	s_nop 1
	v_cndmask_b32_e32 v247, v242, v247, vcc
	v_div_scale_f32 v248, s[52:53], v247, v247, 1.0
	v_rcp_f32_e32 v249, v248
	v_div_scale_f32 v228, vcc, 1.0, v247, 1.0
	s_nop 0
	v_fma_f32 v229, -v248, v249, 1.0
	v_fmac_f32_e32 v249, v229, v249
	v_mul_f32_e32 v230, v228, v249
	v_fma_f32 v229, -v248, v230, v228
	v_fmac_f32_e32 v230, v229, v249
	v_fma_f32 v248, -v248, v230, v228
	v_div_fmas_f32 v248, v248, v249, v230
	v_div_fixup_f32 v236, v248, v247, 1.0
	v_fmamk_f32 v240, v227, 0x3a800000, v89
	v_mul_f32_e32 v241, 0x4f800000, v240
	v_cmp_gt_f32_e32 vcc, s54, v240
	s_nop 1
	v_cndmask_b32_e32 v247, v240, v241, vcc
	v_sqrt_f32_e32 v242, v247
	s_nop 1
	v_add_u32_e32 v243, -1, v242
	v_add_u32_e32 v244, 1, v242
	v_fma_f32 v245, -v243, v242, v247
	v_fma_f32 v246, -v244, v242, v247
	v_cmp_ge_f32_e64 s[52:53], 0, v245
	s_nop 1
	v_cndmask_b32_e64 v242, v242, v243, s[52:53]
	v_cmp_lt_f32_e64 s[52:53], 0, v246
	s_nop 1
	v_cndmask_b32_e64 v242, v242, v244, s[52:53]
	v_mul_f32_e32 v243, 0x37800000, v242
	v_cndmask_b32_e32 v242, v242, v243, vcc
	v_cmp_class_f32_e32 vcc, v247, v90
	s_nop 1
	v_cndmask_b32_e32 v247, v242, v247, vcc
	v_div_scale_f32 v248, s[52:53], v247, v247, 1.0
	v_rcp_f32_e32 v249, v248
	v_div_scale_f32 v228, vcc, 1.0, v247, 1.0
	s_nop 0
	v_fma_f32 v229, -v248, v249, 1.0
	v_fmac_f32_e32 v249, v229, v249
	v_mul_f32_e32 v230, v228, v249
	v_fma_f32 v229, -v248, v230, v228
	v_fmac_f32_e32 v230, v229, v249
	v_fma_f32 v248, -v248, v230, v228
	v_div_fmas_f32 v248, v248, v249, v230
	v_div_fixup_f32 v238, v248, v247, 1.0
	s_waitcnt vmcnt(8)
	v_pk_add_f32 v[160:161], v[160:161], 1.0 op_sel_hi:[1,0]
	v_pk_add_f32 v[162:163], v[162:163], 1.0 op_sel_hi:[1,0]
	v_pk_add_f32 v[164:165], v[164:165], 1.0 op_sel_hi:[1,0]
	v_pk_add_f32 v[166:167], v[166:167], 1.0 op_sel_hi:[1,0]
	v_pk_add_f32 v[168:169], v[168:169], 1.0 op_sel_hi:[1,0]
	v_pk_add_f32 v[170:171], v[170:171], 1.0 op_sel_hi:[1,0]
	v_pk_add_f32 v[172:173], v[172:173], 1.0 op_sel_hi:[1,0]
	v_pk_add_f32 v[174:175], v[174:175], 1.0 op_sel_hi:[1,0]
	v_pk_add_f32 v[192:193], v[192:193], 1.0 op_sel_hi:[1,0]
	v_pk_add_f32 v[194:195], v[194:195], 1.0 op_sel_hi:[1,0]
	v_pk_add_f32 v[196:197], v[196:197], 1.0 op_sel_hi:[1,0]
	v_pk_add_f32 v[198:199], v[198:199], 1.0 op_sel_hi:[1,0]
	v_pk_add_f32 v[200:201], v[200:201], 1.0 op_sel_hi:[1,0]
	v_pk_add_f32 v[202:203], v[202:203], 1.0 op_sel_hi:[1,0]
	v_pk_add_f32 v[204:205], v[204:205], 1.0 op_sel_hi:[1,0]
	v_pk_add_f32 v[206:207], v[206:207], 1.0 op_sel_hi:[1,0]
	s_add_u32 s38, s20, 0x2000000
	s_addc_u32 s39, s21, 0
	s_add_u32 s40, s20, 0x2400000
	s_addc_u32 s41, s21, 0
	s_add_u32 s46, s20, 0x2800000
	s_addc_u32 s47, s21, 0
	s_add_u32 s48, s20, 0x2c00000
	s_addc_u32 s49, s21, 0
	v_pk_mul_f32 v[0:1], v[0:1], v[232:233] op_sel_hi:[1,0]
	v_pk_mul_f32 v[2:3], v[2:3], v[232:233] op_sel_hi:[1,0]
	v_pk_mul_f32 v[0:1], v[64:65], v[0:1]
	v_pk_mul_f32 v[2:3], v[66:67], v[2:3]
	v_pk_fma_f32 v[0:1], v[160:161], v[0:1], v[176:177]
	v_pk_fma_f32 v[2:3], v[162:163], v[2:3], v[178:179]
	v_cvt_pk_bf16_f32 v244, v0, v1
	v_cvt_pk_bf16_f32 v245, v2, v3
	v_pk_mul_f32 v[4:5], v[4:5], v[232:233] op_sel_hi:[1,0]
	v_pk_mul_f32 v[6:7], v[6:7], v[232:233] op_sel_hi:[1,0]
	v_pk_mul_f32 v[4:5], v[68:69], v[4:5]
	v_pk_mul_f32 v[6:7], v[70:71], v[6:7]
	v_pk_fma_f32 v[4:5], v[164:165], v[4:5], v[180:181]
	v_pk_fma_f32 v[6:7], v[166:167], v[6:7], v[182:183]
	v_cvt_pk_bf16_f32 v246, v4, v5
	v_cvt_pk_bf16_f32 v247, v6, v7
	global_store_dwordx4 v82, v[244:247], s[38:39] offset:0
	v_pk_mul_f32 v[8:9], v[8:9], v[232:233] op_sel_hi:[1,0]
	v_pk_mul_f32 v[10:11], v[10:11], v[232:233] op_sel_hi:[1,0]
	v_pk_mul_f32 v[8:9], v[72:73], v[8:9]
	v_pk_mul_f32 v[10:11], v[74:75], v[10:11]
	v_pk_fma_f32 v[8:9], v[168:169], v[8:9], v[184:185]
	v_pk_fma_f32 v[10:11], v[170:171], v[10:11], v[186:187]
	v_cvt_pk_bf16_f32 v240, v8, v9
	v_cvt_pk_bf16_f32 v241, v10, v11
	v_pk_mul_f32 v[12:13], v[12:13], v[232:233] op_sel_hi:[1,0]
	v_pk_mul_f32 v[14:15], v[14:15], v[232:233] op_sel_hi:[1,0]
	v_pk_mul_f32 v[12:13], v[76:77], v[12:13]
	v_pk_mul_f32 v[14:15], v[78:79], v[14:15]
	v_pk_fma_f32 v[12:13], v[172:173], v[12:13], v[188:189]
	v_pk_fma_f32 v[14:15], v[174:175], v[14:15], v[190:191]
	v_cvt_pk_bf16_f32 v242, v12, v13
	v_cvt_pk_bf16_f32 v243, v14, v15
	global_store_dwordx4 v82, v[240:243], s[38:39] offset:1024
	v_pk_mul_f32 v[16:17], v[16:17], v[234:235] op_sel_hi:[1,0]
	v_pk_mul_f32 v[18:19], v[18:19], v[234:235] op_sel_hi:[1,0]
; __device__ __forceinline__ float bf_lo(unsigned w) { return __uint_as_float(w << 16); }
; __device__ __forceinline__ float bf_hi(unsigned w) { return __uint_as_float(w & 0xffff0000u); }
; __device__ __forceinline__ unsigned pk2(float lo, float hi) { return pg8::cvt_pk_bf16(lo, hi); }
; template <bool BF> __device__ __forceinline__ void prep_rows(const float* xp, const float* xs, const bf16* hb, const float* g, const float* MOD, int shoff, int scoff, bf16* U, int gw, int NGW, int lane) {
;     ...
;                 if (BF) { const v2u a0 = *(const v2u*)(hb + (size_t)mc * DM + 4 * lane + 256 * j);
;                     v[r][j].x = pg8::bf_lo(a0.x); v[r][j].y = pg8::bf_hi(a0.x); v[r][j].z = pg8::bf_lo(a0.y); v[r][j].w = pg8::bf_hi(a0.y); }
;                 else { const float* xr = mc < MP ? xp + (size_t)mc * DM : xs + (size_t)(mc - MP) * DM; v[r][j] = *(const f32x4*)(xr + 4 * lane + 256 * j); } } }
;     ...
;         for (int r = 0; r < R; ++r) { const int m = mb + r * NGW; if (m < MT) {
;             const float rstd = 1.0f / sqrtf(s[r] * (1.0f / DM) + RMS_EPS);
;             const float* mr = MOD + (size_t)(m < MP ? (m >> 13) : 8 + ((m - MP) >> 12)) * 6144;
; #pragma unroll
;             for (int j = 0; j < 4; ++j) { const int c = 4 * lane + 256 * j;
;                 const f32x4 gg = *(const f32x4*)(g + c), sc = *(const f32x4*)(mr + scoff + c), sh = *(const f32x4*)(mr + shoff + c);
;                 const f32x4 o = v[r][j] * rstd * gg * (sc + 1.0f) + sh; v2u w; w.x = pk2(o.x, o.y); w.y = pk2(o.z, o.w); *(v2u*)(U + (size_t)m * DM + c) = w; } } }
	v_pk_mul_f32 v[16:17], v[64:65], v[16:17]
	v_pk_mul_f32 v[18:19], v[66:67], v[18:19]
	v_pk_fma_f32 v[16:17], v[160:161], v[16:17], v[176:177]
	v_pk_fma_f32 v[18:19], v[162:163], v[18:19], v[178:179]
	v_cvt_pk_bf16_f32 v244, v16, v17
	v_cvt_pk_bf16_f32 v245, v18, v19
	v_pk_mul_f32 v[20:21], v[20:21], v[234:235] op_sel_hi:[1,0]
	v_pk_mul_f32 v[22:23], v[22:23], v[234:235] op_sel_hi:[1,0]
	v_pk_mul_f32 v[20:21], v[68:69], v[20:21]
	v_pk_mul_f32 v[22:23], v[70:71], v[22:23]
	v_pk_fma_f32 v[20:21], v[164:165], v[20:21], v[180:181]
	v_pk_fma_f32 v[22:23], v[166:167], v[22:23], v[182:183]
	v_cvt_pk_bf16_f32 v246, v20, v21
	v_cvt_pk_bf16_f32 v247, v22, v23
	global_store_dwordx4 v82, v[244:247], s[40:41] offset:0
	v_pk_mul_f32 v[24:25], v[24:25], v[234:235] op_sel_hi:[1,0]
	v_pk_mul_f32 v[26:27], v[26:27], v[234:235] op_sel_hi:[1,0]
	v_pk_mul_f32 v[24:25], v[72:73], v[24:25]
	v_pk_mul_f32 v[26:27], v[74:75], v[26:27]
	v_pk_fma_f32 v[24:25], v[168:169], v[24:25], v[184:185]
	v_pk_fma_f32 v[26:27], v[170:171], v[26:27], v[186:187]
	v_cvt_pk_bf16_f32 v240, v24, v25
	v_cvt_pk_bf16_f32 v241, v26, v27
	v_pk_mul_f32 v[28:29], v[28:29], v[234:235] op_sel_hi:[1,0]
	v_pk_mul_f32 v[30:31], v[30:31], v[234:235] op_sel_hi:[1,0]
	v_pk_mul_f32 v[28:29], v[76:77], v[28:29]
	v_pk_mul_f32 v[30:31], v[78:79], v[30:31]
	v_pk_fma_f32 v[28:29], v[172:173], v[28:29], v[188:189]
	v_pk_fma_f32 v[30:31], v[174:175], v[30:31], v[190:191]
	v_cvt_pk_bf16_f32 v242, v28, v29
	v_cvt_pk_bf16_f32 v243, v30, v31
	global_store_dwordx4 v82, v[240:243], s[40:41] offset:1024
	v_pk_mul_f32 v[32:33], v[32:33], v[236:237] op_sel_hi:[1,0]
	v_pk_mul_f32 v[34:35], v[34:35], v[236:237] op_sel_hi:[1,0]
	v_pk_mul_f32 v[32:33], v[64:65], v[32:33]
	v_pk_mul_f32 v[34:35], v[66:67], v[34:35]
	v_pk_fma_f32 v[32:33], v[192:193], v[32:33], v[208:209]
	v_pk_fma_f32 v[34:35], v[194:195], v[34:35], v[210:211]
	v_cvt_pk_bf16_f32 v244, v32, v33
	v_cvt_pk_bf16_f32 v245, v34, v35
	v_pk_mul_f32 v[36:37], v[36:37], v[236:237] op_sel_hi:[1,0]
	v_pk_mul_f32 v[38:39], v[38:39], v[236:237] op_sel_hi:[1,0]
	v_pk_mul_f32 v[36:37], v[68:69], v[36:37]
	v_pk_mul_f32 v[38:39], v[70:71], v[38:39]
	v_pk_fma_f32 v[36:37], v[196:197], v[36:37], v[212:213]
	v_pk_fma_f32 v[38:39], v[198:199], v[38:39], v[214:215]
	v_cvt_pk_bf16_f32 v246, v36, v37
	v_cvt_pk_bf16_f32 v247, v38, v39
	global_store_dwordx4 v82, v[244:247], s[46:47] offset:0
	v_pk_mul_f32 v[40:41], v[40:41], v[236:237] op_sel_hi:[1,0]
	v_pk_mul_f32 v[42:43], v[42:43], v[236:237] op_sel_hi:[1,0]
	v_pk_mul_f32 v[40:41], v[72:73], v[40:41]
	v_pk_mul_f32 v[42:43], v[74:75], v[42:43]
	v_pk_fma_f32 v[40:41], v[200:201], v[40:41], v[216:217]
	v_pk_fma_f32 v[42:43], v[202:203], v[42:43], v[218:219]
	v_cvt_pk_bf16_f32 v240, v40, v41
	v_cvt_pk_bf16_f32 v241, v42, v43
	v_pk_mul_f32 v[44:45], v[44:45], v[236:237] op_sel_hi:[1,0]
	v_pk_mul_f32 v[46:47], v[46:47], v[236:237] op_sel_hi:[1,0]
	v_pk_mul_f32 v[44:45], v[76:77], v[44:45]
	v_pk_mul_f32 v[46:47], v[78:79], v[46:47]
	v_pk_fma_f32 v[44:45], v[204:205], v[44:45], v[220:221]
	v_pk_fma_f32 v[46:47], v[206:207], v[46:47], v[222:223]
	v_cvt_pk_bf16_f32 v242, v44, v45
	v_cvt_pk_bf16_f32 v243, v46, v47
	global_store_dwordx4 v82, v[240:243], s[46:47] offset:1024
	v_pk_mul_f32 v[48:49], v[48:49], v[238:239] op_sel_hi:[1,0]
	v_pk_mul_f32 v[50:51], v[50:51], v[238:239] op_sel_hi:[1,0]
	v_pk_mul_f32 v[48:49], v[64:65], v[48:49]
	v_pk_mul_f32 v[50:51], v[66:67], v[50:51]
	v_pk_fma_f32 v[48:49], v[192:193], v[48:49], v[208:209]
	v_pk_fma_f32 v[50:51], v[194:195], v[50:51], v[210:211]
	v_cvt_pk_bf16_f32 v244, v48, v49
	v_cvt_pk_bf16_f32 v245, v50, v51
	v_pk_mul_f32 v[52:53], v[52:53], v[238:239] op_sel_hi:[1,0]
	v_pk_mul_f32 v[54:55], v[54:55], v[238:239] op_sel_hi:[1,0]
	v_pk_mul_f32 v[52:53], v[68:69], v[52:53]
	v_pk_mul_f32 v[54:55], v[70:71], v[54:55]
	v_pk_fma_f32 v[52:53], v[196:197], v[52:53], v[212:213]
	v_pk_fma_f32 v[54:55], v[198:199], v[54:55], v[214:215]
	v_cvt_pk_bf16_f32 v246, v52, v53
	v_cvt_pk_bf16_f32 v247, v54, v55
	global_store_dwordx4 v82, v[244:247], s[48:49] offset:0
	v_pk_mul_f32 v[56:57], v[56:57], v[238:239] op_sel_hi:[1,0]
	v_pk_mul_f32 v[58:59], v[58:59], v[238:239] op_sel_hi:[1,0]
	v_pk_mul_f32 v[56:57], v[72:73], v[56:57]
	v_pk_mul_f32 v[58:59], v[74:75], v[58:59]
	v_pk_fma_f32 v[56:57], v[200:201], v[56:57], v[216:217]
	v_pk_fma_f32 v[58:59], v[202:203], v[58:59], v[218:219]
	v_cvt_pk_bf16_f32 v240, v56, v57
	v_cvt_pk_bf16_f32 v241, v58, v59
	v_pk_mul_f32 v[60:61], v[60:61], v[238:239] op_sel_hi:[1,0]
	v_pk_mul_f32 v[62:63], v[62:63], v[238:239] op_sel_hi:[1,0]
	v_pk_mul_f32 v[60:61], v[76:77], v[60:61]
	v_pk_mul_f32 v[62:63], v[78:79], v[62:63]
	v_pk_fma_f32 v[60:61], v[204:205], v[60:61], v[220:221]
	v_pk_fma_f32 v[62:63], v[206:207], v[62:63], v[222:223]
	v_cvt_pk_bf16_f32 v242, v60, v61
	v_cvt_pk_bf16_f32 v243, v62, v63
	global_store_dwordx4 v82, v[240:243], s[48:49] offset:1024
	s_add_u32 s34, s8, 0x15000
	s_addc_u32 s35, s9, 0
	s_add_u32 s36, s8, 0x15000
	s_addc_u32 s37, s9, 0
	global_load_dwordx4 v[176:179], v80, s[34:35] offset:0
	global_load_dwordx4 v[180:183], v80, s[34:35] offset:16
	global_load_dwordx4 v[184:187], v80, s[34:35] offset:2048
	global_load_dwordx4 v[188:191], v80, s[34:35] offset:2064
	global_load_dwordx4 v[160:163], v81, s[34:35] offset:0
	global_load_dwordx4 v[164:167], v81, s[34:35] offset:16
	global_load_dwordx4 v[168:171], v81, s[34:35] offset:2048
	global_load_dwordx4 v[172:175], v81, s[34:35] offset:2064
	global_load_dwordx4 v[208:211], v80, s[36:37] offset:0
	global_load_dwordx4 v[212:215], v80, s[36:37] offset:16
	global_load_dwordx4 v[216:219], v80, s[36:37] offset:2048
	global_load_dwordx4 v[220:223], v80, s[36:37] offset:2064
	global_load_dwordx4 v[192:195], v81, s[36:37] offset:0
	global_load_dwordx4 v[196:199], v81, s[36:37] offset:16
	global_load_dwordx4 v[200:203], v81, s[36:37] offset:2048
	global_load_dwordx4 v[204:207], v81, s[36:37] offset:2064
	s_add_u32 s24, s16, 0x4000000
	s_addc_u32 s25, s17, 0
	s_add_u32 s26, s16, 0x4400000
	s_addc_u32 s27, s17, 0
	s_add_u32 s28, s16, 0x4800000
	s_addc_u32 s29, s17, 0
	s_add_u32 s30, s16, 0x4c00000
	s_addc_u32 s31, s17, 0
	global_load_dwordx4 v[96:99], v82, s[24:25] offset:0
	global_load_dwordx4 v[100:103], v82, s[24:25] offset:1024
	global_load_dwordx4 v[104:107], v82, s[26:27] offset:0
	global_load_dwordx4 v[108:111], v82, s[26:27] offset:1024
	global_load_dwordx4 v[112:115], v82, s[28:29] offset:0
	global_load_dwordx4 v[116:119], v82, s[28:29] offset:1024
	global_load_dwordx4 v[120:123], v82, s[30:31] offset:0
	global_load_dwordx4 v[124:127], v82, s[30:31] offset:1024
	s_waitcnt vmcnt(32)
; __device__ __forceinline__ float bf_lo(unsigned w) { return __uint_as_float(w << 16); }
; __device__ __forceinline__ float bf_hi(unsigned w) { return __uint_as_float(w & 0xffff0000u); }
; template <bool BF> __device__ __forceinline__ void prep_rows(const float* xp, const float* xs, const bf16* hb, const float* g, const float* MOD, int shoff, int scoff, bf16* U, int gw, int NGW, int lane) {
;     ...
;                 if (BF) { const v2u a0 = *(const v2u*)(hb + (size_t)mc * DM + 4 * lane + 256 * j);
;                     v[r][j].x = pg8::bf_lo(a0.x); v[r][j].y = pg8::bf_hi(a0.x); v[r][j].z = pg8::bf_lo(a0.y); v[r][j].w = pg8::bf_hi(a0.y); }
;                 else { const float* xr = mc < MP ? xp + (size_t)mc * DM : xs + (size_t)(mc - MP) * DM; v[r][j] = *(const f32x4*)(xr + 4 * lane + 256 * j); } } }
; #pragma unroll
;         for (int r = 0; r < R; ++r) { float t = 0.f;
; #pragma unroll
;             for (int j = 0; j < 4; ++j) t += (v[r][j].x * v[r][j].x + v[r][j].y * v[r][j].y) + (v[r][j].z * v[r][j].z + v[r][j].w * v[r][j].w);
;             s[r] = t; }
; #pragma unroll
;         for (int o = 1; o < 64; o <<= 1) {
; #pragma unroll
;             for (int r = 0; r < R; ++r) s[r] += __shfl_xor(s[r], o); }
	v_lshlrev_b32_e32 v0, 16, v128
	v_and_b32_e32 v1, 0xffff0000, v128
	v_lshlrev_b32_e32 v2, 16, v129
	v_and_b32_e32 v3, 0xffff0000, v129
	v_lshlrev_b32_e32 v4, 16, v130
	v_and_b32_e32 v5, 0xffff0000, v130
	v_lshlrev_b32_e32 v6, 16, v131
	v_and_b32_e32 v7, 0xffff0000, v131
	v_lshlrev_b32_e32 v8, 16, v132
	v_and_b32_e32 v9, 0xffff0000, v132
	v_lshlrev_b32_e32 v10, 16, v133
	v_and_b32_e32 v11, 0xffff0000, v133
	v_lshlrev_b32_e32 v12, 16, v134
	v_and_b32_e32 v13, 0xffff0000, v134
	v_lshlrev_b32_e32 v14, 16, v135
	v_and_b32_e32 v15, 0xffff0000, v135
	v_lshlrev_b32_e32 v16, 16, v136
	v_and_b32_e32 v17, 0xffff0000, v136
	v_lshlrev_b32_e32 v18, 16, v137
	v_and_b32_e32 v19, 0xffff0000, v137
	v_lshlrev_b32_e32 v20, 16, v138
	v_and_b32_e32 v21, 0xffff0000, v138
	v_lshlrev_b32_e32 v22, 16, v139
	v_and_b32_e32 v23, 0xffff0000, v139
	v_lshlrev_b32_e32 v24, 16, v140
	v_and_b32_e32 v25, 0xffff0000, v140
	v_lshlrev_b32_e32 v26, 16, v141
	v_and_b32_e32 v27, 0xffff0000, v141
	v_lshlrev_b32_e32 v28, 16, v142
	v_and_b32_e32 v29, 0xffff0000, v142
	v_lshlrev_b32_e32 v30, 16, v143
	v_and_b32_e32 v31, 0xffff0000, v143
	v_lshlrev_b32_e32 v32, 16, v144
	v_and_b32_e32 v33, 0xffff0000, v144
	v_lshlrev_b32_e32 v34, 16, v145
	v_and_b32_e32 v35, 0xffff0000, v145
	v_lshlrev_b32_e32 v36, 16, v146
	v_and_b32_e32 v37, 0xffff0000, v146
	v_lshlrev_b32_e32 v38, 16, v147
	v_and_b32_e32 v39, 0xffff0000, v147
	v_lshlrev_b32_e32 v40, 16, v148
	v_and_b32_e32 v41, 0xffff0000, v148
	v_lshlrev_b32_e32 v42, 16, v149
	v_and_b32_e32 v43, 0xffff0000, v149
	v_lshlrev_b32_e32 v44, 16, v150
	v_and_b32_e32 v45, 0xffff0000, v150
	v_lshlrev_b32_e32 v46, 16, v151
	v_and_b32_e32 v47, 0xffff0000, v151
	v_lshlrev_b32_e32 v48, 16, v152
	v_and_b32_e32 v49, 0xffff0000, v152
	v_lshlrev_b32_e32 v50, 16, v153
	v_and_b32_e32 v51, 0xffff0000, v153
	v_lshlrev_b32_e32 v52, 16, v154
	v_and_b32_e32 v53, 0xffff0000, v154
	v_lshlrev_b32_e32 v54, 16, v155
	v_and_b32_e32 v55, 0xffff0000, v155
	v_lshlrev_b32_e32 v56, 16, v156
	v_and_b32_e32 v57, 0xffff0000, v156
	v_lshlrev_b32_e32 v58, 16, v157
	v_and_b32_e32 v59, 0xffff0000, v157
	v_lshlrev_b32_e32 v60, 16, v158
	v_and_b32_e32 v61, 0xffff0000, v158
	v_lshlrev_b32_e32 v62, 16, v159
	v_and_b32_e32 v63, 0xffff0000, v159
	v_pk_mul_f32 v[240:241], v[0:1], v[0:1]
	v_pk_mul_f32 v[242:243], v[16:17], v[16:17]
	v_pk_mul_f32 v[244:245], v[32:33], v[32:33]
	v_pk_mul_f32 v[246:247], v[48:49], v[48:49]
	v_pk_fma_f32 v[240:241], v[2:3], v[2:3], v[240:241]
	v_pk_fma_f32 v[242:243], v[18:19], v[18:19], v[242:243]
	v_pk_fma_f32 v[244:245], v[34:35], v[34:35], v[244:245]
	v_pk_fma_f32 v[246:247], v[50:51], v[50:51], v[246:247]
	v_pk_fma_f32 v[240:241], v[4:5], v[4:5], v[240:241]
	v_pk_fma_f32 v[242:243], v[20:21], v[20:21], v[242:243]
	v_pk_fma_f32 v[244:245], v[36:37], v[36:37], v[244:245]
	v_pk_fma_f32 v[246:247], v[52:53], v[52:53], v[246:247]
	v_pk_fma_f32 v[240:241], v[6:7], v[6:7], v[240:241]
	v_pk_fma_f32 v[242:243], v[22:23], v[22:23], v[242:243]
	v_pk_fma_f32 v[244:245], v[38:39], v[38:39], v[244:245]
	v_pk_fma_f32 v[246:247], v[54:55], v[54:55], v[246:247]
	v_pk_fma_f32 v[240:241], v[8:9], v[8:9], v[240:241]
	v_pk_fma_f32 v[242:243], v[24:25], v[24:25], v[242:243]
	v_pk_fma_f32 v[244:245], v[40:41], v[40:41], v[244:245]
	v_pk_fma_f32 v[246:247], v[56:57], v[56:57], v[246:247]
	v_pk_fma_f32 v[240:241], v[10:11], v[10:11], v[240:241]
	v_pk_fma_f32 v[242:243], v[26:27], v[26:27], v[242:243]
	v_pk_fma_f32 v[244:245], v[42:43], v[42:43], v[244:245]
	v_pk_fma_f32 v[246:247], v[58:59], v[58:59], v[246:247]
	v_pk_fma_f32 v[240:241], v[12:13], v[12:13], v[240:241]
	v_pk_fma_f32 v[242:243], v[28:29], v[28:29], v[242:243]
	v_pk_fma_f32 v[244:245], v[44:45], v[44:45], v[244:245]
	v_pk_fma_f32 v[246:247], v[60:61], v[60:61], v[246:247]
	v_pk_fma_f32 v[240:241], v[14:15], v[14:15], v[240:241]
	v_pk_fma_f32 v[242:243], v[30:31], v[30:31], v[242:243]
	v_pk_fma_f32 v[244:245], v[46:47], v[46:47], v[244:245]
	v_pk_fma_f32 v[246:247], v[62:63], v[62:63], v[246:247]
	v_add_f32_e32 v224, v240, v241
	v_add_f32_e32 v225, v242, v243
	v_add_f32_e32 v226, v244, v245
	v_add_f32_e32 v227, v246, v247
	ds_bpermute_b32 v228, v83, v224
	ds_bpermute_b32 v229, v83, v225
	ds_bpermute_b32 v230, v83, v226
	ds_bpermute_b32 v231, v83, v227
	s_waitcnt lgkmcnt(0)
	v_add_f32_e32 v224, v224, v228
	v_add_f32_e32 v225, v225, v229
	v_add_f32_e32 v226, v226, v230
	v_add_f32_e32 v227, v227, v231
	ds_bpermute_b32 v228, v84, v224
	ds_bpermute_b32 v229, v84, v225
	ds_bpermute_b32 v230, v84, v226
	ds_bpermute_b32 v231, v84, v227
	s_waitcnt lgkmcnt(0)
	v_add_f32_e32 v224, v224, v228
	v_add_f32_e32 v225, v225, v229
	v_add_f32_e32 v226, v226, v230
	v_add_f32_e32 v227, v227, v231
	ds_bpermute_b32 v228, v85, v224
	ds_bpermute_b32 v229, v85, v225
	ds_bpermute_b32 v230, v85, v226
	ds_bpermute_b32 v231, v85, v227
	s_waitcnt lgkmcnt(0)
	v_add_f32_e32 v224, v224, v228
	v_add_f32_e32 v225, v225, v229
	v_add_f32_e32 v226, v226, v230
	v_add_f32_e32 v227, v227, v231
	ds_bpermute_b32 v228, v86, v224
	ds_bpermute_b32 v229, v86, v225
	ds_bpermute_b32 v230, v86, v226
	ds_bpermute_b32 v231, v86, v227
	s_waitcnt lgkmcnt(0)
	v_add_f32_e32 v224, v224, v228
	v_add_f32_e32 v225, v225, v229
	v_add_f32_e32 v226, v226, v230
	v_add_f32_e32 v227, v227, v231
	ds_bpermute_b32 v228, v87, v224
	ds_bpermute_b32 v229, v87, v225
	ds_bpermute_b32 v230, v87, v226
	ds_bpermute_b32 v231, v87, v227
	s_waitcnt lgkmcnt(0)
	v_add_f32_e32 v224, v224, v228
	v_add_f32_e32 v225, v225, v229
	v_add_f32_e32 v226, v226, v230
	v_add_f32_e32 v227, v227, v231
	ds_bpermute_b32 v228, v88, v224
	ds_bpermute_b32 v229, v88, v225
	ds_bpermute_b32 v230, v88, v226
	ds_bpermute_b32 v231, v88, v227
	s_waitcnt lgkmcnt(0)
; template <bool BF> __device__ __forceinline__ void prep_rows(const float* xp, const float* xs, const bf16* hb, const float* g, const float* MOD, int shoff, int scoff, bf16* U, int gw, int NGW, int lane) {
;     ...
;             const float rstd = 1.0f / sqrtf(s[r] * (1.0f / DM) + RMS_EPS);
	v_add_f32_e32 v224, v224, v228
	v_add_f32_e32 v225, v225, v229
	v_add_f32_e32 v226, v226, v230
	v_add_f32_e32 v227, v227, v231
	v_fmamk_f32 v240, v224, 0x3a800000, v89
	v_mul_f32_e32 v241, 0x4f800000, v240
	v_cmp_gt_f32_e32 vcc, s54, v240
	s_nop 1
	v_cndmask_b32_e32 v247, v240, v241, vcc
	v_sqrt_f32_e32 v242, v247
	s_nop 1
	v_add_u32_e32 v243, -1, v242
	v_add_u32_e32 v244, 1, v242
	v_fma_f32 v245, -v243, v242, v247
	v_fma_f32 v246, -v244, v242, v247
	v_cmp_ge_f32_e64 s[52:53], 0, v245
	s_nop 1
	v_cndmask_b32_e64 v242, v242, v243, s[52:53]
	v_cmp_lt_f32_e64 s[52:53], 0, v246
	s_nop 1
	v_cndmask_b32_e64 v242, v242, v244, s[52:53]
	v_mul_f32_e32 v243, 0x37800000, v242
	v_cndmask_b32_e32 v242, v242, v243, vcc
	v_cmp_class_f32_e32 vcc, v247, v90
	s_nop 1
	v_cndmask_b32_e32 v247, v242, v247, vcc
	v_div_scale_f32 v248, s[52:53], v247, v247, 1.0
	v_rcp_f32_e32 v249, v248
	v_div_scale_f32 v228, vcc, 1.0, v247, 1.0
	s_nop 0
	v_fma_f32 v229, -v248, v249, 1.0
	v_fmac_f32_e32 v249, v229, v249
	v_mul_f32_e32 v230, v228, v249
	v_fma_f32 v229, -v248, v230, v228
	v_fmac_f32_e32 v230, v229, v249
	v_fma_f32 v248, -v248, v230, v228
	v_div_fmas_f32 v248, v248, v249, v230
	v_div_fixup_f32 v232, v248, v247, 1.0
	v_fmamk_f32 v240, v225, 0x3a800000, v89
	v_mul_f32_e32 v241, 0x4f800000, v240
	v_cmp_gt_f32_e32 vcc, s54, v240
	s_nop 1
	v_cndmask_b32_e32 v247, v240, v241, vcc
	v_sqrt_f32_e32 v242, v247
	s_nop 1
	v_add_u32_e32 v243, -1, v242
	v_add_u32_e32 v244, 1, v242
	v_fma_f32 v245, -v243, v242, v247
	v_fma_f32 v246, -v244, v242, v247
	v_cmp_ge_f32_e64 s[52:53], 0, v245
	s_nop 1
	v_cndmask_b32_e64 v242, v242, v243, s[52:53]
	v_cmp_lt_f32_e64 s[52:53], 0, v246
	s_nop 1
	v_cndmask_b32_e64 v242, v242, v244, s[52:53]
	v_mul_f32_e32 v243, 0x37800000, v242
	v_cndmask_b32_e32 v242, v242, v243, vcc
	v_cmp_class_f32_e32 vcc, v247, v90
	s_nop 1
	v_cndmask_b32_e32 v247, v242, v247, vcc
	v_div_scale_f32 v248, s[52:53], v247, v247, 1.0
	v_rcp_f32_e32 v249, v248
	v_div_scale_f32 v228, vcc, 1.0, v247, 1.0
	s_nop 0
	v_fma_f32 v229, -v248, v249, 1.0
	v_fmac_f32_e32 v249, v229, v249
	v_mul_f32_e32 v230, v228, v249
	v_fma_f32 v229, -v248, v230, v228
	v_fmac_f32_e32 v230, v229, v249
	v_fma_f32 v248, -v248, v230, v228
	v_div_fmas_f32 v248, v248, v249, v230
	v_div_fixup_f32 v234, v248, v247, 1.0
	v_fmamk_f32 v240, v226, 0x3a800000, v89
	v_mul_f32_e32 v241, 0x4f800000, v240
	v_cmp_gt_f32_e32 vcc, s54, v240
	s_nop 1
	v_cndmask_b32_e32 v247, v240, v241, vcc
	v_sqrt_f32_e32 v242, v247
	s_nop 1
	v_add_u32_e32 v243, -1, v242
	v_add_u32_e32 v244, 1, v242
	v_fma_f32 v245, -v243, v242, v247
	v_fma_f32 v246, -v244, v242, v247
	v_cmp_ge_f32_e64 s[52:53], 0, v245
	s_nop 1
	v_cndmask_b32_e64 v242, v242, v243, s[52:53]
	v_cmp_lt_f32_e64 s[52:53], 0, v246
	s_nop 1
	v_cndmask_b32_e64 v242, v242, v244, s[52:53]
	v_mul_f32_e32 v243, 0x37800000, v242
	v_cndmask_b32_e32 v242, v242, v243, vcc
	v_cmp_class_f32_e32 vcc, v247, v90
	s_nop 1
	v_cndmask_b32_e32 v247, v242, v247, vcc
	v_div_scale_f32 v248, s[52:53], v247, v247, 1.0
	v_rcp_f32_e32 v249, v248
	v_div_scale_f32 v228, vcc, 1.0, v247, 1.0
	s_nop 0
	v_fma_f32 v229, -v248, v249, 1.0
	v_fmac_f32_e32 v249, v229, v249
	v_mul_f32_e32 v230, v228, v249
	v_fma_f32 v229, -v248, v230, v228
	v_fmac_f32_e32 v230, v229, v249
	v_fma_f32 v248, -v248, v230, v228
	v_div_fmas_f32 v248, v248, v249, v230
	v_div_fixup_f32 v236, v248, v247, 1.0
	v_fmamk_f32 v240, v227, 0x3a800000, v89
	v_mul_f32_e32 v241, 0x4f800000, v240
	v_cmp_gt_f32_e32 vcc, s54, v240
	s_nop 1
	v_cndmask_b32_e32 v247, v240, v241, vcc
	v_sqrt_f32_e32 v242, v247
	s_nop 1
	v_add_u32_e32 v243, -1, v242
	v_add_u32_e32 v244, 1, v242
	v_fma_f32 v245, -v243, v242, v247
	v_fma_f32 v246, -v244, v242, v247
	v_cmp_ge_f32_e64 s[52:53], 0, v245
	s_nop 1
	v_cndmask_b32_e64 v242, v242, v243, s[52:53]
	v_cmp_lt_f32_e64 s[52:53], 0, v246
	s_nop 1
	v_cndmask_b32_e64 v242, v242, v244, s[52:53]
	v_mul_f32_e32 v243, 0x37800000, v242
	v_cndmask_b32_e32 v242, v242, v243, vcc
	v_cmp_class_f32_e32 vcc, v247, v90
	s_nop 1
	v_cndmask_b32_e32 v247, v242, v247, vcc
	v_div_scale_f32 v248, s[52:53], v247, v247, 1.0
	v_rcp_f32_e32 v249, v248
	v_div_scale_f32 v228, vcc, 1.0, v247, 1.0
	s_nop 0
	v_fma_f32 v229, -v248, v249, 1.0
	v_fmac_f32_e32 v249, v229, v249
	v_mul_f32_e32 v230, v228, v249
	v_fma_f32 v229, -v248, v230, v228
	v_fmac_f32_e32 v230, v229, v249
	v_fma_f32 v248, -v248, v230, v228
	v_div_fmas_f32 v248, v248, v249, v230
	v_div_fixup_f32 v238, v248, v247, 1.0
	s_waitcnt vmcnt(8)
; __device__ __forceinline__ unsigned pk2(float lo, float hi) { return pg8::cvt_pk_bf16(lo, hi); }
; template <bool BF> __device__ __forceinline__ void prep_rows(const float* xp, const float* xs, const bf16* hb, const float* g, const float* MOD, int shoff, int scoff, bf16* U, int gw, int NGW, int lane) {
;     ...
;         for (int r = 0; r < R; ++r) { const int m = mb + r * NGW; if (m < MT) {
;             const float rstd = 1.0f / sqrtf(s[r] * (1.0f / DM) + RMS_EPS);
;             const float* mr = MOD + (size_t)(m < MP ? (m >> 13) : 8 + ((m - MP) >> 12)) * 6144;
; #pragma unroll
;             for (int j = 0; j < 4; ++j) { const int c = 4 * lane + 256 * j;
;                 const f32x4 gg = *(const f32x4*)(g + c), sc = *(const f32x4*)(mr + scoff + c), sh = *(const f32x4*)(mr + shoff + c);
;                 const f32x4 o = v[r][j] * rstd * gg * (sc + 1.0f) + sh; v2u w; w.x = pk2(o.x, o.y); w.y = pk2(o.z, o.w); *(v2u*)(U + (size_t)m * DM + c) = w; } } }
	v_pk_add_f32 v[160:161], v[160:161], 1.0 op_sel_hi:[1,0]
	v_pk_add_f32 v[162:163], v[162:163], 1.0 op_sel_hi:[1,0]
	v_pk_add_f32 v[164:165], v[164:165], 1.0 op_sel_hi:[1,0]
	v_pk_add_f32 v[166:167], v[166:167], 1.0 op_sel_hi:[1,0]
	v_pk_add_f32 v[168:169], v[168:169], 1.0 op_sel_hi:[1,0]
	v_pk_add_f32 v[170:171], v[170:171], 1.0 op_sel_hi:[1,0]
	v_pk_add_f32 v[172:173], v[172:173], 1.0 op_sel_hi:[1,0]
	v_pk_add_f32 v[174:175], v[174:175], 1.0 op_sel_hi:[1,0]
	v_pk_add_f32 v[192:193], v[192:193], 1.0 op_sel_hi:[1,0]
	v_pk_add_f32 v[194:195], v[194:195], 1.0 op_sel_hi:[1,0]
	v_pk_add_f32 v[196:197], v[196:197], 1.0 op_sel_hi:[1,0]
	v_pk_add_f32 v[198:199], v[198:199], 1.0 op_sel_hi:[1,0]
	v_pk_add_f32 v[200:201], v[200:201], 1.0 op_sel_hi:[1,0]
	v_pk_add_f32 v[202:203], v[202:203], 1.0 op_sel_hi:[1,0]
	v_pk_add_f32 v[204:205], v[204:205], 1.0 op_sel_hi:[1,0]
	v_pk_add_f32 v[206:207], v[206:207], 1.0 op_sel_hi:[1,0]
	s_add_u32 s38, s20, 0x3000000
	s_addc_u32 s39, s21, 0
	s_add_u32 s40, s20, 0x3400000
	s_addc_u32 s41, s21, 0
	s_add_u32 s46, s20, 0x3800000
	s_addc_u32 s47, s21, 0
	s_add_u32 s48, s20, 0x3c00000
	s_addc_u32 s49, s21, 0
	v_pk_mul_f32 v[0:1], v[0:1], v[232:233] op_sel_hi:[1,0]
	v_pk_mul_f32 v[2:3], v[2:3], v[232:233] op_sel_hi:[1,0]
	v_pk_mul_f32 v[0:1], v[64:65], v[0:1]
	v_pk_mul_f32 v[2:3], v[66:67], v[2:3]
	v_pk_fma_f32 v[0:1], v[160:161], v[0:1], v[176:177]
	v_pk_fma_f32 v[2:3], v[162:163], v[2:3], v[178:179]
	v_cvt_pk_bf16_f32 v244, v0, v1
	v_cvt_pk_bf16_f32 v245, v2, v3
	v_pk_mul_f32 v[4:5], v[4:5], v[232:233] op_sel_hi:[1,0]
	v_pk_mul_f32 v[6:7], v[6:7], v[232:233] op_sel_hi:[1,0]
	v_pk_mul_f32 v[4:5], v[68:69], v[4:5]
	v_pk_mul_f32 v[6:7], v[70:71], v[6:7]
	v_pk_fma_f32 v[4:5], v[164:165], v[4:5], v[180:181]
	v_pk_fma_f32 v[6:7], v[166:167], v[6:7], v[182:183]
	v_cvt_pk_bf16_f32 v246, v4, v5
	v_cvt_pk_bf16_f32 v247, v6, v7
	global_store_dwordx4 v82, v[244:247], s[38:39] offset:0
	v_pk_mul_f32 v[8:9], v[8:9], v[232:233] op_sel_hi:[1,0]
	v_pk_mul_f32 v[10:11], v[10:11], v[232:233] op_sel_hi:[1,0]
	v_pk_mul_f32 v[8:9], v[72:73], v[8:9]
	v_pk_mul_f32 v[10:11], v[74:75], v[10:11]
	v_pk_fma_f32 v[8:9], v[168:169], v[8:9], v[184:185]
	v_pk_fma_f32 v[10:11], v[170:171], v[10:11], v[186:187]
	v_cvt_pk_bf16_f32 v240, v8, v9
	v_cvt_pk_bf16_f32 v241, v10, v11
	v_pk_mul_f32 v[12:13], v[12:13], v[232:233] op_sel_hi:[1,0]
	v_pk_mul_f32 v[14:15], v[14:15], v[232:233] op_sel_hi:[1,0]
	v_pk_mul_f32 v[12:13], v[76:77], v[12:13]
	v_pk_mul_f32 v[14:15], v[78:79], v[14:15]
	v_pk_fma_f32 v[12:13], v[172:173], v[12:13], v[188:189]
	v_pk_fma_f32 v[14:15], v[174:175], v[14:15], v[190:191]
	v_cvt_pk_bf16_f32 v242, v12, v13
	v_cvt_pk_bf16_f32 v243, v14, v15
	global_store_dwordx4 v82, v[240:243], s[38:39] offset:1024
	v_pk_mul_f32 v[16:17], v[16:17], v[234:235] op_sel_hi:[1,0]
	v_pk_mul_f32 v[18:19], v[18:19], v[234:235] op_sel_hi:[1,0]
	v_pk_mul_f32 v[16:17], v[64:65], v[16:17]
	v_pk_mul_f32 v[18:19], v[66:67], v[18:19]
	v_pk_fma_f32 v[16:17], v[160:161], v[16:17], v[176:177]
	v_pk_fma_f32 v[18:19], v[162:163], v[18:19], v[178:179]
	v_cvt_pk_bf16_f32 v244, v16, v17
	v_cvt_pk_bf16_f32 v245, v18, v19
	v_pk_mul_f32 v[20:21], v[20:21], v[234:235] op_sel_hi:[1,0]
	v_pk_mul_f32 v[22:23], v[22:23], v[234:235] op_sel_hi:[1,0]
	v_pk_mul_f32 v[20:21], v[68:69], v[20:21]
	v_pk_mul_f32 v[22:23], v[70:71], v[22:23]
	v_pk_fma_f32 v[20:21], v[164:165], v[20:21], v[180:181]
	v_pk_fma_f32 v[22:23], v[166:167], v[22:23], v[182:183]
	v_cvt_pk_bf16_f32 v246, v20, v21
	v_cvt_pk_bf16_f32 v247, v22, v23
	global_store_dwordx4 v82, v[244:247], s[40:41] offset:0
	v_pk_mul_f32 v[24:25], v[24:25], v[234:235] op_sel_hi:[1,0]
	v_pk_mul_f32 v[26:27], v[26:27], v[234:235] op_sel_hi:[1,0]
	v_pk_mul_f32 v[24:25], v[72:73], v[24:25]
	v_pk_mul_f32 v[26:27], v[74:75], v[26:27]
	v_pk_fma_f32 v[24:25], v[168:169], v[24:25], v[184:185]
	v_pk_fma_f32 v[26:27], v[170:171], v[26:27], v[186:187]
	v_cvt_pk_bf16_f32 v240, v24, v25
	v_cvt_pk_bf16_f32 v241, v26, v27
	v_pk_mul_f32 v[28:29], v[28:29], v[234:235] op_sel_hi:[1,0]
	v_pk_mul_f32 v[30:31], v[30:31], v[234:235] op_sel_hi:[1,0]
	v_pk_mul_f32 v[28:29], v[76:77], v[28:29]
	v_pk_mul_f32 v[30:31], v[78:79], v[30:31]
	v_pk_fma_f32 v[28:29], v[172:173], v[28:29], v[188:189]
	v_pk_fma_f32 v[30:31], v[174:175], v[30:31], v[190:191]
	v_cvt_pk_bf16_f32 v242, v28, v29
	v_cvt_pk_bf16_f32 v243, v30, v31
	global_store_dwordx4 v82, v[240:243], s[40:41] offset:1024
	v_pk_mul_f32 v[32:33], v[32:33], v[236:237] op_sel_hi:[1,0]
	v_pk_mul_f32 v[34:35], v[34:35], v[236:237] op_sel_hi:[1,0]
	v_pk_mul_f32 v[32:33], v[64:65], v[32:33]
	v_pk_mul_f32 v[34:35], v[66:67], v[34:35]
	v_pk_fma_f32 v[32:33], v[192:193], v[32:33], v[208:209]
	v_pk_fma_f32 v[34:35], v[194:195], v[34:35], v[210:211]
	v_cvt_pk_bf16_f32 v244, v32, v33
	v_cvt_pk_bf16_f32 v245, v34, v35
	v_pk_mul_f32 v[36:37], v[36:37], v[236:237] op_sel_hi:[1,0]
	v_pk_mul_f32 v[38:39], v[38:39], v[236:237] op_sel_hi:[1,0]
	v_pk_mul_f32 v[36:37], v[68:69], v[36:37]
	v_pk_mul_f32 v[38:39], v[70:71], v[38:39]
	v_pk_fma_f32 v[36:37], v[196:197], v[36:37], v[212:213]
	v_pk_fma_f32 v[38:39], v[198:199], v[38:39], v[214:215]
	v_cvt_pk_bf16_f32 v246, v36, v37
	v_cvt_pk_bf16_f32 v247, v38, v39
	global_store_dwordx4 v82, v[244:247], s[46:47] offset:0
	v_pk_mul_f32 v[40:41], v[40:41], v[236:237] op_sel_hi:[1,0]
	v_pk_mul_f32 v[42:43], v[42:43], v[236:237] op_sel_hi:[1,0]
	v_pk_mul_f32 v[40:41], v[72:73], v[40:41]
	v_pk_mul_f32 v[42:43], v[74:75], v[42:43]
	v_pk_fma_f32 v[40:41], v[200:201], v[40:41], v[216:217]
	v_pk_fma_f32 v[42:43], v[202:203], v[42:43], v[218:219]
	v_cvt_pk_bf16_f32 v240, v40, v41
; __device__ __forceinline__ float bf_lo(unsigned w) { return __uint_as_float(w << 16); }
; __device__ __forceinline__ float bf_hi(unsigned w) { return __uint_as_float(w & 0xffff0000u); }
; __device__ __forceinline__ unsigned pk2(float lo, float hi) { return pg8::cvt_pk_bf16(lo, hi); }
; template <bool BF> __device__ __forceinline__ void prep_rows(const float* xp, const float* xs, const bf16* hb, const float* g, const float* MOD, int shoff, int scoff, bf16* U, int gw, int NGW, int lane) {
;     ...
;                 if (BF) { const v2u a0 = *(const v2u*)(hb + (size_t)mc * DM + 4 * lane + 256 * j);
;                     v[r][j].x = pg8::bf_lo(a0.x); v[r][j].y = pg8::bf_hi(a0.x); v[r][j].z = pg8::bf_lo(a0.y); v[r][j].w = pg8::bf_hi(a0.y); }
;                 else { const float* xr = mc < MP ? xp + (size_t)mc * DM : xs + (size_t)(mc - MP) * DM; v[r][j] = *(const f32x4*)(xr + 4 * lane + 256 * j); } } }
;     ...
;         for (int r = 0; r < R; ++r) { const int m = mb + r * NGW; if (m < MT) {
;             const float rstd = 1.0f / sqrtf(s[r] * (1.0f / DM) + RMS_EPS);
;             const float* mr = MOD + (size_t)(m < MP ? (m >> 13) : 8 + ((m - MP) >> 12)) * 6144;
; #pragma unroll
;             for (int j = 0; j < 4; ++j) { const int c = 4 * lane + 256 * j;
;                 const f32x4 gg = *(const f32x4*)(g + c), sc = *(const f32x4*)(mr + scoff + c), sh = *(const f32x4*)(mr + shoff + c);
;                 const f32x4 o = v[r][j] * rstd * gg * (sc + 1.0f) + sh; v2u w; w.x = pk2(o.x, o.y); w.y = pk2(o.z, o.w); *(v2u*)(U + (size_t)m * DM + c) = w; } } }
	v_cvt_pk_bf16_f32 v241, v42, v43
	v_pk_mul_f32 v[44:45], v[44:45], v[236:237] op_sel_hi:[1,0]
	v_pk_mul_f32 v[46:47], v[46:47], v[236:237] op_sel_hi:[1,0]
	v_pk_mul_f32 v[44:45], v[76:77], v[44:45]
	v_pk_mul_f32 v[46:47], v[78:79], v[46:47]
	v_pk_fma_f32 v[44:45], v[204:205], v[44:45], v[220:221]
	v_pk_fma_f32 v[46:47], v[206:207], v[46:47], v[222:223]
	v_cvt_pk_bf16_f32 v242, v44, v45
	v_cvt_pk_bf16_f32 v243, v46, v47
	global_store_dwordx4 v82, v[240:243], s[46:47] offset:1024
	v_pk_mul_f32 v[48:49], v[48:49], v[238:239] op_sel_hi:[1,0]
	v_pk_mul_f32 v[50:51], v[50:51], v[238:239] op_sel_hi:[1,0]
	v_pk_mul_f32 v[48:49], v[64:65], v[48:49]
	v_pk_mul_f32 v[50:51], v[66:67], v[50:51]
	v_pk_fma_f32 v[48:49], v[192:193], v[48:49], v[208:209]
	v_pk_fma_f32 v[50:51], v[194:195], v[50:51], v[210:211]
	v_cvt_pk_bf16_f32 v244, v48, v49
	v_cvt_pk_bf16_f32 v245, v50, v51
	v_pk_mul_f32 v[52:53], v[52:53], v[238:239] op_sel_hi:[1,0]
	v_pk_mul_f32 v[54:55], v[54:55], v[238:239] op_sel_hi:[1,0]
	v_pk_mul_f32 v[52:53], v[68:69], v[52:53]
	v_pk_mul_f32 v[54:55], v[70:71], v[54:55]
	v_pk_fma_f32 v[52:53], v[196:197], v[52:53], v[212:213]
	v_pk_fma_f32 v[54:55], v[198:199], v[54:55], v[214:215]
	v_cvt_pk_bf16_f32 v246, v52, v53
	v_cvt_pk_bf16_f32 v247, v54, v55
	global_store_dwordx4 v82, v[244:247], s[48:49] offset:0
	v_pk_mul_f32 v[56:57], v[56:57], v[238:239] op_sel_hi:[1,0]
	v_pk_mul_f32 v[58:59], v[58:59], v[238:239] op_sel_hi:[1,0]
	v_pk_mul_f32 v[56:57], v[72:73], v[56:57]
	v_pk_mul_f32 v[58:59], v[74:75], v[58:59]
	v_pk_fma_f32 v[56:57], v[200:201], v[56:57], v[216:217]
	v_pk_fma_f32 v[58:59], v[202:203], v[58:59], v[218:219]
	v_cvt_pk_bf16_f32 v240, v56, v57
	v_cvt_pk_bf16_f32 v241, v58, v59
	v_pk_mul_f32 v[60:61], v[60:61], v[238:239] op_sel_hi:[1,0]
	v_pk_mul_f32 v[62:63], v[62:63], v[238:239] op_sel_hi:[1,0]
	v_pk_mul_f32 v[60:61], v[76:77], v[60:61]
	v_pk_mul_f32 v[62:63], v[78:79], v[62:63]
	v_pk_fma_f32 v[60:61], v[204:205], v[60:61], v[220:221]
	v_pk_fma_f32 v[62:63], v[206:207], v[62:63], v[222:223]
	v_cvt_pk_bf16_f32 v242, v60, v61
	v_cvt_pk_bf16_f32 v243, v62, v63
	global_store_dwordx4 v82, v[240:243], s[48:49] offset:1024
	s_add_u32 s34, s8, 0x1b000
	s_addc_u32 s35, s9, 0
	s_add_u32 s36, s8, 0x1b000
	s_addc_u32 s37, s9, 0
	global_load_dwordx4 v[176:179], v80, s[34:35] offset:0
	global_load_dwordx4 v[180:183], v80, s[34:35] offset:16
	global_load_dwordx4 v[184:187], v80, s[34:35] offset:2048
	global_load_dwordx4 v[188:191], v80, s[34:35] offset:2064
	global_load_dwordx4 v[160:163], v81, s[34:35] offset:0
	global_load_dwordx4 v[164:167], v81, s[34:35] offset:16
	global_load_dwordx4 v[168:171], v81, s[34:35] offset:2048
	global_load_dwordx4 v[172:175], v81, s[34:35] offset:2064
	global_load_dwordx4 v[208:211], v80, s[36:37] offset:0
	global_load_dwordx4 v[212:215], v80, s[36:37] offset:16
	global_load_dwordx4 v[216:219], v80, s[36:37] offset:2048
	global_load_dwordx4 v[220:223], v80, s[36:37] offset:2064
	global_load_dwordx4 v[192:195], v81, s[36:37] offset:0
	global_load_dwordx4 v[196:199], v81, s[36:37] offset:16
	global_load_dwordx4 v[200:203], v81, s[36:37] offset:2048
	global_load_dwordx4 v[204:207], v81, s[36:37] offset:2064
	s_add_u32 s24, s16, 0x5000000
	s_addc_u32 s25, s17, 0
	s_add_u32 s26, s16, 0x5400000
	s_addc_u32 s27, s17, 0
	s_add_u32 s28, s16, 0x5800000
	s_addc_u32 s29, s17, 0
	s_add_u32 s30, s16, 0x5c00000
	s_addc_u32 s31, s17, 0
	global_load_dwordx4 v[128:131], v82, s[24:25] offset:0
	global_load_dwordx4 v[132:135], v82, s[24:25] offset:1024
	global_load_dwordx4 v[136:139], v82, s[26:27] offset:0
	global_load_dwordx4 v[140:143], v82, s[26:27] offset:1024
	global_load_dwordx4 v[144:147], v82, s[28:29] offset:0
	global_load_dwordx4 v[148:151], v82, s[28:29] offset:1024
	global_load_dwordx4 v[152:155], v82, s[30:31] offset:0
	global_load_dwordx4 v[156:159], v82, s[30:31] offset:1024
	s_waitcnt vmcnt(32)
	v_lshlrev_b32_e32 v0, 16, v96
	v_and_b32_e32 v1, 0xffff0000, v96
	v_lshlrev_b32_e32 v2, 16, v97
	v_and_b32_e32 v3, 0xffff0000, v97
	v_lshlrev_b32_e32 v4, 16, v98
	v_and_b32_e32 v5, 0xffff0000, v98
	v_lshlrev_b32_e32 v6, 16, v99
	v_and_b32_e32 v7, 0xffff0000, v99
	v_lshlrev_b32_e32 v8, 16, v100
	v_and_b32_e32 v9, 0xffff0000, v100
	v_lshlrev_b32_e32 v10, 16, v101
	v_and_b32_e32 v11, 0xffff0000, v101
	v_lshlrev_b32_e32 v12, 16, v102
	v_and_b32_e32 v13, 0xffff0000, v102
	v_lshlrev_b32_e32 v14, 16, v103
	v_and_b32_e32 v15, 0xffff0000, v103
	v_lshlrev_b32_e32 v16, 16, v104
	v_and_b32_e32 v17, 0xffff0000, v104
	v_lshlrev_b32_e32 v18, 16, v105
	v_and_b32_e32 v19, 0xffff0000, v105
	v_lshlrev_b32_e32 v20, 16, v106
	v_and_b32_e32 v21, 0xffff0000, v106
	v_lshlrev_b32_e32 v22, 16, v107
	v_and_b32_e32 v23, 0xffff0000, v107
	v_lshlrev_b32_e32 v24, 16, v108
	v_and_b32_e32 v25, 0xffff0000, v108
	v_lshlrev_b32_e32 v26, 16, v109
	v_and_b32_e32 v27, 0xffff0000, v109
	v_lshlrev_b32_e32 v28, 16, v110
	v_and_b32_e32 v29, 0xffff0000, v110
	v_lshlrev_b32_e32 v30, 16, v111
	v_and_b32_e32 v31, 0xffff0000, v111
	v_lshlrev_b32_e32 v32, 16, v112
	v_and_b32_e32 v33, 0xffff0000, v112
	v_lshlrev_b32_e32 v34, 16, v113
	v_and_b32_e32 v35, 0xffff0000, v113
	v_lshlrev_b32_e32 v36, 16, v114
	v_and_b32_e32 v37, 0xffff0000, v114
	v_lshlrev_b32_e32 v38, 16, v115
	v_and_b32_e32 v39, 0xffff0000, v115
	v_lshlrev_b32_e32 v40, 16, v116
	v_and_b32_e32 v41, 0xffff0000, v116
	v_lshlrev_b32_e32 v42, 16, v117
	v_and_b32_e32 v43, 0xffff0000, v117
	v_lshlrev_b32_e32 v44, 16, v118
	v_and_b32_e32 v45, 0xffff0000, v118
	v_lshlrev_b32_e32 v46, 16, v119
	v_and_b32_e32 v47, 0xffff0000, v119
	v_lshlrev_b32_e32 v48, 16, v120
	v_and_b32_e32 v49, 0xffff0000, v120
	v_lshlrev_b32_e32 v50, 16, v121
	v_and_b32_e32 v51, 0xffff0000, v121
	v_lshlrev_b32_e32 v52, 16, v122
	v_and_b32_e32 v53, 0xffff0000, v122
	v_lshlrev_b32_e32 v54, 16, v123
	v_and_b32_e32 v55, 0xffff0000, v123
	v_lshlrev_b32_e32 v56, 16, v124
	v_and_b32_e32 v57, 0xffff0000, v124
	v_lshlrev_b32_e32 v58, 16, v125
	v_and_b32_e32 v59, 0xffff0000, v125
	v_lshlrev_b32_e32 v60, 16, v126
	v_and_b32_e32 v61, 0xffff0000, v126
	v_lshlrev_b32_e32 v62, 16, v127
	v_and_b32_e32 v63, 0xffff0000, v127
	v_pk_mul_f32 v[240:241], v[0:1], v[0:1]
	v_pk_mul_f32 v[242:243], v[16:17], v[16:17]
	v_pk_mul_f32 v[244:245], v[32:33], v[32:33]
	v_pk_mul_f32 v[246:247], v[48:49], v[48:49]
	v_pk_fma_f32 v[240:241], v[2:3], v[2:3], v[240:241]
	v_pk_fma_f32 v[242:243], v[18:19], v[18:19], v[242:243]
	v_pk_fma_f32 v[244:245], v[34:35], v[34:35], v[244:245]
	v_pk_fma_f32 v[246:247], v[50:51], v[50:51], v[246:247]
	v_pk_fma_f32 v[240:241], v[4:5], v[4:5], v[240:241]
	v_pk_fma_f32 v[242:243], v[20:21], v[20:21], v[242:243]
	v_pk_fma_f32 v[244:245], v[36:37], v[36:37], v[244:245]
	v_pk_fma_f32 v[246:247], v[52:53], v[52:53], v[246:247]
	v_pk_fma_f32 v[240:241], v[6:7], v[6:7], v[240:241]
	v_pk_fma_f32 v[242:243], v[22:23], v[22:23], v[242:243]
	v_pk_fma_f32 v[244:245], v[38:39], v[38:39], v[244:245]
	v_pk_fma_f32 v[246:247], v[54:55], v[54:55], v[246:247]
	v_pk_fma_f32 v[240:241], v[8:9], v[8:9], v[240:241]
	v_pk_fma_f32 v[242:243], v[24:25], v[24:25], v[242:243]
	v_pk_fma_f32 v[244:245], v[40:41], v[40:41], v[244:245]
	v_pk_fma_f32 v[246:247], v[56:57], v[56:57], v[246:247]
	v_pk_fma_f32 v[240:241], v[10:11], v[10:11], v[240:241]
	v_pk_fma_f32 v[242:243], v[26:27], v[26:27], v[242:243]
	v_pk_fma_f32 v[244:245], v[42:43], v[42:43], v[244:245]
	v_pk_fma_f32 v[246:247], v[58:59], v[58:59], v[246:247]
	v_pk_fma_f32 v[240:241], v[12:13], v[12:13], v[240:241]
	v_pk_fma_f32 v[242:243], v[28:29], v[28:29], v[242:243]
	v_pk_fma_f32 v[244:245], v[44:45], v[44:45], v[244:245]
	v_pk_fma_f32 v[246:247], v[60:61], v[60:61], v[246:247]
	v_pk_fma_f32 v[240:241], v[14:15], v[14:15], v[240:241]
	v_pk_fma_f32 v[242:243], v[30:31], v[30:31], v[242:243]
	v_pk_fma_f32 v[244:245], v[46:47], v[46:47], v[244:245]
	v_pk_fma_f32 v[246:247], v[62:63], v[62:63], v[246:247]
	v_add_f32_e32 v224, v240, v241
	v_add_f32_e32 v225, v242, v243
	v_add_f32_e32 v226, v244, v245
	v_add_f32_e32 v227, v246, v247
	ds_bpermute_b32 v228, v83, v224
	ds_bpermute_b32 v229, v83, v225
	ds_bpermute_b32 v230, v83, v226
	ds_bpermute_b32 v231, v83, v227
	s_waitcnt lgkmcnt(0)
	v_add_f32_e32 v224, v224, v228
	v_add_f32_e32 v225, v225, v229
	v_add_f32_e32 v226, v226, v230
	v_add_f32_e32 v227, v227, v231
	ds_bpermute_b32 v228, v84, v224
	ds_bpermute_b32 v229, v84, v225
	ds_bpermute_b32 v230, v84, v226
	ds_bpermute_b32 v231, v84, v227
	s_waitcnt lgkmcnt(0)
	v_add_f32_e32 v224, v224, v228
	v_add_f32_e32 v225, v225, v229
	v_add_f32_e32 v226, v226, v230
	v_add_f32_e32 v227, v227, v231
	ds_bpermute_b32 v228, v85, v224
	ds_bpermute_b32 v229, v85, v225
	ds_bpermute_b32 v230, v85, v226
	ds_bpermute_b32 v231, v85, v227
	s_waitcnt lgkmcnt(0)
	v_add_f32_e32 v224, v224, v228
	v_add_f32_e32 v225, v225, v229
	v_add_f32_e32 v226, v226, v230
	v_add_f32_e32 v227, v227, v231
	ds_bpermute_b32 v228, v86, v224
	ds_bpermute_b32 v229, v86, v225
	ds_bpermute_b32 v230, v86, v226
	ds_bpermute_b32 v231, v86, v227
	s_waitcnt lgkmcnt(0)
	v_add_f32_e32 v224, v224, v228
	v_add_f32_e32 v225, v225, v229
	v_add_f32_e32 v226, v226, v230
	v_add_f32_e32 v227, v227, v231
	ds_bpermute_b32 v228, v87, v224
	ds_bpermute_b32 v229, v87, v225
	ds_bpermute_b32 v230, v87, v226
	ds_bpermute_b32 v231, v87, v227
	s_waitcnt lgkmcnt(0)
	v_add_f32_e32 v224, v224, v228
	v_add_f32_e32 v225, v225, v229
	v_add_f32_e32 v226, v226, v230
	v_add_f32_e32 v227, v227, v231
	ds_bpermute_b32 v228, v88, v224
	ds_bpermute_b32 v229, v88, v225
	ds_bpermute_b32 v230, v88, v226
	ds_bpermute_b32 v231, v88, v227
	s_waitcnt lgkmcnt(0)
	v_add_f32_e32 v224, v224, v228
	v_add_f32_e32 v225, v225, v229
	v_add_f32_e32 v226, v226, v230
	v_add_f32_e32 v227, v227, v231
	v_fmamk_f32 v240, v224, 0x3a800000, v89
	v_mul_f32_e32 v241, 0x4f800000, v240
	v_cmp_gt_f32_e32 vcc, s54, v240
	s_nop 1
	v_cndmask_b32_e32 v247, v240, v241, vcc
	v_sqrt_f32_e32 v242, v247
	s_nop 1
	v_add_u32_e32 v243, -1, v242
	v_add_u32_e32 v244, 1, v242
	v_fma_f32 v245, -v243, v242, v247
	v_fma_f32 v246, -v244, v242, v247
	v_cmp_ge_f32_e64 s[52:53], 0, v245
	s_nop 1
	v_cndmask_b32_e64 v242, v242, v243, s[52:53]
	v_cmp_lt_f32_e64 s[52:53], 0, v246
	s_nop 1
	v_cndmask_b32_e64 v242, v242, v244, s[52:53]
	v_mul_f32_e32 v243, 0x37800000, v242
	v_cndmask_b32_e32 v242, v242, v243, vcc
	v_cmp_class_f32_e32 vcc, v247, v90
	s_nop 1
	v_cndmask_b32_e32 v247, v242, v247, vcc
	v_div_scale_f32 v248, s[52:53], v247, v247, 1.0
	v_rcp_f32_e32 v249, v248
	v_div_scale_f32 v228, vcc, 1.0, v247, 1.0
	s_nop 0
	v_fma_f32 v229, -v248, v249, 1.0
	v_fmac_f32_e32 v249, v229, v249
	v_mul_f32_e32 v230, v228, v249
	v_fma_f32 v229, -v248, v230, v228
	v_fmac_f32_e32 v230, v229, v249
	v_fma_f32 v248, -v248, v230, v228
	v_div_fmas_f32 v248, v248, v249, v230
	v_div_fixup_f32 v232, v248, v247, 1.0
	v_fmamk_f32 v240, v225, 0x3a800000, v89
	v_mul_f32_e32 v241, 0x4f800000, v240
	v_cmp_gt_f32_e32 vcc, s54, v240
	s_nop 1
	v_cndmask_b32_e32 v247, v240, v241, vcc
	v_sqrt_f32_e32 v242, v247
	s_nop 1
	v_add_u32_e32 v243, -1, v242
	v_add_u32_e32 v244, 1, v242
	v_fma_f32 v245, -v243, v242, v247
	v_fma_f32 v246, -v244, v242, v247
	v_cmp_ge_f32_e64 s[52:53], 0, v245
	s_nop 1
	v_cndmask_b32_e64 v242, v242, v243, s[52:53]
	v_cmp_lt_f32_e64 s[52:53], 0, v246
	s_nop 1
	v_cndmask_b32_e64 v242, v242, v244, s[52:53]
	v_mul_f32_e32 v243, 0x37800000, v242
	v_cndmask_b32_e32 v242, v242, v243, vcc
	v_cmp_class_f32_e32 vcc, v247, v90
	s_nop 1
	v_cndmask_b32_e32 v247, v242, v247, vcc
	v_div_scale_f32 v248, s[52:53], v247, v247, 1.0
	v_rcp_f32_e32 v249, v248
	v_div_scale_f32 v228, vcc, 1.0, v247, 1.0
	s_nop 0
	v_fma_f32 v229, -v248, v249, 1.0
	v_fmac_f32_e32 v249, v229, v249
	v_mul_f32_e32 v230, v228, v249
	v_fma_f32 v229, -v248, v230, v228
	v_fmac_f32_e32 v230, v229, v249
	v_fma_f32 v248, -v248, v230, v228
	v_div_fmas_f32 v248, v248, v249, v230
	v_div_fixup_f32 v234, v248, v247, 1.0
	v_fmamk_f32 v240, v226, 0x3a800000, v89
	v_mul_f32_e32 v241, 0x4f800000, v240
	v_cmp_gt_f32_e32 vcc, s54, v240
	s_nop 1
	v_cndmask_b32_e32 v247, v240, v241, vcc
	v_sqrt_f32_e32 v242, v247
	s_nop 1
	v_add_u32_e32 v243, -1, v242
	v_add_u32_e32 v244, 1, v242
	v_fma_f32 v245, -v243, v242, v247
	v_fma_f32 v246, -v244, v242, v247
	v_cmp_ge_f32_e64 s[52:53], 0, v245
	s_nop 1
	v_cndmask_b32_e64 v242, v242, v243, s[52:53]
	v_cmp_lt_f32_e64 s[52:53], 0, v246
	s_nop 1
	v_cndmask_b32_e64 v242, v242, v244, s[52:53]
	v_mul_f32_e32 v243, 0x37800000, v242
	v_cndmask_b32_e32 v242, v242, v243, vcc
	v_cmp_class_f32_e32 vcc, v247, v90
	s_nop 1
	v_cndmask_b32_e32 v247, v242, v247, vcc
	v_div_scale_f32 v248, s[52:53], v247, v247, 1.0
	v_rcp_f32_e32 v249, v248
	v_div_scale_f32 v228, vcc, 1.0, v247, 1.0
	s_nop 0
	v_fma_f32 v229, -v248, v249, 1.0
	v_fmac_f32_e32 v249, v229, v249
	v_mul_f32_e32 v230, v228, v249
	v_fma_f32 v229, -v248, v230, v228
	v_fmac_f32_e32 v230, v229, v249
	v_fma_f32 v248, -v248, v230, v228
	v_div_fmas_f32 v248, v248, v249, v230
	v_div_fixup_f32 v236, v248, v247, 1.0
	v_fmamk_f32 v240, v227, 0x3a800000, v89
	v_mul_f32_e32 v241, 0x4f800000, v240
	v_cmp_gt_f32_e32 vcc, s54, v240
	s_nop 1
	v_cndmask_b32_e32 v247, v240, v241, vcc
	v_sqrt_f32_e32 v242, v247
	s_nop 1
	v_add_u32_e32 v243, -1, v242
	v_add_u32_e32 v244, 1, v242
	v_fma_f32 v245, -v243, v242, v247
	v_fma_f32 v246, -v244, v242, v247
	v_cmp_ge_f32_e64 s[52:53], 0, v245
	s_nop 1
	v_cndmask_b32_e64 v242, v242, v243, s[52:53]
	v_cmp_lt_f32_e64 s[52:53], 0, v246
	s_nop 1
	v_cndmask_b32_e64 v242, v242, v244, s[52:53]
	v_mul_f32_e32 v243, 0x37800000, v242
	v_cndmask_b32_e32 v242, v242, v243, vcc
	v_cmp_class_f32_e32 vcc, v247, v90
	s_nop 1
	v_cndmask_b32_e32 v247, v242, v247, vcc
	v_div_scale_f32 v248, s[52:53], v247, v247, 1.0
	v_rcp_f32_e32 v249, v248
	v_div_scale_f32 v228, vcc, 1.0, v247, 1.0
	s_nop 0
	v_fma_f32 v229, -v248, v249, 1.0
	v_fmac_f32_e32 v249, v229, v249
	v_mul_f32_e32 v230, v228, v249
	v_fma_f32 v229, -v248, v230, v228
	v_fmac_f32_e32 v230, v229, v249
	v_fma_f32 v248, -v248, v230, v228
	v_div_fmas_f32 v248, v248, v249, v230
	v_div_fixup_f32 v238, v248, v247, 1.0
	s_waitcnt vmcnt(8)
	v_pk_add_f32 v[160:161], v[160:161], 1.0 op_sel_hi:[1,0]
	v_pk_add_f32 v[162:163], v[162:163], 1.0 op_sel_hi:[1,0]
	v_pk_add_f32 v[164:165], v[164:165], 1.0 op_sel_hi:[1,0]
	v_pk_add_f32 v[166:167], v[166:167], 1.0 op_sel_hi:[1,0]
	v_pk_add_f32 v[168:169], v[168:169], 1.0 op_sel_hi:[1,0]
	v_pk_add_f32 v[170:171], v[170:171], 1.0 op_sel_hi:[1,0]
	v_pk_add_f32 v[172:173], v[172:173], 1.0 op_sel_hi:[1,0]
	v_pk_add_f32 v[174:175], v[174:175], 1.0 op_sel_hi:[1,0]
	v_pk_add_f32 v[192:193], v[192:193], 1.0 op_sel_hi:[1,0]
	v_pk_add_f32 v[194:195], v[194:195], 1.0 op_sel_hi:[1,0]
	v_pk_add_f32 v[196:197], v[196:197], 1.0 op_sel_hi:[1,0]
	v_pk_add_f32 v[198:199], v[198:199], 1.0 op_sel_hi:[1,0]
	v_pk_add_f32 v[200:201], v[200:201], 1.0 op_sel_hi:[1,0]
	v_pk_add_f32 v[202:203], v[202:203], 1.0 op_sel_hi:[1,0]
	v_pk_add_f32 v[204:205], v[204:205], 1.0 op_sel_hi:[1,0]
	v_pk_add_f32 v[206:207], v[206:207], 1.0 op_sel_hi:[1,0]
	s_add_u32 s38, s20, 0x4000000
	s_addc_u32 s39, s21, 0
	s_add_u32 s40, s20, 0x4400000
	s_addc_u32 s41, s21, 0
	s_add_u32 s46, s20, 0x4800000
	s_addc_u32 s47, s21, 0
	s_add_u32 s48, s20, 0x4c00000
	s_addc_u32 s49, s21, 0
	v_pk_mul_f32 v[0:1], v[0:1], v[232:233] op_sel_hi:[1,0]
	v_pk_mul_f32 v[2:3], v[2:3], v[232:233] op_sel_hi:[1,0]
	v_pk_mul_f32 v[0:1], v[64:65], v[0:1]
	v_pk_mul_f32 v[2:3], v[66:67], v[2:3]
	v_pk_fma_f32 v[0:1], v[160:161], v[0:1], v[176:177]
	v_pk_fma_f32 v[2:3], v[162:163], v[2:3], v[178:179]
	v_cvt_pk_bf16_f32 v244, v0, v1
	v_cvt_pk_bf16_f32 v245, v2, v3
	v_pk_mul_f32 v[4:5], v[4:5], v[232:233] op_sel_hi:[1,0]
	v_pk_mul_f32 v[6:7], v[6:7], v[232:233] op_sel_hi:[1,0]
	v_pk_mul_f32 v[4:5], v[68:69], v[4:5]
	v_pk_mul_f32 v[6:7], v[70:71], v[6:7]
	v_pk_fma_f32 v[4:5], v[164:165], v[4:5], v[180:181]
	v_pk_fma_f32 v[6:7], v[166:167], v[6:7], v[182:183]
	v_cvt_pk_bf16_f32 v246, v4, v5
	v_cvt_pk_bf16_f32 v247, v6, v7
	global_store_dwordx4 v82, v[244:247], s[38:39] offset:0
	v_pk_mul_f32 v[8:9], v[8:9], v[232:233] op_sel_hi:[1,0]
	v_pk_mul_f32 v[10:11], v[10:11], v[232:233] op_sel_hi:[1,0]
	v_pk_mul_f32 v[8:9], v[72:73], v[8:9]
	v_pk_mul_f32 v[10:11], v[74:75], v[10:11]
	v_pk_fma_f32 v[8:9], v[168:169], v[8:9], v[184:185]
	v_pk_fma_f32 v[10:11], v[170:171], v[10:11], v[186:187]
	v_cvt_pk_bf16_f32 v240, v8, v9
	v_cvt_pk_bf16_f32 v241, v10, v11
	v_pk_mul_f32 v[12:13], v[12:13], v[232:233] op_sel_hi:[1,0]
	v_pk_mul_f32 v[14:15], v[14:15], v[232:233] op_sel_hi:[1,0]
	v_pk_mul_f32 v[12:13], v[76:77], v[12:13]
	v_pk_mul_f32 v[14:15], v[78:79], v[14:15]
	v_pk_fma_f32 v[12:13], v[172:173], v[12:13], v[188:189]
	v_pk_fma_f32 v[14:15], v[174:175], v[14:15], v[190:191]
	v_cvt_pk_bf16_f32 v242, v12, v13
	v_cvt_pk_bf16_f32 v243, v14, v15
	global_store_dwordx4 v82, v[240:243], s[38:39] offset:1024
	v_pk_mul_f32 v[16:17], v[16:17], v[234:235] op_sel_hi:[1,0]
	v_pk_mul_f32 v[18:19], v[18:19], v[234:235] op_sel_hi:[1,0]
	v_pk_mul_f32 v[16:17], v[64:65], v[16:17]
	v_pk_mul_f32 v[18:19], v[66:67], v[18:19]
	v_pk_fma_f32 v[16:17], v[160:161], v[16:17], v[176:177]
	v_pk_fma_f32 v[18:19], v[162:163], v[18:19], v[178:179]
	v_cvt_pk_bf16_f32 v244, v16, v17
	v_cvt_pk_bf16_f32 v245, v18, v19
	v_pk_mul_f32 v[20:21], v[20:21], v[234:235] op_sel_hi:[1,0]
	v_pk_mul_f32 v[22:23], v[22:23], v[234:235] op_sel_hi:[1,0]
	v_pk_mul_f32 v[20:21], v[68:69], v[20:21]
	v_pk_mul_f32 v[22:23], v[70:71], v[22:23]
	v_pk_fma_f32 v[20:21], v[164:165], v[20:21], v[180:181]
	v_pk_fma_f32 v[22:23], v[166:167], v[22:23], v[182:183]
	v_cvt_pk_bf16_f32 v246, v20, v21
	v_cvt_pk_bf16_f32 v247, v22, v23
	global_store_dwordx4 v82, v[244:247], s[40:41] offset:0
	v_pk_mul_f32 v[24:25], v[24:25], v[234:235] op_sel_hi:[1,0]
	v_pk_mul_f32 v[26:27], v[26:27], v[234:235] op_sel_hi:[1,0]
	v_pk_mul_f32 v[24:25], v[72:73], v[24:25]
	v_pk_mul_f32 v[26:27], v[74:75], v[26:27]
	v_pk_fma_f32 v[24:25], v[168:169], v[24:25], v[184:185]
	v_pk_fma_f32 v[26:27], v[170:171], v[26:27], v[186:187]
	v_cvt_pk_bf16_f32 v240, v24, v25
	v_cvt_pk_bf16_f32 v241, v26, v27
	v_pk_mul_f32 v[28:29], v[28:29], v[234:235] op_sel_hi:[1,0]
	v_pk_mul_f32 v[30:31], v[30:31], v[234:235] op_sel_hi:[1,0]
	v_pk_mul_f32 v[28:29], v[76:77], v[28:29]
	v_pk_mul_f32 v[30:31], v[78:79], v[30:31]
	v_pk_fma_f32 v[28:29], v[172:173], v[28:29], v[188:189]
	v_pk_fma_f32 v[30:31], v[174:175], v[30:31], v[190:191]
	v_cvt_pk_bf16_f32 v242, v28, v29
	v_cvt_pk_bf16_f32 v243, v30, v31
	global_store_dwordx4 v82, v[240:243], s[40:41] offset:1024
	v_pk_mul_f32 v[32:33], v[32:33], v[236:237] op_sel_hi:[1,0]
	v_pk_mul_f32 v[34:35], v[34:35], v[236:237] op_sel_hi:[1,0]
	v_pk_mul_f32 v[32:33], v[64:65], v[32:33]
	v_pk_mul_f32 v[34:35], v[66:67], v[34:35]
	v_pk_fma_f32 v[32:33], v[192:193], v[32:33], v[208:209]
	v_pk_fma_f32 v[34:35], v[194:195], v[34:35], v[210:211]
	v_cvt_pk_bf16_f32 v244, v32, v33
	v_cvt_pk_bf16_f32 v245, v34, v35
	v_pk_mul_f32 v[36:37], v[36:37], v[236:237] op_sel_hi:[1,0]
	v_pk_mul_f32 v[38:39], v[38:39], v[236:237] op_sel_hi:[1,0]
	v_pk_mul_f32 v[36:37], v[68:69], v[36:37]
	v_pk_mul_f32 v[38:39], v[70:71], v[38:39]
	v_pk_fma_f32 v[36:37], v[196:197], v[36:37], v[212:213]
	v_pk_fma_f32 v[38:39], v[198:199], v[38:39], v[214:215]
	v_cvt_pk_bf16_f32 v246, v36, v37
	v_cvt_pk_bf16_f32 v247, v38, v39
	global_store_dwordx4 v82, v[244:247], s[46:47] offset:0
	v_pk_mul_f32 v[40:41], v[40:41], v[236:237] op_sel_hi:[1,0]
	v_pk_mul_f32 v[42:43], v[42:43], v[236:237] op_sel_hi:[1,0]
	v_pk_mul_f32 v[40:41], v[72:73], v[40:41]
	v_pk_mul_f32 v[42:43], v[74:75], v[42:43]
	v_pk_fma_f32 v[40:41], v[200:201], v[40:41], v[216:217]
	v_pk_fma_f32 v[42:43], v[202:203], v[42:43], v[218:219]
	v_cvt_pk_bf16_f32 v240, v40, v41
	v_cvt_pk_bf16_f32 v241, v42, v43
	v_pk_mul_f32 v[44:45], v[44:45], v[236:237] op_sel_hi:[1,0]
	v_pk_mul_f32 v[46:47], v[46:47], v[236:237] op_sel_hi:[1,0]
	v_pk_mul_f32 v[44:45], v[76:77], v[44:45]
	v_pk_mul_f32 v[46:47], v[78:79], v[46:47]
	v_pk_fma_f32 v[44:45], v[204:205], v[44:45], v[220:221]
	v_pk_fma_f32 v[46:47], v[206:207], v[46:47], v[222:223]
	v_cvt_pk_bf16_f32 v242, v44, v45
	v_cvt_pk_bf16_f32 v243, v46, v47
	global_store_dwordx4 v82, v[240:243], s[46:47] offset:1024
	v_pk_mul_f32 v[48:49], v[48:49], v[238:239] op_sel_hi:[1,0]
	v_pk_mul_f32 v[50:51], v[50:51], v[238:239] op_sel_hi:[1,0]
	v_pk_mul_f32 v[48:49], v[64:65], v[48:49]
	v_pk_mul_f32 v[50:51], v[66:67], v[50:51]
	v_pk_fma_f32 v[48:49], v[192:193], v[48:49], v[208:209]
	v_pk_fma_f32 v[50:51], v[194:195], v[50:51], v[210:211]
	v_cvt_pk_bf16_f32 v244, v48, v49
	v_cvt_pk_bf16_f32 v245, v50, v51
	v_pk_mul_f32 v[52:53], v[52:53], v[238:239] op_sel_hi:[1,0]
	v_pk_mul_f32 v[54:55], v[54:55], v[238:239] op_sel_hi:[1,0]
	v_pk_mul_f32 v[52:53], v[68:69], v[52:53]
	v_pk_mul_f32 v[54:55], v[70:71], v[54:55]
	v_pk_fma_f32 v[52:53], v[196:197], v[52:53], v[212:213]
	v_pk_fma_f32 v[54:55], v[198:199], v[54:55], v[214:215]
	v_cvt_pk_bf16_f32 v246, v52, v53
	v_cvt_pk_bf16_f32 v247, v54, v55
	global_store_dwordx4 v82, v[244:247], s[48:49] offset:0
	v_pk_mul_f32 v[56:57], v[56:57], v[238:239] op_sel_hi:[1,0]
	v_pk_mul_f32 v[58:59], v[58:59], v[238:239] op_sel_hi:[1,0]
	v_pk_mul_f32 v[56:57], v[72:73], v[56:57]
	v_pk_mul_f32 v[58:59], v[74:75], v[58:59]
	v_pk_fma_f32 v[56:57], v[200:201], v[56:57], v[216:217]
	v_pk_fma_f32 v[58:59], v[202:203], v[58:59], v[218:219]
	v_cvt_pk_bf16_f32 v240, v56, v57
	v_cvt_pk_bf16_f32 v241, v58, v59
	v_pk_mul_f32 v[60:61], v[60:61], v[238:239] op_sel_hi:[1,0]
	v_pk_mul_f32 v[62:63], v[62:63], v[238:239] op_sel_hi:[1,0]
	v_pk_mul_f32 v[60:61], v[76:77], v[60:61]
	v_pk_mul_f32 v[62:63], v[78:79], v[62:63]
	v_pk_fma_f32 v[60:61], v[204:205], v[60:61], v[220:221]
	v_pk_fma_f32 v[62:63], v[206:207], v[62:63], v[222:223]
	v_cvt_pk_bf16_f32 v242, v60, v61
	v_cvt_pk_bf16_f32 v243, v62, v63
	global_store_dwordx4 v82, v[240:243], s[48:49] offset:1024
	s_add_u32 s34, s8, 0x21000
	s_addc_u32 s35, s9, 0
	s_add_u32 s36, s8, 0x21000
	s_addc_u32 s37, s9, 0
	global_load_dwordx4 v[176:179], v80, s[34:35] offset:0
	global_load_dwordx4 v[180:183], v80, s[34:35] offset:16
	global_load_dwordx4 v[184:187], v80, s[34:35] offset:2048
	global_load_dwordx4 v[188:191], v80, s[34:35] offset:2064
	global_load_dwordx4 v[160:163], v81, s[34:35] offset:0
	global_load_dwordx4 v[164:167], v81, s[34:35] offset:16
	global_load_dwordx4 v[168:171], v81, s[34:35] offset:2048
	global_load_dwordx4 v[172:175], v81, s[34:35] offset:2064
	global_load_dwordx4 v[208:211], v80, s[36:37] offset:0
	global_load_dwordx4 v[212:215], v80, s[36:37] offset:16
	global_load_dwordx4 v[216:219], v80, s[36:37] offset:2048
	global_load_dwordx4 v[220:223], v80, s[36:37] offset:2064
	global_load_dwordx4 v[192:195], v81, s[36:37] offset:0
	global_load_dwordx4 v[196:199], v81, s[36:37] offset:16
	global_load_dwordx4 v[200:203], v81, s[36:37] offset:2048
	global_load_dwordx4 v[204:207], v81, s[36:37] offset:2064
	s_add_u32 s24, s16, 0x6000000
	s_addc_u32 s25, s17, 0
	s_add_u32 s26, s16, 0x6400000
	s_addc_u32 s27, s17, 0
	s_add_u32 s28, s16, 0x6800000
	s_addc_u32 s29, s17, 0
	s_add_u32 s30, s16, 0x6c00000
	s_addc_u32 s31, s17, 0
	global_load_dwordx4 v[96:99], v82, s[24:25] offset:0
	global_load_dwordx4 v[100:103], v82, s[24:25] offset:1024
	global_load_dwordx4 v[104:107], v82, s[26:27] offset:0
	global_load_dwordx4 v[108:111], v82, s[26:27] offset:1024
	global_load_dwordx4 v[112:115], v82, s[28:29] offset:0
	global_load_dwordx4 v[116:119], v82, s[28:29] offset:1024
	global_load_dwordx4 v[120:123], v82, s[30:31] offset:0
	global_load_dwordx4 v[124:127], v82, s[30:31] offset:1024
	s_waitcnt vmcnt(32)
	v_lshlrev_b32_e32 v0, 16, v128
	v_and_b32_e32 v1, 0xffff0000, v128
	v_lshlrev_b32_e32 v2, 16, v129
	v_and_b32_e32 v3, 0xffff0000, v129
	v_lshlrev_b32_e32 v4, 16, v130
	v_and_b32_e32 v5, 0xffff0000, v130
	v_lshlrev_b32_e32 v6, 16, v131
	v_and_b32_e32 v7, 0xffff0000, v131
	v_lshlrev_b32_e32 v8, 16, v132
	v_and_b32_e32 v9, 0xffff0000, v132
	v_lshlrev_b32_e32 v10, 16, v133
	v_and_b32_e32 v11, 0xffff0000, v133
	v_lshlrev_b32_e32 v12, 16, v134
	v_and_b32_e32 v13, 0xffff0000, v134
	v_lshlrev_b32_e32 v14, 16, v135
	v_and_b32_e32 v15, 0xffff0000, v135
	v_lshlrev_b32_e32 v16, 16, v136
	v_and_b32_e32 v17, 0xffff0000, v136
	v_lshlrev_b32_e32 v18, 16, v137
	v_and_b32_e32 v19, 0xffff0000, v137
	v_lshlrev_b32_e32 v20, 16, v138
	v_and_b32_e32 v21, 0xffff0000, v138
	v_lshlrev_b32_e32 v22, 16, v139
	v_and_b32_e32 v23, 0xffff0000, v139
	v_lshlrev_b32_e32 v24, 16, v140
	v_and_b32_e32 v25, 0xffff0000, v140
	v_lshlrev_b32_e32 v26, 16, v141
	v_and_b32_e32 v27, 0xffff0000, v141
	v_lshlrev_b32_e32 v28, 16, v142
	v_and_b32_e32 v29, 0xffff0000, v142
	v_lshlrev_b32_e32 v30, 16, v143
	v_and_b32_e32 v31, 0xffff0000, v143
	v_lshlrev_b32_e32 v32, 16, v144
	v_and_b32_e32 v33, 0xffff0000, v144
	v_lshlrev_b32_e32 v34, 16, v145
	v_and_b32_e32 v35, 0xffff0000, v145
	v_lshlrev_b32_e32 v36, 16, v146
	v_and_b32_e32 v37, 0xffff0000, v146
	v_lshlrev_b32_e32 v38, 16, v147
	v_and_b32_e32 v39, 0xffff0000, v147
	v_lshlrev_b32_e32 v40, 16, v148
	v_and_b32_e32 v41, 0xffff0000, v148
	v_lshlrev_b32_e32 v42, 16, v149
	v_and_b32_e32 v43, 0xffff0000, v149
	v_lshlrev_b32_e32 v44, 16, v150
	v_and_b32_e32 v45, 0xffff0000, v150
	v_lshlrev_b32_e32 v46, 16, v151
	v_and_b32_e32 v47, 0xffff0000, v151
	v_lshlrev_b32_e32 v48, 16, v152
	v_and_b32_e32 v49, 0xffff0000, v152
	v_lshlrev_b32_e32 v50, 16, v153
	v_and_b32_e32 v51, 0xffff0000, v153
	v_lshlrev_b32_e32 v52, 16, v154
	v_and_b32_e32 v53, 0xffff0000, v154
	v_lshlrev_b32_e32 v54, 16, v155
	v_and_b32_e32 v55, 0xffff0000, v155
	v_lshlrev_b32_e32 v56, 16, v156
	v_and_b32_e32 v57, 0xffff0000, v156
	v_lshlrev_b32_e32 v58, 16, v157
	v_and_b32_e32 v59, 0xffff0000, v157
	v_lshlrev_b32_e32 v60, 16, v158
	v_and_b32_e32 v61, 0xffff0000, v158
	v_lshlrev_b32_e32 v62, 16, v159
	v_and_b32_e32 v63, 0xffff0000, v159
	v_pk_mul_f32 v[240:241], v[0:1], v[0:1]
	v_pk_mul_f32 v[242:243], v[16:17], v[16:17]
	v_pk_mul_f32 v[244:245], v[32:33], v[32:33]
	v_pk_mul_f32 v[246:247], v[48:49], v[48:49]
	v_pk_fma_f32 v[240:241], v[2:3], v[2:3], v[240:241]
	v_pk_fma_f32 v[242:243], v[18:19], v[18:19], v[242:243]
	v_pk_fma_f32 v[244:245], v[34:35], v[34:35], v[244:245]
	v_pk_fma_f32 v[246:247], v[50:51], v[50:51], v[246:247]
	v_pk_fma_f32 v[240:241], v[4:5], v[4:5], v[240:241]
	v_pk_fma_f32 v[242:243], v[20:21], v[20:21], v[242:243]
	v_pk_fma_f32 v[244:245], v[36:37], v[36:37], v[244:245]
	v_pk_fma_f32 v[246:247], v[52:53], v[52:53], v[246:247]
	v_pk_fma_f32 v[240:241], v[6:7], v[6:7], v[240:241]
	v_pk_fma_f32 v[242:243], v[22:23], v[22:23], v[242:243]
	v_pk_fma_f32 v[244:245], v[38:39], v[38:39], v[244:245]
	v_pk_fma_f32 v[246:247], v[54:55], v[54:55], v[246:247]
	v_pk_fma_f32 v[240:241], v[8:9], v[8:9], v[240:241]
	v_pk_fma_f32 v[242:243], v[24:25], v[24:25], v[242:243]
	v_pk_fma_f32 v[244:245], v[40:41], v[40:41], v[244:245]
	v_pk_fma_f32 v[246:247], v[56:57], v[56:57], v[246:247]
	v_pk_fma_f32 v[240:241], v[10:11], v[10:11], v[240:241]
	v_pk_fma_f32 v[242:243], v[26:27], v[26:27], v[242:243]
	v_pk_fma_f32 v[244:245], v[42:43], v[42:43], v[244:245]
	v_pk_fma_f32 v[246:247], v[58:59], v[58:59], v[246:247]
	v_pk_fma_f32 v[240:241], v[12:13], v[12:13], v[240:241]
	v_pk_fma_f32 v[242:243], v[28:29], v[28:29], v[242:243]
	v_pk_fma_f32 v[244:245], v[44:45], v[44:45], v[244:245]
	v_pk_fma_f32 v[246:247], v[60:61], v[60:61], v[246:247]
	v_pk_fma_f32 v[240:241], v[14:15], v[14:15], v[240:241]
	v_pk_fma_f32 v[242:243], v[30:31], v[30:31], v[242:243]
	v_pk_fma_f32 v[244:245], v[46:47], v[46:47], v[244:245]
	v_pk_fma_f32 v[246:247], v[62:63], v[62:63], v[246:247]
	v_add_f32_e32 v224, v240, v241
	v_add_f32_e32 v225, v242, v243
	v_add_f32_e32 v226, v244, v245
	v_add_f32_e32 v227, v246, v247
	ds_bpermute_b32 v228, v83, v224
	ds_bpermute_b32 v229, v83, v225
	ds_bpermute_b32 v230, v83, v226
	ds_bpermute_b32 v231, v83, v227
	s_waitcnt lgkmcnt(0)
	v_add_f32_e32 v224, v224, v228
	v_add_f32_e32 v225, v225, v229
	v_add_f32_e32 v226, v226, v230
	v_add_f32_e32 v227, v227, v231
	ds_bpermute_b32 v228, v84, v224
	ds_bpermute_b32 v229, v84, v225
	ds_bpermute_b32 v230, v84, v226
	ds_bpermute_b32 v231, v84, v227
	s_waitcnt lgkmcnt(0)
	v_add_f32_e32 v224, v224, v228
	v_add_f32_e32 v225, v225, v229
	v_add_f32_e32 v226, v226, v230
	v_add_f32_e32 v227, v227, v231
	ds_bpermute_b32 v228, v85, v224
	ds_bpermute_b32 v229, v85, v225
	ds_bpermute_b32 v230, v85, v226
	ds_bpermute_b32 v231, v85, v227
	s_waitcnt lgkmcnt(0)
	v_add_f32_e32 v224, v224, v228
	v_add_f32_e32 v225, v225, v229
	v_add_f32_e32 v226, v226, v230
	v_add_f32_e32 v227, v227, v231
	ds_bpermute_b32 v228, v86, v224
	ds_bpermute_b32 v229, v86, v225
	ds_bpermute_b32 v230, v86, v226
	ds_bpermute_b32 v231, v86, v227
	s_waitcnt lgkmcnt(0)
	v_add_f32_e32 v224, v224, v228
	v_add_f32_e32 v225, v225, v229
	v_add_f32_e32 v226, v226, v230
	v_add_f32_e32 v227, v227, v231
	ds_bpermute_b32 v228, v87, v224
	ds_bpermute_b32 v229, v87, v225
	ds_bpermute_b32 v230, v87, v226
	ds_bpermute_b32 v231, v87, v227
	s_waitcnt lgkmcnt(0)
	v_add_f32_e32 v224, v224, v228
	v_add_f32_e32 v225, v225, v229
	v_add_f32_e32 v226, v226, v230
	v_add_f32_e32 v227, v227, v231
	ds_bpermute_b32 v228, v88, v224
	ds_bpermute_b32 v229, v88, v225
	ds_bpermute_b32 v230, v88, v226
	ds_bpermute_b32 v231, v88, v227
	s_waitcnt lgkmcnt(0)
	v_add_f32_e32 v224, v224, v228
	v_add_f32_e32 v225, v225, v229
	v_add_f32_e32 v226, v226, v230
	v_add_f32_e32 v227, v227, v231
	v_fmamk_f32 v240, v224, 0x3a800000, v89
	v_mul_f32_e32 v241, 0x4f800000, v240
	v_cmp_gt_f32_e32 vcc, s54, v240
	s_nop 1
	v_cndmask_b32_e32 v247, v240, v241, vcc
	v_sqrt_f32_e32 v242, v247
	s_nop 1
	v_add_u32_e32 v243, -1, v242
	v_add_u32_e32 v244, 1, v242
	v_fma_f32 v245, -v243, v242, v247
	v_fma_f32 v246, -v244, v242, v247
	v_cmp_ge_f32_e64 s[52:53], 0, v245
	s_nop 1
	v_cndmask_b32_e64 v242, v242, v243, s[52:53]
	v_cmp_lt_f32_e64 s[52:53], 0, v246
	s_nop 1
	v_cndmask_b32_e64 v242, v242, v244, s[52:53]
	v_mul_f32_e32 v243, 0x37800000, v242
	v_cndmask_b32_e32 v242, v242, v243, vcc
	v_cmp_class_f32_e32 vcc, v247, v90
	s_nop 1
	v_cndmask_b32_e32 v247, v242, v247, vcc
	v_div_scale_f32 v248, s[52:53], v247, v247, 1.0
	v_rcp_f32_e32 v249, v248
	v_div_scale_f32 v228, vcc, 1.0, v247, 1.0
	s_nop 0
	v_fma_f32 v229, -v248, v249, 1.0
	v_fmac_f32_e32 v249, v229, v249
	v_mul_f32_e32 v230, v228, v249
	v_fma_f32 v229, -v248, v230, v228
	v_fmac_f32_e32 v230, v229, v249
	v_fma_f32 v248, -v248, v230, v228
	v_div_fmas_f32 v248, v248, v249, v230
	v_div_fixup_f32 v232, v248, v247, 1.0
	v_fmamk_f32 v240, v225, 0x3a800000, v89
	v_mul_f32_e32 v241, 0x4f800000, v240
	v_cmp_gt_f32_e32 vcc, s54, v240
	s_nop 1
	v_cndmask_b32_e32 v247, v240, v241, vcc
	v_sqrt_f32_e32 v242, v247
	s_nop 1
	v_add_u32_e32 v243, -1, v242
	v_add_u32_e32 v244, 1, v242
	v_fma_f32 v245, -v243, v242, v247
	v_fma_f32 v246, -v244, v242, v247
	v_cmp_ge_f32_e64 s[52:53], 0, v245
	s_nop 1
	v_cndmask_b32_e64 v242, v242, v243, s[52:53]
	v_cmp_lt_f32_e64 s[52:53], 0, v246
	s_nop 1
	v_cndmask_b32_e64 v242, v242, v244, s[52:53]
	v_mul_f32_e32 v243, 0x37800000, v242
	v_cndmask_b32_e32 v242, v242, v243, vcc
	v_cmp_class_f32_e32 vcc, v247, v90
	s_nop 1
	v_cndmask_b32_e32 v247, v242, v247, vcc
	v_div_scale_f32 v248, s[52:53], v247, v247, 1.0
	v_rcp_f32_e32 v249, v248
	v_div_scale_f32 v228, vcc, 1.0, v247, 1.0
	s_nop 0
	v_fma_f32 v229, -v248, v249, 1.0
	v_fmac_f32_e32 v249, v229, v249
	v_mul_f32_e32 v230, v228, v249
	v_fma_f32 v229, -v248, v230, v228
	v_fmac_f32_e32 v230, v229, v249
	v_fma_f32 v248, -v248, v230, v228
	v_div_fmas_f32 v248, v248, v249, v230
	v_div_fixup_f32 v234, v248, v247, 1.0
	v_fmamk_f32 v240, v226, 0x3a800000, v89
	v_mul_f32_e32 v241, 0x4f800000, v240
	v_cmp_gt_f32_e32 vcc, s54, v240
	s_nop 1
	v_cndmask_b32_e32 v247, v240, v241, vcc
	v_sqrt_f32_e32 v242, v247
	s_nop 1
	v_add_u32_e32 v243, -1, v242
	v_add_u32_e32 v244, 1, v242
	v_fma_f32 v245, -v243, v242, v247
	v_fma_f32 v246, -v244, v242, v247
	v_cmp_ge_f32_e64 s[52:53], 0, v245
	s_nop 1
	v_cndmask_b32_e64 v242, v242, v243, s[52:53]
	v_cmp_lt_f32_e64 s[52:53], 0, v246
	s_nop 1
	v_cndmask_b32_e64 v242, v242, v244, s[52:53]
	v_mul_f32_e32 v243, 0x37800000, v242
	v_cndmask_b32_e32 v242, v242, v243, vcc
	v_cmp_class_f32_e32 vcc, v247, v90
	s_nop 1
	v_cndmask_b32_e32 v247, v242, v247, vcc
	v_div_scale_f32 v248, s[52:53], v247, v247, 1.0
	v_rcp_f32_e32 v249, v248
	v_div_scale_f32 v228, vcc, 1.0, v247, 1.0
	s_nop 0
	v_fma_f32 v229, -v248, v249, 1.0
	v_fmac_f32_e32 v249, v229, v249
	v_mul_f32_e32 v230, v228, v249
	v_fma_f32 v229, -v248, v230, v228
	v_fmac_f32_e32 v230, v229, v249
	v_fma_f32 v248, -v248, v230, v228
	v_div_fmas_f32 v248, v248, v249, v230
	v_div_fixup_f32 v236, v248, v247, 1.0
	v_fmamk_f32 v240, v227, 0x3a800000, v89
	v_mul_f32_e32 v241, 0x4f800000, v240
	v_cmp_gt_f32_e32 vcc, s54, v240
	s_nop 1
	v_cndmask_b32_e32 v247, v240, v241, vcc
	v_sqrt_f32_e32 v242, v247
	s_nop 1
	v_add_u32_e32 v243, -1, v242
	v_add_u32_e32 v244, 1, v242
	v_fma_f32 v245, -v243, v242, v247
	v_fma_f32 v246, -v244, v242, v247
	v_cmp_ge_f32_e64 s[52:53], 0, v245
	s_nop 1
	v_cndmask_b32_e64 v242, v242, v243, s[52:53]
	v_cmp_lt_f32_e64 s[52:53], 0, v246
	s_nop 1
	v_cndmask_b32_e64 v242, v242, v244, s[52:53]
	v_mul_f32_e32 v243, 0x37800000, v242
	v_cndmask_b32_e32 v242, v242, v243, vcc
	v_cmp_class_f32_e32 vcc, v247, v90
	s_nop 1
	v_cndmask_b32_e32 v247, v242, v247, vcc
	v_div_scale_f32 v248, s[52:53], v247, v247, 1.0
	v_rcp_f32_e32 v249, v248
	v_div_scale_f32 v228, vcc, 1.0, v247, 1.0
	s_nop 0
	v_fma_f32 v229, -v248, v249, 1.0
	v_fmac_f32_e32 v249, v229, v249
	v_mul_f32_e32 v230, v228, v249
	v_fma_f32 v229, -v248, v230, v228
	v_fmac_f32_e32 v230, v229, v249
	v_fma_f32 v248, -v248, v230, v228
	v_div_fmas_f32 v248, v248, v249, v230
	v_div_fixup_f32 v238, v248, v247, 1.0
	s_waitcnt vmcnt(8)
	v_pk_add_f32 v[160:161], v[160:161], 1.0 op_sel_hi:[1,0]
	v_pk_add_f32 v[162:163], v[162:163], 1.0 op_sel_hi:[1,0]
	v_pk_add_f32 v[164:165], v[164:165], 1.0 op_sel_hi:[1,0]
	v_pk_add_f32 v[166:167], v[166:167], 1.0 op_sel_hi:[1,0]
	v_pk_add_f32 v[168:169], v[168:169], 1.0 op_sel_hi:[1,0]
	v_pk_add_f32 v[170:171], v[170:171], 1.0 op_sel_hi:[1,0]
	v_pk_add_f32 v[172:173], v[172:173], 1.0 op_sel_hi:[1,0]
	v_pk_add_f32 v[174:175], v[174:175], 1.0 op_sel_hi:[1,0]
	v_pk_add_f32 v[192:193], v[192:193], 1.0 op_sel_hi:[1,0]
	v_pk_add_f32 v[194:195], v[194:195], 1.0 op_sel_hi:[1,0]
	v_pk_add_f32 v[196:197], v[196:197], 1.0 op_sel_hi:[1,0]
	v_pk_add_f32 v[198:199], v[198:199], 1.0 op_sel_hi:[1,0]
	v_pk_add_f32 v[200:201], v[200:201], 1.0 op_sel_hi:[1,0]
	v_pk_add_f32 v[202:203], v[202:203], 1.0 op_sel_hi:[1,0]
	v_pk_add_f32 v[204:205], v[204:205], 1.0 op_sel_hi:[1,0]
	v_pk_add_f32 v[206:207], v[206:207], 1.0 op_sel_hi:[1,0]
	s_add_u32 s38, s20, 0x5000000
	s_addc_u32 s39, s21, 0
	s_add_u32 s40, s20, 0x5400000
	s_addc_u32 s41, s21, 0
	s_add_u32 s46, s20, 0x5800000
	s_addc_u32 s47, s21, 0
	s_add_u32 s48, s20, 0x5c00000
	s_addc_u32 s49, s21, 0
	v_pk_mul_f32 v[0:1], v[0:1], v[232:233] op_sel_hi:[1,0]
	v_pk_mul_f32 v[2:3], v[2:3], v[232:233] op_sel_hi:[1,0]
	v_pk_mul_f32 v[0:1], v[64:65], v[0:1]
	v_pk_mul_f32 v[2:3], v[66:67], v[2:3]
	v_pk_fma_f32 v[0:1], v[160:161], v[0:1], v[176:177]
	v_pk_fma_f32 v[2:3], v[162:163], v[2:3], v[178:179]
	v_cvt_pk_bf16_f32 v244, v0, v1
	v_cvt_pk_bf16_f32 v245, v2, v3
	v_pk_mul_f32 v[4:5], v[4:5], v[232:233] op_sel_hi:[1,0]
	v_pk_mul_f32 v[6:7], v[6:7], v[232:233] op_sel_hi:[1,0]
	v_pk_mul_f32 v[4:5], v[68:69], v[4:5]
	v_pk_mul_f32 v[6:7], v[70:71], v[6:7]
	v_pk_fma_f32 v[4:5], v[164:165], v[4:5], v[180:181]
	v_pk_fma_f32 v[6:7], v[166:167], v[6:7], v[182:183]
	v_cvt_pk_bf16_f32 v246, v4, v5
	v_cvt_pk_bf16_f32 v247, v6, v7
	global_store_dwordx4 v82, v[244:247], s[38:39] offset:0
	v_pk_mul_f32 v[8:9], v[8:9], v[232:233] op_sel_hi:[1,0]
	v_pk_mul_f32 v[10:11], v[10:11], v[232:233] op_sel_hi:[1,0]
	v_pk_mul_f32 v[8:9], v[72:73], v[8:9]
	v_pk_mul_f32 v[10:11], v[74:75], v[10:11]
	v_pk_fma_f32 v[8:9], v[168:169], v[8:9], v[184:185]
	v_pk_fma_f32 v[10:11], v[170:171], v[10:11], v[186:187]
	v_cvt_pk_bf16_f32 v240, v8, v9
	v_cvt_pk_bf16_f32 v241, v10, v11
	v_pk_mul_f32 v[12:13], v[12:13], v[232:233] op_sel_hi:[1,0]
	v_pk_mul_f32 v[14:15], v[14:15], v[232:233] op_sel_hi:[1,0]
	v_pk_mul_f32 v[12:13], v[76:77], v[12:13]
	v_pk_mul_f32 v[14:15], v[78:79], v[14:15]
	v_pk_fma_f32 v[12:13], v[172:173], v[12:13], v[188:189]
	v_pk_fma_f32 v[14:15], v[174:175], v[14:15], v[190:191]
	v_cvt_pk_bf16_f32 v242, v12, v13
	v_cvt_pk_bf16_f32 v243, v14, v15
	global_store_dwordx4 v82, v[240:243], s[38:39] offset:1024
	v_pk_mul_f32 v[16:17], v[16:17], v[234:235] op_sel_hi:[1,0]
	v_pk_mul_f32 v[18:19], v[18:19], v[234:235] op_sel_hi:[1,0]
	v_pk_mul_f32 v[16:17], v[64:65], v[16:17]
	v_pk_mul_f32 v[18:19], v[66:67], v[18:19]
	v_pk_fma_f32 v[16:17], v[160:161], v[16:17], v[176:177]
	v_pk_fma_f32 v[18:19], v[162:163], v[18:19], v[178:179]
	v_cvt_pk_bf16_f32 v244, v16, v17
	v_cvt_pk_bf16_f32 v245, v18, v19
	v_pk_mul_f32 v[20:21], v[20:21], v[234:235] op_sel_hi:[1,0]
	v_pk_mul_f32 v[22:23], v[22:23], v[234:235] op_sel_hi:[1,0]
	v_pk_mul_f32 v[20:21], v[68:69], v[20:21]
	v_pk_mul_f32 v[22:23], v[70:71], v[22:23]
	v_pk_fma_f32 v[20:21], v[164:165], v[20:21], v[180:181]
	v_pk_fma_f32 v[22:23], v[166:167], v[22:23], v[182:183]
	v_cvt_pk_bf16_f32 v246, v20, v21
	v_cvt_pk_bf16_f32 v247, v22, v23
	global_store_dwordx4 v82, v[244:247], s[40:41] offset:0
	v_pk_mul_f32 v[24:25], v[24:25], v[234:235] op_sel_hi:[1,0]
	v_pk_mul_f32 v[26:27], v[26:27], v[234:235] op_sel_hi:[1,0]
	v_pk_mul_f32 v[24:25], v[72:73], v[24:25]
	v_pk_mul_f32 v[26:27], v[74:75], v[26:27]
	v_pk_fma_f32 v[24:25], v[168:169], v[24:25], v[184:185]
	v_pk_fma_f32 v[26:27], v[170:171], v[26:27], v[186:187]
	v_cvt_pk_bf16_f32 v240, v24, v25
	v_cvt_pk_bf16_f32 v241, v26, v27
	v_pk_mul_f32 v[28:29], v[28:29], v[234:235] op_sel_hi:[1,0]
	v_pk_mul_f32 v[30:31], v[30:31], v[234:235] op_sel_hi:[1,0]
	v_pk_mul_f32 v[28:29], v[76:77], v[28:29]
	v_pk_mul_f32 v[30:31], v[78:79], v[30:31]
	v_pk_fma_f32 v[28:29], v[172:173], v[28:29], v[188:189]
	v_pk_fma_f32 v[30:31], v[174:175], v[30:31], v[190:191]
	v_cvt_pk_bf16_f32 v242, v28, v29
	v_cvt_pk_bf16_f32 v243, v30, v31
	global_store_dwordx4 v82, v[240:243], s[40:41] offset:1024
	v_pk_mul_f32 v[32:33], v[32:33], v[236:237] op_sel_hi:[1,0]
	v_pk_mul_f32 v[34:35], v[34:35], v[236:237] op_sel_hi:[1,0]
	v_pk_mul_f32 v[32:33], v[64:65], v[32:33]
	v_pk_mul_f32 v[34:35], v[66:67], v[34:35]
	v_pk_fma_f32 v[32:33], v[192:193], v[32:33], v[208:209]
	v_pk_fma_f32 v[34:35], v[194:195], v[34:35], v[210:211]
	v_cvt_pk_bf16_f32 v244, v32, v33
	v_cvt_pk_bf16_f32 v245, v34, v35
	v_pk_mul_f32 v[36:37], v[36:37], v[236:237] op_sel_hi:[1,0]
	v_pk_mul_f32 v[38:39], v[38:39], v[236:237] op_sel_hi:[1,0]
	v_pk_mul_f32 v[36:37], v[68:69], v[36:37]
	v_pk_mul_f32 v[38:39], v[70:71], v[38:39]
	v_pk_fma_f32 v[36:37], v[196:197], v[36:37], v[212:213]
	v_pk_fma_f32 v[38:39], v[198:199], v[38:39], v[214:215]
	v_cvt_pk_bf16_f32 v246, v36, v37
	v_cvt_pk_bf16_f32 v247, v38, v39
	global_store_dwordx4 v82, v[244:247], s[46:47] offset:0
	v_pk_mul_f32 v[40:41], v[40:41], v[236:237] op_sel_hi:[1,0]
	v_pk_mul_f32 v[42:43], v[42:43], v[236:237] op_sel_hi:[1,0]
	v_pk_mul_f32 v[40:41], v[72:73], v[40:41]
	v_pk_mul_f32 v[42:43], v[74:75], v[42:43]
	v_pk_fma_f32 v[40:41], v[200:201], v[40:41], v[216:217]
	v_pk_fma_f32 v[42:43], v[202:203], v[42:43], v[218:219]
	v_cvt_pk_bf16_f32 v240, v40, v41
	v_cvt_pk_bf16_f32 v241, v42, v43
	v_pk_mul_f32 v[44:45], v[44:45], v[236:237] op_sel_hi:[1,0]
	v_pk_mul_f32 v[46:47], v[46:47], v[236:237] op_sel_hi:[1,0]
	v_pk_mul_f32 v[44:45], v[76:77], v[44:45]
	v_pk_mul_f32 v[46:47], v[78:79], v[46:47]
	v_pk_fma_f32 v[44:45], v[204:205], v[44:45], v[220:221]
	v_pk_fma_f32 v[46:47], v[206:207], v[46:47], v[222:223]
	v_cvt_pk_bf16_f32 v242, v44, v45
	v_cvt_pk_bf16_f32 v243, v46, v47
	global_store_dwordx4 v82, v[240:243], s[46:47] offset:1024
	v_pk_mul_f32 v[48:49], v[48:49], v[238:239] op_sel_hi:[1,0]
	v_pk_mul_f32 v[50:51], v[50:51], v[238:239] op_sel_hi:[1,0]
	v_pk_mul_f32 v[48:49], v[64:65], v[48:49]
	v_pk_mul_f32 v[50:51], v[66:67], v[50:51]
	v_pk_fma_f32 v[48:49], v[192:193], v[48:49], v[208:209]
	v_pk_fma_f32 v[50:51], v[194:195], v[50:51], v[210:211]
	v_cvt_pk_bf16_f32 v244, v48, v49
	v_cvt_pk_bf16_f32 v245, v50, v51
	v_pk_mul_f32 v[52:53], v[52:53], v[238:239] op_sel_hi:[1,0]
	v_pk_mul_f32 v[54:55], v[54:55], v[238:239] op_sel_hi:[1,0]
	v_pk_mul_f32 v[52:53], v[68:69], v[52:53]
	v_pk_mul_f32 v[54:55], v[70:71], v[54:55]
	v_pk_fma_f32 v[52:53], v[196:197], v[52:53], v[212:213]
	v_pk_fma_f32 v[54:55], v[198:199], v[54:55], v[214:215]
	v_cvt_pk_bf16_f32 v246, v52, v53
	v_cvt_pk_bf16_f32 v247, v54, v55
	global_store_dwordx4 v82, v[244:247], s[48:49] offset:0
	v_pk_mul_f32 v[56:57], v[56:57], v[238:239] op_sel_hi:[1,0]
	v_pk_mul_f32 v[58:59], v[58:59], v[238:239] op_sel_hi:[1,0]
	v_pk_mul_f32 v[56:57], v[72:73], v[56:57]
	v_pk_mul_f32 v[58:59], v[74:75], v[58:59]
	v_pk_fma_f32 v[56:57], v[200:201], v[56:57], v[216:217]
	v_pk_fma_f32 v[58:59], v[202:203], v[58:59], v[218:219]
	v_cvt_pk_bf16_f32 v240, v56, v57
	v_cvt_pk_bf16_f32 v241, v58, v59
	v_pk_mul_f32 v[60:61], v[60:61], v[238:239] op_sel_hi:[1,0]
	v_pk_mul_f32 v[62:63], v[62:63], v[238:239] op_sel_hi:[1,0]
	v_pk_mul_f32 v[60:61], v[76:77], v[60:61]
	v_pk_mul_f32 v[62:63], v[78:79], v[62:63]
	v_pk_fma_f32 v[60:61], v[204:205], v[60:61], v[220:221]
	v_pk_fma_f32 v[62:63], v[206:207], v[62:63], v[222:223]
	v_cvt_pk_bf16_f32 v242, v60, v61
	v_cvt_pk_bf16_f32 v243, v62, v63
	global_store_dwordx4 v82, v[240:243], s[48:49] offset:1024
	s_add_u32 s34, s8, 0x27000
	s_addc_u32 s35, s9, 0
	s_add_u32 s36, s8, 0x27000
	s_addc_u32 s37, s9, 0
	global_load_dwordx4 v[176:179], v80, s[34:35] offset:0
	global_load_dwordx4 v[180:183], v80, s[34:35] offset:16
	global_load_dwordx4 v[184:187], v80, s[34:35] offset:2048
	global_load_dwordx4 v[188:191], v80, s[34:35] offset:2064
	global_load_dwordx4 v[160:163], v81, s[34:35] offset:0
	global_load_dwordx4 v[164:167], v81, s[34:35] offset:16
	global_load_dwordx4 v[168:171], v81, s[34:35] offset:2048
	global_load_dwordx4 v[172:175], v81, s[34:35] offset:2064
	global_load_dwordx4 v[208:211], v80, s[36:37] offset:0
	global_load_dwordx4 v[212:215], v80, s[36:37] offset:16
	global_load_dwordx4 v[216:219], v80, s[36:37] offset:2048
	global_load_dwordx4 v[220:223], v80, s[36:37] offset:2064
	global_load_dwordx4 v[192:195], v81, s[36:37] offset:0
	global_load_dwordx4 v[196:199], v81, s[36:37] offset:16
	global_load_dwordx4 v[200:203], v81, s[36:37] offset:2048
	global_load_dwordx4 v[204:207], v81, s[36:37] offset:2064
	s_add_u32 s24, s16, 0x7000000
	s_addc_u32 s25, s17, 0
	s_add_u32 s26, s16, 0x7400000
	s_addc_u32 s27, s17, 0
	s_add_u32 s28, s16, 0x7800000
	s_addc_u32 s29, s17, 0
	s_add_u32 s30, s16, 0x7c00000
	s_addc_u32 s31, s17, 0
	global_load_dwordx4 v[128:131], v82, s[24:25] offset:0
	global_load_dwordx4 v[132:135], v82, s[24:25] offset:1024
	global_load_dwordx4 v[136:139], v82, s[26:27] offset:0
	global_load_dwordx4 v[140:143], v82, s[26:27] offset:1024
	global_load_dwordx4 v[144:147], v82, s[28:29] offset:0
	global_load_dwordx4 v[148:151], v82, s[28:29] offset:1024
	global_load_dwordx4 v[152:155], v82, s[30:31] offset:0
	global_load_dwordx4 v[156:159], v82, s[30:31] offset:1024
	s_waitcnt vmcnt(32)
	v_lshlrev_b32_e32 v0, 16, v96
	v_and_b32_e32 v1, 0xffff0000, v96
	v_lshlrev_b32_e32 v2, 16, v97
	v_and_b32_e32 v3, 0xffff0000, v97
	v_lshlrev_b32_e32 v4, 16, v98
	v_and_b32_e32 v5, 0xffff0000, v98
	v_lshlrev_b32_e32 v6, 16, v99
	v_and_b32_e32 v7, 0xffff0000, v99
	v_lshlrev_b32_e32 v8, 16, v100
	v_and_b32_e32 v9, 0xffff0000, v100
	v_lshlrev_b32_e32 v10, 16, v101
	v_and_b32_e32 v11, 0xffff0000, v101
	v_lshlrev_b32_e32 v12, 16, v102
	v_and_b32_e32 v13, 0xffff0000, v102
	v_lshlrev_b32_e32 v14, 16, v103
	v_and_b32_e32 v15, 0xffff0000, v103
	v_lshlrev_b32_e32 v16, 16, v104
	v_and_b32_e32 v17, 0xffff0000, v104
	v_lshlrev_b32_e32 v18, 16, v105
	v_and_b32_e32 v19, 0xffff0000, v105
	v_lshlrev_b32_e32 v20, 16, v106
	v_and_b32_e32 v21, 0xffff0000, v106
	v_lshlrev_b32_e32 v22, 16, v107
	v_and_b32_e32 v23, 0xffff0000, v107
	v_lshlrev_b32_e32 v24, 16, v108
	v_and_b32_e32 v25, 0xffff0000, v108
	v_lshlrev_b32_e32 v26, 16, v109
	v_and_b32_e32 v27, 0xffff0000, v109
	v_lshlrev_b32_e32 v28, 16, v110
	v_and_b32_e32 v29, 0xffff0000, v110
	v_lshlrev_b32_e32 v30, 16, v111
	v_and_b32_e32 v31, 0xffff0000, v111
	v_lshlrev_b32_e32 v32, 16, v112
	v_and_b32_e32 v33, 0xffff0000, v112
	v_lshlrev_b32_e32 v34, 16, v113
	v_and_b32_e32 v35, 0xffff0000, v113
	v_lshlrev_b32_e32 v36, 16, v114
	v_and_b32_e32 v37, 0xffff0000, v114
	v_lshlrev_b32_e32 v38, 16, v115
	v_and_b32_e32 v39, 0xffff0000, v115
	v_lshlrev_b32_e32 v40, 16, v116
	v_and_b32_e32 v41, 0xffff0000, v116
	v_lshlrev_b32_e32 v42, 16, v117
	v_and_b32_e32 v43, 0xffff0000, v117
	v_lshlrev_b32_e32 v44, 16, v118
	v_and_b32_e32 v45, 0xffff0000, v118
	v_lshlrev_b32_e32 v46, 16, v119
	v_and_b32_e32 v47, 0xffff0000, v119
	v_lshlrev_b32_e32 v48, 16, v120
	v_and_b32_e32 v49, 0xffff0000, v120
	v_lshlrev_b32_e32 v50, 16, v121
	v_and_b32_e32 v51, 0xffff0000, v121
	v_lshlrev_b32_e32 v52, 16, v122
	v_and_b32_e32 v53, 0xffff0000, v122
	v_lshlrev_b32_e32 v54, 16, v123
	v_and_b32_e32 v55, 0xffff0000, v123
	v_lshlrev_b32_e32 v56, 16, v124
	v_and_b32_e32 v57, 0xffff0000, v124
	v_lshlrev_b32_e32 v58, 16, v125
	v_and_b32_e32 v59, 0xffff0000, v125
	v_lshlrev_b32_e32 v60, 16, v126
	v_and_b32_e32 v61, 0xffff0000, v126
	v_lshlrev_b32_e32 v62, 16, v127
	v_and_b32_e32 v63, 0xffff0000, v127
	v_pk_mul_f32 v[240:241], v[0:1], v[0:1]
	v_pk_mul_f32 v[242:243], v[16:17], v[16:17]
	v_pk_mul_f32 v[244:245], v[32:33], v[32:33]
	v_pk_mul_f32 v[246:247], v[48:49], v[48:49]
	v_pk_fma_f32 v[240:241], v[2:3], v[2:3], v[240:241]
	v_pk_fma_f32 v[242:243], v[18:19], v[18:19], v[242:243]
	v_pk_fma_f32 v[244:245], v[34:35], v[34:35], v[244:245]
	v_pk_fma_f32 v[246:247], v[50:51], v[50:51], v[246:247]
	v_pk_fma_f32 v[240:241], v[4:5], v[4:5], v[240:241]
	v_pk_fma_f32 v[242:243], v[20:21], v[20:21], v[242:243]
	v_pk_fma_f32 v[244:245], v[36:37], v[36:37], v[244:245]
	v_pk_fma_f32 v[246:247], v[52:53], v[52:53], v[246:247]
	v_pk_fma_f32 v[240:241], v[6:7], v[6:7], v[240:241]
	v_pk_fma_f32 v[242:243], v[22:23], v[22:23], v[242:243]
	v_pk_fma_f32 v[244:245], v[38:39], v[38:39], v[244:245]
	v_pk_fma_f32 v[246:247], v[54:55], v[54:55], v[246:247]
	v_pk_fma_f32 v[240:241], v[8:9], v[8:9], v[240:241]
	v_pk_fma_f32 v[242:243], v[24:25], v[24:25], v[242:243]
	v_pk_fma_f32 v[244:245], v[40:41], v[40:41], v[244:245]
	v_pk_fma_f32 v[246:247], v[56:57], v[56:57], v[246:247]
	v_pk_fma_f32 v[240:241], v[10:11], v[10:11], v[240:241]
	v_pk_fma_f32 v[242:243], v[26:27], v[26:27], v[242:243]
	v_pk_fma_f32 v[244:245], v[42:43], v[42:43], v[244:245]
	v_pk_fma_f32 v[246:247], v[58:59], v[58:59], v[246:247]
	v_pk_fma_f32 v[240:241], v[12:13], v[12:13], v[240:241]
	v_pk_fma_f32 v[242:243], v[28:29], v[28:29], v[242:243]
	v_pk_fma_f32 v[244:245], v[44:45], v[44:45], v[244:245]
	v_pk_fma_f32 v[246:247], v[60:61], v[60:61], v[246:247]
	v_pk_fma_f32 v[240:241], v[14:15], v[14:15], v[240:241]
	v_pk_fma_f32 v[242:243], v[30:31], v[30:31], v[242:243]
	v_pk_fma_f32 v[244:245], v[46:47], v[46:47], v[244:245]
	v_pk_fma_f32 v[246:247], v[62:63], v[62:63], v[246:247]
	v_add_f32_e32 v224, v240, v241
	v_add_f32_e32 v225, v242, v243
	v_add_f32_e32 v226, v244, v245
	v_add_f32_e32 v227, v246, v247
	ds_bpermute_b32 v228, v83, v224
	ds_bpermute_b32 v229, v83, v225
	ds_bpermute_b32 v230, v83, v226
	ds_bpermute_b32 v231, v83, v227
	s_waitcnt lgkmcnt(0)
	v_add_f32_e32 v224, v224, v228
	v_add_f32_e32 v225, v225, v229
	v_add_f32_e32 v226, v226, v230
	v_add_f32_e32 v227, v227, v231
	ds_bpermute_b32 v228, v84, v224
	ds_bpermute_b32 v229, v84, v225
	ds_bpermute_b32 v230, v84, v226
	ds_bpermute_b32 v231, v84, v227
	s_waitcnt lgkmcnt(0)
	v_add_f32_e32 v224, v224, v228
	v_add_f32_e32 v225, v225, v229
	v_add_f32_e32 v226, v226, v230
	v_add_f32_e32 v227, v227, v231
	ds_bpermute_b32 v228, v85, v224
	ds_bpermute_b32 v229, v85, v225
	ds_bpermute_b32 v230, v85, v226
	ds_bpermute_b32 v231, v85, v227
	s_waitcnt lgkmcnt(0)
	v_add_f32_e32 v224, v224, v228
	v_add_f32_e32 v225, v225, v229
	v_add_f32_e32 v226, v226, v230
	v_add_f32_e32 v227, v227, v231
	ds_bpermute_b32 v228, v86, v224
	ds_bpermute_b32 v229, v86, v225
	ds_bpermute_b32 v230, v86, v226
	ds_bpermute_b32 v231, v86, v227
	s_waitcnt lgkmcnt(0)
	v_add_f32_e32 v224, v224, v228
	v_add_f32_e32 v225, v225, v229
	v_add_f32_e32 v226, v226, v230
	v_add_f32_e32 v227, v227, v231
	ds_bpermute_b32 v228, v87, v224
	ds_bpermute_b32 v229, v87, v225
	ds_bpermute_b32 v230, v87, v226
	ds_bpermute_b32 v231, v87, v227
	s_waitcnt lgkmcnt(0)
	v_add_f32_e32 v224, v224, v228
	v_add_f32_e32 v225, v225, v229
	v_add_f32_e32 v226, v226, v230
	v_add_f32_e32 v227, v227, v231
	ds_bpermute_b32 v228, v88, v224
	ds_bpermute_b32 v229, v88, v225
	ds_bpermute_b32 v230, v88, v226
	ds_bpermute_b32 v231, v88, v227
	s_waitcnt lgkmcnt(0)
	v_add_f32_e32 v224, v224, v228
	v_add_f32_e32 v225, v225, v229
	v_add_f32_e32 v226, v226, v230
	v_add_f32_e32 v227, v227, v231
	v_fmamk_f32 v240, v224, 0x3a800000, v89
	v_mul_f32_e32 v241, 0x4f800000, v240
	v_cmp_gt_f32_e32 vcc, s54, v240
	s_nop 1
	v_cndmask_b32_e32 v247, v240, v241, vcc
	v_sqrt_f32_e32 v242, v247
	s_nop 1
	v_add_u32_e32 v243, -1, v242
	v_add_u32_e32 v244, 1, v242
	v_fma_f32 v245, -v243, v242, v247
	v_fma_f32 v246, -v244, v242, v247
	v_cmp_ge_f32_e64 s[52:53], 0, v245
	s_nop 1
	v_cndmask_b32_e64 v242, v242, v243, s[52:53]
	v_cmp_lt_f32_e64 s[52:53], 0, v246
	s_nop 1
	v_cndmask_b32_e64 v242, v242, v244, s[52:53]
	v_mul_f32_e32 v243, 0x37800000, v242
	v_cndmask_b32_e32 v242, v242, v243, vcc
	v_cmp_class_f32_e32 vcc, v247, v90
	s_nop 1
	v_cndmask_b32_e32 v247, v242, v247, vcc
	v_div_scale_f32 v248, s[52:53], v247, v247, 1.0
	v_rcp_f32_e32 v249, v248
	v_div_scale_f32 v228, vcc, 1.0, v247, 1.0
	s_nop 0
	v_fma_f32 v229, -v248, v249, 1.0
	v_fmac_f32_e32 v249, v229, v249
	v_mul_f32_e32 v230, v228, v249
	v_fma_f32 v229, -v248, v230, v228
	v_fmac_f32_e32 v230, v229, v249
	v_fma_f32 v248, -v248, v230, v228
	v_div_fmas_f32 v248, v248, v249, v230
	v_div_fixup_f32 v232, v248, v247, 1.0
	v_fmamk_f32 v240, v225, 0x3a800000, v89
	v_mul_f32_e32 v241, 0x4f800000, v240
	v_cmp_gt_f32_e32 vcc, s54, v240
	s_nop 1
	v_cndmask_b32_e32 v247, v240, v241, vcc
	v_sqrt_f32_e32 v242, v247
	s_nop 1
	v_add_u32_e32 v243, -1, v242
	v_add_u32_e32 v244, 1, v242
	v_fma_f32 v245, -v243, v242, v247
	v_fma_f32 v246, -v244, v242, v247
	v_cmp_ge_f32_e64 s[52:53], 0, v245
	s_nop 1
	v_cndmask_b32_e64 v242, v242, v243, s[52:53]
	v_cmp_lt_f32_e64 s[52:53], 0, v246
	s_nop 1
	v_cndmask_b32_e64 v242, v242, v244, s[52:53]
	v_mul_f32_e32 v243, 0x37800000, v242
	v_cndmask_b32_e32 v242, v242, v243, vcc
	v_cmp_class_f32_e32 vcc, v247, v90
	s_nop 1
	v_cndmask_b32_e32 v247, v242, v247, vcc
	v_div_scale_f32 v248, s[52:53], v247, v247, 1.0
	v_rcp_f32_e32 v249, v248
	v_div_scale_f32 v228, vcc, 1.0, v247, 1.0
	s_nop 0
	v_fma_f32 v229, -v248, v249, 1.0
	v_fmac_f32_e32 v249, v229, v249
	v_mul_f32_e32 v230, v228, v249
	v_fma_f32 v229, -v248, v230, v228
	v_fmac_f32_e32 v230, v229, v249
	v_fma_f32 v248, -v248, v230, v228
	v_div_fmas_f32 v248, v248, v249, v230
	v_div_fixup_f32 v234, v248, v247, 1.0
	v_fmamk_f32 v240, v226, 0x3a800000, v89
	v_mul_f32_e32 v241, 0x4f800000, v240
	v_cmp_gt_f32_e32 vcc, s54, v240
	s_nop 1
	v_cndmask_b32_e32 v247, v240, v241, vcc
	v_sqrt_f32_e32 v242, v247
	s_nop 1
	v_add_u32_e32 v243, -1, v242
	v_add_u32_e32 v244, 1, v242
	v_fma_f32 v245, -v243, v242, v247
	v_fma_f32 v246, -v244, v242, v247
	v_cmp_ge_f32_e64 s[52:53], 0, v245
	s_nop 1
	v_cndmask_b32_e64 v242, v242, v243, s[52:53]
	v_cmp_lt_f32_e64 s[52:53], 0, v246
	s_nop 1
	v_cndmask_b32_e64 v242, v242, v244, s[52:53]
	v_mul_f32_e32 v243, 0x37800000, v242
	v_cndmask_b32_e32 v242, v242, v243, vcc
	v_cmp_class_f32_e32 vcc, v247, v90
	s_nop 1
	v_cndmask_b32_e32 v247, v242, v247, vcc
	v_div_scale_f32 v248, s[52:53], v247, v247, 1.0
	v_rcp_f32_e32 v249, v248
	v_div_scale_f32 v228, vcc, 1.0, v247, 1.0
	s_nop 0
	v_fma_f32 v229, -v248, v249, 1.0
	v_fmac_f32_e32 v249, v229, v249
	v_mul_f32_e32 v230, v228, v249
	v_fma_f32 v229, -v248, v230, v228
	v_fmac_f32_e32 v230, v229, v249
	v_fma_f32 v248, -v248, v230, v228
	v_div_fmas_f32 v248, v248, v249, v230
	v_div_fixup_f32 v236, v248, v247, 1.0
	v_fmamk_f32 v240, v227, 0x3a800000, v89
	v_mul_f32_e32 v241, 0x4f800000, v240
	v_cmp_gt_f32_e32 vcc, s54, v240
	s_nop 1
	v_cndmask_b32_e32 v247, v240, v241, vcc
	v_sqrt_f32_e32 v242, v247
	s_nop 1
	v_add_u32_e32 v243, -1, v242
	v_add_u32_e32 v244, 1, v242
	v_fma_f32 v245, -v243, v242, v247
	v_fma_f32 v246, -v244, v242, v247
	v_cmp_ge_f32_e64 s[52:53], 0, v245
	s_nop 1
	v_cndmask_b32_e64 v242, v242, v243, s[52:53]
	v_cmp_lt_f32_e64 s[52:53], 0, v246
	s_nop 1
	v_cndmask_b32_e64 v242, v242, v244, s[52:53]
	v_mul_f32_e32 v243, 0x37800000, v242
	v_cndmask_b32_e32 v242, v242, v243, vcc
	v_cmp_class_f32_e32 vcc, v247, v90
	s_nop 1
	v_cndmask_b32_e32 v247, v242, v247, vcc
	v_div_scale_f32 v248, s[52:53], v247, v247, 1.0
	v_rcp_f32_e32 v249, v248
	v_div_scale_f32 v228, vcc, 1.0, v247, 1.0
	s_nop 0
	v_fma_f32 v229, -v248, v249, 1.0
	v_fmac_f32_e32 v249, v229, v249
	v_mul_f32_e32 v230, v228, v249
	v_fma_f32 v229, -v248, v230, v228
	v_fmac_f32_e32 v230, v229, v249
	v_fma_f32 v248, -v248, v230, v228
	v_div_fmas_f32 v248, v248, v249, v230
	v_div_fixup_f32 v238, v248, v247, 1.0
	s_waitcnt vmcnt(8)
	v_pk_add_f32 v[160:161], v[160:161], 1.0 op_sel_hi:[1,0]
	v_pk_add_f32 v[162:163], v[162:163], 1.0 op_sel_hi:[1,0]
	v_pk_add_f32 v[164:165], v[164:165], 1.0 op_sel_hi:[1,0]
	v_pk_add_f32 v[166:167], v[166:167], 1.0 op_sel_hi:[1,0]
	v_pk_add_f32 v[168:169], v[168:169], 1.0 op_sel_hi:[1,0]
	v_pk_add_f32 v[170:171], v[170:171], 1.0 op_sel_hi:[1,0]
	v_pk_add_f32 v[172:173], v[172:173], 1.0 op_sel_hi:[1,0]
	v_pk_add_f32 v[174:175], v[174:175], 1.0 op_sel_hi:[1,0]
	v_pk_add_f32 v[192:193], v[192:193], 1.0 op_sel_hi:[1,0]
	v_pk_add_f32 v[194:195], v[194:195], 1.0 op_sel_hi:[1,0]
	v_pk_add_f32 v[196:197], v[196:197], 1.0 op_sel_hi:[1,0]
	v_pk_add_f32 v[198:199], v[198:199], 1.0 op_sel_hi:[1,0]
	v_pk_add_f32 v[200:201], v[200:201], 1.0 op_sel_hi:[1,0]
	v_pk_add_f32 v[202:203], v[202:203], 1.0 op_sel_hi:[1,0]
	v_pk_add_f32 v[204:205], v[204:205], 1.0 op_sel_hi:[1,0]
	v_pk_add_f32 v[206:207], v[206:207], 1.0 op_sel_hi:[1,0]
	s_add_u32 s38, s20, 0x6000000
	s_addc_u32 s39, s21, 0
	s_add_u32 s40, s20, 0x6400000
	s_addc_u32 s41, s21, 0
	s_add_u32 s46, s20, 0x6800000
	s_addc_u32 s47, s21, 0
	s_add_u32 s48, s20, 0x6c00000
	s_addc_u32 s49, s21, 0
	v_pk_mul_f32 v[0:1], v[0:1], v[232:233] op_sel_hi:[1,0]
	v_pk_mul_f32 v[2:3], v[2:3], v[232:233] op_sel_hi:[1,0]
	v_pk_mul_f32 v[0:1], v[64:65], v[0:1]
	v_pk_mul_f32 v[2:3], v[66:67], v[2:3]
	v_pk_fma_f32 v[0:1], v[160:161], v[0:1], v[176:177]
	v_pk_fma_f32 v[2:3], v[162:163], v[2:3], v[178:179]
	v_cvt_pk_bf16_f32 v244, v0, v1
	v_cvt_pk_bf16_f32 v245, v2, v3
	v_pk_mul_f32 v[4:5], v[4:5], v[232:233] op_sel_hi:[1,0]
	v_pk_mul_f32 v[6:7], v[6:7], v[232:233] op_sel_hi:[1,0]
	v_pk_mul_f32 v[4:5], v[68:69], v[4:5]
	v_pk_mul_f32 v[6:7], v[70:71], v[6:7]
	v_pk_fma_f32 v[4:5], v[164:165], v[4:5], v[180:181]
	v_pk_fma_f32 v[6:7], v[166:167], v[6:7], v[182:183]
	v_cvt_pk_bf16_f32 v246, v4, v5
	v_cvt_pk_bf16_f32 v247, v6, v7
	global_store_dwordx4 v82, v[244:247], s[38:39] offset:0
	v_pk_mul_f32 v[8:9], v[8:9], v[232:233] op_sel_hi:[1,0]
	v_pk_mul_f32 v[10:11], v[10:11], v[232:233] op_sel_hi:[1,0]
	v_pk_mul_f32 v[8:9], v[72:73], v[8:9]
	v_pk_mul_f32 v[10:11], v[74:75], v[10:11]
	v_pk_fma_f32 v[8:9], v[168:169], v[8:9], v[184:185]
	v_pk_fma_f32 v[10:11], v[170:171], v[10:11], v[186:187]
	v_cvt_pk_bf16_f32 v240, v8, v9
	v_cvt_pk_bf16_f32 v241, v10, v11
	v_pk_mul_f32 v[12:13], v[12:13], v[232:233] op_sel_hi:[1,0]
	v_pk_mul_f32 v[14:15], v[14:15], v[232:233] op_sel_hi:[1,0]
	v_pk_mul_f32 v[12:13], v[76:77], v[12:13]
	v_pk_mul_f32 v[14:15], v[78:79], v[14:15]
	v_pk_fma_f32 v[12:13], v[172:173], v[12:13], v[188:189]
	v_pk_fma_f32 v[14:15], v[174:175], v[14:15], v[190:191]
	v_cvt_pk_bf16_f32 v242, v12, v13
	v_cvt_pk_bf16_f32 v243, v14, v15
	global_store_dwordx4 v82, v[240:243], s[38:39] offset:1024
	v_pk_mul_f32 v[16:17], v[16:17], v[234:235] op_sel_hi:[1,0]
	v_pk_mul_f32 v[18:19], v[18:19], v[234:235] op_sel_hi:[1,0]
	v_pk_mul_f32 v[16:17], v[64:65], v[16:17]
	v_pk_mul_f32 v[18:19], v[66:67], v[18:19]
	v_pk_fma_f32 v[16:17], v[160:161], v[16:17], v[176:177]
	v_pk_fma_f32 v[18:19], v[162:163], v[18:19], v[178:179]
	v_cvt_pk_bf16_f32 v244, v16, v17
	v_cvt_pk_bf16_f32 v245, v18, v19
	v_pk_mul_f32 v[20:21], v[20:21], v[234:235] op_sel_hi:[1,0]
	v_pk_mul_f32 v[22:23], v[22:23], v[234:235] op_sel_hi:[1,0]
	v_pk_mul_f32 v[20:21], v[68:69], v[20:21]
	v_pk_mul_f32 v[22:23], v[70:71], v[22:23]
	v_pk_fma_f32 v[20:21], v[164:165], v[20:21], v[180:181]
	v_pk_fma_f32 v[22:23], v[166:167], v[22:23], v[182:183]
	v_cvt_pk_bf16_f32 v246, v20, v21
	v_cvt_pk_bf16_f32 v247, v22, v23
	global_store_dwordx4 v82, v[244:247], s[40:41] offset:0
	v_pk_mul_f32 v[24:25], v[24:25], v[234:235] op_sel_hi:[1,0]
	v_pk_mul_f32 v[26:27], v[26:27], v[234:235] op_sel_hi:[1,0]
	v_pk_mul_f32 v[24:25], v[72:73], v[24:25]
	v_pk_mul_f32 v[26:27], v[74:75], v[26:27]
	v_pk_fma_f32 v[24:25], v[168:169], v[24:25], v[184:185]
	v_pk_fma_f32 v[26:27], v[170:171], v[26:27], v[186:187]
	v_cvt_pk_bf16_f32 v240, v24, v25
	v_cvt_pk_bf16_f32 v241, v26, v27
	v_pk_mul_f32 v[28:29], v[28:29], v[234:235] op_sel_hi:[1,0]
	v_pk_mul_f32 v[30:31], v[30:31], v[234:235] op_sel_hi:[1,0]
	v_pk_mul_f32 v[28:29], v[76:77], v[28:29]
	v_pk_mul_f32 v[30:31], v[78:79], v[30:31]
	v_pk_fma_f32 v[28:29], v[172:173], v[28:29], v[188:189]
	v_pk_fma_f32 v[30:31], v[174:175], v[30:31], v[190:191]
	v_cvt_pk_bf16_f32 v242, v28, v29
	v_cvt_pk_bf16_f32 v243, v30, v31
	global_store_dwordx4 v82, v[240:243], s[40:41] offset:1024
	v_pk_mul_f32 v[32:33], v[32:33], v[236:237] op_sel_hi:[1,0]
	v_pk_mul_f32 v[34:35], v[34:35], v[236:237] op_sel_hi:[1,0]
	v_pk_mul_f32 v[32:33], v[64:65], v[32:33]
	v_pk_mul_f32 v[34:35], v[66:67], v[34:35]
	v_pk_fma_f32 v[32:33], v[192:193], v[32:33], v[208:209]
	v_pk_fma_f32 v[34:35], v[194:195], v[34:35], v[210:211]
	v_cvt_pk_bf16_f32 v244, v32, v33
	v_cvt_pk_bf16_f32 v245, v34, v35
	v_pk_mul_f32 v[36:37], v[36:37], v[236:237] op_sel_hi:[1,0]
	v_pk_mul_f32 v[38:39], v[38:39], v[236:237] op_sel_hi:[1,0]
	v_pk_mul_f32 v[36:37], v[68:69], v[36:37]
	v_pk_mul_f32 v[38:39], v[70:71], v[38:39]
	v_pk_fma_f32 v[36:37], v[196:197], v[36:37], v[212:213]
	v_pk_fma_f32 v[38:39], v[198:199], v[38:39], v[214:215]
	v_cvt_pk_bf16_f32 v246, v36, v37
	v_cvt_pk_bf16_f32 v247, v38, v39
	global_store_dwordx4 v82, v[244:247], s[46:47] offset:0
	v_pk_mul_f32 v[40:41], v[40:41], v[236:237] op_sel_hi:[1,0]
	v_pk_mul_f32 v[42:43], v[42:43], v[236:237] op_sel_hi:[1,0]
	v_pk_mul_f32 v[40:41], v[72:73], v[40:41]
	v_pk_mul_f32 v[42:43], v[74:75], v[42:43]
	v_pk_fma_f32 v[40:41], v[200:201], v[40:41], v[216:217]
	v_pk_fma_f32 v[42:43], v[202:203], v[42:43], v[218:219]
	v_cvt_pk_bf16_f32 v240, v40, v41
	v_cvt_pk_bf16_f32 v241, v42, v43
	v_pk_mul_f32 v[44:45], v[44:45], v[236:237] op_sel_hi:[1,0]
	v_pk_mul_f32 v[46:47], v[46:47], v[236:237] op_sel_hi:[1,0]
	v_pk_mul_f32 v[44:45], v[76:77], v[44:45]
	v_pk_mul_f32 v[46:47], v[78:79], v[46:47]
	v_pk_fma_f32 v[44:45], v[204:205], v[44:45], v[220:221]
	v_pk_fma_f32 v[46:47], v[206:207], v[46:47], v[222:223]
	v_cvt_pk_bf16_f32 v242, v44, v45
	v_cvt_pk_bf16_f32 v243, v46, v47
	global_store_dwordx4 v82, v[240:243], s[46:47] offset:1024
	v_pk_mul_f32 v[48:49], v[48:49], v[238:239] op_sel_hi:[1,0]
	v_pk_mul_f32 v[50:51], v[50:51], v[238:239] op_sel_hi:[1,0]
	v_pk_mul_f32 v[48:49], v[64:65], v[48:49]
	v_pk_mul_f32 v[50:51], v[66:67], v[50:51]
	v_pk_fma_f32 v[48:49], v[192:193], v[48:49], v[208:209]
	v_pk_fma_f32 v[50:51], v[194:195], v[50:51], v[210:211]
	v_cvt_pk_bf16_f32 v244, v48, v49
	v_cvt_pk_bf16_f32 v245, v50, v51
	v_pk_mul_f32 v[52:53], v[52:53], v[238:239] op_sel_hi:[1,0]
	v_pk_mul_f32 v[54:55], v[54:55], v[238:239] op_sel_hi:[1,0]
	v_pk_mul_f32 v[52:53], v[68:69], v[52:53]
	v_pk_mul_f32 v[54:55], v[70:71], v[54:55]
	v_pk_fma_f32 v[52:53], v[196:197], v[52:53], v[212:213]
	v_pk_fma_f32 v[54:55], v[198:199], v[54:55], v[214:215]
	v_cvt_pk_bf16_f32 v246, v52, v53
	v_cvt_pk_bf16_f32 v247, v54, v55
	global_store_dwordx4 v82, v[244:247], s[48:49] offset:0
	v_pk_mul_f32 v[56:57], v[56:57], v[238:239] op_sel_hi:[1,0]
	v_pk_mul_f32 v[58:59], v[58:59], v[238:239] op_sel_hi:[1,0]
	v_pk_mul_f32 v[56:57], v[72:73], v[56:57]
	v_pk_mul_f32 v[58:59], v[74:75], v[58:59]
	v_pk_fma_f32 v[56:57], v[200:201], v[56:57], v[216:217]
	v_pk_fma_f32 v[58:59], v[202:203], v[58:59], v[218:219]
	v_cvt_pk_bf16_f32 v240, v56, v57
	v_cvt_pk_bf16_f32 v241, v58, v59
	v_pk_mul_f32 v[60:61], v[60:61], v[238:239] op_sel_hi:[1,0]
	v_pk_mul_f32 v[62:63], v[62:63], v[238:239] op_sel_hi:[1,0]
	v_pk_mul_f32 v[60:61], v[76:77], v[60:61]
	v_pk_mul_f32 v[62:63], v[78:79], v[62:63]
	v_pk_fma_f32 v[60:61], v[204:205], v[60:61], v[220:221]
	v_pk_fma_f32 v[62:63], v[206:207], v[62:63], v[222:223]
	v_cvt_pk_bf16_f32 v242, v60, v61
	v_cvt_pk_bf16_f32 v243, v62, v63
	global_store_dwordx4 v82, v[240:243], s[48:49] offset:1024
	s_add_u32 s34, s8, 0x2d000
	s_addc_u32 s35, s9, 0
	s_add_u32 s36, s8, 0x2d000
	s_addc_u32 s37, s9, 0
	global_load_dwordx4 v[176:179], v80, s[34:35] offset:0
	global_load_dwordx4 v[180:183], v80, s[34:35] offset:16
	global_load_dwordx4 v[184:187], v80, s[34:35] offset:2048
	global_load_dwordx4 v[188:191], v80, s[34:35] offset:2064
	global_load_dwordx4 v[160:163], v81, s[34:35] offset:0
	global_load_dwordx4 v[164:167], v81, s[34:35] offset:16
	global_load_dwordx4 v[168:171], v81, s[34:35] offset:2048
	global_load_dwordx4 v[172:175], v81, s[34:35] offset:2064
	global_load_dwordx4 v[208:211], v80, s[36:37] offset:0
	global_load_dwordx4 v[212:215], v80, s[36:37] offset:16
	global_load_dwordx4 v[216:219], v80, s[36:37] offset:2048
	global_load_dwordx4 v[220:223], v80, s[36:37] offset:2064
	global_load_dwordx4 v[192:195], v81, s[36:37] offset:0
	global_load_dwordx4 v[196:199], v81, s[36:37] offset:16
	global_load_dwordx4 v[200:203], v81, s[36:37] offset:2048
	global_load_dwordx4 v[204:207], v81, s[36:37] offset:2064
	s_add_u32 s24, s16, 0x8000000
	s_addc_u32 s25, s17, 0
	s_add_u32 s26, s16, 0x8400000
	s_addc_u32 s27, s17, 0
	s_add_u32 s28, s16, 0x8800000
	s_addc_u32 s29, s17, 0
	s_add_u32 s30, s16, 0x8c00000
	s_addc_u32 s31, s17, 0
	global_load_dwordx4 v[96:99], v82, s[24:25] offset:0
	global_load_dwordx4 v[100:103], v82, s[24:25] offset:1024
	global_load_dwordx4 v[104:107], v82, s[26:27] offset:0
	global_load_dwordx4 v[108:111], v82, s[26:27] offset:1024
	global_load_dwordx4 v[112:115], v82, s[28:29] offset:0
	global_load_dwordx4 v[116:119], v82, s[28:29] offset:1024
	global_load_dwordx4 v[120:123], v82, s[30:31] offset:0
	global_load_dwordx4 v[124:127], v82, s[30:31] offset:1024
	s_waitcnt vmcnt(32)
	v_lshlrev_b32_e32 v0, 16, v128
	v_and_b32_e32 v1, 0xffff0000, v128
	v_lshlrev_b32_e32 v2, 16, v129
	v_and_b32_e32 v3, 0xffff0000, v129
	v_lshlrev_b32_e32 v4, 16, v130
	v_and_b32_e32 v5, 0xffff0000, v130
	v_lshlrev_b32_e32 v6, 16, v131
	v_and_b32_e32 v7, 0xffff0000, v131
	v_lshlrev_b32_e32 v8, 16, v132
	v_and_b32_e32 v9, 0xffff0000, v132
	v_lshlrev_b32_e32 v10, 16, v133
	v_and_b32_e32 v11, 0xffff0000, v133
	v_lshlrev_b32_e32 v12, 16, v134
	v_and_b32_e32 v13, 0xffff0000, v134
	v_lshlrev_b32_e32 v14, 16, v135
	v_and_b32_e32 v15, 0xffff0000, v135
	v_lshlrev_b32_e32 v16, 16, v136
	v_and_b32_e32 v17, 0xffff0000, v136
	v_lshlrev_b32_e32 v18, 16, v137
	v_and_b32_e32 v19, 0xffff0000, v137
	v_lshlrev_b32_e32 v20, 16, v138
	v_and_b32_e32 v21, 0xffff0000, v138
	v_lshlrev_b32_e32 v22, 16, v139
	v_and_b32_e32 v23, 0xffff0000, v139
	v_lshlrev_b32_e32 v24, 16, v140
	v_and_b32_e32 v25, 0xffff0000, v140
	v_lshlrev_b32_e32 v26, 16, v141
	v_and_b32_e32 v27, 0xffff0000, v141
	v_lshlrev_b32_e32 v28, 16, v142
	v_and_b32_e32 v29, 0xffff0000, v142
	v_lshlrev_b32_e32 v30, 16, v143
	v_and_b32_e32 v31, 0xffff0000, v143
	v_lshlrev_b32_e32 v32, 16, v144
	v_and_b32_e32 v33, 0xffff0000, v144
	v_lshlrev_b32_e32 v34, 16, v145
	v_and_b32_e32 v35, 0xffff0000, v145
	v_lshlrev_b32_e32 v36, 16, v146
	v_and_b32_e32 v37, 0xffff0000, v146
	v_lshlrev_b32_e32 v38, 16, v147
	v_and_b32_e32 v39, 0xffff0000, v147
	v_lshlrev_b32_e32 v40, 16, v148
	v_and_b32_e32 v41, 0xffff0000, v148
	v_lshlrev_b32_e32 v42, 16, v149
	v_and_b32_e32 v43, 0xffff0000, v149
	v_lshlrev_b32_e32 v44, 16, v150
	v_and_b32_e32 v45, 0xffff0000, v150
	v_lshlrev_b32_e32 v46, 16, v151
	v_and_b32_e32 v47, 0xffff0000, v151
	v_lshlrev_b32_e32 v48, 16, v152
	v_and_b32_e32 v49, 0xffff0000, v152
	v_lshlrev_b32_e32 v50, 16, v153
	v_and_b32_e32 v51, 0xffff0000, v153
	v_lshlrev_b32_e32 v52, 16, v154
	v_and_b32_e32 v53, 0xffff0000, v154
	v_lshlrev_b32_e32 v54, 16, v155
	v_and_b32_e32 v55, 0xffff0000, v155
	v_lshlrev_b32_e32 v56, 16, v156
	v_and_b32_e32 v57, 0xffff0000, v156
	v_lshlrev_b32_e32 v58, 16, v157
	v_and_b32_e32 v59, 0xffff0000, v157
	v_lshlrev_b32_e32 v60, 16, v158
	v_and_b32_e32 v61, 0xffff0000, v158
	v_lshlrev_b32_e32 v62, 16, v159
	v_and_b32_e32 v63, 0xffff0000, v159
	v_pk_mul_f32 v[240:241], v[0:1], v[0:1]
	v_pk_mul_f32 v[242:243], v[16:17], v[16:17]
	v_pk_mul_f32 v[244:245], v[32:33], v[32:33]
	v_pk_mul_f32 v[246:247], v[48:49], v[48:49]
	v_pk_fma_f32 v[240:241], v[2:3], v[2:3], v[240:241]
	v_pk_fma_f32 v[242:243], v[18:19], v[18:19], v[242:243]
	v_pk_fma_f32 v[244:245], v[34:35], v[34:35], v[244:245]
	v_pk_fma_f32 v[246:247], v[50:51], v[50:51], v[246:247]
	v_pk_fma_f32 v[240:241], v[4:5], v[4:5], v[240:241]
	v_pk_fma_f32 v[242:243], v[20:21], v[20:21], v[242:243]
	v_pk_fma_f32 v[244:245], v[36:37], v[36:37], v[244:245]
	v_pk_fma_f32 v[246:247], v[52:53], v[52:53], v[246:247]
	v_pk_fma_f32 v[240:241], v[6:7], v[6:7], v[240:241]
	v_pk_fma_f32 v[242:243], v[22:23], v[22:23], v[242:243]
	v_pk_fma_f32 v[244:245], v[38:39], v[38:39], v[244:245]
	v_pk_fma_f32 v[246:247], v[54:55], v[54:55], v[246:247]
	v_pk_fma_f32 v[240:241], v[8:9], v[8:9], v[240:241]
	v_pk_fma_f32 v[242:243], v[24:25], v[24:25], v[242:243]
	v_pk_fma_f32 v[244:245], v[40:41], v[40:41], v[244:245]
	v_pk_fma_f32 v[246:247], v[56:57], v[56:57], v[246:247]
	v_pk_fma_f32 v[240:241], v[10:11], v[10:11], v[240:241]
	v_pk_fma_f32 v[242:243], v[26:27], v[26:27], v[242:243]
	v_pk_fma_f32 v[244:245], v[42:43], v[42:43], v[244:245]
	v_pk_fma_f32 v[246:247], v[58:59], v[58:59], v[246:247]
	v_pk_fma_f32 v[240:241], v[12:13], v[12:13], v[240:241]
	v_pk_fma_f32 v[242:243], v[28:29], v[28:29], v[242:243]
	v_pk_fma_f32 v[244:245], v[44:45], v[44:45], v[244:245]
	v_pk_fma_f32 v[246:247], v[60:61], v[60:61], v[246:247]
	v_pk_fma_f32 v[240:241], v[14:15], v[14:15], v[240:241]
	v_pk_fma_f32 v[242:243], v[30:31], v[30:31], v[242:243]
	v_pk_fma_f32 v[244:245], v[46:47], v[46:47], v[244:245]
	v_pk_fma_f32 v[246:247], v[62:63], v[62:63], v[246:247]
	v_add_f32_e32 v224, v240, v241
	v_add_f32_e32 v225, v242, v243
	v_add_f32_e32 v226, v244, v245
	v_add_f32_e32 v227, v246, v247
	ds_bpermute_b32 v228, v83, v224
	ds_bpermute_b32 v229, v83, v225
	ds_bpermute_b32 v230, v83, v226
	ds_bpermute_b32 v231, v83, v227
	s_waitcnt lgkmcnt(0)
	v_add_f32_e32 v224, v224, v228
	v_add_f32_e32 v225, v225, v229
	v_add_f32_e32 v226, v226, v230
	v_add_f32_e32 v227, v227, v231
	ds_bpermute_b32 v228, v84, v224
	ds_bpermute_b32 v229, v84, v225
	ds_bpermute_b32 v230, v84, v226
	ds_bpermute_b32 v231, v84, v227
	s_waitcnt lgkmcnt(0)
	v_add_f32_e32 v224, v224, v228
	v_add_f32_e32 v225, v225, v229
	v_add_f32_e32 v226, v226, v230
	v_add_f32_e32 v227, v227, v231
	ds_bpermute_b32 v228, v85, v224
	ds_bpermute_b32 v229, v85, v225
	ds_bpermute_b32 v230, v85, v226
	ds_bpermute_b32 v231, v85, v227
	s_waitcnt lgkmcnt(0)
	v_add_f32_e32 v224, v224, v228
	v_add_f32_e32 v225, v225, v229
	v_add_f32_e32 v226, v226, v230
	v_add_f32_e32 v227, v227, v231
	ds_bpermute_b32 v228, v86, v224
	ds_bpermute_b32 v229, v86, v225
	ds_bpermute_b32 v230, v86, v226
	ds_bpermute_b32 v231, v86, v227
	s_waitcnt lgkmcnt(0)
	v_add_f32_e32 v224, v224, v228
	v_add_f32_e32 v225, v225, v229
	v_add_f32_e32 v226, v226, v230
	v_add_f32_e32 v227, v227, v231
	ds_bpermute_b32 v228, v87, v224
	ds_bpermute_b32 v229, v87, v225
	ds_bpermute_b32 v230, v87, v226
	ds_bpermute_b32 v231, v87, v227
	s_waitcnt lgkmcnt(0)
	v_add_f32_e32 v224, v224, v228
	v_add_f32_e32 v225, v225, v229
	v_add_f32_e32 v226, v226, v230
	v_add_f32_e32 v227, v227, v231
	ds_bpermute_b32 v228, v88, v224
	ds_bpermute_b32 v229, v88, v225
	ds_bpermute_b32 v230, v88, v226
	ds_bpermute_b32 v231, v88, v227
	s_waitcnt lgkmcnt(0)
	v_add_f32_e32 v224, v224, v228
	v_add_f32_e32 v225, v225, v229
	v_add_f32_e32 v226, v226, v230
	v_add_f32_e32 v227, v227, v231
	v_fmamk_f32 v240, v224, 0x3a800000, v89
	v_mul_f32_e32 v241, 0x4f800000, v240
	v_cmp_gt_f32_e32 vcc, s54, v240
	s_nop 1
	v_cndmask_b32_e32 v247, v240, v241, vcc
	v_sqrt_f32_e32 v242, v247
	s_nop 1
	v_add_u32_e32 v243, -1, v242
	v_add_u32_e32 v244, 1, v242
	v_fma_f32 v245, -v243, v242, v247
	v_fma_f32 v246, -v244, v242, v247
	v_cmp_ge_f32_e64 s[52:53], 0, v245
	s_nop 1
	v_cndmask_b32_e64 v242, v242, v243, s[52:53]
	v_cmp_lt_f32_e64 s[52:53], 0, v246
	s_nop 1
	v_cndmask_b32_e64 v242, v242, v244, s[52:53]
	v_mul_f32_e32 v243, 0x37800000, v242
	v_cndmask_b32_e32 v242, v242, v243, vcc
	v_cmp_class_f32_e32 vcc, v247, v90
	s_nop 1
	v_cndmask_b32_e32 v247, v242, v247, vcc
	v_div_scale_f32 v248, s[52:53], v247, v247, 1.0
	v_rcp_f32_e32 v249, v248
	v_div_scale_f32 v228, vcc, 1.0, v247, 1.0
	s_nop 0
	v_fma_f32 v229, -v248, v249, 1.0
	v_fmac_f32_e32 v249, v229, v249
	v_mul_f32_e32 v230, v228, v249
	v_fma_f32 v229, -v248, v230, v228
	v_fmac_f32_e32 v230, v229, v249
	v_fma_f32 v248, -v248, v230, v228
	v_div_fmas_f32 v248, v248, v249, v230
	v_div_fixup_f32 v232, v248, v247, 1.0
	v_fmamk_f32 v240, v225, 0x3a800000, v89
	v_mul_f32_e32 v241, 0x4f800000, v240
	v_cmp_gt_f32_e32 vcc, s54, v240
	s_nop 1
	v_cndmask_b32_e32 v247, v240, v241, vcc
	v_sqrt_f32_e32 v242, v247
	s_nop 1
	v_add_u32_e32 v243, -1, v242
	v_add_u32_e32 v244, 1, v242
	v_fma_f32 v245, -v243, v242, v247
	v_fma_f32 v246, -v244, v242, v247
	v_cmp_ge_f32_e64 s[52:53], 0, v245
	s_nop 1
	v_cndmask_b32_e64 v242, v242, v243, s[52:53]
	v_cmp_lt_f32_e64 s[52:53], 0, v246
	s_nop 1
	v_cndmask_b32_e64 v242, v242, v244, s[52:53]
	v_mul_f32_e32 v243, 0x37800000, v242
	v_cndmask_b32_e32 v242, v242, v243, vcc
	v_cmp_class_f32_e32 vcc, v247, v90
	s_nop 1
	v_cndmask_b32_e32 v247, v242, v247, vcc
	v_div_scale_f32 v248, s[52:53], v247, v247, 1.0
	v_rcp_f32_e32 v249, v248
	v_div_scale_f32 v228, vcc, 1.0, v247, 1.0
	s_nop 0
	v_fma_f32 v229, -v248, v249, 1.0
	v_fmac_f32_e32 v249, v229, v249
	v_mul_f32_e32 v230, v228, v249
	v_fma_f32 v229, -v248, v230, v228
	v_fmac_f32_e32 v230, v229, v249
	v_fma_f32 v248, -v248, v230, v228
	v_div_fmas_f32 v248, v248, v249, v230
	v_div_fixup_f32 v234, v248, v247, 1.0
	v_fmamk_f32 v240, v226, 0x3a800000, v89
	v_mul_f32_e32 v241, 0x4f800000, v240
	v_cmp_gt_f32_e32 vcc, s54, v240
	s_nop 1
	v_cndmask_b32_e32 v247, v240, v241, vcc
	v_sqrt_f32_e32 v242, v247
	s_nop 1
	v_add_u32_e32 v243, -1, v242
	v_add_u32_e32 v244, 1, v242
	v_fma_f32 v245, -v243, v242, v247
	v_fma_f32 v246, -v244, v242, v247
	v_cmp_ge_f32_e64 s[52:53], 0, v245
	s_nop 1
	v_cndmask_b32_e64 v242, v242, v243, s[52:53]
	v_cmp_lt_f32_e64 s[52:53], 0, v246
	s_nop 1
	v_cndmask_b32_e64 v242, v242, v244, s[52:53]
	v_mul_f32_e32 v243, 0x37800000, v242
	v_cndmask_b32_e32 v242, v242, v243, vcc
	v_cmp_class_f32_e32 vcc, v247, v90
	s_nop 1
	v_cndmask_b32_e32 v247, v242, v247, vcc
	v_div_scale_f32 v248, s[52:53], v247, v247, 1.0
	v_rcp_f32_e32 v249, v248
	v_div_scale_f32 v228, vcc, 1.0, v247, 1.0
	s_nop 0
	v_fma_f32 v229, -v248, v249, 1.0
	v_fmac_f32_e32 v249, v229, v249
	v_mul_f32_e32 v230, v228, v249
	v_fma_f32 v229, -v248, v230, v228
	v_fmac_f32_e32 v230, v229, v249
	v_fma_f32 v248, -v248, v230, v228
	v_div_fmas_f32 v248, v248, v249, v230
	v_div_fixup_f32 v236, v248, v247, 1.0
	v_fmamk_f32 v240, v227, 0x3a800000, v89
	v_mul_f32_e32 v241, 0x4f800000, v240
	v_cmp_gt_f32_e32 vcc, s54, v240
	s_nop 1
	v_cndmask_b32_e32 v247, v240, v241, vcc
	v_sqrt_f32_e32 v242, v247
	s_nop 1
	v_add_u32_e32 v243, -1, v242
	v_add_u32_e32 v244, 1, v242
	v_fma_f32 v245, -v243, v242, v247
	v_fma_f32 v246, -v244, v242, v247
	v_cmp_ge_f32_e64 s[52:53], 0, v245
	s_nop 1
	v_cndmask_b32_e64 v242, v242, v243, s[52:53]
	v_cmp_lt_f32_e64 s[52:53], 0, v246
	s_nop 1
	v_cndmask_b32_e64 v242, v242, v244, s[52:53]
	v_mul_f32_e32 v243, 0x37800000, v242
	v_cndmask_b32_e32 v242, v242, v243, vcc
	v_cmp_class_f32_e32 vcc, v247, v90
	s_nop 1
	v_cndmask_b32_e32 v247, v242, v247, vcc
	v_div_scale_f32 v248, s[52:53], v247, v247, 1.0
	v_rcp_f32_e32 v249, v248
	v_div_scale_f32 v228, vcc, 1.0, v247, 1.0
	s_nop 0
	v_fma_f32 v229, -v248, v249, 1.0
	v_fmac_f32_e32 v249, v229, v249
	v_mul_f32_e32 v230, v228, v249
	v_fma_f32 v229, -v248, v230, v228
	v_fmac_f32_e32 v230, v229, v249
	v_fma_f32 v248, -v248, v230, v228
	v_div_fmas_f32 v248, v248, v249, v230
	v_div_fixup_f32 v238, v248, v247, 1.0
	s_waitcnt vmcnt(8)
	v_pk_add_f32 v[160:161], v[160:161], 1.0 op_sel_hi:[1,0]
	v_pk_add_f32 v[162:163], v[162:163], 1.0 op_sel_hi:[1,0]
	v_pk_add_f32 v[164:165], v[164:165], 1.0 op_sel_hi:[1,0]
	v_pk_add_f32 v[166:167], v[166:167], 1.0 op_sel_hi:[1,0]
	v_pk_add_f32 v[168:169], v[168:169], 1.0 op_sel_hi:[1,0]
	v_pk_add_f32 v[170:171], v[170:171], 1.0 op_sel_hi:[1,0]
	v_pk_add_f32 v[172:173], v[172:173], 1.0 op_sel_hi:[1,0]
	v_pk_add_f32 v[174:175], v[174:175], 1.0 op_sel_hi:[1,0]
	v_pk_add_f32 v[192:193], v[192:193], 1.0 op_sel_hi:[1,0]
	v_pk_add_f32 v[194:195], v[194:195], 1.0 op_sel_hi:[1,0]
	v_pk_add_f32 v[196:197], v[196:197], 1.0 op_sel_hi:[1,0]
	v_pk_add_f32 v[198:199], v[198:199], 1.0 op_sel_hi:[1,0]
	v_pk_add_f32 v[200:201], v[200:201], 1.0 op_sel_hi:[1,0]
	v_pk_add_f32 v[202:203], v[202:203], 1.0 op_sel_hi:[1,0]
	v_pk_add_f32 v[204:205], v[204:205], 1.0 op_sel_hi:[1,0]
	v_pk_add_f32 v[206:207], v[206:207], 1.0 op_sel_hi:[1,0]
	s_add_u32 s38, s20, 0x7000000
	s_addc_u32 s39, s21, 0
	s_add_u32 s40, s20, 0x7400000
	s_addc_u32 s41, s21, 0
	s_add_u32 s46, s20, 0x7800000
	s_addc_u32 s47, s21, 0
	s_add_u32 s48, s20, 0x7c00000
	s_addc_u32 s49, s21, 0
	v_pk_mul_f32 v[0:1], v[0:1], v[232:233] op_sel_hi:[1,0]
	v_pk_mul_f32 v[2:3], v[2:3], v[232:233] op_sel_hi:[1,0]
	v_pk_mul_f32 v[0:1], v[64:65], v[0:1]
	v_pk_mul_f32 v[2:3], v[66:67], v[2:3]
	v_pk_fma_f32 v[0:1], v[160:161], v[0:1], v[176:177]
	v_pk_fma_f32 v[2:3], v[162:163], v[2:3], v[178:179]
	v_cvt_pk_bf16_f32 v244, v0, v1
	v_cvt_pk_bf16_f32 v245, v2, v3
	v_pk_mul_f32 v[4:5], v[4:5], v[232:233] op_sel_hi:[1,0]
	v_pk_mul_f32 v[6:7], v[6:7], v[232:233] op_sel_hi:[1,0]
	v_pk_mul_f32 v[4:5], v[68:69], v[4:5]
	v_pk_mul_f32 v[6:7], v[70:71], v[6:7]
	v_pk_fma_f32 v[4:5], v[164:165], v[4:5], v[180:181]
	v_pk_fma_f32 v[6:7], v[166:167], v[6:7], v[182:183]
	v_cvt_pk_bf16_f32 v246, v4, v5
	v_cvt_pk_bf16_f32 v247, v6, v7
	global_store_dwordx4 v82, v[244:247], s[38:39] offset:0
	v_pk_mul_f32 v[8:9], v[8:9], v[232:233] op_sel_hi:[1,0]
	v_pk_mul_f32 v[10:11], v[10:11], v[232:233] op_sel_hi:[1,0]
	v_pk_mul_f32 v[8:9], v[72:73], v[8:9]
	v_pk_mul_f32 v[10:11], v[74:75], v[10:11]
	v_pk_fma_f32 v[8:9], v[168:169], v[8:9], v[184:185]
	v_pk_fma_f32 v[10:11], v[170:171], v[10:11], v[186:187]
	v_cvt_pk_bf16_f32 v240, v8, v9
	v_cvt_pk_bf16_f32 v241, v10, v11
	v_pk_mul_f32 v[12:13], v[12:13], v[232:233] op_sel_hi:[1,0]
	v_pk_mul_f32 v[14:15], v[14:15], v[232:233] op_sel_hi:[1,0]
	v_pk_mul_f32 v[12:13], v[76:77], v[12:13]
	v_pk_mul_f32 v[14:15], v[78:79], v[14:15]
	v_pk_fma_f32 v[12:13], v[172:173], v[12:13], v[188:189]
	v_pk_fma_f32 v[14:15], v[174:175], v[14:15], v[190:191]
	v_cvt_pk_bf16_f32 v242, v12, v13
	v_cvt_pk_bf16_f32 v243, v14, v15
	global_store_dwordx4 v82, v[240:243], s[38:39] offset:1024
	v_pk_mul_f32 v[16:17], v[16:17], v[234:235] op_sel_hi:[1,0]
	v_pk_mul_f32 v[18:19], v[18:19], v[234:235] op_sel_hi:[1,0]
	v_pk_mul_f32 v[16:17], v[64:65], v[16:17]
	v_pk_mul_f32 v[18:19], v[66:67], v[18:19]
	v_pk_fma_f32 v[16:17], v[160:161], v[16:17], v[176:177]
	v_pk_fma_f32 v[18:19], v[162:163], v[18:19], v[178:179]
	v_cvt_pk_bf16_f32 v244, v16, v17
	v_cvt_pk_bf16_f32 v245, v18, v19
	v_pk_mul_f32 v[20:21], v[20:21], v[234:235] op_sel_hi:[1,0]
	v_pk_mul_f32 v[22:23], v[22:23], v[234:235] op_sel_hi:[1,0]
	v_pk_mul_f32 v[20:21], v[68:69], v[20:21]
	v_pk_mul_f32 v[22:23], v[70:71], v[22:23]
	v_pk_fma_f32 v[20:21], v[164:165], v[20:21], v[180:181]
	v_pk_fma_f32 v[22:23], v[166:167], v[22:23], v[182:183]
	v_cvt_pk_bf16_f32 v246, v20, v21
	v_cvt_pk_bf16_f32 v247, v22, v23
	global_store_dwordx4 v82, v[244:247], s[40:41] offset:0
	v_pk_mul_f32 v[24:25], v[24:25], v[234:235] op_sel_hi:[1,0]
	v_pk_mul_f32 v[26:27], v[26:27], v[234:235] op_sel_hi:[1,0]
	v_pk_mul_f32 v[24:25], v[72:73], v[24:25]
	v_pk_mul_f32 v[26:27], v[74:75], v[26:27]
	v_pk_fma_f32 v[24:25], v[168:169], v[24:25], v[184:185]
	v_pk_fma_f32 v[26:27], v[170:171], v[26:27], v[186:187]
	v_cvt_pk_bf16_f32 v240, v24, v25
	v_cvt_pk_bf16_f32 v241, v26, v27
	v_pk_mul_f32 v[28:29], v[28:29], v[234:235] op_sel_hi:[1,0]
	v_pk_mul_f32 v[30:31], v[30:31], v[234:235] op_sel_hi:[1,0]
	v_pk_mul_f32 v[28:29], v[76:77], v[28:29]
	v_pk_mul_f32 v[30:31], v[78:79], v[30:31]
	v_pk_fma_f32 v[28:29], v[172:173], v[28:29], v[188:189]
	v_pk_fma_f32 v[30:31], v[174:175], v[30:31], v[190:191]
	v_cvt_pk_bf16_f32 v242, v28, v29
	v_cvt_pk_bf16_f32 v243, v30, v31
	global_store_dwordx4 v82, v[240:243], s[40:41] offset:1024
	v_pk_mul_f32 v[32:33], v[32:33], v[236:237] op_sel_hi:[1,0]
	v_pk_mul_f32 v[34:35], v[34:35], v[236:237] op_sel_hi:[1,0]
	v_pk_mul_f32 v[32:33], v[64:65], v[32:33]
	v_pk_mul_f32 v[34:35], v[66:67], v[34:35]
	v_pk_fma_f32 v[32:33], v[192:193], v[32:33], v[208:209]
	v_pk_fma_f32 v[34:35], v[194:195], v[34:35], v[210:211]
	v_cvt_pk_bf16_f32 v244, v32, v33
	v_cvt_pk_bf16_f32 v245, v34, v35
	v_pk_mul_f32 v[36:37], v[36:37], v[236:237] op_sel_hi:[1,0]
	v_pk_mul_f32 v[38:39], v[38:39], v[236:237] op_sel_hi:[1,0]
	v_pk_mul_f32 v[36:37], v[68:69], v[36:37]
	v_pk_mul_f32 v[38:39], v[70:71], v[38:39]
	v_pk_fma_f32 v[36:37], v[196:197], v[36:37], v[212:213]
	v_pk_fma_f32 v[38:39], v[198:199], v[38:39], v[214:215]
	v_cvt_pk_bf16_f32 v246, v36, v37
	v_cvt_pk_bf16_f32 v247, v38, v39
	global_store_dwordx4 v82, v[244:247], s[46:47] offset:0
	v_pk_mul_f32 v[40:41], v[40:41], v[236:237] op_sel_hi:[1,0]
	v_pk_mul_f32 v[42:43], v[42:43], v[236:237] op_sel_hi:[1,0]
	v_pk_mul_f32 v[40:41], v[72:73], v[40:41]
	v_pk_mul_f32 v[42:43], v[74:75], v[42:43]
	v_pk_fma_f32 v[40:41], v[200:201], v[40:41], v[216:217]
	v_pk_fma_f32 v[42:43], v[202:203], v[42:43], v[218:219]
	v_cvt_pk_bf16_f32 v240, v40, v41
	v_cvt_pk_bf16_f32 v241, v42, v43
	v_pk_mul_f32 v[44:45], v[44:45], v[236:237] op_sel_hi:[1,0]
	v_pk_mul_f32 v[46:47], v[46:47], v[236:237] op_sel_hi:[1,0]
	v_pk_mul_f32 v[44:45], v[76:77], v[44:45]
	v_pk_mul_f32 v[46:47], v[78:79], v[46:47]
	v_pk_fma_f32 v[44:45], v[204:205], v[44:45], v[220:221]
	v_pk_fma_f32 v[46:47], v[206:207], v[46:47], v[222:223]
	v_cvt_pk_bf16_f32 v242, v44, v45
	v_cvt_pk_bf16_f32 v243, v46, v47
	global_store_dwordx4 v82, v[240:243], s[46:47] offset:1024
	v_pk_mul_f32 v[48:49], v[48:49], v[238:239] op_sel_hi:[1,0]
	v_pk_mul_f32 v[50:51], v[50:51], v[238:239] op_sel_hi:[1,0]
	v_pk_mul_f32 v[48:49], v[64:65], v[48:49]
	v_pk_mul_f32 v[50:51], v[66:67], v[50:51]
	v_pk_fma_f32 v[48:49], v[192:193], v[48:49], v[208:209]
	v_pk_fma_f32 v[50:51], v[194:195], v[50:51], v[210:211]
	v_cvt_pk_bf16_f32 v244, v48, v49
	v_cvt_pk_bf16_f32 v245, v50, v51
	v_pk_mul_f32 v[52:53], v[52:53], v[238:239] op_sel_hi:[1,0]
	v_pk_mul_f32 v[54:55], v[54:55], v[238:239] op_sel_hi:[1,0]
	v_pk_mul_f32 v[52:53], v[68:69], v[52:53]
	v_pk_mul_f32 v[54:55], v[70:71], v[54:55]
	v_pk_fma_f32 v[52:53], v[196:197], v[52:53], v[212:213]
	v_pk_fma_f32 v[54:55], v[198:199], v[54:55], v[214:215]
	v_cvt_pk_bf16_f32 v246, v52, v53
	v_cvt_pk_bf16_f32 v247, v54, v55
	global_store_dwordx4 v82, v[244:247], s[48:49] offset:0
	v_pk_mul_f32 v[56:57], v[56:57], v[238:239] op_sel_hi:[1,0]
	v_pk_mul_f32 v[58:59], v[58:59], v[238:239] op_sel_hi:[1,0]
	v_pk_mul_f32 v[56:57], v[72:73], v[56:57]
	v_pk_mul_f32 v[58:59], v[74:75], v[58:59]
	v_pk_fma_f32 v[56:57], v[200:201], v[56:57], v[216:217]
	v_pk_fma_f32 v[58:59], v[202:203], v[58:59], v[218:219]
	v_cvt_pk_bf16_f32 v240, v56, v57
	v_cvt_pk_bf16_f32 v241, v58, v59
	v_pk_mul_f32 v[60:61], v[60:61], v[238:239] op_sel_hi:[1,0]
	v_pk_mul_f32 v[62:63], v[62:63], v[238:239] op_sel_hi:[1,0]
	v_pk_mul_f32 v[60:61], v[76:77], v[60:61]
	v_pk_mul_f32 v[62:63], v[78:79], v[62:63]
	v_pk_fma_f32 v[60:61], v[204:205], v[60:61], v[220:221]
	v_pk_fma_f32 v[62:63], v[206:207], v[62:63], v[222:223]
	v_cvt_pk_bf16_f32 v242, v60, v61
	v_cvt_pk_bf16_f32 v243, v62, v63
	global_store_dwordx4 v82, v[240:243], s[48:49] offset:1024
	s_add_u32 s34, s8, 0x33000
	s_addc_u32 s35, s9, 0
	s_add_u32 s36, s8, 0x39000
	s_addc_u32 s37, s9, 0
	global_load_dwordx4 v[176:179], v80, s[34:35] offset:0
	global_load_dwordx4 v[180:183], v80, s[34:35] offset:16
	global_load_dwordx4 v[184:187], v80, s[34:35] offset:2048
	global_load_dwordx4 v[188:191], v80, s[34:35] offset:2064
	global_load_dwordx4 v[160:163], v81, s[34:35] offset:0
	global_load_dwordx4 v[164:167], v81, s[34:35] offset:16
	global_load_dwordx4 v[168:171], v81, s[34:35] offset:2048
	global_load_dwordx4 v[172:175], v81, s[34:35] offset:2064
	global_load_dwordx4 v[208:211], v80, s[36:37] offset:0
	global_load_dwordx4 v[212:215], v80, s[36:37] offset:16
	global_load_dwordx4 v[216:219], v80, s[36:37] offset:2048
	global_load_dwordx4 v[220:223], v80, s[36:37] offset:2064
	global_load_dwordx4 v[192:195], v81, s[36:37] offset:0
	global_load_dwordx4 v[196:199], v81, s[36:37] offset:16
	global_load_dwordx4 v[200:203], v81, s[36:37] offset:2048
	global_load_dwordx4 v[204:207], v81, s[36:37] offset:2064
	s_add_u32 s24, s16, 0x9000000
	s_addc_u32 s25, s17, 0
	s_add_u32 s26, s16, 0x9400000
	s_addc_u32 s27, s17, 0
	s_add_u32 s28, s16, 0x9800000
	s_addc_u32 s29, s17, 0
	s_add_u32 s30, s16, 0x9c00000
	s_addc_u32 s31, s17, 0
	global_load_dwordx4 v[128:131], v82, s[24:25] offset:0
	global_load_dwordx4 v[132:135], v82, s[24:25] offset:1024
	global_load_dwordx4 v[136:139], v82, s[26:27] offset:0
	global_load_dwordx4 v[140:143], v82, s[26:27] offset:1024
	global_load_dwordx4 v[144:147], v82, s[28:29] offset:0
	global_load_dwordx4 v[148:151], v82, s[28:29] offset:1024
	global_load_dwordx4 v[152:155], v82, s[30:31] offset:0
	global_load_dwordx4 v[156:159], v82, s[30:31] offset:1024
	s_waitcnt vmcnt(32)
	v_lshlrev_b32_e32 v0, 16, v96
	v_and_b32_e32 v1, 0xffff0000, v96
	v_lshlrev_b32_e32 v2, 16, v97
	v_and_b32_e32 v3, 0xffff0000, v97
	v_lshlrev_b32_e32 v4, 16, v98
	v_and_b32_e32 v5, 0xffff0000, v98
	v_lshlrev_b32_e32 v6, 16, v99
	v_and_b32_e32 v7, 0xffff0000, v99
	v_lshlrev_b32_e32 v8, 16, v100
	v_and_b32_e32 v9, 0xffff0000, v100
	v_lshlrev_b32_e32 v10, 16, v101
	v_and_b32_e32 v11, 0xffff0000, v101
	v_lshlrev_b32_e32 v12, 16, v102
	v_and_b32_e32 v13, 0xffff0000, v102
	v_lshlrev_b32_e32 v14, 16, v103
	v_and_b32_e32 v15, 0xffff0000, v103
	v_lshlrev_b32_e32 v16, 16, v104
	v_and_b32_e32 v17, 0xffff0000, v104
	v_lshlrev_b32_e32 v18, 16, v105
	v_and_b32_e32 v19, 0xffff0000, v105
	v_lshlrev_b32_e32 v20, 16, v106
	v_and_b32_e32 v21, 0xffff0000, v106
	v_lshlrev_b32_e32 v22, 16, v107
	v_and_b32_e32 v23, 0xffff0000, v107
	v_lshlrev_b32_e32 v24, 16, v108
	v_and_b32_e32 v25, 0xffff0000, v108
	v_lshlrev_b32_e32 v26, 16, v109
	v_and_b32_e32 v27, 0xffff0000, v109
	v_lshlrev_b32_e32 v28, 16, v110
	v_and_b32_e32 v29, 0xffff0000, v110
	v_lshlrev_b32_e32 v30, 16, v111
	v_and_b32_e32 v31, 0xffff0000, v111
	v_lshlrev_b32_e32 v32, 16, v112
	v_and_b32_e32 v33, 0xffff0000, v112
	v_lshlrev_b32_e32 v34, 16, v113
	v_and_b32_e32 v35, 0xffff0000, v113
	v_lshlrev_b32_e32 v36, 16, v114
	v_and_b32_e32 v37, 0xffff0000, v114
	v_lshlrev_b32_e32 v38, 16, v115
	v_and_b32_e32 v39, 0xffff0000, v115
	v_lshlrev_b32_e32 v40, 16, v116
	v_and_b32_e32 v41, 0xffff0000, v116
	v_lshlrev_b32_e32 v42, 16, v117
	v_and_b32_e32 v43, 0xffff0000, v117
	v_lshlrev_b32_e32 v44, 16, v118
	v_and_b32_e32 v45, 0xffff0000, v118
	v_lshlrev_b32_e32 v46, 16, v119
	v_and_b32_e32 v47, 0xffff0000, v119
	v_lshlrev_b32_e32 v48, 16, v120
	v_and_b32_e32 v49, 0xffff0000, v120
	v_lshlrev_b32_e32 v50, 16, v121
	v_and_b32_e32 v51, 0xffff0000, v121
	v_lshlrev_b32_e32 v52, 16, v122
	v_and_b32_e32 v53, 0xffff0000, v122
	v_lshlrev_b32_e32 v54, 16, v123
	v_and_b32_e32 v55, 0xffff0000, v123
	v_lshlrev_b32_e32 v56, 16, v124
	v_and_b32_e32 v57, 0xffff0000, v124
	v_lshlrev_b32_e32 v58, 16, v125
	v_and_b32_e32 v59, 0xffff0000, v125
	v_lshlrev_b32_e32 v60, 16, v126
	v_and_b32_e32 v61, 0xffff0000, v126
	v_lshlrev_b32_e32 v62, 16, v127
	v_and_b32_e32 v63, 0xffff0000, v127
	v_pk_mul_f32 v[240:241], v[0:1], v[0:1]
	v_pk_mul_f32 v[242:243], v[16:17], v[16:17]
	v_pk_mul_f32 v[244:245], v[32:33], v[32:33]
	v_pk_mul_f32 v[246:247], v[48:49], v[48:49]
	v_pk_fma_f32 v[240:241], v[2:3], v[2:3], v[240:241]
	v_pk_fma_f32 v[242:243], v[18:19], v[18:19], v[242:243]
	v_pk_fma_f32 v[244:245], v[34:35], v[34:35], v[244:245]
	v_pk_fma_f32 v[246:247], v[50:51], v[50:51], v[246:247]
	v_pk_fma_f32 v[240:241], v[4:5], v[4:5], v[240:241]
	v_pk_fma_f32 v[242:243], v[20:21], v[20:21], v[242:243]
	v_pk_fma_f32 v[244:245], v[36:37], v[36:37], v[244:245]
	v_pk_fma_f32 v[246:247], v[52:53], v[52:53], v[246:247]
	v_pk_fma_f32 v[240:241], v[6:7], v[6:7], v[240:241]
	v_pk_fma_f32 v[242:243], v[22:23], v[22:23], v[242:243]
	v_pk_fma_f32 v[244:245], v[38:39], v[38:39], v[244:245]
	v_pk_fma_f32 v[246:247], v[54:55], v[54:55], v[246:247]
	v_pk_fma_f32 v[240:241], v[8:9], v[8:9], v[240:241]
	v_pk_fma_f32 v[242:243], v[24:25], v[24:25], v[242:243]
	v_pk_fma_f32 v[244:245], v[40:41], v[40:41], v[244:245]
	v_pk_fma_f32 v[246:247], v[56:57], v[56:57], v[246:247]
	v_pk_fma_f32 v[240:241], v[10:11], v[10:11], v[240:241]
	v_pk_fma_f32 v[242:243], v[26:27], v[26:27], v[242:243]
	v_pk_fma_f32 v[244:245], v[42:43], v[42:43], v[244:245]
	v_pk_fma_f32 v[246:247], v[58:59], v[58:59], v[246:247]
	v_pk_fma_f32 v[240:241], v[12:13], v[12:13], v[240:241]
	v_pk_fma_f32 v[242:243], v[28:29], v[28:29], v[242:243]
	v_pk_fma_f32 v[244:245], v[44:45], v[44:45], v[244:245]
	v_pk_fma_f32 v[246:247], v[60:61], v[60:61], v[246:247]
	v_pk_fma_f32 v[240:241], v[14:15], v[14:15], v[240:241]
	v_pk_fma_f32 v[242:243], v[30:31], v[30:31], v[242:243]
	v_pk_fma_f32 v[244:245], v[46:47], v[46:47], v[244:245]
	v_pk_fma_f32 v[246:247], v[62:63], v[62:63], v[246:247]
	v_add_f32_e32 v224, v240, v241
	v_add_f32_e32 v225, v242, v243
	v_add_f32_e32 v226, v244, v245
	v_add_f32_e32 v227, v246, v247
	ds_bpermute_b32 v228, v83, v224
	ds_bpermute_b32 v229, v83, v225
	ds_bpermute_b32 v230, v83, v226
	ds_bpermute_b32 v231, v83, v227
	s_waitcnt lgkmcnt(0)
	v_add_f32_e32 v224, v224, v228
	v_add_f32_e32 v225, v225, v229
	v_add_f32_e32 v226, v226, v230
	v_add_f32_e32 v227, v227, v231
	ds_bpermute_b32 v228, v84, v224
	ds_bpermute_b32 v229, v84, v225
	ds_bpermute_b32 v230, v84, v226
	ds_bpermute_b32 v231, v84, v227
	s_waitcnt lgkmcnt(0)
	v_add_f32_e32 v224, v224, v228
	v_add_f32_e32 v225, v225, v229
	v_add_f32_e32 v226, v226, v230
	v_add_f32_e32 v227, v227, v231
	ds_bpermute_b32 v228, v85, v224
	ds_bpermute_b32 v229, v85, v225
	ds_bpermute_b32 v230, v85, v226
	ds_bpermute_b32 v231, v85, v227
	s_waitcnt lgkmcnt(0)
	v_add_f32_e32 v224, v224, v228
	v_add_f32_e32 v225, v225, v229
	v_add_f32_e32 v226, v226, v230
	v_add_f32_e32 v227, v227, v231
	ds_bpermute_b32 v228, v86, v224
	ds_bpermute_b32 v229, v86, v225
	ds_bpermute_b32 v230, v86, v226
	ds_bpermute_b32 v231, v86, v227
	s_waitcnt lgkmcnt(0)
	v_add_f32_e32 v224, v224, v228
	v_add_f32_e32 v225, v225, v229
	v_add_f32_e32 v226, v226, v230
	v_add_f32_e32 v227, v227, v231
	ds_bpermute_b32 v228, v87, v224
	ds_bpermute_b32 v229, v87, v225
	ds_bpermute_b32 v230, v87, v226
	ds_bpermute_b32 v231, v87, v227
	s_waitcnt lgkmcnt(0)
	v_add_f32_e32 v224, v224, v228
	v_add_f32_e32 v225, v225, v229
	v_add_f32_e32 v226, v226, v230
	v_add_f32_e32 v227, v227, v231
	ds_bpermute_b32 v228, v88, v224
	ds_bpermute_b32 v229, v88, v225
	ds_bpermute_b32 v230, v88, v226
	ds_bpermute_b32 v231, v88, v227
	s_waitcnt lgkmcnt(0)
	v_add_f32_e32 v224, v224, v228
	v_add_f32_e32 v225, v225, v229
	v_add_f32_e32 v226, v226, v230
	v_add_f32_e32 v227, v227, v231
	v_fmamk_f32 v240, v224, 0x3a800000, v89
	v_mul_f32_e32 v241, 0x4f800000, v240
	v_cmp_gt_f32_e32 vcc, s54, v240
	s_nop 1
	v_cndmask_b32_e32 v247, v240, v241, vcc
	v_sqrt_f32_e32 v242, v247
	s_nop 1
	v_add_u32_e32 v243, -1, v242
	v_add_u32_e32 v244, 1, v242
	v_fma_f32 v245, -v243, v242, v247
	v_fma_f32 v246, -v244, v242, v247
	v_cmp_ge_f32_e64 s[52:53], 0, v245
	s_nop 1
	v_cndmask_b32_e64 v242, v242, v243, s[52:53]
	v_cmp_lt_f32_e64 s[52:53], 0, v246
	s_nop 1
	v_cndmask_b32_e64 v242, v242, v244, s[52:53]
	v_mul_f32_e32 v243, 0x37800000, v242
	v_cndmask_b32_e32 v242, v242, v243, vcc
	v_cmp_class_f32_e32 vcc, v247, v90
	s_nop 1
	v_cndmask_b32_e32 v247, v242, v247, vcc
	v_div_scale_f32 v248, s[52:53], v247, v247, 1.0
	v_rcp_f32_e32 v249, v248
	v_div_scale_f32 v228, vcc, 1.0, v247, 1.0
	s_nop 0
	v_fma_f32 v229, -v248, v249, 1.0
	v_fmac_f32_e32 v249, v229, v249
	v_mul_f32_e32 v230, v228, v249
	v_fma_f32 v229, -v248, v230, v228
	v_fmac_f32_e32 v230, v229, v249
	v_fma_f32 v248, -v248, v230, v228
	v_div_fmas_f32 v248, v248, v249, v230
	v_div_fixup_f32 v232, v248, v247, 1.0
	v_fmamk_f32 v240, v225, 0x3a800000, v89
	v_mul_f32_e32 v241, 0x4f800000, v240
	v_cmp_gt_f32_e32 vcc, s54, v240
	s_nop 1
	v_cndmask_b32_e32 v247, v240, v241, vcc
	v_sqrt_f32_e32 v242, v247
	s_nop 1
	v_add_u32_e32 v243, -1, v242
	v_add_u32_e32 v244, 1, v242
	v_fma_f32 v245, -v243, v242, v247
	v_fma_f32 v246, -v244, v242, v247
	v_cmp_ge_f32_e64 s[52:53], 0, v245
	s_nop 1
	v_cndmask_b32_e64 v242, v242, v243, s[52:53]
	v_cmp_lt_f32_e64 s[52:53], 0, v246
	s_nop 1
	v_cndmask_b32_e64 v242, v242, v244, s[52:53]
	v_mul_f32_e32 v243, 0x37800000, v242
	v_cndmask_b32_e32 v242, v242, v243, vcc
	v_cmp_class_f32_e32 vcc, v247, v90
	s_nop 1
	v_cndmask_b32_e32 v247, v242, v247, vcc
	v_div_scale_f32 v248, s[52:53], v247, v247, 1.0
	v_rcp_f32_e32 v249, v248
	v_div_scale_f32 v228, vcc, 1.0, v247, 1.0
	s_nop 0
	v_fma_f32 v229, -v248, v249, 1.0
	v_fmac_f32_e32 v249, v229, v249
	v_mul_f32_e32 v230, v228, v249
	v_fma_f32 v229, -v248, v230, v228
	v_fmac_f32_e32 v230, v229, v249
	v_fma_f32 v248, -v248, v230, v228
	v_div_fmas_f32 v248, v248, v249, v230
	v_div_fixup_f32 v234, v248, v247, 1.0
	v_fmamk_f32 v240, v226, 0x3a800000, v89
	v_mul_f32_e32 v241, 0x4f800000, v240
	v_cmp_gt_f32_e32 vcc, s54, v240
	s_nop 1
	v_cndmask_b32_e32 v247, v240, v241, vcc
	v_sqrt_f32_e32 v242, v247
	s_nop 1
	v_add_u32_e32 v243, -1, v242
	v_add_u32_e32 v244, 1, v242
	v_fma_f32 v245, -v243, v242, v247
	v_fma_f32 v246, -v244, v242, v247
	v_cmp_ge_f32_e64 s[52:53], 0, v245
	s_nop 1
	v_cndmask_b32_e64 v242, v242, v243, s[52:53]
	v_cmp_lt_f32_e64 s[52:53], 0, v246
	s_nop 1
	v_cndmask_b32_e64 v242, v242, v244, s[52:53]
	v_mul_f32_e32 v243, 0x37800000, v242
	v_cndmask_b32_e32 v242, v242, v243, vcc
	v_cmp_class_f32_e32 vcc, v247, v90
	s_nop 1
	v_cndmask_b32_e32 v247, v242, v247, vcc
	v_div_scale_f32 v248, s[52:53], v247, v247, 1.0
	v_rcp_f32_e32 v249, v248
	v_div_scale_f32 v228, vcc, 1.0, v247, 1.0
	s_nop 0
	v_fma_f32 v229, -v248, v249, 1.0
	v_fmac_f32_e32 v249, v229, v249
	v_mul_f32_e32 v230, v228, v249
	v_fma_f32 v229, -v248, v230, v228
	v_fmac_f32_e32 v230, v229, v249
	v_fma_f32 v248, -v248, v230, v228
	v_div_fmas_f32 v248, v248, v249, v230
	v_div_fixup_f32 v236, v248, v247, 1.0
	v_fmamk_f32 v240, v227, 0x3a800000, v89
	v_mul_f32_e32 v241, 0x4f800000, v240
	v_cmp_gt_f32_e32 vcc, s54, v240
	s_nop 1
	v_cndmask_b32_e32 v247, v240, v241, vcc
	v_sqrt_f32_e32 v242, v247
	s_nop 1
	v_add_u32_e32 v243, -1, v242
	v_add_u32_e32 v244, 1, v242
	v_fma_f32 v245, -v243, v242, v247
	v_fma_f32 v246, -v244, v242, v247
	v_cmp_ge_f32_e64 s[52:53], 0, v245
	s_nop 1
	v_cndmask_b32_e64 v242, v242, v243, s[52:53]
	v_cmp_lt_f32_e64 s[52:53], 0, v246
	s_nop 1
	v_cndmask_b32_e64 v242, v242, v244, s[52:53]
	v_mul_f32_e32 v243, 0x37800000, v242
	v_cndmask_b32_e32 v242, v242, v243, vcc
	v_cmp_class_f32_e32 vcc, v247, v90
	s_nop 1
	v_cndmask_b32_e32 v247, v242, v247, vcc
	v_div_scale_f32 v248, s[52:53], v247, v247, 1.0
	v_rcp_f32_e32 v249, v248
	v_div_scale_f32 v228, vcc, 1.0, v247, 1.0
	s_nop 0
	v_fma_f32 v229, -v248, v249, 1.0
	v_fmac_f32_e32 v249, v229, v249
	v_mul_f32_e32 v230, v228, v249
	v_fma_f32 v229, -v248, v230, v228
	v_fmac_f32_e32 v230, v229, v249
	v_fma_f32 v248, -v248, v230, v228
	v_div_fmas_f32 v248, v248, v249, v230
	v_div_fixup_f32 v238, v248, v247, 1.0
	s_waitcnt vmcnt(8)
	v_pk_add_f32 v[160:161], v[160:161], 1.0 op_sel_hi:[1,0]
	v_pk_add_f32 v[162:163], v[162:163], 1.0 op_sel_hi:[1,0]
	v_pk_add_f32 v[164:165], v[164:165], 1.0 op_sel_hi:[1,0]
	v_pk_add_f32 v[166:167], v[166:167], 1.0 op_sel_hi:[1,0]
	v_pk_add_f32 v[168:169], v[168:169], 1.0 op_sel_hi:[1,0]
	v_pk_add_f32 v[170:171], v[170:171], 1.0 op_sel_hi:[1,0]
	v_pk_add_f32 v[172:173], v[172:173], 1.0 op_sel_hi:[1,0]
	v_pk_add_f32 v[174:175], v[174:175], 1.0 op_sel_hi:[1,0]
	v_pk_add_f32 v[192:193], v[192:193], 1.0 op_sel_hi:[1,0]
	v_pk_add_f32 v[194:195], v[194:195], 1.0 op_sel_hi:[1,0]
	v_pk_add_f32 v[196:197], v[196:197], 1.0 op_sel_hi:[1,0]
	v_pk_add_f32 v[198:199], v[198:199], 1.0 op_sel_hi:[1,0]
	v_pk_add_f32 v[200:201], v[200:201], 1.0 op_sel_hi:[1,0]
	v_pk_add_f32 v[202:203], v[202:203], 1.0 op_sel_hi:[1,0]
	v_pk_add_f32 v[204:205], v[204:205], 1.0 op_sel_hi:[1,0]
	v_pk_add_f32 v[206:207], v[206:207], 1.0 op_sel_hi:[1,0]
	s_add_u32 s38, s20, 0x8000000
	s_addc_u32 s39, s21, 0
	s_add_u32 s40, s20, 0x8400000
	s_addc_u32 s41, s21, 0
	s_add_u32 s46, s20, 0x8800000
	s_addc_u32 s47, s21, 0
	s_add_u32 s48, s20, 0x8c00000
	s_addc_u32 s49, s21, 0
	v_pk_mul_f32 v[0:1], v[0:1], v[232:233] op_sel_hi:[1,0]
	v_pk_mul_f32 v[2:3], v[2:3], v[232:233] op_sel_hi:[1,0]
	v_pk_mul_f32 v[0:1], v[64:65], v[0:1]
	v_pk_mul_f32 v[2:3], v[66:67], v[2:3]
	v_pk_fma_f32 v[0:1], v[160:161], v[0:1], v[176:177]
	v_pk_fma_f32 v[2:3], v[162:163], v[2:3], v[178:179]
	v_cvt_pk_bf16_f32 v244, v0, v1
	v_cvt_pk_bf16_f32 v245, v2, v3
	v_pk_mul_f32 v[4:5], v[4:5], v[232:233] op_sel_hi:[1,0]
	v_pk_mul_f32 v[6:7], v[6:7], v[232:233] op_sel_hi:[1,0]
	v_pk_mul_f32 v[4:5], v[68:69], v[4:5]
	v_pk_mul_f32 v[6:7], v[70:71], v[6:7]
	v_pk_fma_f32 v[4:5], v[164:165], v[4:5], v[180:181]
	v_pk_fma_f32 v[6:7], v[166:167], v[6:7], v[182:183]
	v_cvt_pk_bf16_f32 v246, v4, v5
	v_cvt_pk_bf16_f32 v247, v6, v7
	global_store_dwordx4 v82, v[244:247], s[38:39] offset:0
	v_pk_mul_f32 v[8:9], v[8:9], v[232:233] op_sel_hi:[1,0]
	v_pk_mul_f32 v[10:11], v[10:11], v[232:233] op_sel_hi:[1,0]
	v_pk_mul_f32 v[8:9], v[72:73], v[8:9]
	v_pk_mul_f32 v[10:11], v[74:75], v[10:11]
	v_pk_fma_f32 v[8:9], v[168:169], v[8:9], v[184:185]
	v_pk_fma_f32 v[10:11], v[170:171], v[10:11], v[186:187]
	v_cvt_pk_bf16_f32 v240, v8, v9
	v_cvt_pk_bf16_f32 v241, v10, v11
	v_pk_mul_f32 v[12:13], v[12:13], v[232:233] op_sel_hi:[1,0]
	v_pk_mul_f32 v[14:15], v[14:15], v[232:233] op_sel_hi:[1,0]
	v_pk_mul_f32 v[12:13], v[76:77], v[12:13]
	v_pk_mul_f32 v[14:15], v[78:79], v[14:15]
	v_pk_fma_f32 v[12:13], v[172:173], v[12:13], v[188:189]
	v_pk_fma_f32 v[14:15], v[174:175], v[14:15], v[190:191]
	v_cvt_pk_bf16_f32 v242, v12, v13
	v_cvt_pk_bf16_f32 v243, v14, v15
	global_store_dwordx4 v82, v[240:243], s[38:39] offset:1024
	v_pk_mul_f32 v[16:17], v[16:17], v[234:235] op_sel_hi:[1,0]
	v_pk_mul_f32 v[18:19], v[18:19], v[234:235] op_sel_hi:[1,0]
	v_pk_mul_f32 v[16:17], v[64:65], v[16:17]
	v_pk_mul_f32 v[18:19], v[66:67], v[18:19]
	v_pk_fma_f32 v[16:17], v[160:161], v[16:17], v[176:177]
	v_pk_fma_f32 v[18:19], v[162:163], v[18:19], v[178:179]
	v_cvt_pk_bf16_f32 v244, v16, v17
	v_cvt_pk_bf16_f32 v245, v18, v19
	v_pk_mul_f32 v[20:21], v[20:21], v[234:235] op_sel_hi:[1,0]
	v_pk_mul_f32 v[22:23], v[22:23], v[234:235] op_sel_hi:[1,0]
	v_pk_mul_f32 v[20:21], v[68:69], v[20:21]
	v_pk_mul_f32 v[22:23], v[70:71], v[22:23]
	v_pk_fma_f32 v[20:21], v[164:165], v[20:21], v[180:181]
	v_pk_fma_f32 v[22:23], v[166:167], v[22:23], v[182:183]
	v_cvt_pk_bf16_f32 v246, v20, v21
	v_cvt_pk_bf16_f32 v247, v22, v23
	global_store_dwordx4 v82, v[244:247], s[40:41] offset:0
	v_pk_mul_f32 v[24:25], v[24:25], v[234:235] op_sel_hi:[1,0]
	v_pk_mul_f32 v[26:27], v[26:27], v[234:235] op_sel_hi:[1,0]
	v_pk_mul_f32 v[24:25], v[72:73], v[24:25]
	v_pk_mul_f32 v[26:27], v[74:75], v[26:27]
	v_pk_fma_f32 v[24:25], v[168:169], v[24:25], v[184:185]
	v_pk_fma_f32 v[26:27], v[170:171], v[26:27], v[186:187]
	v_cvt_pk_bf16_f32 v240, v24, v25
	v_cvt_pk_bf16_f32 v241, v26, v27
	v_pk_mul_f32 v[28:29], v[28:29], v[234:235] op_sel_hi:[1,0]
	v_pk_mul_f32 v[30:31], v[30:31], v[234:235] op_sel_hi:[1,0]
	v_pk_mul_f32 v[28:29], v[76:77], v[28:29]
	v_pk_mul_f32 v[30:31], v[78:79], v[30:31]
	v_pk_fma_f32 v[28:29], v[172:173], v[28:29], v[188:189]
	v_pk_fma_f32 v[30:31], v[174:175], v[30:31], v[190:191]
	v_cvt_pk_bf16_f32 v242, v28, v29
	v_cvt_pk_bf16_f32 v243, v30, v31
	global_store_dwordx4 v82, v[240:243], s[40:41] offset:1024
	v_pk_mul_f32 v[32:33], v[32:33], v[236:237] op_sel_hi:[1,0]
	v_pk_mul_f32 v[34:35], v[34:35], v[236:237] op_sel_hi:[1,0]
	v_pk_mul_f32 v[32:33], v[64:65], v[32:33]
	v_pk_mul_f32 v[34:35], v[66:67], v[34:35]
	v_pk_fma_f32 v[32:33], v[192:193], v[32:33], v[208:209]
	v_pk_fma_f32 v[34:35], v[194:195], v[34:35], v[210:211]
	v_cvt_pk_bf16_f32 v244, v32, v33
	v_cvt_pk_bf16_f32 v245, v34, v35
	v_pk_mul_f32 v[36:37], v[36:37], v[236:237] op_sel_hi:[1,0]
	v_pk_mul_f32 v[38:39], v[38:39], v[236:237] op_sel_hi:[1,0]
	v_pk_mul_f32 v[36:37], v[68:69], v[36:37]
	v_pk_mul_f32 v[38:39], v[70:71], v[38:39]
	v_pk_fma_f32 v[36:37], v[196:197], v[36:37], v[212:213]
	v_pk_fma_f32 v[38:39], v[198:199], v[38:39], v[214:215]
	v_cvt_pk_bf16_f32 v246, v36, v37
	v_cvt_pk_bf16_f32 v247, v38, v39
	global_store_dwordx4 v82, v[244:247], s[46:47] offset:0
	v_pk_mul_f32 v[40:41], v[40:41], v[236:237] op_sel_hi:[1,0]
	v_pk_mul_f32 v[42:43], v[42:43], v[236:237] op_sel_hi:[1,0]
	v_pk_mul_f32 v[40:41], v[72:73], v[40:41]
	v_pk_mul_f32 v[42:43], v[74:75], v[42:43]
	v_pk_fma_f32 v[40:41], v[200:201], v[40:41], v[216:217]
	v_pk_fma_f32 v[42:43], v[202:203], v[42:43], v[218:219]
	v_cvt_pk_bf16_f32 v240, v40, v41
	v_cvt_pk_bf16_f32 v241, v42, v43
	v_pk_mul_f32 v[44:45], v[44:45], v[236:237] op_sel_hi:[1,0]
	v_pk_mul_f32 v[46:47], v[46:47], v[236:237] op_sel_hi:[1,0]
	v_pk_mul_f32 v[44:45], v[76:77], v[44:45]
	v_pk_mul_f32 v[46:47], v[78:79], v[46:47]
	v_pk_fma_f32 v[44:45], v[204:205], v[44:45], v[220:221]
	v_pk_fma_f32 v[46:47], v[206:207], v[46:47], v[222:223]
	v_cvt_pk_bf16_f32 v242, v44, v45
	v_cvt_pk_bf16_f32 v243, v46, v47
	global_store_dwordx4 v82, v[240:243], s[46:47] offset:1024
	v_pk_mul_f32 v[48:49], v[48:49], v[238:239] op_sel_hi:[1,0]
	v_pk_mul_f32 v[50:51], v[50:51], v[238:239] op_sel_hi:[1,0]
	v_pk_mul_f32 v[48:49], v[64:65], v[48:49]
	v_pk_mul_f32 v[50:51], v[66:67], v[50:51]
	v_pk_fma_f32 v[48:49], v[192:193], v[48:49], v[208:209]
	v_pk_fma_f32 v[50:51], v[194:195], v[50:51], v[210:211]
	v_cvt_pk_bf16_f32 v244, v48, v49
	v_cvt_pk_bf16_f32 v245, v50, v51
	v_pk_mul_f32 v[52:53], v[52:53], v[238:239] op_sel_hi:[1,0]
	v_pk_mul_f32 v[54:55], v[54:55], v[238:239] op_sel_hi:[1,0]
	v_pk_mul_f32 v[52:53], v[68:69], v[52:53]
	v_pk_mul_f32 v[54:55], v[70:71], v[54:55]
	v_pk_fma_f32 v[52:53], v[196:197], v[52:53], v[212:213]
	v_pk_fma_f32 v[54:55], v[198:199], v[54:55], v[214:215]
	v_cvt_pk_bf16_f32 v246, v52, v53
	v_cvt_pk_bf16_f32 v247, v54, v55
	global_store_dwordx4 v82, v[244:247], s[48:49] offset:0
	v_pk_mul_f32 v[56:57], v[56:57], v[238:239] op_sel_hi:[1,0]
	v_pk_mul_f32 v[58:59], v[58:59], v[238:239] op_sel_hi:[1,0]
	v_pk_mul_f32 v[56:57], v[72:73], v[56:57]
	v_pk_mul_f32 v[58:59], v[74:75], v[58:59]
	v_pk_fma_f32 v[56:57], v[200:201], v[56:57], v[216:217]
	v_pk_fma_f32 v[58:59], v[202:203], v[58:59], v[218:219]
	v_cvt_pk_bf16_f32 v240, v56, v57
	v_cvt_pk_bf16_f32 v241, v58, v59
	v_pk_mul_f32 v[60:61], v[60:61], v[238:239] op_sel_hi:[1,0]
	v_pk_mul_f32 v[62:63], v[62:63], v[238:239] op_sel_hi:[1,0]
	v_pk_mul_f32 v[60:61], v[76:77], v[60:61]
	v_pk_mul_f32 v[62:63], v[78:79], v[62:63]
	v_pk_fma_f32 v[60:61], v[204:205], v[60:61], v[220:221]
	v_pk_fma_f32 v[62:63], v[206:207], v[62:63], v[222:223]
	v_cvt_pk_bf16_f32 v242, v60, v61
	v_cvt_pk_bf16_f32 v243, v62, v63
	global_store_dwordx4 v82, v[240:243], s[48:49] offset:1024
	s_add_u32 s34, s8, 0x3f000
	s_addc_u32 s35, s9, 0
	s_add_u32 s36, s8, 0x45000
	s_addc_u32 s37, s9, 0
	global_load_dwordx4 v[176:179], v80, s[34:35] offset:0
	global_load_dwordx4 v[180:183], v80, s[34:35] offset:16
	global_load_dwordx4 v[184:187], v80, s[34:35] offset:2048
	global_load_dwordx4 v[188:191], v80, s[34:35] offset:2064
	global_load_dwordx4 v[160:163], v81, s[34:35] offset:0
	global_load_dwordx4 v[164:167], v81, s[34:35] offset:16
	global_load_dwordx4 v[168:171], v81, s[34:35] offset:2048
	global_load_dwordx4 v[172:175], v81, s[34:35] offset:2064
	global_load_dwordx4 v[208:211], v80, s[36:37] offset:0
	global_load_dwordx4 v[212:215], v80, s[36:37] offset:16
	global_load_dwordx4 v[216:219], v80, s[36:37] offset:2048
	global_load_dwordx4 v[220:223], v80, s[36:37] offset:2064
	global_load_dwordx4 v[192:195], v81, s[36:37] offset:0
	global_load_dwordx4 v[196:199], v81, s[36:37] offset:16
	global_load_dwordx4 v[200:203], v81, s[36:37] offset:2048
	global_load_dwordx4 v[204:207], v81, s[36:37] offset:2064
	s_add_u32 s24, s16, 0xa000000
	s_addc_u32 s25, s17, 0
	s_add_u32 s26, s16, 0xa400000
	s_addc_u32 s27, s17, 0
	s_add_u32 s28, s16, 0xa800000
	s_addc_u32 s29, s17, 0
	s_add_u32 s30, s16, 0xac00000
	s_addc_u32 s31, s17, 0
	global_load_dwordx4 v[96:99], v82, s[24:25] offset:0
	global_load_dwordx4 v[100:103], v82, s[24:25] offset:1024
	global_load_dwordx4 v[104:107], v82, s[26:27] offset:0
	global_load_dwordx4 v[108:111], v82, s[26:27] offset:1024
	global_load_dwordx4 v[112:115], v82, s[28:29] offset:0
	global_load_dwordx4 v[116:119], v82, s[28:29] offset:1024
	global_load_dwordx4 v[120:123], v82, s[30:31] offset:0
	global_load_dwordx4 v[124:127], v82, s[30:31] offset:1024
	s_waitcnt vmcnt(32)
	v_lshlrev_b32_e32 v0, 16, v128
	v_and_b32_e32 v1, 0xffff0000, v128
	v_lshlrev_b32_e32 v2, 16, v129
	v_and_b32_e32 v3, 0xffff0000, v129
	v_lshlrev_b32_e32 v4, 16, v130
	v_and_b32_e32 v5, 0xffff0000, v130
	v_lshlrev_b32_e32 v6, 16, v131
	v_and_b32_e32 v7, 0xffff0000, v131
	v_lshlrev_b32_e32 v8, 16, v132
	v_and_b32_e32 v9, 0xffff0000, v132
	v_lshlrev_b32_e32 v10, 16, v133
	v_and_b32_e32 v11, 0xffff0000, v133
	v_lshlrev_b32_e32 v12, 16, v134
	v_and_b32_e32 v13, 0xffff0000, v134
	v_lshlrev_b32_e32 v14, 16, v135
	v_and_b32_e32 v15, 0xffff0000, v135
	v_lshlrev_b32_e32 v16, 16, v136
	v_and_b32_e32 v17, 0xffff0000, v136
	v_lshlrev_b32_e32 v18, 16, v137
	v_and_b32_e32 v19, 0xffff0000, v137
	v_lshlrev_b32_e32 v20, 16, v138
	v_and_b32_e32 v21, 0xffff0000, v138
	v_lshlrev_b32_e32 v22, 16, v139
	v_and_b32_e32 v23, 0xffff0000, v139
	v_lshlrev_b32_e32 v24, 16, v140
	v_and_b32_e32 v25, 0xffff0000, v140
	v_lshlrev_b32_e32 v26, 16, v141
	v_and_b32_e32 v27, 0xffff0000, v141
	v_lshlrev_b32_e32 v28, 16, v142
	v_and_b32_e32 v29, 0xffff0000, v142
	v_lshlrev_b32_e32 v30, 16, v143
	v_and_b32_e32 v31, 0xffff0000, v143
	v_lshlrev_b32_e32 v32, 16, v144
	v_and_b32_e32 v33, 0xffff0000, v144
	v_lshlrev_b32_e32 v34, 16, v145
	v_and_b32_e32 v35, 0xffff0000, v145
	v_lshlrev_b32_e32 v36, 16, v146
	v_and_b32_e32 v37, 0xffff0000, v146
	v_lshlrev_b32_e32 v38, 16, v147
	v_and_b32_e32 v39, 0xffff0000, v147
	v_lshlrev_b32_e32 v40, 16, v148
	v_and_b32_e32 v41, 0xffff0000, v148
	v_lshlrev_b32_e32 v42, 16, v149
	v_and_b32_e32 v43, 0xffff0000, v149
	v_lshlrev_b32_e32 v44, 16, v150
	v_and_b32_e32 v45, 0xffff0000, v150
	v_lshlrev_b32_e32 v46, 16, v151
	v_and_b32_e32 v47, 0xffff0000, v151
	v_lshlrev_b32_e32 v48, 16, v152
	v_and_b32_e32 v49, 0xffff0000, v152
	v_lshlrev_b32_e32 v50, 16, v153
	v_and_b32_e32 v51, 0xffff0000, v153
	v_lshlrev_b32_e32 v52, 16, v154
	v_and_b32_e32 v53, 0xffff0000, v154
	v_lshlrev_b32_e32 v54, 16, v155
	v_and_b32_e32 v55, 0xffff0000, v155
	v_lshlrev_b32_e32 v56, 16, v156
	v_and_b32_e32 v57, 0xffff0000, v156
	v_lshlrev_b32_e32 v58, 16, v157
	v_and_b32_e32 v59, 0xffff0000, v157
	v_lshlrev_b32_e32 v60, 16, v158
	v_and_b32_e32 v61, 0xffff0000, v158
	v_lshlrev_b32_e32 v62, 16, v159
	v_and_b32_e32 v63, 0xffff0000, v159
	v_pk_mul_f32 v[240:241], v[0:1], v[0:1]
	v_pk_mul_f32 v[242:243], v[16:17], v[16:17]
	v_pk_mul_f32 v[244:245], v[32:33], v[32:33]
	v_pk_mul_f32 v[246:247], v[48:49], v[48:49]
	v_pk_fma_f32 v[240:241], v[2:3], v[2:3], v[240:241]
	v_pk_fma_f32 v[242:243], v[18:19], v[18:19], v[242:243]
	v_pk_fma_f32 v[244:245], v[34:35], v[34:35], v[244:245]
	v_pk_fma_f32 v[246:247], v[50:51], v[50:51], v[246:247]
	v_pk_fma_f32 v[240:241], v[4:5], v[4:5], v[240:241]
	v_pk_fma_f32 v[242:243], v[20:21], v[20:21], v[242:243]
	v_pk_fma_f32 v[244:245], v[36:37], v[36:37], v[244:245]
	v_pk_fma_f32 v[246:247], v[52:53], v[52:53], v[246:247]
	v_pk_fma_f32 v[240:241], v[6:7], v[6:7], v[240:241]
	v_pk_fma_f32 v[242:243], v[22:23], v[22:23], v[242:243]
	v_pk_fma_f32 v[244:245], v[38:39], v[38:39], v[244:245]
	v_pk_fma_f32 v[246:247], v[54:55], v[54:55], v[246:247]
	v_pk_fma_f32 v[240:241], v[8:9], v[8:9], v[240:241]
	v_pk_fma_f32 v[242:243], v[24:25], v[24:25], v[242:243]
	v_pk_fma_f32 v[244:245], v[40:41], v[40:41], v[244:245]
	v_pk_fma_f32 v[246:247], v[56:57], v[56:57], v[246:247]
	v_pk_fma_f32 v[240:241], v[10:11], v[10:11], v[240:241]
	v_pk_fma_f32 v[242:243], v[26:27], v[26:27], v[242:243]
	v_pk_fma_f32 v[244:245], v[42:43], v[42:43], v[244:245]
	v_pk_fma_f32 v[246:247], v[58:59], v[58:59], v[246:247]
	v_pk_fma_f32 v[240:241], v[12:13], v[12:13], v[240:241]
	v_pk_fma_f32 v[242:243], v[28:29], v[28:29], v[242:243]
	v_pk_fma_f32 v[244:245], v[44:45], v[44:45], v[244:245]
	v_pk_fma_f32 v[246:247], v[60:61], v[60:61], v[246:247]
	v_pk_fma_f32 v[240:241], v[14:15], v[14:15], v[240:241]
	v_pk_fma_f32 v[242:243], v[30:31], v[30:31], v[242:243]
	v_pk_fma_f32 v[244:245], v[46:47], v[46:47], v[244:245]
	v_pk_fma_f32 v[246:247], v[62:63], v[62:63], v[246:247]
	v_add_f32_e32 v224, v240, v241
	v_add_f32_e32 v225, v242, v243
	v_add_f32_e32 v226, v244, v245
	v_add_f32_e32 v227, v246, v247
	ds_bpermute_b32 v228, v83, v224
	ds_bpermute_b32 v229, v83, v225
	ds_bpermute_b32 v230, v83, v226
	ds_bpermute_b32 v231, v83, v227
	s_waitcnt lgkmcnt(0)
	v_add_f32_e32 v224, v224, v228
	v_add_f32_e32 v225, v225, v229
	v_add_f32_e32 v226, v226, v230
	v_add_f32_e32 v227, v227, v231
	ds_bpermute_b32 v228, v84, v224
	ds_bpermute_b32 v229, v84, v225
	ds_bpermute_b32 v230, v84, v226
	ds_bpermute_b32 v231, v84, v227
	s_waitcnt lgkmcnt(0)
	v_add_f32_e32 v224, v224, v228
	v_add_f32_e32 v225, v225, v229
	v_add_f32_e32 v226, v226, v230
	v_add_f32_e32 v227, v227, v231
	ds_bpermute_b32 v228, v85, v224
	ds_bpermute_b32 v229, v85, v225
	ds_bpermute_b32 v230, v85, v226
	ds_bpermute_b32 v231, v85, v227
	s_waitcnt lgkmcnt(0)
	v_add_f32_e32 v224, v224, v228
	v_add_f32_e32 v225, v225, v229
	v_add_f32_e32 v226, v226, v230
	v_add_f32_e32 v227, v227, v231
	ds_bpermute_b32 v228, v86, v224
	ds_bpermute_b32 v229, v86, v225
	ds_bpermute_b32 v230, v86, v226
	ds_bpermute_b32 v231, v86, v227
	s_waitcnt lgkmcnt(0)
	v_add_f32_e32 v224, v224, v228
	v_add_f32_e32 v225, v225, v229
	v_add_f32_e32 v226, v226, v230
	v_add_f32_e32 v227, v227, v231
	ds_bpermute_b32 v228, v87, v224
	ds_bpermute_b32 v229, v87, v225
	ds_bpermute_b32 v230, v87, v226
	ds_bpermute_b32 v231, v87, v227
	s_waitcnt lgkmcnt(0)
	v_add_f32_e32 v224, v224, v228
	v_add_f32_e32 v225, v225, v229
	v_add_f32_e32 v226, v226, v230
	v_add_f32_e32 v227, v227, v231
	ds_bpermute_b32 v228, v88, v224
	ds_bpermute_b32 v229, v88, v225
	ds_bpermute_b32 v230, v88, v226
	ds_bpermute_b32 v231, v88, v227
	s_waitcnt lgkmcnt(0)
	v_add_f32_e32 v224, v224, v228
	v_add_f32_e32 v225, v225, v229
	v_add_f32_e32 v226, v226, v230
	v_add_f32_e32 v227, v227, v231
	v_fmamk_f32 v240, v224, 0x3a800000, v89
	v_mul_f32_e32 v241, 0x4f800000, v240
	v_cmp_gt_f32_e32 vcc, s54, v240
	s_nop 1
	v_cndmask_b32_e32 v247, v240, v241, vcc
	v_sqrt_f32_e32 v242, v247
	s_nop 1
	v_add_u32_e32 v243, -1, v242
	v_add_u32_e32 v244, 1, v242
	v_fma_f32 v245, -v243, v242, v247
	v_fma_f32 v246, -v244, v242, v247
	v_cmp_ge_f32_e64 s[52:53], 0, v245
	s_nop 1
	v_cndmask_b32_e64 v242, v242, v243, s[52:53]
	v_cmp_lt_f32_e64 s[52:53], 0, v246
	s_nop 1
	v_cndmask_b32_e64 v242, v242, v244, s[52:53]
	v_mul_f32_e32 v243, 0x37800000, v242
	v_cndmask_b32_e32 v242, v242, v243, vcc
	v_cmp_class_f32_e32 vcc, v247, v90
	s_nop 1
	v_cndmask_b32_e32 v247, v242, v247, vcc
	v_div_scale_f32 v248, s[52:53], v247, v247, 1.0
	v_rcp_f32_e32 v249, v248
	v_div_scale_f32 v228, vcc, 1.0, v247, 1.0
	s_nop 0
	v_fma_f32 v229, -v248, v249, 1.0
	v_fmac_f32_e32 v249, v229, v249
	v_mul_f32_e32 v230, v228, v249
	v_fma_f32 v229, -v248, v230, v228
	v_fmac_f32_e32 v230, v229, v249
	v_fma_f32 v248, -v248, v230, v228
	v_div_fmas_f32 v248, v248, v249, v230
	v_div_fixup_f32 v232, v248, v247, 1.0
	v_fmamk_f32 v240, v225, 0x3a800000, v89
	v_mul_f32_e32 v241, 0x4f800000, v240
	v_cmp_gt_f32_e32 vcc, s54, v240
	s_nop 1
	v_cndmask_b32_e32 v247, v240, v241, vcc
	v_sqrt_f32_e32 v242, v247
	s_nop 1
	v_add_u32_e32 v243, -1, v242
	v_add_u32_e32 v244, 1, v242
	v_fma_f32 v245, -v243, v242, v247
	v_fma_f32 v246, -v244, v242, v247
	v_cmp_ge_f32_e64 s[52:53], 0, v245
	s_nop 1
	v_cndmask_b32_e64 v242, v242, v243, s[52:53]
	v_cmp_lt_f32_e64 s[52:53], 0, v246
	s_nop 1
	v_cndmask_b32_e64 v242, v242, v244, s[52:53]
	v_mul_f32_e32 v243, 0x37800000, v242
	v_cndmask_b32_e32 v242, v242, v243, vcc
	v_cmp_class_f32_e32 vcc, v247, v90
	s_nop 1
	v_cndmask_b32_e32 v247, v242, v247, vcc
	v_div_scale_f32 v248, s[52:53], v247, v247, 1.0
	v_rcp_f32_e32 v249, v248
	v_div_scale_f32 v228, vcc, 1.0, v247, 1.0
	s_nop 0
	v_fma_f32 v229, -v248, v249, 1.0
	v_fmac_f32_e32 v249, v229, v249
	v_mul_f32_e32 v230, v228, v249
	v_fma_f32 v229, -v248, v230, v228
	v_fmac_f32_e32 v230, v229, v249
	v_fma_f32 v248, -v248, v230, v228
	v_div_fmas_f32 v248, v248, v249, v230
	v_div_fixup_f32 v234, v248, v247, 1.0
	v_fmamk_f32 v240, v226, 0x3a800000, v89
	v_mul_f32_e32 v241, 0x4f800000, v240
	v_cmp_gt_f32_e32 vcc, s54, v240
	s_nop 1
	v_cndmask_b32_e32 v247, v240, v241, vcc
	v_sqrt_f32_e32 v242, v247
	s_nop 1
	v_add_u32_e32 v243, -1, v242
	v_add_u32_e32 v244, 1, v242
	v_fma_f32 v245, -v243, v242, v247
	v_fma_f32 v246, -v244, v242, v247
	v_cmp_ge_f32_e64 s[52:53], 0, v245
	s_nop 1
	v_cndmask_b32_e64 v242, v242, v243, s[52:53]
	v_cmp_lt_f32_e64 s[52:53], 0, v246
	s_nop 1
	v_cndmask_b32_e64 v242, v242, v244, s[52:53]
	v_mul_f32_e32 v243, 0x37800000, v242
	v_cndmask_b32_e32 v242, v242, v243, vcc
	v_cmp_class_f32_e32 vcc, v247, v90
	s_nop 1
	v_cndmask_b32_e32 v247, v242, v247, vcc
	v_div_scale_f32 v248, s[52:53], v247, v247, 1.0
	v_rcp_f32_e32 v249, v248
	v_div_scale_f32 v228, vcc, 1.0, v247, 1.0
	s_nop 0
	v_fma_f32 v229, -v248, v249, 1.0
	v_fmac_f32_e32 v249, v229, v249
	v_mul_f32_e32 v230, v228, v249
	v_fma_f32 v229, -v248, v230, v228
	v_fmac_f32_e32 v230, v229, v249
	v_fma_f32 v248, -v248, v230, v228
	v_div_fmas_f32 v248, v248, v249, v230
	v_div_fixup_f32 v236, v248, v247, 1.0
	v_fmamk_f32 v240, v227, 0x3a800000, v89
	v_mul_f32_e32 v241, 0x4f800000, v240
	v_cmp_gt_f32_e32 vcc, s54, v240
	s_nop 1
	v_cndmask_b32_e32 v247, v240, v241, vcc
	v_sqrt_f32_e32 v242, v247
	s_nop 1
	v_add_u32_e32 v243, -1, v242
	v_add_u32_e32 v244, 1, v242
	v_fma_f32 v245, -v243, v242, v247
	v_fma_f32 v246, -v244, v242, v247
	v_cmp_ge_f32_e64 s[52:53], 0, v245
	s_nop 1
	v_cndmask_b32_e64 v242, v242, v243, s[52:53]
	v_cmp_lt_f32_e64 s[52:53], 0, v246
	s_nop 1
	v_cndmask_b32_e64 v242, v242, v244, s[52:53]
	v_mul_f32_e32 v243, 0x37800000, v242
	v_cndmask_b32_e32 v242, v242, v243, vcc
	v_cmp_class_f32_e32 vcc, v247, v90
	s_nop 1
	v_cndmask_b32_e32 v247, v242, v247, vcc
	v_div_scale_f32 v248, s[52:53], v247, v247, 1.0
	v_rcp_f32_e32 v249, v248
	v_div_scale_f32 v228, vcc, 1.0, v247, 1.0
	s_nop 0
	v_fma_f32 v229, -v248, v249, 1.0
	v_fmac_f32_e32 v249, v229, v249
	v_mul_f32_e32 v230, v228, v249
	v_fma_f32 v229, -v248, v230, v228
	v_fmac_f32_e32 v230, v229, v249
	v_fma_f32 v248, -v248, v230, v228
	v_div_fmas_f32 v248, v248, v249, v230
	v_div_fixup_f32 v238, v248, v247, 1.0
	s_waitcnt vmcnt(8)
	v_pk_add_f32 v[160:161], v[160:161], 1.0 op_sel_hi:[1,0]
	v_pk_add_f32 v[162:163], v[162:163], 1.0 op_sel_hi:[1,0]
	v_pk_add_f32 v[164:165], v[164:165], 1.0 op_sel_hi:[1,0]
	v_pk_add_f32 v[166:167], v[166:167], 1.0 op_sel_hi:[1,0]
	v_pk_add_f32 v[168:169], v[168:169], 1.0 op_sel_hi:[1,0]
	v_pk_add_f32 v[170:171], v[170:171], 1.0 op_sel_hi:[1,0]
	v_pk_add_f32 v[172:173], v[172:173], 1.0 op_sel_hi:[1,0]
	v_pk_add_f32 v[174:175], v[174:175], 1.0 op_sel_hi:[1,0]
	v_pk_add_f32 v[192:193], v[192:193], 1.0 op_sel_hi:[1,0]
	v_pk_add_f32 v[194:195], v[194:195], 1.0 op_sel_hi:[1,0]
	v_pk_add_f32 v[196:197], v[196:197], 1.0 op_sel_hi:[1,0]
	v_pk_add_f32 v[198:199], v[198:199], 1.0 op_sel_hi:[1,0]
	v_pk_add_f32 v[200:201], v[200:201], 1.0 op_sel_hi:[1,0]
	v_pk_add_f32 v[202:203], v[202:203], 1.0 op_sel_hi:[1,0]
	v_pk_add_f32 v[204:205], v[204:205], 1.0 op_sel_hi:[1,0]
	v_pk_add_f32 v[206:207], v[206:207], 1.0 op_sel_hi:[1,0]
	s_add_u32 s38, s20, 0x9000000
	s_addc_u32 s39, s21, 0
	s_add_u32 s40, s20, 0x9400000
	s_addc_u32 s41, s21, 0
	s_add_u32 s46, s20, 0x9800000
	s_addc_u32 s47, s21, 0
	s_add_u32 s48, s20, 0x9c00000
	s_addc_u32 s49, s21, 0
	v_pk_mul_f32 v[0:1], v[0:1], v[232:233] op_sel_hi:[1,0]
	v_pk_mul_f32 v[2:3], v[2:3], v[232:233] op_sel_hi:[1,0]
	v_pk_mul_f32 v[0:1], v[64:65], v[0:1]
	v_pk_mul_f32 v[2:3], v[66:67], v[2:3]
	v_pk_fma_f32 v[0:1], v[160:161], v[0:1], v[176:177]
	v_pk_fma_f32 v[2:3], v[162:163], v[2:3], v[178:179]
	v_cvt_pk_bf16_f32 v244, v0, v1
	v_cvt_pk_bf16_f32 v245, v2, v3
	v_pk_mul_f32 v[4:5], v[4:5], v[232:233] op_sel_hi:[1,0]
	v_pk_mul_f32 v[6:7], v[6:7], v[232:233] op_sel_hi:[1,0]
	v_pk_mul_f32 v[4:5], v[68:69], v[4:5]
	v_pk_mul_f32 v[6:7], v[70:71], v[6:7]
	v_pk_fma_f32 v[4:5], v[164:165], v[4:5], v[180:181]
	v_pk_fma_f32 v[6:7], v[166:167], v[6:7], v[182:183]
	v_cvt_pk_bf16_f32 v246, v4, v5
	v_cvt_pk_bf16_f32 v247, v6, v7
	global_store_dwordx4 v82, v[244:247], s[38:39] offset:0
	v_pk_mul_f32 v[8:9], v[8:9], v[232:233] op_sel_hi:[1,0]
	v_pk_mul_f32 v[10:11], v[10:11], v[232:233] op_sel_hi:[1,0]
	v_pk_mul_f32 v[8:9], v[72:73], v[8:9]
	v_pk_mul_f32 v[10:11], v[74:75], v[10:11]
	v_pk_fma_f32 v[8:9], v[168:169], v[8:9], v[184:185]
	v_pk_fma_f32 v[10:11], v[170:171], v[10:11], v[186:187]
	v_cvt_pk_bf16_f32 v240, v8, v9
	v_cvt_pk_bf16_f32 v241, v10, v11
	v_pk_mul_f32 v[12:13], v[12:13], v[232:233] op_sel_hi:[1,0]
	v_pk_mul_f32 v[14:15], v[14:15], v[232:233] op_sel_hi:[1,0]
	v_pk_mul_f32 v[12:13], v[76:77], v[12:13]
	v_pk_mul_f32 v[14:15], v[78:79], v[14:15]
	v_pk_fma_f32 v[12:13], v[172:173], v[12:13], v[188:189]
	v_pk_fma_f32 v[14:15], v[174:175], v[14:15], v[190:191]
	v_cvt_pk_bf16_f32 v242, v12, v13
	v_cvt_pk_bf16_f32 v243, v14, v15
	global_store_dwordx4 v82, v[240:243], s[38:39] offset:1024
	v_pk_mul_f32 v[16:17], v[16:17], v[234:235] op_sel_hi:[1,0]
	v_pk_mul_f32 v[18:19], v[18:19], v[234:235] op_sel_hi:[1,0]
	v_pk_mul_f32 v[16:17], v[64:65], v[16:17]
	v_pk_mul_f32 v[18:19], v[66:67], v[18:19]
	v_pk_fma_f32 v[16:17], v[160:161], v[16:17], v[176:177]
	v_pk_fma_f32 v[18:19], v[162:163], v[18:19], v[178:179]
	v_cvt_pk_bf16_f32 v244, v16, v17
	v_cvt_pk_bf16_f32 v245, v18, v19
	v_pk_mul_f32 v[20:21], v[20:21], v[234:235] op_sel_hi:[1,0]
	v_pk_mul_f32 v[22:23], v[22:23], v[234:235] op_sel_hi:[1,0]
	v_pk_mul_f32 v[20:21], v[68:69], v[20:21]
	v_pk_mul_f32 v[22:23], v[70:71], v[22:23]
	v_pk_fma_f32 v[20:21], v[164:165], v[20:21], v[180:181]
	v_pk_fma_f32 v[22:23], v[166:167], v[22:23], v[182:183]
	v_cvt_pk_bf16_f32 v246, v20, v21
	v_cvt_pk_bf16_f32 v247, v22, v23
	global_store_dwordx4 v82, v[244:247], s[40:41] offset:0
	v_pk_mul_f32 v[24:25], v[24:25], v[234:235] op_sel_hi:[1,0]
	v_pk_mul_f32 v[26:27], v[26:27], v[234:235] op_sel_hi:[1,0]
	v_pk_mul_f32 v[24:25], v[72:73], v[24:25]
	v_pk_mul_f32 v[26:27], v[74:75], v[26:27]
	v_pk_fma_f32 v[24:25], v[168:169], v[24:25], v[184:185]
	v_pk_fma_f32 v[26:27], v[170:171], v[26:27], v[186:187]
	v_cvt_pk_bf16_f32 v240, v24, v25
	v_cvt_pk_bf16_f32 v241, v26, v27
	v_pk_mul_f32 v[28:29], v[28:29], v[234:235] op_sel_hi:[1,0]
	v_pk_mul_f32 v[30:31], v[30:31], v[234:235] op_sel_hi:[1,0]
	v_pk_mul_f32 v[28:29], v[76:77], v[28:29]
	v_pk_mul_f32 v[30:31], v[78:79], v[30:31]
	v_pk_fma_f32 v[28:29], v[172:173], v[28:29], v[188:189]
	v_pk_fma_f32 v[30:31], v[174:175], v[30:31], v[190:191]
	v_cvt_pk_bf16_f32 v242, v28, v29
	v_cvt_pk_bf16_f32 v243, v30, v31
	global_store_dwordx4 v82, v[240:243], s[40:41] offset:1024
	v_pk_mul_f32 v[32:33], v[32:33], v[236:237] op_sel_hi:[1,0]
	v_pk_mul_f32 v[34:35], v[34:35], v[236:237] op_sel_hi:[1,0]
	v_pk_mul_f32 v[32:33], v[64:65], v[32:33]
	v_pk_mul_f32 v[34:35], v[66:67], v[34:35]
	v_pk_fma_f32 v[32:33], v[192:193], v[32:33], v[208:209]
	v_pk_fma_f32 v[34:35], v[194:195], v[34:35], v[210:211]
	v_cvt_pk_bf16_f32 v244, v32, v33
	v_cvt_pk_bf16_f32 v245, v34, v35
	v_pk_mul_f32 v[36:37], v[36:37], v[236:237] op_sel_hi:[1,0]
	v_pk_mul_f32 v[38:39], v[38:39], v[236:237] op_sel_hi:[1,0]
	v_pk_mul_f32 v[36:37], v[68:69], v[36:37]
	v_pk_mul_f32 v[38:39], v[70:71], v[38:39]
	v_pk_fma_f32 v[36:37], v[196:197], v[36:37], v[212:213]
	v_pk_fma_f32 v[38:39], v[198:199], v[38:39], v[214:215]
	v_cvt_pk_bf16_f32 v246, v36, v37
	v_cvt_pk_bf16_f32 v247, v38, v39
	global_store_dwordx4 v82, v[244:247], s[46:47] offset:0
	v_pk_mul_f32 v[40:41], v[40:41], v[236:237] op_sel_hi:[1,0]
	v_pk_mul_f32 v[42:43], v[42:43], v[236:237] op_sel_hi:[1,0]
	v_pk_mul_f32 v[40:41], v[72:73], v[40:41]
	v_pk_mul_f32 v[42:43], v[74:75], v[42:43]
	v_pk_fma_f32 v[40:41], v[200:201], v[40:41], v[216:217]
	v_pk_fma_f32 v[42:43], v[202:203], v[42:43], v[218:219]
	v_cvt_pk_bf16_f32 v240, v40, v41
	v_cvt_pk_bf16_f32 v241, v42, v43
	v_pk_mul_f32 v[44:45], v[44:45], v[236:237] op_sel_hi:[1,0]
	v_pk_mul_f32 v[46:47], v[46:47], v[236:237] op_sel_hi:[1,0]
	v_pk_mul_f32 v[44:45], v[76:77], v[44:45]
	v_pk_mul_f32 v[46:47], v[78:79], v[46:47]
	v_pk_fma_f32 v[44:45], v[204:205], v[44:45], v[220:221]
	v_pk_fma_f32 v[46:47], v[206:207], v[46:47], v[222:223]
	v_cvt_pk_bf16_f32 v242, v44, v45
	v_cvt_pk_bf16_f32 v243, v46, v47
	global_store_dwordx4 v82, v[240:243], s[46:47] offset:1024
	v_pk_mul_f32 v[48:49], v[48:49], v[238:239] op_sel_hi:[1,0]
	v_pk_mul_f32 v[50:51], v[50:51], v[238:239] op_sel_hi:[1,0]
	v_pk_mul_f32 v[48:49], v[64:65], v[48:49]
	v_pk_mul_f32 v[50:51], v[66:67], v[50:51]
	v_pk_fma_f32 v[48:49], v[192:193], v[48:49], v[208:209]
	v_pk_fma_f32 v[50:51], v[194:195], v[50:51], v[210:211]
	v_cvt_pk_bf16_f32 v244, v48, v49
	v_cvt_pk_bf16_f32 v245, v50, v51
	v_pk_mul_f32 v[52:53], v[52:53], v[238:239] op_sel_hi:[1,0]
	v_pk_mul_f32 v[54:55], v[54:55], v[238:239] op_sel_hi:[1,0]
	v_pk_mul_f32 v[52:53], v[68:69], v[52:53]
	v_pk_mul_f32 v[54:55], v[70:71], v[54:55]
	v_pk_fma_f32 v[52:53], v[196:197], v[52:53], v[212:213]
	v_pk_fma_f32 v[54:55], v[198:199], v[54:55], v[214:215]
	v_cvt_pk_bf16_f32 v246, v52, v53
	v_cvt_pk_bf16_f32 v247, v54, v55
	global_store_dwordx4 v82, v[244:247], s[48:49] offset:0
	v_pk_mul_f32 v[56:57], v[56:57], v[238:239] op_sel_hi:[1,0]
	v_pk_mul_f32 v[58:59], v[58:59], v[238:239] op_sel_hi:[1,0]
	v_pk_mul_f32 v[56:57], v[72:73], v[56:57]
	v_pk_mul_f32 v[58:59], v[74:75], v[58:59]
	v_pk_fma_f32 v[56:57], v[200:201], v[56:57], v[216:217]
	v_pk_fma_f32 v[58:59], v[202:203], v[58:59], v[218:219]
	v_cvt_pk_bf16_f32 v240, v56, v57
	v_cvt_pk_bf16_f32 v241, v58, v59
	v_pk_mul_f32 v[60:61], v[60:61], v[238:239] op_sel_hi:[1,0]
	v_pk_mul_f32 v[62:63], v[62:63], v[238:239] op_sel_hi:[1,0]
	v_pk_mul_f32 v[60:61], v[76:77], v[60:61]
	v_pk_mul_f32 v[62:63], v[78:79], v[62:63]
	v_pk_fma_f32 v[60:61], v[204:205], v[60:61], v[220:221]
	v_pk_fma_f32 v[62:63], v[206:207], v[62:63], v[222:223]
	v_cvt_pk_bf16_f32 v242, v60, v61
	v_cvt_pk_bf16_f32 v243, v62, v63
	global_store_dwordx4 v82, v[240:243], s[48:49] offset:1024
	s_add_u32 s34, s8, 0x4b000
	s_addc_u32 s35, s9, 0
	s_add_u32 s36, s8, 0x51000
	s_addc_u32 s37, s9, 0
	global_load_dwordx4 v[176:179], v80, s[34:35] offset:0
	global_load_dwordx4 v[180:183], v80, s[34:35] offset:16
	global_load_dwordx4 v[184:187], v80, s[34:35] offset:2048
	global_load_dwordx4 v[188:191], v80, s[34:35] offset:2064
	global_load_dwordx4 v[160:163], v81, s[34:35] offset:0
	global_load_dwordx4 v[164:167], v81, s[34:35] offset:16
	global_load_dwordx4 v[168:171], v81, s[34:35] offset:2048
	global_load_dwordx4 v[172:175], v81, s[34:35] offset:2064
	global_load_dwordx4 v[208:211], v80, s[36:37] offset:0
	global_load_dwordx4 v[212:215], v80, s[36:37] offset:16
	global_load_dwordx4 v[216:219], v80, s[36:37] offset:2048
	global_load_dwordx4 v[220:223], v80, s[36:37] offset:2064
	global_load_dwordx4 v[192:195], v81, s[36:37] offset:0
	global_load_dwordx4 v[196:199], v81, s[36:37] offset:16
	global_load_dwordx4 v[200:203], v81, s[36:37] offset:2048
	global_load_dwordx4 v[204:207], v81, s[36:37] offset:2064
	s_add_u32 s24, s16, 0xb000000
	s_addc_u32 s25, s17, 0
	s_add_u32 s26, s16, 0xb400000
	s_addc_u32 s27, s17, 0
	s_add_u32 s28, s16, 0xb800000
	s_addc_u32 s29, s17, 0
	s_add_u32 s30, s16, 0xbc00000
	s_addc_u32 s31, s17, 0
	global_load_dwordx4 v[128:131], v82, s[24:25] offset:0
	global_load_dwordx4 v[132:135], v82, s[24:25] offset:1024
	global_load_dwordx4 v[136:139], v82, s[26:27] offset:0
	global_load_dwordx4 v[140:143], v82, s[26:27] offset:1024
	global_load_dwordx4 v[144:147], v82, s[28:29] offset:0
	global_load_dwordx4 v[148:151], v82, s[28:29] offset:1024
	global_load_dwordx4 v[152:155], v82, s[30:31] offset:0
	global_load_dwordx4 v[156:159], v82, s[30:31] offset:1024
	s_waitcnt vmcnt(32)
	v_lshlrev_b32_e32 v0, 16, v96
	v_and_b32_e32 v1, 0xffff0000, v96
	v_lshlrev_b32_e32 v2, 16, v97
	v_and_b32_e32 v3, 0xffff0000, v97
	v_lshlrev_b32_e32 v4, 16, v98
	v_and_b32_e32 v5, 0xffff0000, v98
	v_lshlrev_b32_e32 v6, 16, v99
	v_and_b32_e32 v7, 0xffff0000, v99
	v_lshlrev_b32_e32 v8, 16, v100
	v_and_b32_e32 v9, 0xffff0000, v100
	v_lshlrev_b32_e32 v10, 16, v101
	v_and_b32_e32 v11, 0xffff0000, v101
	v_lshlrev_b32_e32 v12, 16, v102
	v_and_b32_e32 v13, 0xffff0000, v102
	v_lshlrev_b32_e32 v14, 16, v103
	v_and_b32_e32 v15, 0xffff0000, v103
	v_lshlrev_b32_e32 v16, 16, v104
	v_and_b32_e32 v17, 0xffff0000, v104
	v_lshlrev_b32_e32 v18, 16, v105
	v_and_b32_e32 v19, 0xffff0000, v105
	v_lshlrev_b32_e32 v20, 16, v106
	v_and_b32_e32 v21, 0xffff0000, v106
	v_lshlrev_b32_e32 v22, 16, v107
	v_and_b32_e32 v23, 0xffff0000, v107
	v_lshlrev_b32_e32 v24, 16, v108
	v_and_b32_e32 v25, 0xffff0000, v108
	v_lshlrev_b32_e32 v26, 16, v109
	v_and_b32_e32 v27, 0xffff0000, v109
	v_lshlrev_b32_e32 v28, 16, v110
	v_and_b32_e32 v29, 0xffff0000, v110
	v_lshlrev_b32_e32 v30, 16, v111
	v_and_b32_e32 v31, 0xffff0000, v111
	v_lshlrev_b32_e32 v32, 16, v112
	v_and_b32_e32 v33, 0xffff0000, v112
	v_lshlrev_b32_e32 v34, 16, v113
	v_and_b32_e32 v35, 0xffff0000, v113
	v_lshlrev_b32_e32 v36, 16, v114
	v_and_b32_e32 v37, 0xffff0000, v114
	v_lshlrev_b32_e32 v38, 16, v115
	v_and_b32_e32 v39, 0xffff0000, v115
	v_lshlrev_b32_e32 v40, 16, v116
	v_and_b32_e32 v41, 0xffff0000, v116
	v_lshlrev_b32_e32 v42, 16, v117
	v_and_b32_e32 v43, 0xffff0000, v117
	v_lshlrev_b32_e32 v44, 16, v118
	v_and_b32_e32 v45, 0xffff0000, v118
	v_lshlrev_b32_e32 v46, 16, v119
	v_and_b32_e32 v47, 0xffff0000, v119
	v_lshlrev_b32_e32 v48, 16, v120
	v_and_b32_e32 v49, 0xffff0000, v120
	v_lshlrev_b32_e32 v50, 16, v121
	v_and_b32_e32 v51, 0xffff0000, v121
	v_lshlrev_b32_e32 v52, 16, v122
	v_and_b32_e32 v53, 0xffff0000, v122
	v_lshlrev_b32_e32 v54, 16, v123
	v_and_b32_e32 v55, 0xffff0000, v123
	v_lshlrev_b32_e32 v56, 16, v124
	v_and_b32_e32 v57, 0xffff0000, v124
	v_lshlrev_b32_e32 v58, 16, v125
	v_and_b32_e32 v59, 0xffff0000, v125
	v_lshlrev_b32_e32 v60, 16, v126
	v_and_b32_e32 v61, 0xffff0000, v126
	v_lshlrev_b32_e32 v62, 16, v127
	v_and_b32_e32 v63, 0xffff0000, v127
	v_pk_mul_f32 v[240:241], v[0:1], v[0:1]
	v_pk_mul_f32 v[242:243], v[16:17], v[16:17]
	v_pk_mul_f32 v[244:245], v[32:33], v[32:33]
	v_pk_mul_f32 v[246:247], v[48:49], v[48:49]
	v_pk_fma_f32 v[240:241], v[2:3], v[2:3], v[240:241]
	v_pk_fma_f32 v[242:243], v[18:19], v[18:19], v[242:243]
	v_pk_fma_f32 v[244:245], v[34:35], v[34:35], v[244:245]
	v_pk_fma_f32 v[246:247], v[50:51], v[50:51], v[246:247]
	v_pk_fma_f32 v[240:241], v[4:5], v[4:5], v[240:241]
	v_pk_fma_f32 v[242:243], v[20:21], v[20:21], v[242:243]
	v_pk_fma_f32 v[244:245], v[36:37], v[36:37], v[244:245]
	v_pk_fma_f32 v[246:247], v[52:53], v[52:53], v[246:247]
	v_pk_fma_f32 v[240:241], v[6:7], v[6:7], v[240:241]
	v_pk_fma_f32 v[242:243], v[22:23], v[22:23], v[242:243]
	v_pk_fma_f32 v[244:245], v[38:39], v[38:39], v[244:245]
	v_pk_fma_f32 v[246:247], v[54:55], v[54:55], v[246:247]
	v_pk_fma_f32 v[240:241], v[8:9], v[8:9], v[240:241]
	v_pk_fma_f32 v[242:243], v[24:25], v[24:25], v[242:243]
	v_pk_fma_f32 v[244:245], v[40:41], v[40:41], v[244:245]
	v_pk_fma_f32 v[246:247], v[56:57], v[56:57], v[246:247]
	v_pk_fma_f32 v[240:241], v[10:11], v[10:11], v[240:241]
	v_pk_fma_f32 v[242:243], v[26:27], v[26:27], v[242:243]
	v_pk_fma_f32 v[244:245], v[42:43], v[42:43], v[244:245]
	v_pk_fma_f32 v[246:247], v[58:59], v[58:59], v[246:247]
	v_pk_fma_f32 v[240:241], v[12:13], v[12:13], v[240:241]
	v_pk_fma_f32 v[242:243], v[28:29], v[28:29], v[242:243]
	v_pk_fma_f32 v[244:245], v[44:45], v[44:45], v[244:245]
	v_pk_fma_f32 v[246:247], v[60:61], v[60:61], v[246:247]
	v_pk_fma_f32 v[240:241], v[14:15], v[14:15], v[240:241]
	v_pk_fma_f32 v[242:243], v[30:31], v[30:31], v[242:243]
	v_pk_fma_f32 v[244:245], v[46:47], v[46:47], v[244:245]
	v_pk_fma_f32 v[246:247], v[62:63], v[62:63], v[246:247]
	v_add_f32_e32 v224, v240, v241
	v_add_f32_e32 v225, v242, v243
	v_add_f32_e32 v226, v244, v245
	v_add_f32_e32 v227, v246, v247
	ds_bpermute_b32 v228, v83, v224
	ds_bpermute_b32 v229, v83, v225
	ds_bpermute_b32 v230, v83, v226
	ds_bpermute_b32 v231, v83, v227
	s_waitcnt lgkmcnt(0)
	v_add_f32_e32 v224, v224, v228
	v_add_f32_e32 v225, v225, v229
	v_add_f32_e32 v226, v226, v230
	v_add_f32_e32 v227, v227, v231
	ds_bpermute_b32 v228, v84, v224
	ds_bpermute_b32 v229, v84, v225
	ds_bpermute_b32 v230, v84, v226
	ds_bpermute_b32 v231, v84, v227
	s_waitcnt lgkmcnt(0)
	v_add_f32_e32 v224, v224, v228
	v_add_f32_e32 v225, v225, v229
	v_add_f32_e32 v226, v226, v230
	v_add_f32_e32 v227, v227, v231
	ds_bpermute_b32 v228, v85, v224
	ds_bpermute_b32 v229, v85, v225
	ds_bpermute_b32 v230, v85, v226
	ds_bpermute_b32 v231, v85, v227
	s_waitcnt lgkmcnt(0)
	v_add_f32_e32 v224, v224, v228
	v_add_f32_e32 v225, v225, v229
	v_add_f32_e32 v226, v226, v230
	v_add_f32_e32 v227, v227, v231
	ds_bpermute_b32 v228, v86, v224
	ds_bpermute_b32 v229, v86, v225
	ds_bpermute_b32 v230, v86, v226
	ds_bpermute_b32 v231, v86, v227
	s_waitcnt lgkmcnt(0)
	v_add_f32_e32 v224, v224, v228
	v_add_f32_e32 v225, v225, v229
	v_add_f32_e32 v226, v226, v230
	v_add_f32_e32 v227, v227, v231
	ds_bpermute_b32 v228, v87, v224
	ds_bpermute_b32 v229, v87, v225
	ds_bpermute_b32 v230, v87, v226
	ds_bpermute_b32 v231, v87, v227
	s_waitcnt lgkmcnt(0)
	v_add_f32_e32 v224, v224, v228
	v_add_f32_e32 v225, v225, v229
	v_add_f32_e32 v226, v226, v230
	v_add_f32_e32 v227, v227, v231
	ds_bpermute_b32 v228, v88, v224
	ds_bpermute_b32 v229, v88, v225
	ds_bpermute_b32 v230, v88, v226
	ds_bpermute_b32 v231, v88, v227
	s_waitcnt lgkmcnt(0)
	v_add_f32_e32 v224, v224, v228
	v_add_f32_e32 v225, v225, v229
	v_add_f32_e32 v226, v226, v230
	v_add_f32_e32 v227, v227, v231
	v_fmamk_f32 v240, v224, 0x3a800000, v89
	v_mul_f32_e32 v241, 0x4f800000, v240
	v_cmp_gt_f32_e32 vcc, s54, v240
	s_nop 1
	v_cndmask_b32_e32 v247, v240, v241, vcc
	v_sqrt_f32_e32 v242, v247
	s_nop 1
	v_add_u32_e32 v243, -1, v242
	v_add_u32_e32 v244, 1, v242
	v_fma_f32 v245, -v243, v242, v247
	v_fma_f32 v246, -v244, v242, v247
	v_cmp_ge_f32_e64 s[52:53], 0, v245
	s_nop 1
	v_cndmask_b32_e64 v242, v242, v243, s[52:53]
	v_cmp_lt_f32_e64 s[52:53], 0, v246
	s_nop 1
	v_cndmask_b32_e64 v242, v242, v244, s[52:53]
	v_mul_f32_e32 v243, 0x37800000, v242
	v_cndmask_b32_e32 v242, v242, v243, vcc
	v_cmp_class_f32_e32 vcc, v247, v90
	s_nop 1
	v_cndmask_b32_e32 v247, v242, v247, vcc
	v_div_scale_f32 v248, s[52:53], v247, v247, 1.0
	v_rcp_f32_e32 v249, v248
	v_div_scale_f32 v228, vcc, 1.0, v247, 1.0
	s_nop 0
	v_fma_f32 v229, -v248, v249, 1.0
	v_fmac_f32_e32 v249, v229, v249
	v_mul_f32_e32 v230, v228, v249
	v_fma_f32 v229, -v248, v230, v228
	v_fmac_f32_e32 v230, v229, v249
	v_fma_f32 v248, -v248, v230, v228
	v_div_fmas_f32 v248, v248, v249, v230
	v_div_fixup_f32 v232, v248, v247, 1.0
	v_fmamk_f32 v240, v225, 0x3a800000, v89
	v_mul_f32_e32 v241, 0x4f800000, v240
	v_cmp_gt_f32_e32 vcc, s54, v240
	s_nop 1
	v_cndmask_b32_e32 v247, v240, v241, vcc
	v_sqrt_f32_e32 v242, v247
	s_nop 1
	v_add_u32_e32 v243, -1, v242
	v_add_u32_e32 v244, 1, v242
	v_fma_f32 v245, -v243, v242, v247
	v_fma_f32 v246, -v244, v242, v247
	v_cmp_ge_f32_e64 s[52:53], 0, v245
	s_nop 1
	v_cndmask_b32_e64 v242, v242, v243, s[52:53]
	v_cmp_lt_f32_e64 s[52:53], 0, v246
	s_nop 1
	v_cndmask_b32_e64 v242, v242, v244, s[52:53]
; __device__ __forceinline__ unsigned pk2(float lo, float hi) { return pg8::cvt_pk_bf16(lo, hi); }
; template <bool BF> __device__ __forceinline__ void prep_rows(const float* xp, const float* xs, const bf16* hb, const float* g, const float* MOD, int shoff, int scoff, bf16* U, int gw, int NGW, int lane) {
;     ...
;         for (int r = 0; r < R; ++r) { const int m = mb + r * NGW; if (m < MT) {
;             const float rstd = 1.0f / sqrtf(s[r] * (1.0f / DM) + RMS_EPS);
;             const float* mr = MOD + (size_t)(m < MP ? (m >> 13) : 8 + ((m - MP) >> 12)) * 6144;
; #pragma unroll
;             for (int j = 0; j < 4; ++j) { const int c = 4 * lane + 256 * j;
;                 const f32x4 gg = *(const f32x4*)(g + c), sc = *(const f32x4*)(mr + scoff + c), sh = *(const f32x4*)(mr + shoff + c);
;                 const f32x4 o = v[r][j] * rstd * gg * (sc + 1.0f) + sh; v2u w; w.x = pk2(o.x, o.y); w.y = pk2(o.z, o.w); *(v2u*)(U + (size_t)m * DM + c) = w; } } }
	v_mul_f32_e32 v243, 0x37800000, v242
	v_cndmask_b32_e32 v242, v242, v243, vcc
	v_cmp_class_f32_e32 vcc, v247, v90
	s_nop 1
	v_cndmask_b32_e32 v247, v242, v247, vcc
	v_div_scale_f32 v248, s[52:53], v247, v247, 1.0
	v_rcp_f32_e32 v249, v248
	v_div_scale_f32 v228, vcc, 1.0, v247, 1.0
	s_nop 0
	v_fma_f32 v229, -v248, v249, 1.0
	v_fmac_f32_e32 v249, v229, v249
	v_mul_f32_e32 v230, v228, v249
	v_fma_f32 v229, -v248, v230, v228
	v_fmac_f32_e32 v230, v229, v249
	v_fma_f32 v248, -v248, v230, v228
	v_div_fmas_f32 v248, v248, v249, v230
	v_div_fixup_f32 v234, v248, v247, 1.0
	v_fmamk_f32 v240, v226, 0x3a800000, v89
	v_mul_f32_e32 v241, 0x4f800000, v240
	v_cmp_gt_f32_e32 vcc, s54, v240
	s_nop 1
	v_cndmask_b32_e32 v247, v240, v241, vcc
	v_sqrt_f32_e32 v242, v247
	s_nop 1
	v_add_u32_e32 v243, -1, v242
	v_add_u32_e32 v244, 1, v242
	v_fma_f32 v245, -v243, v242, v247
	v_fma_f32 v246, -v244, v242, v247
	v_cmp_ge_f32_e64 s[52:53], 0, v245
	s_nop 1
	v_cndmask_b32_e64 v242, v242, v243, s[52:53]
	v_cmp_lt_f32_e64 s[52:53], 0, v246
	s_nop 1
	v_cndmask_b32_e64 v242, v242, v244, s[52:53]
	v_mul_f32_e32 v243, 0x37800000, v242
	v_cndmask_b32_e32 v242, v242, v243, vcc
	v_cmp_class_f32_e32 vcc, v247, v90
	s_nop 1
	v_cndmask_b32_e32 v247, v242, v247, vcc
	v_div_scale_f32 v248, s[52:53], v247, v247, 1.0
	v_rcp_f32_e32 v249, v248
	v_div_scale_f32 v228, vcc, 1.0, v247, 1.0
	s_nop 0
	v_fma_f32 v229, -v248, v249, 1.0
	v_fmac_f32_e32 v249, v229, v249
	v_mul_f32_e32 v230, v228, v249
	v_fma_f32 v229, -v248, v230, v228
	v_fmac_f32_e32 v230, v229, v249
	v_fma_f32 v248, -v248, v230, v228
	v_div_fmas_f32 v248, v248, v249, v230
	v_div_fixup_f32 v236, v248, v247, 1.0
	v_fmamk_f32 v240, v227, 0x3a800000, v89
	v_mul_f32_e32 v241, 0x4f800000, v240
	v_cmp_gt_f32_e32 vcc, s54, v240
	s_nop 1
	v_cndmask_b32_e32 v247, v240, v241, vcc
	v_sqrt_f32_e32 v242, v247
	s_nop 1
	v_add_u32_e32 v243, -1, v242
	v_add_u32_e32 v244, 1, v242
	v_fma_f32 v245, -v243, v242, v247
	v_fma_f32 v246, -v244, v242, v247
	v_cmp_ge_f32_e64 s[52:53], 0, v245
	s_nop 1
	v_cndmask_b32_e64 v242, v242, v243, s[52:53]
	v_cmp_lt_f32_e64 s[52:53], 0, v246
	s_nop 1
	v_cndmask_b32_e64 v242, v242, v244, s[52:53]
	v_mul_f32_e32 v243, 0x37800000, v242
	v_cndmask_b32_e32 v242, v242, v243, vcc
	v_cmp_class_f32_e32 vcc, v247, v90
	s_nop 1
	v_cndmask_b32_e32 v247, v242, v247, vcc
	v_div_scale_f32 v248, s[52:53], v247, v247, 1.0
	v_rcp_f32_e32 v249, v248
	v_div_scale_f32 v228, vcc, 1.0, v247, 1.0
	s_nop 0
	v_fma_f32 v229, -v248, v249, 1.0
	v_fmac_f32_e32 v249, v229, v249
	v_mul_f32_e32 v230, v228, v249
	v_fma_f32 v229, -v248, v230, v228
	v_fmac_f32_e32 v230, v229, v249
	v_fma_f32 v248, -v248, v230, v228
	v_div_fmas_f32 v248, v248, v249, v230
	v_div_fixup_f32 v238, v248, v247, 1.0
	s_waitcnt vmcnt(8)
	v_pk_add_f32 v[160:161], v[160:161], 1.0 op_sel_hi:[1,0]
	v_pk_add_f32 v[162:163], v[162:163], 1.0 op_sel_hi:[1,0]
	v_pk_add_f32 v[164:165], v[164:165], 1.0 op_sel_hi:[1,0]
	v_pk_add_f32 v[166:167], v[166:167], 1.0 op_sel_hi:[1,0]
	v_pk_add_f32 v[168:169], v[168:169], 1.0 op_sel_hi:[1,0]
	v_pk_add_f32 v[170:171], v[170:171], 1.0 op_sel_hi:[1,0]
	v_pk_add_f32 v[172:173], v[172:173], 1.0 op_sel_hi:[1,0]
	v_pk_add_f32 v[174:175], v[174:175], 1.0 op_sel_hi:[1,0]
	v_pk_add_f32 v[192:193], v[192:193], 1.0 op_sel_hi:[1,0]
	v_pk_add_f32 v[194:195], v[194:195], 1.0 op_sel_hi:[1,0]
	v_pk_add_f32 v[196:197], v[196:197], 1.0 op_sel_hi:[1,0]
	v_pk_add_f32 v[198:199], v[198:199], 1.0 op_sel_hi:[1,0]
	v_pk_add_f32 v[200:201], v[200:201], 1.0 op_sel_hi:[1,0]
	v_pk_add_f32 v[202:203], v[202:203], 1.0 op_sel_hi:[1,0]
	v_pk_add_f32 v[204:205], v[204:205], 1.0 op_sel_hi:[1,0]
	v_pk_add_f32 v[206:207], v[206:207], 1.0 op_sel_hi:[1,0]
	s_add_u32 s38, s20, 0xa000000
	s_addc_u32 s39, s21, 0
	s_add_u32 s40, s20, 0xa400000
	s_addc_u32 s41, s21, 0
	s_add_u32 s46, s20, 0xa800000
	s_addc_u32 s47, s21, 0
	s_add_u32 s48, s20, 0xac00000
	s_addc_u32 s49, s21, 0
	v_pk_mul_f32 v[0:1], v[0:1], v[232:233] op_sel_hi:[1,0]
	v_pk_mul_f32 v[2:3], v[2:3], v[232:233] op_sel_hi:[1,0]
	v_pk_mul_f32 v[0:1], v[64:65], v[0:1]
	v_pk_mul_f32 v[2:3], v[66:67], v[2:3]
	v_pk_fma_f32 v[0:1], v[160:161], v[0:1], v[176:177]
	v_pk_fma_f32 v[2:3], v[162:163], v[2:3], v[178:179]
	v_cvt_pk_bf16_f32 v244, v0, v1
	v_cvt_pk_bf16_f32 v245, v2, v3
	v_pk_mul_f32 v[4:5], v[4:5], v[232:233] op_sel_hi:[1,0]
	v_pk_mul_f32 v[6:7], v[6:7], v[232:233] op_sel_hi:[1,0]
	v_pk_mul_f32 v[4:5], v[68:69], v[4:5]
	v_pk_mul_f32 v[6:7], v[70:71], v[6:7]
	v_pk_fma_f32 v[4:5], v[164:165], v[4:5], v[180:181]
	v_pk_fma_f32 v[6:7], v[166:167], v[6:7], v[182:183]
	v_cvt_pk_bf16_f32 v246, v4, v5
	v_cvt_pk_bf16_f32 v247, v6, v7
	global_store_dwordx4 v82, v[244:247], s[38:39] offset:0
	v_pk_mul_f32 v[8:9], v[8:9], v[232:233] op_sel_hi:[1,0]
	v_pk_mul_f32 v[10:11], v[10:11], v[232:233] op_sel_hi:[1,0]
	v_pk_mul_f32 v[8:9], v[72:73], v[8:9]
	v_pk_mul_f32 v[10:11], v[74:75], v[10:11]
	v_pk_fma_f32 v[8:9], v[168:169], v[8:9], v[184:185]
	v_pk_fma_f32 v[10:11], v[170:171], v[10:11], v[186:187]
	v_cvt_pk_bf16_f32 v240, v8, v9
	v_cvt_pk_bf16_f32 v241, v10, v11
	v_pk_mul_f32 v[12:13], v[12:13], v[232:233] op_sel_hi:[1,0]
	v_pk_mul_f32 v[14:15], v[14:15], v[232:233] op_sel_hi:[1,0]
	v_pk_mul_f32 v[12:13], v[76:77], v[12:13]
	v_pk_mul_f32 v[14:15], v[78:79], v[14:15]
	v_pk_fma_f32 v[12:13], v[172:173], v[12:13], v[188:189]
	v_pk_fma_f32 v[14:15], v[174:175], v[14:15], v[190:191]
	v_cvt_pk_bf16_f32 v242, v12, v13
	v_cvt_pk_bf16_f32 v243, v14, v15
	global_store_dwordx4 v82, v[240:243], s[38:39] offset:1024
	v_pk_mul_f32 v[16:17], v[16:17], v[234:235] op_sel_hi:[1,0]
	v_pk_mul_f32 v[18:19], v[18:19], v[234:235] op_sel_hi:[1,0]
; __device__ __forceinline__ unsigned pk2(float lo, float hi) { return pg8::cvt_pk_bf16(lo, hi); }
; template <bool BF> __device__ __forceinline__ void prep_rows(const float* xp, const float* xs, const bf16* hb, const float* g, const float* MOD, int shoff, int scoff, bf16* U, int gw, int NGW, int lane) {
;     ...
;             const float* mr = MOD + (size_t)(m < MP ? (m >> 13) : 8 + ((m - MP) >> 12)) * 6144;
; #pragma unroll
;             for (int j = 0; j < 4; ++j) { const int c = 4 * lane + 256 * j;
;                 const f32x4 gg = *(const f32x4*)(g + c), sc = *(const f32x4*)(mr + scoff + c), sh = *(const f32x4*)(mr + shoff + c);
;                 const f32x4 o = v[r][j] * rstd * gg * (sc + 1.0f) + sh; v2u w; w.x = pk2(o.x, o.y); w.y = pk2(o.z, o.w); *(v2u*)(U + (size_t)m * DM + c) = w; } } }
	v_pk_mul_f32 v[16:17], v[64:65], v[16:17]
	v_pk_mul_f32 v[18:19], v[66:67], v[18:19]
	v_pk_fma_f32 v[16:17], v[160:161], v[16:17], v[176:177]
	v_pk_fma_f32 v[18:19], v[162:163], v[18:19], v[178:179]
	v_cvt_pk_bf16_f32 v244, v16, v17
	v_cvt_pk_bf16_f32 v245, v18, v19
	v_pk_mul_f32 v[20:21], v[20:21], v[234:235] op_sel_hi:[1,0]
	v_pk_mul_f32 v[22:23], v[22:23], v[234:235] op_sel_hi:[1,0]
	v_pk_mul_f32 v[20:21], v[68:69], v[20:21]
	v_pk_mul_f32 v[22:23], v[70:71], v[22:23]
	v_pk_fma_f32 v[20:21], v[164:165], v[20:21], v[180:181]
	v_pk_fma_f32 v[22:23], v[166:167], v[22:23], v[182:183]
	v_cvt_pk_bf16_f32 v246, v20, v21
	v_cvt_pk_bf16_f32 v247, v22, v23
	global_store_dwordx4 v82, v[244:247], s[40:41] offset:0
	v_pk_mul_f32 v[24:25], v[24:25], v[234:235] op_sel_hi:[1,0]
	v_pk_mul_f32 v[26:27], v[26:27], v[234:235] op_sel_hi:[1,0]
	v_pk_mul_f32 v[24:25], v[72:73], v[24:25]
	v_pk_mul_f32 v[26:27], v[74:75], v[26:27]
	v_pk_fma_f32 v[24:25], v[168:169], v[24:25], v[184:185]
	v_pk_fma_f32 v[26:27], v[170:171], v[26:27], v[186:187]
	v_cvt_pk_bf16_f32 v240, v24, v25
	v_cvt_pk_bf16_f32 v241, v26, v27
	v_pk_mul_f32 v[28:29], v[28:29], v[234:235] op_sel_hi:[1,0]
	v_pk_mul_f32 v[30:31], v[30:31], v[234:235] op_sel_hi:[1,0]
	v_pk_mul_f32 v[28:29], v[76:77], v[28:29]
	v_pk_mul_f32 v[30:31], v[78:79], v[30:31]
	v_pk_fma_f32 v[28:29], v[172:173], v[28:29], v[188:189]
	v_pk_fma_f32 v[30:31], v[174:175], v[30:31], v[190:191]
	v_cvt_pk_bf16_f32 v242, v28, v29
	v_cvt_pk_bf16_f32 v243, v30, v31
	global_store_dwordx4 v82, v[240:243], s[40:41] offset:1024
	v_pk_mul_f32 v[32:33], v[32:33], v[236:237] op_sel_hi:[1,0]
	v_pk_mul_f32 v[34:35], v[34:35], v[236:237] op_sel_hi:[1,0]
	v_pk_mul_f32 v[32:33], v[64:65], v[32:33]
	v_pk_mul_f32 v[34:35], v[66:67], v[34:35]
	v_pk_fma_f32 v[32:33], v[192:193], v[32:33], v[208:209]
	v_pk_fma_f32 v[34:35], v[194:195], v[34:35], v[210:211]
	v_cvt_pk_bf16_f32 v244, v32, v33
	v_cvt_pk_bf16_f32 v245, v34, v35
	v_pk_mul_f32 v[36:37], v[36:37], v[236:237] op_sel_hi:[1,0]
	v_pk_mul_f32 v[38:39], v[38:39], v[236:237] op_sel_hi:[1,0]
	v_pk_mul_f32 v[36:37], v[68:69], v[36:37]
	v_pk_mul_f32 v[38:39], v[70:71], v[38:39]
	v_pk_fma_f32 v[36:37], v[196:197], v[36:37], v[212:213]
	v_pk_fma_f32 v[38:39], v[198:199], v[38:39], v[214:215]
	v_cvt_pk_bf16_f32 v246, v36, v37
	v_cvt_pk_bf16_f32 v247, v38, v39
	global_store_dwordx4 v82, v[244:247], s[46:47] offset:0
	v_pk_mul_f32 v[40:41], v[40:41], v[236:237] op_sel_hi:[1,0]
	v_pk_mul_f32 v[42:43], v[42:43], v[236:237] op_sel_hi:[1,0]
	v_pk_mul_f32 v[40:41], v[72:73], v[40:41]
	v_pk_mul_f32 v[42:43], v[74:75], v[42:43]
	v_pk_fma_f32 v[40:41], v[200:201], v[40:41], v[216:217]
	v_pk_fma_f32 v[42:43], v[202:203], v[42:43], v[218:219]
	v_cvt_pk_bf16_f32 v240, v40, v41
	v_cvt_pk_bf16_f32 v241, v42, v43
	v_pk_mul_f32 v[44:45], v[44:45], v[236:237] op_sel_hi:[1,0]
	v_pk_mul_f32 v[46:47], v[46:47], v[236:237] op_sel_hi:[1,0]
	v_pk_mul_f32 v[44:45], v[76:77], v[44:45]
	v_pk_mul_f32 v[46:47], v[78:79], v[46:47]
	v_pk_fma_f32 v[44:45], v[204:205], v[44:45], v[220:221]
	v_pk_fma_f32 v[46:47], v[206:207], v[46:47], v[222:223]
	v_cvt_pk_bf16_f32 v242, v44, v45
	v_cvt_pk_bf16_f32 v243, v46, v47
	global_store_dwordx4 v82, v[240:243], s[46:47] offset:1024
	v_pk_mul_f32 v[48:49], v[48:49], v[238:239] op_sel_hi:[1,0]
	v_pk_mul_f32 v[50:51], v[50:51], v[238:239] op_sel_hi:[1,0]
	v_pk_mul_f32 v[48:49], v[64:65], v[48:49]
	v_pk_mul_f32 v[50:51], v[66:67], v[50:51]
	v_pk_fma_f32 v[48:49], v[192:193], v[48:49], v[208:209]
	v_pk_fma_f32 v[50:51], v[194:195], v[50:51], v[210:211]
	v_cvt_pk_bf16_f32 v244, v48, v49
	v_cvt_pk_bf16_f32 v245, v50, v51
	v_pk_mul_f32 v[52:53], v[52:53], v[238:239] op_sel_hi:[1,0]
	v_pk_mul_f32 v[54:55], v[54:55], v[238:239] op_sel_hi:[1,0]
	v_pk_mul_f32 v[52:53], v[68:69], v[52:53]
	v_pk_mul_f32 v[54:55], v[70:71], v[54:55]
	v_pk_fma_f32 v[52:53], v[196:197], v[52:53], v[212:213]
	v_pk_fma_f32 v[54:55], v[198:199], v[54:55], v[214:215]
	v_cvt_pk_bf16_f32 v246, v52, v53
	v_cvt_pk_bf16_f32 v247, v54, v55
	global_store_dwordx4 v82, v[244:247], s[48:49] offset:0
	v_pk_mul_f32 v[56:57], v[56:57], v[238:239] op_sel_hi:[1,0]
	v_pk_mul_f32 v[58:59], v[58:59], v[238:239] op_sel_hi:[1,0]
	v_pk_mul_f32 v[56:57], v[72:73], v[56:57]
	v_pk_mul_f32 v[58:59], v[74:75], v[58:59]
	v_pk_fma_f32 v[56:57], v[200:201], v[56:57], v[216:217]
	v_pk_fma_f32 v[58:59], v[202:203], v[58:59], v[218:219]
	v_cvt_pk_bf16_f32 v240, v56, v57
	v_cvt_pk_bf16_f32 v241, v58, v59
	v_pk_mul_f32 v[60:61], v[60:61], v[238:239] op_sel_hi:[1,0]
	v_pk_mul_f32 v[62:63], v[62:63], v[238:239] op_sel_hi:[1,0]
	v_pk_mul_f32 v[60:61], v[76:77], v[60:61]
	v_pk_mul_f32 v[62:63], v[78:79], v[62:63]
	v_pk_fma_f32 v[60:61], v[204:205], v[60:61], v[220:221]
	v_pk_fma_f32 v[62:63], v[206:207], v[62:63], v[222:223]
	v_cvt_pk_bf16_f32 v242, v60, v61
	v_cvt_pk_bf16_f32 v243, v62, v63
	global_store_dwordx4 v82, v[240:243], s[48:49] offset:1024
	s_add_u32 s34, s8, 0x57000
	s_addc_u32 s35, s9, 0
	s_add_u32 s36, s8, 0x5d000
	s_addc_u32 s37, s9, 0
	global_load_dwordx4 v[176:179], v80, s[34:35] offset:0
	global_load_dwordx4 v[180:183], v80, s[34:35] offset:16
	global_load_dwordx4 v[184:187], v80, s[34:35] offset:2048
	global_load_dwordx4 v[188:191], v80, s[34:35] offset:2064
	global_load_dwordx4 v[160:163], v81, s[34:35] offset:0
	global_load_dwordx4 v[164:167], v81, s[34:35] offset:16
	global_load_dwordx4 v[168:171], v81, s[34:35] offset:2048
	global_load_dwordx4 v[172:175], v81, s[34:35] offset:2064
	global_load_dwordx4 v[208:211], v80, s[36:37] offset:0
	global_load_dwordx4 v[212:215], v80, s[36:37] offset:16
	global_load_dwordx4 v[216:219], v80, s[36:37] offset:2048
	global_load_dwordx4 v[220:223], v80, s[36:37] offset:2064
	global_load_dwordx4 v[192:195], v81, s[36:37] offset:0
	global_load_dwordx4 v[196:199], v81, s[36:37] offset:16
	global_load_dwordx4 v[200:203], v81, s[36:37] offset:2048
	global_load_dwordx4 v[204:207], v81, s[36:37] offset:2064
	s_waitcnt vmcnt(24)
; __device__ __forceinline__ float bf_lo(unsigned w) { return __uint_as_float(w << 16); }
; __device__ __forceinline__ float bf_hi(unsigned w) { return __uint_as_float(w & 0xffff0000u); }
; template <bool BF> __device__ __forceinline__ void prep_rows(const float* xp, const float* xs, const bf16* hb, const float* g, const float* MOD, int shoff, int scoff, bf16* U, int gw, int NGW, int lane) {
;     ...
;                 if (BF) { const v2u a0 = *(const v2u*)(hb + (size_t)mc * DM + 4 * lane + 256 * j);
;                     v[r][j].x = pg8::bf_lo(a0.x); v[r][j].y = pg8::bf_hi(a0.x); v[r][j].z = pg8::bf_lo(a0.y); v[r][j].w = pg8::bf_hi(a0.y); }
;                 else { const float* xr = mc < MP ? xp + (size_t)mc * DM : xs + (size_t)(mc - MP) * DM; v[r][j] = *(const f32x4*)(xr + 4 * lane + 256 * j); } } }
; #pragma unroll
;         for (int r = 0; r < R; ++r) { float t = 0.f;
; #pragma unroll
;             for (int j = 0; j < 4; ++j) t += (v[r][j].x * v[r][j].x + v[r][j].y * v[r][j].y) + (v[r][j].z * v[r][j].z + v[r][j].w * v[r][j].w);
;             s[r] = t; }
; #pragma unroll
;         for (int o = 1; o < 64; o <<= 1) {
; #pragma unroll
;             for (int r = 0; r < R; ++r) s[r] += __shfl_xor(s[r], o); }
	v_lshlrev_b32_e32 v0, 16, v128
	v_and_b32_e32 v1, 0xffff0000, v128
	v_lshlrev_b32_e32 v2, 16, v129
	v_and_b32_e32 v3, 0xffff0000, v129
	v_lshlrev_b32_e32 v4, 16, v130
	v_and_b32_e32 v5, 0xffff0000, v130
	v_lshlrev_b32_e32 v6, 16, v131
	v_and_b32_e32 v7, 0xffff0000, v131
	v_lshlrev_b32_e32 v8, 16, v132
	v_and_b32_e32 v9, 0xffff0000, v132
	v_lshlrev_b32_e32 v10, 16, v133
	v_and_b32_e32 v11, 0xffff0000, v133
	v_lshlrev_b32_e32 v12, 16, v134
	v_and_b32_e32 v13, 0xffff0000, v134
	v_lshlrev_b32_e32 v14, 16, v135
	v_and_b32_e32 v15, 0xffff0000, v135
	v_lshlrev_b32_e32 v16, 16, v136
	v_and_b32_e32 v17, 0xffff0000, v136
	v_lshlrev_b32_e32 v18, 16, v137
	v_and_b32_e32 v19, 0xffff0000, v137
	v_lshlrev_b32_e32 v20, 16, v138
	v_and_b32_e32 v21, 0xffff0000, v138
	v_lshlrev_b32_e32 v22, 16, v139
	v_and_b32_e32 v23, 0xffff0000, v139
	v_lshlrev_b32_e32 v24, 16, v140
	v_and_b32_e32 v25, 0xffff0000, v140
	v_lshlrev_b32_e32 v26, 16, v141
	v_and_b32_e32 v27, 0xffff0000, v141
	v_lshlrev_b32_e32 v28, 16, v142
	v_and_b32_e32 v29, 0xffff0000, v142
	v_lshlrev_b32_e32 v30, 16, v143
	v_and_b32_e32 v31, 0xffff0000, v143
	v_lshlrev_b32_e32 v32, 16, v144
	v_and_b32_e32 v33, 0xffff0000, v144
	v_lshlrev_b32_e32 v34, 16, v145
	v_and_b32_e32 v35, 0xffff0000, v145
	v_lshlrev_b32_e32 v36, 16, v146
	v_and_b32_e32 v37, 0xffff0000, v146
	v_lshlrev_b32_e32 v38, 16, v147
	v_and_b32_e32 v39, 0xffff0000, v147
	v_lshlrev_b32_e32 v40, 16, v148
	v_and_b32_e32 v41, 0xffff0000, v148
	v_lshlrev_b32_e32 v42, 16, v149
	v_and_b32_e32 v43, 0xffff0000, v149
	v_lshlrev_b32_e32 v44, 16, v150
	v_and_b32_e32 v45, 0xffff0000, v150
	v_lshlrev_b32_e32 v46, 16, v151
	v_and_b32_e32 v47, 0xffff0000, v151
	v_lshlrev_b32_e32 v48, 16, v152
	v_and_b32_e32 v49, 0xffff0000, v152
	v_lshlrev_b32_e32 v50, 16, v153
	v_and_b32_e32 v51, 0xffff0000, v153
	v_lshlrev_b32_e32 v52, 16, v154
	v_and_b32_e32 v53, 0xffff0000, v154
	v_lshlrev_b32_e32 v54, 16, v155
	v_and_b32_e32 v55, 0xffff0000, v155
	v_lshlrev_b32_e32 v56, 16, v156
	v_and_b32_e32 v57, 0xffff0000, v156
	v_lshlrev_b32_e32 v58, 16, v157
	v_and_b32_e32 v59, 0xffff0000, v157
	v_lshlrev_b32_e32 v60, 16, v158
	v_and_b32_e32 v61, 0xffff0000, v158
	v_lshlrev_b32_e32 v62, 16, v159
	v_and_b32_e32 v63, 0xffff0000, v159
	v_pk_mul_f32 v[240:241], v[0:1], v[0:1]
	v_pk_mul_f32 v[242:243], v[16:17], v[16:17]
	v_pk_mul_f32 v[244:245], v[32:33], v[32:33]
	v_pk_mul_f32 v[246:247], v[48:49], v[48:49]
	v_pk_fma_f32 v[240:241], v[2:3], v[2:3], v[240:241]
	v_pk_fma_f32 v[242:243], v[18:19], v[18:19], v[242:243]
	v_pk_fma_f32 v[244:245], v[34:35], v[34:35], v[244:245]
	v_pk_fma_f32 v[246:247], v[50:51], v[50:51], v[246:247]
	v_pk_fma_f32 v[240:241], v[4:5], v[4:5], v[240:241]
	v_pk_fma_f32 v[242:243], v[20:21], v[20:21], v[242:243]
	v_pk_fma_f32 v[244:245], v[36:37], v[36:37], v[244:245]
	v_pk_fma_f32 v[246:247], v[52:53], v[52:53], v[246:247]
	v_pk_fma_f32 v[240:241], v[6:7], v[6:7], v[240:241]
	v_pk_fma_f32 v[242:243], v[22:23], v[22:23], v[242:243]
	v_pk_fma_f32 v[244:245], v[38:39], v[38:39], v[244:245]
	v_pk_fma_f32 v[246:247], v[54:55], v[54:55], v[246:247]
	v_pk_fma_f32 v[240:241], v[8:9], v[8:9], v[240:241]
	v_pk_fma_f32 v[242:243], v[24:25], v[24:25], v[242:243]
	v_pk_fma_f32 v[244:245], v[40:41], v[40:41], v[244:245]
	v_pk_fma_f32 v[246:247], v[56:57], v[56:57], v[246:247]
	v_pk_fma_f32 v[240:241], v[10:11], v[10:11], v[240:241]
	v_pk_fma_f32 v[242:243], v[26:27], v[26:27], v[242:243]
	v_pk_fma_f32 v[244:245], v[42:43], v[42:43], v[244:245]
	v_pk_fma_f32 v[246:247], v[58:59], v[58:59], v[246:247]
	v_pk_fma_f32 v[240:241], v[12:13], v[12:13], v[240:241]
	v_pk_fma_f32 v[242:243], v[28:29], v[28:29], v[242:243]
	v_pk_fma_f32 v[244:245], v[44:45], v[44:45], v[244:245]
	v_pk_fma_f32 v[246:247], v[60:61], v[60:61], v[246:247]
	v_pk_fma_f32 v[240:241], v[14:15], v[14:15], v[240:241]
	v_pk_fma_f32 v[242:243], v[30:31], v[30:31], v[242:243]
	v_pk_fma_f32 v[244:245], v[46:47], v[46:47], v[244:245]
	v_pk_fma_f32 v[246:247], v[62:63], v[62:63], v[246:247]
	v_add_f32_e32 v224, v240, v241
	v_add_f32_e32 v225, v242, v243
	v_add_f32_e32 v226, v244, v245
	v_add_f32_e32 v227, v246, v247
	ds_bpermute_b32 v228, v83, v224
	ds_bpermute_b32 v229, v83, v225
	ds_bpermute_b32 v230, v83, v226
	ds_bpermute_b32 v231, v83, v227
	s_waitcnt lgkmcnt(0)
	v_add_f32_e32 v224, v224, v228
	v_add_f32_e32 v225, v225, v229
	v_add_f32_e32 v226, v226, v230
	v_add_f32_e32 v227, v227, v231
	ds_bpermute_b32 v228, v84, v224
	ds_bpermute_b32 v229, v84, v225
	ds_bpermute_b32 v230, v84, v226
	ds_bpermute_b32 v231, v84, v227
	s_waitcnt lgkmcnt(0)
	v_add_f32_e32 v224, v224, v228
	v_add_f32_e32 v225, v225, v229
	v_add_f32_e32 v226, v226, v230
	v_add_f32_e32 v227, v227, v231
	ds_bpermute_b32 v228, v85, v224
	ds_bpermute_b32 v229, v85, v225
	ds_bpermute_b32 v230, v85, v226
	ds_bpermute_b32 v231, v85, v227
	s_waitcnt lgkmcnt(0)
	v_add_f32_e32 v224, v224, v228
	v_add_f32_e32 v225, v225, v229
	v_add_f32_e32 v226, v226, v230
	v_add_f32_e32 v227, v227, v231
	ds_bpermute_b32 v228, v86, v224
	ds_bpermute_b32 v229, v86, v225
	ds_bpermute_b32 v230, v86, v226
	ds_bpermute_b32 v231, v86, v227
	s_waitcnt lgkmcnt(0)
	v_add_f32_e32 v224, v224, v228
	v_add_f32_e32 v225, v225, v229
	v_add_f32_e32 v226, v226, v230
	v_add_f32_e32 v227, v227, v231
	ds_bpermute_b32 v228, v87, v224
	ds_bpermute_b32 v229, v87, v225
	ds_bpermute_b32 v230, v87, v226
	ds_bpermute_b32 v231, v87, v227
	s_waitcnt lgkmcnt(0)
	v_add_f32_e32 v224, v224, v228
	v_add_f32_e32 v225, v225, v229
	v_add_f32_e32 v226, v226, v230
	v_add_f32_e32 v227, v227, v231
	ds_bpermute_b32 v228, v88, v224
	ds_bpermute_b32 v229, v88, v225
	ds_bpermute_b32 v230, v88, v226
	ds_bpermute_b32 v231, v88, v227
	s_waitcnt lgkmcnt(0)
; template <bool BF> __device__ __forceinline__ void prep_rows(const float* xp, const float* xs, const bf16* hb, const float* g, const float* MOD, int shoff, int scoff, bf16* U, int gw, int NGW, int lane) {
;     ...
;             for (int r = 0; r < R; ++r) s[r] += __shfl_xor(s[r], o); }
; #pragma unroll
;         for (int r = 0; r < R; ++r) { const int m = mb + r * NGW; if (m < MT) {
;             const float rstd = 1.0f / sqrtf(s[r] * (1.0f / DM) + RMS_EPS);
	v_add_f32_e32 v224, v224, v228
	v_add_f32_e32 v225, v225, v229
	v_add_f32_e32 v226, v226, v230
	v_add_f32_e32 v227, v227, v231
	v_fmamk_f32 v240, v224, 0x3a800000, v89
	v_mul_f32_e32 v241, 0x4f800000, v240
	v_cmp_gt_f32_e32 vcc, s54, v240
	s_nop 1
	v_cndmask_b32_e32 v247, v240, v241, vcc
	v_sqrt_f32_e32 v242, v247
	s_nop 1
	v_add_u32_e32 v243, -1, v242
	v_add_u32_e32 v244, 1, v242
	v_fma_f32 v245, -v243, v242, v247
	v_fma_f32 v246, -v244, v242, v247
	v_cmp_ge_f32_e64 s[52:53], 0, v245
	s_nop 1
	v_cndmask_b32_e64 v242, v242, v243, s[52:53]
	v_cmp_lt_f32_e64 s[52:53], 0, v246
	s_nop 1
	v_cndmask_b32_e64 v242, v242, v244, s[52:53]
	v_mul_f32_e32 v243, 0x37800000, v242
	v_cndmask_b32_e32 v242, v242, v243, vcc
	v_cmp_class_f32_e32 vcc, v247, v90
	s_nop 1
	v_cndmask_b32_e32 v247, v242, v247, vcc
	v_div_scale_f32 v248, s[52:53], v247, v247, 1.0
	v_rcp_f32_e32 v249, v248
	v_div_scale_f32 v228, vcc, 1.0, v247, 1.0
	s_nop 0
	v_fma_f32 v229, -v248, v249, 1.0
	v_fmac_f32_e32 v249, v229, v249
	v_mul_f32_e32 v230, v228, v249
	v_fma_f32 v229, -v248, v230, v228
	v_fmac_f32_e32 v230, v229, v249
	v_fma_f32 v248, -v248, v230, v228
	v_div_fmas_f32 v248, v248, v249, v230
	v_div_fixup_f32 v232, v248, v247, 1.0
	v_fmamk_f32 v240, v225, 0x3a800000, v89
	v_mul_f32_e32 v241, 0x4f800000, v240
	v_cmp_gt_f32_e32 vcc, s54, v240
	s_nop 1
	v_cndmask_b32_e32 v247, v240, v241, vcc
	v_sqrt_f32_e32 v242, v247
	s_nop 1
	v_add_u32_e32 v243, -1, v242
	v_add_u32_e32 v244, 1, v242
	v_fma_f32 v245, -v243, v242, v247
	v_fma_f32 v246, -v244, v242, v247
	v_cmp_ge_f32_e64 s[52:53], 0, v245
	s_nop 1
	v_cndmask_b32_e64 v242, v242, v243, s[52:53]
	v_cmp_lt_f32_e64 s[52:53], 0, v246
	s_nop 1
	v_cndmask_b32_e64 v242, v242, v244, s[52:53]
	v_mul_f32_e32 v243, 0x37800000, v242
	v_cndmask_b32_e32 v242, v242, v243, vcc
	v_cmp_class_f32_e32 vcc, v247, v90
	s_nop 1
	v_cndmask_b32_e32 v247, v242, v247, vcc
	v_div_scale_f32 v248, s[52:53], v247, v247, 1.0
	v_rcp_f32_e32 v249, v248
	v_div_scale_f32 v228, vcc, 1.0, v247, 1.0
	s_nop 0
	v_fma_f32 v229, -v248, v249, 1.0
	v_fmac_f32_e32 v249, v229, v249
	v_mul_f32_e32 v230, v228, v249
	v_fma_f32 v229, -v248, v230, v228
	v_fmac_f32_e32 v230, v229, v249
	v_fma_f32 v248, -v248, v230, v228
	v_div_fmas_f32 v248, v248, v249, v230
	v_div_fixup_f32 v234, v248, v247, 1.0
	v_fmamk_f32 v240, v226, 0x3a800000, v89
	v_mul_f32_e32 v241, 0x4f800000, v240
	v_cmp_gt_f32_e32 vcc, s54, v240
	s_nop 1
	v_cndmask_b32_e32 v247, v240, v241, vcc
	v_sqrt_f32_e32 v242, v247
	s_nop 1
	v_add_u32_e32 v243, -1, v242
	v_add_u32_e32 v244, 1, v242
	v_fma_f32 v245, -v243, v242, v247
	v_fma_f32 v246, -v244, v242, v247
	v_cmp_ge_f32_e64 s[52:53], 0, v245
	s_nop 1
	v_cndmask_b32_e64 v242, v242, v243, s[52:53]
	v_cmp_lt_f32_e64 s[52:53], 0, v246
	s_nop 1
	v_cndmask_b32_e64 v242, v242, v244, s[52:53]
	v_mul_f32_e32 v243, 0x37800000, v242
	v_cndmask_b32_e32 v242, v242, v243, vcc
	v_cmp_class_f32_e32 vcc, v247, v90
	s_nop 1
	v_cndmask_b32_e32 v247, v242, v247, vcc
	v_div_scale_f32 v248, s[52:53], v247, v247, 1.0
	v_rcp_f32_e32 v249, v248
	v_div_scale_f32 v228, vcc, 1.0, v247, 1.0
	s_nop 0
	v_fma_f32 v229, -v248, v249, 1.0
	v_fmac_f32_e32 v249, v229, v249
	v_mul_f32_e32 v230, v228, v249
	v_fma_f32 v229, -v248, v230, v228
	v_fmac_f32_e32 v230, v229, v249
	v_fma_f32 v248, -v248, v230, v228
	v_div_fmas_f32 v248, v248, v249, v230
	v_div_fixup_f32 v236, v248, v247, 1.0
	v_fmamk_f32 v240, v227, 0x3a800000, v89
	v_mul_f32_e32 v241, 0x4f800000, v240
	v_cmp_gt_f32_e32 vcc, s54, v240
	s_nop 1
	v_cndmask_b32_e32 v247, v240, v241, vcc
	v_sqrt_f32_e32 v242, v247
	s_nop 1
	v_add_u32_e32 v243, -1, v242
	v_add_u32_e32 v244, 1, v242
	v_fma_f32 v245, -v243, v242, v247
	v_fma_f32 v246, -v244, v242, v247
	v_cmp_ge_f32_e64 s[52:53], 0, v245
	s_nop 1
	v_cndmask_b32_e64 v242, v242, v243, s[52:53]
	v_cmp_lt_f32_e64 s[52:53], 0, v246
	s_nop 1
	v_cndmask_b32_e64 v242, v242, v244, s[52:53]
	v_mul_f32_e32 v243, 0x37800000, v242
	v_cndmask_b32_e32 v242, v242, v243, vcc
	v_cmp_class_f32_e32 vcc, v247, v90
	s_nop 1
	v_cndmask_b32_e32 v247, v242, v247, vcc
	v_div_scale_f32 v248, s[52:53], v247, v247, 1.0
	v_rcp_f32_e32 v249, v248
	v_div_scale_f32 v228, vcc, 1.0, v247, 1.0
	s_nop 0
	v_fma_f32 v229, -v248, v249, 1.0
	v_fmac_f32_e32 v249, v229, v249
	v_mul_f32_e32 v230, v228, v249
	v_fma_f32 v229, -v248, v230, v228
	v_fmac_f32_e32 v230, v229, v249
	v_fma_f32 v248, -v248, v230, v228
	v_div_fmas_f32 v248, v248, v249, v230
	v_div_fixup_f32 v238, v248, v247, 1.0
	s_waitcnt vmcnt(0)
; __device__ __forceinline__ unsigned pk2(float lo, float hi) { return pg8::cvt_pk_bf16(lo, hi); }
; template <bool BF> __device__ __forceinline__ void prep_rows(const float* xp, const float* xs, const bf16* hb, const float* g, const float* MOD, int shoff, int scoff, bf16* U, int gw, int NGW, int lane) {
;     ...
;             const float* mr = MOD + (size_t)(m < MP ? (m >> 13) : 8 + ((m - MP) >> 12)) * 6144;
; #pragma unroll
;             for (int j = 0; j < 4; ++j) { const int c = 4 * lane + 256 * j;
;                 const f32x4 gg = *(const f32x4*)(g + c), sc = *(const f32x4*)(mr + scoff + c), sh = *(const f32x4*)(mr + shoff + c);
;                 const f32x4 o = v[r][j] * rstd * gg * (sc + 1.0f) + sh; v2u w; w.x = pk2(o.x, o.y); w.y = pk2(o.z, o.w); *(v2u*)(U + (size_t)m * DM + c) = w; } } }
	v_pk_add_f32 v[160:161], v[160:161], 1.0 op_sel_hi:[1,0]
	v_pk_add_f32 v[162:163], v[162:163], 1.0 op_sel_hi:[1,0]
	v_pk_add_f32 v[164:165], v[164:165], 1.0 op_sel_hi:[1,0]
	v_pk_add_f32 v[166:167], v[166:167], 1.0 op_sel_hi:[1,0]
	v_pk_add_f32 v[168:169], v[168:169], 1.0 op_sel_hi:[1,0]
	v_pk_add_f32 v[170:171], v[170:171], 1.0 op_sel_hi:[1,0]
	v_pk_add_f32 v[172:173], v[172:173], 1.0 op_sel_hi:[1,0]
	v_pk_add_f32 v[174:175], v[174:175], 1.0 op_sel_hi:[1,0]
	v_pk_add_f32 v[192:193], v[192:193], 1.0 op_sel_hi:[1,0]
	v_pk_add_f32 v[194:195], v[194:195], 1.0 op_sel_hi:[1,0]
	v_pk_add_f32 v[196:197], v[196:197], 1.0 op_sel_hi:[1,0]
	v_pk_add_f32 v[198:199], v[198:199], 1.0 op_sel_hi:[1,0]
	v_pk_add_f32 v[200:201], v[200:201], 1.0 op_sel_hi:[1,0]
	v_pk_add_f32 v[202:203], v[202:203], 1.0 op_sel_hi:[1,0]
	v_pk_add_f32 v[204:205], v[204:205], 1.0 op_sel_hi:[1,0]
	v_pk_add_f32 v[206:207], v[206:207], 1.0 op_sel_hi:[1,0]
	s_add_u32 s38, s20, 0xb000000
	s_addc_u32 s39, s21, 0
	s_add_u32 s40, s20, 0xb400000
	s_addc_u32 s41, s21, 0
	s_add_u32 s46, s20, 0xb800000
	s_addc_u32 s47, s21, 0
	s_add_u32 s48, s20, 0xbc00000
	s_addc_u32 s49, s21, 0
	v_pk_mul_f32 v[0:1], v[0:1], v[232:233] op_sel_hi:[1,0]
	v_pk_mul_f32 v[2:3], v[2:3], v[232:233] op_sel_hi:[1,0]
	v_pk_mul_f32 v[0:1], v[64:65], v[0:1]
	v_pk_mul_f32 v[2:3], v[66:67], v[2:3]
	v_pk_fma_f32 v[0:1], v[160:161], v[0:1], v[176:177]
	v_pk_fma_f32 v[2:3], v[162:163], v[2:3], v[178:179]
	v_cvt_pk_bf16_f32 v244, v0, v1
	v_cvt_pk_bf16_f32 v245, v2, v3
	v_pk_mul_f32 v[4:5], v[4:5], v[232:233] op_sel_hi:[1,0]
	v_pk_mul_f32 v[6:7], v[6:7], v[232:233] op_sel_hi:[1,0]
	v_pk_mul_f32 v[4:5], v[68:69], v[4:5]
	v_pk_mul_f32 v[6:7], v[70:71], v[6:7]
	v_pk_fma_f32 v[4:5], v[164:165], v[4:5], v[180:181]
	v_pk_fma_f32 v[6:7], v[166:167], v[6:7], v[182:183]
	v_cvt_pk_bf16_f32 v246, v4, v5
	v_cvt_pk_bf16_f32 v247, v6, v7
	global_store_dwordx4 v82, v[244:247], s[38:39] offset:0
	v_pk_mul_f32 v[8:9], v[8:9], v[232:233] op_sel_hi:[1,0]
	v_pk_mul_f32 v[10:11], v[10:11], v[232:233] op_sel_hi:[1,0]
	v_pk_mul_f32 v[8:9], v[72:73], v[8:9]
	v_pk_mul_f32 v[10:11], v[74:75], v[10:11]
	v_pk_fma_f32 v[8:9], v[168:169], v[8:9], v[184:185]
	v_pk_fma_f32 v[10:11], v[170:171], v[10:11], v[186:187]
	v_cvt_pk_bf16_f32 v240, v8, v9
	v_cvt_pk_bf16_f32 v241, v10, v11
	v_pk_mul_f32 v[12:13], v[12:13], v[232:233] op_sel_hi:[1,0]
	v_pk_mul_f32 v[14:15], v[14:15], v[232:233] op_sel_hi:[1,0]
	v_pk_mul_f32 v[12:13], v[76:77], v[12:13]
	v_pk_mul_f32 v[14:15], v[78:79], v[14:15]
	v_pk_fma_f32 v[12:13], v[172:173], v[12:13], v[188:189]
	v_pk_fma_f32 v[14:15], v[174:175], v[14:15], v[190:191]
	v_cvt_pk_bf16_f32 v242, v12, v13
	v_cvt_pk_bf16_f32 v243, v14, v15
	global_store_dwordx4 v82, v[240:243], s[38:39] offset:1024
	v_pk_mul_f32 v[16:17], v[16:17], v[234:235] op_sel_hi:[1,0]
	v_pk_mul_f32 v[18:19], v[18:19], v[234:235] op_sel_hi:[1,0]
	v_pk_mul_f32 v[16:17], v[64:65], v[16:17]
	v_pk_mul_f32 v[18:19], v[66:67], v[18:19]
	v_pk_fma_f32 v[16:17], v[160:161], v[16:17], v[176:177]
	v_pk_fma_f32 v[18:19], v[162:163], v[18:19], v[178:179]
	v_cvt_pk_bf16_f32 v244, v16, v17
	v_cvt_pk_bf16_f32 v245, v18, v19
	v_pk_mul_f32 v[20:21], v[20:21], v[234:235] op_sel_hi:[1,0]
	v_pk_mul_f32 v[22:23], v[22:23], v[234:235] op_sel_hi:[1,0]
	v_pk_mul_f32 v[20:21], v[68:69], v[20:21]
	v_pk_mul_f32 v[22:23], v[70:71], v[22:23]
	v_pk_fma_f32 v[20:21], v[164:165], v[20:21], v[180:181]
	v_pk_fma_f32 v[22:23], v[166:167], v[22:23], v[182:183]
	v_cvt_pk_bf16_f32 v246, v20, v21
	v_cvt_pk_bf16_f32 v247, v22, v23
	global_store_dwordx4 v82, v[244:247], s[40:41] offset:0
	v_pk_mul_f32 v[24:25], v[24:25], v[234:235] op_sel_hi:[1,0]
	v_pk_mul_f32 v[26:27], v[26:27], v[234:235] op_sel_hi:[1,0]
	v_pk_mul_f32 v[24:25], v[72:73], v[24:25]
	v_pk_mul_f32 v[26:27], v[74:75], v[26:27]
	v_pk_fma_f32 v[24:25], v[168:169], v[24:25], v[184:185]
	v_pk_fma_f32 v[26:27], v[170:171], v[26:27], v[186:187]
; __device__ __forceinline__ unsigned pk2(float lo, float hi) { return pg8::cvt_pk_bf16(lo, hi); }
; template <bool BF> __device__ __forceinline__ void prep_rows(const float* xp, const float* xs, const bf16* hb, const float* g, const float* MOD, int shoff, int scoff, bf16* U, int gw, int NGW, int lane) {
;     ...
;             const float* mr = MOD + (size_t)(m < MP ? (m >> 13) : 8 + ((m - MP) >> 12)) * 6144;
; #pragma unroll
;             for (int j = 0; j < 4; ++j) { const int c = 4 * lane + 256 * j;
;                 const f32x4 gg = *(const f32x4*)(g + c), sc = *(const f32x4*)(mr + scoff + c), sh = *(const f32x4*)(mr + shoff + c);
;                 const f32x4 o = v[r][j] * rstd * gg * (sc + 1.0f) + sh; v2u w; w.x = pk2(o.x, o.y); w.y = pk2(o.z, o.w); *(v2u*)(U + (size_t)m * DM + c) = w; } } }
	v_cvt_pk_bf16_f32 v240, v24, v25
	v_cvt_pk_bf16_f32 v241, v26, v27
	v_pk_mul_f32 v[28:29], v[28:29], v[234:235] op_sel_hi:[1,0]
	v_pk_mul_f32 v[30:31], v[30:31], v[234:235] op_sel_hi:[1,0]
	v_pk_mul_f32 v[28:29], v[76:77], v[28:29]
	v_pk_mul_f32 v[30:31], v[78:79], v[30:31]
	v_pk_fma_f32 v[28:29], v[172:173], v[28:29], v[188:189]
	v_pk_fma_f32 v[30:31], v[174:175], v[30:31], v[190:191]
	v_cvt_pk_bf16_f32 v242, v28, v29
	v_cvt_pk_bf16_f32 v243, v30, v31
	global_store_dwordx4 v82, v[240:243], s[40:41] offset:1024
	v_pk_mul_f32 v[32:33], v[32:33], v[236:237] op_sel_hi:[1,0]
	v_pk_mul_f32 v[34:35], v[34:35], v[236:237] op_sel_hi:[1,0]
	v_pk_mul_f32 v[32:33], v[64:65], v[32:33]
	v_pk_mul_f32 v[34:35], v[66:67], v[34:35]
	v_pk_fma_f32 v[32:33], v[192:193], v[32:33], v[208:209]
	v_pk_fma_f32 v[34:35], v[194:195], v[34:35], v[210:211]
	v_cvt_pk_bf16_f32 v244, v32, v33
	v_cvt_pk_bf16_f32 v245, v34, v35
	v_pk_mul_f32 v[36:37], v[36:37], v[236:237] op_sel_hi:[1,0]
	v_pk_mul_f32 v[38:39], v[38:39], v[236:237] op_sel_hi:[1,0]
	v_pk_mul_f32 v[36:37], v[68:69], v[36:37]
	v_pk_mul_f32 v[38:39], v[70:71], v[38:39]
	v_pk_fma_f32 v[36:37], v[196:197], v[36:37], v[212:213]
	v_pk_fma_f32 v[38:39], v[198:199], v[38:39], v[214:215]
	v_cvt_pk_bf16_f32 v246, v36, v37
	v_cvt_pk_bf16_f32 v247, v38, v39
	global_store_dwordx4 v82, v[244:247], s[46:47] offset:0
	v_pk_mul_f32 v[40:41], v[40:41], v[236:237] op_sel_hi:[1,0]
	v_pk_mul_f32 v[42:43], v[42:43], v[236:237] op_sel_hi:[1,0]
	v_pk_mul_f32 v[40:41], v[72:73], v[40:41]
	v_pk_mul_f32 v[42:43], v[74:75], v[42:43]
	v_pk_fma_f32 v[40:41], v[200:201], v[40:41], v[216:217]
	v_pk_fma_f32 v[42:43], v[202:203], v[42:43], v[218:219]
	v_cvt_pk_bf16_f32 v240, v40, v41
	v_cvt_pk_bf16_f32 v241, v42, v43
	v_pk_mul_f32 v[44:45], v[44:45], v[236:237] op_sel_hi:[1,0]
	v_pk_mul_f32 v[46:47], v[46:47], v[236:237] op_sel_hi:[1,0]
	v_pk_mul_f32 v[44:45], v[76:77], v[44:45]
	v_pk_mul_f32 v[46:47], v[78:79], v[46:47]
	v_pk_fma_f32 v[44:45], v[204:205], v[44:45], v[220:221]
	v_pk_fma_f32 v[46:47], v[206:207], v[46:47], v[222:223]
	v_cvt_pk_bf16_f32 v242, v44, v45
	v_cvt_pk_bf16_f32 v243, v46, v47
	global_store_dwordx4 v82, v[240:243], s[46:47] offset:1024
	v_pk_mul_f32 v[48:49], v[48:49], v[238:239] op_sel_hi:[1,0]
	v_pk_mul_f32 v[50:51], v[50:51], v[238:239] op_sel_hi:[1,0]
	v_pk_mul_f32 v[48:49], v[64:65], v[48:49]
	v_pk_mul_f32 v[50:51], v[66:67], v[50:51]
	v_pk_fma_f32 v[48:49], v[192:193], v[48:49], v[208:209]
	v_pk_fma_f32 v[50:51], v[194:195], v[50:51], v[210:211]
	v_cvt_pk_bf16_f32 v244, v48, v49
	v_cvt_pk_bf16_f32 v245, v50, v51
	v_pk_mul_f32 v[52:53], v[52:53], v[238:239] op_sel_hi:[1,0]
	v_pk_mul_f32 v[54:55], v[54:55], v[238:239] op_sel_hi:[1,0]
	v_pk_mul_f32 v[52:53], v[68:69], v[52:53]
	v_pk_mul_f32 v[54:55], v[70:71], v[54:55]
	v_pk_fma_f32 v[52:53], v[196:197], v[52:53], v[212:213]
	v_pk_fma_f32 v[54:55], v[198:199], v[54:55], v[214:215]
	v_cvt_pk_bf16_f32 v246, v52, v53
	v_cvt_pk_bf16_f32 v247, v54, v55
	global_store_dwordx4 v82, v[244:247], s[48:49] offset:0
	v_pk_mul_f32 v[56:57], v[56:57], v[238:239] op_sel_hi:[1,0]
	v_pk_mul_f32 v[58:59], v[58:59], v[238:239] op_sel_hi:[1,0]
	v_pk_mul_f32 v[56:57], v[72:73], v[56:57]
	v_pk_mul_f32 v[58:59], v[74:75], v[58:59]
	v_pk_fma_f32 v[56:57], v[200:201], v[56:57], v[216:217]
	v_pk_fma_f32 v[58:59], v[202:203], v[58:59], v[218:219]
	v_cvt_pk_bf16_f32 v240, v56, v57
	v_cvt_pk_bf16_f32 v241, v58, v59
	v_pk_mul_f32 v[60:61], v[60:61], v[238:239] op_sel_hi:[1,0]
	v_pk_mul_f32 v[62:63], v[62:63], v[238:239] op_sel_hi:[1,0]
	v_pk_mul_f32 v[60:61], v[76:77], v[60:61]
	v_pk_mul_f32 v[62:63], v[78:79], v[62:63]
	v_pk_fma_f32 v[60:61], v[204:205], v[60:61], v[220:221]
	v_pk_fma_f32 v[62:63], v[206:207], v[62:63], v[222:223]
	v_cvt_pk_bf16_f32 v242, v60, v61
	v_cvt_pk_bf16_f32 v243, v62, v63
	global_store_dwordx4 v82, v[240:243], s[48:49] offset:1024

; #define LAS __attribute__((address_space(3)))
; template <int PHM> __global__ void __launch_bounds__(512, 2) mk_fwd(Args karg) {
;     extern __shared__ __attribute__((aligned(16))) unsigned char lds_raw[];
;     LAS unsigned char* lds = (LAS unsigned char*)lds_raw;
;     const int bid = blockIdx.x, G = gridDim.x, NGW = G * 8;
	.amdhsa_kernel _Z6mk_fwdILi65535EEv4Args
		.amdhsa_group_segment_fixed_size 0
		.amdhsa_private_segment_fixed_size 0
		.amdhsa_kernarg_size 504
		.amdhsa_user_sgpr_count 2
		.amdhsa_user_sgpr_dispatch_ptr 0
		.amdhsa_user_sgpr_queue_ptr 0
		.amdhsa_user_sgpr_kernarg_segment_ptr 1
		.amdhsa_user_sgpr_dispatch_id 0
		.amdhsa_user_sgpr_kernarg_preload_length 0
		.amdhsa_user_sgpr_kernarg_preload_offset 0
		.amdhsa_user_sgpr_private_segment_size 0
		.amdhsa_uses_dynamic_stack 0
		.amdhsa_enable_private_segment 0
		.amdhsa_system_sgpr_workgroup_id_x 1
		.amdhsa_system_sgpr_workgroup_id_y 0
		.amdhsa_system_sgpr_workgroup_id_z 0
		.amdhsa_system_sgpr_workgroup_info 0
		.amdhsa_system_vgpr_workitem_id 2
		.amdhsa_next_free_vgpr 256
		.amdhsa_next_free_sgpr 100
		.amdhsa_accum_offset 256
		.amdhsa_reserve_vcc 1
		.amdhsa_float_round_mode_32 0
		.amdhsa_float_round_mode_16_64 0
		.amdhsa_float_denorm_mode_32 3
		.amdhsa_float_denorm_mode_16_64 3
		.amdhsa_dx10_clamp 1
		.amdhsa_ieee_mode 1
		.amdhsa_fp16_overflow 0
		.amdhsa_tg_split 0
		.amdhsa_exception_fp_ieee_invalid_op 0
		.amdhsa_exception_fp_denorm_src 0
		.amdhsa_exception_fp_ieee_div_zero 0
		.amdhsa_exception_fp_ieee_overflow 0
		.amdhsa_exception_fp_ieee_underflow 0
		.amdhsa_exception_fp_ieee_inexact 0
		.amdhsa_exception_int_div_zero 0
	.end_amdhsa_kernel

; #define LAS __attribute__((address_space(3)))
; template <int PHM> __global__ void __launch_bounds__(512, 2) mk_fwd(Args karg) {
;     extern __shared__ __attribute__((aligned(16))) unsigned char lds_raw[];
;     LAS unsigned char* lds = (LAS unsigned char*)lds_raw;
;     const int bid = blockIdx.x, G = gridDim.x, NGW = G * 8;
amdhsa.kernels:
  - .agpr_count:     0
    .args:
      - .offset:         0
        .size:           248
        .value_kind:     by_value
      - .offset:         248
        .size:           4
        .value_kind:     hidden_block_count_x
      - .offset:         252
        .size:           4
        .value_kind:     hidden_block_count_y
      - .offset:         256
        .size:           4
        .value_kind:     hidden_block_count_z
      - .offset:         260
        .size:           2
        .value_kind:     hidden_group_size_x
      - .offset:         262
        .size:           2
        .value_kind:     hidden_group_size_y
      - .offset:         264
        .size:           2
        .value_kind:     hidden_group_size_z
      - .offset:         266
        .size:           2
        .value_kind:     hidden_remainder_x
      - .offset:         268
        .size:           2
        .value_kind:     hidden_remainder_y
      - .offset:         270
        .size:           2
        .value_kind:     hidden_remainder_z
      - .offset:         288
        .size:           8
        .value_kind:     hidden_global_offset_x
      - .offset:         296
        .size:           8
        .value_kind:     hidden_global_offset_y
      - .offset:         304
        .size:           8
        .value_kind:     hidden_global_offset_z
      - .offset:         312
        .size:           2
        .value_kind:     hidden_grid_dims
      - .offset:         336
        .size:           8
        .value_kind:     hidden_multigrid_sync_arg
      - .offset:         368
        .size:           4
        .value_kind:     hidden_dynamic_lds_size
    .group_segment_fixed_size: 0
    .kernarg_segment_align: 8
    .kernarg_segment_size: 504
    .language:       OpenCL C
    .language_version:
      - 2
      - 0
    .max_flat_workgroup_size: 512
    .name:           _Z6mk_fwdILi65535EEv4Args
    .private_segment_fixed_size: 0
    .sgpr_count:     106
    .sgpr_spill_count: 82
    .symbol:         _Z6mk_fwdILi65535EEv4Args.kd
    .uniform_work_group_size: 1
    .uses_dynamic_stack: false
    .vgpr_count:     256
    .vgpr_spill_count: 0
    .wavefront_size: 64
